# flat_load/store/atomic converted to global_* everywhere outside the attention code (no more lgkmcnt coupling)
# baseline (speedup 1.0000x reference)
; #define LAS __attribute__((address_space(3)))
; __device__ __forceinline__ unsigned xb_add(unsigned* p, unsigned v) { return __hip_atomic_fetch_add(p, v, __ATOMIC_RELAXED, __HIP_MEMORY_SCOPE_AGENT); }
; __device__ __forceinline__ unsigned xb_xcc_id() { return (unsigned)__builtin_amdgcn_s_getreg((3 << 11) | 20) & 0xFu; }
; #define LAS __attribute__((address_space(3)))
; #define PH_WS() unsigned char* ws = p.ws; asm volatile("" : "+s"(ws))
; __device__ __forceinline__ XcdBarrier xcd_barrier_post(unsigned* bar, volatile LAS unsigned* st) {
;     XcdBarrier b; b.bar = bar; b.x = xb_xcc_id(); b.st = st;
;     if (threadIdx.x == 0) (void)xb_add(&bar[XB_XCNT(b.x)], 1u);
;     return b;
; __global__ void __launch_bounds__(512, 2) fwd_megakernel(Params p) {
;     ...
;     volatile LAS unsigned* bst = (volatile LAS unsigned*)(lds + 131072 + 64);
;     if (threadIdx.x < 2) bst[threadIdx.x] = 0u;
;     __syncthreads();
;     { PH_WS(); (void)xcd_barrier_post((unsigned*)(ws + Z_BAR), bst); }
_Z14fwd_megakernel6Params:
	s_load_dwordx8 s[88:95], s[0:1], 0xc0
	s_load_dword s33, s[0:1], 0xe0
	s_add_u32 s12, s0, 0xd8
	v_and_b32_e32 v222, 0x3ff, v0
	s_addc_u32 s13, s1, 0
	v_cmp_gt_u32_e32 vcc, 2, v222
	s_and_saveexec_b64 s[4:5], vcc
	v_lshl_add_u32 v1, v222, 2, 0
	v_add_u32_e32 v1, 0x20040, v1
	v_mov_b32_e32 v2, 0
	ds_write_b32 v1, v2
	s_or_b64 exec, exec, s[4:5]
	s_waitcnt lgkmcnt(0)
	s_mov_b64 s[6:7], s[92:93]
	s_barrier
	s_getreg_b32 s3, hwreg(HW_REG_XCC_ID, 0, 4)
	v_cmp_eq_u32_e64 s[8:9], 0, v222
	s_mov_b64 s[4:5], exec
	s_nop 0
	v_writelane_b32 v248, s8, 0
	s_nop 1
	v_writelane_b32 v248, s9, 1
	s_and_b64 s[8:9], s[4:5], s[8:9]
	s_mov_b64 exec, s[8:9]
	s_cbranch_execz .LBB0_4
	s_lshl_b32 s3, s3, 8
	s_and_b32 s3, s3, 0xf00
	s_add_u32 s3, s6, s3
	s_addc_u32 s6, s7, 0
	v_mov_b32_e32 v1, s3
	v_add_co_u32_e32 v2, vcc, 0x180000, v1
	v_mov_b32_e32 v1, s6
	s_nop 0
	v_addc_co_u32_e32 v3, vcc, 0, v1, vcc
	v_mov_b32_e32 v1, 1
	global_atomic_add v[2:3], v1, off offset:1024

; __device__ __forceinline__ unsigned xb_ld(unsigned* p)              { return __hip_atomic_load(p, __ATOMIC_RELAXED, __HIP_MEMORY_SCOPE_AGENT); }
; __device__ __forceinline__ void xcd_barrier_complete(unsigned* bar, unsigned x, unsigned& nloc, unsigned& nx) {
;     ...
;     for (;;) {
;         sum = 0u; cnt = 0u; mine = 0u;
; #pragma unroll
;         for (unsigned j = 0; j < 16; ++j) { const unsigned c = xb_ld(&bar[XB_XCNT(j)]); sum += c; cnt += (c > 0u) ? 1u : 0u; mine = (j == x) ? c : mine; }
;         if (sum == G) break;
;         __builtin_amdgcn_s_sleep(1);
;         if ((++sp & 255u) == 0u) { if (xb_ld(&bar[XB_TMO])) break; if (sp > XB_SPIN_CAP) { atomicAdd(&bar[XB_TMO], 1u); break; } }
;     }
.LBB0_77:
	global_load_dword v25, v[0:1], off offset:1024 sc1
	global_load_dword v10, v[0:1], off offset:1280 sc1
	global_load_dword v11, v[0:1], off offset:1536 sc1
	global_load_dword v12, v[0:1], off offset:1792 sc1
	global_load_dword v13, v[0:1], off offset:2048 sc1
	global_load_dword v14, v[0:1], off offset:2304 sc1
	global_load_dword v15, v[0:1], off offset:2560 sc1
	global_load_dword v16, v[0:1], off offset:2816 sc1
	global_load_dword v17, v[0:1], off offset:3072 sc1
	global_load_dword v18, v[0:1], off offset:3328 sc1
	global_load_dword v19, v[0:1], off offset:3584 sc1
	global_load_dword v20, v[0:1], off offset:3840 sc1
	global_load_dword v21, v[2:3], off sc1
	global_load_dword v22, v[4:5], off sc1
	global_load_dword v23, v[6:7], off sc1
	global_load_dword v24, v[8:9], off sc1
	s_or_b64 s[8:9], s[8:9], exec
	s_or_b64 s[6:7], s[6:7], exec
	s_waitcnt vmcnt(0) lgkmcnt(0)
	v_add_u32_e32 v26, v10, v25
	v_add_u32_e32 v26, v26, v11
	v_add_u32_e32 v26, v26, v12
	v_add_u32_e32 v26, v26, v13
	v_add_u32_e32 v26, v26, v14
	v_add_u32_e32 v26, v26, v15
	v_add_u32_e32 v26, v26, v16
	v_add_u32_e32 v26, v26, v17
	v_add_u32_e32 v26, v26, v18
	v_add_u32_e32 v26, v26, v19
	v_add_u32_e32 v26, v26, v20
	v_add_u32_e32 v26, v26, v21
	v_add_u32_e32 v26, v26, v22
	v_add_u32_e32 v26, v26, v23
	v_add_u32_e32 v26, v26, v24
	v_cmp_ne_u32_e32 vcc, s22, v26
	s_and_saveexec_b64 s[10:11], vcc
	s_cbranch_execz .LBB0_76
	s_and_b32 s16, s23, 0xff
	s_mov_b64 s[12:13], -1
	s_cmp_eq_u32 s16, 0
	s_mov_b64 s[18:19], -1
	s_mov_b64 s[16:17], -1
	s_sleep 1
	s_cbranch_scc1 .LBB0_80
	s_and_saveexec_b64 s[20:21], s[18:19]
	s_cbranch_execz .LBB0_75
	s_branch .LBB0_83
.LBB0_80:
	global_load_dword v26, v[0:1], off offset:512 sc1
	s_mov_b64 s[18:19], 0
	s_waitcnt vmcnt(0) lgkmcnt(0)
	v_cmp_eq_u32_e32 vcc, 0, v26
	s_and_saveexec_b64 s[20:21], vcc
	s_cmp_lt_u32 s23, 0x40001
	s_cselect_b64 s[18:19], -1, 0
	s_xor_b64 s[16:17], exec, -1
	s_and_b64 s[18:19], s[18:19], exec
	s_or_b64 exec, exec, s[20:21]
	s_and_saveexec_b64 s[20:21], s[18:19]
	s_cbranch_execz .LBB0_75

; __device__ __forceinline__ unsigned xb_ld(unsigned* p)              { return __hip_atomic_load(p, __ATOMIC_RELAXED, __HIP_MEMORY_SCOPE_AGENT); }
; __device__ __forceinline__ void xcd_barrier_complete(unsigned* bar, unsigned x, unsigned& nloc, unsigned& nx) {
;     ...
;         for (unsigned j = 0; j < 16; ++j) { const unsigned c = xb_ld(&bar[XB_XCNT(j)]); sum += c; cnt += (c > 0u) ? 1u : 0u; mine = (j == x) ? c : mine; }
;         if (sum == G) break;
;         __builtin_amdgcn_s_sleep(1);
;         if ((++sp & 255u) == 0u) { if (xb_ld(&bar[XB_TMO])) break; if (sp > XB_SPIN_CAP) { atomicAdd(&bar[XB_TMO], 1u); break; } }
;     }
;     nloc = mine > 0u ? mine : 1u; nx = cnt > 0u ? cnt : 1u;
.LBB0_84:
	s_or_b64 exec, exec, s[0:1]
	s_xor_b64 s[0:1], s[4:5], -1
	s_and_saveexec_b64 s[4:5], s[0:1]
	s_xor_b64 s[0:1], exec, s[4:5]
	s_cbranch_execz .LBB0_86
	v_mov_b32_e32 v2, 1
	v_mov_b64_e32 v[0:1], s[38:39]
	global_atomic_add v[0:1], v2, off offset:512

; __device__ __forceinline__ unsigned xb_ld(unsigned* p)              { return __hip_atomic_load(p, __ATOMIC_RELAXED, __HIP_MEMORY_SCOPE_AGENT); }
; __device__ __forceinline__ unsigned xb_add(unsigned* p, unsigned v) { return __hip_atomic_fetch_add(p, v, __ATOMIC_RELAXED, __HIP_MEMORY_SCOPE_AGENT); }
; #define XB_SPIN(cond, bar) do { unsigned _sp = 0; while (cond) { __builtin_amdgcn_s_sleep(1); \
;     if ((++_sp & 255u) == 0u) { if (xb_ld(&(bar)[XB_TMO])) break; if (_sp > XB_SPIN_CAP) { atomicAdd(&(bar)[XB_TMO], 1u); break; } } } } while (0)
; __device__ __forceinline__ void xcd_barrier(const XcdBarrier& b) {
;     ...
;         const unsigned old = xb_add(&bar[XB_XSUB(b.x)], 1u);
;         const unsigned gen = old / nloc;
;         if (old + 1u == (gen + 1u) * nloc) {
;             __builtin_amdgcn_fence(__ATOMIC_RELEASE, "agent");
;             asm volatile("s_waitcnt vmcnt(0)" ::: "memory");
;             const unsigned og = xb_add(&bar[XB_TOP], 1u);
;             const unsigned tg = og / nx;
;             if (og + 1u == (tg + 1u) * nx) xb_add(&bar[XB_TOPGEN], 1u);
;             else XB_SPIN(xb_ld(&bar[XB_TOPGEN]) == tg, bar);
;             __builtin_amdgcn_fence(__ATOMIC_ACQUIRE, "agent");
;             xb_add(&bar[XB_XGEN(b.x)], 1u);
;             asm volatile("s_waitcnt vmcnt(0)" ::: "memory");
;         } else {
;             XB_SPIN(xb_ld(&bar[XB_XGEN(b.x)]) == gen, bar);
.LBB0_87:
	s_lshl_b32 s0, s37, 8
	s_add_u32 s25, s38, s0
	s_addc_u32 s24, s39, 0
	v_mov_b32_e32 v1, s25
	v_add_co_u32_e32 v4, vcc, 0x1000, v1
	v_mov_b32_e32 v1, s24
	s_nop 0
	v_addc_co_u32_e32 v5, vcc, 0, v1, vcc
	v_mov_b32_e32 v1, 1
	global_atomic_add v1, v[4:5], v1, off offset:1024 sc0
	v_cvt_f32_u32_e32 v3, v2
	v_sub_u32_e32 v4, 0, v2
	v_rcp_iflag_f32_e32 v3, v3
	s_nop 0
	v_mul_f32_e32 v3, 0x4f7ffffe, v3
	v_cvt_u32_f32_e32 v3, v3
	v_mul_lo_u32 v4, v4, v3
	v_mul_hi_u32 v4, v3, v4
	v_add_u32_e32 v3, v3, v4
	s_waitcnt vmcnt(0) lgkmcnt(0)
	v_mul_hi_u32 v3, v1, v3
	v_mul_lo_u32 v5, v3, v2
	v_add_u32_e32 v4, 1, v1
	v_sub_u32_e32 v1, v1, v5
	v_add_u32_e32 v6, 1, v3
	v_cmp_ge_u32_e32 vcc, v1, v2
	v_sub_u32_e32 v5, v1, v2
	s_nop 0
	v_cndmask_b32_e32 v3, v3, v6, vcc
	v_cndmask_b32_e32 v1, v1, v5, vcc
	v_add_u32_e32 v5, 1, v3
	v_cmp_ge_u32_e32 vcc, v1, v2
	s_nop 1
	v_cndmask_b32_e32 v1, v3, v5, vcc
	v_mad_u64_u32 v[2:3], s[0:1], v2, v1, v[2:3]
	v_cmp_ne_u32_e32 vcc, v4, v2
	s_and_saveexec_b64 s[0:1], vcc
	s_xor_b64 s[0:1], exec, s[0:1]
	s_cbranch_execz .LBB0_100
	v_mov_b32_e32 v0, s25
	v_add_co_u32_e32 v2, vcc, 0x2000, v0
	v_mov_b32_e32 v0, s24
	s_nop 0
	v_addc_co_u32_e32 v3, vcc, 0, v0, vcc
	global_load_dword v0, v[2:3], off offset:1024 sc1
	s_add_u32 s6, s25, 0x2400
	s_addc_u32 s7, s24, 0
	s_waitcnt vmcnt(0) lgkmcnt(0)
	v_cmp_eq_u32_e32 vcc, v0, v1
	s_and_saveexec_b64 s[4:5], vcc
	s_cbranch_execz .LBB0_99
	s_mov_b32 s26, 1
	s_mov_b64 s[8:9], 0
	s_branch .LBB0_91

; __device__ __forceinline__ unsigned xb_ld(unsigned* p)              { return __hip_atomic_load(p, __ATOMIC_RELAXED, __HIP_MEMORY_SCOPE_AGENT); }
; __device__ __forceinline__ unsigned xb_add(unsigned* p, unsigned v) { return __hip_atomic_fetch_add(p, v, __ATOMIC_RELAXED, __HIP_MEMORY_SCOPE_AGENT); }
; #define XB_SPIN(cond, bar) do { unsigned _sp = 0; while (cond) { __builtin_amdgcn_s_sleep(1); \
;     if ((++_sp & 255u) == 0u) { if (xb_ld(&(bar)[XB_TMO])) break; if (_sp > XB_SPIN_CAP) { atomicAdd(&(bar)[XB_TMO], 1u); break; } } } } while (0)
; __device__ __forceinline__ void xcd_barrier(const XcdBarrier& b) {
;     ...
;             else XB_SPIN(xb_ld(&bar[XB_TOPGEN]) == tg, bar);
;             __builtin_amdgcn_fence(__ATOMIC_ACQUIRE, "agent");
;             xb_add(&bar[XB_XGEN(b.x)], 1u);
;             asm volatile("s_waitcnt vmcnt(0)" ::: "memory");
;         } else {
;             XB_SPIN(xb_ld(&bar[XB_XGEN(b.x)]) == gen, bar);
.LBB0_91:
	s_and_b32 s18, s26, 0xff
	s_mov_b64 s[16:17], -1
	s_cmp_lg_u32 s18, 0
	s_mov_b64 s[18:19], -1
	s_sleep 1
	s_cbranch_scc1 .LBB0_95
	v_mov_b64_e32 v[2:3], s[38:39]
	global_load_dword v0, v[2:3], off offset:512 sc1
	s_mov_b64 s[18:19], 0
	s_mov_b64 s[20:21], -1
	s_waitcnt vmcnt(0) lgkmcnt(0)
	v_cmp_eq_u32_e32 vcc, 0, v0
	s_and_saveexec_b64 s[22:23], vcc
	s_cmp_lt_u32 s26, 0x40001
	s_cselect_b64 s[18:19], -1, 0
	s_xor_b64 s[20:21], exec, -1
	s_and_b64 s[18:19], s[18:19], exec
	s_or_b64 exec, exec, s[22:23]
.LBB0_95:
	s_andn2_b64 s[12:13], s[12:13], exec
	s_and_b64 s[20:21], s[20:21], exec
	s_or_b64 s[12:13], s[12:13], s[20:21]
	s_and_saveexec_b64 s[20:21], s[18:19]
	s_cbranch_execz .LBB0_90
	v_mov_b64_e32 v[2:3], s[6:7]
	global_load_dword v0, v[2:3], off sc1
	s_add_i32 s26, s26, 1
	s_or_b64 s[12:13], s[12:13], exec
	s_waitcnt vmcnt(0) lgkmcnt(0)
	v_cmp_ne_u32_e32 vcc, v0, v1
	s_orn2_b64 s[16:17], vcc, exec
	s_branch .LBB0_90
.LBB0_97:
	s_or_b64 exec, exec, s[8:9]
	s_xor_b64 s[6:7], s[10:11], -1
	s_and_saveexec_b64 s[8:9], s[6:7]
	s_xor_b64 s[8:9], exec, s[8:9]
	s_cbranch_execz .LBB0_99
	v_mov_b32_e32 v2, 1
	v_mov_b64_e32 v[0:1], s[38:39]
	global_atomic_add v[0:1], v2, off offset:512

; __device__ __forceinline__ unsigned xb_ld(unsigned* p)              { return __hip_atomic_load(p, __ATOMIC_RELAXED, __HIP_MEMORY_SCOPE_AGENT); }
; __device__ __forceinline__ unsigned xb_add(unsigned* p, unsigned v) { return __hip_atomic_fetch_add(p, v, __ATOMIC_RELAXED, __HIP_MEMORY_SCOPE_AGENT); }
; #define XB_SPIN(cond, bar) do { unsigned _sp = 0; while (cond) { __builtin_amdgcn_s_sleep(1); \
;     if ((++_sp & 255u) == 0u) { if (xb_ld(&(bar)[XB_TMO])) break; if (_sp > XB_SPIN_CAP) { atomicAdd(&(bar)[XB_TMO], 1u); break; } } } } while (0)
; __device__ __forceinline__ void xcd_barrier(const XcdBarrier& b) {
;     ...
;         if (old + 1u == (gen + 1u) * nloc) {
;             __builtin_amdgcn_fence(__ATOMIC_RELEASE, "agent");
;             asm volatile("s_waitcnt vmcnt(0)" ::: "memory");
;             const unsigned og = xb_add(&bar[XB_TOP], 1u);
;             const unsigned tg = og / nx;
;             if (og + 1u == (tg + 1u) * nx) xb_add(&bar[XB_TOPGEN], 1u);
;             else XB_SPIN(xb_ld(&bar[XB_TOPGEN]) == tg, bar);
.LBB0_100:
	s_andn2_saveexec_b64 s[0:1], s[0:1]
	s_cbranch_execz .LBB0_116
	v_mov_b32_e32 v1, s38
	v_add_co_u32_e32 v2, vcc, 0x3000, v1
	v_mov_b32_e32 v1, s39
	buffer_wbl2 sc1
	s_waitcnt vmcnt(0)
	v_addc_co_u32_e32 v3, vcc, 0, v1, vcc
	v_mov_b32_e32 v1, 1
	global_atomic_add v1, v[2:3], v1, off offset:1024 sc0
	v_cvt_f32_u32_e32 v2, v0
	v_sub_u32_e32 v3, 0, v0
	s_add_u32 s0, s38, 0x3500
	s_addc_u32 s1, s39, 0
	v_rcp_iflag_f32_e32 v2, v2
	s_mov_b64 s[6:7], -1
	v_mul_f32_e32 v2, 0x4f7ffffe, v2
	v_cvt_u32_f32_e32 v2, v2
	v_mul_lo_u32 v3, v3, v2
	v_mul_hi_u32 v3, v2, v3
	v_add_u32_e32 v2, v2, v3
	s_waitcnt vmcnt(0) lgkmcnt(0)
	v_mul_hi_u32 v2, v1, v2
	v_mul_lo_u32 v4, v2, v0
	v_add_u32_e32 v3, 1, v1
	v_sub_u32_e32 v1, v1, v4
	v_add_u32_e32 v5, 1, v2
	v_cmp_ge_u32_e32 vcc, v1, v0
	v_sub_u32_e32 v4, v1, v0
	s_nop 0
	v_cndmask_b32_e32 v2, v2, v5, vcc
	v_cndmask_b32_e32 v1, v1, v4, vcc
	v_add_u32_e32 v4, 1, v2
	v_cmp_ge_u32_e32 vcc, v1, v0
	s_nop 1
	v_cndmask_b32_e32 v2, v2, v4, vcc
	v_mad_u64_u32 v[0:1], s[4:5], v0, v2, v[0:1]
	v_cmp_ne_u32_e32 vcc, v3, v0
	v_mov_b64_e32 v[0:1], s[0:1]
	s_and_saveexec_b64 s[4:5], vcc
	s_cbranch_execz .LBB0_113
	v_mov_b64_e32 v[0:1], s[0:1]
	global_load_dword v0, v[0:1], off sc1
	s_mov_b64 s[10:11], 0
	s_waitcnt vmcnt(0) lgkmcnt(0)
	v_cmp_eq_u32_e32 vcc, v0, v2
	s_and_saveexec_b64 s[8:9], vcc
	s_cbranch_execz .LBB0_112
	s_add_u32 s6, s38, 0x200
	s_addc_u32 s7, s39, 0
	s_mov_b32 s26, 1
	s_branch .LBB0_105

; __device__ __forceinline__ unsigned xb_ld(unsigned* p)              { return __hip_atomic_load(p, __ATOMIC_RELAXED, __HIP_MEMORY_SCOPE_AGENT); }
; __device__ __forceinline__ unsigned xb_add(unsigned* p, unsigned v) { return __hip_atomic_fetch_add(p, v, __ATOMIC_RELAXED, __HIP_MEMORY_SCOPE_AGENT); }
; #define XB_SPIN(cond, bar) do { unsigned _sp = 0; while (cond) { __builtin_amdgcn_s_sleep(1); \
;     if ((++_sp & 255u) == 0u) { if (xb_ld(&(bar)[XB_TMO])) break; if (_sp > XB_SPIN_CAP) { atomicAdd(&(bar)[XB_TMO], 1u); break; } } } } while (0)
; __device__ __forceinline__ void xcd_barrier(const XcdBarrier& b) {
;     ...
;             const unsigned og = xb_add(&bar[XB_TOP], 1u);
;             const unsigned tg = og / nx;
;             if (og + 1u == (tg + 1u) * nx) xb_add(&bar[XB_TOPGEN], 1u);
;             else XB_SPIN(xb_ld(&bar[XB_TOPGEN]) == tg, bar);
.LBB0_107:
	v_mov_b64_e32 v[0:1], s[6:7]
	global_load_dword v0, v[0:1], off sc1
	s_mov_b64 s[18:19], 0
	s_mov_b64 s[16:17], -1
	s_waitcnt vmcnt(0) lgkmcnt(0)
	v_cmp_eq_u32_e32 vcc, 0, v0
	s_and_saveexec_b64 s[20:21], vcc
	s_cmp_lt_u32 s26, 0x40001
	s_cselect_b64 s[18:19], -1, 0
	s_xor_b64 s[16:17], exec, -1
	s_and_b64 s[18:19], s[18:19], exec
	s_or_b64 exec, exec, s[20:21]
	s_mov_b64 s[20:21], -1
	s_and_saveexec_b64 s[22:23], s[18:19]
	s_cbranch_execz .LBB0_104
.LBB0_110:
	v_mov_b64_e32 v[0:1], s[0:1]
	global_load_dword v0, v[0:1], off sc1
	s_add_i32 s26, s26, 1
	s_or_b64 s[16:17], s[16:17], exec
	s_waitcnt vmcnt(0) lgkmcnt(0)
	v_cmp_ne_u32_e32 vcc, v0, v2
	s_orn2_b64 s[20:21], vcc, exec
	s_branch .LBB0_104

; __device__ __forceinline__ unsigned xb_ld(unsigned* p)              { return __hip_atomic_load(p, __ATOMIC_RELAXED, __HIP_MEMORY_SCOPE_AGENT); }
; __device__ __forceinline__ unsigned xb_add(unsigned* p, unsigned v) { return __hip_atomic_fetch_add(p, v, __ATOMIC_RELAXED, __HIP_MEMORY_SCOPE_AGENT); }
; #define XB_SPIN(cond, bar) do { unsigned _sp = 0; while (cond) { __builtin_amdgcn_s_sleep(1); \
;     if ((++_sp & 255u) == 0u) { if (xb_ld(&(bar)[XB_TMO])) break; if (_sp > XB_SPIN_CAP) { atomicAdd(&(bar)[XB_TMO], 1u); break; } } } } while (0)
; __device__ __forceinline__ void xcd_barrier(const XcdBarrier& b) {
;     ...
;             if (og + 1u == (tg + 1u) * nx) xb_add(&bar[XB_TOPGEN], 1u);
;             else XB_SPIN(xb_ld(&bar[XB_TOPGEN]) == tg, bar);
;             __builtin_amdgcn_fence(__ATOMIC_ACQUIRE, "agent");
;             xb_add(&bar[XB_XGEN(b.x)], 1u);
;             asm volatile("s_waitcnt vmcnt(0)" ::: "memory");
.LBB0_113:
	s_or_b64 exec, exec, s[4:5]
	s_and_saveexec_b64 s[0:1], s[6:7]
	s_cbranch_execz .LBB0_115
	v_mov_b32_e32 v2, 1
	global_atomic_add v[0:1], v2, off
.LBB0_115:
	s_or_b64 exec, exec, s[0:1]
	v_mov_b32_e32 v0, s25
	v_add_co_u32_e32 v0, vcc, 0x2000, v0
	v_mov_b32_e32 v1, s24
	s_nop 0
	v_addc_co_u32_e32 v1, vcc, 0, v1, vcc
	v_mov_b32_e32 v2, 1
	s_waitcnt vmcnt(0) lgkmcnt(0)
	buffer_inv sc1
	global_atomic_add v[0:1], v2, off offset:1024
	s_waitcnt vmcnt(0)

; __device__ __forceinline__ unsigned xb_ld(unsigned* p)              { return __hip_atomic_load(p, __ATOMIC_RELAXED, __HIP_MEMORY_SCOPE_AGENT); }
; __device__ __forceinline__ void xcd_barrier_complete(unsigned* bar, unsigned x, unsigned& nloc, unsigned& nx) {
;     ...
;         for (unsigned j = 0; j < 16; ++j) { const unsigned c = xb_ld(&bar[XB_XCNT(j)]); sum += c; cnt += (c > 0u) ? 1u : 0u; mine = (j == x) ? c : mine; }
;         if (sum == G) break;
;         __builtin_amdgcn_s_sleep(1);
;         if ((++sp & 255u) == 0u) { if (xb_ld(&bar[XB_TMO])) break; if (sp > XB_SPIN_CAP) { atomicAdd(&bar[XB_TMO], 1u); break; } }
;     }
;     nloc = mine > 0u ? mine : 1u; nx = cnt > 0u ? cnt : 1u;
.LBB0_162:
	s_or_b64 exec, exec, s[0:1]
	s_xor_b64 s[0:1], s[4:5], -1
	s_and_saveexec_b64 s[4:5], s[0:1]
	s_xor_b64 s[0:1], exec, s[4:5]
	s_cbranch_execz .LBB0_164
	v_mov_b32_e32 v2, 1
	v_mov_b64_e32 v[0:1], s[36:37]
	global_atomic_add v[0:1], v2, off offset:512

; __device__ __forceinline__ unsigned xb_ld(unsigned* p)              { return __hip_atomic_load(p, __ATOMIC_RELAXED, __HIP_MEMORY_SCOPE_AGENT); }
; __device__ __forceinline__ unsigned xb_add(unsigned* p, unsigned v) { return __hip_atomic_fetch_add(p, v, __ATOMIC_RELAXED, __HIP_MEMORY_SCOPE_AGENT); }
; #define XB_SPIN(cond, bar) do { unsigned _sp = 0; while (cond) { __builtin_amdgcn_s_sleep(1); \
;     if ((++_sp & 255u) == 0u) { if (xb_ld(&(bar)[XB_TMO])) break; if (_sp > XB_SPIN_CAP) { atomicAdd(&(bar)[XB_TMO], 1u); break; } } } } while (0)
; __device__ __forceinline__ void xcd_barrier(const XcdBarrier& b) {
;     ...
;         const unsigned old = xb_add(&bar[XB_XSUB(b.x)], 1u);
;         const unsigned gen = old / nloc;
;         if (old + 1u == (gen + 1u) * nloc) {
;             __builtin_amdgcn_fence(__ATOMIC_RELEASE, "agent");
;             asm volatile("s_waitcnt vmcnt(0)" ::: "memory");
;             const unsigned og = xb_add(&bar[XB_TOP], 1u);
;             const unsigned tg = og / nx;
;             if (og + 1u == (tg + 1u) * nx) xb_add(&bar[XB_TOPGEN], 1u);
;             else XB_SPIN(xb_ld(&bar[XB_TOPGEN]) == tg, bar);
;             __builtin_amdgcn_fence(__ATOMIC_ACQUIRE, "agent");
;             xb_add(&bar[XB_XGEN(b.x)], 1u);
;             asm volatile("s_waitcnt vmcnt(0)" ::: "memory");
;         } else {
;             XB_SPIN(xb_ld(&bar[XB_XGEN(b.x)]) == gen, bar);
.LBB0_165:
	s_lshl_b32 s0, s3, 8
	s_add_u32 s24, s36, s0
	s_addc_u32 s3, s37, 0
	v_mov_b32_e32 v1, s24
	v_add_co_u32_e32 v4, vcc, 0x1000, v1
	v_mov_b32_e32 v1, s3
	s_nop 0
	v_addc_co_u32_e32 v5, vcc, 0, v1, vcc
	v_mov_b32_e32 v1, 1
	global_atomic_add v1, v[4:5], v1, off offset:1024 sc0
	v_cvt_f32_u32_e32 v3, v2
	v_sub_u32_e32 v4, 0, v2
	v_rcp_iflag_f32_e32 v3, v3
	s_nop 0
	v_mul_f32_e32 v3, 0x4f7ffffe, v3
	v_cvt_u32_f32_e32 v3, v3
	v_mul_lo_u32 v4, v4, v3
	v_mul_hi_u32 v4, v3, v4
	v_add_u32_e32 v3, v3, v4
	s_waitcnt vmcnt(0) lgkmcnt(0)
	v_mul_hi_u32 v3, v1, v3
	v_mul_lo_u32 v5, v3, v2
	v_add_u32_e32 v4, 1, v1
	v_sub_u32_e32 v1, v1, v5
	v_add_u32_e32 v6, 1, v3
	v_cmp_ge_u32_e32 vcc, v1, v2
	v_sub_u32_e32 v5, v1, v2
	s_nop 0
	v_cndmask_b32_e32 v3, v3, v6, vcc
	v_cndmask_b32_e32 v1, v1, v5, vcc
	v_add_u32_e32 v5, 1, v3
	v_cmp_ge_u32_e32 vcc, v1, v2
	s_nop 1
	v_cndmask_b32_e32 v1, v3, v5, vcc
	v_mad_u64_u32 v[2:3], s[0:1], v2, v1, v[2:3]
	v_cmp_ne_u32_e32 vcc, v4, v2
	s_and_saveexec_b64 s[0:1], vcc
	s_xor_b64 s[0:1], exec, s[0:1]
	s_cbranch_execz .LBB0_178
	v_mov_b32_e32 v0, s24
	v_add_co_u32_e32 v2, vcc, 0x2000, v0
	v_mov_b32_e32 v0, s3
	s_nop 0
	v_addc_co_u32_e32 v3, vcc, 0, v0, vcc
	global_load_dword v0, v[2:3], off offset:1024 sc1
	s_add_u32 s6, s24, 0x2400
	s_addc_u32 s7, s3, 0
	s_waitcnt vmcnt(0) lgkmcnt(0)
	v_cmp_eq_u32_e32 vcc, v0, v1
	s_and_saveexec_b64 s[4:5], vcc
	s_cbranch_execz .LBB0_177
	s_mov_b32 s25, 1
	s_mov_b64 s[8:9], 0
	s_branch .LBB0_169

; __device__ __forceinline__ unsigned xb_ld(unsigned* p)              { return __hip_atomic_load(p, __ATOMIC_RELAXED, __HIP_MEMORY_SCOPE_AGENT); }
; __device__ __forceinline__ unsigned xb_add(unsigned* p, unsigned v) { return __hip_atomic_fetch_add(p, v, __ATOMIC_RELAXED, __HIP_MEMORY_SCOPE_AGENT); }
; #define XB_SPIN(cond, bar) do { unsigned _sp = 0; while (cond) { __builtin_amdgcn_s_sleep(1); \
;     if ((++_sp & 255u) == 0u) { if (xb_ld(&(bar)[XB_TMO])) break; if (_sp > XB_SPIN_CAP) { atomicAdd(&(bar)[XB_TMO], 1u); break; } } } } while (0)
; __device__ __forceinline__ void xcd_barrier(const XcdBarrier& b) {
;     ...
;             else XB_SPIN(xb_ld(&bar[XB_TOPGEN]) == tg, bar);
;             __builtin_amdgcn_fence(__ATOMIC_ACQUIRE, "agent");
;             xb_add(&bar[XB_XGEN(b.x)], 1u);
;             asm volatile("s_waitcnt vmcnt(0)" ::: "memory");
;         } else {
;             XB_SPIN(xb_ld(&bar[XB_XGEN(b.x)]) == gen, bar);
.LBB0_169:
	s_and_b32 s18, s25, 0xff
	s_mov_b64 s[16:17], -1
	s_cmp_lg_u32 s18, 0
	s_mov_b64 s[18:19], -1
	s_sleep 1
	s_cbranch_scc1 .LBB0_173
	v_mov_b64_e32 v[2:3], s[36:37]
	global_load_dword v0, v[2:3], off offset:512 sc1
	s_mov_b64 s[18:19], 0
	s_mov_b64 s[20:21], -1
	s_waitcnt vmcnt(0) lgkmcnt(0)
	v_cmp_eq_u32_e32 vcc, 0, v0
	s_and_saveexec_b64 s[22:23], vcc
	s_cmp_lt_u32 s25, 0x40001
	s_cselect_b64 s[18:19], -1, 0
	s_xor_b64 s[20:21], exec, -1
	s_and_b64 s[18:19], s[18:19], exec
	s_or_b64 exec, exec, s[22:23]
.LBB0_173:
	s_andn2_b64 s[12:13], s[12:13], exec
	s_and_b64 s[20:21], s[20:21], exec
	s_or_b64 s[12:13], s[12:13], s[20:21]
	s_and_saveexec_b64 s[20:21], s[18:19]
	s_cbranch_execz .LBB0_168
	v_mov_b64_e32 v[2:3], s[6:7]
	global_load_dword v0, v[2:3], off sc1
	s_add_i32 s25, s25, 1
	s_or_b64 s[12:13], s[12:13], exec
	s_waitcnt vmcnt(0) lgkmcnt(0)
	v_cmp_ne_u32_e32 vcc, v0, v1
	s_orn2_b64 s[16:17], vcc, exec
	s_branch .LBB0_168
.LBB0_175:
	s_or_b64 exec, exec, s[8:9]
	s_xor_b64 s[6:7], s[10:11], -1
	s_and_saveexec_b64 s[8:9], s[6:7]
	s_xor_b64 s[8:9], exec, s[8:9]
	s_cbranch_execz .LBB0_177
	v_mov_b32_e32 v2, 1
	v_mov_b64_e32 v[0:1], s[36:37]
	global_atomic_add v[0:1], v2, off offset:512

; __device__ __forceinline__ unsigned xb_ld(unsigned* p)              { return __hip_atomic_load(p, __ATOMIC_RELAXED, __HIP_MEMORY_SCOPE_AGENT); }
; __device__ __forceinline__ unsigned xb_add(unsigned* p, unsigned v) { return __hip_atomic_fetch_add(p, v, __ATOMIC_RELAXED, __HIP_MEMORY_SCOPE_AGENT); }
; #define XB_SPIN(cond, bar) do { unsigned _sp = 0; while (cond) { __builtin_amdgcn_s_sleep(1); \
;     if ((++_sp & 255u) == 0u) { if (xb_ld(&(bar)[XB_TMO])) break; if (_sp > XB_SPIN_CAP) { atomicAdd(&(bar)[XB_TMO], 1u); break; } } } } while (0)
; __device__ __forceinline__ void xcd_barrier(const XcdBarrier& b) {
;     ...
;         if (old + 1u == (gen + 1u) * nloc) {
;             __builtin_amdgcn_fence(__ATOMIC_RELEASE, "agent");
;             asm volatile("s_waitcnt vmcnt(0)" ::: "memory");
;             const unsigned og = xb_add(&bar[XB_TOP], 1u);
;             const unsigned tg = og / nx;
;             if (og + 1u == (tg + 1u) * nx) xb_add(&bar[XB_TOPGEN], 1u);
;             else XB_SPIN(xb_ld(&bar[XB_TOPGEN]) == tg, bar);
.LBB0_178:
	s_andn2_saveexec_b64 s[0:1], s[0:1]
	s_cbranch_execz .LBB0_194
	v_mov_b32_e32 v1, s36
	v_add_co_u32_e32 v2, vcc, 0x3000, v1
	v_mov_b32_e32 v1, s37
	buffer_wbl2 sc1
	s_waitcnt vmcnt(0)
	v_addc_co_u32_e32 v3, vcc, 0, v1, vcc
	v_mov_b32_e32 v1, 1
	global_atomic_add v1, v[2:3], v1, off offset:1024 sc0
	v_cvt_f32_u32_e32 v2, v0
	v_sub_u32_e32 v3, 0, v0
	s_add_u32 s0, s36, 0x3500
	s_addc_u32 s1, s37, 0
	v_rcp_iflag_f32_e32 v2, v2
	s_mov_b64 s[6:7], -1
	v_mul_f32_e32 v2, 0x4f7ffffe, v2
	v_cvt_u32_f32_e32 v2, v2
	v_mul_lo_u32 v3, v3, v2
	v_mul_hi_u32 v3, v2, v3
	v_add_u32_e32 v2, v2, v3
	s_waitcnt vmcnt(0) lgkmcnt(0)
	v_mul_hi_u32 v2, v1, v2
	v_mul_lo_u32 v4, v2, v0
	v_add_u32_e32 v3, 1, v1
	v_sub_u32_e32 v1, v1, v4
	v_add_u32_e32 v5, 1, v2
	v_cmp_ge_u32_e32 vcc, v1, v0
	v_sub_u32_e32 v4, v1, v0
	s_nop 0
	v_cndmask_b32_e32 v2, v2, v5, vcc
	v_cndmask_b32_e32 v1, v1, v4, vcc
	v_add_u32_e32 v4, 1, v2
	v_cmp_ge_u32_e32 vcc, v1, v0
	s_nop 1
	v_cndmask_b32_e32 v2, v2, v4, vcc
	v_mad_u64_u32 v[0:1], s[4:5], v0, v2, v[0:1]
	v_cmp_ne_u32_e32 vcc, v3, v0
	v_mov_b64_e32 v[0:1], s[0:1]
	s_and_saveexec_b64 s[4:5], vcc
	s_cbranch_execz .LBB0_191
	v_mov_b64_e32 v[0:1], s[0:1]
	global_load_dword v0, v[0:1], off sc1
	s_mov_b64 s[10:11], 0
	s_waitcnt vmcnt(0) lgkmcnt(0)
	v_cmp_eq_u32_e32 vcc, v0, v2
	s_and_saveexec_b64 s[8:9], vcc
	s_cbranch_execz .LBB0_190
	s_add_u32 s6, s36, 0x200
	s_addc_u32 s7, s37, 0
	s_mov_b32 s25, 1
	s_branch .LBB0_183

; __device__ __forceinline__ unsigned xb_ld(unsigned* p)              { return __hip_atomic_load(p, __ATOMIC_RELAXED, __HIP_MEMORY_SCOPE_AGENT); }
; __device__ __forceinline__ unsigned xb_add(unsigned* p, unsigned v) { return __hip_atomic_fetch_add(p, v, __ATOMIC_RELAXED, __HIP_MEMORY_SCOPE_AGENT); }
; #define XB_SPIN(cond, bar) do { unsigned _sp = 0; while (cond) { __builtin_amdgcn_s_sleep(1); \
;     if ((++_sp & 255u) == 0u) { if (xb_ld(&(bar)[XB_TMO])) break; if (_sp > XB_SPIN_CAP) { atomicAdd(&(bar)[XB_TMO], 1u); break; } } } } while (0)
; __device__ __forceinline__ void xcd_barrier(const XcdBarrier& b) {
;     ...
;             const unsigned og = xb_add(&bar[XB_TOP], 1u);
;             const unsigned tg = og / nx;
;             if (og + 1u == (tg + 1u) * nx) xb_add(&bar[XB_TOPGEN], 1u);
;             else XB_SPIN(xb_ld(&bar[XB_TOPGEN]) == tg, bar);
.LBB0_185:
	v_mov_b64_e32 v[0:1], s[6:7]
	global_load_dword v0, v[0:1], off sc1
	s_mov_b64 s[18:19], 0
	s_mov_b64 s[16:17], -1
	s_waitcnt vmcnt(0) lgkmcnt(0)
	v_cmp_eq_u32_e32 vcc, 0, v0
	s_and_saveexec_b64 s[20:21], vcc
	s_cmp_lt_u32 s25, 0x40001
	s_cselect_b64 s[18:19], -1, 0
	s_xor_b64 s[16:17], exec, -1
	s_and_b64 s[18:19], s[18:19], exec
	s_or_b64 exec, exec, s[20:21]
	s_mov_b64 s[20:21], -1
	s_and_saveexec_b64 s[22:23], s[18:19]
	s_cbranch_execz .LBB0_182
.LBB0_188:
	v_mov_b64_e32 v[0:1], s[0:1]
	global_load_dword v0, v[0:1], off sc1
	s_add_i32 s25, s25, 1
	s_or_b64 s[16:17], s[16:17], exec
	s_waitcnt vmcnt(0) lgkmcnt(0)
	v_cmp_ne_u32_e32 vcc, v0, v2
	s_orn2_b64 s[20:21], vcc, exec
	s_branch .LBB0_182

; __device__ __forceinline__ unsigned xb_add(unsigned* p, unsigned v) { return __hip_atomic_fetch_add(p, v, __ATOMIC_RELAXED, __HIP_MEMORY_SCOPE_AGENT); }
; __device__ __forceinline__ void xcd_barrier(const XcdBarrier& b) {
;     ...
;             __builtin_amdgcn_fence(__ATOMIC_ACQUIRE, "agent");
;             xb_add(&bar[XB_XGEN(b.x)], 1u);
;             asm volatile("s_waitcnt vmcnt(0)" ::: "memory");
.LBB0_193:
	s_or_b64 exec, exec, s[0:1]
	v_mov_b32_e32 v0, s24
	v_add_co_u32_e32 v0, vcc, 0x2000, v0
	v_mov_b32_e32 v1, s3
	s_nop 0
	v_addc_co_u32_e32 v1, vcc, 0, v1, vcc
	v_mov_b32_e32 v2, 1
	s_waitcnt vmcnt(0) lgkmcnt(0)
	buffer_inv sc1
	global_atomic_add v[0:1], v2, off offset:1024
	s_waitcnt vmcnt(0)

; __device__ __forceinline__ unsigned xb_add(unsigned* p, unsigned v) { return __hip_atomic_fetch_add(p, v, __ATOMIC_RELAXED, __HIP_MEMORY_SCOPE_AGENT); }
; __device__ __forceinline__ void xcd_barrier(const XcdBarrier& b) {
;     ...
;             __builtin_amdgcn_fence(__ATOMIC_ACQUIRE, "agent");
;             xb_add(&bar[XB_XGEN(b.x)], 1u);
;             asm volatile("s_waitcnt vmcnt(0)" ::: "memory");
.LBB0_195:
	s_or_b64 exec, exec, s[0:1]
	v_mov_b32_e32 v0, s25
	v_add_co_u32_e32 v0, vcc, 0x2000, v0
	v_mov_b32_e32 v1, s24
	s_nop 0
	v_addc_co_u32_e32 v1, vcc, 0, v1, vcc
	s_waitcnt vmcnt(0) lgkmcnt(0)
	buffer_inv sc1
	global_atomic_add v[0:1], v225, off offset:1024
	s_waitcnt vmcnt(0)

; __device__ __forceinline__ float sigm(float v) { return __builtin_amdgcn_rcpf(1.f + __builtin_amdgcn_exp2f(-1.4426950408889634f * v)); }
;     __device__ __forceinline__ void operator()(const f32x4 (&acc)[2][2][4][2], const Unit& u, int wr, int wc, int fr, int fq) const {
;         const int pn = u.pn, pm = u.pm;
;         const bool isctx = pm >= 64;
;         const int v = isctx ? 2 : (pm >> 5);
;         const int cb = pn * 256 + wc * 32 + 8 * fq;
;         f32x4 bv[2][2];
; #pragma unroll
;         for (int bj = 0; bj < 2; ++bj)
; #pragma unroll
;             for (int n = 0; n < 2; ++n) bv[bj][n] = *(const f32x4*)(bias + v * INW + cb + 128 * bj + 4 * n);
;     ...
;             const int ch0 = 128 * (pn - 7) + 32 * wc + 8 * fq;
; #pragma unroll
;             for (int ai = 0; ai < 2; ++ai)
; #pragma unroll
;                 for (int m = 0; m < 4; ++m) {
;                     const int row = pm * 256 + ai * 128 + wr * 64 + m * 16 + fr;
;                     const float rinv = rsqrtf(rowsq[row] * (1.f / DM) + EPSN);
; #pragma unroll
;                     for (int n = 0; n < 2; ++n) {
;                         const f32x4 a = acc[ai][0][m][n] * rinv + bv[0][n], g = acc[ai][1][m][n] * rinv + bv[1][n];
;                         f32x4 o;
; #pragma unroll
;                         for (int j = 0; j < 4; ++j) o[j] = a[j] * sigm(g[j]);
;                         *(f32x4*)(uconv + (size_t)row * 256 + ch0 + 4 * n) = o;
;                     }
.LBB0_215:
	s_min_i32 s0, s6, 64
	s_lshr_b32 s0, s0, 5
	s_mulk_i32 s0, 0x900
	s_ashr_i32 s1, s0, 31
	s_lshl_b64 s[0:1], s[0:1], 2
	v_lshl_or_b32 v32, s36, 8, v197
	s_add_u32 s0, s52, s0
	s_addc_u32 s1, s53, s1
	v_ashrrev_i32_e32 v33, 31, v32
	v_lshl_add_u64 v[32:33], v[32:33], 2, s[0:1]
	global_load_dwordx4 v[44:47], v[32:33], off
	global_load_dwordx4 v[40:43], v[32:33], off offset:16
	global_load_dwordx4 v[36:39], v[32:33], off offset:512
	s_nop 0
	global_load_dwordx4 v[32:35], v[32:33], off offset:528
	s_cmp_gt_i32 s6, 63
	s_cselect_b64 s[4:5], -1, 0
	s_cmp_lt_i32 s6, 64
	s_cselect_b64 s[54:55], -1, 0
	s_cmp_gt_i32 s36, 3
	s_mov_b64 s[0:1], -1
	s_cbranch_scc0 .LBB0_226
	s_cmp_gt_u32 s36, 5
	s_cbranch_scc0 .LBB0_222
	s_cmp_lg_u32 s36, 6
	v_lshl_add_u32 v144, s6, 8, v173
	s_cbranch_scc0 .LBB0_219
	v_ashrrev_i32_e32 v145, 31, v144
	v_lshl_add_u64 v[146:147], v[144:145], 2, s[16:17]
	global_load_dword v148, v[146:147], off
	global_load_dword v214, v[146:147], off offset:64
	global_load_dword v215, v[146:147], off offset:128
	global_load_dword v216, v[146:147], off offset:192
	global_load_dword v217, v[146:147], off offset:512
	global_load_dword v218, v[146:147], off offset:576
	global_load_dword v219, v[146:147], off offset:640
	global_load_dword v220, v[146:147], off offset:704
	v_lshl_add_u32 v176, s36, 7, v198
	s_mov_b64 s[0:1], 0
	s_waitcnt vmcnt(0) lgkmcnt(0)
	v_fmamk_f32 v148, v148, 0x3a800000, v224
	v_cmp_gt_f32_e32 vcc, s33, v148
	v_mul_f32_e32 v149, 0x4b800000, v148
	s_nop 0
	v_cndmask_b32_e32 v148, v148, v149, vcc
	v_rsq_f32_e32 v148, v148
	s_nop 0
	v_mul_f32_e32 v149, 0x45800000, v148
	v_cndmask_b32_e32 v150, v148, v149, vcc
	v_lshlrev_b64 v[148:149], 10, v[144:145]
	v_fma_f32 v145, v132, v150, v36
	v_mul_f32_e32 v145, 0xbfb8aa3b, v145
	v_exp_f32_e32 v145, v145
	v_pk_fma_f32 v[158:159], v[140:141], v[150:151], v[44:45] op_sel_hi:[1,0,1]
	v_pk_fma_f32 v[156:157], v[142:143], v[150:151], v[46:47] op_sel_hi:[1,0,1]
	v_add_f32_e32 v145, 1.0, v145
	v_rcp_f32_e32 v152, v145
	v_fma_f32 v145, v133, v150, v37
	v_mul_f32_e32 v145, 0xbfb8aa3b, v145
	v_exp_f32_e32 v145, v145
	s_nop 0
	v_add_f32_e32 v145, 1.0, v145
	v_rcp_f32_e32 v153, v145
	v_fma_f32 v145, v134, v150, v38
	v_mul_f32_e32 v145, 0xbfb8aa3b, v145
	v_exp_f32_e32 v145, v145
	s_nop 0
	v_add_f32_e32 v145, 1.0, v145
	v_rcp_f32_e32 v154, v145
	v_fma_f32 v145, v135, v150, v39
	v_mul_f32_e32 v145, 0xbfb8aa3b, v145
	v_exp_f32_e32 v145, v145
	s_nop 0
	v_add_f32_e32 v145, 1.0, v145
	v_rcp_f32_e32 v155, v145
	v_fma_f32 v145, v128, v150, v32
	v_mul_f32_e32 v145, 0xbfb8aa3b, v145
	v_exp_f32_e32 v145, v145
	v_pk_mul_f32 v[156:157], v[156:157], v[154:155]
	v_pk_mul_f32 v[154:155], v[158:159], v[152:153]
	v_lshl_add_u64 v[152:153], s[20:21], 0, v[148:149]
	v_lshlrev_b64 v[148:149], 2, v[176:177]
	v_lshl_add_u64 v[152:153], v[152:153], 0, v[148:149]
	v_add_f32_e32 v145, 1.0, v145
	global_store_dwordx4 v[152:153], v[154:157], off
	v_pk_fma_f32 v[158:159], v[136:137], v[150:151], v[40:41] op_sel_hi:[1,0,1]
	s_nop 0
	v_rcp_f32_e32 v154, v145
	v_fma_f32 v145, v129, v150, v33
	v_mul_f32_e32 v145, 0xbfb8aa3b, v145
	v_exp_f32_e32 v145, v145
	s_nop 0
	v_add_f32_e32 v145, 1.0, v145
	v_rcp_f32_e32 v155, v145
	v_fma_f32 v145, v130, v150, v34
	v_mul_f32_e32 v145, 0xbfb8aa3b, v145
	v_exp_f32_e32 v145, v145
	v_pk_mul_f32 v[154:155], v[158:159], v[154:155]
	v_add_f32_e32 v145, 1.0, v145
	v_rcp_f32_e32 v156, v145
	v_fma_f32 v145, v131, v150, v35
	v_mul_f32_e32 v145, 0xbfb8aa3b, v145
	v_exp_f32_e32 v145, v145
	v_pk_fma_f32 v[150:151], v[138:139], v[150:151], v[42:43] op_sel_hi:[1,0,1]
	v_add_f32_e32 v145, 1.0, v145
	v_rcp_f32_e32 v157, v145
	s_nop 0
	v_pk_mul_f32 v[156:157], v[150:151], v[156:157]
	global_store_dwordx4 v[152:153], v[154:157], off offset:16
	s_nop 1
	v_or_b32_e32 v150, 16, v144
	v_ashrrev_i32_e32 v151, 31, v150
	v_lshlrev_b64 v[150:151], 10, v[150:151]
	v_lshl_add_u64 v[150:151], s[20:21], 0, v[150:151]
	v_lshl_add_u64 v[150:151], v[150:151], 0, v[148:149]
	v_fmamk_f32 v145, v214, 0x3a800000, v224
	v_cmp_gt_f32_e32 vcc, s33, v145
	v_mul_f32_e32 v152, 0x4b800000, v145
	s_nop 0
	v_cndmask_b32_e32 v145, v145, v152, vcc
	v_rsq_f32_e32 v145, v145
	s_nop 0
	v_mul_f32_e32 v152, 0x45800000, v145
	v_cndmask_b32_e32 v152, v145, v152, vcc
	v_fma_f32 v145, v116, v152, v36
	v_mul_f32_e32 v145, 0xbfb8aa3b, v145
	v_exp_f32_e32 v145, v145
	v_pk_fma_f32 v[158:159], v[124:125], v[152:153], v[44:45] op_sel_hi:[1,0,1]
	v_pk_fma_f32 v[186:187], v[126:127], v[152:153], v[46:47] op_sel_hi:[1,0,1]
	v_add_f32_e32 v145, 1.0, v145
	v_rcp_f32_e32 v154, v145
	v_fma_f32 v145, v117, v152, v37
	v_mul_f32_e32 v145, 0xbfb8aa3b, v145
	v_exp_f32_e32 v145, v145
	s_nop 0
	v_add_f32_e32 v145, 1.0, v145
	v_rcp_f32_e32 v155, v145
	v_fma_f32 v145, v118, v152, v38
	v_mul_f32_e32 v145, 0xbfb8aa3b, v145
	v_exp_f32_e32 v145, v145
	v_pk_mul_f32 v[154:155], v[158:159], v[154:155]
	v_pk_fma_f32 v[158:159], v[120:121], v[152:153], v[40:41] op_sel_hi:[1,0,1]
	v_add_f32_e32 v145, 1.0, v145
	v_rcp_f32_e32 v156, v145
	v_fma_f32 v145, v119, v152, v39
	v_mul_f32_e32 v145, 0xbfb8aa3b, v145
	v_exp_f32_e32 v145, v145
	s_nop 0
	v_add_f32_e32 v145, 1.0, v145
	v_rcp_f32_e32 v157, v145
	v_fma_f32 v145, v112, v152, v32
	v_mul_f32_e32 v145, 0xbfb8aa3b, v145
	v_exp_f32_e32 v145, v145
	v_pk_mul_f32 v[156:157], v[186:187], v[156:157]
	global_store_dwordx4 v[150:151], v[154:157], off
	v_add_f32_e32 v145, 1.0, v145
	s_nop 0
	v_rcp_f32_e32 v156, v145
	v_fma_f32 v145, v113, v152, v33
	v_mul_f32_e32 v145, 0xbfb8aa3b, v145
	v_exp_f32_e32 v145, v145
	s_nop 0
	v_add_f32_e32 v145, 1.0, v145
	v_rcp_f32_e32 v157, v145
	v_fma_f32 v145, v114, v152, v34
	v_mul_f32_e32 v145, 0xbfb8aa3b, v145
; __device__ __forceinline__ float sigm(float v) { return __builtin_amdgcn_rcpf(1.f + __builtin_amdgcn_exp2f(-1.4426950408889634f * v)); }
;     __device__ __forceinline__ void operator()(const f32x4 (&acc)[2][2][4][2], const Unit& u, int wr, int wc, int fr, int fq) const {
;     ...
;                 for (int m = 0; m < 4; ++m) {
;                     const int row = pm * 256 + ai * 128 + wr * 64 + m * 16 + fr;
;                     const float rinv = rsqrtf(rowsq[row] * (1.f / DM) + EPSN);
; #pragma unroll
;                     for (int n = 0; n < 2; ++n) {
;                         const f32x4 a = acc[ai][0][m][n] * rinv + bv[0][n], g = acc[ai][1][m][n] * rinv + bv[1][n];
;                         f32x4 o;
; #pragma unroll
;                         for (int j = 0; j < 4; ++j) o[j] = a[j] * sigm(g[j]);
;                         *(f32x4*)(uconv + (size_t)row * 256 + ch0 + 4 * n) = o;
;                     }
	v_exp_f32_e32 v145, v145
	s_nop 0
	v_add_f32_e32 v145, 1.0, v145
	v_rcp_f32_e32 v154, v145
	v_fma_f32 v145, v115, v152, v35
	v_mul_f32_e32 v145, 0xbfb8aa3b, v145
	v_exp_f32_e32 v145, v145
	v_pk_fma_f32 v[152:153], v[122:123], v[152:153], v[42:43] op_sel_hi:[1,0,1]
	v_add_f32_e32 v145, 1.0, v145
	v_rcp_f32_e32 v155, v145
	s_nop 0
	v_pk_mul_f32 v[154:155], v[152:153], v[154:155]
	v_pk_mul_f32 v[152:153], v[158:159], v[156:157]
	global_store_dwordx4 v[150:151], v[152:155], off offset:16
	s_nop 1
	v_or_b32_e32 v150, 32, v144
	v_ashrrev_i32_e32 v151, 31, v150
	v_lshlrev_b64 v[150:151], 10, v[150:151]
	v_lshl_add_u64 v[150:151], s[20:21], 0, v[150:151]
	v_lshl_add_u64 v[150:151], v[150:151], 0, v[148:149]
	v_fmamk_f32 v145, v215, 0x3a800000, v224
	v_cmp_gt_f32_e32 vcc, s33, v145
	v_mul_f32_e32 v152, 0x4b800000, v145
	s_nop 0
	v_cndmask_b32_e32 v145, v145, v152, vcc
	v_rsq_f32_e32 v145, v145
	s_nop 0
	v_mul_f32_e32 v152, 0x45800000, v145
	v_cndmask_b32_e32 v152, v145, v152, vcc
	v_fma_f32 v145, v100, v152, v36
	v_mul_f32_e32 v145, 0xbfb8aa3b, v145
	v_exp_f32_e32 v145, v145
	v_pk_fma_f32 v[158:159], v[108:109], v[152:153], v[44:45] op_sel_hi:[1,0,1]
	v_pk_fma_f32 v[186:187], v[110:111], v[152:153], v[46:47] op_sel_hi:[1,0,1]
	v_add_f32_e32 v145, 1.0, v145
	v_rcp_f32_e32 v154, v145
	v_fma_f32 v145, v101, v152, v37
	v_mul_f32_e32 v145, 0xbfb8aa3b, v145
	v_exp_f32_e32 v145, v145
	s_nop 0
	v_add_f32_e32 v145, 1.0, v145
	v_rcp_f32_e32 v155, v145
	v_fma_f32 v145, v102, v152, v38
	v_mul_f32_e32 v145, 0xbfb8aa3b, v145
	v_exp_f32_e32 v145, v145
	v_pk_mul_f32 v[154:155], v[158:159], v[154:155]
	v_pk_fma_f32 v[158:159], v[104:105], v[152:153], v[40:41] op_sel_hi:[1,0,1]
	v_add_f32_e32 v145, 1.0, v145
	v_rcp_f32_e32 v156, v145
	v_fma_f32 v145, v103, v152, v39
	v_mul_f32_e32 v145, 0xbfb8aa3b, v145
	v_exp_f32_e32 v145, v145
	s_nop 0
	v_add_f32_e32 v145, 1.0, v145
	v_rcp_f32_e32 v157, v145
	v_fma_f32 v145, v96, v152, v32
	v_mul_f32_e32 v145, 0xbfb8aa3b, v145
	v_exp_f32_e32 v145, v145
	v_pk_mul_f32 v[156:157], v[186:187], v[156:157]
	global_store_dwordx4 v[150:151], v[154:157], off
	v_add_f32_e32 v145, 1.0, v145
	s_nop 0
	v_rcp_f32_e32 v156, v145
	v_fma_f32 v145, v97, v152, v33
	v_mul_f32_e32 v145, 0xbfb8aa3b, v145
	v_exp_f32_e32 v145, v145
	s_nop 0
	v_add_f32_e32 v145, 1.0, v145
	v_rcp_f32_e32 v157, v145
	v_fma_f32 v145, v98, v152, v34
	v_mul_f32_e32 v145, 0xbfb8aa3b, v145
	v_exp_f32_e32 v145, v145
	s_nop 0
	v_add_f32_e32 v145, 1.0, v145
	v_rcp_f32_e32 v154, v145
	v_fma_f32 v145, v99, v152, v35
	v_mul_f32_e32 v145, 0xbfb8aa3b, v145
	v_exp_f32_e32 v145, v145
	v_pk_fma_f32 v[152:153], v[106:107], v[152:153], v[42:43] op_sel_hi:[1,0,1]
	v_add_f32_e32 v145, 1.0, v145
	v_rcp_f32_e32 v155, v145
	s_nop 0
	v_pk_mul_f32 v[154:155], v[152:153], v[154:155]
	v_pk_mul_f32 v[152:153], v[158:159], v[156:157]
	global_store_dwordx4 v[150:151], v[152:155], off offset:16
	s_nop 1
	v_or_b32_e32 v150, 48, v144
	v_ashrrev_i32_e32 v151, 31, v150
	v_lshlrev_b64 v[150:151], 10, v[150:151]
	v_lshl_add_u64 v[150:151], s[20:21], 0, v[150:151]
	v_lshl_add_u64 v[150:151], v[150:151], 0, v[148:149]
	v_fmamk_f32 v145, v216, 0x3a800000, v224
	v_cmp_gt_f32_e32 vcc, s33, v145
	v_mul_f32_e32 v152, 0x4b800000, v145
	s_nop 0
	v_cndmask_b32_e32 v145, v145, v152, vcc
	v_rsq_f32_e32 v145, v145
	s_nop 0
	v_mul_f32_e32 v152, 0x45800000, v145
	v_cndmask_b32_e32 v152, v145, v152, vcc
	v_fma_f32 v145, v84, v152, v36
	v_mul_f32_e32 v145, 0xbfb8aa3b, v145
	v_exp_f32_e32 v145, v145
	v_pk_fma_f32 v[158:159], v[92:93], v[152:153], v[44:45] op_sel_hi:[1,0,1]
	v_pk_fma_f32 v[186:187], v[94:95], v[152:153], v[46:47] op_sel_hi:[1,0,1]
	v_add_f32_e32 v145, 1.0, v145
	v_rcp_f32_e32 v154, v145
	v_fma_f32 v145, v85, v152, v37
	v_mul_f32_e32 v145, 0xbfb8aa3b, v145
	v_exp_f32_e32 v145, v145
	s_nop 0
	v_add_f32_e32 v145, 1.0, v145
	v_rcp_f32_e32 v155, v145
	v_fma_f32 v145, v86, v152, v38
	v_mul_f32_e32 v145, 0xbfb8aa3b, v145
	v_exp_f32_e32 v145, v145
	v_pk_mul_f32 v[154:155], v[158:159], v[154:155]
	v_pk_fma_f32 v[158:159], v[88:89], v[152:153], v[40:41] op_sel_hi:[1,0,1]
	v_add_f32_e32 v145, 1.0, v145
	v_rcp_f32_e32 v156, v145
	v_fma_f32 v145, v87, v152, v39
	v_mul_f32_e32 v145, 0xbfb8aa3b, v145
	v_exp_f32_e32 v145, v145
	s_nop 0
	v_add_f32_e32 v145, 1.0, v145
	v_rcp_f32_e32 v157, v145
	v_fma_f32 v145, v80, v152, v32
	v_mul_f32_e32 v145, 0xbfb8aa3b, v145
	v_exp_f32_e32 v145, v145
	v_pk_mul_f32 v[156:157], v[186:187], v[156:157]
	global_store_dwordx4 v[150:151], v[154:157], off
	v_add_f32_e32 v145, 1.0, v145
	s_nop 0
	v_rcp_f32_e32 v156, v145
	v_fma_f32 v145, v81, v152, v33
	v_mul_f32_e32 v145, 0xbfb8aa3b, v145
	v_exp_f32_e32 v145, v145
	s_nop 0
	v_add_f32_e32 v145, 1.0, v145
	v_rcp_f32_e32 v157, v145
	v_fma_f32 v145, v82, v152, v34
	v_mul_f32_e32 v145, 0xbfb8aa3b, v145
	v_exp_f32_e32 v145, v145
	s_nop 0
	v_add_f32_e32 v145, 1.0, v145
	v_rcp_f32_e32 v154, v145
	v_fma_f32 v145, v83, v152, v35
	v_mul_f32_e32 v145, 0xbfb8aa3b, v145
	v_exp_f32_e32 v145, v145
	v_pk_fma_f32 v[152:153], v[90:91], v[152:153], v[42:43] op_sel_hi:[1,0,1]
	v_add_f32_e32 v145, 1.0, v145
	v_rcp_f32_e32 v155, v145
	s_nop 0
	v_pk_mul_f32 v[154:155], v[152:153], v[154:155]
	v_pk_mul_f32 v[152:153], v[158:159], v[156:157]
	global_store_dwordx4 v[150:151], v[152:155], off offset:16
	s_nop 1
	v_add_u32_e32 v150, 0x80, v144
	v_ashrrev_i32_e32 v151, 31, v150
	v_lshlrev_b64 v[150:151], 10, v[150:151]
	v_lshl_add_u64 v[150:151], s[20:21], 0, v[150:151]
	v_lshl_add_u64 v[150:151], v[150:151], 0, v[148:149]
	v_fmamk_f32 v145, v217, 0x3a800000, v224
	v_cmp_gt_f32_e32 vcc, s33, v145
	v_mul_f32_e32 v152, 0x4b800000, v145
	s_nop 0
	v_cndmask_b32_e32 v145, v145, v152, vcc
; __device__ __forceinline__ float sigm(float v) { return __builtin_amdgcn_rcpf(1.f + __builtin_amdgcn_exp2f(-1.4426950408889634f * v)); }
;     __device__ __forceinline__ void operator()(const f32x4 (&acc)[2][2][4][2], const Unit& u, int wr, int wc, int fr, int fq) const {
;     ...
;                 for (int m = 0; m < 4; ++m) {
;                     const int row = pm * 256 + ai * 128 + wr * 64 + m * 16 + fr;
;                     const float rinv = rsqrtf(rowsq[row] * (1.f / DM) + EPSN);
; #pragma unroll
;                     for (int n = 0; n < 2; ++n) {
;                         const f32x4 a = acc[ai][0][m][n] * rinv + bv[0][n], g = acc[ai][1][m][n] * rinv + bv[1][n];
;                         f32x4 o;
; #pragma unroll
;                         for (int j = 0; j < 4; ++j) o[j] = a[j] * sigm(g[j]);
;                         *(f32x4*)(uconv + (size_t)row * 256 + ch0 + 4 * n) = o;
;                     }
	v_rsq_f32_e32 v145, v145
	s_nop 0
	v_mul_f32_e32 v152, 0x45800000, v145
	v_cndmask_b32_e32 v152, v145, v152, vcc
	v_fma_f32 v145, v68, v152, v36
	v_mul_f32_e32 v145, 0xbfb8aa3b, v145
	v_exp_f32_e32 v145, v145
	v_pk_fma_f32 v[158:159], v[76:77], v[152:153], v[44:45] op_sel_hi:[1,0,1]
	v_pk_fma_f32 v[186:187], v[78:79], v[152:153], v[46:47] op_sel_hi:[1,0,1]
	v_add_f32_e32 v145, 1.0, v145
	v_rcp_f32_e32 v154, v145
	v_fma_f32 v145, v69, v152, v37
	v_mul_f32_e32 v145, 0xbfb8aa3b, v145
	v_exp_f32_e32 v145, v145
	s_nop 0
	v_add_f32_e32 v145, 1.0, v145
	v_rcp_f32_e32 v155, v145
	v_fma_f32 v145, v70, v152, v38
	v_mul_f32_e32 v145, 0xbfb8aa3b, v145
	v_exp_f32_e32 v145, v145
	v_pk_mul_f32 v[154:155], v[158:159], v[154:155]
	v_pk_fma_f32 v[158:159], v[72:73], v[152:153], v[40:41] op_sel_hi:[1,0,1]
	v_add_f32_e32 v145, 1.0, v145
	v_rcp_f32_e32 v156, v145
	v_fma_f32 v145, v71, v152, v39
	v_mul_f32_e32 v145, 0xbfb8aa3b, v145
	v_exp_f32_e32 v145, v145
	s_nop 0
	v_add_f32_e32 v145, 1.0, v145
	v_rcp_f32_e32 v157, v145
	v_fma_f32 v145, v64, v152, v32
	v_mul_f32_e32 v145, 0xbfb8aa3b, v145
	v_exp_f32_e32 v145, v145
	v_pk_mul_f32 v[156:157], v[186:187], v[156:157]
	global_store_dwordx4 v[150:151], v[154:157], off
	v_add_f32_e32 v145, 1.0, v145
	s_nop 0
	v_rcp_f32_e32 v156, v145
	v_fma_f32 v145, v65, v152, v33
	v_mul_f32_e32 v145, 0xbfb8aa3b, v145
	v_exp_f32_e32 v145, v145
	s_nop 0
	v_add_f32_e32 v145, 1.0, v145
	v_rcp_f32_e32 v157, v145
	v_fma_f32 v145, v66, v152, v34
	v_mul_f32_e32 v145, 0xbfb8aa3b, v145
	v_exp_f32_e32 v145, v145
	s_nop 0
	v_add_f32_e32 v145, 1.0, v145
	v_rcp_f32_e32 v154, v145
	v_fma_f32 v145, v67, v152, v35
	v_mul_f32_e32 v145, 0xbfb8aa3b, v145
	v_exp_f32_e32 v145, v145
	v_pk_fma_f32 v[152:153], v[74:75], v[152:153], v[42:43] op_sel_hi:[1,0,1]
	v_add_f32_e32 v145, 1.0, v145
	v_rcp_f32_e32 v155, v145
	s_nop 0
	v_pk_mul_f32 v[154:155], v[152:153], v[154:155]
	v_pk_mul_f32 v[152:153], v[158:159], v[156:157]
	global_store_dwordx4 v[150:151], v[152:155], off offset:16
	s_nop 1
	v_add_u32_e32 v150, 0x90, v144
	v_ashrrev_i32_e32 v151, 31, v150
	v_lshlrev_b64 v[150:151], 10, v[150:151]
	v_lshl_add_u64 v[150:151], s[20:21], 0, v[150:151]
	v_lshl_add_u64 v[150:151], v[150:151], 0, v[148:149]
	v_fmamk_f32 v145, v218, 0x3a800000, v224
	v_cmp_gt_f32_e32 vcc, s33, v145
	v_mul_f32_e32 v152, 0x4b800000, v145
	s_nop 0
	v_cndmask_b32_e32 v145, v145, v152, vcc
	v_rsq_f32_e32 v145, v145
	s_nop 0
	v_mul_f32_e32 v152, 0x45800000, v145
	v_cndmask_b32_e32 v152, v145, v152, vcc
	v_fma_f32 v145, v52, v152, v36
	v_mul_f32_e32 v145, 0xbfb8aa3b, v145
	v_exp_f32_e32 v145, v145
	v_pk_fma_f32 v[158:159], v[60:61], v[152:153], v[44:45] op_sel_hi:[1,0,1]
	v_pk_fma_f32 v[186:187], v[62:63], v[152:153], v[46:47] op_sel_hi:[1,0,1]
	v_add_f32_e32 v145, 1.0, v145
	v_rcp_f32_e32 v154, v145
	v_fma_f32 v145, v53, v152, v37
	v_mul_f32_e32 v145, 0xbfb8aa3b, v145
	v_exp_f32_e32 v145, v145
	s_nop 0
	v_add_f32_e32 v145, 1.0, v145
	v_rcp_f32_e32 v155, v145
	v_fma_f32 v145, v54, v152, v38
	v_mul_f32_e32 v145, 0xbfb8aa3b, v145
	v_exp_f32_e32 v145, v145
	v_pk_mul_f32 v[154:155], v[158:159], v[154:155]
	v_pk_fma_f32 v[158:159], v[56:57], v[152:153], v[40:41] op_sel_hi:[1,0,1]
	v_add_f32_e32 v145, 1.0, v145
	v_rcp_f32_e32 v156, v145
	v_fma_f32 v145, v55, v152, v39
	v_mul_f32_e32 v145, 0xbfb8aa3b, v145
	v_exp_f32_e32 v145, v145
	s_nop 0
	v_add_f32_e32 v145, 1.0, v145
	v_rcp_f32_e32 v157, v145
	v_fma_f32 v145, v48, v152, v32
	v_mul_f32_e32 v145, 0xbfb8aa3b, v145
	v_exp_f32_e32 v145, v145
	v_pk_mul_f32 v[156:157], v[186:187], v[156:157]
	global_store_dwordx4 v[150:151], v[154:157], off
	v_add_f32_e32 v145, 1.0, v145
	s_nop 0
	v_rcp_f32_e32 v156, v145
	v_fma_f32 v145, v49, v152, v33
	v_mul_f32_e32 v145, 0xbfb8aa3b, v145
	v_exp_f32_e32 v145, v145
	s_nop 0
	v_add_f32_e32 v145, 1.0, v145
	v_rcp_f32_e32 v157, v145
	v_fma_f32 v145, v50, v152, v34
	v_mul_f32_e32 v145, 0xbfb8aa3b, v145
	v_exp_f32_e32 v145, v145
	s_nop 0
	v_add_f32_e32 v145, 1.0, v145
	v_rcp_f32_e32 v154, v145
	v_fma_f32 v145, v51, v152, v35
	v_mul_f32_e32 v145, 0xbfb8aa3b, v145
	v_exp_f32_e32 v145, v145
	v_pk_fma_f32 v[152:153], v[58:59], v[152:153], v[42:43] op_sel_hi:[1,0,1]
	v_add_f32_e32 v145, 1.0, v145
	v_rcp_f32_e32 v155, v145
	s_nop 0
	v_pk_mul_f32 v[154:155], v[152:153], v[154:155]
	v_pk_mul_f32 v[152:153], v[158:159], v[156:157]
	global_store_dwordx4 v[150:151], v[152:155], off offset:16
	s_nop 1
	v_add_u32_e32 v150, 0xa0, v144
	v_ashrrev_i32_e32 v151, 31, v150
	v_lshlrev_b64 v[150:151], 10, v[150:151]
	v_lshl_add_u64 v[150:151], s[20:21], 0, v[150:151]
	v_lshl_add_u64 v[150:151], v[150:151], 0, v[148:149]
	v_fmamk_f32 v145, v219, 0x3a800000, v224
	v_cmp_gt_f32_e32 vcc, s33, v145
	v_mul_f32_e32 v152, 0x4b800000, v145
	s_nop 0
	v_cndmask_b32_e32 v145, v145, v152, vcc
	v_rsq_f32_e32 v145, v145
	s_nop 0
	v_mul_f32_e32 v152, 0x45800000, v145
	v_cndmask_b32_e32 v152, v145, v152, vcc
	v_fma_f32 v145, v20, v152, v36
	v_mul_f32_e32 v145, 0xbfb8aa3b, v145
	v_exp_f32_e32 v145, v145
	v_pk_fma_f32 v[158:159], v[28:29], v[152:153], v[44:45] op_sel_hi:[1,0,1]
	v_pk_fma_f32 v[186:187], v[30:31], v[152:153], v[46:47] op_sel_hi:[1,0,1]
	v_add_f32_e32 v145, 1.0, v145
	v_rcp_f32_e32 v154, v145
	v_fma_f32 v145, v21, v152, v37
	v_mul_f32_e32 v145, 0xbfb8aa3b, v145
	v_exp_f32_e32 v145, v145
	s_nop 0
	v_add_f32_e32 v145, 1.0, v145
	v_rcp_f32_e32 v155, v145
	v_fma_f32 v145, v22, v152, v38
	v_mul_f32_e32 v145, 0xbfb8aa3b, v145
	v_exp_f32_e32 v145, v145
	v_pk_mul_f32 v[154:155], v[158:159], v[154:155]
	v_pk_fma_f32 v[158:159], v[24:25], v[152:153], v[40:41] op_sel_hi:[1,0,1]
	v_add_f32_e32 v145, 1.0, v145
	v_rcp_f32_e32 v156, v145
; __device__ __forceinline__ float sigm(float v) { return __builtin_amdgcn_rcpf(1.f + __builtin_amdgcn_exp2f(-1.4426950408889634f * v)); }
;     __device__ __forceinline__ void operator()(const f32x4 (&acc)[2][2][4][2], const Unit& u, int wr, int wc, int fr, int fq) const {
;     ...
; #pragma unroll
;             for (int ai = 0; ai < 2; ++ai)
; #pragma unroll
;                 for (int m = 0; m < 4; ++m) {
;                     const int row = pm * 256 + ai * 128 + wr * 64 + m * 16 + fr;
;                     const float rinv = rsqrtf(rowsq[row] * (1.f / DM) + EPSN);
; #pragma unroll
;                     for (int bj = 0; bj < 2; ++bj)
; #pragma unroll
;                         for (int n = 0; n < 2; ++n) *(f32x4*)(upool + (size_t)row * 256 + 128 * bj + 32 * wc + 8 * fq + 4 * n) = acc[ai][bj][m][n] * rinv + bv[bj][n];
;                 }
;     ...
;                 for (int m = 0; m < 4; ++m) {
;                     const int row = pm * 256 + ai * 128 + wr * 64 + m * 16 + fr;
;                     const float rinv = rsqrtf(rowsq[row] * (1.f / DM) + EPSN);
; #pragma unroll
;                     for (int n = 0; n < 2; ++n) {
;                         const f32x4 a = acc[ai][0][m][n] * rinv + bv[0][n], g = acc[ai][1][m][n] * rinv + bv[1][n];
;                         f32x4 o;
; #pragma unroll
;                         for (int j = 0; j < 4; ++j) o[j] = a[j] * sigm(g[j]);
;                         *(f32x4*)(uconv + (size_t)row * 256 + ch0 + 4 * n) = o;
;                     }
	v_fma_f32 v145, v23, v152, v39
	v_mul_f32_e32 v145, 0xbfb8aa3b, v145
	v_exp_f32_e32 v145, v145
	s_nop 0
	v_add_f32_e32 v145, 1.0, v145
	v_rcp_f32_e32 v157, v145
	v_fma_f32 v145, v16, v152, v32
	v_mul_f32_e32 v145, 0xbfb8aa3b, v145
	v_exp_f32_e32 v145, v145
	v_pk_mul_f32 v[156:157], v[186:187], v[156:157]
	global_store_dwordx4 v[150:151], v[154:157], off
	v_add_f32_e32 v145, 1.0, v145
	s_nop 0
	v_rcp_f32_e32 v156, v145
	v_fma_f32 v145, v17, v152, v33
	v_mul_f32_e32 v145, 0xbfb8aa3b, v145
	v_exp_f32_e32 v145, v145
	s_nop 0
	v_add_f32_e32 v145, 1.0, v145
	v_rcp_f32_e32 v157, v145
	v_fma_f32 v145, v18, v152, v34
	v_mul_f32_e32 v145, 0xbfb8aa3b, v145
	v_exp_f32_e32 v145, v145
	s_nop 0
	v_add_f32_e32 v145, 1.0, v145
	v_rcp_f32_e32 v154, v145
	v_fma_f32 v145, v19, v152, v35
	v_mul_f32_e32 v145, 0xbfb8aa3b, v145
	v_exp_f32_e32 v145, v145
	v_pk_fma_f32 v[152:153], v[26:27], v[152:153], v[42:43] op_sel_hi:[1,0,1]
	v_add_f32_e32 v145, 1.0, v145
	v_rcp_f32_e32 v155, v145
	s_nop 0
	v_pk_mul_f32 v[154:155], v[152:153], v[154:155]
	v_pk_mul_f32 v[152:153], v[158:159], v[156:157]
	global_store_dwordx4 v[150:151], v[152:155], off offset:16
	s_nop 1
	v_fmamk_f32 v145, v220, 0x3a800000, v224
	v_cmp_gt_f32_e32 vcc, s33, v145
	v_mul_f32_e32 v146, 0x4b800000, v145
	v_add_u32_e32 v152, 0xb0, v144
	v_cndmask_b32_e32 v145, v145, v146, vcc
	v_rsq_f32_e32 v145, v145
	v_ashrrev_i32_e32 v153, 31, v152
	v_mul_f32_e32 v146, 0x45800000, v145
	v_cndmask_b32_e32 v150, v145, v146, vcc
	v_fma_f32 v145, v4, v150, v36
	v_mul_f32_e32 v145, 0xbfb8aa3b, v145
	v_exp_f32_e32 v145, v145
	v_lshlrev_b64 v[146:147], 10, v[152:153]
	v_lshl_add_u64 v[146:147], s[20:21], 0, v[146:147]
	v_lshl_add_u64 v[146:147], v[146:147], 0, v[148:149]
	v_add_f32_e32 v145, 1.0, v145
	v_rcp_f32_e32 v152, v145
	v_fma_f32 v145, v5, v150, v37
	v_mul_f32_e32 v145, 0xbfb8aa3b, v145
	v_exp_f32_e32 v145, v145
	v_pk_fma_f32 v[156:157], v[12:13], v[150:151], v[44:45] op_sel_hi:[1,0,1]
	v_pk_fma_f32 v[158:159], v[14:15], v[150:151], v[46:47] op_sel_hi:[1,0,1]
	v_add_f32_e32 v145, 1.0, v145
	v_rcp_f32_e32 v153, v145
	v_fma_f32 v145, v6, v150, v38
	v_mul_f32_e32 v145, 0xbfb8aa3b, v145
	v_exp_f32_e32 v145, v145
	v_pk_mul_f32 v[152:153], v[156:157], v[152:153]
	v_add_f32_e32 v145, 1.0, v145
	v_rcp_f32_e32 v154, v145
	v_fma_f32 v145, v7, v150, v39
	v_mul_f32_e32 v145, 0xbfb8aa3b, v145
	v_exp_f32_e32 v145, v145
	s_nop 0
	v_add_f32_e32 v145, 1.0, v145
	v_rcp_f32_e32 v155, v145
	v_fma_f32 v145, v0, v150, v32
	v_mul_f32_e32 v145, 0xbfb8aa3b, v145
	v_exp_f32_e32 v145, v145
	v_pk_mul_f32 v[154:155], v[158:159], v[154:155]
	global_store_dwordx4 v[146:147], v[152:155], off
	v_add_f32_e32 v145, 1.0, v145
	v_rcp_f32_e32 v148, v145
	v_fma_f32 v145, v1, v150, v33
	v_mul_f32_e32 v145, 0xbfb8aa3b, v145
	v_exp_f32_e32 v145, v145
	v_pk_fma_f32 v[154:155], v[8:9], v[150:151], v[40:41] op_sel_hi:[1,0,1]
	v_add_f32_e32 v145, 1.0, v145
	v_rcp_f32_e32 v149, v145
	v_fma_f32 v145, v2, v150, v34
	v_mul_f32_e32 v145, 0xbfb8aa3b, v145
	v_exp_f32_e32 v145, v145
	v_pk_mul_f32 v[148:149], v[154:155], v[148:149]
	v_add_f32_e32 v145, 1.0, v145
	v_rcp_f32_e32 v152, v145
	v_fma_f32 v145, v3, v150, v35
	v_mul_f32_e32 v145, 0xbfb8aa3b, v145
	v_exp_f32_e32 v145, v145
	v_pk_fma_f32 v[150:151], v[10:11], v[150:151], v[42:43] op_sel_hi:[1,0,1]
	v_add_f32_e32 v145, 1.0, v145
	v_rcp_f32_e32 v153, v145
	s_nop 0
	v_pk_mul_f32 v[150:151], v[150:151], v[152:153]
	global_store_dwordx4 v[146:147], v[148:151], off offset:16
.LBB0_219:
	s_andn2_b64 vcc, exec, s[0:1]
	s_cbranch_vccnz .LBB0_221
	v_ashrrev_i32_e32 v145, 31, v144
	v_lshl_add_u64 v[146:147], v[144:145], 2, s[16:17]
	global_load_dword v148, v[146:147], off
	global_load_dword v214, v[146:147], off offset:64
	global_load_dword v215, v[146:147], off offset:128
	global_load_dword v216, v[146:147], off offset:192
	global_load_dword v217, v[146:147], off offset:512
	global_load_dword v218, v[146:147], off offset:576
	global_load_dword v219, v[146:147], off offset:640
	v_lshlrev_b64 v[154:155], 10, v[144:145]
	v_lshl_add_u64 v[154:155], v[174:175], 0, v[154:155]
	s_waitcnt vmcnt(0) lgkmcnt(0)
	v_fmamk_f32 v148, v148, 0x3a800000, v224
	v_cmp_gt_f32_e32 vcc, s33, v148
	v_mul_f32_e32 v149, 0x4b800000, v148
	s_nop 0
	v_cndmask_b32_e32 v148, v148, v149, vcc
	v_rsq_f32_e32 v148, v148
	s_nop 0
	v_mul_f32_e32 v149, 0x45800000, v148
	v_cndmask_b32_e32 v152, v148, v149, vcc
	v_pk_fma_f32 v[150:151], v[142:143], v[152:153], v[46:47] op_sel_hi:[1,0,1]
	v_pk_fma_f32 v[148:149], v[140:141], v[152:153], v[44:45] op_sel_hi:[1,0,1]
	global_store_dwordx4 v[154:155], v[148:151], off
	s_nop 1
	v_pk_fma_f32 v[150:151], v[138:139], v[152:153], v[42:43] op_sel_hi:[1,0,1]
	v_pk_fma_f32 v[148:149], v[136:137], v[152:153], v[40:41] op_sel_hi:[1,0,1]
	global_store_dwordx4 v[154:155], v[148:151], off offset:16
	s_nop 1
	v_pk_fma_f32 v[150:151], v[134:135], v[152:153], v[38:39] op_sel_hi:[1,0,1]
	v_pk_fma_f32 v[148:149], v[132:133], v[152:153], v[36:37] op_sel_hi:[1,0,1]
	global_store_dwordx4 v[154:155], v[148:151], off offset:512
	s_nop 1
	v_pk_fma_f32 v[150:151], v[130:131], v[152:153], v[34:35] op_sel_hi:[1,0,1]
	v_pk_fma_f32 v[148:149], v[128:129], v[152:153], v[32:33] op_sel_hi:[1,0,1]
	global_store_dwordx4 v[154:155], v[148:151], off offset:528
	s_nop 1
	v_fmamk_f32 v145, v214, 0x3a800000, v224
	v_cmp_gt_f32_e32 vcc, s33, v145
	v_mul_f32_e32 v150, 0x4b800000, v145
	v_or_b32_e32 v148, 16, v144
	v_cndmask_b32_e32 v145, v145, v150, vcc
	v_rsq_f32_e32 v145, v145
	v_ashrrev_i32_e32 v149, 31, v148
	v_lshlrev_b64 v[154:155], 10, v[148:149]
	v_lshl_add_u64 v[154:155], v[174:175], 0, v[154:155]
	v_mul_f32_e32 v150, 0x45800000, v145
;     __device__ __forceinline__ void operator()(const f32x4 (&acc)[2][2][4][2], const Unit& u, int wr, int wc, int fr, int fq) const {
;     ...
; #pragma unroll
;             for (int ai = 0; ai < 2; ++ai)
; #pragma unroll
;                 for (int m = 0; m < 4; ++m) {
;                     const int row = pm * 256 + ai * 128 + wr * 64 + m * 16 + fr;
;                     const float rinv = rsqrtf(rowsq[row] * (1.f / DM) + EPSN);
; #pragma unroll
;                     for (int bj = 0; bj < 2; ++bj)
; #pragma unroll
;                         for (int n = 0; n < 2; ++n) *(f32x4*)(upool + (size_t)row * 256 + 128 * bj + 32 * wc + 8 * fq + 4 * n) = acc[ai][bj][m][n] * rinv + bv[bj][n];
;                 }
	v_cndmask_b32_e32 v152, v145, v150, vcc
	v_pk_fma_f32 v[150:151], v[126:127], v[152:153], v[46:47] op_sel_hi:[1,0,1]
	v_pk_fma_f32 v[148:149], v[124:125], v[152:153], v[44:45] op_sel_hi:[1,0,1]
	global_store_dwordx4 v[154:155], v[148:151], off
	s_nop 1
	v_pk_fma_f32 v[150:151], v[122:123], v[152:153], v[42:43] op_sel_hi:[1,0,1]
	v_pk_fma_f32 v[148:149], v[120:121], v[152:153], v[40:41] op_sel_hi:[1,0,1]
	global_store_dwordx4 v[154:155], v[148:151], off offset:16
	s_nop 1
	v_pk_fma_f32 v[150:151], v[118:119], v[152:153], v[38:39] op_sel_hi:[1,0,1]
	v_pk_fma_f32 v[148:149], v[116:117], v[152:153], v[36:37] op_sel_hi:[1,0,1]
	global_store_dwordx4 v[154:155], v[148:151], off offset:512
	s_nop 1
	v_pk_fma_f32 v[150:151], v[114:115], v[152:153], v[34:35] op_sel_hi:[1,0,1]
	v_pk_fma_f32 v[148:149], v[112:113], v[152:153], v[32:33] op_sel_hi:[1,0,1]
	global_store_dwordx4 v[154:155], v[148:151], off offset:528
	s_nop 1
	v_fmamk_f32 v145, v215, 0x3a800000, v224
	v_cmp_gt_f32_e32 vcc, s33, v145
	v_mul_f32_e32 v150, 0x4b800000, v145
	v_or_b32_e32 v148, 32, v144
	v_cndmask_b32_e32 v145, v145, v150, vcc
	v_rsq_f32_e32 v145, v145
	v_ashrrev_i32_e32 v149, 31, v148
	v_lshlrev_b64 v[154:155], 10, v[148:149]
	v_lshl_add_u64 v[154:155], v[174:175], 0, v[154:155]
	v_mul_f32_e32 v150, 0x45800000, v145
	v_cndmask_b32_e32 v152, v145, v150, vcc
	v_pk_fma_f32 v[150:151], v[110:111], v[152:153], v[46:47] op_sel_hi:[1,0,1]
	v_pk_fma_f32 v[148:149], v[108:109], v[152:153], v[44:45] op_sel_hi:[1,0,1]
	global_store_dwordx4 v[154:155], v[148:151], off
	s_nop 1
	v_pk_fma_f32 v[150:151], v[106:107], v[152:153], v[42:43] op_sel_hi:[1,0,1]
	v_pk_fma_f32 v[148:149], v[104:105], v[152:153], v[40:41] op_sel_hi:[1,0,1]
	global_store_dwordx4 v[154:155], v[148:151], off offset:16
	s_nop 1
	v_pk_fma_f32 v[150:151], v[102:103], v[152:153], v[38:39] op_sel_hi:[1,0,1]
	v_pk_fma_f32 v[148:149], v[100:101], v[152:153], v[36:37] op_sel_hi:[1,0,1]
	global_store_dwordx4 v[154:155], v[148:151], off offset:512
	s_nop 1
	v_pk_fma_f32 v[150:151], v[98:99], v[152:153], v[34:35] op_sel_hi:[1,0,1]
	v_pk_fma_f32 v[148:149], v[96:97], v[152:153], v[32:33] op_sel_hi:[1,0,1]
	global_store_dwordx4 v[154:155], v[148:151], off offset:528
	s_nop 1
	v_fmamk_f32 v145, v216, 0x3a800000, v224
	v_cmp_gt_f32_e32 vcc, s33, v145
	v_mul_f32_e32 v150, 0x4b800000, v145
	v_or_b32_e32 v148, 48, v144
	v_cndmask_b32_e32 v145, v145, v150, vcc
	v_rsq_f32_e32 v145, v145
	v_ashrrev_i32_e32 v149, 31, v148
	v_lshlrev_b64 v[154:155], 10, v[148:149]
	v_lshl_add_u64 v[154:155], v[174:175], 0, v[154:155]
	v_mul_f32_e32 v150, 0x45800000, v145
	v_cndmask_b32_e32 v152, v145, v150, vcc
	v_pk_fma_f32 v[150:151], v[94:95], v[152:153], v[46:47] op_sel_hi:[1,0,1]
	v_pk_fma_f32 v[148:149], v[92:93], v[152:153], v[44:45] op_sel_hi:[1,0,1]
	global_store_dwordx4 v[154:155], v[148:151], off
	s_nop 1
	v_pk_fma_f32 v[150:151], v[90:91], v[152:153], v[42:43] op_sel_hi:[1,0,1]
	v_pk_fma_f32 v[148:149], v[88:89], v[152:153], v[40:41] op_sel_hi:[1,0,1]
	global_store_dwordx4 v[154:155], v[148:151], off offset:16
	s_nop 1
	v_pk_fma_f32 v[150:151], v[86:87], v[152:153], v[38:39] op_sel_hi:[1,0,1]
	v_pk_fma_f32 v[148:149], v[84:85], v[152:153], v[36:37] op_sel_hi:[1,0,1]
	global_store_dwordx4 v[154:155], v[148:151], off offset:512
	s_nop 1
	v_pk_fma_f32 v[150:151], v[82:83], v[152:153], v[34:35] op_sel_hi:[1,0,1]
	v_pk_fma_f32 v[148:149], v[80:81], v[152:153], v[32:33] op_sel_hi:[1,0,1]
	global_store_dwordx4 v[154:155], v[148:151], off offset:528
	s_nop 1
	v_fmamk_f32 v145, v217, 0x3a800000, v224
	v_cmp_gt_f32_e32 vcc, s33, v145
	v_mul_f32_e32 v150, 0x4b800000, v145
	v_add_u32_e32 v148, 0x80, v144
	v_cndmask_b32_e32 v145, v145, v150, vcc
	v_rsq_f32_e32 v145, v145
	v_ashrrev_i32_e32 v149, 31, v148
	v_lshlrev_b64 v[154:155], 10, v[148:149]
	v_lshl_add_u64 v[154:155], v[174:175], 0, v[154:155]
	v_mul_f32_e32 v150, 0x45800000, v145
	v_cndmask_b32_e32 v152, v145, v150, vcc
	v_pk_fma_f32 v[150:151], v[78:79], v[152:153], v[46:47] op_sel_hi:[1,0,1]
	v_pk_fma_f32 v[148:149], v[76:77], v[152:153], v[44:45] op_sel_hi:[1,0,1]
	global_store_dwordx4 v[154:155], v[148:151], off
	s_nop 1
	v_pk_fma_f32 v[150:151], v[74:75], v[152:153], v[42:43] op_sel_hi:[1,0,1]
	v_pk_fma_f32 v[148:149], v[72:73], v[152:153], v[40:41] op_sel_hi:[1,0,1]
	global_store_dwordx4 v[154:155], v[148:151], off offset:16
	s_nop 1
;     __device__ __forceinline__ void operator()(const f32x4 (&acc)[2][2][4][2], const Unit& u, int wr, int wc, int fr, int fq) const {
;     ...
; #pragma unroll
;             for (int ai = 0; ai < 2; ++ai)
; #pragma unroll
;                 for (int m = 0; m < 4; ++m) {
;                     const int row = pm * 256 + ai * 128 + wr * 64 + m * 16 + fr;
;                     const float rinv = rsqrtf(rowsq[row] * (1.f / DM) + EPSN);
; #pragma unroll
;                     for (int bj = 0; bj < 2; ++bj)
; #pragma unroll
;                         for (int n = 0; n < 2; ++n) *(f32x4*)(upool + (size_t)row * 256 + 128 * bj + 32 * wc + 8 * fq + 4 * n) = acc[ai][bj][m][n] * rinv + bv[bj][n];
;                 }
	v_pk_fma_f32 v[150:151], v[70:71], v[152:153], v[38:39] op_sel_hi:[1,0,1]
	v_pk_fma_f32 v[148:149], v[68:69], v[152:153], v[36:37] op_sel_hi:[1,0,1]
	global_store_dwordx4 v[154:155], v[148:151], off offset:512
	s_nop 1
	v_pk_fma_f32 v[150:151], v[66:67], v[152:153], v[34:35] op_sel_hi:[1,0,1]
	v_pk_fma_f32 v[148:149], v[64:65], v[152:153], v[32:33] op_sel_hi:[1,0,1]
	global_store_dwordx4 v[154:155], v[148:151], off offset:528
	s_nop 1
	v_fmamk_f32 v145, v218, 0x3a800000, v224
	v_cmp_gt_f32_e32 vcc, s33, v145
	v_mul_f32_e32 v150, 0x4b800000, v145
	v_add_u32_e32 v148, 0x90, v144
	v_cndmask_b32_e32 v145, v145, v150, vcc
	v_rsq_f32_e32 v145, v145
	v_ashrrev_i32_e32 v149, 31, v148
	v_lshlrev_b64 v[154:155], 10, v[148:149]
	v_lshl_add_u64 v[154:155], v[174:175], 0, v[154:155]
	v_mul_f32_e32 v150, 0x45800000, v145
	v_cndmask_b32_e32 v152, v145, v150, vcc
	v_pk_fma_f32 v[150:151], v[62:63], v[152:153], v[46:47] op_sel_hi:[1,0,1]
	v_pk_fma_f32 v[148:149], v[60:61], v[152:153], v[44:45] op_sel_hi:[1,0,1]
	global_store_dwordx4 v[154:155], v[148:151], off
	s_nop 1
	v_pk_fma_f32 v[150:151], v[58:59], v[152:153], v[42:43] op_sel_hi:[1,0,1]
	v_pk_fma_f32 v[148:149], v[56:57], v[152:153], v[40:41] op_sel_hi:[1,0,1]
	global_store_dwordx4 v[154:155], v[148:151], off offset:16
	s_nop 1
	v_pk_fma_f32 v[150:151], v[54:55], v[152:153], v[38:39] op_sel_hi:[1,0,1]
	v_pk_fma_f32 v[148:149], v[52:53], v[152:153], v[36:37] op_sel_hi:[1,0,1]
	global_store_dwordx4 v[154:155], v[148:151], off offset:512
	s_nop 1
	v_pk_fma_f32 v[150:151], v[50:51], v[152:153], v[34:35] op_sel_hi:[1,0,1]
	v_pk_fma_f32 v[148:149], v[48:49], v[152:153], v[32:33] op_sel_hi:[1,0,1]
	global_store_dwordx4 v[154:155], v[148:151], off offset:528
	s_nop 1
	v_fmamk_f32 v145, v219, 0x3a800000, v224
	v_cmp_gt_f32_e32 vcc, s33, v145
	v_mul_f32_e32 v150, 0x4b800000, v145
	v_add_u32_e32 v148, 0xa0, v144
	v_cndmask_b32_e32 v145, v145, v150, vcc
	v_rsq_f32_e32 v145, v145
	v_ashrrev_i32_e32 v149, 31, v148
	v_lshlrev_b64 v[154:155], 10, v[148:149]
	v_lshl_add_u64 v[154:155], v[174:175], 0, v[154:155]
	v_mul_f32_e32 v150, 0x45800000, v145
	v_cndmask_b32_e32 v152, v145, v150, vcc
	v_pk_fma_f32 v[150:151], v[30:31], v[152:153], v[46:47] op_sel_hi:[1,0,1]
	v_pk_fma_f32 v[148:149], v[28:29], v[152:153], v[44:45] op_sel_hi:[1,0,1]
	global_store_dwordx4 v[154:155], v[148:151], off
	v_add_u32_e32 v144, 0xb0, v144
	v_ashrrev_i32_e32 v145, 31, v144
	v_pk_fma_f32 v[150:151], v[26:27], v[152:153], v[42:43] op_sel_hi:[1,0,1]
	v_pk_fma_f32 v[148:149], v[24:25], v[152:153], v[40:41] op_sel_hi:[1,0,1]
	global_store_dwordx4 v[154:155], v[148:151], off offset:16
	s_nop 1
	v_pk_fma_f32 v[150:151], v[22:23], v[152:153], v[38:39] op_sel_hi:[1,0,1]
	v_pk_fma_f32 v[148:149], v[20:21], v[152:153], v[36:37] op_sel_hi:[1,0,1]
	global_store_dwordx4 v[154:155], v[148:151], off offset:512
	s_nop 1
	v_pk_fma_f32 v[150:151], v[18:19], v[152:153], v[34:35] op_sel_hi:[1,0,1]
	v_pk_fma_f32 v[148:149], v[16:17], v[152:153], v[32:33] op_sel_hi:[1,0,1]
	global_store_dwordx4 v[154:155], v[148:151], off offset:528
	global_load_dword v146, v[146:147], off offset:704
	s_waitcnt vmcnt(0) lgkmcnt(0)
	v_fmamk_f32 v146, v146, 0x3a800000, v224
	v_cmp_gt_f32_e32 vcc, s33, v146
	v_mul_f32_e32 v147, 0x4b800000, v146
	v_lshlrev_b64 v[150:151], 10, v[144:145]
	v_cndmask_b32_e32 v146, v146, v147, vcc
	v_rsq_f32_e32 v146, v146
	v_lshl_add_u64 v[150:151], v[174:175], 0, v[150:151]
	v_mul_f32_e32 v147, 0x45800000, v146
	v_cndmask_b32_e32 v148, v146, v147, vcc
	v_pk_fma_f32 v[146:147], v[14:15], v[148:149], v[46:47] op_sel_hi:[1,0,1]
	v_pk_fma_f32 v[144:145], v[12:13], v[148:149], v[44:45] op_sel_hi:[1,0,1]
	global_store_dwordx4 v[150:151], v[144:147], off
	s_nop 1
	v_pk_fma_f32 v[146:147], v[10:11], v[148:149], v[42:43] op_sel_hi:[1,0,1]
	v_pk_fma_f32 v[144:145], v[8:9], v[148:149], v[40:41] op_sel_hi:[1,0,1]
	global_store_dwordx4 v[150:151], v[144:147], off offset:16
	s_nop 1
	v_pk_fma_f32 v[146:147], v[6:7], v[148:149], v[38:39] op_sel_hi:[1,0,1]
	v_pk_fma_f32 v[144:145], v[4:5], v[148:149], v[36:37] op_sel_hi:[1,0,1]
	global_store_dwordx4 v[150:151], v[144:147], off offset:512
	s_nop 1
	v_pk_fma_f32 v[146:147], v[2:3], v[148:149], v[34:35] op_sel_hi:[1,0,1]
	v_pk_fma_f32 v[144:145], v[0:1], v[148:149], v[32:33] op_sel_hi:[1,0,1]
	global_store_dwordx4 v[150:151], v[144:147], off offset:528

; __device__ __forceinline__ unsigned pkbf(float lo, float hi) { return pg8::cvt_pk_bf16(lo, hi); }
;     __device__ __forceinline__ void operator()(const f32x4 (&acc)[2][2][4][2], const Unit& u, int wr, int wc, int fr, int fq) const {
;     ...
;         } else if (pn < 6) {
; #pragma unroll
;             for (int ai = 0; ai < 2; ++ai)
; #pragma unroll
;                 for (int m = 0; m < 4; ++m) {
;                     const int row = pm * 256 + ai * 128 + wr * 64 + m * 16 + fr;
;                     const float rinv = rsqrtf(rowsq[row] * (1.f / DM) + EPSN);
;                     int b, kidx;
;                     if (isctx) { const int rc = row - MLAT; b = rc >> 8; kidx = rc & 255; } else { b = row >> 13; kidx = CTXL + (row & (SEQ - 1)); }
; #pragma unroll
;                     for (int bj = 0; bj < 2; ++bj) {
;                         const f32x4 y0 = acc[ai][bj][m][0] * rinv + bv[bj][0], y1 = acc[ai][bj][m][1] * rinv + bv[bj][1];
;                         u32x4 w; w.x = pkbf(y0[0], y0[1]); w.y = pkbf(y0[2], y0[3]); w.z = pkbf(y1[0], y1[1]); w.w = pkbf(y1[2], y1[3]);
;                         const int head = 2 * (pn - 4) + bj;
;                         const size_t off = (size_t)(b * 4 + head) * (LK * 128) + (size_t)(kidx >> 6) * 8192 + (size_t)(voff(kidx & 63, 4 * wc + fq) >> 1);
;                         *(u32x4*)(Vb + off) = w;
;                     }
;                 }
.LBB0_222:
	s_andn2_b64 vcc, exec, s[0:1]
	s_cbranch_vccnz .LBB0_224
	s_lshl_b32 s25, s6, 8
	s_add_i32 s25, s25, s75
	v_or_b32_e32 v148, s25, v171
	v_ashrrev_i32_e32 v149, 31, v148
	v_lshl_add_u64 v[150:151], v[148:149], 2, s[16:17]
	global_load_dword v144, v[150:151], off
	s_lshl_b32 s7, s36, 1
	s_add_i32 s0, s25, 0xffffc000
	s_add_i32 s7, s7, -8
	s_ashr_i32 s14, s25, 13
	s_ashr_i32 s15, s0, 8
	s_and_b64 s[0:1], s[4:5], exec
	s_cselect_b32 s0, s15, s14
	s_lshl_b32 s14, s0, 2
	s_add_i32 s14, s14, s7
	s_mul_i32 s0, s14, 0x210000
	s_mul_hi_i32 s1, s14, 0x210000
	s_add_u32 s0, s72, s0
	s_addc_u32 s1, s73, s1
	s_or_b32 s14, s14, 1
	s_mul_hi_i32 s15, s14, 0x210000
	s_mul_i32 s14, s14, 0x210000
	s_add_u32 s14, s72, s14
	s_addc_u32 s15, s73, s15
	s_waitcnt vmcnt(0) lgkmcnt(0)
	v_fmamk_f32 v144, v144, 0x3a800000, v224
	v_cmp_gt_f32_e32 vcc, s33, v144
	v_mul_f32_e32 v145, 0x4b800000, v144
	s_nop 0
	v_cndmask_b32_e32 v144, v144, v145, vcc
	v_rsq_f32_e32 v144, v144
	s_nop 0
	v_mul_f32_e32 v145, 0x45800000, v144
	v_cndmask_b32_e32 v154, v144, v145, vcc
	v_bitop3_b32 v145, s25, v228, v171 bitop3:0xc8
	v_bitop3_b32 v144, s25, v227, v171 bitop3:0xc8
	v_add_u32_e32 v145, 0x100, v145
	v_cndmask_b32_e64 v144, v145, v144, s[4:5]
	v_lshrrev_b32_e32 v147, 2, v144
	v_lshlrev_b32_e32 v145, 7, v144
	v_xor_b32_e32 v147, v147, v169
	v_and_b32_e32 v145, 0x400, v145
	v_lshlrev_b32_e32 v146, 5, v144
	v_lshlrev_b32_e32 v147, 3, v147
	v_and_b32_e32 v147, 24, v147
	v_and_or_b32 v145, v146, s79, v145
	v_lshlrev_b32_e32 v144, 8, v144
	v_or3_b32 v149, v145, v147, s38
	v_and_b32_e32 v176, 0x3fc000, v144
	v_pk_fma_f32 v[146:147], v[142:143], v[154:155], v[46:47] op_sel_hi:[1,0,1]
	v_pk_fma_f32 v[144:145], v[140:141], v[154:155], v[44:45] op_sel_hi:[1,0,1]
	v_pk_fma_f32 v[152:153], v[138:139], v[154:155], v[42:43] op_sel_hi:[1,0,1]
	v_pk_fma_f32 v[156:157], v[136:137], v[154:155], v[40:41] op_sel_hi:[1,0,1]
	v_cvt_pk_bf16_f32 v144, v144, v145
	v_cvt_pk_bf16_f32 v145, v146, v147
	s_nop 0
	v_cvt_pk_bf16_f32 v146, v156, v157
	v_cvt_pk_bf16_f32 v147, v152, v153
	v_lshl_add_u64 v[156:157], s[0:1], 0, v[176:177]
	v_lshlrev_b32_e32 v152, 1, v149
	v_mov_b32_e32 v153, v177
	v_lshl_add_u64 v[156:157], v[156:157], 0, v[152:153]
	global_store_dwordx4 v[156:157], v[144:147], off
	v_pk_fma_f32 v[156:157], v[130:131], v[154:155], v[34:35] op_sel_hi:[1,0,1]
	s_nop 0
	v_pk_fma_f32 v[146:147], v[134:135], v[154:155], v[38:39] op_sel_hi:[1,0,1]
	v_pk_fma_f32 v[144:145], v[132:133], v[154:155], v[36:37] op_sel_hi:[1,0,1]
	v_pk_fma_f32 v[154:155], v[128:129], v[154:155], v[32:33] op_sel_hi:[1,0,1]
	v_cvt_pk_bf16_f32 v144, v144, v145
	v_cvt_pk_bf16_f32 v145, v146, v147
	s_nop 0
	v_cvt_pk_bf16_f32 v146, v154, v155
	v_lshl_add_u64 v[154:155], s[14:15], 0, v[176:177]
	v_lshl_add_u64 v[152:153], v[154:155], 0, v[152:153]
	v_cvt_pk_bf16_f32 v147, v156, v157
	global_store_dwordx4 v[152:153], v[144:147], off
	global_load_dword v144, v[150:151], off offset:64
	global_load_dword v214, v[150:151], off offset:128
	global_load_dword v215, v[150:151], off offset:192
	s_waitcnt vmcnt(0) lgkmcnt(0)
	v_fmamk_f32 v144, v144, 0x3a800000, v224
	v_cmp_gt_f32_e32 vcc, s33, v144
	v_mul_f32_e32 v145, 0x4b800000, v144
	s_nop 0
	v_cndmask_b32_e32 v144, v144, v145, vcc
	v_rsq_f32_e32 v144, v144
	s_nop 0
	v_mul_f32_e32 v145, 0x45800000, v144
	v_cndmask_b32_e32 v146, v144, v145, vcc
	v_bitop3_b32 v145, v148, s84, 16 bitop3:0xc8
	v_bitop3_b32 v144, v148, s95, 16 bitop3:0xc8
	v_add_u32_e32 v145, 0x100, v145
	v_cndmask_b32_e64 v144, v145, v144, s[4:5]
	v_lshrrev_b32_e32 v149, 2, v144
	v_lshlrev_b32_e32 v145, 7, v144
	v_xor_b32_e32 v149, v149, v169
	v_and_b32_e32 v145, 0xc00, v145
	v_lshlrev_b32_e32 v147, 5, v144
	v_lshlrev_b32_e32 v149, 3, v149
	v_and_b32_e32 v149, 24, v149
	v_and_or_b32 v145, v147, s79, v145
	v_or3_b32 v147, v145, v149, s38
	v_lshlrev_b32_e32 v144, 8, v144
	v_and_b32_e32 v176, 0x3fc000, v144
	v_pk_fma_f32 v[144:145], v[126:127], v[146:147], v[46:47] op_sel_hi:[1,0,1]
	v_pk_fma_f32 v[152:153], v[124:125], v[146:147], v[44:45] op_sel_hi:[1,0,1]
	v_pk_fma_f32 v[156:157], v[122:123], v[146:147], v[42:43] op_sel_hi:[1,0,1]
	v_pk_fma_f32 v[154:155], v[120:121], v[146:147], v[40:41] op_sel_hi:[1,0,1]
	v_cvt_pk_bf16_f32 v152, v152, v153
	v_cvt_pk_bf16_f32 v153, v144, v145
	v_lshlrev_b32_e32 v144, 1, v147
	v_cvt_pk_bf16_f32 v154, v154, v155
	v_cvt_pk_bf16_f32 v155, v156, v157
	v_lshl_add_u64 v[156:157], s[0:1], 0, v[176:177]
	v_mov_b32_e32 v145, v177
	v_lshl_add_u64 v[156:157], v[156:157], 0, v[144:145]
	global_store_dwordx4 v[156:157], v[152:155], off
	v_pk_fma_f32 v[156:157], v[114:115], v[146:147], v[34:35] op_sel_hi:[1,0,1]
	s_nop 0
	v_pk_fma_f32 v[154:155], v[118:119], v[146:147], v[38:39] op_sel_hi:[1,0,1]
	v_pk_fma_f32 v[152:153], v[116:117], v[146:147], v[36:37] op_sel_hi:[1,0,1]
	v_pk_fma_f32 v[146:147], v[112:113], v[146:147], v[32:33] op_sel_hi:[1,0,1]
	v_cvt_pk_bf16_f32 v152, v152, v153
	v_cvt_pk_bf16_f32 v153, v154, v155
	s_nop 0
	v_cvt_pk_bf16_f32 v154, v146, v147
	v_lshl_add_u64 v[146:147], s[14:15], 0, v[176:177]
	v_lshl_add_u64 v[144:145], v[146:147], 0, v[144:145]
	v_cvt_pk_bf16_f32 v155, v156, v157
	global_store_dwordx4 v[144:145], v[152:155], off
	s_nop 1
	v_fmamk_f32 v144, v214, 0x3a800000, v224
	v_cmp_gt_f32_e32 vcc, s33, v144
	v_mul_f32_e32 v145, 0x4b800000, v144
	s_nop 0
	v_cndmask_b32_e32 v144, v144, v145, vcc
	v_rsq_f32_e32 v144, v144
	s_nop 0
	v_mul_f32_e32 v145, 0x45800000, v144
	v_cndmask_b32_e32 v146, v144, v145, vcc
	v_bitop3_b32 v145, v148, s81, 32 bitop3:0xc8
	v_bitop3_b32 v144, v148, s80, 32 bitop3:0xc8
	v_add_u32_e32 v145, 0x100, v145
	v_cndmask_b32_e64 v144, v145, v144, s[4:5]
; __device__ __forceinline__ unsigned pkbf(float lo, float hi) { return pg8::cvt_pk_bf16(lo, hi); }
;     __device__ __forceinline__ void operator()(const f32x4 (&acc)[2][2][4][2], const Unit& u, int wr, int wc, int fr, int fq) const {
;     ...
;             for (int ai = 0; ai < 2; ++ai)
; #pragma unroll
;                 for (int m = 0; m < 4; ++m) {
;                     const int row = pm * 256 + ai * 128 + wr * 64 + m * 16 + fr;
;                     const float rinv = rsqrtf(rowsq[row] * (1.f / DM) + EPSN);
;                     int b, kidx;
;                     if (isctx) { const int rc = row - MLAT; b = rc >> 8; kidx = rc & 255; } else { b = row >> 13; kidx = CTXL + (row & (SEQ - 1)); }
; #pragma unroll
;                     for (int bj = 0; bj < 2; ++bj) {
;                         const f32x4 y0 = acc[ai][bj][m][0] * rinv + bv[bj][0], y1 = acc[ai][bj][m][1] * rinv + bv[bj][1];
;                         u32x4 w; w.x = pkbf(y0[0], y0[1]); w.y = pkbf(y0[2], y0[3]); w.z = pkbf(y1[0], y1[1]); w.w = pkbf(y1[2], y1[3]);
;                         const int head = 2 * (pn - 4) + bj;
;                         const size_t off = (size_t)(b * 4 + head) * (LK * 128) + (size_t)(kidx >> 6) * 8192 + (size_t)(voff(kidx & 63, 4 * wc + fq) >> 1);
;                         *(u32x4*)(Vb + off) = w;
;                     }
;                 }
	v_lshrrev_b32_e32 v149, 2, v144
	v_lshlrev_b32_e32 v145, 7, v144
	v_xor_b32_e32 v149, v149, v169
	v_and_b32_e32 v145, 0x1400, v145
	v_lshlrev_b32_e32 v147, 5, v144
	v_lshlrev_b32_e32 v149, 3, v149
	v_and_b32_e32 v149, 24, v149
	v_and_or_b32 v145, v147, s79, v145
	v_or3_b32 v147, v145, v149, s38
	v_lshlrev_b32_e32 v144, 8, v144
	v_and_b32_e32 v176, 0x3fc000, v144
	v_pk_fma_f32 v[144:145], v[110:111], v[146:147], v[46:47] op_sel_hi:[1,0,1]
	v_pk_fma_f32 v[152:153], v[108:109], v[146:147], v[44:45] op_sel_hi:[1,0,1]
	v_pk_fma_f32 v[156:157], v[106:107], v[146:147], v[42:43] op_sel_hi:[1,0,1]
	v_pk_fma_f32 v[154:155], v[104:105], v[146:147], v[40:41] op_sel_hi:[1,0,1]
	v_cvt_pk_bf16_f32 v152, v152, v153
	v_cvt_pk_bf16_f32 v153, v144, v145
	v_lshlrev_b32_e32 v144, 1, v147
	v_cvt_pk_bf16_f32 v154, v154, v155
	v_cvt_pk_bf16_f32 v155, v156, v157
	v_lshl_add_u64 v[156:157], s[0:1], 0, v[176:177]
	v_mov_b32_e32 v145, v177
	v_lshl_add_u64 v[156:157], v[156:157], 0, v[144:145]
	global_store_dwordx4 v[156:157], v[152:155], off
	v_pk_fma_f32 v[156:157], v[98:99], v[146:147], v[34:35] op_sel_hi:[1,0,1]
	s_nop 0
	v_pk_fma_f32 v[154:155], v[102:103], v[146:147], v[38:39] op_sel_hi:[1,0,1]
	v_pk_fma_f32 v[152:153], v[100:101], v[146:147], v[36:37] op_sel_hi:[1,0,1]
	v_pk_fma_f32 v[146:147], v[96:97], v[146:147], v[32:33] op_sel_hi:[1,0,1]
	v_cvt_pk_bf16_f32 v152, v152, v153
	v_cvt_pk_bf16_f32 v153, v154, v155
	s_nop 0
	v_cvt_pk_bf16_f32 v154, v146, v147
	v_lshl_add_u64 v[146:147], s[14:15], 0, v[176:177]
	v_lshl_add_u64 v[144:145], v[146:147], 0, v[144:145]
	v_cvt_pk_bf16_f32 v155, v156, v157
	global_store_dwordx4 v[144:145], v[152:155], off
	s_nop 1
	v_fmamk_f32 v144, v215, 0x3a800000, v224
	v_cmp_gt_f32_e32 vcc, s33, v144
	v_mul_f32_e32 v145, 0x4b800000, v144
	s_nop 0
	v_cndmask_b32_e32 v144, v144, v145, vcc
	v_rsq_f32_e32 v144, v144
	s_nop 0
	v_mul_f32_e32 v145, 0x45800000, v144
	v_cndmask_b32_e32 v150, v144, v145, vcc
	v_bitop3_b32 v145, v148, s68, 48 bitop3:0xc8
	v_bitop3_b32 v144, v148, s48, 48 bitop3:0xc8
	v_add_u32_e32 v145, 0x100, v145
	v_cndmask_b32_e64 v144, v145, v144, s[4:5]
	v_lshrrev_b32_e32 v147, 2, v144
	v_lshlrev_b32_e32 v145, 7, v144
	v_xor_b32_e32 v147, v147, v169
	v_and_b32_e32 v145, 0x1c00, v145
	v_lshlrev_b32_e32 v146, 5, v144
	v_lshlrev_b32_e32 v147, 3, v147
	v_and_b32_e32 v147, 24, v147
	v_and_or_b32 v145, v146, s79, v145
	v_or3_b32 v151, v145, v147, s38
	v_lshlrev_b32_e32 v144, 8, v144
	v_and_b32_e32 v176, 0x3fc000, v144
	v_pk_fma_f32 v[146:147], v[94:95], v[150:151], v[46:47] op_sel_hi:[1,0,1]
	v_pk_fma_f32 v[144:145], v[92:93], v[150:151], v[44:45] op_sel_hi:[1,0,1]
	v_pk_fma_f32 v[148:149], v[90:91], v[150:151], v[42:43] op_sel_hi:[1,0,1]
	v_pk_fma_f32 v[152:153], v[88:89], v[150:151], v[40:41] op_sel_hi:[1,0,1]
	v_cvt_pk_bf16_f32 v144, v144, v145
	v_cvt_pk_bf16_f32 v145, v146, v147
	s_nop 0
	v_cvt_pk_bf16_f32 v146, v152, v153
	v_cvt_pk_bf16_f32 v147, v148, v149
	v_lshl_add_u64 v[148:149], s[0:1], 0, v[176:177]
	v_lshlrev_b32_e32 v152, 1, v151
	v_mov_b32_e32 v153, v177
	v_lshl_add_u64 v[148:149], v[148:149], 0, v[152:153]
	global_store_dwordx4 v[148:149], v[144:147], off
	v_pk_fma_f32 v[148:149], v[82:83], v[150:151], v[34:35] op_sel_hi:[1,0,1]
	s_add_i32 s0, s25, 0x80
	v_pk_fma_f32 v[146:147], v[86:87], v[150:151], v[38:39] op_sel_hi:[1,0,1]
	v_pk_fma_f32 v[144:145], v[84:85], v[150:151], v[36:37] op_sel_hi:[1,0,1]
	v_pk_fma_f32 v[150:151], v[80:81], v[150:151], v[32:33] op_sel_hi:[1,0,1]
	v_cvt_pk_bf16_f32 v144, v144, v145
	v_cvt_pk_bf16_f32 v145, v146, v147
	s_addk_i32 s25, 0xc080
	v_cvt_pk_bf16_f32 v146, v150, v151
	v_cvt_pk_bf16_f32 v147, v148, v149
	v_lshl_add_u64 v[148:149], s[14:15], 0, v[176:177]
	v_lshl_add_u64 v[148:149], v[148:149], 0, v[152:153]
	global_store_dwordx4 v[148:149], v[144:147], off
	v_or_b32_e32 v148, s0, v171
	v_ashrrev_i32_e32 v149, 31, v148
	v_lshl_add_u64 v[150:151], v[148:149], 2, s[16:17]
	global_load_dword v144, v[150:151], off
	global_load_dword v214, v[150:151], off offset:64
	global_load_dword v215, v[150:151], off offset:128
	global_load_dword v216, v[150:151], off offset:192
	s_ashr_i32 s14, s0, 13
	s_ashr_i32 s15, s25, 8
	s_waitcnt vmcnt(0) lgkmcnt(0)
	v_fmamk_f32 v144, v144, 0x3a800000, v224
	v_cmp_gt_f32_e32 vcc, s33, v144
	v_mul_f32_e32 v145, 0x4b800000, v144
	s_nop 0
	v_cndmask_b32_e32 v144, v144, v145, vcc
	v_rsq_f32_e32 v144, v144
	s_nop 0
	v_mul_f32_e32 v145, 0x45800000, v144
	v_cndmask_b32_e32 v154, v144, v145, vcc
	v_bitop3_b32 v145, s0, v228, v171 bitop3:0xc8
	v_bitop3_b32 v144, s0, v227, v171 bitop3:0xc8
	v_add_u32_e32 v145, 0x100, v145
	s_and_b64 s[0:1], s[4:5], exec
	s_cselect_b32 s0, s15, s14
	v_cndmask_b32_e64 v144, v145, v144, s[4:5]
	s_lshl_b32 s0, s0, 2
	v_lshrrev_b32_e32 v147, 2, v144
	s_add_i32 s7, s0, s7
	v_lshlrev_b32_e32 v145, 7, v144
	v_xor_b32_e32 v147, v147, v169
	v_and_b32_e32 v145, 0x400, v145
	v_lshlrev_b32_e32 v146, 5, v144
	v_lshlrev_b32_e32 v147, 3, v147
	s_mul_i32 s0, s7, 0x210000
	v_and_b32_e32 v147, 24, v147
	v_and_or_b32 v145, v146, s79, v145
	v_lshlrev_b32_e32 v144, 8, v144
	s_mul_hi_i32 s1, s7, 0x210000
	s_add_u32 s0, s72, s0
	v_or3_b32 v149, v145, v147, s38
	v_and_b32_e32 v176, 0x3fc000, v144
	v_pk_fma_f32 v[146:147], v[78:79], v[154:155], v[46:47] op_sel_hi:[1,0,1]
	v_pk_fma_f32 v[144:145], v[76:77], v[154:155], v[44:45] op_sel_hi:[1,0,1]
	v_pk_fma_f32 v[152:153], v[74:75], v[154:155], v[42:43] op_sel_hi:[1,0,1]
	v_pk_fma_f32 v[156:157], v[72:73], v[154:155], v[40:41] op_sel_hi:[1,0,1]
	s_addc_u32 s1, s73, s1
	s_or_b32 s7, s7, 1
	v_cvt_pk_bf16_f32 v144, v144, v145
	v_cvt_pk_bf16_f32 v145, v146, v147
	v_cvt_pk_bf16_f32 v146, v156, v157
; __device__ __forceinline__ unsigned pkbf(float lo, float hi) { return pg8::cvt_pk_bf16(lo, hi); }
;     __device__ __forceinline__ void operator()(const f32x4 (&acc)[2][2][4][2], const Unit& u, int wr, int wc, int fr, int fq) const {
;     ...
;             for (int ai = 0; ai < 2; ++ai)
; #pragma unroll
;                 for (int m = 0; m < 4; ++m) {
;                     const int row = pm * 256 + ai * 128 + wr * 64 + m * 16 + fr;
;                     const float rinv = rsqrtf(rowsq[row] * (1.f / DM) + EPSN);
;                     int b, kidx;
;                     if (isctx) { const int rc = row - MLAT; b = rc >> 8; kidx = rc & 255; } else { b = row >> 13; kidx = CTXL + (row & (SEQ - 1)); }
; #pragma unroll
;                     for (int bj = 0; bj < 2; ++bj) {
;                         const f32x4 y0 = acc[ai][bj][m][0] * rinv + bv[bj][0], y1 = acc[ai][bj][m][1] * rinv + bv[bj][1];
;                         u32x4 w; w.x = pkbf(y0[0], y0[1]); w.y = pkbf(y0[2], y0[3]); w.z = pkbf(y1[0], y1[1]); w.w = pkbf(y1[2], y1[3]);
;                         const int head = 2 * (pn - 4) + bj;
;                         const size_t off = (size_t)(b * 4 + head) * (LK * 128) + (size_t)(kidx >> 6) * 8192 + (size_t)(voff(kidx & 63, 4 * wc + fq) >> 1);
;                         *(u32x4*)(Vb + off) = w;
;                     }
;                 }
	v_cvt_pk_bf16_f32 v147, v152, v153
	v_lshl_add_u64 v[156:157], s[0:1], 0, v[176:177]
	v_lshlrev_b32_e32 v152, 1, v149
	v_mov_b32_e32 v153, v177
	s_mul_hi_i32 s15, s7, 0x210000
	s_mul_i32 s7, s7, 0x210000
	v_lshl_add_u64 v[156:157], v[156:157], 0, v[152:153]
	s_add_u32 s14, s72, s7
	global_store_dwordx4 v[156:157], v[144:147], off
	v_pk_fma_f32 v[156:157], v[66:67], v[154:155], v[34:35] op_sel_hi:[1,0,1]
	s_addc_u32 s15, s73, s15
	v_pk_fma_f32 v[146:147], v[70:71], v[154:155], v[38:39] op_sel_hi:[1,0,1]
	v_pk_fma_f32 v[144:145], v[68:69], v[154:155], v[36:37] op_sel_hi:[1,0,1]
	v_pk_fma_f32 v[154:155], v[64:65], v[154:155], v[32:33] op_sel_hi:[1,0,1]
	v_cvt_pk_bf16_f32 v144, v144, v145
	v_cvt_pk_bf16_f32 v145, v146, v147
	s_nop 0
	v_cvt_pk_bf16_f32 v146, v154, v155
	v_lshl_add_u64 v[154:155], s[14:15], 0, v[176:177]
	v_lshl_add_u64 v[152:153], v[154:155], 0, v[152:153]
	v_cvt_pk_bf16_f32 v147, v156, v157
	global_store_dwordx4 v[152:153], v[144:147], off
	s_nop 1
	v_fmamk_f32 v144, v214, 0x3a800000, v224
	v_cmp_gt_f32_e32 vcc, s33, v144
	v_mul_f32_e32 v145, 0x4b800000, v144
	s_nop 0
	v_cndmask_b32_e32 v144, v144, v145, vcc
	v_rsq_f32_e32 v144, v144
	s_nop 0
	v_mul_f32_e32 v145, 0x45800000, v144
	v_cndmask_b32_e32 v146, v144, v145, vcc
	v_bitop3_b32 v145, v148, s84, 16 bitop3:0xc8
	v_bitop3_b32 v144, v148, s95, 16 bitop3:0xc8
	v_add_u32_e32 v145, 0x100, v145
	v_cndmask_b32_e64 v144, v145, v144, s[4:5]
	v_lshrrev_b32_e32 v149, 2, v144
	v_lshlrev_b32_e32 v145, 7, v144
	v_xor_b32_e32 v149, v149, v169
	v_and_b32_e32 v145, 0xc00, v145
	v_lshlrev_b32_e32 v147, 5, v144
	v_lshlrev_b32_e32 v149, 3, v149
	v_and_b32_e32 v149, 24, v149
	v_and_or_b32 v145, v147, s79, v145
	v_or3_b32 v147, v145, v149, s38
	v_lshlrev_b32_e32 v144, 8, v144
	v_and_b32_e32 v176, 0x3fc000, v144
	v_pk_fma_f32 v[144:145], v[62:63], v[146:147], v[46:47] op_sel_hi:[1,0,1]
	v_pk_fma_f32 v[152:153], v[60:61], v[146:147], v[44:45] op_sel_hi:[1,0,1]
	v_pk_fma_f32 v[156:157], v[58:59], v[146:147], v[42:43] op_sel_hi:[1,0,1]
	v_pk_fma_f32 v[154:155], v[56:57], v[146:147], v[40:41] op_sel_hi:[1,0,1]
	v_cvt_pk_bf16_f32 v152, v152, v153
	v_cvt_pk_bf16_f32 v153, v144, v145
	v_lshlrev_b32_e32 v144, 1, v147
	v_cvt_pk_bf16_f32 v154, v154, v155
	v_cvt_pk_bf16_f32 v155, v156, v157
	v_lshl_add_u64 v[156:157], s[0:1], 0, v[176:177]
	v_mov_b32_e32 v145, v177
	v_lshl_add_u64 v[156:157], v[156:157], 0, v[144:145]
	global_store_dwordx4 v[156:157], v[152:155], off
	v_pk_fma_f32 v[156:157], v[50:51], v[146:147], v[34:35] op_sel_hi:[1,0,1]
	s_nop 0
	v_pk_fma_f32 v[154:155], v[54:55], v[146:147], v[38:39] op_sel_hi:[1,0,1]
	v_pk_fma_f32 v[152:153], v[52:53], v[146:147], v[36:37] op_sel_hi:[1,0,1]
	v_pk_fma_f32 v[146:147], v[48:49], v[146:147], v[32:33] op_sel_hi:[1,0,1]
	v_cvt_pk_bf16_f32 v152, v152, v153
	v_cvt_pk_bf16_f32 v153, v154, v155
	s_nop 0
	v_cvt_pk_bf16_f32 v154, v146, v147
	v_lshl_add_u64 v[146:147], s[14:15], 0, v[176:177]
	v_lshl_add_u64 v[144:145], v[146:147], 0, v[144:145]
	v_cvt_pk_bf16_f32 v155, v156, v157
	global_store_dwordx4 v[144:145], v[152:155], off
	s_nop 1
	v_fmamk_f32 v144, v215, 0x3a800000, v224
	v_cmp_gt_f32_e32 vcc, s33, v144
	v_mul_f32_e32 v145, 0x4b800000, v144
	s_nop 0
	v_cndmask_b32_e32 v144, v144, v145, vcc
	v_rsq_f32_e32 v144, v144
	s_nop 0
	v_mul_f32_e32 v145, 0x45800000, v144
	v_cndmask_b32_e32 v146, v144, v145, vcc
	v_bitop3_b32 v145, v148, s81, 32 bitop3:0xc8
	v_bitop3_b32 v144, v148, s80, 32 bitop3:0xc8
	v_add_u32_e32 v145, 0x100, v145
	v_cndmask_b32_e64 v144, v145, v144, s[4:5]
	v_lshrrev_b32_e32 v149, 2, v144
	v_lshlrev_b32_e32 v145, 7, v144
	v_xor_b32_e32 v149, v149, v169
; __device__ __forceinline__ unsigned pkbf(float lo, float hi) { return pg8::cvt_pk_bf16(lo, hi); }
;     __device__ __forceinline__ void operator()(const f32x4 (&acc)[2][2][4][2], const Unit& u, int wr, int wc, int fr, int fq) const {
;     ...
;             for (int ai = 0; ai < 2; ++ai)
; #pragma unroll
;                 for (int m = 0; m < 4; ++m) {
;                     const int row = pm * 256 + ai * 128 + wr * 64 + m * 16 + fr;
;                     const float rinv = rsqrtf(rowsq[row] * (1.f / DM) + EPSN);
;                     int b, kidx;
;                     if (isctx) { const int rc = row - MLAT; b = rc >> 8; kidx = rc & 255; } else { b = row >> 13; kidx = CTXL + (row & (SEQ - 1)); }
; #pragma unroll
;                     for (int bj = 0; bj < 2; ++bj) {
;                         const f32x4 y0 = acc[ai][bj][m][0] * rinv + bv[bj][0], y1 = acc[ai][bj][m][1] * rinv + bv[bj][1];
;                         u32x4 w; w.x = pkbf(y0[0], y0[1]); w.y = pkbf(y0[2], y0[3]); w.z = pkbf(y1[0], y1[1]); w.w = pkbf(y1[2], y1[3]);
;                         const int head = 2 * (pn - 4) + bj;
;                         const size_t off = (size_t)(b * 4 + head) * (LK * 128) + (size_t)(kidx >> 6) * 8192 + (size_t)(voff(kidx & 63, 4 * wc + fq) >> 1);
;                         *(u32x4*)(Vb + off) = w;
;                     }
;                 }
	v_and_b32_e32 v145, 0x1400, v145
	v_lshlrev_b32_e32 v147, 5, v144
	v_lshlrev_b32_e32 v149, 3, v149
	v_and_b32_e32 v149, 24, v149
	v_and_or_b32 v145, v147, s79, v145
	v_or3_b32 v147, v145, v149, s38
	v_lshlrev_b32_e32 v144, 8, v144
	v_and_b32_e32 v176, 0x3fc000, v144
	v_pk_fma_f32 v[144:145], v[30:31], v[146:147], v[46:47] op_sel_hi:[1,0,1]
	v_pk_fma_f32 v[152:153], v[28:29], v[146:147], v[44:45] op_sel_hi:[1,0,1]
	v_pk_fma_f32 v[156:157], v[26:27], v[146:147], v[42:43] op_sel_hi:[1,0,1]
	v_pk_fma_f32 v[154:155], v[24:25], v[146:147], v[40:41] op_sel_hi:[1,0,1]
	v_cvt_pk_bf16_f32 v152, v152, v153
	v_cvt_pk_bf16_f32 v153, v144, v145
	v_lshlrev_b32_e32 v144, 1, v147
	v_cvt_pk_bf16_f32 v154, v154, v155
	v_cvt_pk_bf16_f32 v155, v156, v157
	v_lshl_add_u64 v[156:157], s[0:1], 0, v[176:177]
	v_mov_b32_e32 v145, v177
	v_lshl_add_u64 v[156:157], v[156:157], 0, v[144:145]
	global_store_dwordx4 v[156:157], v[152:155], off
	v_pk_fma_f32 v[156:157], v[18:19], v[146:147], v[34:35] op_sel_hi:[1,0,1]
	s_nop 0
	v_pk_fma_f32 v[154:155], v[22:23], v[146:147], v[38:39] op_sel_hi:[1,0,1]
	v_pk_fma_f32 v[152:153], v[20:21], v[146:147], v[36:37] op_sel_hi:[1,0,1]
	v_pk_fma_f32 v[146:147], v[16:17], v[146:147], v[32:33] op_sel_hi:[1,0,1]
	v_cvt_pk_bf16_f32 v152, v152, v153
	v_cvt_pk_bf16_f32 v153, v154, v155
	s_nop 0
	v_cvt_pk_bf16_f32 v154, v146, v147
	v_lshl_add_u64 v[146:147], s[14:15], 0, v[176:177]
	v_lshl_add_u64 v[144:145], v[146:147], 0, v[144:145]
	v_cvt_pk_bf16_f32 v155, v156, v157
	global_store_dwordx4 v[144:145], v[152:155], off
	s_nop 1
	v_fmamk_f32 v144, v216, 0x3a800000, v224
	v_cmp_gt_f32_e32 vcc, s33, v144
	v_mul_f32_e32 v145, 0x4b800000, v144
	s_nop 0
	v_cndmask_b32_e32 v144, v144, v145, vcc
	v_rsq_f32_e32 v144, v144
	s_nop 0
	v_mul_f32_e32 v145, 0x45800000, v144
	v_cndmask_b32_e32 v150, v144, v145, vcc
	v_bitop3_b32 v145, v148, s68, 48 bitop3:0xc8
	v_bitop3_b32 v144, v148, s48, 48 bitop3:0xc8
	v_add_u32_e32 v145, 0x100, v145
	v_cndmask_b32_e64 v144, v145, v144, s[4:5]
	v_lshrrev_b32_e32 v147, 2, v144
	v_lshlrev_b32_e32 v145, 7, v144
	v_xor_b32_e32 v147, v147, v169
	v_and_b32_e32 v145, 0x1c00, v145
	v_lshlrev_b32_e32 v146, 5, v144
	v_lshlrev_b32_e32 v147, 3, v147
	v_and_b32_e32 v147, 24, v147
	v_and_or_b32 v145, v146, s79, v145
	v_or3_b32 v151, v145, v147, s38
	v_lshlrev_b32_e32 v144, 8, v144
	v_and_b32_e32 v176, 0x3fc000, v144
	v_pk_fma_f32 v[144:145], v[14:15], v[150:151], v[46:47] op_sel_hi:[1,0,1]
	v_pk_fma_f32 v[146:147], v[12:13], v[150:151], v[44:45] op_sel_hi:[1,0,1]
	v_pk_fma_f32 v[152:153], v[10:11], v[150:151], v[42:43] op_sel_hi:[1,0,1]
	v_pk_fma_f32 v[148:149], v[8:9], v[150:151], v[40:41] op_sel_hi:[1,0,1]
	v_cvt_pk_bf16_f32 v146, v146, v147
	v_cvt_pk_bf16_f32 v147, v144, v145
	v_lshlrev_b32_e32 v144, 1, v151
	v_cvt_pk_bf16_f32 v148, v148, v149
	v_cvt_pk_bf16_f32 v149, v152, v153
	v_lshl_add_u64 v[152:153], s[0:1], 0, v[176:177]
	v_mov_b32_e32 v145, v177
	v_lshl_add_u64 v[152:153], v[152:153], 0, v[144:145]
	global_store_dwordx4 v[152:153], v[146:149], off
	v_pk_fma_f32 v[152:153], v[2:3], v[150:151], v[34:35] op_sel_hi:[1,0,1]
	s_nop 0
	v_pk_fma_f32 v[148:149], v[6:7], v[150:151], v[38:39] op_sel_hi:[1,0,1]
	v_pk_fma_f32 v[146:147], v[4:5], v[150:151], v[36:37] op_sel_hi:[1,0,1]
	v_pk_fma_f32 v[150:151], v[0:1], v[150:151], v[32:33] op_sel_hi:[1,0,1]
	v_cvt_pk_bf16_f32 v146, v146, v147
	v_cvt_pk_bf16_f32 v147, v148, v149
	s_nop 0
	v_cvt_pk_bf16_f32 v148, v150, v151
	v_lshl_add_u64 v[150:151], s[14:15], 0, v[176:177]
	v_lshl_add_u64 v[144:145], v[150:151], 0, v[144:145]
	v_cvt_pk_bf16_f32 v149, v152, v153
	global_store_dwordx4 v[144:145], v[146:149], off

;     __device__ __forceinline__ void operator()(const f32x4 (&acc)[2][2][4][2], const Unit& u, int wr, int wc, int fr, int fq) const {
;     ...
;         if (pn < 4) {
;             const bool isq = pn < 2;
;             const float* gp = isq ? qg : kg;
;             f32x4 gv[2][2];
; #pragma unroll
;             for (int bj = 0; bj < 2; ++bj)
; #pragma unroll
;                 for (int n = 0; n < 2; ++n) gv[bj][n] = *(const f32x4*)(gp + 32 * bj + 8 * fq + 4 * n);
;             const int hc = (isq ? pn : pn - 2) * 4 + wc;
;             bf16_t* dst = isq ? Qb : Kb;
;             const float osc = isq ? QSCALE : 1.f;
; #pragma unroll
;             for (int ai = 0; ai < 2; ++ai)
; #pragma unroll
;                 for (int m = 0; m < 4; ++m) {
;                     const int row = pm * 256 + ai * 128 + wr * 64 + m * 16 + fr;
;                     const float rinv = rsqrtf(rowsq[row] * (1.f / DM) + EPSN);
;                     int b, kidx, t = 0;
;                     if (isctx) { const int rc = row - MLAT; b = rc >> 8; kidx = rc & 255; } else { b = row >> 13; t = row & (SEQ - 1); kidx = CTXL + t; }
;                     f32x4 val[2][2]; float ss = 0.f;
; #pragma unroll
;                     for (int bj = 0; bj < 2; ++bj)
; #pragma unroll
;                         for (int n = 0; n < 2; ++n) { val[bj][n] = acc[ai][bj][m][n] * rinv + bv[bj][n]; const f32x4 q = val[bj][n]; ss += (q[0] * q[0] + q[1] * q[1]) + (q[2] * q[2] + q[3] * q[3]); }
;                     ss += __shfl_xor(ss, 16); ss += __shfl_xor(ss, 32);
;                     const float rn = rsqrtf(ss * (1.f / 64.f) + EPSN);
; #pragma unroll
;                     for (int bj = 0; bj < 2; ++bj) {
;                         f32x4 y0 = val[bj][0] * rn * gv[bj][0], y1 = val[bj][1] * rn * gv[bj][1];
;                         if (!isctx) {
;                             const int pos = bj == 0 ? (t >> 6) : (t & 63);
;                             const f32x4 r0 = *(const f32x4*)(rope + (size_t)(pos * 16 + 4 * fq) * 2);
.LBB0_227:
	s_cmp_lt_i32 s36, 2
	s_cselect_b64 s[0:1], -1, 0
	v_readlane_b32 s56, v248, 18
	s_and_b64 s[14:15], s[0:1], exec
	v_readlane_b32 s57, v248, 19
	v_readlane_b32 s58, v248, 20
	v_readlane_b32 s59, v248, 21
	v_and_b32_e32 v186, 64, v229
	s_cselect_b32 s7, s57, s59
	s_cselect_b32 s25, s56, s58
	s_lshl_b64 s[14:15], s[76:77], 2
	v_xor_b32_e32 v176, 16, v229
	v_add_u32_e32 v186, 64, v186
	s_add_u32 s14, s25, s14
	v_cmp_lt_i32_e32 vcc, v176, v186
	s_addc_u32 s15, s7, s15
	s_lshl_b32 s25, s6, 8
	v_cndmask_b32_e32 v176, v229, v176, vcc
	s_add_i32 s25, s25, s75
	v_lshlrev_b32_e32 v201, 2, v176
	v_xor_b32_e32 v176, 32, v229
	v_cmp_lt_i32_e32 vcc, v176, v186
	v_or_b32_e32 v186, s25, v171
	v_ashrrev_i32_e32 v187, 31, v186
	v_cndmask_b32_e32 v176, v229, v176, vcc
	v_lshl_add_u64 v[188:189], v[186:187], 2, s[16:17]
	global_load_dwordx4 v[152:155], v200, s[14:15] offset:16
	global_load_dwordx4 v[156:159], v200, s[14:15]
	global_load_dwordx4 v[144:147], v200, s[14:15] offset:144
	global_load_dwordx4 v[148:151], v200, s[14:15] offset:128
	v_lshlrev_b32_e32 v202, 2, v176
	global_load_dword v176, v[188:189], off
	v_readlane_b32 s60, v248, 22
	v_readlane_b32 s61, v248, 23
	v_readlane_b32 s62, v248, 24
	v_readlane_b32 s63, v248, 25
	v_readlane_b32 s64, v248, 26
	v_readlane_b32 s65, v248, 27
	v_readlane_b32 s66, v248, 28
	v_readlane_b32 s67, v248, 29
	v_readlane_b32 s68, v248, 30
	v_readlane_b32 s69, v248, 31
	v_readlane_b32 s70, v248, 32
	v_readlane_b32 s71, v248, 33
	s_waitcnt vmcnt(0) lgkmcnt(0)
	v_fmamk_f32 v176, v176, 0x3a800000, v224
	v_cmp_gt_f32_e32 vcc, s33, v176
	v_mul_f32_e32 v187, 0x4b800000, v176
	s_nop 0
	v_cndmask_b32_e32 v176, v176, v187, vcc
	v_rsq_f32_e32 v176, v176
	s_nop 0
	v_mul_f32_e32 v187, 0x45800000, v176
	v_cndmask_b32_e32 v176, v176, v187, vcc
	v_pk_fma_f32 v[140:141], v[140:141], v[176:177], v[44:45] op_sel_hi:[1,0,1]
	v_pk_fma_f32 v[142:143], v[142:143], v[176:177], v[46:47] op_sel_hi:[1,0,1]
	v_pk_mul_f32 v[192:193], v[140:141], v[140:141]
	v_pk_mul_f32 v[190:191], v[142:143], v[142:143]
	v_pk_fma_f32 v[204:205], v[138:139], v[176:177], v[42:43] op_sel_hi:[1,0,1]
	v_pk_mov_b32 v[194:195], v[192:193], v[190:191] op_sel:[1,0]
	v_mov_b32_e32 v193, v191
	v_pk_add_f32 v[190:191], v[194:195], v[192:193]
	v_pk_fma_f32 v[192:193], v[136:137], v[176:177], v[40:41] op_sel_hi:[1,0,1]
	v_pk_mul_f32 v[136:137], v[204:205], v[204:205]
	v_pk_mul_f32 v[138:139], v[192:193], v[192:193]
	v_pk_fma_f32 v[132:133], v[132:133], v[176:177], v[36:37] op_sel_hi:[1,0,1]
	v_pk_mov_b32 v[194:195], v[138:139], v[136:137] op_sel:[1,0]
	v_mov_b32_e32 v139, v137
	v_pk_add_f32 v[136:137], v[194:195], v[138:139]
	v_pk_fma_f32 v[134:135], v[134:135], v[176:177], v[38:39] op_sel_hi:[1,0,1]
	v_pk_add_f32 v[138:139], v[136:137], v[136:137] op_sel_hi:[0,1]
	v_mul_f32_e32 v136, v132, v132
	v_pk_fma_f32 v[194:195], v[132:133], v[132:133], v[136:137] op_sel_hi:[1,1,0]
	v_mul_f32_e32 v136, v134, v134
	v_pk_add_f32 v[190:191], v[190:191], v[190:191] op_sel_hi:[0,1]
	v_pk_fma_f32 v[206:207], v[134:135], v[134:135], v[136:137] op_sel_hi:[1,1,0]
	v_pk_fma_f32 v[130:131], v[130:131], v[176:177], v[34:35] op_sel_hi:[1,0,1]
	v_pk_fma_f32 v[136:137], v[128:129], v[176:177], v[32:33] op_sel_hi:[1,0,1]
	v_mul_f32_e32 v190, v130, v130
	v_mul_f32_e32 v194, v136, v136
	v_mul_f32_e32 v206, v137, v137
	v_mul_f32_e32 v138, v131, v131
	v_pk_add_f32 v[128:129], v[194:195], v[206:207]
	v_pk_add_f32 v[138:139], v[190:191], v[138:139]
	s_nop 0
	v_pk_add_f32 v[128:129], v[128:129], v[138:139]
	s_nop 0
	v_add_f32_e32 v128, v128, v129
	ds_bpermute_b32 v129, v201, v128
	s_waitcnt lgkmcnt(0)
	v_add_f32_e32 v128, v128, v129
	ds_bpermute_b32 v129, v202, v128
	s_waitcnt lgkmcnt(0)
	v_add_f32_e32 v128, v128, v129
	v_fmamk_f32 v128, v128, 0x3c800000, v224
	v_cmp_gt_f32_e32 vcc, s33, v128
	v_mul_f32_e32 v129, 0x4b800000, v128
	s_nop 0
	v_cndmask_b32_e32 v128, v128, v129, vcc
	v_rsq_f32_e32 v128, v128
	s_nop 0
	v_mul_f32_e32 v129, 0x45800000, v128
	v_cndmask_b32_e32 v138, v128, v129, vcc
	v_pk_mul_f32 v[128:129], v[140:141], v[138:139] op_sel_hi:[1,0]
	v_pk_mul_f32 v[140:141], v[142:143], v[138:139] op_sel_hi:[1,0]
	v_pk_mul_f32 v[142:143], v[156:157], v[128:129]
	v_pk_mul_f32 v[194:195], v[158:159], v[140:141]
	v_pk_mul_f32 v[128:129], v[192:193], v[138:139] op_sel_hi:[1,0]
	v_pk_mul_f32 v[140:141], v[204:205], v[138:139] op_sel_hi:[1,0]
	s_andn2_b64 vcc, exec, s[54:55]
	v_pk_mul_f32 v[190:191], v[154:155], v[140:141]
	v_pk_mul_f32 v[140:141], v[152:153], v[128:129]
	v_cndmask_b32_e64 v128, 0, 1, s[54:55]
	v_cmp_ne_u32_e64 s[6:7], 1, v128
	s_cbranch_vccnz .LBB0_229
	s_lshr_b32 s14, s25, 1
	s_and_b32 s14, s14, 0xfe0
	v_or_b32_e32 v128, s14, v168
	v_lshlrev_b32_e32 v176, 2, v128
	v_lshl_add_u64 v[128:129], s[18:19], 0, v[176:177]
	global_load_dwordx4 v[204:207], v[128:129], off
	global_load_dwordx4 v[208:211], v[128:129], off offset:16
	s_waitcnt vmcnt(0) lgkmcnt(0)
	v_pk_mul_f32 v[192:193], v[142:143], v[204:205] op_sel:[1,1] op_sel_hi:[1,0]
	v_pk_mul_f32 v[128:129], v[142:143], v[204:205]
	v_pk_fma_f32 v[142:143], v[142:143], v[204:205], v[192:193] op_sel_hi:[0,1,1]
	v_mul_f32_e32 v142, v195, v207
	v_pk_fma_f32 v[204:205], v[194:195], v[206:207], v[142:143] op_sel_hi:[1,1,0] neg_lo:[0,0,1] neg_hi:[0,0,1]
	v_mul_f32_e32 v142, v195, v206
	v_pk_mul_f32 v[212:213], v[140:141], v[208:209] op_sel:[1,1] op_sel_hi:[1,0]
	v_pk_fma_f32 v[206:207], v[194:195], v[206:207], v[142:143] op_sel:[0,1,0] op_sel_hi:[1,0,0]
	v_pk_mul_f32 v[194:195], v[140:141], v[208:209]
	v_pk_fma_f32 v[140:141], v[140:141], v[208:209], v[212:213] op_sel_hi:[0,1,1]
	v_mul_f32_e32 v140, v191, v211
	v_pk_fma_f32 v[208:209], v[190:191], v[210:211], v[140:141] op_sel_hi:[1,1,0] neg_lo:[0,0,1] neg_hi:[0,0,1]
	v_mul_f32_e32 v140, v191, v210
	v_pk_fma_f32 v[210:211], v[190:191], v[210:211], v[140:141] op_sel:[0,1,0] op_sel_hi:[1,0,0]
	v_sub_f32_e32 v140, v194, v212
	v_sub_f32_e32 v142, v128, v192
	v_mov_b32_e32 v190, v208
	v_mov_b32_e32 v191, v210
	v_mov_b32_e32 v194, v204
	v_mov_b32_e32 v195, v206
; __device__ __forceinline__ unsigned pkbf(float lo, float hi) { return pg8::cvt_pk_bf16(lo, hi); }
;     __device__ __forceinline__ void operator()(const f32x4 (&acc)[2][2][4][2], const Unit& u, int wr, int wc, int fr, int fq) const {
;     ...
;                     for (int bj = 0; bj < 2; ++bj) {
;                         f32x4 y0 = val[bj][0] * rn * gv[bj][0], y1 = val[bj][1] * rn * gv[bj][1];
;                         if (!isctx) {
;                             const int pos = bj == 0 ? (t >> 6) : (t & 63);
;                             const f32x4 r0 = *(const f32x4*)(rope + (size_t)(pos * 16 + 4 * fq) * 2);
;                             const f32x4 r1 = *(const f32x4*)(rope + (size_t)(pos * 16 + 4 * fq + 2) * 2);
;                             f32x4 z0, z1;
;                             z0[0] = y0[0] * r0[0] - y0[1] * r0[1]; z0[1] = y0[0] * r0[1] + y0[1] * r0[0];
;                             z0[2] = y0[2] * r0[2] - y0[3] * r0[3]; z0[3] = y0[2] * r0[3] + y0[3] * r0[2];
;                             z1[0] = y1[0] * r1[0] - y1[1] * r1[1]; z1[1] = y1[0] * r1[1] + y1[1] * r1[0];
;                             z1[2] = y1[2] * r1[2] - y1[3] * r1[3]; z1[3] = y1[2] * r1[3] + y1[3] * r1[2];
;                             y0 = z0; y1 = z1;
;                         }
;                         y0 = y0 * osc; y1 = y1 * osc;
;                         u32x4 w; w.x = pkbf(y0[0], y0[1]); w.y = pkbf(y0[2], y0[3]); w.z = pkbf(y1[0], y1[1]); w.w = pkbf(y1[2], y1[3]);
;                         const size_t off = (size_t)(b * 8 + hc) * (LK * 64) + (size_t)(kidx >> 6) * 4096 + (size_t)(4 * bj + fq) * 512 + (size_t)(kidx & 63) * 8;
;                         *(u32x4*)(dst + off) = w;
.LBB0_229:
	s_lshl_b32 s27, s36, 2
	s_add_i32 s36, s27, -8
	s_and_b64 s[14:15], s[0:1], exec
	s_cselect_b32 s14, s27, s36
	s_or_b32 s27, s14, s74
	v_cndmask_b32_e64 v128, 1.0, v230, s[0:1]
	s_and_b64 s[0:1], s[0:1], exec
	s_mov_b32 s0, 0x8c00000
	s_cselect_b32 s0, s0, 0x9d00000
	s_add_u32 s36, s10, s0
	s_addc_u32 s54, s11, 0
	s_add_i32 s0, s25, 0xffffc000
	s_ashr_i32 s14, s25, 13
	s_ashr_i32 s15, s0, 8
	s_and_b64 s[0:1], s[4:5], exec
	s_cselect_b32 s0, s15, s14
	v_and_b32_e32 v129, 0x1fcf, v186
	s_lshl_b32 s0, s0, 3
	v_and_b32_e32 v176, 0xcf, v186
	v_add_u32_e32 v187, 0x100, v129
	s_add_i32 s0, s0, s27
	v_cndmask_b32_e64 v187, v187, v176, s[4:5]
	s_mul_hi_i32 s1, s0, 0x108000
	s_mul_i32 s0, s0, 0x108000
	s_add_u32 s14, s36, s0
	v_lshlrev_b32_e32 v176, 7, v187
	s_addc_u32 s15, s54, s1
	v_and_b32_e32 v176, 0x1fe000, v176
	v_lshl_add_u64 v[192:193], s[14:15], 0, v[176:177]
	v_lshlrev_b32_e32 v176, 4, v187
	v_and_b32_e32 v176, 0xf0, v176
	v_lshl_add_u64 v[192:193], v[192:193], 0, v[176:177]
	v_pk_mul_f32 v[142:143], v[128:129], v[142:143] op_sel_hi:[0,1]
	v_pk_mul_f32 v[190:191], v[128:129], v[190:191] op_sel_hi:[0,1]
	v_lshlrev_b32_e32 v176, 1, v170
	v_pk_mul_f32 v[194:195], v[128:129], v[194:195] op_sel_hi:[0,1]
	v_pk_mul_f32 v[204:205], v[128:129], v[140:141] op_sel_hi:[0,1]
	v_cvt_pk_bf16_f32 v140, v142, v143
	v_cvt_pk_bf16_f32 v141, v194, v195
	v_cvt_pk_bf16_f32 v142, v204, v205
	v_cvt_pk_bf16_f32 v143, v190, v191
	v_lshl_add_u64 v[190:191], v[192:193], 0, v[176:177]
	v_mov_b32_e32 v139, v138
	global_store_dwordx4 v[190:191], v[140:143], off
	v_pk_mul_f32 v[132:133], v[132:133], v[138:139]
	s_and_b64 vcc, exec, s[6:7]
	v_mov_b32_e32 v142, v138
	v_mov_b32_e32 v143, v138
	v_pk_mul_f32 v[134:135], v[134:135], v[142:143]
	v_pk_mul_f32 v[130:131], v[130:131], v[142:143]
	v_pk_mul_f32 v[140:141], v[150:151], v[134:135]
	v_pk_mul_f32 v[134:135], v[148:149], v[132:133]
	v_pk_mul_f32 v[132:133], v[136:137], v[138:139]
	v_pk_mul_f32 v[136:137], v[146:147], v[130:131]
	v_pk_mul_f32 v[130:131], v[144:145], v[132:133]
	s_cbranch_vccnz .LBB0_231
	v_lshlrev_b32_e32 v129, 5, v129
	s_movk_i32 s0, 0x1e0
	v_and_or_b32 v129, v129, s0, v168
	v_lshlrev_b32_e32 v132, 2, v129
	v_mov_b32_e32 v133, v177
	v_lshl_add_u64 v[132:133], s[18:19], 0, v[132:133]
	global_load_dwordx4 v[204:207], v[132:133], off
	global_load_dwordx4 v[208:211], v[132:133], off offset:16
	s_waitcnt vmcnt(0) lgkmcnt(0)
	v_pk_mul_f32 v[138:139], v[134:135], v[204:205] op_sel:[1,1] op_sel_hi:[1,0]
	v_pk_mul_f32 v[132:133], v[134:135], v[204:205]
	v_pk_fma_f32 v[134:135], v[134:135], v[204:205], v[138:139] op_sel_hi:[0,1,1]
	v_mul_f32_e32 v134, v141, v207
	v_pk_fma_f32 v[142:143], v[140:141], v[206:207], v[134:135] op_sel_hi:[1,1,0] neg_lo:[0,0,1] neg_hi:[0,0,1]
	v_mul_f32_e32 v134, v141, v206
	v_pk_mul_f32 v[194:195], v[130:131], v[208:209] op_sel:[1,1] op_sel_hi:[1,0]
	v_pk_fma_f32 v[190:191], v[140:141], v[206:207], v[134:135] op_sel:[0,1,0] op_sel_hi:[1,0,0]
	v_pk_mul_f32 v[140:141], v[130:131], v[208:209]
	v_pk_fma_f32 v[130:131], v[130:131], v[208:209], v[194:195] op_sel_hi:[0,1,1]
	v_mul_f32_e32 v130, v137, v211
	v_pk_fma_f32 v[204:205], v[136:137], v[210:211], v[130:131] op_sel_hi:[1,1,0] neg_lo:[0,0,1] neg_hi:[0,0,1]
	v_mul_f32_e32 v130, v137, v210
	v_pk_fma_f32 v[206:207], v[136:137], v[210:211], v[130:131] op_sel:[0,1,0] op_sel_hi:[1,0,0]
	v_sub_f32_e32 v130, v140, v194
	v_sub_f32_e32 v134, v132, v138
	v_mov_b32_e32 v136, v204
	v_mov_b32_e32 v137, v206
	v_mov_b32_e32 v140, v142
	v_mov_b32_e32 v141, v190
.LBB0_231:
	v_mov_b32_e32 v129, v128
	v_mov_b32_e32 v132, v128
	v_mov_b32_e32 v133, v128
	v_pk_mul_f32 v[134:135], v[128:129], v[134:135]
	v_pk_mul_f32 v[130:131], v[128:129], v[130:131]
	v_pk_mul_f32 v[138:139], v[132:133], v[140:141]
	v_pk_mul_f32 v[140:141], v[132:133], v[136:137]
	v_cvt_pk_bf16_f32 v134, v134, v135
	v_cvt_pk_bf16_f32 v135, v138, v139
	v_cvt_pk_bf16_f32 v136, v130, v131
	v_lshlrev_b32_e32 v130, 1, v172
	v_mov_b32_e32 v131, v177
	v_lshl_add_u64 v[138:139], v[192:193], 0, v[130:131]
	v_cvt_pk_bf16_f32 v137, v140, v141
	global_store_dwordx4 v[138:139], v[134:137], off
	global_load_dword v131, v[188:189], off offset:64
	s_movk_i32 s68, 0x1fff
	s_waitcnt vmcnt(0) lgkmcnt(0)
	v_fmamk_f32 v131, v131, 0x3a800000, v224
	v_cmp_gt_f32_e32 vcc, s33, v131
	v_mul_f32_e32 v134, 0x4b800000, v131
	s_nop 0
	v_cndmask_b32_e32 v131, v131, v134, vcc
	v_rsq_f32_e32 v131, v131
	s_nop 0
	v_mul_f32_e32 v134, 0x45800000, v131
	v_cndmask_b32_e32 v134, v131, v134, vcc
	v_pk_fma_f32 v[124:125], v[124:125], v[134:135], v[44:45] op_sel_hi:[1,0,1]
	v_pk_fma_f32 v[126:127], v[126:127], v[134:135], v[46:47] op_sel_hi:[1,0,1]
	v_pk_mul_f32 v[138:139], v[124:125], v[124:125]
	v_pk_mul_f32 v[136:137], v[126:127], v[126:127]
	v_pk_fma_f32 v[122:123], v[122:123], v[134:135], v[42:43] op_sel_hi:[1,0,1]
	v_pk_mov_b32 v[140:141], v[138:139], v[136:137] op_sel:[1,0]
	v_mov_b32_e32 v139, v137
	v_pk_add_f32 v[136:137], v[140:141], v[138:139]
	v_pk_fma_f32 v[138:139], v[120:121], v[134:135], v[40:41] op_sel_hi:[1,0,1]
	v_pk_mul_f32 v[120:121], v[122:123], v[122:123]
	v_pk_mul_f32 v[140:141], v[138:139], v[138:139]
	v_pk_fma_f32 v[116:117], v[116:117], v[134:135], v[36:37] op_sel_hi:[1,0,1]
	v_pk_mov_b32 v[142:143], v[140:141], v[120:121] op_sel:[1,0]
	v_mov_b32_e32 v141, v121
	v_pk_add_f32 v[120:121], v[142:143], v[140:141]
	v_pk_fma_f32 v[118:119], v[118:119], v[134:135], v[38:39] op_sel_hi:[1,0,1]
	v_pk_add_f32 v[120:121], v[120:121], v[120:121] op_sel_hi:[0,1]
	v_mul_f32_e32 v120, v116, v116
	v_pk_fma_f32 v[140:141], v[116:117], v[116:117], v[120:121] op_sel_hi:[1,1,0]
	v_mul_f32_e32 v120, v118, v118
	v_pk_add_f32 v[136:137], v[136:137], v[136:137] op_sel_hi:[0,1]
	v_pk_fma_f32 v[142:143], v[118:119], v[118:119], v[120:121] op_sel_hi:[1,1,0]
	v_pk_fma_f32 v[114:115], v[114:115], v[134:135], v[34:35] op_sel_hi:[1,0,1]
	v_pk_fma_f32 v[112:113], v[112:113], v[134:135], v[32:33] op_sel_hi:[1,0,1]
	v_mul_f32_e32 v136, v114, v114
	v_mul_f32_e32 v140, v112, v112
	v_mul_f32_e32 v142, v113, v113
	v_mul_f32_e32 v120, v115, v115
	v_pk_add_f32 v[134:135], v[140:141], v[142:143]
	v_pk_add_f32 v[120:121], v[136:137], v[120:121]
	s_nop 0
	v_pk_add_f32 v[120:121], v[134:135], v[120:121]
	s_nop 0
	v_add_f32_e32 v120, v120, v121
	ds_bpermute_b32 v121, v201, v120
	s_waitcnt lgkmcnt(0)
; __device__ __forceinline__ unsigned pkbf(float lo, float hi) { return pg8::cvt_pk_bf16(lo, hi); }
;     __device__ __forceinline__ void operator()(const f32x4 (&acc)[2][2][4][2], const Unit& u, int wr, int wc, int fr, int fq) const {
;     ...
; #pragma unroll
;                         for (int n = 0; n < 2; ++n) { val[bj][n] = acc[ai][bj][m][n] * rinv + bv[bj][n]; const f32x4 q = val[bj][n]; ss += (q[0] * q[0] + q[1] * q[1]) + (q[2] * q[2] + q[3] * q[3]); }
;                     ss += __shfl_xor(ss, 16); ss += __shfl_xor(ss, 32);
;                     const float rn = rsqrtf(ss * (1.f / 64.f) + EPSN);
; #pragma unroll
;                     for (int bj = 0; bj < 2; ++bj) {
;                         f32x4 y0 = val[bj][0] * rn * gv[bj][0], y1 = val[bj][1] * rn * gv[bj][1];
;                         if (!isctx) {
;                             const int pos = bj == 0 ? (t >> 6) : (t & 63);
;                             const f32x4 r0 = *(const f32x4*)(rope + (size_t)(pos * 16 + 4 * fq) * 2);
;                             const f32x4 r1 = *(const f32x4*)(rope + (size_t)(pos * 16 + 4 * fq + 2) * 2);
;                             f32x4 z0, z1;
;                             z0[0] = y0[0] * r0[0] - y0[1] * r0[1]; z0[1] = y0[0] * r0[1] + y0[1] * r0[0];
;                             z0[2] = y0[2] * r0[2] - y0[3] * r0[3]; z0[3] = y0[2] * r0[3] + y0[3] * r0[2];
;                             z1[0] = y1[0] * r1[0] - y1[1] * r1[1]; z1[1] = y1[0] * r1[1] + y1[1] * r1[0];
;                             z1[2] = y1[2] * r1[2] - y1[3] * r1[3]; z1[3] = y1[2] * r1[3] + y1[3] * r1[2];
;                             y0 = z0; y1 = z1;
;                         }
;                         y0 = y0 * osc; y1 = y1 * osc;
;                         u32x4 w; w.x = pkbf(y0[0], y0[1]); w.y = pkbf(y0[2], y0[3]); w.z = pkbf(y1[0], y1[1]); w.w = pkbf(y1[2], y1[3]);
;                         const size_t off = (size_t)(b * 8 + hc) * (LK * 64) + (size_t)(kidx >> 6) * 4096 + (size_t)(4 * bj + fq) * 512 + (size_t)(kidx & 63) * 8;
;                         *(u32x4*)(dst + off) = w;
	v_add_f32_e32 v120, v120, v121
	ds_bpermute_b32 v121, v202, v120
	s_waitcnt lgkmcnt(0)
	v_add_f32_e32 v120, v120, v121
	v_fmamk_f32 v120, v120, 0x3c800000, v224
	v_cmp_gt_f32_e32 vcc, s33, v120
	v_mul_f32_e32 v121, 0x4b800000, v120
	s_nop 0
	v_cndmask_b32_e32 v120, v120, v121, vcc
	v_rsq_f32_e32 v120, v120
	s_nop 0
	v_mul_f32_e32 v121, 0x45800000, v120
	v_cndmask_b32_e32 v120, v120, v121, vcc
	v_pk_mul_f32 v[124:125], v[124:125], v[120:121] op_sel_hi:[1,0]
	v_pk_mul_f32 v[126:127], v[126:127], v[120:121] op_sel_hi:[1,0]
	v_pk_mul_f32 v[134:135], v[138:139], v[120:121] op_sel_hi:[1,0]
	v_pk_mul_f32 v[122:123], v[122:123], v[120:121] op_sel_hi:[1,0]
	v_pk_mul_f32 v[136:137], v[158:159], v[126:127]
	v_pk_mul_f32 v[124:125], v[156:157], v[124:125]
	v_pk_mul_f32 v[126:127], v[154:155], v[122:123]
	v_pk_mul_f32 v[122:123], v[152:153], v[134:135]
	s_and_b64 vcc, exec, s[6:7]
	s_cbranch_vccnz .LBB0_233
	s_lshr_b32 s0, s25, 1
	s_and_b32 s0, s0, 0xfe0
	v_or_b32_e32 v121, s0, v168
	v_lshlrev_b32_e32 v134, 2, v121
	v_mov_b32_e32 v135, v177
	v_lshl_add_u64 v[134:135], s[18:19], 0, v[134:135]
	global_load_dwordx4 v[138:141], v[134:135], off
	global_load_dwordx4 v[190:193], v[134:135], off offset:16
	s_waitcnt vmcnt(0) lgkmcnt(0)
	v_pk_mul_f32 v[142:143], v[124:125], v[138:139] op_sel:[1,1] op_sel_hi:[1,0]
	v_pk_mul_f32 v[134:135], v[124:125], v[138:139]
	v_pk_fma_f32 v[124:125], v[124:125], v[138:139], v[142:143] op_sel_hi:[0,1,1]
	v_mul_f32_e32 v124, v137, v141
	v_pk_fma_f32 v[138:139], v[136:137], v[140:141], v[124:125] op_sel_hi:[1,1,0] neg_lo:[0,0,1] neg_hi:[0,0,1]
	v_mul_f32_e32 v124, v137, v140
	v_pk_mul_f32 v[194:195], v[122:123], v[190:191] op_sel:[1,1] op_sel_hi:[1,0]
	v_pk_fma_f32 v[140:141], v[136:137], v[140:141], v[124:125] op_sel:[0,1,0] op_sel_hi:[1,0,0]
	v_pk_mul_f32 v[136:137], v[122:123], v[190:191]
	v_pk_fma_f32 v[122:123], v[122:123], v[190:191], v[194:195] op_sel_hi:[0,1,1]
	v_mul_f32_e32 v122, v127, v193
	v_pk_fma_f32 v[190:191], v[126:127], v[192:193], v[122:123] op_sel_hi:[1,1,0] neg_lo:[0,0,1] neg_hi:[0,0,1]
	v_mul_f32_e32 v122, v127, v192
	v_pk_fma_f32 v[192:193], v[126:127], v[192:193], v[122:123] op_sel:[0,1,0] op_sel_hi:[1,0,0]
	v_sub_f32_e32 v122, v136, v194
	v_sub_f32_e32 v124, v134, v142
	v_mov_b32_e32 v126, v190
	v_mov_b32_e32 v127, v192
	v_mov_b32_e32 v136, v138
	v_mov_b32_e32 v137, v140
.LBB0_233:
	v_bitop3_b32 v131, v186, s84, 16 bitop3:0xc8
	v_bitop3_b32 v134, v186, s95, 16 bitop3:0xc8
	v_add_u32_e32 v135, 0x100, v131
	v_cndmask_b32_e64 v138, v135, v134, s[4:5]
	v_lshlrev_b32_e32 v134, 7, v138
	v_and_b32_e32 v134, 0x1fe000, v134
	v_mov_b32_e32 v135, v177
	v_lshlrev_b32_e32 v138, 4, v138
	v_lshl_add_u64 v[134:135], s[14:15], 0, v[134:135]
	v_and_b32_e32 v138, 0x1f0, v138
	v_mov_b32_e32 v139, v177
	v_lshl_add_u64 v[134:135], v[134:135], 0, v[138:139]
	v_pk_mul_f32 v[124:125], v[128:129], v[124:125]
	v_pk_mul_f32 v[126:127], v[132:133], v[126:127]
	v_pk_mul_f32 v[136:137], v[132:133], v[136:137]
	v_pk_mul_f32 v[132:133], v[128:129], v[122:123]
	v_cvt_pk_bf16_f32 v122, v124, v125
	v_cvt_pk_bf16_f32 v123, v136, v137
	v_mov_b32_e32 v121, v120
	v_cvt_pk_bf16_f32 v124, v132, v133
	v_cvt_pk_bf16_f32 v125, v126, v127
	v_lshl_add_u64 v[126:127], v[134:135], 0, v[176:177]
	global_store_dwordx4 v[126:127], v[122:125], off
	v_pk_mul_f32 v[116:117], v[116:117], v[120:121]
	v_pk_mul_f32 v[112:113], v[112:113], v[120:121]
	v_mov_b32_e32 v124, v120
	v_mov_b32_e32 v125, v120
	v_pk_mul_f32 v[118:119], v[118:119], v[124:125]
	v_pk_mul_f32 v[114:115], v[114:115], v[124:125]
	v_pk_mul_f32 v[122:123], v[150:151], v[118:119]
	v_pk_mul_f32 v[116:117], v[148:149], v[116:117]
	v_pk_mul_f32 v[118:119], v[146:147], v[114:115]
	s_and_b64 vcc, exec, s[6:7]
	v_pk_mul_f32 v[114:115], v[144:145], v[112:113]
	s_cbranch_vccnz .LBB0_235
	v_lshlrev_b32_e32 v112, 5, v131
	s_movk_i32 s0, 0x3e0
	v_and_or_b32 v112, v112, s0, v168
	v_lshlrev_b32_e32 v112, 2, v112
	v_mov_b32_e32 v113, v177
	v_lshl_add_u64 v[112:113], s[18:19], 0, v[112:113]
	global_load_dwordx4 v[124:127], v[112:113], off
	global_load_dwordx4 v[136:139], v[112:113], off offset:16
	s_waitcnt vmcnt(0) lgkmcnt(0)
	v_pk_mul_f32 v[120:121], v[116:117], v[124:125] op_sel:[1,1] op_sel_hi:[1,0]
	v_pk_mul_f32 v[112:113], v[116:117], v[124:125]
	v_pk_fma_f32 v[116:117], v[116:117], v[124:125], v[120:121] op_sel_hi:[0,1,1]
	v_mul_f32_e32 v116, v123, v127
	v_pk_fma_f32 v[124:125], v[122:123], v[126:127], v[116:117] op_sel_hi:[1,1,0] neg_lo:[0,0,1] neg_hi:[0,0,1]
	v_mul_f32_e32 v116, v123, v126
	v_pk_mul_f32 v[132:133], v[114:115], v[136:137] op_sel:[1,1] op_sel_hi:[1,0]
	v_pk_fma_f32 v[126:127], v[122:123], v[126:127], v[116:117] op_sel:[0,1,0] op_sel_hi:[1,0,0]
	v_pk_mul_f32 v[122:123], v[114:115], v[136:137]
	v_pk_fma_f32 v[114:115], v[114:115], v[136:137], v[132:133] op_sel_hi:[0,1,1]
	v_mul_f32_e32 v114, v119, v139
	v_pk_fma_f32 v[136:137], v[118:119], v[138:139], v[114:115] op_sel_hi:[1,1,0] neg_lo:[0,0,1] neg_hi:[0,0,1]
	v_mul_f32_e32 v114, v119, v138
	v_pk_fma_f32 v[138:139], v[118:119], v[138:139], v[114:115] op_sel:[0,1,0] op_sel_hi:[1,0,0]
	v_sub_f32_e32 v114, v122, v132
	v_sub_f32_e32 v116, v112, v120
	v_mov_b32_e32 v118, v136
	v_mov_b32_e32 v119, v138
	v_mov_b32_e32 v122, v124
	v_mov_b32_e32 v123, v126
; __device__ __forceinline__ unsigned pkbf(float lo, float hi) { return pg8::cvt_pk_bf16(lo, hi); }
;     __device__ __forceinline__ void operator()(const f32x4 (&acc)[2][2][4][2], const Unit& u, int wr, int wc, int fr, int fq) const {
;     ...
;                 for (int m = 0; m < 4; ++m) {
;                     const int row = pm * 256 + ai * 128 + wr * 64 + m * 16 + fr;
;                     const float rinv = rsqrtf(rowsq[row] * (1.f / DM) + EPSN);
;                     int b, kidx, t = 0;
;                     if (isctx) { const int rc = row - MLAT; b = rc >> 8; kidx = rc & 255; } else { b = row >> 13; t = row & (SEQ - 1); kidx = CTXL + t; }
;                     f32x4 val[2][2]; float ss = 0.f;
; #pragma unroll
;                     for (int bj = 0; bj < 2; ++bj)
; #pragma unroll
;                         for (int n = 0; n < 2; ++n) { val[bj][n] = acc[ai][bj][m][n] * rinv + bv[bj][n]; const f32x4 q = val[bj][n]; ss += (q[0] * q[0] + q[1] * q[1]) + (q[2] * q[2] + q[3] * q[3]); }
;                     ss += __shfl_xor(ss, 16); ss += __shfl_xor(ss, 32);
;                     const float rn = rsqrtf(ss * (1.f / 64.f) + EPSN);
; #pragma unroll
;                     for (int bj = 0; bj < 2; ++bj) {
;                         f32x4 y0 = val[bj][0] * rn * gv[bj][0], y1 = val[bj][1] * rn * gv[bj][1];
;                         if (!isctx) {
;                             const int pos = bj == 0 ? (t >> 6) : (t & 63);
;                             const f32x4 r0 = *(const f32x4*)(rope + (size_t)(pos * 16 + 4 * fq) * 2);
;                             const f32x4 r1 = *(const f32x4*)(rope + (size_t)(pos * 16 + 4 * fq + 2) * 2);
;                             f32x4 z0, z1;
;                             z0[0] = y0[0] * r0[0] - y0[1] * r0[1]; z0[1] = y0[0] * r0[1] + y0[1] * r0[0];
;                             z0[2] = y0[2] * r0[2] - y0[3] * r0[3]; z0[3] = y0[2] * r0[3] + y0[3] * r0[2];
;                             z1[0] = y1[0] * r1[0] - y1[1] * r1[1]; z1[1] = y1[0] * r1[1] + y1[1] * r1[0];
;                             z1[2] = y1[2] * r1[2] - y1[3] * r1[3]; z1[3] = y1[2] * r1[3] + y1[3] * r1[2];
;                             y0 = z0; y1 = z1;
;                         }
;                         y0 = y0 * osc; y1 = y1 * osc;
;                         u32x4 w; w.x = pkbf(y0[0], y0[1]); w.y = pkbf(y0[2], y0[3]); w.z = pkbf(y1[0], y1[1]); w.w = pkbf(y1[2], y1[3]);
.LBB0_235:
	v_mov_b32_e32 v112, v128
	v_mov_b32_e32 v113, v128
	v_pk_mul_f32 v[116:117], v[128:129], v[116:117]
	v_pk_mul_f32 v[118:119], v[112:113], v[118:119]
	v_mov_b32_e32 v131, v177
	v_pk_mul_f32 v[120:121], v[112:113], v[122:123]
	v_pk_mul_f32 v[122:123], v[128:129], v[114:115]
	v_cvt_pk_bf16_f32 v114, v116, v117
	v_cvt_pk_bf16_f32 v115, v120, v121
	s_nop 0
	v_cvt_pk_bf16_f32 v116, v122, v123
	v_cvt_pk_bf16_f32 v117, v118, v119
	v_lshl_add_u64 v[118:119], v[134:135], 0, v[130:131]
	global_store_dwordx4 v[118:119], v[114:117], off
	global_load_dword v114, v[188:189], off offset:128
	s_waitcnt vmcnt(0) lgkmcnt(0)
	v_fmamk_f32 v114, v114, 0x3a800000, v224
	v_mul_f32_e32 v115, 0x4b800000, v114
	v_cmp_gt_f32_e32 vcc, s33, v114
	s_nop 1
	v_cndmask_b32_e32 v114, v114, v115, vcc
	v_rsq_f32_e32 v114, v114
	s_nop 0
	v_mul_f32_e32 v115, 0x45800000, v114
	v_cndmask_b32_e32 v114, v114, v115, vcc
	v_pk_fma_f32 v[108:109], v[108:109], v[114:115], v[44:45] op_sel_hi:[1,0,1]
	v_pk_fma_f32 v[110:111], v[110:111], v[114:115], v[46:47] op_sel_hi:[1,0,1]
	v_pk_fma_f32 v[104:105], v[104:105], v[114:115], v[40:41] op_sel_hi:[1,0,1]
	v_pk_fma_f32 v[116:117], v[106:107], v[114:115], v[42:43] op_sel_hi:[1,0,1]
	v_pk_fma_f32 v[102:103], v[102:103], v[114:115], v[38:39] op_sel_hi:[1,0,1]
	v_pk_fma_f32 v[100:101], v[100:101], v[114:115], v[36:37] op_sel_hi:[1,0,1]
	v_pk_fma_f32 v[98:99], v[98:99], v[114:115], v[34:35] op_sel_hi:[1,0,1]
	v_pk_fma_f32 v[96:97], v[96:97], v[114:115], v[32:33] op_sel_hi:[1,0,1]
	v_pk_mul_f32 v[106:107], v[110:111], v[110:111]
	v_pk_mul_f32 v[114:115], v[108:109], v[108:109]
	v_pk_mul_f32 v[118:119], v[116:117], v[116:117]
	v_pk_mul_f32 v[120:121], v[104:105], v[104:105]
	v_pk_mov_b32 v[126:127], v[114:115], v[106:107] op_sel:[1,0]
	v_mov_b32_e32 v115, v107
	v_pk_mov_b32 v[106:107], v[120:121], v[118:119] op_sel:[1,0]
	v_mov_b32_e32 v121, v119
	v_mul_f32_e32 v122, v100, v100
	v_mul_f32_e32 v124, v102, v102
	v_pk_add_f32 v[114:115], v[126:127], v[114:115]
	v_pk_add_f32 v[106:107], v[106:107], v[120:121]
	v_pk_fma_f32 v[118:119], v[100:101], v[100:101], v[122:123] op_sel_hi:[1,1,0]
	v_pk_fma_f32 v[122:123], v[102:103], v[102:103], v[124:125] op_sel_hi:[1,1,0]
	v_pk_add_f32 v[114:115], v[114:115], v[114:115] op_sel_hi:[0,1]
	v_pk_add_f32 v[106:107], v[106:107], v[106:107] op_sel_hi:[0,1]
	v_mul_f32_e32 v118, v96, v96
	v_mul_f32_e32 v122, v97, v97
	v_mul_f32_e32 v114, v98, v98
	v_mul_f32_e32 v106, v99, v99
	v_pk_add_f32 v[118:119], v[118:119], v[122:123]
	v_pk_add_f32 v[106:107], v[114:115], v[106:107]
	s_and_b64 vcc, exec, s[6:7]
	v_pk_add_f32 v[106:107], v[118:119], v[106:107]
	s_nop 0
	v_add_f32_e32 v106, v106, v107
	ds_bpermute_b32 v107, v201, v106
	s_waitcnt lgkmcnt(0)
	v_add_f32_e32 v106, v106, v107
	ds_bpermute_b32 v107, v202, v106
	s_waitcnt lgkmcnt(0)
	v_add_f32_e32 v106, v106, v107
	v_fmamk_f32 v106, v106, 0x3c800000, v224
	v_mul_f32_e32 v107, 0x4b800000, v106
	v_cmp_gt_f32_e64 s[0:1], s33, v106
	s_nop 1
	v_cndmask_b32_e64 v106, v106, v107, s[0:1]
	v_rsq_f32_e32 v106, v106
	s_nop 0
	v_mul_f32_e32 v107, 0x45800000, v106
	v_cndmask_b32_e64 v106, v106, v107, s[0:1]
	v_pk_mul_f32 v[108:109], v[108:109], v[106:107] op_sel_hi:[1,0]
	v_pk_mul_f32 v[110:111], v[110:111], v[106:107] op_sel_hi:[1,0]
	v_pk_mul_f32 v[104:105], v[104:105], v[106:107] op_sel_hi:[1,0]
	v_pk_mul_f32 v[114:115], v[116:117], v[106:107] op_sel_hi:[1,0]
	v_pk_mul_f32 v[116:117], v[158:159], v[110:111]
	v_pk_mul_f32 v[110:111], v[156:157], v[108:109]
	v_pk_mul_f32 v[114:115], v[154:155], v[114:115]
	v_pk_mul_f32 v[108:109], v[152:153], v[104:105]
	s_cbranch_vccnz .LBB0_237
	s_lshr_b32 s0, s25, 1
	s_and_b32 s0, s0, 0xfe0
	v_or_b32_e32 v104, s0, v168
	v_lshlrev_b32_e32 v104, 2, v104
	v_mov_b32_e32 v105, v177
	v_lshl_add_u64 v[104:105], s[18:19], 0, v[104:105]
	global_load_dwordx4 v[118:121], v[104:105], off
	global_load_dwordx4 v[122:125], v[104:105], off offset:16
	s_waitcnt vmcnt(0) lgkmcnt(0)
	v_pk_mul_f32 v[126:127], v[110:111], v[118:119] op_sel:[1,1] op_sel_hi:[1,0]
	v_pk_mul_f32 v[104:105], v[110:111], v[118:119]
	v_pk_fma_f32 v[110:111], v[110:111], v[118:119], v[126:127] op_sel_hi:[0,1,1]
	v_mul_f32_e32 v110, v117, v121
	v_pk_fma_f32 v[118:119], v[116:117], v[120:121], v[110:111] op_sel_hi:[1,1,0] neg_lo:[0,0,1] neg_hi:[0,0,1]
	v_mul_f32_e32 v110, v117, v120
	v_pk_mul_f32 v[132:133], v[108:109], v[122:123] op_sel:[1,1] op_sel_hi:[1,0]
	v_pk_fma_f32 v[120:121], v[116:117], v[120:121], v[110:111] op_sel:[0,1,0] op_sel_hi:[1,0,0]
	v_pk_mul_f32 v[116:117], v[108:109], v[122:123]
	v_pk_fma_f32 v[108:109], v[108:109], v[122:123], v[132:133] op_sel_hi:[0,1,1]
	v_mul_f32_e32 v108, v115, v125
	v_pk_fma_f32 v[122:123], v[114:115], v[124:125], v[108:109] op_sel_hi:[1,1,0] neg_lo:[0,0,1] neg_hi:[0,0,1]
	v_mul_f32_e32 v108, v115, v124
	v_pk_fma_f32 v[124:125], v[114:115], v[124:125], v[108:109] op_sel:[0,1,0] op_sel_hi:[1,0,0]
	v_sub_f32_e32 v108, v116, v132
	v_sub_f32_e32 v110, v104, v126
	v_mov_b32_e32 v114, v122
	v_mov_b32_e32 v115, v124
	v_mov_b32_e32 v116, v118
	v_mov_b32_e32 v117, v120
; __device__ __forceinline__ unsigned pkbf(float lo, float hi) { return pg8::cvt_pk_bf16(lo, hi); }
;     __device__ __forceinline__ void operator()(const f32x4 (&acc)[2][2][4][2], const Unit& u, int wr, int wc, int fr, int fq) const {
;     ...
;                 for (int m = 0; m < 4; ++m) {
;                     const int row = pm * 256 + ai * 128 + wr * 64 + m * 16 + fr;
;                     const float rinv = rsqrtf(rowsq[row] * (1.f / DM) + EPSN);
;                     int b, kidx, t = 0;
;                     if (isctx) { const int rc = row - MLAT; b = rc >> 8; kidx = rc & 255; } else { b = row >> 13; t = row & (SEQ - 1); kidx = CTXL + t; }
;                     f32x4 val[2][2]; float ss = 0.f;
; #pragma unroll
;                     for (int bj = 0; bj < 2; ++bj)
; #pragma unroll
;                         for (int n = 0; n < 2; ++n) { val[bj][n] = acc[ai][bj][m][n] * rinv + bv[bj][n]; const f32x4 q = val[bj][n]; ss += (q[0] * q[0] + q[1] * q[1]) + (q[2] * q[2] + q[3] * q[3]); }
;                     ss += __shfl_xor(ss, 16); ss += __shfl_xor(ss, 32);
;                     const float rn = rsqrtf(ss * (1.f / 64.f) + EPSN);
; #pragma unroll
;                     for (int bj = 0; bj < 2; ++bj) {
;                         f32x4 y0 = val[bj][0] * rn * gv[bj][0], y1 = val[bj][1] * rn * gv[bj][1];
;                         if (!isctx) {
;                             const int pos = bj == 0 ? (t >> 6) : (t & 63);
;                             const f32x4 r0 = *(const f32x4*)(rope + (size_t)(pos * 16 + 4 * fq) * 2);
;                             const f32x4 r1 = *(const f32x4*)(rope + (size_t)(pos * 16 + 4 * fq + 2) * 2);
;                             f32x4 z0, z1;
;                             z0[0] = y0[0] * r0[0] - y0[1] * r0[1]; z0[1] = y0[0] * r0[1] + y0[1] * r0[0];
;                             z0[2] = y0[2] * r0[2] - y0[3] * r0[3]; z0[3] = y0[2] * r0[3] + y0[3] * r0[2];
;                             z1[0] = y1[0] * r1[0] - y1[1] * r1[1]; z1[1] = y1[0] * r1[1] + y1[1] * r1[0];
;                             z1[2] = y1[2] * r1[2] - y1[3] * r1[3]; z1[3] = y1[2] * r1[3] + y1[3] * r1[2];
;                             y0 = z0; y1 = z1;
;                         }
;                         y0 = y0 * osc; y1 = y1 * osc;
;                         u32x4 w; w.x = pkbf(y0[0], y0[1]); w.y = pkbf(y0[2], y0[3]); w.z = pkbf(y1[0], y1[1]); w.w = pkbf(y1[2], y1[3]);
.LBB0_237:
	v_bitop3_b32 v118, v186, s81, 32 bitop3:0xc8
	v_bitop3_b32 v104, v186, s80, 32 bitop3:0xc8
	v_add_u32_e32 v105, 0x100, v118
	v_cndmask_b32_e64 v119, v105, v104, s[4:5]
	v_lshlrev_b32_e32 v104, 7, v119
	v_and_b32_e32 v104, 0x1fe000, v104
	v_mov_b32_e32 v105, v177
	v_lshlrev_b32_e32 v119, 4, v119
	v_lshl_add_u64 v[104:105], s[14:15], 0, v[104:105]
	v_and_b32_e32 v120, 0x2f0, v119
	v_mov_b32_e32 v121, v177
	v_lshl_add_u64 v[104:105], v[104:105], 0, v[120:121]
	v_pk_mul_f32 v[116:117], v[112:113], v[116:117]
	v_pk_mul_f32 v[110:111], v[128:129], v[110:111]
	v_pk_mul_f32 v[112:113], v[112:113], v[114:115]
	v_pk_mul_f32 v[114:115], v[128:129], v[108:109]
	v_cvt_pk_bf16_f32 v108, v110, v111
	v_cvt_pk_bf16_f32 v109, v116, v117
	v_mov_b32_e32 v107, v106
	v_cvt_pk_bf16_f32 v110, v114, v115
	v_cvt_pk_bf16_f32 v111, v112, v113
	v_lshl_add_u64 v[112:113], v[104:105], 0, v[176:177]
	global_store_dwordx4 v[112:113], v[108:111], off
	v_pk_mul_f32 v[100:101], v[100:101], v[106:107]
	v_pk_mul_f32 v[96:97], v[96:97], v[106:107]
	v_mov_b32_e32 v110, v106
	v_mov_b32_e32 v111, v106
	v_pk_mul_f32 v[102:103], v[102:103], v[110:111]
	v_pk_mul_f32 v[98:99], v[98:99], v[110:111]
	v_pk_mul_f32 v[108:109], v[150:151], v[102:103]
	v_pk_mul_f32 v[100:101], v[148:149], v[100:101]
	v_pk_mul_f32 v[102:103], v[146:147], v[98:99]
	s_and_b64 vcc, exec, s[6:7]
	v_pk_mul_f32 v[98:99], v[144:145], v[96:97]
	s_cbranch_vccnz .LBB0_239
	v_lshlrev_b32_e32 v96, 5, v118
	s_movk_i32 s0, 0x5e0
	v_and_or_b32 v96, v96, s0, v168
	v_lshlrev_b32_e32 v96, 2, v96
	v_mov_b32_e32 v97, v177
	v_lshl_add_u64 v[96:97], s[18:19], 0, v[96:97]
	global_load_dwordx4 v[110:113], v[96:97], off
	global_load_dwordx4 v[114:117], v[96:97], off offset:16
	s_waitcnt vmcnt(0) lgkmcnt(0)
	v_pk_mul_f32 v[106:107], v[100:101], v[110:111] op_sel:[1,1] op_sel_hi:[1,0]
	v_pk_mul_f32 v[96:97], v[100:101], v[110:111]
	v_pk_fma_f32 v[100:101], v[100:101], v[110:111], v[106:107] op_sel_hi:[0,1,1]
	v_mul_f32_e32 v100, v109, v113
	v_pk_fma_f32 v[110:111], v[108:109], v[112:113], v[100:101] op_sel_hi:[1,1,0] neg_lo:[0,0,1] neg_hi:[0,0,1]
	v_mul_f32_e32 v100, v109, v112
	v_pk_mul_f32 v[118:119], v[98:99], v[114:115] op_sel:[1,1] op_sel_hi:[1,0]
	v_pk_fma_f32 v[112:113], v[108:109], v[112:113], v[100:101] op_sel:[0,1,0] op_sel_hi:[1,0,0]
	v_pk_mul_f32 v[108:109], v[98:99], v[114:115]
	v_pk_fma_f32 v[98:99], v[98:99], v[114:115], v[118:119] op_sel_hi:[0,1,1]
	v_mul_f32_e32 v98, v103, v117
	v_pk_fma_f32 v[114:115], v[102:103], v[116:117], v[98:99] op_sel_hi:[1,1,0] neg_lo:[0,0,1] neg_hi:[0,0,1]
	v_mul_f32_e32 v98, v103, v116
	v_pk_fma_f32 v[116:117], v[102:103], v[116:117], v[98:99] op_sel:[0,1,0] op_sel_hi:[1,0,0]
	v_sub_f32_e32 v98, v108, v118
	v_sub_f32_e32 v100, v96, v106
	v_mov_b32_e32 v102, v114
	v_mov_b32_e32 v103, v116
	v_mov_b32_e32 v108, v110
	v_mov_b32_e32 v109, v112
.LBB0_239:
	v_mov_b32_e32 v96, v128
	v_mov_b32_e32 v97, v128
	v_pk_mul_f32 v[100:101], v[128:129], v[100:101]
	v_pk_mul_f32 v[102:103], v[96:97], v[102:103]
	v_mov_b32_e32 v131, v177
	v_pk_mul_f32 v[106:107], v[96:97], v[108:109]
	v_pk_mul_f32 v[108:109], v[128:129], v[98:99]
	v_cvt_pk_bf16_f32 v98, v100, v101
	v_cvt_pk_bf16_f32 v99, v106, v107
	s_nop 0
	v_cvt_pk_bf16_f32 v100, v108, v109
	v_cvt_pk_bf16_f32 v101, v102, v103
	v_lshl_add_u64 v[102:103], v[104:105], 0, v[130:131]
	global_store_dwordx4 v[102:103], v[98:101], off
	global_load_dword v98, v[188:189], off offset:192
	s_waitcnt vmcnt(0) lgkmcnt(0)
	v_fmamk_f32 v98, v98, 0x3a800000, v224
	v_mul_f32_e32 v99, 0x4b800000, v98
	v_cmp_gt_f32_e32 vcc, s33, v98
	s_nop 1
	v_cndmask_b32_e32 v98, v98, v99, vcc
	v_rsq_f32_e32 v98, v98
	s_nop 0
	v_mul_f32_e32 v99, 0x45800000, v98
	v_cndmask_b32_e32 v98, v98, v99, vcc
	v_pk_fma_f32 v[92:93], v[92:93], v[98:99], v[44:45] op_sel_hi:[1,0,1]
	v_pk_fma_f32 v[94:95], v[94:95], v[98:99], v[46:47] op_sel_hi:[1,0,1]
	v_pk_fma_f32 v[88:89], v[88:89], v[98:99], v[40:41] op_sel_hi:[1,0,1]
	v_pk_fma_f32 v[100:101], v[90:91], v[98:99], v[42:43] op_sel_hi:[1,0,1]
	v_pk_fma_f32 v[86:87], v[86:87], v[98:99], v[38:39] op_sel_hi:[1,0,1]
	v_pk_fma_f32 v[84:85], v[84:85], v[98:99], v[36:37] op_sel_hi:[1,0,1]
	v_pk_fma_f32 v[82:83], v[82:83], v[98:99], v[34:35] op_sel_hi:[1,0,1]
	v_pk_fma_f32 v[80:81], v[80:81], v[98:99], v[32:33] op_sel_hi:[1,0,1]
	v_pk_mul_f32 v[90:91], v[94:95], v[94:95]
	v_pk_mul_f32 v[98:99], v[92:93], v[92:93]
	v_pk_mul_f32 v[102:103], v[100:101], v[100:101]
	v_pk_mul_f32 v[104:105], v[88:89], v[88:89]
	v_pk_mov_b32 v[110:111], v[98:99], v[90:91] op_sel:[1,0]
	v_mov_b32_e32 v99, v91
	v_pk_mov_b32 v[90:91], v[104:105], v[102:103] op_sel:[1,0]
	v_mov_b32_e32 v105, v103
	v_mul_f32_e32 v106, v84, v84
	v_mul_f32_e32 v108, v86, v86
	v_pk_add_f32 v[98:99], v[110:111], v[98:99]
	v_pk_add_f32 v[90:91], v[90:91], v[104:105]
	v_pk_fma_f32 v[102:103], v[84:85], v[84:85], v[106:107] op_sel_hi:[1,1,0]
	v_pk_fma_f32 v[106:107], v[86:87], v[86:87], v[108:109] op_sel_hi:[1,1,0]
	v_pk_add_f32 v[98:99], v[98:99], v[98:99] op_sel_hi:[0,1]
	v_pk_add_f32 v[90:91], v[90:91], v[90:91] op_sel_hi:[0,1]
	v_mul_f32_e32 v102, v80, v80
	v_mul_f32_e32 v106, v81, v81
	v_mul_f32_e32 v98, v82, v82
	v_mul_f32_e32 v90, v83, v83
	v_pk_add_f32 v[102:103], v[102:103], v[106:107]
	v_pk_add_f32 v[90:91], v[98:99], v[90:91]
	s_and_b64 vcc, exec, s[6:7]
	v_pk_add_f32 v[90:91], v[102:103], v[90:91]
	s_nop 0
	v_add_f32_e32 v90, v90, v91
	ds_bpermute_b32 v91, v201, v90
	s_waitcnt lgkmcnt(0)
	v_add_f32_e32 v90, v90, v91
	ds_bpermute_b32 v91, v202, v90
	s_waitcnt lgkmcnt(0)
	v_add_f32_e32 v90, v90, v91
	v_fmamk_f32 v90, v90, 0x3c800000, v224
	v_mul_f32_e32 v91, 0x4b800000, v90
	v_cmp_gt_f32_e64 s[0:1], s33, v90
	s_nop 1
	v_cndmask_b32_e64 v90, v90, v91, s[0:1]
	v_rsq_f32_e32 v90, v90
	s_nop 0
	v_mul_f32_e32 v91, 0x45800000, v90
	v_cndmask_b32_e64 v90, v90, v91, s[0:1]
	v_pk_mul_f32 v[92:93], v[92:93], v[90:91] op_sel_hi:[1,0]
	v_pk_mul_f32 v[94:95], v[94:95], v[90:91] op_sel_hi:[1,0]
	v_pk_mul_f32 v[88:89], v[88:89], v[90:91] op_sel_hi:[1,0]
	v_pk_mul_f32 v[98:99], v[100:101], v[90:91] op_sel_hi:[1,0]
	v_pk_mul_f32 v[100:101], v[158:159], v[94:95]
	v_pk_mul_f32 v[94:95], v[156:157], v[92:93]
	v_pk_mul_f32 v[98:99], v[154:155], v[98:99]
	v_pk_mul_f32 v[92:93], v[152:153], v[88:89]
	s_cbranch_vccnz .LBB0_241
; __device__ __forceinline__ unsigned pkbf(float lo, float hi) { return pg8::cvt_pk_bf16(lo, hi); }
;     __device__ __forceinline__ void operator()(const f32x4 (&acc)[2][2][4][2], const Unit& u, int wr, int wc, int fr, int fq) const {
;     ...
;                 for (int m = 0; m < 4; ++m) {
;                     const int row = pm * 256 + ai * 128 + wr * 64 + m * 16 + fr;
;                     const float rinv = rsqrtf(rowsq[row] * (1.f / DM) + EPSN);
;                     int b, kidx, t = 0;
;                     if (isctx) { const int rc = row - MLAT; b = rc >> 8; kidx = rc & 255; } else { b = row >> 13; t = row & (SEQ - 1); kidx = CTXL + t; }
;                     f32x4 val[2][2]; float ss = 0.f;
; #pragma unroll
;                     for (int bj = 0; bj < 2; ++bj)
; #pragma unroll
;                         for (int n = 0; n < 2; ++n) { val[bj][n] = acc[ai][bj][m][n] * rinv + bv[bj][n]; const f32x4 q = val[bj][n]; ss += (q[0] * q[0] + q[1] * q[1]) + (q[2] * q[2] + q[3] * q[3]); }
;                     ss += __shfl_xor(ss, 16); ss += __shfl_xor(ss, 32);
;                     const float rn = rsqrtf(ss * (1.f / 64.f) + EPSN);
; #pragma unroll
;                     for (int bj = 0; bj < 2; ++bj) {
;                         f32x4 y0 = val[bj][0] * rn * gv[bj][0], y1 = val[bj][1] * rn * gv[bj][1];
;                         if (!isctx) {
;                             const int pos = bj == 0 ? (t >> 6) : (t & 63);
;                             const f32x4 r0 = *(const f32x4*)(rope + (size_t)(pos * 16 + 4 * fq) * 2);
;                             const f32x4 r1 = *(const f32x4*)(rope + (size_t)(pos * 16 + 4 * fq + 2) * 2);
;                             f32x4 z0, z1;
;                             z0[0] = y0[0] * r0[0] - y0[1] * r0[1]; z0[1] = y0[0] * r0[1] + y0[1] * r0[0];
;                             z0[2] = y0[2] * r0[2] - y0[3] * r0[3]; z0[3] = y0[2] * r0[3] + y0[3] * r0[2];
;                             z1[0] = y1[0] * r1[0] - y1[1] * r1[1]; z1[1] = y1[0] * r1[1] + y1[1] * r1[0];
;                             z1[2] = y1[2] * r1[2] - y1[3] * r1[3]; z1[3] = y1[2] * r1[3] + y1[3] * r1[2];
;                             y0 = z0; y1 = z1;
;                         }
;                         y0 = y0 * osc; y1 = y1 * osc;
;                         u32x4 w; w.x = pkbf(y0[0], y0[1]); w.y = pkbf(y0[2], y0[3]); w.z = pkbf(y1[0], y1[1]); w.w = pkbf(y1[2], y1[3]);
	s_lshr_b32 s0, s25, 1
	s_and_b32 s0, s0, 0xfe0
	v_or_b32_e32 v88, s0, v168
	v_lshlrev_b32_e32 v88, 2, v88
	v_mov_b32_e32 v89, v177
	v_lshl_add_u64 v[88:89], s[18:19], 0, v[88:89]
	global_load_dwordx4 v[102:105], v[88:89], off
	global_load_dwordx4 v[106:109], v[88:89], off offset:16
	s_waitcnt vmcnt(0) lgkmcnt(0)
	v_pk_mul_f32 v[110:111], v[94:95], v[102:103] op_sel:[1,1] op_sel_hi:[1,0]
	v_pk_mul_f32 v[88:89], v[94:95], v[102:103]
	v_pk_fma_f32 v[94:95], v[94:95], v[102:103], v[110:111] op_sel_hi:[0,1,1]
	v_mul_f32_e32 v94, v101, v105
	v_pk_fma_f32 v[102:103], v[100:101], v[104:105], v[94:95] op_sel_hi:[1,1,0] neg_lo:[0,0,1] neg_hi:[0,0,1]
	v_mul_f32_e32 v94, v101, v104
	v_pk_mul_f32 v[112:113], v[92:93], v[106:107] op_sel:[1,1] op_sel_hi:[1,0]
	v_pk_fma_f32 v[104:105], v[100:101], v[104:105], v[94:95] op_sel:[0,1,0] op_sel_hi:[1,0,0]
	v_pk_mul_f32 v[100:101], v[92:93], v[106:107]
	v_pk_fma_f32 v[92:93], v[92:93], v[106:107], v[112:113] op_sel_hi:[0,1,1]
	v_mul_f32_e32 v92, v99, v109
	v_pk_fma_f32 v[106:107], v[98:99], v[108:109], v[92:93] op_sel_hi:[1,1,0] neg_lo:[0,0,1] neg_hi:[0,0,1]
	v_mul_f32_e32 v92, v99, v108
	v_pk_fma_f32 v[108:109], v[98:99], v[108:109], v[92:93] op_sel:[0,1,0] op_sel_hi:[1,0,0]
	v_sub_f32_e32 v92, v100, v112
	v_sub_f32_e32 v94, v88, v110
	v_mov_b32_e32 v98, v106
	v_mov_b32_e32 v99, v108
	v_mov_b32_e32 v100, v102
	v_mov_b32_e32 v101, v104
.LBB0_241:
	v_bitop3_b32 v102, v186, s68, 48 bitop3:0xc8
	v_bitop3_b32 v88, v186, s48, 48 bitop3:0xc8
	v_add_u32_e32 v89, 0x100, v102
	v_cndmask_b32_e64 v103, v89, v88, s[4:5]
	v_lshlrev_b32_e32 v88, 7, v103
	v_and_b32_e32 v88, 0x1fe000, v88
	v_mov_b32_e32 v89, v177
	v_lshlrev_b32_e32 v103, 4, v103
	v_lshl_add_u64 v[88:89], s[14:15], 0, v[88:89]
	v_and_b32_e32 v104, 0x3f0, v103
	v_mov_b32_e32 v105, v177
	v_lshl_add_u64 v[88:89], v[88:89], 0, v[104:105]
	v_pk_mul_f32 v[100:101], v[96:97], v[100:101]
	v_pk_mul_f32 v[94:95], v[128:129], v[94:95]
	v_pk_mul_f32 v[96:97], v[96:97], v[98:99]
	v_pk_mul_f32 v[98:99], v[128:129], v[92:93]
	v_cvt_pk_bf16_f32 v92, v94, v95
	v_cvt_pk_bf16_f32 v93, v100, v101
	v_mov_b32_e32 v91, v90
	v_cvt_pk_bf16_f32 v94, v98, v99
	v_cvt_pk_bf16_f32 v95, v96, v97
	v_lshl_add_u64 v[96:97], v[88:89], 0, v[176:177]
	global_store_dwordx4 v[96:97], v[92:95], off
	v_pk_mul_f32 v[84:85], v[84:85], v[90:91]
	v_pk_mul_f32 v[80:81], v[80:81], v[90:91]
	v_mov_b32_e32 v94, v90
	v_mov_b32_e32 v95, v90
	v_pk_mul_f32 v[86:87], v[86:87], v[94:95]
	v_pk_mul_f32 v[82:83], v[82:83], v[94:95]
	v_pk_mul_f32 v[92:93], v[150:151], v[86:87]
	v_pk_mul_f32 v[86:87], v[148:149], v[84:85]
	v_pk_mul_f32 v[82:83], v[146:147], v[82:83]
	s_and_b64 vcc, exec, s[6:7]
	v_pk_mul_f32 v[80:81], v[144:145], v[80:81]
	s_cbranch_vccnz .LBB0_243
	v_lshlrev_b32_e32 v84, 5, v102
	s_movk_i32 s0, 0x7e0
	v_and_or_b32 v84, v84, s0, v168
	v_lshlrev_b32_e32 v84, 2, v84
	v_mov_b32_e32 v85, v177
	v_lshl_add_u64 v[84:85], s[18:19], 0, v[84:85]
	global_load_dwordx4 v[94:97], v[84:85], off
	global_load_dwordx4 v[98:101], v[84:85], off offset:16
	s_waitcnt vmcnt(0) lgkmcnt(0)
	v_pk_mul_f32 v[90:91], v[86:87], v[94:95] op_sel:[1,1] op_sel_hi:[1,0]
	v_pk_mul_f32 v[84:85], v[86:87], v[94:95]
	v_pk_fma_f32 v[86:87], v[86:87], v[94:95], v[90:91] op_sel_hi:[0,1,1]
	v_mul_f32_e32 v86, v93, v97
	v_pk_fma_f32 v[94:95], v[92:93], v[96:97], v[86:87] op_sel_hi:[1,1,0] neg_lo:[0,0,1] neg_hi:[0,0,1]
	v_mul_f32_e32 v86, v93, v96
	v_pk_mul_f32 v[102:103], v[80:81], v[98:99] op_sel:[1,1] op_sel_hi:[1,0]
	v_pk_fma_f32 v[96:97], v[92:93], v[96:97], v[86:87] op_sel:[0,1,0] op_sel_hi:[1,0,0]
	v_pk_mul_f32 v[92:93], v[80:81], v[98:99]
	v_pk_fma_f32 v[80:81], v[80:81], v[98:99], v[102:103] op_sel_hi:[0,1,1]
	v_mul_f32_e32 v80, v83, v101
	v_pk_fma_f32 v[98:99], v[82:83], v[100:101], v[80:81] op_sel_hi:[1,1,0] neg_lo:[0,0,1] neg_hi:[0,0,1]
	v_mul_f32_e32 v80, v83, v100
	v_pk_fma_f32 v[100:101], v[82:83], v[100:101], v[80:81] op_sel:[0,1,0] op_sel_hi:[1,0,0]
	v_sub_f32_e32 v80, v92, v102
	v_sub_f32_e32 v86, v84, v90
	v_mov_b32_e32 v82, v98
	v_mov_b32_e32 v83, v100
	v_mov_b32_e32 v92, v94
	v_mov_b32_e32 v93, v96
.LBB0_243:
	v_mov_b32_e32 v84, v128
	v_mov_b32_e32 v85, v128
	v_pk_mul_f32 v[86:87], v[128:129], v[86:87]
	v_mov_b32_e32 v131, v177
	v_pk_mul_f32 v[90:91], v[84:85], v[92:93]
	v_pk_mul_f32 v[92:93], v[84:85], v[82:83]
	v_pk_mul_f32 v[82:83], v[128:129], v[80:81]
	v_cvt_pk_bf16_f32 v80, v86, v87
	v_lshl_add_u64 v[86:87], v[88:89], 0, v[130:131]
	s_add_i32 s56, s25, 0x80
	v_cvt_pk_bf16_f32 v81, v90, v91
	v_cvt_pk_bf16_f32 v82, v82, v83
	v_cvt_pk_bf16_f32 v83, v92, v93
	global_store_dwordx4 v[86:87], v[80:83], off
	s_nop 1
	v_or_b32_e32 v80, s56, v171
	v_ashrrev_i32_e32 v81, 31, v80
	v_lshl_add_u64 v[82:83], v[80:81], 2, s[16:17]
	global_load_dword v81, v[82:83], off
	s_waitcnt vmcnt(0) lgkmcnt(0)
; __device__ __forceinline__ unsigned pkbf(float lo, float hi) { return pg8::cvt_pk_bf16(lo, hi); }
;     __device__ __forceinline__ void operator()(const f32x4 (&acc)[2][2][4][2], const Unit& u, int wr, int wc, int fr, int fq) const {
;     ...
;                 for (int m = 0; m < 4; ++m) {
;                     const int row = pm * 256 + ai * 128 + wr * 64 + m * 16 + fr;
;                     const float rinv = rsqrtf(rowsq[row] * (1.f / DM) + EPSN);
;                     int b, kidx, t = 0;
;                     if (isctx) { const int rc = row - MLAT; b = rc >> 8; kidx = rc & 255; } else { b = row >> 13; t = row & (SEQ - 1); kidx = CTXL + t; }
;                     f32x4 val[2][2]; float ss = 0.f;
; #pragma unroll
;                     for (int bj = 0; bj < 2; ++bj)
; #pragma unroll
;                         for (int n = 0; n < 2; ++n) { val[bj][n] = acc[ai][bj][m][n] * rinv + bv[bj][n]; const f32x4 q = val[bj][n]; ss += (q[0] * q[0] + q[1] * q[1]) + (q[2] * q[2] + q[3] * q[3]); }
;                     ss += __shfl_xor(ss, 16); ss += __shfl_xor(ss, 32);
;                     const float rn = rsqrtf(ss * (1.f / 64.f) + EPSN);
; #pragma unroll
;                     for (int bj = 0; bj < 2; ++bj) {
;                         f32x4 y0 = val[bj][0] * rn * gv[bj][0], y1 = val[bj][1] * rn * gv[bj][1];
;                         if (!isctx) {
;                             const int pos = bj == 0 ? (t >> 6) : (t & 63);
;                             const f32x4 r0 = *(const f32x4*)(rope + (size_t)(pos * 16 + 4 * fq) * 2);
;                             const f32x4 r1 = *(const f32x4*)(rope + (size_t)(pos * 16 + 4 * fq + 2) * 2);
;                             f32x4 z0, z1;
;                             z0[0] = y0[0] * r0[0] - y0[1] * r0[1]; z0[1] = y0[0] * r0[1] + y0[1] * r0[0];
;                             z0[2] = y0[2] * r0[2] - y0[3] * r0[3]; z0[3] = y0[2] * r0[3] + y0[3] * r0[2];
;                             z1[0] = y1[0] * r1[0] - y1[1] * r1[1]; z1[1] = y1[0] * r1[1] + y1[1] * r1[0];
;                             z1[2] = y1[2] * r1[2] - y1[3] * r1[3]; z1[3] = y1[2] * r1[3] + y1[3] * r1[2];
;                             y0 = z0; y1 = z1;
;                         }
;                         y0 = y0 * osc; y1 = y1 * osc;
;                         u32x4 w; w.x = pkbf(y0[0], y0[1]); w.y = pkbf(y0[2], y0[3]); w.z = pkbf(y1[0], y1[1]); w.w = pkbf(y1[2], y1[3]);
	v_fmamk_f32 v81, v81, 0x3a800000, v224
	v_cmp_gt_f32_e32 vcc, s33, v81
	v_mul_f32_e32 v86, 0x4b800000, v81
	s_nop 0
	v_cndmask_b32_e32 v81, v81, v86, vcc
	v_rsq_f32_e32 v81, v81
	s_nop 0
	v_mul_f32_e32 v86, 0x45800000, v81
	v_cndmask_b32_e32 v86, v81, v86, vcc
	v_pk_fma_f32 v[76:77], v[76:77], v[86:87], v[44:45] op_sel_hi:[1,0,1]
	v_pk_fma_f32 v[78:79], v[78:79], v[86:87], v[46:47] op_sel_hi:[1,0,1]
	v_pk_mul_f32 v[90:91], v[76:77], v[76:77]
	v_pk_mul_f32 v[88:89], v[78:79], v[78:79]
	v_pk_fma_f32 v[74:75], v[74:75], v[86:87], v[42:43] op_sel_hi:[1,0,1]
	v_pk_mov_b32 v[92:93], v[90:91], v[88:89] op_sel:[1,0]
	v_mov_b32_e32 v91, v89
	v_pk_add_f32 v[88:89], v[92:93], v[90:91]
	v_pk_fma_f32 v[90:91], v[72:73], v[86:87], v[40:41] op_sel_hi:[1,0,1]
	v_pk_mul_f32 v[72:73], v[74:75], v[74:75]
	v_pk_mul_f32 v[92:93], v[90:91], v[90:91]
	v_pk_fma_f32 v[68:69], v[68:69], v[86:87], v[36:37] op_sel_hi:[1,0,1]
	v_pk_mov_b32 v[94:95], v[92:93], v[72:73] op_sel:[1,0]
	v_mov_b32_e32 v93, v73
	v_pk_add_f32 v[72:73], v[94:95], v[92:93]
	v_pk_fma_f32 v[70:71], v[70:71], v[86:87], v[38:39] op_sel_hi:[1,0,1]
	v_pk_add_f32 v[72:73], v[72:73], v[72:73] op_sel_hi:[0,1]
	v_mul_f32_e32 v72, v68, v68
	v_pk_fma_f32 v[92:93], v[68:69], v[68:69], v[72:73] op_sel_hi:[1,1,0]
	v_mul_f32_e32 v72, v70, v70
	v_pk_add_f32 v[88:89], v[88:89], v[88:89] op_sel_hi:[0,1]
	v_pk_fma_f32 v[94:95], v[70:71], v[70:71], v[72:73] op_sel_hi:[1,1,0]
	v_pk_fma_f32 v[66:67], v[66:67], v[86:87], v[34:35] op_sel_hi:[1,0,1]
	v_pk_fma_f32 v[64:65], v[64:65], v[86:87], v[32:33] op_sel_hi:[1,0,1]
	v_mul_f32_e32 v88, v66, v66
	v_mul_f32_e32 v92, v64, v64
	v_mul_f32_e32 v94, v65, v65
	v_mul_f32_e32 v72, v67, v67
	v_pk_add_f32 v[86:87], v[92:93], v[94:95]
	v_pk_add_f32 v[72:73], v[88:89], v[72:73]
	s_nop 0
	v_pk_add_f32 v[72:73], v[86:87], v[72:73]
	s_nop 0
	v_add_f32_e32 v72, v72, v73
	ds_bpermute_b32 v73, v201, v72
	s_waitcnt lgkmcnt(0)
	v_add_f32_e32 v72, v72, v73
	ds_bpermute_b32 v73, v202, v72
	s_waitcnt lgkmcnt(0)
	v_add_f32_e32 v72, v72, v73
	v_fmamk_f32 v72, v72, 0x3c800000, v224
	v_cmp_gt_f32_e32 vcc, s33, v72
	v_mul_f32_e32 v73, 0x4b800000, v72
	s_nop 0
	v_cndmask_b32_e32 v72, v72, v73, vcc
	v_rsq_f32_e32 v72, v72
	s_nop 0
	v_mul_f32_e32 v73, 0x45800000, v72
	v_cndmask_b32_e32 v72, v72, v73, vcc
	v_pk_mul_f32 v[76:77], v[76:77], v[72:73] op_sel_hi:[1,0]
	v_pk_mul_f32 v[78:79], v[78:79], v[72:73] op_sel_hi:[1,0]
	v_pk_mul_f32 v[86:87], v[90:91], v[72:73] op_sel_hi:[1,0]
	v_pk_mul_f32 v[74:75], v[74:75], v[72:73] op_sel_hi:[1,0]
	v_pk_mul_f32 v[88:89], v[158:159], v[78:79]
	v_pk_mul_f32 v[76:77], v[156:157], v[76:77]
	v_pk_mul_f32 v[78:79], v[154:155], v[74:75]
	v_pk_mul_f32 v[74:75], v[152:153], v[86:87]
	s_and_b64 vcc, exec, s[6:7]
	s_cbranch_vccnz .LBB0_245
	s_lshr_b32 s0, s56, 1
	s_and_b32 s0, s0, 0xfe0
	v_or_b32_e32 v73, s0, v168
	v_lshlrev_b32_e32 v86, 2, v73
	v_mov_b32_e32 v87, v177
	v_lshl_add_u64 v[86:87], s[18:19], 0, v[86:87]
	global_load_dwordx4 v[90:93], v[86:87], off
	global_load_dwordx4 v[94:97], v[86:87], off offset:16
	s_waitcnt vmcnt(0) lgkmcnt(0)
	v_pk_mul_f32 v[98:99], v[76:77], v[90:91] op_sel:[1,1] op_sel_hi:[1,0]
	v_pk_mul_f32 v[86:87], v[76:77], v[90:91]
	v_pk_fma_f32 v[76:77], v[76:77], v[90:91], v[98:99] op_sel_hi:[0,1,1]
	v_mul_f32_e32 v76, v89, v93
	v_pk_fma_f32 v[90:91], v[88:89], v[92:93], v[76:77] op_sel_hi:[1,1,0] neg_lo:[0,0,1] neg_hi:[0,0,1]
	v_mul_f32_e32 v76, v89, v92
	v_pk_mul_f32 v[100:101], v[74:75], v[94:95] op_sel:[1,1] op_sel_hi:[1,0]
	v_pk_fma_f32 v[92:93], v[88:89], v[92:93], v[76:77] op_sel:[0,1,0] op_sel_hi:[1,0,0]
	v_pk_mul_f32 v[88:89], v[74:75], v[94:95]
	v_pk_fma_f32 v[74:75], v[74:75], v[94:95], v[100:101] op_sel_hi:[0,1,1]
	v_mul_f32_e32 v74, v79, v97
	v_pk_fma_f32 v[94:95], v[78:79], v[96:97], v[74:75] op_sel_hi:[1,1,0] neg_lo:[0,0,1] neg_hi:[0,0,1]
	v_mul_f32_e32 v74, v79, v96
	v_pk_fma_f32 v[96:97], v[78:79], v[96:97], v[74:75] op_sel:[0,1,0] op_sel_hi:[1,0,0]
	v_sub_f32_e32 v74, v88, v100
	v_sub_f32_e32 v76, v86, v98
	v_mov_b32_e32 v78, v94
	v_mov_b32_e32 v79, v96
	v_mov_b32_e32 v88, v90
	v_mov_b32_e32 v89, v92
.LBB0_245:
	s_addk_i32 s25, 0xc080
	s_ashr_i32 s14, s56, 13
	s_ashr_i32 s15, s25, 8
	s_and_b64 s[0:1], s[4:5], exec
	s_cselect_b32 s0, s15, s14
	v_and_b32_e32 v81, 0x1fcf, v80
	s_lshl_b32 s0, s0, 3
	v_and_b32_e32 v86, 0xcf, v80
	v_add_u32_e32 v87, 0x100, v81
	s_add_i32 s0, s0, s27
	v_cndmask_b32_e64 v90, v87, v86, s[4:5]
	s_mul_hi_i32 s1, s0, 0x108000
	s_mul_i32 s0, s0, 0x108000
	s_add_u32 s14, s36, s0
	v_lshlrev_b32_e32 v86, 7, v90
	s_addc_u32 s15, s54, s1
	v_and_b32_e32 v86, 0x1fe000, v86
	v_mov_b32_e32 v87, v177
	v_lshlrev_b32_e32 v90, 4, v90
	v_lshl_add_u64 v[86:87], s[14:15], 0, v[86:87]
	v_and_b32_e32 v90, 0xf0, v90
	v_mov_b32_e32 v91, v177
	v_lshl_add_u64 v[86:87], v[86:87], 0, v[90:91]
	v_pk_mul_f32 v[76:77], v[128:129], v[76:77]
	v_pk_mul_f32 v[78:79], v[84:85], v[78:79]
	v_pk_mul_f32 v[88:89], v[84:85], v[88:89]
	v_pk_mul_f32 v[84:85], v[128:129], v[74:75]
	v_cvt_pk_bf16_f32 v74, v76, v77
	v_cvt_pk_bf16_f32 v75, v88, v89
	v_mov_b32_e32 v73, v72
	v_cvt_pk_bf16_f32 v76, v84, v85
	v_cvt_pk_bf16_f32 v77, v78, v79
	v_lshl_add_u64 v[78:79], v[86:87], 0, v[176:177]
	global_store_dwordx4 v[78:79], v[74:77], off
	v_pk_mul_f32 v[68:69], v[68:69], v[72:73]
	v_pk_mul_f32 v[64:65], v[64:65], v[72:73]
	v_mov_b32_e32 v76, v72
	v_mov_b32_e32 v77, v72
	v_pk_mul_f32 v[70:71], v[70:71], v[76:77]
	v_pk_mul_f32 v[66:67], v[66:67], v[76:77]
	v_pk_mul_f32 v[74:75], v[150:151], v[70:71]
	v_pk_mul_f32 v[68:69], v[148:149], v[68:69]
	v_pk_mul_f32 v[70:71], v[146:147], v[66:67]
	s_and_b64 vcc, exec, s[6:7]
	v_pk_mul_f32 v[66:67], v[144:145], v[64:65]
	s_cbranch_vccnz .LBB0_247
	v_lshlrev_b32_e32 v64, 5, v81
	s_movk_i32 s0, 0x1e0
	v_and_or_b32 v64, v64, s0, v168
	v_lshlrev_b32_e32 v64, 2, v64
	v_mov_b32_e32 v65, v177
	v_lshl_add_u64 v[64:65], s[18:19], 0, v[64:65]
	global_load_dwordx4 v[76:79], v[64:65], off
	global_load_dwordx4 v[88:91], v[64:65], off offset:16
	s_waitcnt vmcnt(0) lgkmcnt(0)
	v_pk_mul_f32 v[72:73], v[68:69], v[76:77] op_sel:[1,1] op_sel_hi:[1,0]
	v_pk_mul_f32 v[64:65], v[68:69], v[76:77]
	v_pk_fma_f32 v[68:69], v[68:69], v[76:77], v[72:73] op_sel_hi:[0,1,1]
	v_mul_f32_e32 v68, v75, v79
	v_pk_fma_f32 v[76:77], v[74:75], v[78:79], v[68:69] op_sel_hi:[1,1,0] neg_lo:[0,0,1] neg_hi:[0,0,1]
	v_mul_f32_e32 v68, v75, v78
	v_pk_mul_f32 v[84:85], v[66:67], v[88:89] op_sel:[1,1] op_sel_hi:[1,0]
	v_pk_fma_f32 v[78:79], v[74:75], v[78:79], v[68:69] op_sel:[0,1,0] op_sel_hi:[1,0,0]
	v_pk_mul_f32 v[74:75], v[66:67], v[88:89]
	v_pk_fma_f32 v[66:67], v[66:67], v[88:89], v[84:85] op_sel_hi:[0,1,1]
	v_mul_f32_e32 v66, v71, v91
	v_pk_fma_f32 v[88:89], v[70:71], v[90:91], v[66:67] op_sel_hi:[1,1,0] neg_lo:[0,0,1] neg_hi:[0,0,1]
	v_mul_f32_e32 v66, v71, v90
	v_pk_fma_f32 v[90:91], v[70:71], v[90:91], v[66:67] op_sel:[0,1,0] op_sel_hi:[1,0,0]
	v_sub_f32_e32 v66, v74, v84
	v_sub_f32_e32 v68, v64, v72
	v_mov_b32_e32 v70, v88
	v_mov_b32_e32 v71, v90
	v_mov_b32_e32 v74, v76
	v_mov_b32_e32 v75, v78
; __device__ __forceinline__ unsigned pkbf(float lo, float hi) { return pg8::cvt_pk_bf16(lo, hi); }
;     __device__ __forceinline__ void operator()(const f32x4 (&acc)[2][2][4][2], const Unit& u, int wr, int wc, int fr, int fq) const {
;     ...
;                 for (int m = 0; m < 4; ++m) {
;                     const int row = pm * 256 + ai * 128 + wr * 64 + m * 16 + fr;
;                     const float rinv = rsqrtf(rowsq[row] * (1.f / DM) + EPSN);
;                     int b, kidx, t = 0;
;                     if (isctx) { const int rc = row - MLAT; b = rc >> 8; kidx = rc & 255; } else { b = row >> 13; t = row & (SEQ - 1); kidx = CTXL + t; }
;                     f32x4 val[2][2]; float ss = 0.f;
; #pragma unroll
;                     for (int bj = 0; bj < 2; ++bj)
; #pragma unroll
;                         for (int n = 0; n < 2; ++n) { val[bj][n] = acc[ai][bj][m][n] * rinv + bv[bj][n]; const f32x4 q = val[bj][n]; ss += (q[0] * q[0] + q[1] * q[1]) + (q[2] * q[2] + q[3] * q[3]); }
;                     ss += __shfl_xor(ss, 16); ss += __shfl_xor(ss, 32);
;                     const float rn = rsqrtf(ss * (1.f / 64.f) + EPSN);
; #pragma unroll
;                     for (int bj = 0; bj < 2; ++bj) {
;                         f32x4 y0 = val[bj][0] * rn * gv[bj][0], y1 = val[bj][1] * rn * gv[bj][1];
;                         if (!isctx) {
;                             const int pos = bj == 0 ? (t >> 6) : (t & 63);
;                             const f32x4 r0 = *(const f32x4*)(rope + (size_t)(pos * 16 + 4 * fq) * 2);
;                             const f32x4 r1 = *(const f32x4*)(rope + (size_t)(pos * 16 + 4 * fq + 2) * 2);
;                             f32x4 z0, z1;
;                             z0[0] = y0[0] * r0[0] - y0[1] * r0[1]; z0[1] = y0[0] * r0[1] + y0[1] * r0[0];
;                             z0[2] = y0[2] * r0[2] - y0[3] * r0[3]; z0[3] = y0[2] * r0[3] + y0[3] * r0[2];
;                             z1[0] = y1[0] * r1[0] - y1[1] * r1[1]; z1[1] = y1[0] * r1[1] + y1[1] * r1[0];
;                             z1[2] = y1[2] * r1[2] - y1[3] * r1[3]; z1[3] = y1[2] * r1[3] + y1[3] * r1[2];
;                             y0 = z0; y1 = z1;
;                         }
;                         y0 = y0 * osc; y1 = y1 * osc;
;                         u32x4 w; w.x = pkbf(y0[0], y0[1]); w.y = pkbf(y0[2], y0[3]); w.z = pkbf(y1[0], y1[1]); w.w = pkbf(y1[2], y1[3]);
.LBB0_247:
	v_mov_b32_e32 v64, v128
	v_mov_b32_e32 v65, v128
	v_pk_mul_f32 v[68:69], v[128:129], v[68:69]
	v_pk_mul_f32 v[70:71], v[64:65], v[70:71]
	v_mov_b32_e32 v131, v177
	v_pk_mul_f32 v[72:73], v[64:65], v[74:75]
	v_pk_mul_f32 v[74:75], v[128:129], v[66:67]
	v_cvt_pk_bf16_f32 v66, v68, v69
	v_cvt_pk_bf16_f32 v67, v72, v73
	s_nop 0
	v_cvt_pk_bf16_f32 v68, v74, v75
	v_cvt_pk_bf16_f32 v69, v70, v71
	v_lshl_add_u64 v[70:71], v[86:87], 0, v[130:131]
	global_store_dwordx4 v[70:71], v[66:69], off
	global_load_dword v66, v[82:83], off offset:64
	s_waitcnt vmcnt(0) lgkmcnt(0)
	v_fmamk_f32 v66, v66, 0x3a800000, v224
	v_mul_f32_e32 v67, 0x4b800000, v66
	v_cmp_gt_f32_e32 vcc, s33, v66
	s_nop 1
	v_cndmask_b32_e32 v66, v66, v67, vcc
	v_rsq_f32_e32 v66, v66
	s_nop 0
	v_mul_f32_e32 v67, 0x45800000, v66
	v_cndmask_b32_e32 v66, v66, v67, vcc
	v_pk_fma_f32 v[60:61], v[60:61], v[66:67], v[44:45] op_sel_hi:[1,0,1]
	v_pk_fma_f32 v[62:63], v[62:63], v[66:67], v[46:47] op_sel_hi:[1,0,1]
	v_pk_fma_f32 v[56:57], v[56:57], v[66:67], v[40:41] op_sel_hi:[1,0,1]
	v_pk_fma_f32 v[68:69], v[58:59], v[66:67], v[42:43] op_sel_hi:[1,0,1]
	v_pk_fma_f32 v[54:55], v[54:55], v[66:67], v[38:39] op_sel_hi:[1,0,1]
	v_pk_fma_f32 v[52:53], v[52:53], v[66:67], v[36:37] op_sel_hi:[1,0,1]
	v_pk_fma_f32 v[50:51], v[50:51], v[66:67], v[34:35] op_sel_hi:[1,0,1]
	v_pk_fma_f32 v[48:49], v[48:49], v[66:67], v[32:33] op_sel_hi:[1,0,1]
	v_pk_mul_f32 v[58:59], v[62:63], v[62:63]
	v_pk_mul_f32 v[66:67], v[60:61], v[60:61]
	v_pk_mul_f32 v[70:71], v[68:69], v[68:69]
	v_pk_mul_f32 v[72:73], v[56:57], v[56:57]
	v_pk_mov_b32 v[78:79], v[66:67], v[58:59] op_sel:[1,0]
	v_mov_b32_e32 v67, v59
	v_pk_mov_b32 v[58:59], v[72:73], v[70:71] op_sel:[1,0]
	v_mov_b32_e32 v73, v71
	v_mul_f32_e32 v74, v52, v52
	v_mul_f32_e32 v76, v54, v54
	v_pk_add_f32 v[66:67], v[78:79], v[66:67]
	v_pk_add_f32 v[58:59], v[58:59], v[72:73]
	v_pk_fma_f32 v[70:71], v[52:53], v[52:53], v[74:75] op_sel_hi:[1,1,0]
	v_pk_fma_f32 v[74:75], v[54:55], v[54:55], v[76:77] op_sel_hi:[1,1,0]
	v_pk_add_f32 v[66:67], v[66:67], v[66:67] op_sel_hi:[0,1]
	v_pk_add_f32 v[58:59], v[58:59], v[58:59] op_sel_hi:[0,1]
	v_mul_f32_e32 v70, v48, v48
	v_mul_f32_e32 v74, v49, v49
	v_mul_f32_e32 v66, v50, v50
	v_mul_f32_e32 v58, v51, v51
	v_pk_add_f32 v[70:71], v[70:71], v[74:75]
	v_pk_add_f32 v[58:59], v[66:67], v[58:59]
	s_and_b64 vcc, exec, s[6:7]
	v_pk_add_f32 v[58:59], v[70:71], v[58:59]
	s_nop 0
	v_add_f32_e32 v58, v58, v59
	ds_bpermute_b32 v59, v201, v58
	s_waitcnt lgkmcnt(0)
	v_add_f32_e32 v58, v58, v59
	ds_bpermute_b32 v59, v202, v58
	s_waitcnt lgkmcnt(0)
	v_add_f32_e32 v58, v58, v59
	v_fmamk_f32 v58, v58, 0x3c800000, v224
	v_mul_f32_e32 v59, 0x4b800000, v58
	v_cmp_gt_f32_e64 s[0:1], s33, v58
	s_nop 1
	v_cndmask_b32_e64 v58, v58, v59, s[0:1]
	v_rsq_f32_e32 v58, v58
	s_nop 0
	v_mul_f32_e32 v59, 0x45800000, v58
	v_cndmask_b32_e64 v58, v58, v59, s[0:1]
	v_pk_mul_f32 v[60:61], v[60:61], v[58:59] op_sel_hi:[1,0]
	v_pk_mul_f32 v[62:63], v[62:63], v[58:59] op_sel_hi:[1,0]
	v_pk_mul_f32 v[56:57], v[56:57], v[58:59] op_sel_hi:[1,0]
	v_pk_mul_f32 v[66:67], v[68:69], v[58:59] op_sel_hi:[1,0]
	v_pk_mul_f32 v[68:69], v[158:159], v[62:63]
	v_pk_mul_f32 v[62:63], v[156:157], v[60:61]
	v_pk_mul_f32 v[66:67], v[154:155], v[66:67]
	v_pk_mul_f32 v[60:61], v[152:153], v[56:57]
	s_cbranch_vccnz .LBB0_249
	s_lshr_b32 s0, s56, 1
	s_and_b32 s0, s0, 0xfe0
	v_or_b32_e32 v56, s0, v168
	v_lshlrev_b32_e32 v56, 2, v56
	v_mov_b32_e32 v57, v177
	v_lshl_add_u64 v[56:57], s[18:19], 0, v[56:57]
	global_load_dwordx4 v[70:73], v[56:57], off
	global_load_dwordx4 v[74:77], v[56:57], off offset:16
	s_waitcnt vmcnt(0) lgkmcnt(0)
	v_pk_mul_f32 v[78:79], v[62:63], v[70:71] op_sel:[1,1] op_sel_hi:[1,0]
	v_pk_mul_f32 v[56:57], v[62:63], v[70:71]
	v_pk_fma_f32 v[62:63], v[62:63], v[70:71], v[78:79] op_sel_hi:[0,1,1]
	v_mul_f32_e32 v62, v69, v73
	v_pk_fma_f32 v[70:71], v[68:69], v[72:73], v[62:63] op_sel_hi:[1,1,0] neg_lo:[0,0,1] neg_hi:[0,0,1]
	v_mul_f32_e32 v62, v69, v72
	v_pk_mul_f32 v[84:85], v[60:61], v[74:75] op_sel:[1,1] op_sel_hi:[1,0]
	v_pk_fma_f32 v[72:73], v[68:69], v[72:73], v[62:63] op_sel:[0,1,0] op_sel_hi:[1,0,0]
	v_pk_mul_f32 v[68:69], v[60:61], v[74:75]
	v_pk_fma_f32 v[60:61], v[60:61], v[74:75], v[84:85] op_sel_hi:[0,1,1]
	v_mul_f32_e32 v60, v67, v77
	v_pk_fma_f32 v[74:75], v[66:67], v[76:77], v[60:61] op_sel_hi:[1,1,0] neg_lo:[0,0,1] neg_hi:[0,0,1]
	v_mul_f32_e32 v60, v67, v76
	v_pk_fma_f32 v[76:77], v[66:67], v[76:77], v[60:61] op_sel:[0,1,0] op_sel_hi:[1,0,0]
	v_sub_f32_e32 v60, v68, v84
	v_sub_f32_e32 v62, v56, v78
	v_mov_b32_e32 v66, v74
	v_mov_b32_e32 v67, v76
	v_mov_b32_e32 v68, v70
	v_mov_b32_e32 v69, v72
; __device__ __forceinline__ unsigned pkbf(float lo, float hi) { return pg8::cvt_pk_bf16(lo, hi); }
;     __device__ __forceinline__ void operator()(const f32x4 (&acc)[2][2][4][2], const Unit& u, int wr, int wc, int fr, int fq) const {
;     ...
;                 for (int m = 0; m < 4; ++m) {
;                     const int row = pm * 256 + ai * 128 + wr * 64 + m * 16 + fr;
;                     const float rinv = rsqrtf(rowsq[row] * (1.f / DM) + EPSN);
;                     int b, kidx, t = 0;
;                     if (isctx) { const int rc = row - MLAT; b = rc >> 8; kidx = rc & 255; } else { b = row >> 13; t = row & (SEQ - 1); kidx = CTXL + t; }
;                     f32x4 val[2][2]; float ss = 0.f;
; #pragma unroll
;                     for (int bj = 0; bj < 2; ++bj)
; #pragma unroll
;                         for (int n = 0; n < 2; ++n) { val[bj][n] = acc[ai][bj][m][n] * rinv + bv[bj][n]; const f32x4 q = val[bj][n]; ss += (q[0] * q[0] + q[1] * q[1]) + (q[2] * q[2] + q[3] * q[3]); }
;                     ss += __shfl_xor(ss, 16); ss += __shfl_xor(ss, 32);
;                     const float rn = rsqrtf(ss * (1.f / 64.f) + EPSN);
; #pragma unroll
;                     for (int bj = 0; bj < 2; ++bj) {
;                         f32x4 y0 = val[bj][0] * rn * gv[bj][0], y1 = val[bj][1] * rn * gv[bj][1];
;                         if (!isctx) {
;                             const int pos = bj == 0 ? (t >> 6) : (t & 63);
;                             const f32x4 r0 = *(const f32x4*)(rope + (size_t)(pos * 16 + 4 * fq) * 2);
;                             const f32x4 r1 = *(const f32x4*)(rope + (size_t)(pos * 16 + 4 * fq + 2) * 2);
;                             f32x4 z0, z1;
;                             z0[0] = y0[0] * r0[0] - y0[1] * r0[1]; z0[1] = y0[0] * r0[1] + y0[1] * r0[0];
;                             z0[2] = y0[2] * r0[2] - y0[3] * r0[3]; z0[3] = y0[2] * r0[3] + y0[3] * r0[2];
;                             z1[0] = y1[0] * r1[0] - y1[1] * r1[1]; z1[1] = y1[0] * r1[1] + y1[1] * r1[0];
;                             z1[2] = y1[2] * r1[2] - y1[3] * r1[3]; z1[3] = y1[2] * r1[3] + y1[3] * r1[2];
;                             y0 = z0; y1 = z1;
;                         }
;                         y0 = y0 * osc; y1 = y1 * osc;
;                         u32x4 w; w.x = pkbf(y0[0], y0[1]); w.y = pkbf(y0[2], y0[3]); w.z = pkbf(y1[0], y1[1]); w.w = pkbf(y1[2], y1[3]);
.LBB0_249:
	v_bitop3_b32 v70, v80, s84, 16 bitop3:0xc8
	v_bitop3_b32 v56, v80, s95, 16 bitop3:0xc8
	v_add_u32_e32 v57, 0x100, v70
	v_cndmask_b32_e64 v71, v57, v56, s[4:5]
	v_lshlrev_b32_e32 v56, 7, v71
	v_and_b32_e32 v56, 0x1fe000, v56
	v_mov_b32_e32 v57, v177
	v_lshlrev_b32_e32 v71, 4, v71
	v_lshl_add_u64 v[56:57], s[14:15], 0, v[56:57]
	v_and_b32_e32 v72, 0x1f0, v71
	v_mov_b32_e32 v73, v177
	v_lshl_add_u64 v[56:57], v[56:57], 0, v[72:73]
	v_pk_mul_f32 v[68:69], v[64:65], v[68:69]
	v_pk_mul_f32 v[62:63], v[128:129], v[62:63]
	v_pk_mul_f32 v[64:65], v[64:65], v[66:67]
	v_pk_mul_f32 v[66:67], v[128:129], v[60:61]
	v_cvt_pk_bf16_f32 v60, v62, v63
	v_cvt_pk_bf16_f32 v61, v68, v69
	v_mov_b32_e32 v59, v58
	v_cvt_pk_bf16_f32 v62, v66, v67
	v_cvt_pk_bf16_f32 v63, v64, v65
	v_lshl_add_u64 v[64:65], v[56:57], 0, v[176:177]
	global_store_dwordx4 v[64:65], v[60:63], off
	v_pk_mul_f32 v[52:53], v[52:53], v[58:59]
	v_pk_mul_f32 v[48:49], v[48:49], v[58:59]
	v_mov_b32_e32 v62, v58
	v_mov_b32_e32 v63, v58
	v_pk_mul_f32 v[54:55], v[54:55], v[62:63]
	v_pk_mul_f32 v[50:51], v[50:51], v[62:63]
	v_pk_mul_f32 v[60:61], v[150:151], v[54:55]
	v_pk_mul_f32 v[52:53], v[148:149], v[52:53]
	v_pk_mul_f32 v[54:55], v[146:147], v[50:51]
	s_and_b64 vcc, exec, s[6:7]
	v_pk_mul_f32 v[50:51], v[144:145], v[48:49]
	s_cbranch_vccnz .LBB0_251
	v_lshlrev_b32_e32 v48, 5, v70
	s_movk_i32 s0, 0x3e0
	v_and_or_b32 v48, v48, s0, v168
	v_lshlrev_b32_e32 v48, 2, v48
	v_mov_b32_e32 v49, v177
	v_lshl_add_u64 v[48:49], s[18:19], 0, v[48:49]
	global_load_dwordx4 v[62:65], v[48:49], off
	global_load_dwordx4 v[66:69], v[48:49], off offset:16
	s_waitcnt vmcnt(0) lgkmcnt(0)
	v_pk_mul_f32 v[58:59], v[52:53], v[62:63] op_sel:[1,1] op_sel_hi:[1,0]
	v_pk_mul_f32 v[48:49], v[52:53], v[62:63]
	v_pk_fma_f32 v[52:53], v[52:53], v[62:63], v[58:59] op_sel_hi:[0,1,1]
	v_mul_f32_e32 v52, v61, v65
	v_pk_fma_f32 v[62:63], v[60:61], v[64:65], v[52:53] op_sel_hi:[1,1,0] neg_lo:[0,0,1] neg_hi:[0,0,1]
	v_mul_f32_e32 v52, v61, v64
	v_pk_mul_f32 v[70:71], v[50:51], v[66:67] op_sel:[1,1] op_sel_hi:[1,0]
	v_pk_fma_f32 v[64:65], v[60:61], v[64:65], v[52:53] op_sel:[0,1,0] op_sel_hi:[1,0,0]
	v_pk_mul_f32 v[60:61], v[50:51], v[66:67]
	v_pk_fma_f32 v[50:51], v[50:51], v[66:67], v[70:71] op_sel_hi:[0,1,1]
	v_mul_f32_e32 v50, v55, v69
	v_pk_fma_f32 v[66:67], v[54:55], v[68:69], v[50:51] op_sel_hi:[1,1,0] neg_lo:[0,0,1] neg_hi:[0,0,1]
	v_mul_f32_e32 v50, v55, v68
	v_pk_fma_f32 v[68:69], v[54:55], v[68:69], v[50:51] op_sel:[0,1,0] op_sel_hi:[1,0,0]
	v_sub_f32_e32 v50, v60, v70
	v_sub_f32_e32 v52, v48, v58
	v_mov_b32_e32 v54, v66
	v_mov_b32_e32 v55, v68
	v_mov_b32_e32 v60, v62
	v_mov_b32_e32 v61, v64
.LBB0_251:
	v_mov_b32_e32 v48, v128
	v_mov_b32_e32 v49, v128
	v_pk_mul_f32 v[52:53], v[128:129], v[52:53]
	v_pk_mul_f32 v[54:55], v[48:49], v[54:55]
	v_mov_b32_e32 v131, v177
	v_pk_mul_f32 v[58:59], v[48:49], v[60:61]
	v_pk_mul_f32 v[60:61], v[128:129], v[50:51]
	v_cvt_pk_bf16_f32 v50, v52, v53
	v_cvt_pk_bf16_f32 v51, v58, v59
	s_nop 0
	v_cvt_pk_bf16_f32 v52, v60, v61
	v_cvt_pk_bf16_f32 v53, v54, v55
	v_lshl_add_u64 v[54:55], v[56:57], 0, v[130:131]
	global_store_dwordx4 v[54:55], v[50:53], off
	global_load_dword v50, v[82:83], off offset:128
	s_waitcnt vmcnt(0) lgkmcnt(0)
	v_fmamk_f32 v50, v50, 0x3a800000, v224
	v_mul_f32_e32 v51, 0x4b800000, v50
	v_cmp_gt_f32_e32 vcc, s33, v50
	s_nop 1
	v_cndmask_b32_e32 v50, v50, v51, vcc
	v_rsq_f32_e32 v50, v50
	s_nop 0
	v_mul_f32_e32 v51, 0x45800000, v50
	v_cndmask_b32_e32 v50, v50, v51, vcc
	v_pk_fma_f32 v[28:29], v[28:29], v[50:51], v[44:45] op_sel_hi:[1,0,1]
	v_pk_fma_f32 v[30:31], v[30:31], v[50:51], v[46:47] op_sel_hi:[1,0,1]
	v_pk_fma_f32 v[24:25], v[24:25], v[50:51], v[40:41] op_sel_hi:[1,0,1]
	v_pk_fma_f32 v[52:53], v[26:27], v[50:51], v[42:43] op_sel_hi:[1,0,1]
	v_pk_fma_f32 v[22:23], v[22:23], v[50:51], v[38:39] op_sel_hi:[1,0,1]
	v_pk_fma_f32 v[20:21], v[20:21], v[50:51], v[36:37] op_sel_hi:[1,0,1]
	v_pk_fma_f32 v[18:19], v[18:19], v[50:51], v[34:35] op_sel_hi:[1,0,1]
	v_pk_fma_f32 v[16:17], v[16:17], v[50:51], v[32:33] op_sel_hi:[1,0,1]
	v_pk_mul_f32 v[26:27], v[30:31], v[30:31]
	v_pk_mul_f32 v[50:51], v[28:29], v[28:29]
	v_pk_mul_f32 v[54:55], v[52:53], v[52:53]
	v_pk_mul_f32 v[56:57], v[24:25], v[24:25]
	v_pk_mov_b32 v[62:63], v[50:51], v[26:27] op_sel:[1,0]
	v_mov_b32_e32 v51, v27
	v_pk_mov_b32 v[26:27], v[56:57], v[54:55] op_sel:[1,0]
	v_mov_b32_e32 v57, v55
	v_mul_f32_e32 v58, v20, v20
	v_mul_f32_e32 v60, v22, v22
	v_pk_add_f32 v[50:51], v[62:63], v[50:51]
	v_pk_add_f32 v[26:27], v[26:27], v[56:57]
	v_pk_fma_f32 v[54:55], v[20:21], v[20:21], v[58:59] op_sel_hi:[1,1,0]
	v_pk_fma_f32 v[58:59], v[22:23], v[22:23], v[60:61] op_sel_hi:[1,1,0]
	v_pk_add_f32 v[50:51], v[50:51], v[50:51] op_sel_hi:[0,1]
	v_pk_add_f32 v[26:27], v[26:27], v[26:27] op_sel_hi:[0,1]
	v_mul_f32_e32 v54, v16, v16
	v_mul_f32_e32 v58, v17, v17
	v_mul_f32_e32 v50, v18, v18
	v_mul_f32_e32 v26, v19, v19
	v_pk_add_f32 v[54:55], v[54:55], v[58:59]
	v_pk_add_f32 v[26:27], v[50:51], v[26:27]
	s_and_b64 vcc, exec, s[6:7]
	v_pk_add_f32 v[26:27], v[54:55], v[26:27]
	s_nop 0
	v_add_f32_e32 v26, v26, v27
	ds_bpermute_b32 v27, v201, v26
	s_waitcnt lgkmcnt(0)
	v_add_f32_e32 v26, v26, v27
	ds_bpermute_b32 v27, v202, v26
	s_waitcnt lgkmcnt(0)
	v_add_f32_e32 v26, v26, v27
	v_fmamk_f32 v26, v26, 0x3c800000, v224
	v_mul_f32_e32 v27, 0x4b800000, v26
	v_cmp_gt_f32_e64 s[0:1], s33, v26
	s_nop 1
	v_cndmask_b32_e64 v26, v26, v27, s[0:1]
	v_rsq_f32_e32 v26, v26
	s_nop 0
	v_mul_f32_e32 v27, 0x45800000, v26
	v_cndmask_b32_e64 v26, v26, v27, s[0:1]
	v_pk_mul_f32 v[28:29], v[28:29], v[26:27] op_sel_hi:[1,0]
	v_pk_mul_f32 v[30:31], v[30:31], v[26:27] op_sel_hi:[1,0]
	v_pk_mul_f32 v[24:25], v[24:25], v[26:27] op_sel_hi:[1,0]
	v_pk_mul_f32 v[50:51], v[52:53], v[26:27] op_sel_hi:[1,0]
	v_pk_mul_f32 v[52:53], v[158:159], v[30:31]
	v_pk_mul_f32 v[30:31], v[156:157], v[28:29]
	v_pk_mul_f32 v[50:51], v[154:155], v[50:51]
	v_pk_mul_f32 v[28:29], v[152:153], v[24:25]
	s_cbranch_vccnz .LBB0_253
; __device__ __forceinline__ unsigned pkbf(float lo, float hi) { return pg8::cvt_pk_bf16(lo, hi); }
;     __device__ __forceinline__ void operator()(const f32x4 (&acc)[2][2][4][2], const Unit& u, int wr, int wc, int fr, int fq) const {
;     ...
;                 for (int m = 0; m < 4; ++m) {
;                     const int row = pm * 256 + ai * 128 + wr * 64 + m * 16 + fr;
;                     const float rinv = rsqrtf(rowsq[row] * (1.f / DM) + EPSN);
;                     int b, kidx, t = 0;
;                     if (isctx) { const int rc = row - MLAT; b = rc >> 8; kidx = rc & 255; } else { b = row >> 13; t = row & (SEQ - 1); kidx = CTXL + t; }
;                     f32x4 val[2][2]; float ss = 0.f;
; #pragma unroll
;                     for (int bj = 0; bj < 2; ++bj)
; #pragma unroll
;                         for (int n = 0; n < 2; ++n) { val[bj][n] = acc[ai][bj][m][n] * rinv + bv[bj][n]; const f32x4 q = val[bj][n]; ss += (q[0] * q[0] + q[1] * q[1]) + (q[2] * q[2] + q[3] * q[3]); }
;                     ss += __shfl_xor(ss, 16); ss += __shfl_xor(ss, 32);
;                     const float rn = rsqrtf(ss * (1.f / 64.f) + EPSN);
; #pragma unroll
;                     for (int bj = 0; bj < 2; ++bj) {
;                         f32x4 y0 = val[bj][0] * rn * gv[bj][0], y1 = val[bj][1] * rn * gv[bj][1];
;                         if (!isctx) {
;                             const int pos = bj == 0 ? (t >> 6) : (t & 63);
;                             const f32x4 r0 = *(const f32x4*)(rope + (size_t)(pos * 16 + 4 * fq) * 2);
;                             const f32x4 r1 = *(const f32x4*)(rope + (size_t)(pos * 16 + 4 * fq + 2) * 2);
;                             f32x4 z0, z1;
;                             z0[0] = y0[0] * r0[0] - y0[1] * r0[1]; z0[1] = y0[0] * r0[1] + y0[1] * r0[0];
;                             z0[2] = y0[2] * r0[2] - y0[3] * r0[3]; z0[3] = y0[2] * r0[3] + y0[3] * r0[2];
;                             z1[0] = y1[0] * r1[0] - y1[1] * r1[1]; z1[1] = y1[0] * r1[1] + y1[1] * r1[0];
;                             z1[2] = y1[2] * r1[2] - y1[3] * r1[3]; z1[3] = y1[2] * r1[3] + y1[3] * r1[2];
;                             y0 = z0; y1 = z1;
;                         }
;                         y0 = y0 * osc; y1 = y1 * osc;
;                         u32x4 w; w.x = pkbf(y0[0], y0[1]); w.y = pkbf(y0[2], y0[3]); w.z = pkbf(y1[0], y1[1]); w.w = pkbf(y1[2], y1[3]);
	s_lshr_b32 s0, s56, 1
	s_and_b32 s0, s0, 0xfe0
	v_or_b32_e32 v24, s0, v168
	v_lshlrev_b32_e32 v24, 2, v24
	v_mov_b32_e32 v25, v177
	v_lshl_add_u64 v[24:25], s[18:19], 0, v[24:25]
	global_load_dwordx4 v[54:57], v[24:25], off
	global_load_dwordx4 v[58:61], v[24:25], off offset:16
	s_waitcnt vmcnt(0) lgkmcnt(0)
	v_pk_mul_f32 v[62:63], v[30:31], v[54:55] op_sel:[1,1] op_sel_hi:[1,0]
	v_pk_mul_f32 v[24:25], v[30:31], v[54:55]
	v_pk_fma_f32 v[30:31], v[30:31], v[54:55], v[62:63] op_sel_hi:[0,1,1]
	v_mul_f32_e32 v30, v53, v57
	v_pk_fma_f32 v[54:55], v[52:53], v[56:57], v[30:31] op_sel_hi:[1,1,0] neg_lo:[0,0,1] neg_hi:[0,0,1]
	v_mul_f32_e32 v30, v53, v56
	v_pk_mul_f32 v[64:65], v[28:29], v[58:59] op_sel:[1,1] op_sel_hi:[1,0]
	v_pk_fma_f32 v[56:57], v[52:53], v[56:57], v[30:31] op_sel:[0,1,0] op_sel_hi:[1,0,0]
	v_pk_mul_f32 v[52:53], v[28:29], v[58:59]
	v_pk_fma_f32 v[28:29], v[28:29], v[58:59], v[64:65] op_sel_hi:[0,1,1]
	v_mul_f32_e32 v28, v51, v61
	v_pk_fma_f32 v[58:59], v[50:51], v[60:61], v[28:29] op_sel_hi:[1,1,0] neg_lo:[0,0,1] neg_hi:[0,0,1]
	v_mul_f32_e32 v28, v51, v60
	v_pk_fma_f32 v[60:61], v[50:51], v[60:61], v[28:29] op_sel:[0,1,0] op_sel_hi:[1,0,0]
	v_sub_f32_e32 v28, v52, v64
	v_sub_f32_e32 v30, v24, v62
	v_mov_b32_e32 v50, v58
	v_mov_b32_e32 v51, v60
	v_mov_b32_e32 v52, v54
	v_mov_b32_e32 v53, v56
.LBB0_253:
	v_bitop3_b32 v54, v80, s81, 32 bitop3:0xc8
	v_bitop3_b32 v24, v80, s80, 32 bitop3:0xc8
	v_add_u32_e32 v25, 0x100, v54
	v_cndmask_b32_e64 v55, v25, v24, s[4:5]
	v_lshlrev_b32_e32 v24, 7, v55
	v_and_b32_e32 v24, 0x1fe000, v24
	v_mov_b32_e32 v25, v177
	v_lshlrev_b32_e32 v55, 4, v55
	v_lshl_add_u64 v[24:25], s[14:15], 0, v[24:25]
	v_and_b32_e32 v56, 0x2f0, v55
	v_mov_b32_e32 v57, v177
	v_lshl_add_u64 v[24:25], v[24:25], 0, v[56:57]
	v_pk_mul_f32 v[52:53], v[48:49], v[52:53]
	v_pk_mul_f32 v[30:31], v[128:129], v[30:31]
	v_pk_mul_f32 v[48:49], v[48:49], v[50:51]
	v_pk_mul_f32 v[50:51], v[128:129], v[28:29]
	v_cvt_pk_bf16_f32 v28, v30, v31
	v_cvt_pk_bf16_f32 v29, v52, v53
	v_mov_b32_e32 v27, v26
	v_cvt_pk_bf16_f32 v30, v50, v51
	v_cvt_pk_bf16_f32 v31, v48, v49
	v_lshl_add_u64 v[48:49], v[24:25], 0, v[176:177]
	global_store_dwordx4 v[48:49], v[28:31], off
	v_pk_mul_f32 v[20:21], v[20:21], v[26:27]
	v_pk_mul_f32 v[16:17], v[16:17], v[26:27]
	v_mov_b32_e32 v30, v26
	v_mov_b32_e32 v31, v26
	v_pk_mul_f32 v[22:23], v[22:23], v[30:31]
	v_pk_mul_f32 v[18:19], v[18:19], v[30:31]
	v_pk_mul_f32 v[28:29], v[150:151], v[22:23]
	v_pk_mul_f32 v[20:21], v[148:149], v[20:21]
	v_pk_mul_f32 v[22:23], v[146:147], v[18:19]
	s_and_b64 vcc, exec, s[6:7]
	v_pk_mul_f32 v[18:19], v[144:145], v[16:17]
	s_cbranch_vccnz .LBB0_255
	v_lshlrev_b32_e32 v16, 5, v54
	s_movk_i32 s0, 0x5e0
	v_and_or_b32 v16, v16, s0, v168
	v_lshlrev_b32_e32 v16, 2, v16
	v_mov_b32_e32 v17, v177
	v_lshl_add_u64 v[16:17], s[18:19], 0, v[16:17]
	global_load_dwordx4 v[48:51], v[16:17], off
	global_load_dwordx4 v[52:55], v[16:17], off offset:16
	s_waitcnt vmcnt(0) lgkmcnt(0)
	v_pk_mul_f32 v[26:27], v[20:21], v[48:49] op_sel:[1,1] op_sel_hi:[1,0]
	v_pk_mul_f32 v[16:17], v[20:21], v[48:49]
	v_pk_fma_f32 v[20:21], v[20:21], v[48:49], v[26:27] op_sel_hi:[0,1,1]
	v_mul_f32_e32 v20, v29, v51
	v_pk_fma_f32 v[30:31], v[28:29], v[50:51], v[20:21] op_sel_hi:[1,1,0] neg_lo:[0,0,1] neg_hi:[0,0,1]
	v_mul_f32_e32 v20, v29, v50
	v_pk_fma_f32 v[48:49], v[28:29], v[50:51], v[20:21] op_sel:[0,1,0] op_sel_hi:[1,0,0]
	v_pk_mul_f32 v[50:51], v[18:19], v[52:53] op_sel:[1,1] op_sel_hi:[1,0]
	v_pk_mul_f32 v[28:29], v[18:19], v[52:53]
	v_pk_fma_f32 v[18:19], v[18:19], v[52:53], v[50:51] op_sel_hi:[0,1,1]
	v_mul_f32_e32 v18, v23, v55
	v_pk_fma_f32 v[52:53], v[22:23], v[54:55], v[18:19] op_sel_hi:[1,1,0] neg_lo:[0,0,1] neg_hi:[0,0,1]
	v_mul_f32_e32 v18, v23, v54
	v_pk_fma_f32 v[54:55], v[22:23], v[54:55], v[18:19] op_sel:[0,1,0] op_sel_hi:[1,0,0]
	v_sub_f32_e32 v18, v28, v50
	v_sub_f32_e32 v20, v16, v26
	v_mov_b32_e32 v22, v52
	v_mov_b32_e32 v23, v54
	v_mov_b32_e32 v28, v30
	v_mov_b32_e32 v29, v48
.LBB0_255:
	v_mov_b32_e32 v16, v128
	v_mov_b32_e32 v17, v128
	v_pk_mul_f32 v[20:21], v[128:129], v[20:21]
	v_pk_mul_f32 v[22:23], v[16:17], v[22:23]
	v_mov_b32_e32 v131, v177
	v_pk_mul_f32 v[26:27], v[16:17], v[28:29]
	v_pk_mul_f32 v[28:29], v[128:129], v[18:19]
	v_cvt_pk_bf16_f32 v18, v20, v21
	v_cvt_pk_bf16_f32 v19, v26, v27
	s_nop 0
	v_cvt_pk_bf16_f32 v20, v28, v29
	v_cvt_pk_bf16_f32 v21, v22, v23
	v_lshl_add_u64 v[22:23], v[24:25], 0, v[130:131]
	global_store_dwordx4 v[22:23], v[18:21], off
	global_load_dword v18, v[82:83], off offset:192
	s_waitcnt vmcnt(0) lgkmcnt(0)
	v_fmamk_f32 v18, v18, 0x3a800000, v224
	v_mul_f32_e32 v19, 0x4b800000, v18
	v_cmp_gt_f32_e32 vcc, s33, v18
	s_nop 1
	v_cndmask_b32_e32 v18, v18, v19, vcc
	v_rsq_f32_e32 v18, v18
	s_nop 0
	v_mul_f32_e32 v19, 0x45800000, v18
	v_cndmask_b32_e32 v18, v18, v19, vcc
	v_pk_fma_f32 v[12:13], v[12:13], v[18:19], v[44:45] op_sel_hi:[1,0,1]
	v_pk_fma_f32 v[14:15], v[14:15], v[18:19], v[46:47] op_sel_hi:[1,0,1]
	v_pk_fma_f32 v[8:9], v[8:9], v[18:19], v[40:41] op_sel_hi:[1,0,1]
	v_pk_fma_f32 v[20:21], v[10:11], v[18:19], v[42:43] op_sel_hi:[1,0,1]
	v_pk_fma_f32 v[6:7], v[6:7], v[18:19], v[38:39] op_sel_hi:[1,0,1]
	v_pk_fma_f32 v[4:5], v[4:5], v[18:19], v[36:37] op_sel_hi:[1,0,1]
	v_pk_fma_f32 v[2:3], v[2:3], v[18:19], v[34:35] op_sel_hi:[1,0,1]
	v_pk_fma_f32 v[0:1], v[0:1], v[18:19], v[32:33] op_sel_hi:[1,0,1]
	v_pk_mul_f32 v[10:11], v[14:15], v[14:15]
	v_pk_mul_f32 v[18:19], v[12:13], v[12:13]
	v_pk_mul_f32 v[22:23], v[20:21], v[20:21]
	v_pk_mul_f32 v[24:25], v[8:9], v[8:9]
	v_pk_mov_b32 v[30:31], v[18:19], v[10:11] op_sel:[1,0]
	v_mov_b32_e32 v19, v11
	v_pk_mov_b32 v[10:11], v[24:25], v[22:23] op_sel:[1,0]
	v_mov_b32_e32 v25, v23
	v_mul_f32_e32 v26, v4, v4
	v_mul_f32_e32 v28, v6, v6
	v_pk_add_f32 v[18:19], v[30:31], v[18:19]
	v_pk_add_f32 v[10:11], v[10:11], v[24:25]
	v_pk_fma_f32 v[22:23], v[4:5], v[4:5], v[26:27] op_sel_hi:[1,1,0]
	v_pk_fma_f32 v[26:27], v[6:7], v[6:7], v[28:29] op_sel_hi:[1,1,0]
	v_pk_add_f32 v[18:19], v[18:19], v[18:19] op_sel_hi:[0,1]
	v_pk_add_f32 v[10:11], v[10:11], v[10:11] op_sel_hi:[0,1]
	v_mul_f32_e32 v22, v0, v0
	v_mul_f32_e32 v26, v1, v1
	v_mul_f32_e32 v18, v2, v2
	v_mul_f32_e32 v10, v3, v3
	v_pk_add_f32 v[22:23], v[22:23], v[26:27]
	v_pk_add_f32 v[10:11], v[18:19], v[10:11]
	s_and_b64 vcc, exec, s[6:7]
	v_pk_add_f32 v[10:11], v[22:23], v[10:11]
	s_nop 0
	v_add_f32_e32 v10, v10, v11
	ds_bpermute_b32 v11, v201, v10
	s_waitcnt lgkmcnt(0)
; __device__ __forceinline__ unsigned pkbf(float lo, float hi) { return pg8::cvt_pk_bf16(lo, hi); }
;     __device__ __forceinline__ void operator()(const f32x4 (&acc)[2][2][4][2], const Unit& u, int wr, int wc, int fr, int fq) const {
;     ...
;                 for (int m = 0; m < 4; ++m) {
;                     const int row = pm * 256 + ai * 128 + wr * 64 + m * 16 + fr;
;                     const float rinv = rsqrtf(rowsq[row] * (1.f / DM) + EPSN);
;                     int b, kidx, t = 0;
;                     if (isctx) { const int rc = row - MLAT; b = rc >> 8; kidx = rc & 255; } else { b = row >> 13; t = row & (SEQ - 1); kidx = CTXL + t; }
;                     f32x4 val[2][2]; float ss = 0.f;
; #pragma unroll
;                     for (int bj = 0; bj < 2; ++bj)
; #pragma unroll
;                         for (int n = 0; n < 2; ++n) { val[bj][n] = acc[ai][bj][m][n] * rinv + bv[bj][n]; const f32x4 q = val[bj][n]; ss += (q[0] * q[0] + q[1] * q[1]) + (q[2] * q[2] + q[3] * q[3]); }
;                     ss += __shfl_xor(ss, 16); ss += __shfl_xor(ss, 32);
;                     const float rn = rsqrtf(ss * (1.f / 64.f) + EPSN);
; #pragma unroll
;                     for (int bj = 0; bj < 2; ++bj) {
;                         f32x4 y0 = val[bj][0] * rn * gv[bj][0], y1 = val[bj][1] * rn * gv[bj][1];
;                         if (!isctx) {
;                             const int pos = bj == 0 ? (t >> 6) : (t & 63);
;                             const f32x4 r0 = *(const f32x4*)(rope + (size_t)(pos * 16 + 4 * fq) * 2);
;                             const f32x4 r1 = *(const f32x4*)(rope + (size_t)(pos * 16 + 4 * fq + 2) * 2);
;                             f32x4 z0, z1;
;                             z0[0] = y0[0] * r0[0] - y0[1] * r0[1]; z0[1] = y0[0] * r0[1] + y0[1] * r0[0];
;                             z0[2] = y0[2] * r0[2] - y0[3] * r0[3]; z0[3] = y0[2] * r0[3] + y0[3] * r0[2];
;                             z1[0] = y1[0] * r1[0] - y1[1] * r1[1]; z1[1] = y1[0] * r1[1] + y1[1] * r1[0];
;                             z1[2] = y1[2] * r1[2] - y1[3] * r1[3]; z1[3] = y1[2] * r1[3] + y1[3] * r1[2];
;                             y0 = z0; y1 = z1;
;                         }
;                         y0 = y0 * osc; y1 = y1 * osc;
;                         u32x4 w; w.x = pkbf(y0[0], y0[1]); w.y = pkbf(y0[2], y0[3]); w.z = pkbf(y1[0], y1[1]); w.w = pkbf(y1[2], y1[3]);
	v_add_f32_e32 v10, v10, v11
	ds_bpermute_b32 v11, v202, v10
	s_waitcnt lgkmcnt(0)
	v_add_f32_e32 v10, v10, v11
	v_fmamk_f32 v10, v10, 0x3c800000, v224
	v_mul_f32_e32 v11, 0x4b800000, v10
	v_cmp_gt_f32_e64 s[0:1], s33, v10
	s_nop 1
	v_cndmask_b32_e64 v10, v10, v11, s[0:1]
	v_rsq_f32_e32 v10, v10
	s_nop 0
	v_mul_f32_e32 v11, 0x45800000, v10
	v_cndmask_b32_e64 v10, v10, v11, s[0:1]
	v_pk_mul_f32 v[12:13], v[12:13], v[10:11] op_sel_hi:[1,0]
	v_pk_mul_f32 v[14:15], v[14:15], v[10:11] op_sel_hi:[1,0]
	v_pk_mul_f32 v[8:9], v[8:9], v[10:11] op_sel_hi:[1,0]
	v_pk_mul_f32 v[18:19], v[20:21], v[10:11] op_sel_hi:[1,0]
	v_pk_mul_f32 v[20:21], v[158:159], v[14:15]
	v_pk_mul_f32 v[14:15], v[156:157], v[12:13]
	v_pk_mul_f32 v[18:19], v[154:155], v[18:19]
	v_pk_mul_f32 v[12:13], v[152:153], v[8:9]
	s_cbranch_vccnz .LBB0_257
	s_lshr_b32 s0, s56, 1
	s_and_b32 s0, s0, 0xfe0
	v_or_b32_e32 v8, s0, v168
	v_lshlrev_b32_e32 v8, 2, v8
	v_mov_b32_e32 v9, v177
	v_lshl_add_u64 v[8:9], s[18:19], 0, v[8:9]
	global_load_dwordx4 v[22:25], v[8:9], off
	global_load_dwordx4 v[26:29], v[8:9], off offset:16
	s_waitcnt vmcnt(0) lgkmcnt(0)
	v_pk_mul_f32 v[30:31], v[14:15], v[22:23] op_sel:[1,1] op_sel_hi:[1,0]
	v_pk_mul_f32 v[8:9], v[14:15], v[22:23]
	v_pk_fma_f32 v[14:15], v[14:15], v[22:23], v[30:31] op_sel_hi:[0,1,1]
	v_mul_f32_e32 v14, v21, v25
	v_pk_fma_f32 v[22:23], v[20:21], v[24:25], v[14:15] op_sel_hi:[1,1,0] neg_lo:[0,0,1] neg_hi:[0,0,1]
	v_mul_f32_e32 v14, v21, v24
	v_pk_mul_f32 v[32:33], v[12:13], v[26:27] op_sel:[1,1] op_sel_hi:[1,0]
	v_pk_fma_f32 v[24:25], v[20:21], v[24:25], v[14:15] op_sel:[0,1,0] op_sel_hi:[1,0,0]
	v_pk_mul_f32 v[20:21], v[12:13], v[26:27]
	v_pk_fma_f32 v[12:13], v[12:13], v[26:27], v[32:33] op_sel_hi:[0,1,1]
	v_mul_f32_e32 v12, v19, v29
	v_pk_fma_f32 v[26:27], v[18:19], v[28:29], v[12:13] op_sel_hi:[1,1,0] neg_lo:[0,0,1] neg_hi:[0,0,1]
	v_mul_f32_e32 v12, v19, v28
	v_pk_fma_f32 v[28:29], v[18:19], v[28:29], v[12:13] op_sel:[0,1,0] op_sel_hi:[1,0,0]
	v_sub_f32_e32 v12, v20, v32
	v_sub_f32_e32 v14, v8, v30
	v_mov_b32_e32 v18, v26
	v_mov_b32_e32 v19, v28
	v_mov_b32_e32 v20, v22
	v_mov_b32_e32 v21, v24
.LBB0_257:
	v_bitop3_b32 v22, v80, s68, 48 bitop3:0xc8
	v_bitop3_b32 v8, v80, s48, 48 bitop3:0xc8
	v_add_u32_e32 v9, 0x100, v22
	v_cndmask_b32_e64 v23, v9, v8, s[4:5]
	v_lshlrev_b32_e32 v8, 7, v23
	v_and_b32_e32 v8, 0x1fe000, v8
	v_mov_b32_e32 v9, v177
	v_lshlrev_b32_e32 v23, 4, v23
	v_lshl_add_u64 v[8:9], s[14:15], 0, v[8:9]
	v_and_b32_e32 v24, 0x3f0, v23
	v_mov_b32_e32 v25, v177
	v_lshl_add_u64 v[8:9], v[8:9], 0, v[24:25]
	v_pk_mul_f32 v[20:21], v[16:17], v[20:21]
	v_pk_mul_f32 v[14:15], v[128:129], v[14:15]
	v_pk_mul_f32 v[16:17], v[16:17], v[18:19]
	v_pk_mul_f32 v[18:19], v[128:129], v[12:13]
	v_cvt_pk_bf16_f32 v12, v14, v15
	v_cvt_pk_bf16_f32 v13, v20, v21
	v_mov_b32_e32 v11, v10
	v_cvt_pk_bf16_f32 v14, v18, v19
	v_cvt_pk_bf16_f32 v15, v16, v17
	v_lshl_add_u64 v[16:17], v[8:9], 0, v[176:177]
	global_store_dwordx4 v[16:17], v[12:15], off
	v_pk_mul_f32 v[4:5], v[4:5], v[10:11]
	v_pk_mul_f32 v[0:1], v[0:1], v[10:11]
	v_mov_b32_e32 v12, v10
	v_mov_b32_e32 v13, v10
	v_pk_mul_f32 v[6:7], v[6:7], v[12:13]
	v_pk_mul_f32 v[2:3], v[2:3], v[12:13]
	v_pk_mul_f32 v[6:7], v[150:151], v[6:7]
	v_pk_mul_f32 v[4:5], v[148:149], v[4:5]
	v_pk_mul_f32 v[2:3], v[146:147], v[2:3]
	s_and_b64 vcc, exec, s[6:7]
	v_pk_mul_f32 v[0:1], v[144:145], v[0:1]
	s_cbranch_vccnz .LBB0_259
	v_lshlrev_b32_e32 v10, 5, v22
	s_movk_i32 s0, 0x7e0
	v_and_or_b32 v10, v10, s0, v168
	v_lshlrev_b32_e32 v176, 2, v10
	v_lshl_add_u64 v[14:15], s[18:19], 0, v[176:177]
	global_load_dwordx4 v[10:13], v[14:15], off
	s_nop 0
	global_load_dwordx4 v[14:17], v[14:15], off offset:16
	s_waitcnt vmcnt(0) lgkmcnt(0)
	v_pk_mul_f32 v[20:21], v[4:5], v[10:11] op_sel:[1,1] op_sel_hi:[1,0]
	v_pk_mul_f32 v[18:19], v[4:5], v[10:11]
	v_pk_fma_f32 v[4:5], v[4:5], v[10:11], v[20:21] op_sel_hi:[0,1,1]
	v_mul_f32_e32 v4, v7, v13
	v_pk_fma_f32 v[10:11], v[6:7], v[12:13], v[4:5] op_sel_hi:[1,1,0] neg_lo:[0,0,1] neg_hi:[0,0,1]
	v_mul_f32_e32 v4, v7, v12
	v_pk_mul_f32 v[22:23], v[0:1], v[14:15] op_sel:[1,1] op_sel_hi:[1,0]
	v_pk_fma_f32 v[12:13], v[6:7], v[12:13], v[4:5] op_sel:[0,1,0] op_sel_hi:[1,0,0]
	v_pk_mul_f32 v[6:7], v[0:1], v[14:15]
	v_pk_fma_f32 v[0:1], v[0:1], v[14:15], v[22:23] op_sel_hi:[0,1,1]
	v_mul_f32_e32 v0, v3, v17
	v_pk_fma_f32 v[14:15], v[2:3], v[16:17], v[0:1] op_sel_hi:[1,1,0] neg_lo:[0,0,1] neg_hi:[0,0,1]
	v_mul_f32_e32 v0, v3, v16
	v_pk_fma_f32 v[16:17], v[2:3], v[16:17], v[0:1] op_sel:[0,1,0] op_sel_hi:[1,0,0]
	v_sub_f32_e32 v0, v6, v22
	v_sub_f32_e32 v4, v18, v20
	v_mov_b32_e32 v2, v14
	v_mov_b32_e32 v3, v16
	v_mov_b32_e32 v6, v10
	v_mov_b32_e32 v7, v12
.LBB0_259:
	v_mov_b32_e32 v10, v128
	v_mov_b32_e32 v11, v128
	v_pk_mul_f32 v[4:5], v[128:129], v[4:5]
	v_mov_b32_e32 v131, v177
	v_pk_mul_f32 v[6:7], v[10:11], v[6:7]
	v_pk_mul_f32 v[10:11], v[10:11], v[2:3]
	v_pk_mul_f32 v[2:3], v[128:129], v[0:1]
	v_cvt_pk_bf16_f32 v0, v4, v5
	v_lshl_add_u64 v[4:5], v[8:9], 0, v[130:131]
	v_cvt_pk_bf16_f32 v1, v6, v7
	v_cvt_pk_bf16_f32 v2, v2, v3
	v_cvt_pk_bf16_f32 v3, v10, v11
	global_store_dwordx4 v[4:5], v[0:3], off
	s_andn2_b64 vcc, exec, s[28:29]
	s_mov_b64 s[0:1], -1
	s_cbranch_vccnz .LBB0_205

; __device__ __forceinline__ unsigned xb_ld(unsigned* p)              { return __hip_atomic_load(p, __ATOMIC_RELAXED, __HIP_MEMORY_SCOPE_AGENT); }
; __device__ __forceinline__ void xcd_barrier_complete(unsigned* bar, unsigned x, unsigned& nloc, unsigned& nx) {
;     const unsigned G = gridDim.x * gridDim.y * gridDim.z;
;     unsigned sum, cnt, mine, sp = 0u;
;     for (;;) {
;         sum = 0u; cnt = 0u; mine = 0u;
; #pragma unroll
;         for (unsigned j = 0; j < 16; ++j) { const unsigned c = xb_ld(&bar[XB_XCNT(j)]); sum += c; cnt += (c > 0u) ? 1u : 0u; mine = (j == x) ? c : mine; }
;         if (sum == G) break;
;         __builtin_amdgcn_s_sleep(1);
;         if ((++sp & 255u) == 0u) { if (xb_ld(&bar[XB_TMO])) break; if (sp > XB_SPIN_CAP) { atomicAdd(&bar[XB_TMO], 1u); break; } }
;     }
;     nloc = mine > 0u ? mine : 1u; nx = cnt > 0u ? cnt : 1u;
; }
.LBB0_268:
	v_mov_b64_e32 v[12:13], s[40:41]
	global_load_dword v1, v[12:13], off offset:1024 sc1
	s_waitcnt lgkmcnt(0)
	global_load_dword v0, v[12:13], off offset:1280 sc1
	global_load_dword v2, v[12:13], off offset:1536 sc1
	s_or_b64 s[20:21], s[20:21], exec
	s_or_b64 s[18:19], s[18:19], exec
	s_waitcnt vmcnt(0) lgkmcnt(0)
	v_add_u32_e32 v3, v0, v1
	v_add_u32_e32 v4, v3, v2
	global_load_dword v3, v[12:13], off offset:1792 sc1
	s_waitcnt vmcnt(0) lgkmcnt(0)
	v_add_u32_e32 v5, v4, v3
	global_load_dword v4, v[12:13], off offset:2048 sc1
	s_waitcnt vmcnt(0) lgkmcnt(0)
	v_add_u32_e32 v6, v5, v4
	global_load_dword v5, v[12:13], off offset:2304 sc1
	s_waitcnt vmcnt(0) lgkmcnt(0)
	v_add_u32_e32 v7, v6, v5
	global_load_dword v6, v[12:13], off offset:2560 sc1
	s_waitcnt vmcnt(0) lgkmcnt(0)
	v_add_u32_e32 v8, v7, v6
	global_load_dword v7, v[12:13], off offset:2816 sc1
	s_waitcnt vmcnt(0) lgkmcnt(0)
	v_add_u32_e32 v9, v8, v7
	global_load_dword v8, v[12:13], off offset:3072 sc1
	s_waitcnt vmcnt(0) lgkmcnt(0)
	v_add_u32_e32 v10, v9, v8
	global_load_dword v9, v[12:13], off offset:3328 sc1
	s_waitcnt vmcnt(0) lgkmcnt(0)
	v_add_u32_e32 v11, v10, v9
	global_load_dword v10, v[12:13], off offset:3584 sc1
	s_waitcnt vmcnt(0) lgkmcnt(0)
	v_add_u32_e32 v14, v11, v10
	global_load_dword v11, v[12:13], off offset:3840 sc1
	v_mov_b64_e32 v[12:13], s[0:1]
	global_load_dword v12, v[12:13], off sc1
	s_waitcnt vmcnt(0) lgkmcnt(0)
	v_add_u32_e32 v14, v14, v11
	v_add_u32_e32 v16, v14, v12
	v_mov_b64_e32 v[14:15], s[4:5]
	global_load_dword v13, v[14:15], off sc1
	v_mov_b64_e32 v[14:15], s[6:7]
	global_load_dword v14, v[14:15], off sc1
	s_waitcnt vmcnt(0) lgkmcnt(0)
	v_add_u32_e32 v16, v16, v13
	v_add_u32_e32 v18, v16, v14
	v_mov_b64_e32 v[16:17], s[10:11]
	global_load_dword v15, v[16:17], off sc1
	s_waitcnt vmcnt(0) lgkmcnt(0)
	v_add_u32_e32 v16, v18, v15
	v_cmp_ne_u32_e32 vcc, s78, v16
	s_and_saveexec_b64 s[22:23], vcc
	s_cbranch_execz .LBB0_267
	s_and_b32 s26, s34, 0xff
	s_mov_b64 s[24:25], -1
	s_cmp_eq_u32 s26, 0
	s_mov_b64 s[28:29], -1
	s_mov_b64 s[26:27], -1
	s_sleep 1
	s_cbranch_scc1 .LBB0_271
	s_and_saveexec_b64 s[30:31], s[28:29]
	s_cbranch_execz .LBB0_266
	s_branch .LBB0_274
.LBB0_271:
	v_mov_b64_e32 v[16:17], s[40:41]
	global_load_dword v16, v[16:17], off offset:512 sc1
	s_mov_b64 s[28:29], 0
	s_waitcnt vmcnt(0) lgkmcnt(0)
	v_cmp_eq_u32_e32 vcc, 0, v16
	s_and_saveexec_b64 s[30:31], vcc
	s_cmp_lt_u32 s34, 0x40001
	s_cselect_b64 s[28:29], -1, 0
	s_xor_b64 s[26:27], exec, -1
	s_and_b64 s[28:29], s[28:29], exec
	s_or_b64 exec, exec, s[30:31]
	s_and_saveexec_b64 s[30:31], s[28:29]
	s_cbranch_execz .LBB0_266

; __device__ __forceinline__ unsigned xb_ld(unsigned* p)              { return __hip_atomic_load(p, __ATOMIC_RELAXED, __HIP_MEMORY_SCOPE_AGENT); }
; __device__ __forceinline__ void xcd_barrier_complete(unsigned* bar, unsigned x, unsigned& nloc, unsigned& nx) {
;     ...
;         if ((++sp & 255u) == 0u) { if (xb_ld(&bar[XB_TMO])) break; if (sp > XB_SPIN_CAP) { atomicAdd(&bar[XB_TMO], 1u); break; } }
.LBB0_275:
	s_or_b64 exec, exec, s[12:13]
	s_xor_b64 s[0:1], s[16:17], -1
	s_and_saveexec_b64 s[4:5], s[0:1]
	s_xor_b64 s[0:1], exec, s[4:5]
	s_cbranch_execz .LBB0_277
	v_mov_b64_e32 v[16:17], s[40:41]
	global_atomic_add v[16:17], v225, off offset:512

; __device__ __forceinline__ unsigned xb_ld(unsigned* p)              { return __hip_atomic_load(p, __ATOMIC_RELAXED, __HIP_MEMORY_SCOPE_AGENT); }
; __device__ __forceinline__ unsigned xb_add(unsigned* p, unsigned v) { return __hip_atomic_fetch_add(p, v, __ATOMIC_RELAXED, __HIP_MEMORY_SCOPE_AGENT); }
; #define XB_SPIN(cond, bar) do { unsigned _sp = 0; while (cond) { __builtin_amdgcn_s_sleep(1); \
;     if ((++_sp & 255u) == 0u) { if (xb_ld(&(bar)[XB_TMO])) break; if (_sp > XB_SPIN_CAP) { atomicAdd(&(bar)[XB_TMO], 1u); break; } } } } while (0)
; __device__ __forceinline__ void xcd_barrier(const XcdBarrier& b) {
;     ...
;         const unsigned old = xb_add(&bar[XB_XSUB(b.x)], 1u);
;         const unsigned gen = old / nloc;
;         if (old + 1u == (gen + 1u) * nloc) {
;             __builtin_amdgcn_fence(__ATOMIC_RELEASE, "agent");
;             asm volatile("s_waitcnt vmcnt(0)" ::: "memory");
;             const unsigned og = xb_add(&bar[XB_TOP], 1u);
;             const unsigned tg = og / nx;
;             if (og + 1u == (tg + 1u) * nx) xb_add(&bar[XB_TOPGEN], 1u);
;             else XB_SPIN(xb_ld(&bar[XB_TOPGEN]) == tg, bar);
;             __builtin_amdgcn_fence(__ATOMIC_ACQUIRE, "agent");
;             xb_add(&bar[XB_XGEN(b.x)], 1u);
;             asm volatile("s_waitcnt vmcnt(0)" ::: "memory");
;         } else {
;             XB_SPIN(xb_ld(&bar[XB_XGEN(b.x)]) == gen, bar);
.LBB0_278:
	s_lshl_b32 s0, s38, 8
	s_add_u32 s27, s40, s0
	s_addc_u32 s26, s41, 0
	v_mov_b32_e32 v1, s27
	v_add_co_u32_e32 v4, vcc, 0x1000, v1
	v_mov_b32_e32 v1, s26
	s_nop 0
	v_addc_co_u32_e32 v5, vcc, 0, v1, vcc
	global_atomic_add v3, v[4:5], v225, off offset:1024 sc0
	v_cvt_f32_u32_e32 v1, v2
	v_sub_u32_e32 v4, 0, v2
	v_rcp_iflag_f32_e32 v1, v1
	s_nop 0
	v_mul_f32_e32 v1, 0x4f7ffffe, v1
	v_cvt_u32_f32_e32 v1, v1
	v_mul_lo_u32 v4, v4, v1
	v_mul_hi_u32 v4, v1, v4
	v_add_u32_e32 v1, v1, v4
	s_waitcnt vmcnt(0) lgkmcnt(0)
	v_mul_hi_u32 v1, v3, v1
	v_mul_lo_u32 v4, v1, v2
	v_sub_u32_e32 v4, v3, v4
	v_cmp_ge_u32_e32 vcc, v4, v2
	v_add_u32_e32 v5, 1, v1
	s_nop 0
	v_cndmask_b32_e32 v1, v1, v5, vcc
	v_sub_u32_e32 v5, v4, v2
	v_cndmask_b32_e32 v4, v4, v5, vcc
	v_cmp_ge_u32_e32 vcc, v4, v2
	v_add_u32_e32 v4, 1, v1
	s_nop 0
	v_cndmask_b32_e32 v1, v1, v4, vcc
	v_add_u32_e32 v4, 1, v3
	v_mad_u64_u32 v[2:3], s[0:1], v2, v1, v[2:3]
	v_cmp_ne_u32_e32 vcc, v4, v2
	s_and_saveexec_b64 s[0:1], vcc
	s_xor_b64 s[0:1], exec, s[0:1]
	s_cbranch_execz .LBB0_291
	v_mov_b32_e32 v0, s27
	v_add_co_u32_e32 v2, vcc, 0x2000, v0
	v_mov_b32_e32 v0, s26
	s_nop 0
	v_addc_co_u32_e32 v3, vcc, 0, v0, vcc
	global_load_dword v0, v[2:3], off offset:1024 sc1
	s_add_u32 s6, s27, 0x2400
	s_addc_u32 s7, s26, 0
	s_waitcnt vmcnt(0) lgkmcnt(0)
	v_cmp_eq_u32_e32 vcc, v0, v1
	s_and_saveexec_b64 s[4:5], vcc
	s_cbranch_execz .LBB0_290
	s_mov_b32 s28, 1
	s_mov_b64 s[10:11], 0
	s_branch .LBB0_282

; __device__ __forceinline__ unsigned xb_ld(unsigned* p)              { return __hip_atomic_load(p, __ATOMIC_RELAXED, __HIP_MEMORY_SCOPE_AGENT); }
; #define XB_SPIN(cond, bar) do { unsigned _sp = 0; while (cond) { __builtin_amdgcn_s_sleep(1); \
;     if ((++_sp & 255u) == 0u) { if (xb_ld(&(bar)[XB_TMO])) break; if (_sp > XB_SPIN_CAP) { atomicAdd(&(bar)[XB_TMO], 1u); break; } } } } while (0)
; __device__ __forceinline__ void xcd_barrier(const XcdBarrier& b) {
;     ...
;             XB_SPIN(xb_ld(&bar[XB_XGEN(b.x)]) == gen, bar);
.LBB0_282:
	s_and_b32 s20, s28, 0xff
	s_mov_b64 s[18:19], -1
	s_cmp_lg_u32 s20, 0
	s_mov_b64 s[20:21], -1
	s_sleep 1
	s_cbranch_scc1 .LBB0_286
	v_mov_b64_e32 v[2:3], s[40:41]
	global_load_dword v0, v[2:3], off offset:512 sc1
	s_mov_b64 s[20:21], 0
	s_mov_b64 s[22:23], -1
	s_waitcnt vmcnt(0) lgkmcnt(0)
	v_cmp_eq_u32_e32 vcc, 0, v0
	s_and_saveexec_b64 s[24:25], vcc
	s_cmp_lt_u32 s28, 0x40001
	s_cselect_b64 s[20:21], -1, 0
	s_xor_b64 s[22:23], exec, -1
	s_and_b64 s[20:21], s[20:21], exec
	s_or_b64 exec, exec, s[24:25]
.LBB0_286:
	s_andn2_b64 s[16:17], s[16:17], exec
	s_and_b64 s[22:23], s[22:23], exec
	s_or_b64 s[16:17], s[16:17], s[22:23]
	s_and_saveexec_b64 s[22:23], s[20:21]
	s_cbranch_execz .LBB0_281
	v_mov_b64_e32 v[2:3], s[6:7]
	global_load_dword v0, v[2:3], off sc1
	s_add_i32 s28, s28, 1
	s_or_b64 s[16:17], s[16:17], exec
	s_waitcnt vmcnt(0) lgkmcnt(0)
	v_cmp_ne_u32_e32 vcc, v0, v1
	s_orn2_b64 s[18:19], vcc, exec
	s_branch .LBB0_281
.LBB0_288:
	s_or_b64 exec, exec, s[10:11]
	s_xor_b64 s[6:7], s[12:13], -1
	s_and_saveexec_b64 s[10:11], s[6:7]
	s_xor_b64 s[10:11], exec, s[10:11]
	s_cbranch_execz .LBB0_290
	v_mov_b64_e32 v[0:1], s[40:41]
	global_atomic_add v[0:1], v225, off offset:512

; __device__ __forceinline__ unsigned xb_ld(unsigned* p)              { return __hip_atomic_load(p, __ATOMIC_RELAXED, __HIP_MEMORY_SCOPE_AGENT); }
; __device__ __forceinline__ unsigned xb_add(unsigned* p, unsigned v) { return __hip_atomic_fetch_add(p, v, __ATOMIC_RELAXED, __HIP_MEMORY_SCOPE_AGENT); }
; #define XB_SPIN(cond, bar) do { unsigned _sp = 0; while (cond) { __builtin_amdgcn_s_sleep(1); \
;     if ((++_sp & 255u) == 0u) { if (xb_ld(&(bar)[XB_TMO])) break; if (_sp > XB_SPIN_CAP) { atomicAdd(&(bar)[XB_TMO], 1u); break; } } } } while (0)
; __device__ __forceinline__ void xcd_barrier(const XcdBarrier& b) {
;     ...
;         if (old + 1u == (gen + 1u) * nloc) {
;             __builtin_amdgcn_fence(__ATOMIC_RELEASE, "agent");
;             asm volatile("s_waitcnt vmcnt(0)" ::: "memory");
;             const unsigned og = xb_add(&bar[XB_TOP], 1u);
;             const unsigned tg = og / nx;
;             if (og + 1u == (tg + 1u) * nx) xb_add(&bar[XB_TOPGEN], 1u);
;             else XB_SPIN(xb_ld(&bar[XB_TOPGEN]) == tg, bar);
.LBB0_291:
	s_andn2_saveexec_b64 s[0:1], s[0:1]
	s_cbranch_execz .LBB0_307
	v_mov_b32_e32 v1, s40
	v_add_co_u32_e32 v2, vcc, 0x3000, v1
	v_mov_b32_e32 v1, s41
	buffer_wbl2 sc1
	s_waitcnt vmcnt(0)
	v_addc_co_u32_e32 v3, vcc, 0, v1, vcc
	global_atomic_add v1, v[2:3], v225, off offset:1024 sc0
	v_cvt_f32_u32_e32 v2, v0
	v_sub_u32_e32 v3, 0, v0
	s_mov_b64 s[6:7], -1
	v_rcp_iflag_f32_e32 v2, v2
	s_nop 0
	v_mul_f32_e32 v2, 0x4f7ffffe, v2
	v_cvt_u32_f32_e32 v2, v2
	v_mul_lo_u32 v3, v3, v2
	v_mul_hi_u32 v3, v2, v3
	v_add_u32_e32 v2, v2, v3
	s_waitcnt vmcnt(0) lgkmcnt(0)
	v_mul_hi_u32 v2, v1, v2
	v_mul_lo_u32 v3, v2, v0
	v_sub_u32_e32 v3, v1, v3
	v_cmp_ge_u32_e32 vcc, v3, v0
	v_add_u32_e32 v4, 1, v2
	s_nop 0
	v_cndmask_b32_e32 v2, v2, v4, vcc
	v_sub_u32_e32 v4, v3, v0
	v_cndmask_b32_e32 v3, v3, v4, vcc
	v_cmp_ge_u32_e32 vcc, v3, v0
	v_add_u32_e32 v3, 1, v2
	s_nop 0
	v_cndmask_b32_e32 v2, v2, v3, vcc
	v_add_u32_e32 v3, 1, v1
	v_mad_u64_u32 v[0:1], s[0:1], v0, v2, v[0:1]
	s_add_u32 s0, s40, 0x3500
	s_addc_u32 s1, s41, 0
	v_cmp_ne_u32_e32 vcc, v3, v0
	v_mov_b64_e32 v[0:1], s[0:1]
	s_and_saveexec_b64 s[4:5], vcc
	s_cbranch_execz .LBB0_304
	v_mov_b64_e32 v[0:1], s[0:1]
	global_load_dword v0, v[0:1], off sc1
	s_mov_b64 s[12:13], 0
	s_waitcnt vmcnt(0) lgkmcnt(0)
	v_cmp_eq_u32_e32 vcc, v0, v2
	s_and_saveexec_b64 s[10:11], vcc
	s_cbranch_execz .LBB0_303
	s_add_u32 s6, s40, 0x200
	s_addc_u32 s7, s41, 0
	s_mov_b32 s28, 1
	s_branch .LBB0_296

; __device__ __forceinline__ unsigned xb_ld(unsigned* p)              { return __hip_atomic_load(p, __ATOMIC_RELAXED, __HIP_MEMORY_SCOPE_AGENT); }
; #define XB_SPIN(cond, bar) do { unsigned _sp = 0; while (cond) { __builtin_amdgcn_s_sleep(1); \
;     if ((++_sp & 255u) == 0u) { if (xb_ld(&(bar)[XB_TMO])) break; if (_sp > XB_SPIN_CAP) { atomicAdd(&(bar)[XB_TMO], 1u); break; } } } } while (0)
; __device__ __forceinline__ void xcd_barrier(const XcdBarrier& b) {
;     ...
;             else XB_SPIN(xb_ld(&bar[XB_TOPGEN]) == tg, bar);
.LBB0_298:
	v_mov_b64_e32 v[0:1], s[6:7]
	global_load_dword v0, v[0:1], off sc1
	s_mov_b64 s[22:23], 0
	s_mov_b64 s[20:21], -1
	s_waitcnt vmcnt(0) lgkmcnt(0)
	v_cmp_eq_u32_e32 vcc, 0, v0
	s_and_saveexec_b64 s[24:25], vcc
	s_cmp_lt_u32 s28, 0x40001
	s_cselect_b64 s[22:23], -1, 0
	s_xor_b64 s[20:21], exec, -1
	s_and_b64 s[22:23], s[22:23], exec
	s_or_b64 exec, exec, s[24:25]
	s_and_saveexec_b64 s[24:25], s[22:23]
	s_cbranch_execz .LBB0_295
.LBB0_301:
	v_mov_b64_e32 v[0:1], s[0:1]
	global_load_dword v0, v[0:1], off sc1
	s_add_i32 s28, s28, 1
	s_or_b64 s[20:21], s[20:21], exec
	s_waitcnt vmcnt(0) lgkmcnt(0)
	v_cmp_ne_u32_e32 vcc, v0, v2
	s_orn2_b64 s[18:19], vcc, exec
	s_branch .LBB0_295

; __device__ __forceinline__ unsigned xb_ld(unsigned* p)              { return __hip_atomic_load(p, __ATOMIC_RELAXED, __HIP_MEMORY_SCOPE_AGENT); }
; __device__ __forceinline__ unsigned xb_add(unsigned* p, unsigned v) { return __hip_atomic_fetch_add(p, v, __ATOMIC_RELAXED, __HIP_MEMORY_SCOPE_AGENT); }
; #define XB_SPIN(cond, bar) do { unsigned _sp = 0; while (cond) { __builtin_amdgcn_s_sleep(1); \
;     if ((++_sp & 255u) == 0u) { if (xb_ld(&(bar)[XB_TMO])) break; if (_sp > XB_SPIN_CAP) { atomicAdd(&(bar)[XB_TMO], 1u); break; } } } } while (0)
; __device__ __forceinline__ void xcd_barrier(const XcdBarrier& b) {
;     ...
;             if (og + 1u == (tg + 1u) * nx) xb_add(&bar[XB_TOPGEN], 1u);
;             else XB_SPIN(xb_ld(&bar[XB_TOPGEN]) == tg, bar);
;             __builtin_amdgcn_fence(__ATOMIC_ACQUIRE, "agent");
;             xb_add(&bar[XB_XGEN(b.x)], 1u);
;             asm volatile("s_waitcnt vmcnt(0)" ::: "memory");
.LBB0_304:
	s_or_b64 exec, exec, s[4:5]
	s_and_saveexec_b64 s[0:1], s[6:7]
	s_cbranch_execz .LBB0_306
	global_atomic_add v[0:1], v225, off
.LBB0_306:
	s_or_b64 exec, exec, s[0:1]
	v_mov_b32_e32 v0, s27
	v_add_co_u32_e32 v0, vcc, 0x2000, v0
	v_mov_b32_e32 v1, s26
	s_nop 0
	v_addc_co_u32_e32 v1, vcc, 0, v1, vcc
	s_waitcnt vmcnt(0) lgkmcnt(0)
	buffer_inv sc1
	global_atomic_add v[0:1], v225, off offset:1024
	s_waitcnt vmcnt(0)

; __device__ __forceinline__ float sigm(float v) { return __builtin_amdgcn_rcpf(1.f + __builtin_amdgcn_exp2f(-1.4426950408889634f * v)); }
;     __device__ __forceinline__ void operator()(const f32x4 (&acc)[2][2][4][2], const Unit& u, int wr, int wc, int fr, int fq) const {
;     ...
;         const int cb = pn * 256 + wc * 32 + 8 * fq;
;         f32x4 bv[2][2];
; #pragma unroll
;         for (int bj = 0; bj < 2; ++bj)
; #pragma unroll
;             for (int n = 0; n < 2; ++n) bv[bj][n] = *(const f32x4*)(bias + v * INW + cb + 128 * bj + 4 * n);
;     ...
;         } else {
;             const int ch0 = 128 * (pn - 7) + 32 * wc + 8 * fq;
; #pragma unroll
;             for (int ai = 0; ai < 2; ++ai)
; #pragma unroll
;                 for (int m = 0; m < 4; ++m) {
;                     const int row = pm * 256 + ai * 128 + wr * 64 + m * 16 + fr;
;                     const float rinv = rsqrtf(rowsq[row] * (1.f / DM) + EPSN);
; #pragma unroll
;                     for (int n = 0; n < 2; ++n) {
;                         const f32x4 a = acc[ai][0][m][n] * rinv + bv[0][n], g = acc[ai][1][m][n] * rinv + bv[1][n];
;                         f32x4 o;
; #pragma unroll
;                         for (int j = 0; j < 4; ++j) o[j] = a[j] * sigm(g[j]);
;                         *(f32x4*)(uconv + (size_t)row * 256 + ch0 + 4 * n) = o;
;                     }
;                 }
.LBB0_319:
	s_min_i32 s0, s66, 64
	s_lshr_b32 s0, s0, 5
	s_mulk_i32 s0, 0x900
	s_ashr_i32 s1, s0, 31
	s_lshl_b64 s[0:1], s[0:1], 2
	v_lshl_or_b32 v32, s67, 8, v172
	s_add_u32 s0, s43, s0
	s_addc_u32 s1, s44, s1
	v_ashrrev_i32_e32 v33, 31, v32
	v_lshl_add_u64 v[32:33], v[32:33], 2, s[0:1]
	global_load_dwordx4 v[52:55], v[32:33], off
	global_load_dwordx4 v[48:51], v[32:33], off offset:16
	global_load_dwordx4 v[36:39], v[32:33], off offset:512
	s_nop 0
	global_load_dwordx4 v[32:35], v[32:33], off offset:528
	s_cmp_gt_u32 s67, 5
	s_mov_b64 s[0:1], -1
	s_cbranch_scc0 .LBB0_326
	s_cmp_lg_u32 s67, 6
	v_lshl_add_u32 v158, s66, 8, v170
	s_cbranch_scc0 .LBB0_322
	v_ashrrev_i32_e32 v159, 31, v158
	v_lshl_add_u64 v[160:161], v[158:159], 2, s[12:13]
	global_load_dword v162, v[160:161], off
	global_load_dword v214, v[160:161], off offset:64
	global_load_dword v215, v[160:161], off offset:128
	global_load_dword v216, v[160:161], off offset:192
	global_load_dword v217, v[160:161], off offset:512
	global_load_dword v218, v[160:161], off offset:576
	global_load_dword v219, v[160:161], off offset:640
	global_load_dword v220, v[160:161], off offset:704
	v_lshl_add_u32 v176, s67, 7, v173
	s_mov_b64 s[0:1], 0
	s_waitcnt vmcnt(0) lgkmcnt(0)
	v_fmamk_f32 v162, v162, 0x3a800000, v224
	v_cmp_gt_f32_e32 vcc, s33, v162
	v_mul_f32_e32 v163, 0x4b800000, v162
	s_nop 0
	v_cndmask_b32_e32 v162, v162, v163, vcc
	v_rsq_f32_e32 v162, v162
	s_nop 0
	v_mul_f32_e32 v163, 0x45800000, v162
	v_cndmask_b32_e32 v164, v162, v163, vcc
	v_lshlrev_b64 v[162:163], 10, v[158:159]
	v_fma_f32 v159, v132, v164, v36
	v_mul_f32_e32 v159, 0xbfb8aa3b, v159
	v_exp_f32_e32 v159, v159
	v_pk_fma_f32 v[186:187], v[140:141], v[164:165], v[52:53] op_sel_hi:[1,0,1]
	v_pk_fma_f32 v[184:185], v[142:143], v[164:165], v[54:55] op_sel_hi:[1,0,1]
	v_add_f32_e32 v159, 1.0, v159
	v_rcp_f32_e32 v166, v159
	v_fma_f32 v159, v133, v164, v37
	v_mul_f32_e32 v159, 0xbfb8aa3b, v159
	v_exp_f32_e32 v159, v159
	s_nop 0
	v_add_f32_e32 v159, 1.0, v159
	v_rcp_f32_e32 v167, v159
	v_fma_f32 v159, v134, v164, v38
	v_mul_f32_e32 v159, 0xbfb8aa3b, v159
	v_exp_f32_e32 v159, v159
	s_nop 0
	v_add_f32_e32 v159, 1.0, v159
	v_rcp_f32_e32 v182, v159
	v_fma_f32 v159, v135, v164, v39
	v_mul_f32_e32 v159, 0xbfb8aa3b, v159
	v_exp_f32_e32 v159, v159
	s_nop 0
	v_add_f32_e32 v159, 1.0, v159
	v_rcp_f32_e32 v183, v159
	v_fma_f32 v159, v128, v164, v32
	v_mul_f32_e32 v159, 0xbfb8aa3b, v159
	v_exp_f32_e32 v159, v159
	v_pk_mul_f32 v[184:185], v[184:185], v[182:183]
	v_pk_mul_f32 v[182:183], v[186:187], v[166:167]
	v_lshl_add_u64 v[166:167], s[16:17], 0, v[162:163]
	v_lshlrev_b64 v[162:163], 2, v[176:177]
	v_lshl_add_u64 v[166:167], v[166:167], 0, v[162:163]
	v_add_f32_e32 v159, 1.0, v159
	global_store_dwordx4 v[166:167], v[182:185], off
	v_pk_fma_f32 v[186:187], v[136:137], v[164:165], v[48:49] op_sel_hi:[1,0,1]
	s_nop 0
	v_rcp_f32_e32 v182, v159
	v_fma_f32 v159, v129, v164, v33
	v_mul_f32_e32 v159, 0xbfb8aa3b, v159
	v_exp_f32_e32 v159, v159
	s_nop 0
	v_add_f32_e32 v159, 1.0, v159
	v_rcp_f32_e32 v183, v159
	v_fma_f32 v159, v130, v164, v34
	v_mul_f32_e32 v159, 0xbfb8aa3b, v159
	v_exp_f32_e32 v159, v159
	v_pk_mul_f32 v[182:183], v[186:187], v[182:183]
	v_add_f32_e32 v159, 1.0, v159
	v_rcp_f32_e32 v184, v159
	v_fma_f32 v159, v131, v164, v35
	v_mul_f32_e32 v159, 0xbfb8aa3b, v159
	v_exp_f32_e32 v159, v159
	v_pk_fma_f32 v[164:165], v[138:139], v[164:165], v[50:51] op_sel_hi:[1,0,1]
	v_add_f32_e32 v159, 1.0, v159
	v_rcp_f32_e32 v185, v159
	s_nop 0
	v_pk_mul_f32 v[184:185], v[164:165], v[184:185]
	global_store_dwordx4 v[166:167], v[182:185], off offset:16
	s_nop 1
	v_or_b32_e32 v164, 16, v158
	v_ashrrev_i32_e32 v165, 31, v164
	v_lshlrev_b64 v[164:165], 10, v[164:165]
	v_lshl_add_u64 v[164:165], s[16:17], 0, v[164:165]
	v_lshl_add_u64 v[164:165], v[164:165], 0, v[162:163]
	v_fmamk_f32 v159, v214, 0x3a800000, v224
	v_cmp_gt_f32_e32 vcc, s33, v159
	v_mul_f32_e32 v166, 0x4b800000, v159
	s_nop 0
	v_cndmask_b32_e32 v159, v159, v166, vcc
	v_rsq_f32_e32 v159, v159
	s_nop 0
	v_mul_f32_e32 v166, 0x45800000, v159
	v_cndmask_b32_e32 v166, v159, v166, vcc
	v_fma_f32 v159, v116, v166, v36
	v_mul_f32_e32 v159, 0xbfb8aa3b, v159
	v_exp_f32_e32 v159, v159
	v_pk_fma_f32 v[186:187], v[124:125], v[166:167], v[52:53] op_sel_hi:[1,0,1]
	v_pk_fma_f32 v[188:189], v[126:127], v[166:167], v[54:55] op_sel_hi:[1,0,1]
	v_add_f32_e32 v159, 1.0, v159
	v_rcp_f32_e32 v182, v159
	v_fma_f32 v159, v117, v166, v37
	v_mul_f32_e32 v159, 0xbfb8aa3b, v159
	v_exp_f32_e32 v159, v159
	s_nop 0
	v_add_f32_e32 v159, 1.0, v159
	v_rcp_f32_e32 v183, v159
	v_fma_f32 v159, v118, v166, v38
	v_mul_f32_e32 v159, 0xbfb8aa3b, v159
	v_exp_f32_e32 v159, v159
	v_pk_mul_f32 v[182:183], v[186:187], v[182:183]
	v_pk_fma_f32 v[186:187], v[120:121], v[166:167], v[48:49] op_sel_hi:[1,0,1]
	v_add_f32_e32 v159, 1.0, v159
	v_rcp_f32_e32 v184, v159
	v_fma_f32 v159, v119, v166, v39
	v_mul_f32_e32 v159, 0xbfb8aa3b, v159
	v_exp_f32_e32 v159, v159
	s_nop 0
	v_add_f32_e32 v159, 1.0, v159
	v_rcp_f32_e32 v185, v159
	v_fma_f32 v159, v112, v166, v32
	v_mul_f32_e32 v159, 0xbfb8aa3b, v159
	v_exp_f32_e32 v159, v159
	v_pk_mul_f32 v[184:185], v[188:189], v[184:185]
	global_store_dwordx4 v[164:165], v[182:185], off
	v_add_f32_e32 v159, 1.0, v159
	s_nop 0
	v_rcp_f32_e32 v182, v159
	v_fma_f32 v159, v113, v166, v33
	v_mul_f32_e32 v159, 0xbfb8aa3b, v159
	v_exp_f32_e32 v159, v159
	s_nop 0
	v_add_f32_e32 v159, 1.0, v159
	v_rcp_f32_e32 v183, v159
	v_fma_f32 v159, v114, v166, v34
	v_mul_f32_e32 v159, 0xbfb8aa3b, v159
	v_exp_f32_e32 v159, v159
	v_pk_mul_f32 v[182:183], v[186:187], v[182:183]
	v_add_f32_e32 v159, 1.0, v159
	v_rcp_f32_e32 v184, v159
; __device__ __forceinline__ float sigm(float v) { return __builtin_amdgcn_rcpf(1.f + __builtin_amdgcn_exp2f(-1.4426950408889634f * v)); }
;     __device__ __forceinline__ void operator()(const f32x4 (&acc)[2][2][4][2], const Unit& u, int wr, int wc, int fr, int fq) const {
;     ...
;         } else {
;             const int ch0 = 128 * (pn - 7) + 32 * wc + 8 * fq;
; #pragma unroll
;             for (int ai = 0; ai < 2; ++ai)
; #pragma unroll
;                 for (int m = 0; m < 4; ++m) {
;                     const int row = pm * 256 + ai * 128 + wr * 64 + m * 16 + fr;
;                     const float rinv = rsqrtf(rowsq[row] * (1.f / DM) + EPSN);
; #pragma unroll
;                     for (int n = 0; n < 2; ++n) {
;                         const f32x4 a = acc[ai][0][m][n] * rinv + bv[0][n], g = acc[ai][1][m][n] * rinv + bv[1][n];
;                         f32x4 o;
; #pragma unroll
;                         for (int j = 0; j < 4; ++j) o[j] = a[j] * sigm(g[j]);
;                         *(f32x4*)(uconv + (size_t)row * 256 + ch0 + 4 * n) = o;
;                     }
;                 }
	v_fma_f32 v159, v115, v166, v35
	v_mul_f32_e32 v159, 0xbfb8aa3b, v159
	v_exp_f32_e32 v159, v159
	v_pk_fma_f32 v[166:167], v[122:123], v[166:167], v[50:51] op_sel_hi:[1,0,1]
	v_add_f32_e32 v159, 1.0, v159
	v_rcp_f32_e32 v185, v159
	s_nop 0
	v_pk_mul_f32 v[184:185], v[166:167], v[184:185]
	global_store_dwordx4 v[164:165], v[182:185], off offset:16
	s_nop 1
	v_or_b32_e32 v164, 32, v158
	v_ashrrev_i32_e32 v165, 31, v164
	v_lshlrev_b64 v[164:165], 10, v[164:165]
	v_lshl_add_u64 v[164:165], s[16:17], 0, v[164:165]
	v_lshl_add_u64 v[164:165], v[164:165], 0, v[162:163]
	v_fmamk_f32 v159, v215, 0x3a800000, v224
	v_cmp_gt_f32_e32 vcc, s33, v159
	v_mul_f32_e32 v166, 0x4b800000, v159
	s_nop 0
	v_cndmask_b32_e32 v159, v159, v166, vcc
	v_rsq_f32_e32 v159, v159
	s_nop 0
	v_mul_f32_e32 v166, 0x45800000, v159
	v_cndmask_b32_e32 v166, v159, v166, vcc
	v_fma_f32 v159, v100, v166, v36
	v_mul_f32_e32 v159, 0xbfb8aa3b, v159
	v_exp_f32_e32 v159, v159
	v_pk_fma_f32 v[186:187], v[108:109], v[166:167], v[52:53] op_sel_hi:[1,0,1]
	v_pk_fma_f32 v[188:189], v[110:111], v[166:167], v[54:55] op_sel_hi:[1,0,1]
	v_add_f32_e32 v159, 1.0, v159
	v_rcp_f32_e32 v182, v159
	v_fma_f32 v159, v101, v166, v37
	v_mul_f32_e32 v159, 0xbfb8aa3b, v159
	v_exp_f32_e32 v159, v159
	s_nop 0
	v_add_f32_e32 v159, 1.0, v159
	v_rcp_f32_e32 v183, v159
	v_fma_f32 v159, v102, v166, v38
	v_mul_f32_e32 v159, 0xbfb8aa3b, v159
	v_exp_f32_e32 v159, v159
	v_pk_mul_f32 v[182:183], v[186:187], v[182:183]
	v_pk_fma_f32 v[186:187], v[104:105], v[166:167], v[48:49] op_sel_hi:[1,0,1]
	v_add_f32_e32 v159, 1.0, v159
	v_rcp_f32_e32 v184, v159
	v_fma_f32 v159, v103, v166, v39
	v_mul_f32_e32 v159, 0xbfb8aa3b, v159
	v_exp_f32_e32 v159, v159
	s_nop 0
	v_add_f32_e32 v159, 1.0, v159
	v_rcp_f32_e32 v185, v159
	v_fma_f32 v159, v96, v166, v32
	v_mul_f32_e32 v159, 0xbfb8aa3b, v159
	v_exp_f32_e32 v159, v159
	v_pk_mul_f32 v[184:185], v[188:189], v[184:185]
	global_store_dwordx4 v[164:165], v[182:185], off
	v_add_f32_e32 v159, 1.0, v159
	s_nop 0
	v_rcp_f32_e32 v182, v159
	v_fma_f32 v159, v97, v166, v33
	v_mul_f32_e32 v159, 0xbfb8aa3b, v159
	v_exp_f32_e32 v159, v159
	s_nop 0
	v_add_f32_e32 v159, 1.0, v159
	v_rcp_f32_e32 v183, v159
	v_fma_f32 v159, v98, v166, v34
	v_mul_f32_e32 v159, 0xbfb8aa3b, v159
	v_exp_f32_e32 v159, v159
	v_pk_mul_f32 v[182:183], v[186:187], v[182:183]
	v_add_f32_e32 v159, 1.0, v159
	v_rcp_f32_e32 v184, v159
	v_fma_f32 v159, v99, v166, v35
	v_mul_f32_e32 v159, 0xbfb8aa3b, v159
	v_exp_f32_e32 v159, v159
	v_pk_fma_f32 v[166:167], v[106:107], v[166:167], v[50:51] op_sel_hi:[1,0,1]
	v_add_f32_e32 v159, 1.0, v159
	v_rcp_f32_e32 v185, v159
	s_nop 0
	v_pk_mul_f32 v[184:185], v[166:167], v[184:185]
	global_store_dwordx4 v[164:165], v[182:185], off offset:16
	s_nop 1
	v_or_b32_e32 v164, 48, v158
	v_ashrrev_i32_e32 v165, 31, v164
	v_lshlrev_b64 v[164:165], 10, v[164:165]
	v_lshl_add_u64 v[164:165], s[16:17], 0, v[164:165]
	v_lshl_add_u64 v[164:165], v[164:165], 0, v[162:163]
	v_fmamk_f32 v159, v216, 0x3a800000, v224
	v_cmp_gt_f32_e32 vcc, s33, v159
	v_mul_f32_e32 v166, 0x4b800000, v159
	s_nop 0
	v_cndmask_b32_e32 v159, v159, v166, vcc
	v_rsq_f32_e32 v159, v159
	s_nop 0
	v_mul_f32_e32 v166, 0x45800000, v159
	v_cndmask_b32_e32 v166, v159, v166, vcc
	v_fma_f32 v159, v84, v166, v36
	v_mul_f32_e32 v159, 0xbfb8aa3b, v159
	v_exp_f32_e32 v159, v159
	v_pk_fma_f32 v[186:187], v[92:93], v[166:167], v[52:53] op_sel_hi:[1,0,1]
	v_pk_fma_f32 v[188:189], v[94:95], v[166:167], v[54:55] op_sel_hi:[1,0,1]
	v_add_f32_e32 v159, 1.0, v159
	v_rcp_f32_e32 v182, v159
	v_fma_f32 v159, v85, v166, v37
	v_mul_f32_e32 v159, 0xbfb8aa3b, v159
	v_exp_f32_e32 v159, v159
	s_nop 0
	v_add_f32_e32 v159, 1.0, v159
	v_rcp_f32_e32 v183, v159
	v_fma_f32 v159, v86, v166, v38
	v_mul_f32_e32 v159, 0xbfb8aa3b, v159
	v_exp_f32_e32 v159, v159
	v_pk_mul_f32 v[182:183], v[186:187], v[182:183]
	v_pk_fma_f32 v[186:187], v[88:89], v[166:167], v[48:49] op_sel_hi:[1,0,1]
	v_add_f32_e32 v159, 1.0, v159
	v_rcp_f32_e32 v184, v159
	v_fma_f32 v159, v87, v166, v39
	v_mul_f32_e32 v159, 0xbfb8aa3b, v159
	v_exp_f32_e32 v159, v159
	s_nop 0
	v_add_f32_e32 v159, 1.0, v159
	v_rcp_f32_e32 v185, v159
	v_fma_f32 v159, v80, v166, v32
	v_mul_f32_e32 v159, 0xbfb8aa3b, v159
	v_exp_f32_e32 v159, v159
	v_pk_mul_f32 v[184:185], v[188:189], v[184:185]
	global_store_dwordx4 v[164:165], v[182:185], off
	v_add_f32_e32 v159, 1.0, v159
	s_nop 0
	v_rcp_f32_e32 v182, v159
	v_fma_f32 v159, v81, v166, v33
	v_mul_f32_e32 v159, 0xbfb8aa3b, v159
	v_exp_f32_e32 v159, v159
	s_nop 0
	v_add_f32_e32 v159, 1.0, v159
	v_rcp_f32_e32 v183, v159
	v_fma_f32 v159, v82, v166, v34
	v_mul_f32_e32 v159, 0xbfb8aa3b, v159
	v_exp_f32_e32 v159, v159
	v_pk_mul_f32 v[182:183], v[186:187], v[182:183]
	v_add_f32_e32 v159, 1.0, v159
	v_rcp_f32_e32 v184, v159
	v_fma_f32 v159, v83, v166, v35
	v_mul_f32_e32 v159, 0xbfb8aa3b, v159
	v_exp_f32_e32 v159, v159
	v_pk_fma_f32 v[166:167], v[90:91], v[166:167], v[50:51] op_sel_hi:[1,0,1]
	v_add_f32_e32 v159, 1.0, v159
	v_rcp_f32_e32 v185, v159
	s_nop 0
	v_pk_mul_f32 v[184:185], v[166:167], v[184:185]
	global_store_dwordx4 v[164:165], v[182:185], off offset:16
	s_nop 1
	v_add_u32_e32 v164, 0x80, v158
	v_ashrrev_i32_e32 v165, 31, v164
	v_lshlrev_b64 v[164:165], 10, v[164:165]
	v_lshl_add_u64 v[164:165], s[16:17], 0, v[164:165]
	v_lshl_add_u64 v[164:165], v[164:165], 0, v[162:163]
	v_fmamk_f32 v159, v217, 0x3a800000, v224
	v_cmp_gt_f32_e32 vcc, s33, v159
	v_mul_f32_e32 v166, 0x4b800000, v159
	s_nop 0
	v_cndmask_b32_e32 v159, v159, v166, vcc
	v_rsq_f32_e32 v159, v159
	s_nop 0
	v_mul_f32_e32 v166, 0x45800000, v159
	v_cndmask_b32_e32 v166, v159, v166, vcc
	v_fma_f32 v159, v68, v166, v36
; __device__ __forceinline__ float sigm(float v) { return __builtin_amdgcn_rcpf(1.f + __builtin_amdgcn_exp2f(-1.4426950408889634f * v)); }
;     __device__ __forceinline__ void operator()(const f32x4 (&acc)[2][2][4][2], const Unit& u, int wr, int wc, int fr, int fq) const {
;     ...
;         } else {
;             const int ch0 = 128 * (pn - 7) + 32 * wc + 8 * fq;
; #pragma unroll
;             for (int ai = 0; ai < 2; ++ai)
; #pragma unroll
;                 for (int m = 0; m < 4; ++m) {
;                     const int row = pm * 256 + ai * 128 + wr * 64 + m * 16 + fr;
;                     const float rinv = rsqrtf(rowsq[row] * (1.f / DM) + EPSN);
; #pragma unroll
;                     for (int n = 0; n < 2; ++n) {
;                         const f32x4 a = acc[ai][0][m][n] * rinv + bv[0][n], g = acc[ai][1][m][n] * rinv + bv[1][n];
;                         f32x4 o;
; #pragma unroll
;                         for (int j = 0; j < 4; ++j) o[j] = a[j] * sigm(g[j]);
;                         *(f32x4*)(uconv + (size_t)row * 256 + ch0 + 4 * n) = o;
;                     }
;                 }
	v_mul_f32_e32 v159, 0xbfb8aa3b, v159
	v_exp_f32_e32 v159, v159
	v_pk_fma_f32 v[186:187], v[76:77], v[166:167], v[52:53] op_sel_hi:[1,0,1]
	v_pk_fma_f32 v[188:189], v[78:79], v[166:167], v[54:55] op_sel_hi:[1,0,1]
	v_add_f32_e32 v159, 1.0, v159
	v_rcp_f32_e32 v182, v159
	v_fma_f32 v159, v69, v166, v37
	v_mul_f32_e32 v159, 0xbfb8aa3b, v159
	v_exp_f32_e32 v159, v159
	s_nop 0
	v_add_f32_e32 v159, 1.0, v159
	v_rcp_f32_e32 v183, v159
	v_fma_f32 v159, v70, v166, v38
	v_mul_f32_e32 v159, 0xbfb8aa3b, v159
	v_exp_f32_e32 v159, v159
	v_pk_mul_f32 v[182:183], v[186:187], v[182:183]
	v_pk_fma_f32 v[186:187], v[72:73], v[166:167], v[48:49] op_sel_hi:[1,0,1]
	v_add_f32_e32 v159, 1.0, v159
	v_rcp_f32_e32 v184, v159
	v_fma_f32 v159, v71, v166, v39
	v_mul_f32_e32 v159, 0xbfb8aa3b, v159
	v_exp_f32_e32 v159, v159
	s_nop 0
	v_add_f32_e32 v159, 1.0, v159
	v_rcp_f32_e32 v185, v159
	v_fma_f32 v159, v64, v166, v32
	v_mul_f32_e32 v159, 0xbfb8aa3b, v159
	v_exp_f32_e32 v159, v159
	v_pk_mul_f32 v[184:185], v[188:189], v[184:185]
	global_store_dwordx4 v[164:165], v[182:185], off
	v_add_f32_e32 v159, 1.0, v159
	s_nop 0
	v_rcp_f32_e32 v182, v159
	v_fma_f32 v159, v65, v166, v33
	v_mul_f32_e32 v159, 0xbfb8aa3b, v159
	v_exp_f32_e32 v159, v159
	s_nop 0
	v_add_f32_e32 v159, 1.0, v159
	v_rcp_f32_e32 v183, v159
	v_fma_f32 v159, v66, v166, v34
	v_mul_f32_e32 v159, 0xbfb8aa3b, v159
	v_exp_f32_e32 v159, v159
	v_pk_mul_f32 v[182:183], v[186:187], v[182:183]
	v_add_f32_e32 v159, 1.0, v159
	v_rcp_f32_e32 v184, v159
	v_fma_f32 v159, v67, v166, v35
	v_mul_f32_e32 v159, 0xbfb8aa3b, v159
	v_exp_f32_e32 v159, v159
	v_pk_fma_f32 v[166:167], v[74:75], v[166:167], v[50:51] op_sel_hi:[1,0,1]
	v_add_f32_e32 v159, 1.0, v159
	v_rcp_f32_e32 v185, v159
	s_nop 0
	v_pk_mul_f32 v[184:185], v[166:167], v[184:185]
	global_store_dwordx4 v[164:165], v[182:185], off offset:16
	s_nop 1
	v_add_u32_e32 v164, 0x90, v158
	v_ashrrev_i32_e32 v165, 31, v164
	v_lshlrev_b64 v[164:165], 10, v[164:165]
	v_lshl_add_u64 v[164:165], s[16:17], 0, v[164:165]
	v_lshl_add_u64 v[164:165], v[164:165], 0, v[162:163]
	v_fmamk_f32 v159, v218, 0x3a800000, v224
	v_cmp_gt_f32_e32 vcc, s33, v159
	v_mul_f32_e32 v166, 0x4b800000, v159
	s_nop 0
	v_cndmask_b32_e32 v159, v159, v166, vcc
	v_rsq_f32_e32 v159, v159
	s_nop 0
	v_mul_f32_e32 v166, 0x45800000, v159
	v_cndmask_b32_e32 v166, v159, v166, vcc
	v_fma_f32 v159, v44, v166, v36
	v_mul_f32_e32 v159, 0xbfb8aa3b, v159
	v_exp_f32_e32 v159, v159
	v_pk_fma_f32 v[186:187], v[60:61], v[166:167], v[52:53] op_sel_hi:[1,0,1]
	v_pk_fma_f32 v[188:189], v[62:63], v[166:167], v[54:55] op_sel_hi:[1,0,1]
	v_add_f32_e32 v159, 1.0, v159
	v_rcp_f32_e32 v182, v159
	v_fma_f32 v159, v45, v166, v37
	v_mul_f32_e32 v159, 0xbfb8aa3b, v159
	v_exp_f32_e32 v159, v159
	s_nop 0
	v_add_f32_e32 v159, 1.0, v159
	v_rcp_f32_e32 v183, v159
	v_fma_f32 v159, v46, v166, v38
	v_mul_f32_e32 v159, 0xbfb8aa3b, v159
	v_exp_f32_e32 v159, v159
	v_pk_mul_f32 v[182:183], v[186:187], v[182:183]
	v_pk_fma_f32 v[186:187], v[56:57], v[166:167], v[48:49] op_sel_hi:[1,0,1]
	v_add_f32_e32 v159, 1.0, v159
	v_rcp_f32_e32 v184, v159
	v_fma_f32 v159, v47, v166, v39
	v_mul_f32_e32 v159, 0xbfb8aa3b, v159
	v_exp_f32_e32 v159, v159
	s_nop 0
	v_add_f32_e32 v159, 1.0, v159
	v_rcp_f32_e32 v185, v159
	v_fma_f32 v159, v40, v166, v32
	v_mul_f32_e32 v159, 0xbfb8aa3b, v159
	v_exp_f32_e32 v159, v159
	v_pk_mul_f32 v[184:185], v[188:189], v[184:185]
	global_store_dwordx4 v[164:165], v[182:185], off
	v_add_f32_e32 v159, 1.0, v159
	s_nop 0
	v_rcp_f32_e32 v182, v159
	v_fma_f32 v159, v41, v166, v33
	v_mul_f32_e32 v159, 0xbfb8aa3b, v159
	v_exp_f32_e32 v159, v159
	s_nop 0
	v_add_f32_e32 v159, 1.0, v159
	v_rcp_f32_e32 v183, v159
	v_fma_f32 v159, v42, v166, v34
	v_mul_f32_e32 v159, 0xbfb8aa3b, v159
	v_exp_f32_e32 v159, v159
	v_pk_mul_f32 v[182:183], v[186:187], v[182:183]
	v_add_f32_e32 v159, 1.0, v159
	v_rcp_f32_e32 v184, v159
	v_fma_f32 v159, v43, v166, v35
	v_mul_f32_e32 v159, 0xbfb8aa3b, v159
	v_exp_f32_e32 v159, v159
	v_pk_fma_f32 v[166:167], v[58:59], v[166:167], v[50:51] op_sel_hi:[1,0,1]
	v_add_f32_e32 v159, 1.0, v159
	v_rcp_f32_e32 v185, v159
	s_nop 0
	v_pk_mul_f32 v[184:185], v[166:167], v[184:185]
	global_store_dwordx4 v[164:165], v[182:185], off offset:16
	s_nop 1
	v_add_u32_e32 v164, 0xa0, v158
	v_ashrrev_i32_e32 v165, 31, v164
	v_lshlrev_b64 v[164:165], 10, v[164:165]
	v_lshl_add_u64 v[164:165], s[16:17], 0, v[164:165]
	v_lshl_add_u64 v[164:165], v[164:165], 0, v[162:163]
	v_fmamk_f32 v159, v219, 0x3a800000, v224
	v_cmp_gt_f32_e32 vcc, s33, v159
	v_mul_f32_e32 v166, 0x4b800000, v159
	s_nop 0
	v_cndmask_b32_e32 v159, v159, v166, vcc
	v_rsq_f32_e32 v159, v159
	s_nop 0
	v_mul_f32_e32 v166, 0x45800000, v159
	v_cndmask_b32_e32 v166, v159, v166, vcc
	v_fma_f32 v159, v20, v166, v36
	v_mul_f32_e32 v159, 0xbfb8aa3b, v159
	v_exp_f32_e32 v159, v159
	v_pk_fma_f32 v[186:187], v[28:29], v[166:167], v[52:53] op_sel_hi:[1,0,1]
	v_pk_fma_f32 v[188:189], v[30:31], v[166:167], v[54:55] op_sel_hi:[1,0,1]
	v_add_f32_e32 v159, 1.0, v159
	v_rcp_f32_e32 v182, v159
	v_fma_f32 v159, v21, v166, v37
	v_mul_f32_e32 v159, 0xbfb8aa3b, v159
	v_exp_f32_e32 v159, v159
	s_nop 0
	v_add_f32_e32 v159, 1.0, v159
	v_rcp_f32_e32 v183, v159
	v_fma_f32 v159, v22, v166, v38
	v_mul_f32_e32 v159, 0xbfb8aa3b, v159
	v_exp_f32_e32 v159, v159
	v_pk_mul_f32 v[182:183], v[186:187], v[182:183]
	v_pk_fma_f32 v[186:187], v[24:25], v[166:167], v[48:49] op_sel_hi:[1,0,1]
	v_add_f32_e32 v159, 1.0, v159
	v_rcp_f32_e32 v184, v159
	v_fma_f32 v159, v23, v166, v39
	v_mul_f32_e32 v159, 0xbfb8aa3b, v159
	v_exp_f32_e32 v159, v159
	s_nop 0
	v_add_f32_e32 v159, 1.0, v159
	v_rcp_f32_e32 v185, v159
	v_fma_f32 v159, v16, v166, v32
; __device__ __forceinline__ float sigm(float v) { return __builtin_amdgcn_rcpf(1.f + __builtin_amdgcn_exp2f(-1.4426950408889634f * v)); }
;     __device__ __forceinline__ void operator()(const f32x4 (&acc)[2][2][4][2], const Unit& u, int wr, int wc, int fr, int fq) const {
;     ...
;         } else if (pn == 6) {
; #pragma unroll
;             for (int ai = 0; ai < 2; ++ai)
; #pragma unroll
;                 for (int m = 0; m < 4; ++m) {
;                     const int row = pm * 256 + ai * 128 + wr * 64 + m * 16 + fr;
;                     const float rinv = rsqrtf(rowsq[row] * (1.f / DM) + EPSN);
; #pragma unroll
;                     for (int bj = 0; bj < 2; ++bj)
; #pragma unroll
;                         for (int n = 0; n < 2; ++n) *(f32x4*)(upool + (size_t)row * 256 + 128 * bj + 32 * wc + 8 * fq + 4 * n) = acc[ai][bj][m][n] * rinv + bv[bj][n];
;                 }
;         } else {
;             const int ch0 = 128 * (pn - 7) + 32 * wc + 8 * fq;
; #pragma unroll
;             for (int ai = 0; ai < 2; ++ai)
; #pragma unroll
;                 for (int m = 0; m < 4; ++m) {
;                     const int row = pm * 256 + ai * 128 + wr * 64 + m * 16 + fr;
;                     const float rinv = rsqrtf(rowsq[row] * (1.f / DM) + EPSN);
; #pragma unroll
;                     for (int n = 0; n < 2; ++n) {
;                         const f32x4 a = acc[ai][0][m][n] * rinv + bv[0][n], g = acc[ai][1][m][n] * rinv + bv[1][n];
;                         f32x4 o;
; #pragma unroll
;                         for (int j = 0; j < 4; ++j) o[j] = a[j] * sigm(g[j]);
;                         *(f32x4*)(uconv + (size_t)row * 256 + ch0 + 4 * n) = o;
;                     }
;                 }
	v_mul_f32_e32 v159, 0xbfb8aa3b, v159
	v_exp_f32_e32 v159, v159
	v_pk_mul_f32 v[184:185], v[188:189], v[184:185]
	global_store_dwordx4 v[164:165], v[182:185], off
	v_add_f32_e32 v159, 1.0, v159
	s_nop 0
	v_rcp_f32_e32 v182, v159
	v_fma_f32 v159, v17, v166, v33
	v_mul_f32_e32 v159, 0xbfb8aa3b, v159
	v_exp_f32_e32 v159, v159
	s_nop 0
	v_add_f32_e32 v159, 1.0, v159
	v_rcp_f32_e32 v183, v159
	v_fma_f32 v159, v18, v166, v34
	v_mul_f32_e32 v159, 0xbfb8aa3b, v159
	v_exp_f32_e32 v159, v159
	v_pk_mul_f32 v[182:183], v[186:187], v[182:183]
	v_add_f32_e32 v159, 1.0, v159
	v_rcp_f32_e32 v184, v159
	v_fma_f32 v159, v19, v166, v35
	v_mul_f32_e32 v159, 0xbfb8aa3b, v159
	v_exp_f32_e32 v159, v159
	v_pk_fma_f32 v[166:167], v[26:27], v[166:167], v[50:51] op_sel_hi:[1,0,1]
	v_add_f32_e32 v159, 1.0, v159
	v_rcp_f32_e32 v185, v159
	s_nop 0
	v_pk_mul_f32 v[184:185], v[166:167], v[184:185]
	global_store_dwordx4 v[164:165], v[182:185], off offset:16
	s_nop 1
	v_add_u32_e32 v166, 0xb0, v158
	v_ashrrev_i32_e32 v167, 31, v166
	v_fmamk_f32 v159, v220, 0x3a800000, v224
	v_cmp_gt_f32_e32 vcc, s33, v159
	v_mul_f32_e32 v160, 0x4b800000, v159
	s_nop 0
	v_cndmask_b32_e32 v159, v159, v160, vcc
	v_rsq_f32_e32 v159, v159
	s_nop 0
	v_mul_f32_e32 v160, 0x45800000, v159
	v_cndmask_b32_e32 v164, v159, v160, vcc
	v_fma_f32 v159, v4, v164, v36
	v_mul_f32_e32 v159, 0xbfb8aa3b, v159
	v_exp_f32_e32 v159, v159
	v_lshlrev_b64 v[160:161], 10, v[166:167]
	v_lshl_add_u64 v[160:161], s[16:17], 0, v[160:161]
	v_lshl_add_u64 v[160:161], v[160:161], 0, v[162:163]
	v_add_f32_e32 v159, 1.0, v159
	v_rcp_f32_e32 v166, v159
	v_fma_f32 v159, v5, v164, v37
	v_mul_f32_e32 v159, 0xbfb8aa3b, v159
	v_exp_f32_e32 v159, v159
	v_pk_fma_f32 v[186:187], v[12:13], v[164:165], v[52:53] op_sel_hi:[1,0,1]
	v_pk_fma_f32 v[184:185], v[14:15], v[164:165], v[54:55] op_sel_hi:[1,0,1]
	v_add_f32_e32 v159, 1.0, v159
	v_rcp_f32_e32 v167, v159
	v_fma_f32 v159, v6, v164, v38
	v_mul_f32_e32 v159, 0xbfb8aa3b, v159
	v_exp_f32_e32 v159, v159
	s_nop 0
	v_add_f32_e32 v159, 1.0, v159
	v_rcp_f32_e32 v182, v159
	v_fma_f32 v159, v7, v164, v39
	v_mul_f32_e32 v159, 0xbfb8aa3b, v159
	v_exp_f32_e32 v159, v159
	s_nop 0
	v_add_f32_e32 v159, 1.0, v159
	v_rcp_f32_e32 v183, v159
	v_fma_f32 v159, v0, v164, v32
	v_mul_f32_e32 v159, 0xbfb8aa3b, v159
	v_exp_f32_e32 v159, v159
	v_pk_mul_f32 v[184:185], v[184:185], v[182:183]
	v_pk_mul_f32 v[182:183], v[186:187], v[166:167]
	global_store_dwordx4 v[160:161], v[182:185], off
	v_add_f32_e32 v159, 1.0, v159
	v_rcp_f32_e32 v162, v159
	v_fma_f32 v159, v1, v164, v33
	v_mul_f32_e32 v159, 0xbfb8aa3b, v159
	v_exp_f32_e32 v159, v159
	v_pk_fma_f32 v[182:183], v[8:9], v[164:165], v[48:49] op_sel_hi:[1,0,1]
	v_add_f32_e32 v159, 1.0, v159
	v_rcp_f32_e32 v163, v159
	v_fma_f32 v159, v2, v164, v34
	v_mul_f32_e32 v159, 0xbfb8aa3b, v159
	v_exp_f32_e32 v159, v159
	v_pk_mul_f32 v[162:163], v[182:183], v[162:163]
	v_add_f32_e32 v159, 1.0, v159
	v_rcp_f32_e32 v166, v159
	v_fma_f32 v159, v3, v164, v35
	v_mul_f32_e32 v159, 0xbfb8aa3b, v159
	v_exp_f32_e32 v159, v159
	v_pk_fma_f32 v[164:165], v[10:11], v[164:165], v[50:51] op_sel_hi:[1,0,1]
	v_add_f32_e32 v159, 1.0, v159
	v_rcp_f32_e32 v167, v159
	s_nop 0
	v_pk_mul_f32 v[164:165], v[164:165], v[166:167]
	global_store_dwordx4 v[160:161], v[162:165], off offset:16
.LBB0_322:
	s_andn2_b64 vcc, exec, s[0:1]
	s_cbranch_vccnz .LBB0_324
	v_ashrrev_i32_e32 v159, 31, v158
	v_lshl_add_u64 v[160:161], v[158:159], 2, s[12:13]
	global_load_dword v162, v[160:161], off
	global_load_dword v214, v[160:161], off offset:64
	global_load_dword v215, v[160:161], off offset:128
	global_load_dword v216, v[160:161], off offset:192
	global_load_dword v217, v[160:161], off offset:512
	global_load_dword v218, v[160:161], off offset:576
	global_load_dword v219, v[160:161], off offset:640
	v_lshlrev_b64 v[182:183], 10, v[158:159]
	v_lshl_add_u64 v[182:183], v[152:153], 0, v[182:183]
	s_waitcnt vmcnt(0) lgkmcnt(0)
	v_fmamk_f32 v162, v162, 0x3a800000, v224
	v_cmp_gt_f32_e32 vcc, s33, v162
	v_mul_f32_e32 v163, 0x4b800000, v162
	s_nop 0
	v_cndmask_b32_e32 v162, v162, v163, vcc
	v_rsq_f32_e32 v162, v162
	s_nop 0
	v_mul_f32_e32 v163, 0x45800000, v162
	v_cndmask_b32_e32 v166, v162, v163, vcc
	v_pk_fma_f32 v[164:165], v[142:143], v[166:167], v[54:55] op_sel_hi:[1,0,1]
	v_pk_fma_f32 v[162:163], v[140:141], v[166:167], v[52:53] op_sel_hi:[1,0,1]
	global_store_dwordx4 v[182:183], v[162:165], off
	s_nop 1
	v_pk_fma_f32 v[164:165], v[138:139], v[166:167], v[50:51] op_sel_hi:[1,0,1]
	v_pk_fma_f32 v[162:163], v[136:137], v[166:167], v[48:49] op_sel_hi:[1,0,1]
	global_store_dwordx4 v[182:183], v[162:165], off offset:16
	s_nop 1
	v_pk_fma_f32 v[164:165], v[134:135], v[166:167], v[38:39] op_sel_hi:[1,0,1]
	v_pk_fma_f32 v[162:163], v[132:133], v[166:167], v[36:37] op_sel_hi:[1,0,1]
	global_store_dwordx4 v[182:183], v[162:165], off offset:512
	s_nop 1
	v_pk_fma_f32 v[164:165], v[130:131], v[166:167], v[34:35] op_sel_hi:[1,0,1]
	v_pk_fma_f32 v[162:163], v[128:129], v[166:167], v[32:33] op_sel_hi:[1,0,1]
	global_store_dwordx4 v[182:183], v[162:165], off offset:528
	s_nop 1
	v_fmamk_f32 v159, v214, 0x3a800000, v224
	v_cmp_gt_f32_e32 vcc, s33, v159
	v_mul_f32_e32 v164, 0x4b800000, v159
	v_or_b32_e32 v162, 16, v158
	v_cndmask_b32_e32 v159, v159, v164, vcc
	v_rsq_f32_e32 v159, v159
	v_ashrrev_i32_e32 v163, 31, v162
	v_lshlrev_b64 v[182:183], 10, v[162:163]
	v_lshl_add_u64 v[182:183], v[152:153], 0, v[182:183]
	v_mul_f32_e32 v164, 0x45800000, v159
	v_cndmask_b32_e32 v166, v159, v164, vcc
	v_pk_fma_f32 v[164:165], v[126:127], v[166:167], v[54:55] op_sel_hi:[1,0,1]
	v_pk_fma_f32 v[162:163], v[124:125], v[166:167], v[52:53] op_sel_hi:[1,0,1]
;     __device__ __forceinline__ void operator()(const f32x4 (&acc)[2][2][4][2], const Unit& u, int wr, int wc, int fr, int fq) const {
;     ...
;         } else if (pn == 6) {
; #pragma unroll
;             for (int ai = 0; ai < 2; ++ai)
; #pragma unroll
;                 for (int m = 0; m < 4; ++m) {
;                     const int row = pm * 256 + ai * 128 + wr * 64 + m * 16 + fr;
;                     const float rinv = rsqrtf(rowsq[row] * (1.f / DM) + EPSN);
; #pragma unroll
;                     for (int bj = 0; bj < 2; ++bj)
; #pragma unroll
;                         for (int n = 0; n < 2; ++n) *(f32x4*)(upool + (size_t)row * 256 + 128 * bj + 32 * wc + 8 * fq + 4 * n) = acc[ai][bj][m][n] * rinv + bv[bj][n];
;                 }
	global_store_dwordx4 v[182:183], v[162:165], off
	s_nop 1
	v_pk_fma_f32 v[164:165], v[122:123], v[166:167], v[50:51] op_sel_hi:[1,0,1]
	v_pk_fma_f32 v[162:163], v[120:121], v[166:167], v[48:49] op_sel_hi:[1,0,1]
	global_store_dwordx4 v[182:183], v[162:165], off offset:16
	s_nop 1
	v_pk_fma_f32 v[164:165], v[118:119], v[166:167], v[38:39] op_sel_hi:[1,0,1]
	v_pk_fma_f32 v[162:163], v[116:117], v[166:167], v[36:37] op_sel_hi:[1,0,1]
	global_store_dwordx4 v[182:183], v[162:165], off offset:512
	s_nop 1
	v_pk_fma_f32 v[164:165], v[114:115], v[166:167], v[34:35] op_sel_hi:[1,0,1]
	v_pk_fma_f32 v[162:163], v[112:113], v[166:167], v[32:33] op_sel_hi:[1,0,1]
	global_store_dwordx4 v[182:183], v[162:165], off offset:528
	s_nop 1
	v_fmamk_f32 v159, v215, 0x3a800000, v224
	v_cmp_gt_f32_e32 vcc, s33, v159
	v_mul_f32_e32 v164, 0x4b800000, v159
	v_or_b32_e32 v162, 32, v158
	v_cndmask_b32_e32 v159, v159, v164, vcc
	v_rsq_f32_e32 v159, v159
	v_ashrrev_i32_e32 v163, 31, v162
	v_lshlrev_b64 v[182:183], 10, v[162:163]
	v_lshl_add_u64 v[182:183], v[152:153], 0, v[182:183]
	v_mul_f32_e32 v164, 0x45800000, v159
	v_cndmask_b32_e32 v166, v159, v164, vcc
	v_pk_fma_f32 v[164:165], v[110:111], v[166:167], v[54:55] op_sel_hi:[1,0,1]
	v_pk_fma_f32 v[162:163], v[108:109], v[166:167], v[52:53] op_sel_hi:[1,0,1]
	global_store_dwordx4 v[182:183], v[162:165], off
	s_nop 1
	v_pk_fma_f32 v[164:165], v[106:107], v[166:167], v[50:51] op_sel_hi:[1,0,1]
	v_pk_fma_f32 v[162:163], v[104:105], v[166:167], v[48:49] op_sel_hi:[1,0,1]
	global_store_dwordx4 v[182:183], v[162:165], off offset:16
	s_nop 1
	v_pk_fma_f32 v[164:165], v[102:103], v[166:167], v[38:39] op_sel_hi:[1,0,1]
	v_pk_fma_f32 v[162:163], v[100:101], v[166:167], v[36:37] op_sel_hi:[1,0,1]
	global_store_dwordx4 v[182:183], v[162:165], off offset:512
	s_nop 1
	v_pk_fma_f32 v[164:165], v[98:99], v[166:167], v[34:35] op_sel_hi:[1,0,1]
	v_pk_fma_f32 v[162:163], v[96:97], v[166:167], v[32:33] op_sel_hi:[1,0,1]
	global_store_dwordx4 v[182:183], v[162:165], off offset:528
	s_nop 1
	v_fmamk_f32 v159, v216, 0x3a800000, v224
	v_cmp_gt_f32_e32 vcc, s33, v159
	v_mul_f32_e32 v164, 0x4b800000, v159
	v_or_b32_e32 v162, 48, v158
	v_cndmask_b32_e32 v159, v159, v164, vcc
	v_rsq_f32_e32 v159, v159
	v_ashrrev_i32_e32 v163, 31, v162
	v_lshlrev_b64 v[182:183], 10, v[162:163]
	v_lshl_add_u64 v[182:183], v[152:153], 0, v[182:183]
	v_mul_f32_e32 v164, 0x45800000, v159
	v_cndmask_b32_e32 v166, v159, v164, vcc
	v_pk_fma_f32 v[164:165], v[94:95], v[166:167], v[54:55] op_sel_hi:[1,0,1]
	v_pk_fma_f32 v[162:163], v[92:93], v[166:167], v[52:53] op_sel_hi:[1,0,1]
	global_store_dwordx4 v[182:183], v[162:165], off
	s_nop 1
	v_pk_fma_f32 v[164:165], v[90:91], v[166:167], v[50:51] op_sel_hi:[1,0,1]
	v_pk_fma_f32 v[162:163], v[88:89], v[166:167], v[48:49] op_sel_hi:[1,0,1]
	global_store_dwordx4 v[182:183], v[162:165], off offset:16
	s_nop 1
	v_pk_fma_f32 v[164:165], v[86:87], v[166:167], v[38:39] op_sel_hi:[1,0,1]
	v_pk_fma_f32 v[162:163], v[84:85], v[166:167], v[36:37] op_sel_hi:[1,0,1]
	global_store_dwordx4 v[182:183], v[162:165], off offset:512
	s_nop 1
	v_pk_fma_f32 v[164:165], v[82:83], v[166:167], v[34:35] op_sel_hi:[1,0,1]
	v_pk_fma_f32 v[162:163], v[80:81], v[166:167], v[32:33] op_sel_hi:[1,0,1]
	global_store_dwordx4 v[182:183], v[162:165], off offset:528
	s_nop 1
	v_fmamk_f32 v159, v217, 0x3a800000, v224
	v_cmp_gt_f32_e32 vcc, s33, v159
	v_mul_f32_e32 v164, 0x4b800000, v159
	v_add_u32_e32 v162, 0x80, v158
	v_cndmask_b32_e32 v159, v159, v164, vcc
	v_rsq_f32_e32 v159, v159
	v_ashrrev_i32_e32 v163, 31, v162
	v_lshlrev_b64 v[182:183], 10, v[162:163]
	v_lshl_add_u64 v[182:183], v[152:153], 0, v[182:183]
	v_mul_f32_e32 v164, 0x45800000, v159
	v_cndmask_b32_e32 v166, v159, v164, vcc
	v_pk_fma_f32 v[164:165], v[78:79], v[166:167], v[54:55] op_sel_hi:[1,0,1]
	v_pk_fma_f32 v[162:163], v[76:77], v[166:167], v[52:53] op_sel_hi:[1,0,1]
	global_store_dwordx4 v[182:183], v[162:165], off
	s_nop 1
	v_pk_fma_f32 v[164:165], v[74:75], v[166:167], v[50:51] op_sel_hi:[1,0,1]
	v_pk_fma_f32 v[162:163], v[72:73], v[166:167], v[48:49] op_sel_hi:[1,0,1]
	global_store_dwordx4 v[182:183], v[162:165], off offset:16
	s_nop 1
	v_pk_fma_f32 v[164:165], v[70:71], v[166:167], v[38:39] op_sel_hi:[1,0,1]
;     __device__ __forceinline__ void operator()(const f32x4 (&acc)[2][2][4][2], const Unit& u, int wr, int wc, int fr, int fq) const {
;     ...
;         } else if (pn == 6) {
; #pragma unroll
;             for (int ai = 0; ai < 2; ++ai)
; #pragma unroll
;                 for (int m = 0; m < 4; ++m) {
;                     const int row = pm * 256 + ai * 128 + wr * 64 + m * 16 + fr;
;                     const float rinv = rsqrtf(rowsq[row] * (1.f / DM) + EPSN);
; #pragma unroll
;                     for (int bj = 0; bj < 2; ++bj)
; #pragma unroll
;                         for (int n = 0; n < 2; ++n) *(f32x4*)(upool + (size_t)row * 256 + 128 * bj + 32 * wc + 8 * fq + 4 * n) = acc[ai][bj][m][n] * rinv + bv[bj][n];
;                 }
	v_pk_fma_f32 v[162:163], v[68:69], v[166:167], v[36:37] op_sel_hi:[1,0,1]
	global_store_dwordx4 v[182:183], v[162:165], off offset:512
	s_nop 1
	v_pk_fma_f32 v[164:165], v[66:67], v[166:167], v[34:35] op_sel_hi:[1,0,1]
	v_pk_fma_f32 v[162:163], v[64:65], v[166:167], v[32:33] op_sel_hi:[1,0,1]
	global_store_dwordx4 v[182:183], v[162:165], off offset:528
	s_nop 1
	v_fmamk_f32 v159, v218, 0x3a800000, v224
	v_cmp_gt_f32_e32 vcc, s33, v159
	v_mul_f32_e32 v164, 0x4b800000, v159
	v_add_u32_e32 v162, 0x90, v158
	v_cndmask_b32_e32 v159, v159, v164, vcc
	v_rsq_f32_e32 v159, v159
	v_ashrrev_i32_e32 v163, 31, v162
	v_lshlrev_b64 v[182:183], 10, v[162:163]
	v_lshl_add_u64 v[182:183], v[152:153], 0, v[182:183]
	v_mul_f32_e32 v164, 0x45800000, v159
	v_cndmask_b32_e32 v166, v159, v164, vcc
	v_pk_fma_f32 v[164:165], v[62:63], v[166:167], v[54:55] op_sel_hi:[1,0,1]
	v_pk_fma_f32 v[162:163], v[60:61], v[166:167], v[52:53] op_sel_hi:[1,0,1]
	global_store_dwordx4 v[182:183], v[162:165], off
	s_nop 1
	v_pk_fma_f32 v[164:165], v[58:59], v[166:167], v[50:51] op_sel_hi:[1,0,1]
	v_pk_fma_f32 v[162:163], v[56:57], v[166:167], v[48:49] op_sel_hi:[1,0,1]
	global_store_dwordx4 v[182:183], v[162:165], off offset:16
	s_nop 1
	v_pk_fma_f32 v[164:165], v[46:47], v[166:167], v[38:39] op_sel_hi:[1,0,1]
	v_pk_fma_f32 v[162:163], v[44:45], v[166:167], v[36:37] op_sel_hi:[1,0,1]
	global_store_dwordx4 v[182:183], v[162:165], off offset:512
	s_nop 1
	v_pk_fma_f32 v[164:165], v[42:43], v[166:167], v[34:35] op_sel_hi:[1,0,1]
	v_pk_fma_f32 v[162:163], v[40:41], v[166:167], v[32:33] op_sel_hi:[1,0,1]
	global_store_dwordx4 v[182:183], v[162:165], off offset:528
	s_nop 1
	v_fmamk_f32 v159, v219, 0x3a800000, v224
	v_cmp_gt_f32_e32 vcc, s33, v159
	v_mul_f32_e32 v164, 0x4b800000, v159
	v_add_u32_e32 v162, 0xa0, v158
	v_cndmask_b32_e32 v159, v159, v164, vcc
	v_rsq_f32_e32 v159, v159
	v_ashrrev_i32_e32 v163, 31, v162
	v_lshlrev_b64 v[182:183], 10, v[162:163]
	v_lshl_add_u64 v[182:183], v[152:153], 0, v[182:183]
	v_mul_f32_e32 v164, 0x45800000, v159
	v_cndmask_b32_e32 v166, v159, v164, vcc
	v_pk_fma_f32 v[164:165], v[30:31], v[166:167], v[54:55] op_sel_hi:[1,0,1]
	v_pk_fma_f32 v[162:163], v[28:29], v[166:167], v[52:53] op_sel_hi:[1,0,1]
	global_store_dwordx4 v[182:183], v[162:165], off
	v_add_u32_e32 v158, 0xb0, v158
	v_ashrrev_i32_e32 v159, 31, v158
	v_pk_fma_f32 v[164:165], v[26:27], v[166:167], v[50:51] op_sel_hi:[1,0,1]
	v_pk_fma_f32 v[162:163], v[24:25], v[166:167], v[48:49] op_sel_hi:[1,0,1]
	global_store_dwordx4 v[182:183], v[162:165], off offset:16
	s_nop 1
	v_pk_fma_f32 v[164:165], v[22:23], v[166:167], v[38:39] op_sel_hi:[1,0,1]
	v_pk_fma_f32 v[162:163], v[20:21], v[166:167], v[36:37] op_sel_hi:[1,0,1]
	global_store_dwordx4 v[182:183], v[162:165], off offset:512
	s_nop 1
	v_pk_fma_f32 v[164:165], v[18:19], v[166:167], v[34:35] op_sel_hi:[1,0,1]
	v_pk_fma_f32 v[162:163], v[16:17], v[166:167], v[32:33] op_sel_hi:[1,0,1]
	global_store_dwordx4 v[182:183], v[162:165], off offset:528
	global_load_dword v160, v[160:161], off offset:704
	s_waitcnt vmcnt(0) lgkmcnt(0)
	v_fmamk_f32 v160, v160, 0x3a800000, v224
	v_cmp_gt_f32_e32 vcc, s33, v160
	v_mul_f32_e32 v161, 0x4b800000, v160
	v_lshlrev_b64 v[164:165], 10, v[158:159]
	v_cndmask_b32_e32 v160, v160, v161, vcc
	v_rsq_f32_e32 v160, v160
	v_lshl_add_u64 v[164:165], v[152:153], 0, v[164:165]
	v_mul_f32_e32 v161, 0x45800000, v160
	v_cndmask_b32_e32 v162, v160, v161, vcc
	v_pk_fma_f32 v[160:161], v[14:15], v[162:163], v[54:55] op_sel_hi:[1,0,1]
	v_pk_fma_f32 v[158:159], v[12:13], v[162:163], v[52:53] op_sel_hi:[1,0,1]
	global_store_dwordx4 v[164:165], v[158:161], off
	s_nop 1
	v_pk_fma_f32 v[160:161], v[10:11], v[162:163], v[50:51] op_sel_hi:[1,0,1]
	v_pk_fma_f32 v[158:159], v[8:9], v[162:163], v[48:49] op_sel_hi:[1,0,1]
	global_store_dwordx4 v[164:165], v[158:161], off offset:16
	s_nop 1
	v_pk_fma_f32 v[160:161], v[6:7], v[162:163], v[38:39] op_sel_hi:[1,0,1]
	v_pk_fma_f32 v[158:159], v[4:5], v[162:163], v[36:37] op_sel_hi:[1,0,1]
	global_store_dwordx4 v[164:165], v[158:161], off offset:512
	s_nop 1
	v_pk_fma_f32 v[160:161], v[2:3], v[162:163], v[34:35] op_sel_hi:[1,0,1]
	v_pk_fma_f32 v[158:159], v[0:1], v[162:163], v[32:33] op_sel_hi:[1,0,1]
	global_store_dwordx4 v[164:165], v[158:161], off offset:528

; __device__ __forceinline__ unsigned pkbf(float lo, float hi) { return pg8::cvt_pk_bf16(lo, hi); }
;     __device__ __forceinline__ void operator()(const f32x4 (&acc)[2][2][4][2], const Unit& u, int wr, int wc, int fr, int fq) const {
;     ...
;         } else if (pn < 6) {
; #pragma unroll
;             for (int ai = 0; ai < 2; ++ai)
; #pragma unroll
;                 for (int m = 0; m < 4; ++m) {
;                     const int row = pm * 256 + ai * 128 + wr * 64 + m * 16 + fr;
;                     const float rinv = rsqrtf(rowsq[row] * (1.f / DM) + EPSN);
;                     int b, kidx;
;                     if (isctx) { const int rc = row - MLAT; b = rc >> 8; kidx = rc & 255; } else { b = row >> 13; kidx = CTXL + (row & (SEQ - 1)); }
; #pragma unroll
;                     for (int bj = 0; bj < 2; ++bj) {
;                         const f32x4 y0 = acc[ai][bj][m][0] * rinv + bv[bj][0], y1 = acc[ai][bj][m][1] * rinv + bv[bj][1];
;                         u32x4 w; w.x = pkbf(y0[0], y0[1]); w.y = pkbf(y0[2], y0[3]); w.z = pkbf(y1[0], y1[1]); w.w = pkbf(y1[2], y1[3]);
;                         const int head = 2 * (pn - 4) + bj;
;                         const size_t off = (size_t)(b * 4 + head) * (LK * 128) + (size_t)(kidx >> 6) * 8192 + (size_t)(voff(kidx & 63, 4 * wc + fq) >> 1);
;                         *(u32x4*)(Vb + off) = w;
;                     }
;                 }
.LBB0_327:
	s_lshl_b32 s0, s66, 8
	s_add_i32 s14, s0, s49
	v_or_b32_e32 v158, s14, v169
	v_ashrrev_i32_e32 v159, 31, v158
	v_lshl_add_u64 v[160:161], v[158:159], 2, s[12:13]
	global_load_dword v159, v[160:161], off
	s_add_i32 s0, s14, 0xffffc000
	s_ashr_i32 s30, s0, 8
	s_add_i32 s0, s14, 0xffffc080
	s_ashr_i32 s54, s0, 8
	s_lshl_b32 s21, s67, 1
	s_add_i32 s23, s14, 0x80
	s_add_i32 s21, s21, -8
	s_ashr_i32 s15, s14, 13
	s_ashr_i32 s31, s23, 13
	s_cmp_gt_i32 s66, 63
	s_cselect_b64 vcc, -1, 0
	v_bitop3_b32 v163, s14, v228, v169 bitop3:0xc8
	v_add_u32_e32 v163, 0x100, v163
	s_waitcnt vmcnt(0) lgkmcnt(0)
	v_fmamk_f32 v159, v159, 0x3a800000, v224
	v_cmp_gt_f32_e64 s[0:1], s33, v159
	v_mul_f32_e32 v162, 0x4b800000, v159
	s_nop 0
	v_cndmask_b32_e64 v159, v159, v162, s[0:1]
	v_rsq_f32_e32 v159, v159
	s_nop 0
	v_mul_f32_e32 v162, 0x45800000, v159
	v_cndmask_b32_e64 v162, v159, v162, s[0:1]
	v_bitop3_b32 v159, s14, v227, v169 bitop3:0xc8
	s_and_b64 s[0:1], vcc, exec
	s_cselect_b32 s0, s30, s15
	v_cndmask_b32_e32 v159, v163, v159, vcc
	s_cselect_b32 s54, s54, s31
	s_lshl_b32 s0, s0, 2
	v_lshrrev_b32_e32 v165, 2, v159
	s_add_i32 s0, s0, s21
	v_lshlrev_b32_e32 v163, 7, v159
	v_xor_b32_e32 v165, v165, v168
	v_and_b32_e32 v163, 0x400, v163
	v_lshlrev_b32_e32 v164, 5, v159
	v_lshlrev_b32_e32 v165, 3, v165
	s_mul_i32 s14, s0, 0x210000
	v_and_b32_e32 v165, 24, v165
	v_and_or_b32 v163, v164, s79, v163
	s_mul_hi_i32 s1, s0, 0x210000
	s_add_u32 s14, s45, s14
	v_or3_b32 v163, v163, v165, s64
	v_lshlrev_b32_e32 v159, 8, v159
	s_addc_u32 s15, s46, s1
	s_or_b32 s0, s0, 1
	v_and_b32_e32 v176, 0x3fc000, v159
	v_pk_fma_f32 v[142:143], v[142:143], v[162:163], v[54:55] op_sel_hi:[1,0,1]
	v_pk_fma_f32 v[140:141], v[140:141], v[162:163], v[52:53] op_sel_hi:[1,0,1]
	v_pk_fma_f32 v[136:137], v[136:137], v[162:163], v[48:49] op_sel_hi:[1,0,1]
	s_mul_hi_i32 s1, s0, 0x210000
	s_mul_i32 s0, s0, 0x210000
	v_pk_fma_f32 v[164:165], v[138:139], v[162:163], v[50:51] op_sel_hi:[1,0,1]
	v_cvt_pk_bf16_f32 v138, v140, v141
	v_cvt_pk_bf16_f32 v139, v142, v143
	v_cvt_pk_bf16_f32 v140, v136, v137
	v_lshl_add_u64 v[142:143], s[14:15], 0, v[176:177]
	v_lshlrev_b32_e32 v136, 1, v163
	v_mov_b32_e32 v137, v177
	s_add_u32 s30, s45, s0
	v_lshl_add_u64 v[142:143], v[142:143], 0, v[136:137]
	v_pk_fma_f32 v[132:133], v[132:133], v[162:163], v[36:37] op_sel_hi:[1,0,1]
	s_addc_u32 s31, s46, s1
	v_cvt_pk_bf16_f32 v141, v164, v165
	global_store_dwordx4 v[142:143], v[138:141], off
	v_pk_fma_f32 v[134:135], v[134:135], v[162:163], v[38:39] op_sel_hi:[1,0,1]
	s_nop 0
	v_pk_fma_f32 v[138:139], v[130:131], v[162:163], v[34:35] op_sel_hi:[1,0,1]
	v_pk_fma_f32 v[130:131], v[128:129], v[162:163], v[32:33] op_sel_hi:[1,0,1]
	v_cvt_pk_bf16_f32 v128, v132, v133
	v_lshl_add_u64 v[132:133], s[30:31], 0, v[176:177]
	v_lshl_add_u64 v[132:133], v[132:133], 0, v[136:137]
	v_cvt_pk_bf16_f32 v129, v134, v135
	v_cvt_pk_bf16_f32 v130, v130, v131
	v_cvt_pk_bf16_f32 v131, v138, v139
	global_store_dwordx4 v[132:133], v[128:131], off
	global_load_dword v128, v[160:161], off offset:64
	global_load_dword v214, v[160:161], off offset:128
	global_load_dword v215, v[160:161], off offset:192
	s_nop 0
	v_bitop3_b32 v130, v158, s84, 16 bitop3:0xc8
	v_add_u32_e32 v130, 0x100, v130
	s_waitcnt vmcnt(0) lgkmcnt(0)
	v_fmamk_f32 v128, v128, 0x3a800000, v224
	v_cmp_gt_f32_e64 s[0:1], s33, v128
	v_mul_f32_e32 v129, 0x4b800000, v128
	s_nop 0
	v_cndmask_b32_e64 v128, v128, v129, s[0:1]
	v_rsq_f32_e32 v128, v128
	s_nop 0
	v_mul_f32_e32 v129, 0x45800000, v128
	v_cndmask_b32_e64 v128, v128, v129, s[0:1]
	v_bitop3_b32 v129, v158, s95, 16 bitop3:0xc8
	v_cndmask_b32_e32 v129, v130, v129, vcc
	v_lshrrev_b32_e32 v132, 2, v129
	v_lshlrev_b32_e32 v130, 7, v129
	v_xor_b32_e32 v132, v132, v168
	v_and_b32_e32 v130, 0xc00, v130
	v_lshlrev_b32_e32 v131, 5, v129
	v_lshlrev_b32_e32 v132, 3, v132
	v_and_b32_e32 v132, 24, v132
	v_and_or_b32 v130, v131, s79, v130
	v_lshlrev_b32_e32 v129, 8, v129
	v_or3_b32 v132, v130, v132, s64
	v_and_b32_e32 v176, 0x3fc000, v129
	v_pk_fma_f32 v[126:127], v[126:127], v[128:129], v[54:55] op_sel_hi:[1,0,1]
	v_pk_fma_f32 v[124:125], v[124:125], v[128:129], v[52:53] op_sel_hi:[1,0,1]
	v_pk_fma_f32 v[120:121], v[120:121], v[128:129], v[48:49] op_sel_hi:[1,0,1]
	v_pk_fma_f32 v[130:131], v[122:123], v[128:129], v[50:51] op_sel_hi:[1,0,1]
	v_cvt_pk_bf16_f32 v122, v124, v125
	v_cvt_pk_bf16_f32 v123, v126, v127
	v_cvt_pk_bf16_f32 v124, v120, v121
	v_lshl_add_u64 v[126:127], s[14:15], 0, v[176:177]
	v_lshlrev_b32_e32 v120, 1, v132
	v_mov_b32_e32 v121, v177
	v_lshl_add_u64 v[126:127], v[126:127], 0, v[120:121]
	v_pk_fma_f32 v[116:117], v[116:117], v[128:129], v[36:37] op_sel_hi:[1,0,1]
	v_cvt_pk_bf16_f32 v125, v130, v131
	global_store_dwordx4 v[126:127], v[122:125], off
	v_pk_fma_f32 v[118:119], v[118:119], v[128:129], v[38:39] op_sel_hi:[1,0,1]
	s_nop 0
	v_pk_fma_f32 v[122:123], v[114:115], v[128:129], v[34:35] op_sel_hi:[1,0,1]
	v_pk_fma_f32 v[114:115], v[112:113], v[128:129], v[32:33] op_sel_hi:[1,0,1]
	v_cvt_pk_bf16_f32 v112, v116, v117
	v_lshl_add_u64 v[116:117], s[30:31], 0, v[176:177]
	v_lshl_add_u64 v[116:117], v[116:117], 0, v[120:121]
	v_cvt_pk_bf16_f32 v113, v118, v119
	v_cvt_pk_bf16_f32 v114, v114, v115
	v_cvt_pk_bf16_f32 v115, v122, v123
	global_store_dwordx4 v[116:117], v[112:115], off
	s_nop 1
	s_nop 0
	v_bitop3_b32 v114, v158, s81, 32 bitop3:0xc8
	v_add_u32_e32 v114, 0x100, v114
	v_fmamk_f32 v112, v214, 0x3a800000, v224
	v_cmp_gt_f32_e64 s[0:1], s33, v112
	v_mul_f32_e32 v113, 0x4b800000, v112
	s_nop 0
	v_cndmask_b32_e64 v112, v112, v113, s[0:1]
	v_rsq_f32_e32 v112, v112
	s_nop 0
	v_mul_f32_e32 v113, 0x45800000, v112
; __device__ __forceinline__ unsigned pkbf(float lo, float hi) { return pg8::cvt_pk_bf16(lo, hi); }
;     __device__ __forceinline__ void operator()(const f32x4 (&acc)[2][2][4][2], const Unit& u, int wr, int wc, int fr, int fq) const {
;     ...
;         } else if (pn < 6) {
; #pragma unroll
;             for (int ai = 0; ai < 2; ++ai)
; #pragma unroll
;                 for (int m = 0; m < 4; ++m) {
;                     const int row = pm * 256 + ai * 128 + wr * 64 + m * 16 + fr;
;                     const float rinv = rsqrtf(rowsq[row] * (1.f / DM) + EPSN);
;                     int b, kidx;
;                     if (isctx) { const int rc = row - MLAT; b = rc >> 8; kidx = rc & 255; } else { b = row >> 13; kidx = CTXL + (row & (SEQ - 1)); }
; #pragma unroll
;                     for (int bj = 0; bj < 2; ++bj) {
;                         const f32x4 y0 = acc[ai][bj][m][0] * rinv + bv[bj][0], y1 = acc[ai][bj][m][1] * rinv + bv[bj][1];
;                         u32x4 w; w.x = pkbf(y0[0], y0[1]); w.y = pkbf(y0[2], y0[3]); w.z = pkbf(y1[0], y1[1]); w.w = pkbf(y1[2], y1[3]);
;                         const int head = 2 * (pn - 4) + bj;
;                         const size_t off = (size_t)(b * 4 + head) * (LK * 128) + (size_t)(kidx >> 6) * 8192 + (size_t)(voff(kidx & 63, 4 * wc + fq) >> 1);
;                         *(u32x4*)(Vb + off) = w;
;                     }
;                 }
	v_cndmask_b32_e64 v112, v112, v113, s[0:1]
	v_bitop3_b32 v113, v158, s80, 32 bitop3:0xc8
	v_cndmask_b32_e32 v113, v114, v113, vcc
	v_lshrrev_b32_e32 v116, 2, v113
	v_lshlrev_b32_e32 v114, 7, v113
	v_xor_b32_e32 v116, v116, v168
	v_and_b32_e32 v114, 0x1400, v114
	v_lshlrev_b32_e32 v115, 5, v113
	v_lshlrev_b32_e32 v116, 3, v116
	v_and_b32_e32 v116, 24, v116
	v_and_or_b32 v114, v115, s79, v114
	v_lshlrev_b32_e32 v113, 8, v113
	v_or3_b32 v116, v114, v116, s64
	v_and_b32_e32 v176, 0x3fc000, v113
	v_pk_fma_f32 v[110:111], v[110:111], v[112:113], v[54:55] op_sel_hi:[1,0,1]
	v_pk_fma_f32 v[108:109], v[108:109], v[112:113], v[52:53] op_sel_hi:[1,0,1]
	v_pk_fma_f32 v[104:105], v[104:105], v[112:113], v[48:49] op_sel_hi:[1,0,1]
	v_pk_fma_f32 v[114:115], v[106:107], v[112:113], v[50:51] op_sel_hi:[1,0,1]
	v_cvt_pk_bf16_f32 v106, v108, v109
	v_cvt_pk_bf16_f32 v107, v110, v111
	v_cvt_pk_bf16_f32 v108, v104, v105
	v_lshl_add_u64 v[110:111], s[14:15], 0, v[176:177]
	v_lshlrev_b32_e32 v104, 1, v116
	v_mov_b32_e32 v105, v177
	v_lshl_add_u64 v[110:111], v[110:111], 0, v[104:105]
	v_pk_fma_f32 v[100:101], v[100:101], v[112:113], v[36:37] op_sel_hi:[1,0,1]
	v_cvt_pk_bf16_f32 v109, v114, v115
	global_store_dwordx4 v[110:111], v[106:109], off
	v_pk_fma_f32 v[102:103], v[102:103], v[112:113], v[38:39] op_sel_hi:[1,0,1]
	s_nop 0
	v_pk_fma_f32 v[106:107], v[98:99], v[112:113], v[34:35] op_sel_hi:[1,0,1]
	v_pk_fma_f32 v[98:99], v[96:97], v[112:113], v[32:33] op_sel_hi:[1,0,1]
	v_cvt_pk_bf16_f32 v96, v100, v101
	v_lshl_add_u64 v[100:101], s[30:31], 0, v[176:177]
	v_lshl_add_u64 v[100:101], v[100:101], 0, v[104:105]
	v_cvt_pk_bf16_f32 v97, v102, v103
	v_cvt_pk_bf16_f32 v98, v98, v99
	v_cvt_pk_bf16_f32 v99, v106, v107
	global_store_dwordx4 v[100:101], v[96:99], off
	s_nop 1
	s_nop 0
	v_bitop3_b32 v98, v158, s68, 48 bitop3:0xc8
	v_add_u32_e32 v98, 0x100, v98
	v_fmamk_f32 v96, v215, 0x3a800000, v224
	v_cmp_gt_f32_e64 s[0:1], s33, v96
	v_mul_f32_e32 v97, 0x4b800000, v96
	s_nop 0
	v_cndmask_b32_e64 v96, v96, v97, s[0:1]
	v_rsq_f32_e32 v96, v96
	s_nop 0
	v_mul_f32_e32 v97, 0x45800000, v96
	v_cndmask_b32_e64 v96, v96, v97, s[0:1]
	v_bitop3_b32 v97, v158, s48, 48 bitop3:0xc8
	v_cndmask_b32_e32 v97, v98, v97, vcc
	v_lshrrev_b32_e32 v100, 2, v97
	v_lshlrev_b32_e32 v98, 7, v97
	v_xor_b32_e32 v100, v100, v168
	v_and_b32_e32 v98, 0x1c00, v98
	v_lshlrev_b32_e32 v99, 5, v97
	v_lshlrev_b32_e32 v100, 3, v100
	v_and_b32_e32 v100, 24, v100
	v_and_or_b32 v98, v99, s79, v98
	v_lshlrev_b32_e32 v97, 8, v97
	v_or3_b32 v100, v98, v100, s64
	v_and_b32_e32 v176, 0x3fc000, v97
	v_pk_fma_f32 v[94:95], v[94:95], v[96:97], v[54:55] op_sel_hi:[1,0,1]
	v_pk_fma_f32 v[92:93], v[92:93], v[96:97], v[52:53] op_sel_hi:[1,0,1]
	v_pk_fma_f32 v[98:99], v[90:91], v[96:97], v[50:51] op_sel_hi:[1,0,1]
	v_pk_fma_f32 v[90:91], v[88:89], v[96:97], v[48:49] op_sel_hi:[1,0,1]
	v_cvt_pk_bf16_f32 v88, v92, v93
	v_cvt_pk_bf16_f32 v89, v94, v95
	v_lshl_add_u64 v[92:93], s[14:15], 0, v[176:177]
	v_lshlrev_b32_e32 v94, 1, v100
	v_mov_b32_e32 v95, v177
	v_lshl_add_u64 v[92:93], v[92:93], 0, v[94:95]
	v_pk_fma_f32 v[84:85], v[84:85], v[96:97], v[36:37] op_sel_hi:[1,0,1]
	v_cvt_pk_bf16_f32 v90, v90, v91
	v_cvt_pk_bf16_f32 v91, v98, v99
	global_store_dwordx4 v[92:93], v[88:91], off
	v_pk_fma_f32 v[86:87], v[86:87], v[96:97], v[38:39] op_sel_hi:[1,0,1]
	s_nop 0
	v_pk_fma_f32 v[88:89], v[82:83], v[96:97], v[34:35] op_sel_hi:[1,0,1]
	v_pk_fma_f32 v[82:83], v[80:81], v[96:97], v[32:33] op_sel_hi:[1,0,1]
	v_cvt_pk_bf16_f32 v80, v84, v85
	v_lshl_add_u64 v[84:85], s[30:31], 0, v[176:177]
	v_lshl_add_u64 v[84:85], v[84:85], 0, v[94:95]
	v_cvt_pk_bf16_f32 v81, v86, v87
	v_cvt_pk_bf16_f32 v82, v82, v83
	v_cvt_pk_bf16_f32 v83, v88, v89
	global_store_dwordx4 v[84:85], v[80:83], off
	v_bitop3_b32 v85, s23, v228, v169 bitop3:0xc8
	v_add_u32_e32 v85, 0x100, v85
	v_or_b32_e32 v80, s23, v169
	v_ashrrev_i32_e32 v81, 31, v80
	v_lshl_add_u64 v[82:83], v[80:81], 2, s[12:13]
	global_load_dword v81, v[82:83], off
	global_load_dword v214, v[82:83], off offset:64
	global_load_dword v215, v[82:83], off offset:128
	global_load_dword v216, v[82:83], off offset:192
	s_waitcnt vmcnt(0) lgkmcnt(0)
	v_fmamk_f32 v81, v81, 0x3a800000, v224
	v_cmp_gt_f32_e64 s[0:1], s33, v81
	v_mul_f32_e32 v84, 0x4b800000, v81
	s_nop 0
	v_cndmask_b32_e64 v81, v81, v84, s[0:1]
	v_rsq_f32_e32 v81, v81
	s_nop 0
	v_mul_f32_e32 v84, 0x45800000, v81
	v_cndmask_b32_e64 v84, v81, v84, s[0:1]
	v_bitop3_b32 v81, s23, v227, v169 bitop3:0xc8
	v_cndmask_b32_e32 v81, v85, v81, vcc
	s_lshl_b32 s0, s54, 2
	v_lshrrev_b32_e32 v87, 2, v81
	s_add_i32 s0, s0, s21
	v_lshlrev_b32_e32 v85, 7, v81
	v_xor_b32_e32 v87, v87, v168
	v_and_b32_e32 v85, 0x400, v85
	v_lshlrev_b32_e32 v86, 5, v81
	v_lshlrev_b32_e32 v87, 3, v87
	s_mul_i32 s14, s0, 0x210000
	v_and_b32_e32 v87, 24, v87
	v_and_or_b32 v85, v86, s79, v85
	s_mul_hi_i32 s1, s0, 0x210000
	s_add_u32 s14, s45, s14
	v_or3_b32 v85, v85, v87, s64
	v_lshlrev_b32_e32 v81, 8, v81
	s_addc_u32 s15, s46, s1
	s_or_b32 s0, s0, 1
	v_and_b32_e32 v176, 0x3fc000, v81
	v_pk_fma_f32 v[78:79], v[78:79], v[84:85], v[54:55] op_sel_hi:[1,0,1]
	v_pk_fma_f32 v[76:77], v[76:77], v[84:85], v[52:53] op_sel_hi:[1,0,1]
	v_pk_fma_f32 v[72:73], v[72:73], v[84:85], v[48:49] op_sel_hi:[1,0,1]
	s_mul_hi_i32 s1, s0, 0x210000
	s_mul_i32 s0, s0, 0x210000
	v_pk_fma_f32 v[86:87], v[74:75], v[84:85], v[50:51] op_sel_hi:[1,0,1]
	v_cvt_pk_bf16_f32 v74, v76, v77
	v_cvt_pk_bf16_f32 v75, v78, v79
	v_cvt_pk_bf16_f32 v76, v72, v73
	v_lshl_add_u64 v[78:79], s[14:15], 0, v[176:177]
	v_lshlrev_b32_e32 v72, 1, v85
	v_mov_b32_e32 v73, v177
	s_add_u32 s30, s45, s0
	v_lshl_add_u64 v[78:79], v[78:79], 0, v[72:73]
; __device__ __forceinline__ unsigned pkbf(float lo, float hi) { return pg8::cvt_pk_bf16(lo, hi); }
;     __device__ __forceinline__ void operator()(const f32x4 (&acc)[2][2][4][2], const Unit& u, int wr, int wc, int fr, int fq) const {
;     ...
;         } else if (pn < 6) {
; #pragma unroll
;             for (int ai = 0; ai < 2; ++ai)
; #pragma unroll
;                 for (int m = 0; m < 4; ++m) {
;                     const int row = pm * 256 + ai * 128 + wr * 64 + m * 16 + fr;
;                     const float rinv = rsqrtf(rowsq[row] * (1.f / DM) + EPSN);
;                     int b, kidx;
;                     if (isctx) { const int rc = row - MLAT; b = rc >> 8; kidx = rc & 255; } else { b = row >> 13; kidx = CTXL + (row & (SEQ - 1)); }
; #pragma unroll
;                     for (int bj = 0; bj < 2; ++bj) {
;                         const f32x4 y0 = acc[ai][bj][m][0] * rinv + bv[bj][0], y1 = acc[ai][bj][m][1] * rinv + bv[bj][1];
;                         u32x4 w; w.x = pkbf(y0[0], y0[1]); w.y = pkbf(y0[2], y0[3]); w.z = pkbf(y1[0], y1[1]); w.w = pkbf(y1[2], y1[3]);
;                         const int head = 2 * (pn - 4) + bj;
;                         const size_t off = (size_t)(b * 4 + head) * (LK * 128) + (size_t)(kidx >> 6) * 8192 + (size_t)(voff(kidx & 63, 4 * wc + fq) >> 1);
;                         *(u32x4*)(Vb + off) = w;
;                     }
;                 }
	v_pk_fma_f32 v[68:69], v[68:69], v[84:85], v[36:37] op_sel_hi:[1,0,1]
	s_addc_u32 s31, s46, s1
	v_cvt_pk_bf16_f32 v77, v86, v87
	global_store_dwordx4 v[78:79], v[74:77], off
	v_pk_fma_f32 v[70:71], v[70:71], v[84:85], v[38:39] op_sel_hi:[1,0,1]
	s_nop 0
	v_pk_fma_f32 v[74:75], v[66:67], v[84:85], v[34:35] op_sel_hi:[1,0,1]
	v_pk_fma_f32 v[66:67], v[64:65], v[84:85], v[32:33] op_sel_hi:[1,0,1]
	v_cvt_pk_bf16_f32 v64, v68, v69
	v_lshl_add_u64 v[68:69], s[30:31], 0, v[176:177]
	v_lshl_add_u64 v[68:69], v[68:69], 0, v[72:73]
	v_cvt_pk_bf16_f32 v65, v70, v71
	v_cvt_pk_bf16_f32 v66, v66, v67
	v_cvt_pk_bf16_f32 v67, v74, v75
	global_store_dwordx4 v[68:69], v[64:67], off
	s_nop 1
	s_nop 0
	v_bitop3_b32 v66, v80, s84, 16 bitop3:0xc8
	v_add_u32_e32 v66, 0x100, v66
	v_fmamk_f32 v64, v214, 0x3a800000, v224
	v_cmp_gt_f32_e64 s[0:1], s33, v64
	v_mul_f32_e32 v65, 0x4b800000, v64
	s_nop 0
	v_cndmask_b32_e64 v64, v64, v65, s[0:1]
	v_rsq_f32_e32 v64, v64
	s_nop 0
	v_mul_f32_e32 v65, 0x45800000, v64
	v_cndmask_b32_e64 v64, v64, v65, s[0:1]
	v_bitop3_b32 v65, v80, s95, 16 bitop3:0xc8
	v_cndmask_b32_e32 v65, v66, v65, vcc
	v_lshrrev_b32_e32 v68, 2, v65
	v_lshlrev_b32_e32 v66, 7, v65
	v_xor_b32_e32 v68, v68, v168
	v_and_b32_e32 v66, 0xc00, v66
	v_lshlrev_b32_e32 v67, 5, v65
	v_lshlrev_b32_e32 v68, 3, v68
	v_and_b32_e32 v68, 24, v68
	v_and_or_b32 v66, v67, s79, v66
	v_lshlrev_b32_e32 v65, 8, v65
	v_or3_b32 v68, v66, v68, s64
	v_and_b32_e32 v176, 0x3fc000, v65
	v_pk_fma_f32 v[62:63], v[62:63], v[64:65], v[54:55] op_sel_hi:[1,0,1]
	v_pk_fma_f32 v[60:61], v[60:61], v[64:65], v[52:53] op_sel_hi:[1,0,1]
	v_pk_fma_f32 v[56:57], v[56:57], v[64:65], v[48:49] op_sel_hi:[1,0,1]
	v_pk_fma_f32 v[66:67], v[58:59], v[64:65], v[50:51] op_sel_hi:[1,0,1]
	v_cvt_pk_bf16_f32 v58, v60, v61
	v_cvt_pk_bf16_f32 v59, v62, v63
	v_cvt_pk_bf16_f32 v60, v56, v57
	v_lshl_add_u64 v[62:63], s[14:15], 0, v[176:177]
	v_lshlrev_b32_e32 v56, 1, v68
	v_mov_b32_e32 v57, v177
	v_lshl_add_u64 v[62:63], v[62:63], 0, v[56:57]
	v_pk_fma_f32 v[44:45], v[44:45], v[64:65], v[36:37] op_sel_hi:[1,0,1]
	v_cvt_pk_bf16_f32 v61, v66, v67
	global_store_dwordx4 v[62:63], v[58:61], off
	v_pk_fma_f32 v[46:47], v[46:47], v[64:65], v[38:39] op_sel_hi:[1,0,1]
	s_nop 0
	v_pk_fma_f32 v[58:59], v[42:43], v[64:65], v[34:35] op_sel_hi:[1,0,1]
	v_pk_fma_f32 v[42:43], v[40:41], v[64:65], v[32:33] op_sel_hi:[1,0,1]
	v_cvt_pk_bf16_f32 v40, v44, v45
	v_lshl_add_u64 v[44:45], s[30:31], 0, v[176:177]
	v_lshl_add_u64 v[44:45], v[44:45], 0, v[56:57]
	v_cvt_pk_bf16_f32 v41, v46, v47
	v_cvt_pk_bf16_f32 v42, v42, v43
	v_cvt_pk_bf16_f32 v43, v58, v59
	global_store_dwordx4 v[44:45], v[40:43], off
	s_nop 1
	s_nop 0
	v_bitop3_b32 v42, v80, s81, 32 bitop3:0xc8
	v_add_u32_e32 v42, 0x100, v42
	v_fmamk_f32 v40, v215, 0x3a800000, v224
	v_cmp_gt_f32_e64 s[0:1], s33, v40
	v_mul_f32_e32 v41, 0x4b800000, v40
	s_nop 0
	v_cndmask_b32_e64 v40, v40, v41, s[0:1]
	v_rsq_f32_e32 v40, v40
	s_nop 0
	v_mul_f32_e32 v41, 0x45800000, v40
	v_cndmask_b32_e64 v40, v40, v41, s[0:1]
	v_bitop3_b32 v41, v80, s80, 32 bitop3:0xc8
	v_cndmask_b32_e32 v41, v42, v41, vcc
	v_lshrrev_b32_e32 v44, 2, v41
	v_lshlrev_b32_e32 v42, 7, v41
	v_xor_b32_e32 v44, v44, v168
	v_and_b32_e32 v42, 0x1400, v42
	v_lshlrev_b32_e32 v43, 5, v41
	v_lshlrev_b32_e32 v44, 3, v44
	v_and_b32_e32 v44, 24, v44
	v_and_or_b32 v42, v43, s79, v42
	v_lshlrev_b32_e32 v41, 8, v41
	v_or3_b32 v44, v42, v44, s64
	v_and_b32_e32 v176, 0x3fc000, v41
	v_pk_fma_f32 v[30:31], v[30:31], v[40:41], v[54:55] op_sel_hi:[1,0,1]
	v_pk_fma_f32 v[28:29], v[28:29], v[40:41], v[52:53] op_sel_hi:[1,0,1]
	v_pk_fma_f32 v[24:25], v[24:25], v[40:41], v[48:49] op_sel_hi:[1,0,1]
	v_pk_fma_f32 v[42:43], v[26:27], v[40:41], v[50:51] op_sel_hi:[1,0,1]
	v_cvt_pk_bf16_f32 v26, v28, v29
	v_cvt_pk_bf16_f32 v27, v30, v31
	v_cvt_pk_bf16_f32 v28, v24, v25
	v_lshl_add_u64 v[30:31], s[14:15], 0, v[176:177]
	v_lshlrev_b32_e32 v24, 1, v44
	v_mov_b32_e32 v25, v177
	v_lshl_add_u64 v[30:31], v[30:31], 0, v[24:25]
	v_pk_fma_f32 v[20:21], v[20:21], v[40:41], v[36:37] op_sel_hi:[1,0,1]
	v_cvt_pk_bf16_f32 v29, v42, v43
	global_store_dwordx4 v[30:31], v[26:29], off
	v_pk_fma_f32 v[22:23], v[22:23], v[40:41], v[38:39] op_sel_hi:[1,0,1]
	s_nop 0
	v_pk_fma_f32 v[26:27], v[18:19], v[40:41], v[34:35] op_sel_hi:[1,0,1]
	v_pk_fma_f32 v[18:19], v[16:17], v[40:41], v[32:33] op_sel_hi:[1,0,1]
	v_cvt_pk_bf16_f32 v16, v20, v21
	v_lshl_add_u64 v[20:21], s[30:31], 0, v[176:177]
	v_lshl_add_u64 v[20:21], v[20:21], 0, v[24:25]
	v_cvt_pk_bf16_f32 v17, v22, v23
	v_cvt_pk_bf16_f32 v18, v18, v19
	v_cvt_pk_bf16_f32 v19, v26, v27
	global_store_dwordx4 v[20:21], v[16:19], off
	s_nop 1
	s_nop 0
	v_bitop3_b32 v18, v80, s68, 48 bitop3:0xc8
	v_add_u32_e32 v18, 0x100, v18
	v_fmamk_f32 v16, v216, 0x3a800000, v224
	v_cmp_gt_f32_e64 s[0:1], s33, v16
	v_mul_f32_e32 v17, 0x4b800000, v16
	s_nop 0
	v_cndmask_b32_e64 v16, v16, v17, s[0:1]
	v_rsq_f32_e32 v16, v16
	s_nop 0
	v_mul_f32_e32 v17, 0x45800000, v16
	v_cndmask_b32_e64 v16, v16, v17, s[0:1]
	v_bitop3_b32 v17, v80, s48, 48 bitop3:0xc8
	v_cndmask_b32_e32 v17, v18, v17, vcc
	v_lshrrev_b32_e32 v20, 2, v17
	v_lshlrev_b32_e32 v18, 7, v17
	v_xor_b32_e32 v20, v20, v168
	v_and_b32_e32 v18, 0x1c00, v18
	v_lshlrev_b32_e32 v19, 5, v17
	v_lshlrev_b32_e32 v20, 3, v20
	v_and_b32_e32 v20, 24, v20
	v_and_or_b32 v18, v19, s79, v18
	v_lshlrev_b32_e32 v17, 8, v17
	v_or3_b32 v20, v18, v20, s64
	v_and_b32_e32 v176, 0x3fc000, v17
	v_pk_fma_f32 v[14:15], v[14:15], v[16:17], v[54:55] op_sel_hi:[1,0,1]
	v_pk_fma_f32 v[12:13], v[12:13], v[16:17], v[52:53] op_sel_hi:[1,0,1]
	v_pk_fma_f32 v[8:9], v[8:9], v[16:17], v[48:49] op_sel_hi:[1,0,1]
	v_pk_fma_f32 v[18:19], v[10:11], v[16:17], v[50:51] op_sel_hi:[1,0,1]
	v_cvt_pk_bf16_f32 v10, v12, v13
	v_cvt_pk_bf16_f32 v11, v14, v15
	v_cvt_pk_bf16_f32 v12, v8, v9
	v_lshl_add_u64 v[14:15], s[14:15], 0, v[176:177]
	v_lshlrev_b32_e32 v8, 1, v20
	v_mov_b32_e32 v9, v177
	v_lshl_add_u64 v[14:15], v[14:15], 0, v[8:9]
	v_pk_fma_f32 v[4:5], v[4:5], v[16:17], v[36:37] op_sel_hi:[1,0,1]
	v_cvt_pk_bf16_f32 v13, v18, v19
	global_store_dwordx4 v[14:15], v[10:13], off
	v_pk_fma_f32 v[6:7], v[6:7], v[16:17], v[38:39] op_sel_hi:[1,0,1]
	s_nop 0
	v_pk_fma_f32 v[10:11], v[2:3], v[16:17], v[34:35] op_sel_hi:[1,0,1]
	v_pk_fma_f32 v[2:3], v[0:1], v[16:17], v[32:33] op_sel_hi:[1,0,1]
	v_cvt_pk_bf16_f32 v0, v4, v5
	v_lshl_add_u64 v[4:5], s[30:31], 0, v[176:177]
	v_lshl_add_u64 v[4:5], v[4:5], 0, v[8:9]
	v_cvt_pk_bf16_f32 v1, v6, v7
	v_cvt_pk_bf16_f32 v2, v2, v3
	v_cvt_pk_bf16_f32 v3, v10, v11
	global_store_dwordx4 v[4:5], v[0:3], off
	s_andn2_b64 vcc, exec, s[26:27]
	s_mov_b64 s[0:1], -1
	s_cbranch_vccnz .LBB0_312

; __global__ void __launch_bounds__(512, 2) fwd_megakernel(Params p) {
;     ...
;                 if (threadIdx.x == 0) {
;                     int ntile = 0; for (int i = 0; i * G + bx < IPB_N; ++i) ++ntile;
;                     __builtin_amdgcn_fence(__ATOMIC_RELEASE, "agent"); asm volatile("s_waitcnt vmcnt(0)" ::: "memory");
;                     __hip_atomic_fetch_add(cntw, (unsigned)ntile, __ATOMIC_RELAXED, __HIP_MEMORY_SCOPE_AGENT);
;                 }
.LBB0_332:
	s_add_i32 s10, s10, s94
	s_cmpk_gt_i32 s10, 0x51
	s_cbranch_scc0 .LBB0_332
	buffer_wbl2 sc1
	s_waitcnt vmcnt(0)
	v_mov_b64_e32 v[0:1], s[6:7]
	global_atomic_add v[0:1], v238, off

; __global__ void __launch_bounds__(512, 2) fwd_megakernel(Params p) {
;     ...
;             const float lam = ((const float*)(ws + WS_LAM))[l];
;             const float post = 1.f - (0.8f - 0.6f * expf(-0.3f * (float)l));
;             for (int u = bx; u < 512; u += G) attn_unit(lds, QB, KB, VB, MIX, (u & 7) >> 2, u & 3, CTXL + (u >> 3) * 128, lam, post, p.subln_g + l * 128);
.LBB0_335:
	s_lshl_b64 s[0:1], s[50:51], 2
	s_add_u32 s0, s4, s0
	s_addc_u32 s1, s5, s1
	v_mov_b32_e32 v0, s0
	v_add_co_u32_e32 v0, vcc, 0x204000, v0
	v_mov_b32_e32 v1, s1
	s_nop 0
	v_addc_co_u32_e32 v1, vcc, 0, v1, vcc
	global_load_dword v168, v[0:1], off
	v_cvt_f32_u32_e32 v0, s50
	s_mov_b32 s0, 0x3fb8aa3b
	s_movk_i32 s47, 0x52
	v_mul_f32_e32 v0, 0xbe99999a, v0
	v_mul_f32_e32 v1, 0x3fb8aa3b, v0
	v_fma_f32 v2, v0, s0, -v1
	v_rndne_f32_e32 v3, v1
	v_fmac_f32_e32 v2, 0x32a5705f, v0
	v_sub_f32_e32 v1, v1, v3
	v_add_f32_e32 v1, v1, v2
	v_exp_f32_e32 v1, v1
	v_cvt_i32_f32_e32 v2, v3
	s_mov_b32 s0, 0xc2ce8ed0
	v_cmp_ngt_f32_e32 vcc, s0, v0
	s_mov_b32 s0, 0x42b17218
	v_ldexp_f32 v1, v1, v2
	v_cndmask_b32_e32 v1, 0, v1, vcc
	v_cmp_nlt_f32_e32 vcc, s0, v0
	s_nop 1
	v_cndmask_b32_e32 v0, v231, v1, vcc
	v_fmamk_f32 v0, v0, 0x3f19999a, v226
	s_and_b64 vcc, exec, s[8:9]
	v_add_f32_e32 v169, 1.0, v0
	s_cbranch_vccnz .LBB0_379
	s_add_u32 s34, s4, 0x8c00000
	s_addc_u32 s35, s5, 0
	s_add_u32 s36, s4, 0x9d00000
	s_addc_u32 s37, s5, 0
	s_add_u32 s38, s4, 0xae00000
	s_addc_u32 s39, s5, 0
	s_add_u32 s8, s4, 0xe100000
	s_addc_u32 s9, s5, 0
	s_lshl_b32 s76, s50, 7
	v_readlane_b32 s12, v248, 18
	s_lshl_b64 s[0:1], s[76:77], 2
	v_readlane_b32 s24, v248, 30
	v_readlane_b32 s25, v248, 31
	s_add_u32 s10, s24, s0
	s_addc_u32 s11, s25, s1
	s_mov_b32 s40, s2
	s_mov_b32 s41, s2
	v_readlane_b32 s13, v248, 19
	v_readlane_b32 s14, v248, 20
	v_readlane_b32 s15, v248, 21
	v_readlane_b32 s16, v248, 22
	v_readlane_b32 s17, v248, 23
	v_readlane_b32 s18, v248, 24
	v_readlane_b32 s19, v248, 25
	v_readlane_b32 s20, v248, 26
	v_readlane_b32 s21, v248, 27
	v_readlane_b32 s22, v248, 28
	v_readlane_b32 s23, v248, 29
	v_readlane_b32 s26, v248, 32
	v_readlane_b32 s27, v248, 33
	s_branch .LBB0_338

; template <int W> __device__ __forceinline__ void pool_win(const float* up, int seq0, int L, int tfirst, int ch, LAS float* Pout) {
;     ...
;     float u[NV];
; #pragma unroll
;     for (int j = 0; j < NV; ++j) { const int tt = tfirst - LO + j; u[j] = (tt >= 0 && tt < L) ? up[(size_t)(seq0 + tt) * 256 + ch] : 0.f; }
.LBB0_501:
	s_and_b64 vcc, exec, s[14:15]
	s_cbranch_vccz .LBB0_581
	s_add_i32 s14, s45, -4
	v_mov_b32_e32 v13, 0
	s_cmp_ge_u32 s14, s44
	v_mov_b32_e32 v51, 0
	s_cbranch_scc1 .LBB0_504
	s_add_i32 s76, s14, s51
	s_lshl_b64 s[14:15], s[76:77], 10
	v_lshl_add_u64 v[6:7], v[0:1], 0, s[14:15]
	global_load_dword v5, v[6:7], off
	s_waitcnt vmcnt(0) lgkmcnt(0)
	v_add_f32_e32 v51, 0, v5
.LBB0_504:
	s_add_i32 s14, s45, -3
	s_cmp_ge_u32 s14, s44
	s_cbranch_scc1 .LBB0_506
	s_add_i32 s76, s14, s51
	s_lshl_b64 s[14:15], s[76:77], 10
	v_lshl_add_u64 v[6:7], v[0:1], 0, s[14:15]
	global_load_dword v13, v[6:7], off
.LBB0_506:
	s_add_i32 s14, s45, -2
	v_mov_b32_e32 v14, 0
	s_cmp_ge_u32 s14, s44
	v_mov_b32_e32 v17, 0
	s_cbranch_scc1 .LBB0_512
	s_add_i32 s76, s14, s51
	s_lshl_b64 s[14:15], s[76:77], 10
	v_lshl_add_u64 v[6:7], v[0:1], 0, s[14:15]
	global_load_dword v17, v[6:7], off
	s_add_i32 s14, s45, -1
	s_cmp_ge_u32 s14, s44
	s_cbranch_scc0 .LBB0_513

; template <int W> __device__ __forceinline__ void pool_win(const float* up, int seq0, int L, int tfirst, int ch, LAS float* Pout) {
;     ...
;     float u[NV];
; #pragma unroll
;     for (int j = 0; j < NV; ++j) { const int tt = tfirst - LO + j; u[j] = (tt >= 0 && tt < L) ? up[(size_t)(seq0 + tt) * 256 + ch] : 0.f; }
.LBB0_509:
	s_add_i32 s14, s38, s26
	s_ashr_i32 s15, s14, 31
	s_lshl_b64 s[14:15], s[14:15], 10
	v_lshl_add_u64 v[6:7], v[0:1], 0, s[14:15]
	global_load_dword v58, v[6:7], off
	s_or_b32 s95, s45, 1
	s_cmp_ge_u32 s95, s44
	s_cbranch_scc0 .LBB0_515
	s_branch .LBB0_516

; template <int W> __device__ __forceinline__ void pool_win(const float* up, int seq0, int L, int tfirst, int ch, LAS float* Pout) {
;     ...
;     float u[NV];
; #pragma unroll
;     for (int j = 0; j < NV; ++j) { const int tt = tfirst - LO + j; u[j] = (tt >= 0 && tt < L) ? up[(size_t)(seq0 + tt) * 256 + ch] : 0.f; }
.LBB0_511:
	s_add_i32 s76, s58, s51
	s_lshl_b64 s[0:1], s[76:77], 10
	v_lshl_add_u64 v[46:47], v[0:1], 0, s[0:1]
	global_load_dword v74, v[46:47], off
	s_add_i32 s57, s45, 38
	s_cmp_ge_u32 s57, s44
	v_mov_b32_e32 v76, 0
	s_cbranch_scc0 .LBB0_499
	s_branch .LBB0_500

; template <int W> __device__ __forceinline__ void pool_win(const float* up, int seq0, int L, int tfirst, int ch, LAS float* Pout) {
;     ...
;     float u[NV];
; #pragma unroll
;     for (int j = 0; j < NV; ++j) { const int tt = tfirst - LO + j; u[j] = (tt >= 0 && tt < L) ? up[(size_t)(seq0 + tt) * 256 + ch] : 0.f; }
.LBB0_513:
	s_add_i32 s76, s14, s51
	s_lshl_b64 s[14:15], s[76:77], 10
	v_lshl_add_u64 v[6:7], v[0:1], 0, s[14:15]
	global_load_dword v14, v[6:7], off
	v_mov_b32_e32 v57, 0
	s_cmp_ge_u32 s45, s44
	v_mov_b32_e32 v58, 0
	s_cbranch_scc0 .LBB0_509

; template <int W> __device__ __forceinline__ void pool_win(const float* up, int seq0, int L, int tfirst, int ch, LAS float* Pout) {
;     ...
;     float u[NV];
; #pragma unroll
;     for (int j = 0; j < NV; ++j) { const int tt = tfirst - LO + j; u[j] = (tt >= 0 && tt < L) ? up[(size_t)(seq0 + tt) * 256 + ch] : 0.f; }
.LBB0_515:
	s_add_i32 s76, s95, s51
	s_lshl_b64 s[14:15], s[76:77], 10
	v_lshl_add_u64 v[6:7], v[0:1], 0, s[14:15]
	global_load_dword v57, v[6:7], off
.LBB0_516:
	s_or_b32 s87, s45, 2
	v_mov_b32_e32 v53, 0
	s_cmp_ge_u32 s87, s44
	v_mov_b32_e32 v55, 0
	s_cbranch_scc1 .LBB0_518
	s_add_i32 s76, s87, s51
	s_lshl_b64 s[14:15], s[76:77], 10
	v_lshl_add_u64 v[6:7], v[0:1], 0, s[14:15]
	global_load_dword v55, v[6:7], off
.LBB0_518:
	s_or_b32 s84, s45, 3
	s_cmp_ge_u32 s84, s44
	s_cbranch_scc1 .LBB0_520
	s_add_i32 s76, s84, s51
	s_lshl_b64 s[14:15], s[76:77], 10
	v_lshl_add_u64 v[6:7], v[0:1], 0, s[14:15]
	global_load_dword v53, v[6:7], off
.LBB0_520:
	s_or_b32 s61, s45, 4
	v_mov_b32_e32 v50, 0
	s_cmp_ge_u32 s61, s44
	v_mov_b32_e32 v52, 0
	s_cbranch_scc1 .LBB0_522
	s_add_i32 s76, s61, s51
	s_lshl_b64 s[14:15], s[76:77], 10
	v_lshl_add_u64 v[6:7], v[0:1], 0, s[14:15]
	global_load_dword v52, v[6:7], off
.LBB0_522:
	s_or_b32 s60, s45, 5
	s_cmp_ge_u32 s60, s44
	s_cbranch_scc1 .LBB0_524
	s_add_i32 s76, s60, s51
	s_lshl_b64 s[14:15], s[76:77], 10
	v_lshl_add_u64 v[6:7], v[0:1], 0, s[14:15]
	global_load_dword v50, v[6:7], off
.LBB0_524:
	s_or_b32 s81, s45, 6
	v_mov_b32_e32 v46, 0
	s_cmp_ge_u32 s81, s44
	v_mov_b32_e32 v48, 0
	s_cbranch_scc1 .LBB0_526
	s_add_i32 s76, s81, s51
	s_lshl_b64 s[14:15], s[76:77], 10
	v_lshl_add_u64 v[6:7], v[0:1], 0, s[14:15]
	global_load_dword v48, v[6:7], off
.LBB0_526:
	s_or_b32 s80, s45, 7
	s_cmp_ge_u32 s80, s44
	s_cbranch_scc1 .LBB0_528
	s_add_i32 s76, s80, s51
	s_lshl_b64 s[14:15], s[76:77], 10
	v_lshl_add_u64 v[6:7], v[0:1], 0, s[14:15]
	global_load_dword v46, v[6:7], off
.LBB0_528:
	s_or_b32 s55, s45, 8
	v_mov_b32_e32 v43, 0
	s_cmp_ge_u32 s55, s44
	v_mov_b32_e32 v45, 0
	s_cbranch_scc1 .LBB0_530
	s_add_i32 s76, s55, s51
	s_lshl_b64 s[14:15], s[76:77], 10
	v_lshl_add_u64 v[6:7], v[0:1], 0, s[14:15]
	global_load_dword v45, v[6:7], off
.LBB0_530:
	s_or_b32 s75, s45, 9
	s_cmp_ge_u32 s75, s44
	s_cbranch_scc1 .LBB0_532
	s_add_i32 s76, s75, s51
	s_lshl_b64 s[14:15], s[76:77], 10
	v_lshl_add_u64 v[6:7], v[0:1], 0, s[14:15]
	global_load_dword v43, v[6:7], off
.LBB0_532:
	s_or_b32 s74, s45, 10
	v_mov_b32_e32 v39, 0
	s_cmp_ge_u32 s74, s44
	v_mov_b32_e32 v41, 0
	s_cbranch_scc1 .LBB0_534
	s_add_i32 s76, s74, s51
	s_lshl_b64 s[14:15], s[76:77], 10
	v_lshl_add_u64 v[6:7], v[0:1], 0, s[14:15]
	global_load_dword v41, v[6:7], off
.LBB0_534:
	s_or_b32 s73, s45, 11
	s_cmp_ge_u32 s73, s44
	s_cbranch_scc1 .LBB0_536
	s_add_i32 s76, s73, s51
	s_lshl_b64 s[14:15], s[76:77], 10
	v_lshl_add_u64 v[6:7], v[0:1], 0, s[14:15]
	global_load_dword v39, v[6:7], off
.LBB0_536:
	s_or_b32 s72, s45, 12
	v_mov_b32_e32 v35, 0
	s_cmp_ge_u32 s72, s44
	v_mov_b32_e32 v38, 0
	s_cbranch_scc1 .LBB0_538
	s_add_i32 s76, s72, s51
	s_lshl_b64 s[14:15], s[76:77], 10
	v_lshl_add_u64 v[6:7], v[0:1], 0, s[14:15]
	global_load_dword v38, v[6:7], off
.LBB0_538:
	s_or_b32 s71, s45, 13
	s_cmp_ge_u32 s71, s44
	s_cbranch_scc1 .LBB0_540
	s_add_i32 s76, s71, s51
	s_lshl_b64 s[14:15], s[76:77], 10
	v_lshl_add_u64 v[6:7], v[0:1], 0, s[14:15]
	global_load_dword v35, v[6:7], off
.LBB0_540:
	s_or_b32 s70, s45, 14
	v_mov_b32_e32 v31, 0
	s_cmp_ge_u32 s70, s44
	v_mov_b32_e32 v33, 0
	s_cbranch_scc1 .LBB0_542
	s_add_i32 s76, s70, s51
	s_lshl_b64 s[14:15], s[76:77], 10
	v_lshl_add_u64 v[6:7], v[0:1], 0, s[14:15]
	global_load_dword v33, v[6:7], off
.LBB0_542:
	s_or_b32 s69, s45, 15
	s_cmp_ge_u32 s69, s44
	s_cbranch_scc1 .LBB0_544
	s_add_i32 s76, s69, s51
	s_lshl_b64 s[14:15], s[76:77], 10
	v_lshl_add_u64 v[6:7], v[0:1], 0, s[14:15]
	global_load_dword v31, v[6:7], off
.LBB0_544:
	s_or_b32 s68, s45, 16
	v_mov_b32_e32 v27, 0
	s_cmp_ge_u32 s68, s44
	v_mov_b32_e32 v29, 0
	s_cbranch_scc1 .LBB0_546
	s_add_i32 s76, s68, s51
	s_lshl_b64 s[14:15], s[76:77], 10
	v_lshl_add_u64 v[6:7], v[0:1], 0, s[14:15]
	global_load_dword v29, v[6:7], off
.LBB0_546:
	s_or_b32 s67, s45, 17
	s_cmp_ge_u32 s67, s44
	s_cbranch_scc1 .LBB0_548
	s_add_i32 s76, s67, s51
	s_lshl_b64 s[14:15], s[76:77], 10
	v_lshl_add_u64 v[6:7], v[0:1], 0, s[14:15]
	global_load_dword v27, v[6:7], off
; template <int W> __device__ __forceinline__ void pool_win(const float* up, int seq0, int L, int tfirst, int ch, LAS float* Pout) {
;     ...
;     float u[NV];
; #pragma unroll
;     for (int j = 0; j < NV; ++j) { const int tt = tfirst - LO + j; u[j] = (tt >= 0 && tt < L) ? up[(size_t)(seq0 + tt) * 256 + ch] : 0.f; }
.LBB0_548:
	s_or_b32 s66, s45, 18
	v_mov_b32_e32 v23, 0
	s_cmp_ge_u32 s66, s44
	v_mov_b32_e32 v24, 0
	s_cbranch_scc1 .LBB0_550
	s_add_i32 s76, s66, s51
	s_lshl_b64 s[14:15], s[76:77], 10
	v_lshl_add_u64 v[6:7], v[0:1], 0, s[14:15]
	global_load_dword v24, v[6:7], off
.LBB0_550:
	s_or_b32 s65, s45, 19
	s_cmp_ge_u32 s65, s44
	s_cbranch_scc1 .LBB0_552
	s_add_i32 s76, s65, s51
	s_lshl_b64 s[14:15], s[76:77], 10
	v_lshl_add_u64 v[6:7], v[0:1], 0, s[14:15]
	global_load_dword v23, v[6:7], off
.LBB0_552:
	s_or_b32 s64, s45, 20
	v_mov_b32_e32 v18, 0
	s_cmp_ge_u32 s64, s44
	v_mov_b32_e32 v21, 0
	s_cbranch_scc1 .LBB0_554
	s_add_i32 s76, s64, s51
	s_lshl_b64 s[14:15], s[76:77], 10
	v_lshl_add_u64 v[6:7], v[0:1], 0, s[14:15]
	global_load_dword v21, v[6:7], off
.LBB0_554:
	s_or_b32 s63, s45, 21
	s_cmp_ge_u32 s63, s44
	s_cbranch_scc1 .LBB0_556
	s_add_i32 s76, s63, s51
	s_lshl_b64 s[14:15], s[76:77], 10
	v_lshl_add_u64 v[6:7], v[0:1], 0, s[14:15]
	global_load_dword v18, v[6:7], off
.LBB0_556:
	s_or_b32 s62, s45, 22
	v_mov_b32_e32 v15, 0
	s_cmp_ge_u32 s62, s44
	v_mov_b32_e32 v16, 0
	s_cbranch_scc1 .LBB0_558
	s_add_i32 s76, s62, s51
	s_lshl_b64 s[14:15], s[76:77], 10
	v_lshl_add_u64 v[6:7], v[0:1], 0, s[14:15]
	global_load_dword v16, v[6:7], off
.LBB0_558:
	s_or_b32 s59, s45, 23
	s_cmp_ge_u32 s59, s44
	s_cbranch_scc1 .LBB0_560
	s_add_i32 s76, s59, s51
	s_lshl_b64 s[14:15], s[76:77], 10
	v_lshl_add_u64 v[6:7], v[0:1], 0, s[14:15]
	global_load_dword v15, v[6:7], off
.LBB0_560:
	s_or_b32 s58, s45, 24
	v_mov_b32_e32 v11, 0
	s_cmp_ge_u32 s58, s44
	v_mov_b32_e32 v12, 0
	s_cbranch_scc1 .LBB0_562
	s_add_i32 s76, s58, s51
	s_lshl_b64 s[14:15], s[76:77], 10
	v_lshl_add_u64 v[6:7], v[0:1], 0, s[14:15]
	global_load_dword v12, v[6:7], off
.LBB0_562:
	s_or_b32 s56, s45, 25
	s_cmp_ge_u32 s56, s44
	s_cbranch_scc1 .LBB0_564
	s_add_i32 s76, s56, s51
	s_lshl_b64 s[14:15], s[76:77], 10
	v_lshl_add_u64 v[6:7], v[0:1], 0, s[14:15]
	global_load_dword v11, v[6:7], off
.LBB0_564:
	s_or_b32 s53, s45, 26
	v_mov_b32_e32 v9, 0
	s_cmp_ge_u32 s53, s44
	v_mov_b32_e32 v10, 0
	s_cbranch_scc1 .LBB0_566
	s_add_i32 s76, s53, s51
	s_lshl_b64 s[14:15], s[76:77], 10
	v_lshl_add_u64 v[6:7], v[0:1], 0, s[14:15]
	global_load_dword v10, v[6:7], off
.LBB0_566:
	s_or_b32 s49, s45, 27
	s_cmp_ge_u32 s49, s44
	s_cbranch_scc1 .LBB0_568
	s_add_i32 s76, s49, s51
	s_lshl_b64 s[14:15], s[76:77], 10
	v_lshl_add_u64 v[6:7], v[0:1], 0, s[14:15]
	global_load_dword v9, v[6:7], off
.LBB0_568:
	s_or_b32 s37, s45, 28
	v_mov_b32_e32 v7, 0
	s_cmp_ge_u32 s37, s44
	v_mov_b32_e32 v8, 0
	s_cbranch_scc1 .LBB0_570
	s_add_i32 s76, s37, s51
	s_lshl_b64 s[14:15], s[76:77], 10
	v_lshl_add_u64 v[36:37], v[0:1], 0, s[14:15]
	global_load_dword v8, v[36:37], off
.LBB0_570:
	s_or_b32 s36, s45, 29
	s_cmp_ge_u32 s36, s44
	s_cbranch_scc1 .LBB0_572
	s_add_i32 s76, s36, s51
	s_lshl_b64 s[14:15], s[76:77], 10
	v_lshl_add_u64 v[6:7], v[0:1], 0, s[14:15]
	global_load_dword v7, v[6:7], off
.LBB0_572:
	s_or_b32 s15, s45, 30
	v_mov_b32_e32 v5, 0
	s_cmp_ge_u32 s15, s44
	v_mov_b32_e32 v6, 0
	s_cbranch_scc1 .LBB0_574
	s_add_i32 s76, s15, s51
	s_lshl_b64 s[96:97], s[76:77], 10
	v_lshl_add_u64 v[36:37], v[0:1], 0, s[96:97]
	global_load_dword v6, v[36:37], off
	s_mov_b32 s97, 0x10820
	s_movk_i32 s96, 0x1000
.LBB0_574:
	s_or_b32 s14, s45, 31
	s_cmp_ge_u32 s14, s44
	s_cbranch_scc1 .LBB0_576
	s_add_i32 s76, s14, s51
	s_lshl_b64 s[96:97], s[76:77], 10
	v_lshl_add_u64 v[36:37], v[0:1], 0, s[96:97]
	global_load_dword v5, v[36:37], off
	s_mov_b32 s97, 0x10820
	s_movk_i32 s96, 0x1000
.LBB0_576:
	s_add_i32 s57, s45, 32
	v_mov_b32_e32 v19, 0
	s_cmp_ge_u32 s57, s44
	v_mov_b32_e32 v22, 0
	s_cbranch_scc1 .LBB0_654
	s_add_i32 s76, s57, s51
	s_lshl_b64 s[96:97], s[76:77], 10
	v_lshl_add_u64 v[36:37], v[0:1], 0, s[96:97]
	global_load_dword v22, v[36:37], off
	s_mov_b32 s97, 0x10820
	s_movk_i32 s96, 0x1000
	s_add_i32 s54, s45, 33
	s_cmp_ge_u32 s54, s44
	s_cbranch_scc0 .LBB0_655

; template <int W> __device__ __forceinline__ void pool_win(const float* up, int seq0, int L, int tfirst, int ch, LAS float* Pout) {
;     ...
;     float u[NV];
; #pragma unroll
;     for (int j = 0; j < NV; ++j) { const int tt = tfirst - LO + j; u[j] = (tt >= 0 && tt < L) ? up[(size_t)(seq0 + tt) * 256 + ch] : 0.f; }
.LBB0_579:
	s_add_i32 s76, s52, s51
	s_lshl_b64 s[96:97], s[76:77], 10
	v_lshl_add_u64 v[36:37], v[0:1], 0, s[96:97]
	global_load_dword v64, v[36:37], off
	s_mov_b32 s97, 0x10820
	s_movk_i32 s96, 0x1000

; #define LAS __attribute__((address_space(3)))
; #define LAS __attribute__((address_space(3)))
; template <int W> __device__ __forceinline__ void pool_win(const float* up, int seq0, int L, int tfirst, int ch, LAS float* Pout) {
;     constexpr int LO = W / 2, HI = W - W / 2, NV = 31 + W;
;     float u[NV];
; #pragma unroll
;     for (int j = 0; j < NV; ++j) { const int tt = tfirst - LO + j; u[j] = (tt >= 0 && tt < L) ? up[(size_t)(seq0 + tt) * 256 + ch] : 0.f; }
;     float c[NV + 1]; c[0] = 0.f;
; #pragma unroll
;     for (int j = 0; j < NV; ++j) c[j + 1] = c[j] + u[j];
.LBB0_582:
	s_andn2_b64 vcc, exec, s[14:15]
	s_cbranch_vccnz .LBB0_723
	s_cmp_eq_u32 s43, 1
	s_mov_b64 s[14:15], -1
	s_cbranch_scc1 .LBB0_649
	s_add_i32 s14, s45, -1
	v_mov_b32_e32 v53, 0
	s_cmp_ge_u32 s14, s44
	v_mov_b32_e32 v51, 0
	s_cbranch_scc1 .LBB0_586
	s_add_i32 s76, s14, s51
	s_lshl_b64 s[14:15], s[76:77], 10
	v_lshl_add_u64 v[6:7], v[0:1], 0, s[14:15]
	global_load_dword v5, v[6:7], off
	s_waitcnt vmcnt(0) lgkmcnt(0)
	v_add_f32_e32 v51, 0, v5
.LBB0_586:
	s_cmp_ge_u32 s45, s44
	s_cbranch_scc1 .LBB0_588
	s_add_i32 s14, s38, s26
	s_ashr_i32 s15, s14, 31
	s_lshl_b64 s[14:15], s[14:15], 10
	v_lshl_add_u64 v[6:7], v[0:1], 0, s[14:15]
	global_load_dword v53, v[6:7], off
.LBB0_588:
	s_or_b32 s81, s45, 1
	v_mov_b32_e32 v48, 0
	s_cmp_ge_u32 s81, s44
	v_mov_b32_e32 v54, 0
	s_cbranch_scc1 .LBB0_590
	s_add_i32 s76, s81, s51
	s_lshl_b64 s[14:15], s[76:77], 10
	v_lshl_add_u64 v[6:7], v[0:1], 0, s[14:15]
	global_load_dword v54, v[6:7], off
.LBB0_590:
	s_or_b32 s80, s45, 2
	s_cmp_ge_u32 s80, s44
	s_cbranch_scc1 .LBB0_592
	s_add_i32 s76, s80, s51
	s_lshl_b64 s[14:15], s[76:77], 10
	v_lshl_add_u64 v[6:7], v[0:1], 0, s[14:15]
	global_load_dword v48, v[6:7], off
.LBB0_592:
	s_or_b32 s75, s45, 3
	v_mov_b32_e32 v46, 0
	s_cmp_ge_u32 s75, s44
	v_mov_b32_e32 v50, 0
	s_cbranch_scc1 .LBB0_594
	s_add_i32 s76, s75, s51
	s_lshl_b64 s[14:15], s[76:77], 10
	v_lshl_add_u64 v[6:7], v[0:1], 0, s[14:15]
	global_load_dword v50, v[6:7], off
.LBB0_594:
	s_or_b32 s74, s45, 4
	s_cmp_ge_u32 s74, s44
	s_cbranch_scc1 .LBB0_596
	s_add_i32 s76, s74, s51
	s_lshl_b64 s[14:15], s[76:77], 10
	v_lshl_add_u64 v[6:7], v[0:1], 0, s[14:15]
	global_load_dword v46, v[6:7], off
.LBB0_596:
	s_or_b32 s73, s45, 5
	v_mov_b32_e32 v42, 0
	s_cmp_ge_u32 s73, s44
	v_mov_b32_e32 v47, 0
	s_cbranch_scc1 .LBB0_598
	s_add_i32 s76, s73, s51
	s_lshl_b64 s[14:15], s[76:77], 10
	v_lshl_add_u64 v[6:7], v[0:1], 0, s[14:15]
	global_load_dword v47, v[6:7], off
.LBB0_598:
	s_or_b32 s72, s45, 6
	s_cmp_ge_u32 s72, s44
	s_cbranch_scc1 .LBB0_600
	s_add_i32 s76, s72, s51
	s_lshl_b64 s[14:15], s[76:77], 10
	v_lshl_add_u64 v[6:7], v[0:1], 0, s[14:15]
	global_load_dword v42, v[6:7], off
.LBB0_600:
	s_or_b32 s61, s45, 7
	v_mov_b32_e32 v39, 0
	s_cmp_ge_u32 s61, s44
	v_mov_b32_e32 v44, 0
	s_cbranch_scc1 .LBB0_602
	s_add_i32 s76, s61, s51
	s_lshl_b64 s[14:15], s[76:77], 10
	v_lshl_add_u64 v[6:7], v[0:1], 0, s[14:15]
	global_load_dword v44, v[6:7], off
.LBB0_602:
	s_or_b32 s60, s45, 8
	s_cmp_ge_u32 s60, s44
	s_cbranch_scc1 .LBB0_604
	s_add_i32 s76, s60, s51
	s_lshl_b64 s[14:15], s[76:77], 10
	v_lshl_add_u64 v[6:7], v[0:1], 0, s[14:15]
	global_load_dword v39, v[6:7], off
.LBB0_604:
	s_or_b32 s71, s45, 9
	v_mov_b32_e32 v36, 0
	s_cmp_ge_u32 s71, s44
	v_mov_b32_e32 v41, 0
	s_cbranch_scc1 .LBB0_606
	s_add_i32 s76, s71, s51
	s_lshl_b64 s[14:15], s[76:77], 10
	v_lshl_add_u64 v[6:7], v[0:1], 0, s[14:15]
	global_load_dword v41, v[6:7], off
.LBB0_606:
	s_or_b32 s70, s45, 10
	s_cmp_ge_u32 s70, s44
	s_cbranch_scc1 .LBB0_608
	s_add_i32 s76, s70, s51
	s_lshl_b64 s[14:15], s[76:77], 10
	v_lshl_add_u64 v[6:7], v[0:1], 0, s[14:15]
	global_load_dword v36, v[6:7], off
.LBB0_608:
	s_or_b32 s69, s45, 11
	v_mov_b32_e32 v33, 0
	s_cmp_ge_u32 s69, s44
	v_mov_b32_e32 v38, 0
	s_cbranch_scc1 .LBB0_610
	s_add_i32 s76, s69, s51
	s_lshl_b64 s[14:15], s[76:77], 10
	v_lshl_add_u64 v[6:7], v[0:1], 0, s[14:15]
	global_load_dword v38, v[6:7], off
.LBB0_610:
	s_or_b32 s55, s45, 12
	s_cmp_ge_u32 s55, s44
	s_cbranch_scc1 .LBB0_612
	s_add_i32 s76, s55, s51
	s_lshl_b64 s[14:15], s[76:77], 10
	v_lshl_add_u64 v[6:7], v[0:1], 0, s[14:15]
	global_load_dword v33, v[6:7], off
.LBB0_612:
	s_or_b32 s68, s45, 13
	v_mov_b32_e32 v30, 0
	s_cmp_ge_u32 s68, s44
	v_mov_b32_e32 v35, 0
	s_cbranch_scc1 .LBB0_614
	s_add_i32 s76, s68, s51
	s_lshl_b64 s[14:15], s[76:77], 10
	v_lshl_add_u64 v[6:7], v[0:1], 0, s[14:15]
	global_load_dword v35, v[6:7], off
; #define LAS __attribute__((address_space(3)))
; #define LAS __attribute__((address_space(3)))
; template <int W> __device__ __forceinline__ void pool_win(const float* up, int seq0, int L, int tfirst, int ch, LAS float* Pout) {
;     constexpr int LO = W / 2, HI = W - W / 2, NV = 31 + W;
;     float u[NV];
; #pragma unroll
;     for (int j = 0; j < NV; ++j) { const int tt = tfirst - LO + j; u[j] = (tt >= 0 && tt < L) ? up[(size_t)(seq0 + tt) * 256 + ch] : 0.f; }
;     float c[NV + 1]; c[0] = 0.f;
; #pragma unroll
;     for (int j = 0; j < NV; ++j) c[j + 1] = c[j] + u[j];
.LBB0_614:
	s_or_b32 s67, s45, 14
	s_cmp_ge_u32 s67, s44
	s_cbranch_scc1 .LBB0_616
	s_add_i32 s76, s67, s51
	s_lshl_b64 s[14:15], s[76:77], 10
	v_lshl_add_u64 v[6:7], v[0:1], 0, s[14:15]
	global_load_dword v30, v[6:7], off
.LBB0_616:
	s_or_b32 s66, s45, 15
	v_mov_b32_e32 v27, 0
	s_cmp_ge_u32 s66, s44
	v_mov_b32_e32 v31, 0
	s_cbranch_scc1 .LBB0_618
	s_add_i32 s76, s66, s51
	s_lshl_b64 s[14:15], s[76:77], 10
	v_lshl_add_u64 v[6:7], v[0:1], 0, s[14:15]
	global_load_dword v31, v[6:7], off
.LBB0_618:
	s_or_b32 s65, s45, 16
	s_cmp_ge_u32 s65, s44
	s_cbranch_scc1 .LBB0_620
	s_add_i32 s76, s65, s51
	s_lshl_b64 s[14:15], s[76:77], 10
	v_lshl_add_u64 v[6:7], v[0:1], 0, s[14:15]
	global_load_dword v27, v[6:7], off
.LBB0_620:
	s_or_b32 s64, s45, 17
	v_mov_b32_e32 v24, 0
	s_cmp_ge_u32 s64, s44
	v_mov_b32_e32 v29, 0
	s_cbranch_scc1 .LBB0_622
	s_add_i32 s76, s64, s51
	s_lshl_b64 s[14:15], s[76:77], 10
	v_lshl_add_u64 v[6:7], v[0:1], 0, s[14:15]
	global_load_dword v29, v[6:7], off
.LBB0_622:
	s_or_b32 s63, s45, 18
	s_cmp_ge_u32 s63, s44
	s_cbranch_scc1 .LBB0_624
	s_add_i32 s76, s63, s51
	s_lshl_b64 s[14:15], s[76:77], 10
	v_lshl_add_u64 v[6:7], v[0:1], 0, s[14:15]
	global_load_dword v24, v[6:7], off
.LBB0_624:
	s_or_b32 s62, s45, 19
	v_mov_b32_e32 v21, 0
	s_cmp_ge_u32 s62, s44
	v_mov_b32_e32 v25, 0
	s_cbranch_scc1 .LBB0_626
	s_add_i32 s76, s62, s51
	s_lshl_b64 s[14:15], s[76:77], 10
	v_lshl_add_u64 v[6:7], v[0:1], 0, s[14:15]
	global_load_dword v25, v[6:7], off
.LBB0_626:
	s_or_b32 s59, s45, 20
	s_cmp_ge_u32 s59, s44
	s_cbranch_scc1 .LBB0_628
	s_add_i32 s76, s59, s51
	s_lshl_b64 s[14:15], s[76:77], 10
	v_lshl_add_u64 v[6:7], v[0:1], 0, s[14:15]
	global_load_dword v21, v[6:7], off
.LBB0_628:
	s_or_b32 s58, s45, 21
	v_mov_b32_e32 v18, 0
	s_cmp_ge_u32 s58, s44
	v_mov_b32_e32 v22, 0
	s_cbranch_scc1 .LBB0_630
	s_add_i32 s76, s58, s51
	s_lshl_b64 s[14:15], s[76:77], 10
	v_lshl_add_u64 v[6:7], v[0:1], 0, s[14:15]
	global_load_dword v22, v[6:7], off
.LBB0_630:
	s_or_b32 s57, s45, 22
	s_cmp_ge_u32 s57, s44
	s_cbranch_scc1 .LBB0_632
	s_add_i32 s76, s57, s51
	s_lshl_b64 s[14:15], s[76:77], 10
	v_lshl_add_u64 v[6:7], v[0:1], 0, s[14:15]
	global_load_dword v18, v[6:7], off
.LBB0_632:
	s_or_b32 s56, s45, 23
	v_mov_b32_e32 v13, 0
	s_cmp_ge_u32 s56, s44
	v_mov_b32_e32 v19, 0
	s_cbranch_scc1 .LBB0_634
	s_add_i32 s76, s56, s51
	s_lshl_b64 s[14:15], s[76:77], 10
	v_lshl_add_u64 v[6:7], v[0:1], 0, s[14:15]
	global_load_dword v19, v[6:7], off
.LBB0_634:
	s_or_b32 s54, s45, 24
	s_cmp_ge_u32 s54, s44
	s_cbranch_scc1 .LBB0_636
	s_add_i32 s76, s54, s51
	s_lshl_b64 s[14:15], s[76:77], 10
	v_lshl_add_u64 v[6:7], v[0:1], 0, s[14:15]
	global_load_dword v13, v[6:7], off
.LBB0_636:
	s_or_b32 s53, s45, 25
	v_mov_b32_e32 v9, 0
	s_cmp_ge_u32 s53, s44
	v_mov_b32_e32 v16, 0
	s_cbranch_scc1 .LBB0_638
	s_add_i32 s76, s53, s51
	s_lshl_b64 s[14:15], s[76:77], 10
	v_lshl_add_u64 v[6:7], v[0:1], 0, s[14:15]
	global_load_dword v16, v[6:7], off
.LBB0_638:
	s_or_b32 s52, s45, 26
	s_cmp_ge_u32 s52, s44
	s_cbranch_scc1 .LBB0_640
	s_add_i32 s76, s52, s51
	s_lshl_b64 s[14:15], s[76:77], 10
	v_lshl_add_u64 v[6:7], v[0:1], 0, s[14:15]
	global_load_dword v9, v[6:7], off
.LBB0_640:
	s_or_b32 s49, s45, 27
	v_mov_b32_e32 v7, 0
	s_cmp_ge_u32 s49, s44
	v_mov_b32_e32 v12, 0
	s_cbranch_scc1 .LBB0_642
	s_add_i32 s76, s49, s51
	s_lshl_b64 s[14:15], s[76:77], 10
	v_lshl_add_u64 v[10:11], v[0:1], 0, s[14:15]
	global_load_dword v12, v[10:11], off
.LBB0_642:
	s_or_b32 s37, s45, 28
	s_cmp_ge_u32 s37, s44
	s_cbranch_scc1 .LBB0_644
	s_add_i32 s76, s37, s51
	s_lshl_b64 s[14:15], s[76:77], 10
	v_lshl_add_u64 v[6:7], v[0:1], 0, s[14:15]
	global_load_dword v7, v[6:7], off
.LBB0_644:
	s_or_b32 s36, s45, 29
	v_mov_b32_e32 v6, 0
	s_cmp_ge_u32 s36, s44
	v_mov_b32_e32 v8, 0
	s_cbranch_scc1 .LBB0_656
	s_add_i32 s76, s36, s51
	s_lshl_b64 s[14:15], s[76:77], 10
	v_lshl_add_u64 v[10:11], v[0:1], 0, s[14:15]
	global_load_dword v8, v[10:11], off
	s_or_b32 s15, s45, 30
	s_cmp_ge_u32 s15, s44
	s_cbranch_scc0 .LBB0_657

; template <int W> __device__ __forceinline__ void pool_win(const float* up, int seq0, int L, int tfirst, int ch, LAS float* Pout) {
;     ...
;     for (int j = 0; j < NV; ++j) { const int tt = tfirst - LO + j; u[j] = (tt >= 0 && tt < L) ? up[(size_t)(seq0 + tt) * 256 + ch] : 0.f; }
.LBB0_647:
	s_add_i32 s76, s14, s51
	s_lshl_b64 s[96:97], s[76:77], 10
	v_lshl_add_u64 v[10:11], v[0:1], 0, s[96:97]
	global_load_dword v5, v[10:11], off
	s_mov_b32 s97, 0x10820
	s_movk_i32 s96, 0x1000

; #define LAS __attribute__((address_space(3)))
; #define LAS __attribute__((address_space(3)))
; template <int W> __device__ __forceinline__ void pool_win(const float* up, int seq0, int L, int tfirst, int ch, LAS float* Pout) {
;     constexpr int LO = W / 2, HI = W - W / 2, NV = 31 + W;
;     float u[NV];
; #pragma unroll
;     for (int j = 0; j < NV; ++j) { const int tt = tfirst - LO + j; u[j] = (tt >= 0 && tt < L) ? up[(size_t)(seq0 + tt) * 256 + ch] : 0.f; }
;     float c[NV + 1]; c[0] = 0.f;
; #pragma unroll
;     for (int j = 0; j < NV; ++j) c[j + 1] = c[j] + u[j];
.LBB0_649:
	s_and_b64 vcc, exec, s[14:15]
	s_cbranch_vccz .LBB0_723
	s_add_i32 s14, s45, -2
	v_mov_b32_e32 v13, 0
	s_cmp_ge_u32 s14, s44
	v_mov_b32_e32 v49, 0
	s_cbranch_scc1 .LBB0_658
	s_add_i32 s76, s14, s51
	s_lshl_b64 s[14:15], s[76:77], 10
	v_lshl_add_u64 v[6:7], v[0:1], 0, s[14:15]
	global_load_dword v5, v[6:7], off
	s_waitcnt vmcnt(0) lgkmcnt(0)
	v_add_f32_e32 v49, 0, v5
	s_add_i32 s14, s45, -1
	s_cmp_ge_u32 s14, s44
	s_cbranch_scc0 .LBB0_659

; template <int W> __device__ __forceinline__ void pool_win(const float* up, int seq0, int L, int tfirst, int ch, LAS float* Pout) {
;     ...
;     for (int j = 0; j < NV; ++j) { const int tt = tfirst - LO + j; u[j] = (tt >= 0 && tt < L) ? up[(size_t)(seq0 + tt) * 256 + ch] : 0.f; }
.LBB0_653:
	s_add_i32 s14, s38, s26
	s_ashr_i32 s15, s14, 31
	s_lshl_b64 s[14:15], s[14:15], 10
	v_lshl_add_u64 v[6:7], v[0:1], 0, s[14:15]
	global_load_dword v54, v[6:7], off
	s_or_b32 s84, s45, 1
	s_cmp_ge_u32 s84, s44
	s_cbranch_scc0 .LBB0_661
	s_branch .LBB0_662

; template <int W> __device__ __forceinline__ void pool_win(const float* up, int seq0, int L, int tfirst, int ch, LAS float* Pout) {
;     ...
;     for (int j = 0; j < NV; ++j) { const int tt = tfirst - LO + j; u[j] = (tt >= 0 && tt < L) ? up[(size_t)(seq0 + tt) * 256 + ch] : 0.f; }
.LBB0_655:
	s_add_i32 s76, s54, s51
	s_lshl_b64 s[96:97], s[76:77], 10
	v_lshl_add_u64 v[36:37], v[0:1], 0, s[96:97]
	global_load_dword v19, v[36:37], off
	s_mov_b32 s97, 0x10820
	s_movk_i32 s96, 0x1000
	s_add_i32 s52, s45, 34
	s_cmp_ge_u32 s52, s44
	v_mov_b32_e32 v64, 0
	s_cbranch_scc0 .LBB0_579
	s_branch .LBB0_580

; template <int W> __device__ __forceinline__ void pool_win(const float* up, int seq0, int L, int tfirst, int ch, LAS float* Pout) {
;     ...
;     for (int j = 0; j < NV; ++j) { const int tt = tfirst - LO + j; u[j] = (tt >= 0 && tt < L) ? up[(size_t)(seq0 + tt) * 256 + ch] : 0.f; }
.LBB0_657:
	s_add_i32 s76, s15, s51
	s_lshl_b64 s[96:97], s[76:77], 10
	v_lshl_add_u64 v[10:11], v[0:1], 0, s[96:97]
	global_load_dword v6, v[10:11], off
	s_mov_b32 s97, 0x10820
	s_movk_i32 s96, 0x1000
	s_or_b32 s14, s45, 31
	s_cmp_ge_u32 s14, s44
	v_mov_b32_e32 v5, 0
	s_cbranch_scc0 .LBB0_647
	s_branch .LBB0_648

; template <int W> __device__ __forceinline__ void pool_win(const float* up, int seq0, int L, int tfirst, int ch, LAS float* Pout) {
;     ...
;     for (int j = 0; j < NV; ++j) { const int tt = tfirst - LO + j; u[j] = (tt >= 0 && tt < L) ? up[(size_t)(seq0 + tt) * 256 + ch] : 0.f; }
.LBB0_659:
	s_add_i32 s76, s14, s51
	s_lshl_b64 s[14:15], s[76:77], 10
	v_lshl_add_u64 v[6:7], v[0:1], 0, s[14:15]
	global_load_dword v13, v[6:7], off
	v_mov_b32_e32 v52, 0
	s_cmp_ge_u32 s45, s44
	v_mov_b32_e32 v54, 0
	s_cbranch_scc0 .LBB0_653

; #define LAS __attribute__((address_space(3)))
; #define LAS __attribute__((address_space(3)))
; template <int W> __device__ __forceinline__ void pool_win(const float* up, int seq0, int L, int tfirst, int ch, LAS float* Pout) {
;     constexpr int LO = W / 2, HI = W - W / 2, NV = 31 + W;
;     float u[NV];
; #pragma unroll
;     for (int j = 0; j < NV; ++j) { const int tt = tfirst - LO + j; u[j] = (tt >= 0 && tt < L) ? up[(size_t)(seq0 + tt) * 256 + ch] : 0.f; }
;     float c[NV + 1]; c[0] = 0.f;
; #pragma unroll
;     for (int j = 0; j < NV; ++j) c[j + 1] = c[j] + u[j];
.LBB0_661:
	s_add_i32 s76, s84, s51
	s_lshl_b64 s[14:15], s[76:77], 10
	v_lshl_add_u64 v[6:7], v[0:1], 0, s[14:15]
	global_load_dword v52, v[6:7], off
.LBB0_662:
	s_or_b32 s81, s45, 2
	v_mov_b32_e32 v48, 0
	s_cmp_ge_u32 s81, s44
	v_mov_b32_e32 v50, 0
	s_cbranch_scc1 .LBB0_664
	s_add_i32 s76, s81, s51
	s_lshl_b64 s[14:15], s[76:77], 10
	v_lshl_add_u64 v[6:7], v[0:1], 0, s[14:15]
	global_load_dword v50, v[6:7], off
.LBB0_664:
	s_or_b32 s80, s45, 3
	s_cmp_ge_u32 s80, s44
	s_cbranch_scc1 .LBB0_666
	s_add_i32 s76, s80, s51
	s_lshl_b64 s[14:15], s[76:77], 10
	v_lshl_add_u64 v[6:7], v[0:1], 0, s[14:15]
	global_load_dword v48, v[6:7], off
.LBB0_666:
	s_or_b32 s75, s45, 4
	v_mov_b32_e32 v45, 0
	s_cmp_ge_u32 s75, s44
	v_mov_b32_e32 v46, 0
	s_cbranch_scc1 .LBB0_668
	s_add_i32 s76, s75, s51
	s_lshl_b64 s[14:15], s[76:77], 10
	v_lshl_add_u64 v[6:7], v[0:1], 0, s[14:15]
	global_load_dword v46, v[6:7], off
.LBB0_668:
	s_or_b32 s74, s45, 5
	s_cmp_ge_u32 s74, s44
	s_cbranch_scc1 .LBB0_670
	s_add_i32 s76, s74, s51
	s_lshl_b64 s[14:15], s[76:77], 10
	v_lshl_add_u64 v[6:7], v[0:1], 0, s[14:15]
	global_load_dword v45, v[6:7], off
.LBB0_670:
	s_or_b32 s61, s45, 6
	v_mov_b32_e32 v42, 0
	s_cmp_ge_u32 s61, s44
	v_mov_b32_e32 v43, 0
	s_cbranch_scc1 .LBB0_672
	s_add_i32 s76, s61, s51
	s_lshl_b64 s[14:15], s[76:77], 10
	v_lshl_add_u64 v[6:7], v[0:1], 0, s[14:15]
	global_load_dword v43, v[6:7], off
.LBB0_672:
	s_or_b32 s60, s45, 7
	s_cmp_ge_u32 s60, s44
	s_cbranch_scc1 .LBB0_674
	s_add_i32 s76, s60, s51
	s_lshl_b64 s[14:15], s[76:77], 10
	v_lshl_add_u64 v[6:7], v[0:1], 0, s[14:15]
	global_load_dword v42, v[6:7], off
.LBB0_674:
	s_or_b32 s73, s45, 8
	v_mov_b32_e32 v38, 0
	s_cmp_ge_u32 s73, s44
	v_mov_b32_e32 v40, 0
	s_cbranch_scc1 .LBB0_676
	s_add_i32 s76, s73, s51
	s_lshl_b64 s[14:15], s[76:77], 10
	v_lshl_add_u64 v[6:7], v[0:1], 0, s[14:15]
	global_load_dword v40, v[6:7], off
.LBB0_676:
	s_or_b32 s72, s45, 9
	s_cmp_ge_u32 s72, s44
	s_cbranch_scc1 .LBB0_678
	s_add_i32 s76, s72, s51
	s_lshl_b64 s[14:15], s[76:77], 10
	v_lshl_add_u64 v[6:7], v[0:1], 0, s[14:15]
	global_load_dword v38, v[6:7], off
.LBB0_678:
	s_or_b32 s55, s45, 10
	v_mov_b32_e32 v36, 0
	s_cmp_ge_u32 s55, s44
	v_mov_b32_e32 v37, 0
	s_cbranch_scc1 .LBB0_680
	s_add_i32 s76, s55, s51
	s_lshl_b64 s[14:15], s[76:77], 10
	v_lshl_add_u64 v[6:7], v[0:1], 0, s[14:15]
	global_load_dword v37, v[6:7], off
.LBB0_680:
	s_or_b32 s71, s45, 11
	s_cmp_ge_u32 s71, s44
	s_cbranch_scc1 .LBB0_682
	s_add_i32 s76, s71, s51
	s_lshl_b64 s[14:15], s[76:77], 10
	v_lshl_add_u64 v[6:7], v[0:1], 0, s[14:15]
	global_load_dword v36, v[6:7], off
.LBB0_682:
	s_or_b32 s70, s45, 12
	v_mov_b32_e32 v32, 0
	s_cmp_ge_u32 s70, s44
	v_mov_b32_e32 v34, 0
	s_cbranch_scc1 .LBB0_684
	s_add_i32 s76, s70, s51
	s_lshl_b64 s[14:15], s[76:77], 10
	v_lshl_add_u64 v[6:7], v[0:1], 0, s[14:15]
	global_load_dword v34, v[6:7], off
.LBB0_684:
	s_or_b32 s69, s45, 13
	s_cmp_ge_u32 s69, s44
	s_cbranch_scc1 .LBB0_686
	s_add_i32 s76, s69, s51
	s_lshl_b64 s[14:15], s[76:77], 10
	v_lshl_add_u64 v[6:7], v[0:1], 0, s[14:15]
	global_load_dword v32, v[6:7], off
.LBB0_686:
	s_or_b32 s68, s45, 14
	v_mov_b32_e32 v29, 0
	s_cmp_ge_u32 s68, s44
	v_mov_b32_e32 v31, 0
	s_cbranch_scc1 .LBB0_688
	s_add_i32 s76, s68, s51
	s_lshl_b64 s[14:15], s[76:77], 10
	v_lshl_add_u64 v[6:7], v[0:1], 0, s[14:15]
	global_load_dword v31, v[6:7], off
.LBB0_688:
	s_or_b32 s67, s45, 15
	s_cmp_ge_u32 s67, s44
	s_cbranch_scc1 .LBB0_690
	s_add_i32 s76, s67, s51
	s_lshl_b64 s[14:15], s[76:77], 10
	v_lshl_add_u64 v[6:7], v[0:1], 0, s[14:15]
	global_load_dword v29, v[6:7], off
.LBB0_690:
	s_or_b32 s66, s45, 16
	v_mov_b32_e32 v26, 0
	s_cmp_ge_u32 s66, s44
	v_mov_b32_e32 v28, 0
	s_cbranch_scc1 .LBB0_692
	s_add_i32 s76, s66, s51
	s_lshl_b64 s[14:15], s[76:77], 10
	v_lshl_add_u64 v[6:7], v[0:1], 0, s[14:15]
	global_load_dword v28, v[6:7], off
.LBB0_692:
	s_or_b32 s65, s45, 17
	s_cmp_ge_u32 s65, s44
	s_cbranch_scc1 .LBB0_694
	s_add_i32 s76, s65, s51
	s_lshl_b64 s[14:15], s[76:77], 10
	v_lshl_add_u64 v[6:7], v[0:1], 0, s[14:15]
	global_load_dword v26, v[6:7], off
.LBB0_694:
	s_or_b32 s64, s45, 18
	v_mov_b32_e32 v23, 0
	s_cmp_ge_u32 s64, s44
	v_mov_b32_e32 v25, 0
	s_cbranch_scc1 .LBB0_696
	s_add_i32 s76, s64, s51
	s_lshl_b64 s[14:15], s[76:77], 10
	v_lshl_add_u64 v[6:7], v[0:1], 0, s[14:15]
	global_load_dword v25, v[6:7], off
.LBB0_696:
	s_or_b32 s63, s45, 19
	s_cmp_ge_u32 s63, s44
	s_cbranch_scc1 .LBB0_698
	s_add_i32 s76, s63, s51
	s_lshl_b64 s[14:15], s[76:77], 10
	v_lshl_add_u64 v[6:7], v[0:1], 0, s[14:15]
	global_load_dword v23, v[6:7], off
.LBB0_698:
	s_or_b32 s62, s45, 20
	v_mov_b32_e32 v19, 0
	s_cmp_ge_u32 s62, s44
	v_mov_b32_e32 v21, 0
	s_cbranch_scc1 .LBB0_700
	s_add_i32 s76, s62, s51
	s_lshl_b64 s[14:15], s[76:77], 10
	v_lshl_add_u64 v[6:7], v[0:1], 0, s[14:15]
	global_load_dword v21, v[6:7], off
.LBB0_700:
	s_or_b32 s59, s45, 21
	s_cmp_ge_u32 s59, s44
	s_cbranch_scc1 .LBB0_702
	s_add_i32 s76, s59, s51
	s_lshl_b64 s[14:15], s[76:77], 10
	v_lshl_add_u64 v[6:7], v[0:1], 0, s[14:15]
	global_load_dword v19, v[6:7], off
.LBB0_702:
	s_or_b32 s58, s45, 22
	v_mov_b32_e32 v15, 0
	s_cmp_ge_u32 s58, s44
	v_mov_b32_e32 v18, 0
	s_cbranch_scc1 .LBB0_704
	s_add_i32 s76, s58, s51
	s_lshl_b64 s[14:15], s[76:77], 10
	v_lshl_add_u64 v[6:7], v[0:1], 0, s[14:15]
	global_load_dword v18, v[6:7], off
.LBB0_704:
	s_or_b32 s57, s45, 23
	s_cmp_ge_u32 s57, s44
	s_cbranch_scc1 .LBB0_706
	s_add_i32 s76, s57, s51
	s_lshl_b64 s[14:15], s[76:77], 10
	v_lshl_add_u64 v[6:7], v[0:1], 0, s[14:15]
	global_load_dword v15, v[6:7], off
.LBB0_706:
	s_or_b32 s56, s45, 24
	v_mov_b32_e32 v11, 0
	s_cmp_ge_u32 s56, s44
	v_mov_b32_e32 v12, 0
	s_cbranch_scc1 .LBB0_708
	s_add_i32 s76, s56, s51
	s_lshl_b64 s[14:15], s[76:77], 10
	v_lshl_add_u64 v[6:7], v[0:1], 0, s[14:15]
	global_load_dword v12, v[6:7], off
.LBB0_708:
	s_or_b32 s54, s45, 25
	s_cmp_ge_u32 s54, s44
	s_cbranch_scc1 .LBB0_710
	s_add_i32 s76, s54, s51
	s_lshl_b64 s[14:15], s[76:77], 10
	v_lshl_add_u64 v[6:7], v[0:1], 0, s[14:15]
	global_load_dword v11, v[6:7], off

; template <int W> __device__ __forceinline__ void pool_win(const float* up, int seq0, int L, int tfirst, int ch, LAS float* Pout) {
;     ...
;     for (int j = 0; j < NV; ++j) { const int tt = tfirst - LO + j; u[j] = (tt >= 0 && tt < L) ? up[(size_t)(seq0 + tt) * 256 + ch] : 0.f; }
.LBB0_712:
	s_or_b32 s52, s45, 27
	s_cmp_ge_u32 s52, s44
	s_cbranch_scc1 .LBB0_714
	s_add_i32 s76, s52, s51
	s_lshl_b64 s[14:15], s[76:77], 10
	v_lshl_add_u64 v[6:7], v[0:1], 0, s[14:15]
	global_load_dword v9, v[6:7], off
.LBB0_714:
	s_or_b32 s49, s45, 28
	v_mov_b32_e32 v7, 0
	s_cmp_ge_u32 s49, s44
	v_mov_b32_e32 v8, 0
	s_cbranch_scc1 .LBB0_716
	s_add_i32 s76, s49, s51
	s_lshl_b64 s[14:15], s[76:77], 10
	v_lshl_add_u64 v[16:17], v[0:1], 0, s[14:15]
	global_load_dword v8, v[16:17], off

; template <int W> __device__ __forceinline__ void pool_win(const float* up, int seq0, int L, int tfirst, int ch, LAS float* Pout) {
;     ...
;     for (int j = 0; j < NV; ++j) { const int tt = tfirst - LO + j; u[j] = (tt >= 0 && tt < L) ? up[(size_t)(seq0 + tt) * 256 + ch] : 0.f; }
.LBB0_718:
	s_or_b32 s15, s45, 30
	v_mov_b32_e32 v5, 0
	s_cmp_ge_u32 s15, s44
	v_mov_b32_e32 v6, 0
	s_cbranch_scc1 .LBB0_851
	s_add_i32 s76, s15, s51
	s_lshl_b64 s[96:97], s[76:77], 10
	v_lshl_add_u64 v[16:17], v[0:1], 0, s[96:97]
	global_load_dword v6, v[16:17], off
	s_mov_b32 s97, 0x10820
	s_movk_i32 s96, 0x1000
	s_or_b32 s14, s45, 31
	s_cmp_ge_u32 s14, s44
	s_cbranch_scc0 .LBB0_852

; template <int W> __device__ __forceinline__ void pool_win(const float* up, int seq0, int L, int tfirst, int ch, LAS float* Pout) {
;     ...
;     for (int j = 0; j < NV; ++j) { const int tt = tfirst - LO + j; u[j] = (tt >= 0 && tt < L) ? up[(size_t)(seq0 + tt) * 256 + ch] : 0.f; }
.LBB0_721:
	s_add_i32 s76, s37, s51
	s_lshl_b64 s[96:97], s[76:77], 10
	v_lshl_add_u64 v[0:1], v[0:1], 0, s[96:97]
	global_load_dword v57, v[0:1], off
	s_mov_b32 s97, 0x10820
	s_movk_i32 s96, 0x1000

; #define LAS __attribute__((address_space(3)))
; #define LAS __attribute__((address_space(3)))
; __device__ __forceinline__ unsigned pkbf(float lo, float hi) { return pg8::cvt_pk_bf16(lo, hi); }
; template <int W> __device__ __forceinline__ void pool_win(const float* up, int seq0, int L, int tfirst, int ch, LAS float* Pout) {
;     ...
;         Pout[i * PPITCH] = (c[i + W] - c[i]) * __builtin_amdgcn_rcpf((float)(hi - lo)) - u[i + LO];
;     }
; }
; __device__ __forceinline__ void pool_unit(LAS unsigned char* lds, const float* upool, const float* pw  , const float* pscale, bf16_t* mix, int row0) {
;     int tid_l = threadIdx.x; asm volatile("" : "+v"(tid_l)); const int tid = tid_l, lane = tid & 63, wid = __builtin_amdgcn_readfirstlane(tid >> 6);
;     LAS float* P = (LAS float*)lds;
;     int seq0, L;
;     if (row0 < MLAT) { seq0 = row0 & ~(SEQ - 1); L = SEQ; } else { seq0 = MLAT + ((row0 - MLAT) & ~(CTXL - 1)); L = CTXL; }
;     const int g = wid & 3, half = wid >> 2;
;     {
;         const int ch = g * 64 + lane, tfirst = row0 - seq0 + half * 32;
;         LAS float* Pout = P + (half * 32) * PPITCH + ch;
;         if (g == 0) pool_win<2>(upool, seq0, L, tfirst, ch, Pout);
;         else if (g == 1) pool_win<4>(upool, seq0, L, tfirst, ch, Pout);
;         else if (g == 2) pool_win<8>(upool, seq0, L, tfirst, ch, Pout);
;         else pool_win<16>(upool, seq0, L, tfirst, ch, Pout);
;     }
;     const int r = lane & 31, h = lane >> 5;
;     bf16x8 bw[4][2];
; #pragma unroll
;     for (int ks = 0; ks < 4; ++ks)
; #pragma unroll
;         for (int nt = 0; nt < 2; ++nt) {
;             const float* wp = pw + (size_t)(g * 64 + 16 * ks + 8 * h) * 64 + 32 * nt + r;
;             u32x4 w; w.x = pkbf(wp[0], wp[64]); w.y = pkbf(wp[128], wp[192]); w.z = pkbf(wp[256], wp[320]); w.w = pkbf(wp[384], wp[448]);
;             bw[ks][nt] = __builtin_bit_cast(bf16x8, w);
;         }
;     const float sc0 = pscale[g * 64 + r], sc1 = pscale[g * 64 + 32 + r];
;     __syncthreads();
;     {
;         f32x16 d0, d1;
; #pragma unroll
;         for (int i = 0; i < 16; ++i) { d0[i] = 0.f; d1[i] = 0.f; }
;         const LAS float* pa = P + (half * 32 + r) * PPITCH + g * 64 + 8 * h;
.LBB0_723:
	v_cvt_f32_i32_e32 v0, s36
	v_and_b32_e32 v32, 31, v2
	v_lshrrev_b32_e32 v68, 5, v3
	v_lshlrev_b32_e32 v176, 2, v32
	v_rcp_iflag_f32_e32 v0, v0
	v_lshlrev_b32_e32 v3, 11, v68
	s_movk_i32 s0, 0x3000
	v_fma_f32 v0, v6, v0, -v5
	ds_write_b32 v4, v0 offset:32240
	v_lshl_add_u64 v[0:1], s[6:7], 0, v[176:177]
	v_lshl_or_b32 v176, s43, 14, v3
	v_lshl_add_u64 v[0:1], v[0:1], 0, v[176:177]
	global_load_dword v198, v[0:1], off offset:256
	global_load_dword v199, v[0:1], off
	v_lshlrev_b32_e32 v176, 1, v32
	global_load_dword v200, v[0:1], off offset:768
	global_load_dword v201, v[0:1], off offset:512
	global_load_dword v202, v[0:1], off offset:1280
	global_load_dword v203, v[0:1], off offset:1024
	global_load_dword v204, v[0:1], off offset:1792
	global_load_dword v205, v[0:1], off offset:1536
	global_load_dword v206, v[0:1], off offset:384
	global_load_dword v207, v[0:1], off offset:128
	global_load_dword v208, v[0:1], off offset:896
	global_load_dword v209, v[0:1], off offset:640
	global_load_dword v210, v[0:1], off offset:1408
	global_load_dword v211, v[0:1], off offset:1152
	global_load_dword v212, v[0:1], off offset:1920
	global_load_dword v213, v[0:1], off offset:1664
	s_waitcnt vmcnt(0)
	v_cvt_pk_bf16_f32 v4, v199, v198
	v_cvt_pk_bf16_f32 v5, v201, v200
	v_cvt_pk_bf16_f32 v6, v203, v202
	v_cvt_pk_bf16_f32 v7, v205, v204
	v_cvt_pk_bf16_f32 v16, v207, v206
	v_cvt_pk_bf16_f32 v17, v209, v208
	v_cvt_pk_bf16_f32 v18, v211, v210
	v_cvt_pk_bf16_f32 v19, v213, v212
	v_add_co_u32_e32 v8, vcc, s96, v0
	s_nop 1
	v_addc_co_u32_e32 v9, vcc, 0, v1, vcc
	v_add_co_u32_e32 v10, vcc, s48, v0
	global_load_dword v198, v[8:9], off offset:256
	s_nop 0
	v_addc_co_u32_e32 v11, vcc, 0, v1, vcc
	global_load_dword v199, v[10:11], off offset:-4096
	global_load_dword v200, v[8:9], off offset:768
	global_load_dword v201, v[8:9], off offset:512
	v_add_co_u32_e32 v0, vcc, s0, v0
	s_movk_i32 s0, 0x410
	s_nop 0
	v_addc_co_u32_e32 v1, vcc, 0, v1, vcc
	global_load_dword v202, v[8:9], off offset:1280
	global_load_dword v203, v[8:9], off offset:1024
	global_load_dword v204, v[8:9], off offset:1792
	global_load_dword v205, v[8:9], off offset:1536
	global_load_dword v206, v[8:9], off offset:384
	global_load_dword v207, v[8:9], off offset:128
	global_load_dword v208, v[8:9], off offset:896
	global_load_dword v209, v[8:9], off offset:640
	global_load_dword v210, v[8:9], off offset:1408
	global_load_dword v211, v[8:9], off offset:1152
	global_load_dword v212, v[8:9], off offset:1920
	s_nop 0
	global_load_dword v213, v[8:9], off offset:1664
	s_waitcnt vmcnt(0)
	v_cvt_pk_bf16_f32 v36, v199, v198
	v_cvt_pk_bf16_f32 v37, v201, v200
	v_cvt_pk_bf16_f32 v38, v203, v202
	v_cvt_pk_bf16_f32 v39, v205, v204
	v_cvt_pk_bf16_f32 v40, v207, v206
	v_cvt_pk_bf16_f32 v41, v209, v208
	v_cvt_pk_bf16_f32 v42, v211, v210
	v_cvt_pk_bf16_f32 v43, v213, v212
	global_load_dword v198, v[10:11], off offset:256
	global_load_dword v199, v[10:11], off
	global_load_dword v200, v[10:11], off offset:768
	global_load_dword v201, v[10:11], off offset:512
	global_load_dword v202, v[10:11], off offset:1280
	global_load_dword v203, v[10:11], off offset:1024
	global_load_dword v204, v[10:11], off offset:1792
	global_load_dword v205, v[10:11], off offset:1536
	global_load_dword v206, v[10:11], off offset:384
	global_load_dword v207, v[10:11], off offset:128
	global_load_dword v208, v[10:11], off offset:896
	global_load_dword v209, v[10:11], off offset:640
	global_load_dword v210, v[10:11], off offset:1408
	global_load_dword v211, v[10:11], off offset:1152
	global_load_dword v212, v[10:11], off offset:1920
	global_load_dword v213, v[10:11], off offset:1664
	s_waitcnt vmcnt(0)
	v_cvt_pk_bf16_f32 v44, v199, v198
	v_cvt_pk_bf16_f32 v45, v201, v200
	v_cvt_pk_bf16_f32 v46, v203, v202
	v_cvt_pk_bf16_f32 v47, v205, v204
	v_cvt_pk_bf16_f32 v48, v207, v206
	v_cvt_pk_bf16_f32 v49, v209, v208
	v_cvt_pk_bf16_f32 v50, v211, v210
	v_cvt_pk_bf16_f32 v51, v213, v212
	global_load_dword v198, v[0:1], off offset:256
	global_load_dword v199, v[0:1], off
	global_load_dword v200, v[0:1], off offset:768
	global_load_dword v201, v[0:1], off offset:512
	global_load_dword v202, v[0:1], off offset:1280
	global_load_dword v203, v[0:1], off offset:1024
	global_load_dword v204, v[0:1], off offset:1792
	global_load_dword v205, v[0:1], off offset:1536
	global_load_dword v206, v[0:1], off offset:384
	global_load_dword v207, v[0:1], off offset:128
	global_load_dword v208, v[0:1], off offset:896
	global_load_dword v209, v[0:1], off offset:640
	global_load_dword v210, v[0:1], off offset:1408
	global_load_dword v211, v[0:1], off offset:1152
	global_load_dword v212, v[0:1], off offset:1920
	s_nop 0
	global_load_dword v213, v[0:1], off offset:1664
	v_and_b32_e32 v1, 32, v2
	s_waitcnt vmcnt(0)
	v_cvt_pk_bf16_f32 v52, v199, v198
	v_cvt_pk_bf16_f32 v53, v201, v200
	v_cvt_pk_bf16_f32 v54, v203, v202
	v_cvt_pk_bf16_f32 v55, v205, v204
	v_cvt_pk_bf16_f32 v56, v207, v206
	v_cvt_pk_bf16_f32 v57, v209, v208
	v_cvt_pk_bf16_f32 v58, v211, v210
	v_cvt_pk_bf16_f32 v59, v213, v212
	v_or_b32_e32 v0, s27, v32
	v_lshlrev_b32_e32 v0, 2, v0
	global_load_dword v34, v0, s[8:9]
	global_load_dword v35, v0, s[8:9] offset:128
	v_or_b32_e32 v0, s38, v32
	v_mul_lo_u32 v0, v0, s0
	s_lshl_b32 s0, s27, 2
	s_add_i32 s0, s0, 0
	v_add3_u32 v33, s0, v0, v1
	s_waitcnt lgkmcnt(0)
	s_barrier
; #define LAS __attribute__((address_space(3)))
; #define LAS __attribute__((address_space(3)))
; __device__ __forceinline__ unsigned pkbf(float lo, float hi) { return pg8::cvt_pk_bf16(lo, hi); }
; __device__ __forceinline__ void pool_unit(LAS unsigned char* lds, const float* upool, const float* pw  , const float* pscale, bf16_t* mix, int row0) {
;     ...
;     {
;         f32x16 d0, d1;
; #pragma unroll
;         for (int i = 0; i < 16; ++i) { d0[i] = 0.f; d1[i] = 0.f; }
;         const LAS float* pa = P + (half * 32 + r) * PPITCH + g * 64 + 8 * h;
; #pragma unroll
;         for (int ks = 0; ks < 4; ++ks) {
;             const f32x4 a0 = *(const LAS f32x4*)(pa + 16 * ks), a1 = *(const LAS f32x4*)(pa + 16 * ks + 4);
;             u32x4 w; w.x = pkbf(a0[0], a0[1]); w.y = pkbf(a0[2], a0[3]); w.z = pkbf(a1[0], a1[1]); w.w = pkbf(a1[2], a1[3]);
;             const bf16x8 af = __builtin_bit_cast(bf16x8, w);
;             d0 = __builtin_amdgcn_mfma_f32_32x32x16_bf16(af, bw[ks][0], d0, 0, 0, 0);
;             d1 = __builtin_amdgcn_mfma_f32_32x32x16_bf16(af, bw[ks][1], d1, 0, 0, 0);
;         }
;         bf16_t* ob = mix + (size_t)(row0 + half * 32) * DM + 512 + g * 64 + r;
; #pragma unroll
;         for (int i = 0; i < 16; ++i) {
;             const int tk = (i & 3) + 8 * (i >> 2) + 4 * h;
;             const unsigned bits = pkbf(d0[i] * sc0, d1[i] * sc1);
;             ob[(size_t)tk * DM] = (bf16_t)(bits & 0xffffu);
;             ob[(size_t)tk * DM + 32] = (bf16_t)(bits >> 16);
;         }
;     }
;     __syncthreads();
	ds_read_b128 v[0:3], v33
	ds_read_b128 v[8:11], v33 offset:16
	s_waitcnt lgkmcnt(1)
	v_cvt_pk_bf16_f32 v20, v0, v1
	v_cvt_pk_bf16_f32 v21, v2, v3
	s_waitcnt lgkmcnt(0)
	v_cvt_pk_bf16_f32 v22, v8, v9
	v_cvt_pk_bf16_f32 v23, v10, v11
	ds_read_b128 v[60:63], v33 offset:64
	ds_read_b128 v[64:67], v33 offset:80
	v_mfma_f32_32x32x16_bf16 v[0:15], v[20:23], v[4:7], 0
	s_waitcnt lgkmcnt(1)
	v_cvt_pk_bf16_f32 v60, v60, v61
	v_cvt_pk_bf16_f32 v61, v62, v63
	s_waitcnt lgkmcnt(0)
	v_cvt_pk_bf16_f32 v62, v64, v65
	v_cvt_pk_bf16_f32 v63, v66, v67
	s_add_i32 s0, s38, s26
	v_mfma_f32_32x32x16_bf16 v[16:31], v[20:23], v[16:19], 0
	s_ashr_i32 s1, s0, 31
	s_lshl_b64 s[0:1], s[0:1], 11
	s_add_u32 s0, s4, s0
	s_addc_u32 s1, s5, s1
	s_lshl_b32 s14, s27, 1
	s_add_u32 s0, s0, s14
	s_addc_u32 s1, s1, 0
	v_mfma_f32_32x32x16_bf16 v[0:15], v[60:63], v[36:39], v[0:15]
	s_mov_b64 s[14:15], 0
	v_mfma_f32_32x32x16_bf16 v[16:31], v[60:63], v[40:43], v[16:31]
	ds_read_b128 v[36:39], v33 offset:128
	ds_read_b128 v[40:43], v33 offset:144
	s_waitcnt lgkmcnt(1)
	v_cvt_pk_bf16_f32 v36, v36, v37
	v_cvt_pk_bf16_f32 v37, v38, v39
	s_waitcnt lgkmcnt(0)
	v_cvt_pk_bf16_f32 v38, v40, v41
	v_cvt_pk_bf16_f32 v39, v42, v43
	s_nop 0
	v_mfma_f32_32x32x16_bf16 v[0:15], v[36:39], v[44:47], v[0:15]
	v_mfma_f32_32x32x16_bf16 v[16:31], v[36:39], v[48:51], v[16:31]
	ds_read_b128 v[36:39], v33 offset:192
	ds_read_b128 v[40:43], v33 offset:208
	s_waitcnt lgkmcnt(1)
	v_cvt_pk_bf16_f32 v36, v36, v37
	v_cvt_pk_bf16_f32 v37, v38, v39
	s_waitcnt lgkmcnt(0)
	v_cvt_pk_bf16_f32 v38, v40, v41
	v_cvt_pk_bf16_f32 v39, v42, v43
	v_lshl_add_u64 v[32:33], s[0:1], 0, v[176:177]
	v_mfma_f32_32x32x16_bf16 v[0:15], v[36:39], v[52:55], v[0:15]
	v_lshlrev_b32_e32 v176, 13, v68
	v_lshl_add_u64 v[32:33], v[32:33], 0, v[176:177]
	s_mov_b64 s[0:1], 0xe100400
	v_mfma_f32_32x32x16_bf16 v[16:31], v[36:39], v[56:59], v[16:31]
	v_lshl_add_u64 v[36:37], v[32:33], 0, s[0:1]
	s_mov_b32 s0, 0xe100000
	s_waitcnt vmcnt(1)
	s_nop 4
	v_mul_f32_e32 v0, v34, v0
	v_add_co_u32_e32 v38, vcc, s0, v32
	s_mov_b32 s0, 0xe101000
	s_nop 0
	v_addc_co_u32_e32 v39, vcc, 0, v33, vcc
	s_waitcnt vmcnt(0)
	v_mul_f32_e32 v16, v35, v16
	v_cvt_pk_bf16_f32 v0, v0, v16
	global_store_short v[38:39], v0, off offset:1024
	global_store_short_d16_hi v[36:37], v0, off offset:64
	v_mul_f32_e32 v0, v34, v1
	v_mul_f32_e32 v1, v35, v17
	v_cvt_pk_bf16_f32 v0, v0, v1
	global_store_short v[36:37], v0, off offset:2048
	global_store_short_d16_hi v[36:37], v0, off offset:2112
	v_mul_f32_e32 v0, v34, v2
	v_mul_f32_e32 v1, v35, v18
	v_cvt_pk_bf16_f32 v2, v0, v1
	v_add_co_u32_e32 v0, vcc, s0, v32
	s_mov_b32 s0, 0xe104000
	s_nop 0
	v_addc_co_u32_e32 v1, vcc, 0, v33, vcc
	global_store_short v[0:1], v2, off offset:1024
	global_store_short_d16_hi v[0:1], v2, off offset:1088
	v_mul_f32_e32 v2, v34, v3
	v_mul_f32_e32 v3, v35, v19
	v_cvt_pk_bf16_f32 v2, v2, v3
	global_store_short v[0:1], v2, off offset:3072
	global_store_short_d16_hi v[0:1], v2, off offset:3136
	v_mul_f32_e32 v0, v34, v4
	v_mul_f32_e32 v1, v35, v20
	v_cvt_pk_bf16_f32 v2, v0, v1
	v_add_co_u32_e32 v0, vcc, s0, v32
	v_mul_f32_e32 v3, v35, v21
	s_nop 0
	v_addc_co_u32_e32 v1, vcc, 0, v33, vcc
	global_store_short v[0:1], v2, off offset:1024
	global_store_short_d16_hi v[0:1], v2, off offset:1088
	v_mul_f32_e32 v2, v34, v5
	v_cvt_pk_bf16_f32 v2, v2, v3
	global_store_short v[0:1], v2, off offset:3072
	global_store_short_d16_hi v[0:1], v2, off offset:3136
	v_mul_f32_e32 v0, v34, v6
	s_mov_b32 s0, 0xe105000
	v_mul_f32_e32 v1, v35, v22
	v_cvt_pk_bf16_f32 v2, v0, v1
	v_add_co_u32_e32 v0, vcc, s0, v32
	v_mul_f32_e32 v3, v35, v23
	s_nop 0
	v_addc_co_u32_e32 v1, vcc, 0, v33, vcc
	global_store_short v[0:1], v2, off offset:1024
	global_store_short_d16_hi v[0:1], v2, off offset:1088
	v_mul_f32_e32 v2, v34, v7
	v_cvt_pk_bf16_f32 v2, v2, v3
	global_store_short v[0:1], v2, off offset:3072
	global_store_short_d16_hi v[0:1], v2, off offset:3136
	v_mul_f32_e32 v0, v34, v8
	s_mov_b32 s0, 0xe108000
	v_mul_f32_e32 v1, v35, v24
	v_cvt_pk_bf16_f32 v2, v0, v1
	v_add_co_u32_e32 v0, vcc, s0, v32
	v_mul_f32_e32 v3, v35, v25
	s_nop 0
	v_addc_co_u32_e32 v1, vcc, 0, v33, vcc
	global_store_short v[0:1], v2, off offset:1024
	global_store_short_d16_hi v[0:1], v2, off offset:1088
	v_mul_f32_e32 v2, v34, v9
	v_cvt_pk_bf16_f32 v2, v2, v3
	global_store_short v[0:1], v2, off offset:3072
	global_store_short_d16_hi v[0:1], v2, off offset:3136
	v_mul_f32_e32 v0, v34, v10
	s_mov_b32 s0, 0xe109000
	v_mul_f32_e32 v1, v35, v26
	v_cvt_pk_bf16_f32 v2, v0, v1
	v_add_co_u32_e32 v0, vcc, s0, v32
	v_mul_f32_e32 v3, v35, v27
	s_nop 0
	v_addc_co_u32_e32 v1, vcc, 0, v33, vcc
	global_store_short v[0:1], v2, off offset:1024
	global_store_short_d16_hi v[0:1], v2, off offset:1088
	v_mul_f32_e32 v2, v34, v11
	v_cvt_pk_bf16_f32 v2, v2, v3
	global_store_short v[0:1], v2, off offset:3072
	global_store_short_d16_hi v[0:1], v2, off offset:3136
	v_mul_f32_e32 v0, v34, v12
	s_mov_b32 s0, 0xe10c000
	v_mul_f32_e32 v1, v35, v28
	v_cvt_pk_bf16_f32 v2, v0, v1
	v_add_co_u32_e32 v0, vcc, s0, v32
	v_mul_f32_e32 v3, v35, v29
	s_nop 0
	v_addc_co_u32_e32 v1, vcc, 0, v33, vcc
	global_store_short v[0:1], v2, off offset:1024
	global_store_short_d16_hi v[0:1], v2, off offset:1088
	v_mul_f32_e32 v2, v34, v13
	v_cvt_pk_bf16_f32 v2, v2, v3
	global_store_short v[0:1], v2, off offset:3072
	global_store_short_d16_hi v[0:1], v2, off offset:3136
	v_mul_f32_e32 v0, v34, v14
	s_mov_b32 s0, 0xe10d000
	v_mul_f32_e32 v1, v35, v30
	v_cvt_pk_bf16_f32 v2, v0, v1
	v_add_co_u32_e32 v0, vcc, s0, v32
	v_mul_f32_e32 v3, v35, v31
	s_nop 0
	v_addc_co_u32_e32 v1, vcc, 0, v33, vcc
	global_store_short v[0:1], v2, off offset:1024
	global_store_short_d16_hi v[0:1], v2, off offset:1088
	v_mul_f32_e32 v2, v34, v15
	v_cvt_pk_bf16_f32 v2, v2, v3
	global_store_short v[0:1], v2, off offset:3072
	global_store_short_d16_hi v[0:1], v2, off offset:3136
	s_waitcnt lgkmcnt(0)
	s_barrier
; #define LAS __attribute__((address_space(3)))
; #define LAS __attribute__((address_space(3)))
; __device__ __forceinline__ void conv_unit(LAS unsigned char* lds, const float* uconv, const float* cw  , const float* cb, const float* lng, const float* lnb, bf16_t* mix, int row0) {
;     int tid_l = threadIdx.x; asm volatile("" : "+v"(tid_l)); const int tid = tid_l, lane = tid & 63, wid = tid >> 6;
;     LAS float* Y = (LAS float*)lds;
;     int seq0, L;
;     if (row0 < MLAT) { seq0 = row0 & ~(SEQ - 1); L = SEQ; } else { seq0 = MLAT + ((row0 - MLAT) & ~(CTXL - 1)); L = CTXL; }
;     {
;         const int ch = tid & 255, half = tid >> 8;
;         const int t0 = row0 - seq0 + half * 32;
;         float uwin[62];
; #pragma unroll
;         for (int j = 0; j < 62; ++j) { const int tt = t0 - 15 + j; uwin[j] = (tt >= 0 && tt < L) ? uconv[(size_t)(seq0 + tt) * 256 + ch] : 0.f; }
.LBB0_724:
	s_and_b64 vcc, exec, s[14:15]
	s_cbranch_vccz .LBB0_850
	s_sub_i32 s0, s42, s28
	s_lshl_b32 s26, s0, 6
	s_cmpk_lt_i32 s0, 0x100
	s_movk_i32 s0, 0xe000
	v_mov_b32_e32 v2, v222
	s_cselect_b32 s0, s0, 0x7fffff00
	s_cselect_b32 s36, s48, 0x100
	s_and_b32 s27, s0, s26
	v_ashrrev_i32_e32 v3, 3, v2
	s_add_i32 s37, s26, -15
	v_and_b32_e32 v86, 0xffffffe0, v3
	s_sub_i32 s0, s37, s27
	v_add_u32_e32 v50, s0, v86
	v_lshlrev_b32_sdwa v176, v232, v2 dst_sel:DWORD dst_unused:UNUSED_PAD src0_sel:DWORD src1_sel:BYTE_0
	v_lshl_add_u64 v[0:1], s[10:11], 0, v[176:177]
	v_cmp_gt_u32_e32 vcc, s36, v50
	v_mov_b32_e32 v96, 0
	v_mov_b32_e32 v97, 0
	s_and_saveexec_b64 s[14:15], vcc
	s_cbranch_execz .LBB0_727
	v_add_u32_e32 v4, s37, v86
	v_ashrrev_i32_e32 v5, 31, v4
	v_lshlrev_b64 v[4:5], 10, v[4:5]
	v_lshl_add_u64 v[4:5], v[0:1], 0, v[4:5]
	global_load_dword v97, v[4:5], off
.LBB0_727:
	s_or_b64 exec, exec, s[14:15]
	v_add_u32_e32 v4, 1, v50
	v_cmp_gt_u32_e32 vcc, s36, v4
	s_and_saveexec_b64 s[14:15], vcc
	s_cbranch_execz .LBB0_729
	v_add_u32_e32 v4, s27, v4
	v_ashrrev_i32_e32 v5, 31, v4
	v_lshlrev_b64 v[4:5], 10, v[4:5]
	v_lshl_add_u64 v[4:5], v[0:1], 0, v[4:5]
	global_load_dword v96, v[4:5], off
.LBB0_729:
	s_or_b64 exec, exec, s[14:15]
	v_or_b32_e32 v4, 2, v50
	v_cmp_gt_u32_e32 vcc, s36, v4
	v_mov_b32_e32 v94, 0
	v_mov_b32_e32 v95, 0
	s_and_saveexec_b64 s[14:15], vcc
	s_cbranch_execz .LBB0_731
	v_add_u32_e32 v4, s27, v4
	v_ashrrev_i32_e32 v5, 31, v4
	v_lshlrev_b64 v[4:5], 10, v[4:5]
	v_lshl_add_u64 v[4:5], v[0:1], 0, v[4:5]
	global_load_dword v95, v[4:5], off
.LBB0_731:
	s_or_b64 exec, exec, s[14:15]
	v_add_u32_e32 v4, 3, v50
	v_cmp_gt_u32_e32 vcc, s36, v4
	s_and_saveexec_b64 s[14:15], vcc
	s_cbranch_execz .LBB0_733
	v_add_u32_e32 v4, s27, v4
	v_ashrrev_i32_e32 v5, 31, v4
	v_lshlrev_b64 v[4:5], 10, v[4:5]
	v_lshl_add_u64 v[4:5], v[0:1], 0, v[4:5]
	global_load_dword v94, v[4:5], off
.LBB0_733:
	s_or_b64 exec, exec, s[14:15]
	v_or_b32_e32 v4, 4, v50
	v_cmp_gt_u32_e32 vcc, s36, v4
	v_mov_b32_e32 v92, 0
	v_mov_b32_e32 v93, 0
	s_and_saveexec_b64 s[14:15], vcc
	s_cbranch_execz .LBB0_735
	v_add_u32_e32 v4, s27, v4
	v_ashrrev_i32_e32 v5, 31, v4
	v_lshlrev_b64 v[4:5], 10, v[4:5]
	v_lshl_add_u64 v[4:5], v[0:1], 0, v[4:5]
	global_load_dword v93, v[4:5], off
.LBB0_735:
	s_or_b64 exec, exec, s[14:15]
	v_add_u32_e32 v4, 5, v50
	v_cmp_gt_u32_e32 vcc, s36, v4
	s_and_saveexec_b64 s[14:15], vcc
	s_cbranch_execz .LBB0_737
	v_add_u32_e32 v4, s27, v4
	v_ashrrev_i32_e32 v5, 31, v4
	v_lshlrev_b64 v[4:5], 10, v[4:5]
	v_lshl_add_u64 v[4:5], v[0:1], 0, v[4:5]
	global_load_dword v92, v[4:5], off
.LBB0_737:
	s_or_b64 exec, exec, s[14:15]
	v_or_b32_e32 v4, 6, v50
	v_cmp_gt_u32_e32 vcc, s36, v4
	v_mov_b32_e32 v90, 0
	v_mov_b32_e32 v91, 0
	s_and_saveexec_b64 s[14:15], vcc
	s_cbranch_execz .LBB0_739
	v_add_u32_e32 v4, s27, v4
	v_ashrrev_i32_e32 v5, 31, v4
	v_lshlrev_b64 v[4:5], 10, v[4:5]
	v_lshl_add_u64 v[4:5], v[0:1], 0, v[4:5]
	global_load_dword v91, v[4:5], off
.LBB0_739:
	s_or_b64 exec, exec, s[14:15]
	v_add_u32_e32 v4, 7, v50
	v_cmp_gt_u32_e32 vcc, s36, v4
	s_and_saveexec_b64 s[14:15], vcc
	s_cbranch_execz .LBB0_741
	v_add_u32_e32 v4, s27, v4
	v_ashrrev_i32_e32 v5, 31, v4
	v_lshlrev_b64 v[4:5], 10, v[4:5]
	v_lshl_add_u64 v[4:5], v[0:1], 0, v[4:5]
	global_load_dword v90, v[4:5], off
.LBB0_741:
	s_or_b64 exec, exec, s[14:15]
	v_or_b32_e32 v4, 8, v50
	v_cmp_gt_u32_e32 vcc, s36, v4
	v_mov_b32_e32 v88, 0
	v_mov_b32_e32 v89, 0
	s_and_saveexec_b64 s[14:15], vcc
	s_cbranch_execz .LBB0_743
	v_add_u32_e32 v4, s27, v4
	v_ashrrev_i32_e32 v5, 31, v4
	v_lshlrev_b64 v[4:5], 10, v[4:5]
	v_lshl_add_u64 v[4:5], v[0:1], 0, v[4:5]
	global_load_dword v89, v[4:5], off
.LBB0_743:
	s_or_b64 exec, exec, s[14:15]
	v_add_u32_e32 v4, 9, v50
	v_cmp_gt_u32_e32 vcc, s36, v4
	s_and_saveexec_b64 s[14:15], vcc
	s_cbranch_execz .LBB0_745
	v_add_u32_e32 v4, s27, v4
	v_ashrrev_i32_e32 v5, 31, v4
	v_lshlrev_b64 v[4:5], 10, v[4:5]
	v_lshl_add_u64 v[4:5], v[0:1], 0, v[4:5]
	global_load_dword v88, v[4:5], off
.LBB0_745:
	s_or_b64 exec, exec, s[14:15]
	v_or_b32_e32 v4, 10, v50
	v_cmp_gt_u32_e32 vcc, s36, v4
	v_mov_b32_e32 v85, 0
	v_mov_b32_e32 v87, 0
	s_and_saveexec_b64 s[14:15], vcc
	s_cbranch_execz .LBB0_747
	v_add_u32_e32 v4, s27, v4
	v_ashrrev_i32_e32 v5, 31, v4
	v_lshlrev_b64 v[4:5], 10, v[4:5]
	v_lshl_add_u64 v[4:5], v[0:1], 0, v[4:5]
	global_load_dword v87, v[4:5], off
.LBB0_747:
	s_or_b64 exec, exec, s[14:15]
	v_add_u32_e32 v4, 11, v50
	v_cmp_gt_u32_e32 vcc, s36, v4
	s_and_saveexec_b64 s[14:15], vcc
	s_cbranch_execz .LBB0_749
	v_add_u32_e32 v4, s27, v4
	v_ashrrev_i32_e32 v5, 31, v4
	v_lshlrev_b64 v[4:5], 10, v[4:5]
	v_lshl_add_u64 v[4:5], v[0:1], 0, v[4:5]
	global_load_dword v85, v[4:5], off
.LBB0_749:
	s_or_b64 exec, exec, s[14:15]
	v_or_b32_e32 v4, 12, v50
	v_cmp_gt_u32_e32 vcc, s36, v4
	v_mov_b32_e32 v83, 0
	v_mov_b32_e32 v84, 0
	s_and_saveexec_b64 s[14:15], vcc
	s_cbranch_execz .LBB0_751
	v_add_u32_e32 v4, s27, v4
	v_ashrrev_i32_e32 v5, 31, v4
	v_lshlrev_b64 v[4:5], 10, v[4:5]
	v_lshl_add_u64 v[4:5], v[0:1], 0, v[4:5]
	global_load_dword v84, v[4:5], off
.LBB0_751:
	s_or_b64 exec, exec, s[14:15]
	v_add_u32_e32 v4, 13, v50
	v_cmp_gt_u32_e32 vcc, s36, v4
	s_and_saveexec_b64 s[14:15], vcc
	s_cbranch_execz .LBB0_753
	v_add_u32_e32 v4, s27, v4
	v_ashrrev_i32_e32 v5, 31, v4
	v_lshlrev_b64 v[4:5], 10, v[4:5]
	v_lshl_add_u64 v[4:5], v[0:1], 0, v[4:5]
	global_load_dword v83, v[4:5], off
.LBB0_753:
	s_or_b64 exec, exec, s[14:15]
	v_or_b32_e32 v4, 14, v50
	v_cmp_gt_u32_e32 vcc, s36, v4
	v_mov_b32_e32 v52, 0
	v_mov_b32_e32 v79, 0
	s_and_saveexec_b64 s[14:15], vcc
	s_cbranch_execz .LBB0_755
	v_add_u32_e32 v4, s27, v4
	v_ashrrev_i32_e32 v5, 31, v4
	v_lshlrev_b64 v[4:5], 10, v[4:5]
	v_lshl_add_u64 v[4:5], v[0:1], 0, v[4:5]
	global_load_dword v79, v[4:5], off
; __device__ __forceinline__ void conv_unit(LAS unsigned char* lds, const float* uconv, const float* cw  , const float* cb, const float* lng, const float* lnb, bf16_t* mix, int row0) {
;     ...
;         float uwin[62];
; #pragma unroll
;         for (int j = 0; j < 62; ++j) { const int tt = t0 - 15 + j; uwin[j] = (tt >= 0 && tt < L) ? uconv[(size_t)(seq0 + tt) * 256 + ch] : 0.f; }
.LBB0_755:
	s_or_b64 exec, exec, s[14:15]
	v_add_u32_e32 v4, 15, v50
	v_cmp_gt_u32_e32 vcc, s36, v4
	s_and_saveexec_b64 s[14:15], vcc
	s_cbranch_execz .LBB0_757
	v_add_u32_e32 v4, s27, v4
	v_ashrrev_i32_e32 v5, 31, v4
	v_lshlrev_b64 v[4:5], 10, v[4:5]
	v_lshl_add_u64 v[4:5], v[0:1], 0, v[4:5]
	global_load_dword v52, v[4:5], off
.LBB0_757:
	s_or_b64 exec, exec, s[14:15]
	v_add_u32_e32 v4, 16, v50
	v_cmp_gt_u32_e32 vcc, s36, v4
	v_mov_b32_e32 v48, 0
	v_mov_b32_e32 v49, 0
	s_and_saveexec_b64 s[14:15], vcc
	s_cbranch_execz .LBB0_759
	v_add_u32_e32 v4, s27, v4
	v_ashrrev_i32_e32 v5, 31, v4
	v_lshlrev_b64 v[4:5], 10, v[4:5]
	v_lshl_add_u64 v[4:5], v[0:1], 0, v[4:5]
	global_load_dword v49, v[4:5], off
.LBB0_759:
	s_or_b64 exec, exec, s[14:15]
	v_add_u32_e32 v4, 17, v50
	v_cmp_gt_u32_e32 vcc, s36, v4
	s_and_saveexec_b64 s[14:15], vcc
	s_cbranch_execz .LBB0_761
	v_add_u32_e32 v4, s27, v4
	v_ashrrev_i32_e32 v5, 31, v4
	v_lshlrev_b64 v[4:5], 10, v[4:5]
	v_lshl_add_u64 v[4:5], v[0:1], 0, v[4:5]
	global_load_dword v48, v[4:5], off
.LBB0_761:
	s_or_b64 exec, exec, s[14:15]
	v_add_u32_e32 v4, 18, v50
	v_cmp_gt_u32_e32 vcc, s36, v4
	v_mov_b32_e32 v42, 0
	v_mov_b32_e32 v46, 0
	s_and_saveexec_b64 s[14:15], vcc
	s_cbranch_execz .LBB0_763
	v_add_u32_e32 v4, s27, v4
	v_ashrrev_i32_e32 v5, 31, v4
	v_lshlrev_b64 v[4:5], 10, v[4:5]
	v_lshl_add_u64 v[4:5], v[0:1], 0, v[4:5]
	global_load_dword v46, v[4:5], off
.LBB0_763:
	s_or_b64 exec, exec, s[14:15]
	v_add_u32_e32 v4, 19, v50
	v_cmp_gt_u32_e32 vcc, s36, v4
	s_and_saveexec_b64 s[14:15], vcc
	s_cbranch_execz .LBB0_765
	v_add_u32_e32 v4, s27, v4
	v_ashrrev_i32_e32 v5, 31, v4
	v_lshlrev_b64 v[4:5], 10, v[4:5]
	v_lshl_add_u64 v[4:5], v[0:1], 0, v[4:5]
	global_load_dword v42, v[4:5], off
.LBB0_765:
	s_or_b64 exec, exec, s[14:15]
	v_add_u32_e32 v4, 20, v50
	v_cmp_gt_u32_e32 vcc, s36, v4
	v_mov_b32_e32 v36, 0
	v_mov_b32_e32 v39, 0
	s_and_saveexec_b64 s[14:15], vcc
	s_cbranch_execz .LBB0_767
	v_add_u32_e32 v4, s27, v4
	v_ashrrev_i32_e32 v5, 31, v4
	v_lshlrev_b64 v[4:5], 10, v[4:5]
	v_lshl_add_u64 v[4:5], v[0:1], 0, v[4:5]
	global_load_dword v39, v[4:5], off
.LBB0_767:
	s_or_b64 exec, exec, s[14:15]
	v_add_u32_e32 v4, 21, v50
	v_cmp_gt_u32_e32 vcc, s36, v4
	s_and_saveexec_b64 s[14:15], vcc
	s_cbranch_execz .LBB0_769
	v_add_u32_e32 v4, s27, v4
	v_ashrrev_i32_e32 v5, 31, v4
	v_lshlrev_b64 v[4:5], 10, v[4:5]
	v_lshl_add_u64 v[4:5], v[0:1], 0, v[4:5]
	global_load_dword v36, v[4:5], off
.LBB0_769:
	s_or_b64 exec, exec, s[14:15]
	v_add_u32_e32 v4, 22, v50
	v_cmp_gt_u32_e32 vcc, s36, v4
	v_mov_b32_e32 v28, 0
	v_mov_b32_e32 v33, 0
	s_and_saveexec_b64 s[14:15], vcc
	s_cbranch_execz .LBB0_771
	v_add_u32_e32 v4, s27, v4
	v_ashrrev_i32_e32 v5, 31, v4
	v_lshlrev_b64 v[4:5], 10, v[4:5]
	v_lshl_add_u64 v[4:5], v[0:1], 0, v[4:5]
	global_load_dword v33, v[4:5], off
.LBB0_771:
	s_or_b64 exec, exec, s[14:15]
	v_add_u32_e32 v4, 23, v50
	v_cmp_gt_u32_e32 vcc, s36, v4
	s_and_saveexec_b64 s[14:15], vcc
	s_cbranch_execz .LBB0_773
	v_add_u32_e32 v4, s27, v4
	v_ashrrev_i32_e32 v5, 31, v4
	v_lshlrev_b64 v[4:5], 10, v[4:5]
	v_lshl_add_u64 v[4:5], v[0:1], 0, v[4:5]
	global_load_dword v28, v[4:5], off
.LBB0_773:
	s_or_b64 exec, exec, s[14:15]
	v_add_u32_e32 v4, 24, v50
	v_cmp_gt_u32_e32 vcc, s36, v4
	v_mov_b32_e32 v22, 0
	v_mov_b32_e32 v27, 0
	s_and_saveexec_b64 s[14:15], vcc
	s_cbranch_execz .LBB0_775
	v_add_u32_e32 v4, s27, v4
	v_ashrrev_i32_e32 v5, 31, v4
	v_lshlrev_b64 v[4:5], 10, v[4:5]
	v_lshl_add_u64 v[4:5], v[0:1], 0, v[4:5]
	global_load_dword v27, v[4:5], off
.LBB0_775:
	s_or_b64 exec, exec, s[14:15]
	v_add_u32_e32 v4, 25, v50
	v_cmp_gt_u32_e32 vcc, s36, v4
	s_and_saveexec_b64 s[14:15], vcc
	s_cbranch_execz .LBB0_777
	v_add_u32_e32 v4, s27, v4
	v_ashrrev_i32_e32 v5, 31, v4
	v_lshlrev_b64 v[4:5], 10, v[4:5]
	v_lshl_add_u64 v[4:5], v[0:1], 0, v[4:5]
	global_load_dword v22, v[4:5], off
.LBB0_777:
	s_or_b64 exec, exec, s[14:15]
	v_add_u32_e32 v4, 26, v50
	v_cmp_gt_u32_e32 vcc, s36, v4
	v_mov_b32_e32 v16, 0
	v_mov_b32_e32 v21, 0
	s_and_saveexec_b64 s[14:15], vcc
	s_cbranch_execz .LBB0_779
	v_add_u32_e32 v4, s27, v4
	v_ashrrev_i32_e32 v5, 31, v4
	v_lshlrev_b64 v[4:5], 10, v[4:5]
	v_lshl_add_u64 v[4:5], v[0:1], 0, v[4:5]
	global_load_dword v21, v[4:5], off
.LBB0_779:
	s_or_b64 exec, exec, s[14:15]
	v_add_u32_e32 v4, 27, v50
	v_cmp_gt_u32_e32 vcc, s36, v4
	s_and_saveexec_b64 s[14:15], vcc
	s_cbranch_execz .LBB0_781
	v_add_u32_e32 v4, s27, v4
	v_ashrrev_i32_e32 v5, 31, v4
	v_lshlrev_b64 v[4:5], 10, v[4:5]
	v_lshl_add_u64 v[4:5], v[0:1], 0, v[4:5]
	global_load_dword v16, v[4:5], off
.LBB0_781:
	s_or_b64 exec, exec, s[14:15]
	v_add_u32_e32 v4, 28, v50
	v_cmp_gt_u32_e32 vcc, s36, v4
	v_mov_b32_e32 v10, 0
	v_mov_b32_e32 v13, 0
	s_and_saveexec_b64 s[14:15], vcc
	s_cbranch_execz .LBB0_783
	v_add_u32_e32 v4, s27, v4
	v_ashrrev_i32_e32 v5, 31, v4
	v_lshlrev_b64 v[4:5], 10, v[4:5]
	v_lshl_add_u64 v[4:5], v[0:1], 0, v[4:5]
	global_load_dword v13, v[4:5], off
.LBB0_783:
	s_or_b64 exec, exec, s[14:15]
	v_add_u32_e32 v4, 29, v50
	v_cmp_gt_u32_e32 vcc, s36, v4
	s_and_saveexec_b64 s[14:15], vcc
	s_cbranch_execz .LBB0_785
	v_add_u32_e32 v4, s27, v4
	v_ashrrev_i32_e32 v5, 31, v4
	v_lshlrev_b64 v[4:5], 10, v[4:5]
	v_lshl_add_u64 v[4:5], v[0:1], 0, v[4:5]
	global_load_dword v10, v[4:5], off
.LBB0_785:
	s_or_b64 exec, exec, s[14:15]
	v_add_u32_e32 v5, 30, v50
	v_cmp_gt_u32_e32 vcc, s36, v5
	v_mov_b32_e32 v4, 0
	v_mov_b32_e32 v7, 0
	s_and_saveexec_b64 s[14:15], vcc
	s_cbranch_execz .LBB0_787
	v_add_u32_e32 v6, s27, v5
	v_ashrrev_i32_e32 v7, 31, v6
	v_lshlrev_b64 v[6:7], 10, v[6:7]
	v_lshl_add_u64 v[6:7], v[0:1], 0, v[6:7]
	global_load_dword v7, v[6:7], off
; __device__ __forceinline__ void conv_unit(LAS unsigned char* lds, const float* uconv, const float* cw  , const float* cb, const float* lng, const float* lnb, bf16_t* mix, int row0) {
;     ...
;         float uwin[62];
; #pragma unroll
;         for (int j = 0; j < 62; ++j) { const int tt = t0 - 15 + j; uwin[j] = (tt >= 0 && tt < L) ? uconv[(size_t)(seq0 + tt) * 256 + ch] : 0.f; }
.LBB0_787:
	s_or_b64 exec, exec, s[14:15]
	v_add_u32_e32 v5, 31, v50
	v_cmp_gt_u32_e32 vcc, s36, v5
	s_and_saveexec_b64 s[14:15], vcc
	s_cbranch_execz .LBB0_789
	v_add_u32_e32 v4, s27, v5
	v_ashrrev_i32_e32 v5, 31, v4
	v_lshlrev_b64 v[4:5], 10, v[4:5]
	v_lshl_add_u64 v[4:5], v[0:1], 0, v[4:5]
	global_load_dword v4, v[4:5], off
.LBB0_789:
	s_or_b64 exec, exec, s[14:15]
	v_add_u32_e32 v8, 32, v50
	v_cmp_gt_u32_e32 vcc, s36, v8
	v_mov_b32_e32 v5, 0
	v_mov_b32_e32 v6, 0
	s_and_saveexec_b64 s[14:15], vcc
	s_cbranch_execz .LBB0_791
	v_add_u32_e32 v8, s27, v8
	v_ashrrev_i32_e32 v9, 31, v8
	v_lshlrev_b64 v[8:9], 10, v[8:9]
	v_lshl_add_u64 v[8:9], v[0:1], 0, v[8:9]
	global_load_dword v6, v[8:9], off
.LBB0_791:
	s_or_b64 exec, exec, s[14:15]
	v_add_u32_e32 v8, 33, v50
	v_cmp_gt_u32_e32 vcc, s36, v8
	s_and_saveexec_b64 s[14:15], vcc
	s_cbranch_execz .LBB0_793
	v_add_u32_e32 v8, s27, v8
	v_ashrrev_i32_e32 v9, 31, v8
	v_lshlrev_b64 v[8:9], 10, v[8:9]
	v_lshl_add_u64 v[8:9], v[0:1], 0, v[8:9]
	global_load_dword v5, v[8:9], off
.LBB0_793:
	s_or_b64 exec, exec, s[14:15]
	v_add_u32_e32 v11, 34, v50
	v_cmp_gt_u32_e32 vcc, s36, v11
	v_mov_b32_e32 v8, 0
	v_mov_b32_e32 v9, 0
	s_and_saveexec_b64 s[14:15], vcc
	s_cbranch_execz .LBB0_795
	v_add_u32_e32 v14, s27, v11
	v_ashrrev_i32_e32 v15, 31, v14
	v_lshlrev_b64 v[14:15], 10, v[14:15]
	v_lshl_add_u64 v[14:15], v[0:1], 0, v[14:15]
	global_load_dword v9, v[14:15], off
.LBB0_795:
	s_or_b64 exec, exec, s[14:15]
	v_add_u32_e32 v11, 35, v50
	v_cmp_gt_u32_e32 vcc, s36, v11
	s_and_saveexec_b64 s[14:15], vcc
	s_cbranch_execz .LBB0_797
	v_add_u32_e32 v14, s27, v11
	v_ashrrev_i32_e32 v15, 31, v14
	v_lshlrev_b64 v[14:15], 10, v[14:15]
	v_lshl_add_u64 v[14:15], v[0:1], 0, v[14:15]
	global_load_dword v8, v[14:15], off
.LBB0_797:
	s_or_b64 exec, exec, s[14:15]
	v_add_u32_e32 v14, 36, v50
	v_cmp_gt_u32_e32 vcc, s36, v14
	v_mov_b32_e32 v11, 0
	v_mov_b32_e32 v12, 0
	s_and_saveexec_b64 s[14:15], vcc
	s_cbranch_execz .LBB0_799
	v_add_u32_e32 v14, s27, v14
	v_ashrrev_i32_e32 v15, 31, v14
	v_lshlrev_b64 v[14:15], 10, v[14:15]
	v_lshl_add_u64 v[14:15], v[0:1], 0, v[14:15]
	global_load_dword v12, v[14:15], off
.LBB0_799:
	s_or_b64 exec, exec, s[14:15]
	v_add_u32_e32 v14, 37, v50
	v_cmp_gt_u32_e32 vcc, s36, v14
	s_and_saveexec_b64 s[14:15], vcc
	s_cbranch_execz .LBB0_801
	v_add_u32_e32 v14, s27, v14
	v_ashrrev_i32_e32 v15, 31, v14
	v_lshlrev_b64 v[14:15], 10, v[14:15]
	v_lshl_add_u64 v[14:15], v[0:1], 0, v[14:15]
	global_load_dword v11, v[14:15], off
.LBB0_801:
	s_or_b64 exec, exec, s[14:15]
	v_add_u32_e32 v17, 38, v50
	v_cmp_gt_u32_e32 vcc, s36, v17
	v_mov_b32_e32 v14, 0
	v_mov_b32_e32 v15, 0
	s_and_saveexec_b64 s[14:15], vcc
	s_cbranch_execz .LBB0_803
	v_add_u32_e32 v18, s27, v17
	v_ashrrev_i32_e32 v19, 31, v18
	v_lshlrev_b64 v[18:19], 10, v[18:19]
	v_lshl_add_u64 v[18:19], v[0:1], 0, v[18:19]
	global_load_dword v15, v[18:19], off
.LBB0_803:
	s_or_b64 exec, exec, s[14:15]
	v_add_u32_e32 v17, 39, v50
	v_cmp_gt_u32_e32 vcc, s36, v17
	s_and_saveexec_b64 s[14:15], vcc
	s_cbranch_execz .LBB0_805
	v_add_u32_e32 v18, s27, v17
	v_ashrrev_i32_e32 v19, 31, v18
	v_lshlrev_b64 v[18:19], 10, v[18:19]
	v_lshl_add_u64 v[18:19], v[0:1], 0, v[18:19]
	global_load_dword v14, v[18:19], off
.LBB0_805:
	s_or_b64 exec, exec, s[14:15]
	v_add_u32_e32 v19, 40, v50
	v_cmp_gt_u32_e32 vcc, s36, v19
	v_mov_b32_e32 v17, 0
	v_mov_b32_e32 v18, 0
	s_and_saveexec_b64 s[14:15], vcc
	s_cbranch_execz .LBB0_807
	v_add_u32_e32 v18, s27, v19
	v_ashrrev_i32_e32 v19, 31, v18
	v_lshlrev_b64 v[18:19], 10, v[18:19]
	v_lshl_add_u64 v[18:19], v[0:1], 0, v[18:19]
	global_load_dword v18, v[18:19], off
.LBB0_807:
	s_or_b64 exec, exec, s[14:15]
	v_add_u32_e32 v19, 41, v50
	v_cmp_gt_u32_e32 vcc, s36, v19
	s_and_saveexec_b64 s[14:15], vcc
	s_cbranch_execz .LBB0_809
	v_add_u32_e32 v24, s27, v19
	v_ashrrev_i32_e32 v25, 31, v24
	v_lshlrev_b64 v[24:25], 10, v[24:25]
	v_lshl_add_u64 v[24:25], v[0:1], 0, v[24:25]
	global_load_dword v17, v[24:25], off
.LBB0_809:
	s_or_b64 exec, exec, s[14:15]
	v_add_u32_e32 v23, 42, v50
	v_cmp_gt_u32_e32 vcc, s36, v23
	v_mov_b32_e32 v19, 0
	v_mov_b32_e32 v20, 0
	s_and_saveexec_b64 s[14:15], vcc
	s_cbranch_execz .LBB0_811
	v_add_u32_e32 v24, s27, v23
	v_ashrrev_i32_e32 v25, 31, v24
	v_lshlrev_b64 v[24:25], 10, v[24:25]
	v_lshl_add_u64 v[24:25], v[0:1], 0, v[24:25]
	global_load_dword v20, v[24:25], off
.LBB0_811:
	s_or_b64 exec, exec, s[14:15]
	v_add_u32_e32 v23, 43, v50
	v_cmp_gt_u32_e32 vcc, s36, v23
	s_and_saveexec_b64 s[14:15], vcc
	s_cbranch_execz .LBB0_813
	v_add_u32_e32 v24, s27, v23
	v_ashrrev_i32_e32 v25, 31, v24
	v_lshlrev_b64 v[24:25], 10, v[24:25]
	v_lshl_add_u64 v[24:25], v[0:1], 0, v[24:25]
	global_load_dword v19, v[24:25], off
.LBB0_813:
	s_or_b64 exec, exec, s[14:15]
	v_add_u32_e32 v25, 44, v50
	v_cmp_gt_u32_e32 vcc, s36, v25
	v_mov_b32_e32 v23, 0
	v_mov_b32_e32 v24, 0
	s_and_saveexec_b64 s[14:15], vcc
	s_cbranch_execz .LBB0_815
	v_add_u32_e32 v24, s27, v25
	v_ashrrev_i32_e32 v25, 31, v24
	v_lshlrev_b64 v[24:25], 10, v[24:25]
	v_lshl_add_u64 v[24:25], v[0:1], 0, v[24:25]
	global_load_dword v24, v[24:25], off
.LBB0_815:
	s_or_b64 exec, exec, s[14:15]
	v_add_u32_e32 v25, 45, v50
	v_cmp_gt_u32_e32 vcc, s36, v25
	s_and_saveexec_b64 s[14:15], vcc
	s_cbranch_execz .LBB0_817
	v_add_u32_e32 v30, s27, v25
	v_ashrrev_i32_e32 v31, 31, v30
	v_lshlrev_b64 v[30:31], 10, v[30:31]
	v_lshl_add_u64 v[30:31], v[0:1], 0, v[30:31]
	global_load_dword v23, v[30:31], off
.LBB0_817:
	s_or_b64 exec, exec, s[14:15]
	v_add_u32_e32 v29, 46, v50
	v_cmp_gt_u32_e32 vcc, s36, v29
	v_mov_b32_e32 v25, 0
	v_mov_b32_e32 v26, 0
	s_and_saveexec_b64 s[14:15], vcc
	s_cbranch_execz .LBB0_819
	v_add_u32_e32 v30, s27, v29
	v_ashrrev_i32_e32 v31, 31, v30
	v_lshlrev_b64 v[30:31], 10, v[30:31]
	v_lshl_add_u64 v[30:31], v[0:1], 0, v[30:31]
	global_load_dword v26, v[30:31], off
; __device__ __forceinline__ void conv_unit(LAS unsigned char* lds, const float* uconv, const float* cw  , const float* cb, const float* lng, const float* lnb, bf16_t* mix, int row0) {
;     ...
;         float uwin[62];
; #pragma unroll
;         for (int j = 0; j < 62; ++j) { const int tt = t0 - 15 + j; uwin[j] = (tt >= 0 && tt < L) ? uconv[(size_t)(seq0 + tt) * 256 + ch] : 0.f; }
.LBB0_819:
	s_or_b64 exec, exec, s[14:15]
	v_add_u32_e32 v29, 47, v50
	v_cmp_gt_u32_e32 vcc, s36, v29
	s_and_saveexec_b64 s[14:15], vcc
	s_cbranch_execz .LBB0_821
	v_add_u32_e32 v30, s27, v29
	v_ashrrev_i32_e32 v31, 31, v30
	v_lshlrev_b64 v[30:31], 10, v[30:31]
	v_lshl_add_u64 v[30:31], v[0:1], 0, v[30:31]
	global_load_dword v25, v[30:31], off
.LBB0_821:
	s_or_b64 exec, exec, s[14:15]
	v_add_u32_e32 v31, 48, v50
	v_cmp_gt_u32_e32 vcc, s36, v31
	v_mov_b32_e32 v29, 0
	v_mov_b32_e32 v30, 0
	s_and_saveexec_b64 s[14:15], vcc
	s_cbranch_execz .LBB0_823
	v_add_u32_e32 v30, s27, v31
	v_ashrrev_i32_e32 v31, 31, v30
	v_lshlrev_b64 v[30:31], 10, v[30:31]
	v_lshl_add_u64 v[30:31], v[0:1], 0, v[30:31]
	global_load_dword v30, v[30:31], off
.LBB0_823:
	s_or_b64 exec, exec, s[14:15]
	v_add_u32_e32 v31, 49, v50
	v_cmp_gt_u32_e32 vcc, s36, v31
	s_and_saveexec_b64 s[14:15], vcc
	s_cbranch_execz .LBB0_825
	v_add_u32_e32 v34, s27, v31
	v_ashrrev_i32_e32 v35, 31, v34
	v_lshlrev_b64 v[34:35], 10, v[34:35]
	v_lshl_add_u64 v[34:35], v[0:1], 0, v[34:35]
	global_load_dword v29, v[34:35], off
.LBB0_825:
	s_or_b64 exec, exec, s[14:15]
	v_add_u32_e32 v34, 50, v50
	v_cmp_gt_u32_e32 vcc, s36, v34
	v_mov_b32_e32 v31, 0
	v_mov_b32_e32 v32, 0
	s_and_saveexec_b64 s[14:15], vcc
	s_cbranch_execz .LBB0_827
	v_add_u32_e32 v34, s27, v34
	v_ashrrev_i32_e32 v35, 31, v34
	v_lshlrev_b64 v[34:35], 10, v[34:35]
	v_lshl_add_u64 v[34:35], v[0:1], 0, v[34:35]
	global_load_dword v32, v[34:35], off
.LBB0_827:
	s_or_b64 exec, exec, s[14:15]
	v_add_u32_e32 v34, 51, v50
	v_cmp_gt_u32_e32 vcc, s36, v34
	s_and_saveexec_b64 s[14:15], vcc
	s_cbranch_execz .LBB0_829
	v_add_u32_e32 v34, s27, v34
	v_ashrrev_i32_e32 v35, 31, v34
	v_lshlrev_b64 v[34:35], 10, v[34:35]
	v_lshl_add_u64 v[34:35], v[0:1], 0, v[34:35]
	global_load_dword v31, v[34:35], off
.LBB0_829:
	s_or_b64 exec, exec, s[14:15]
	v_add_u32_e32 v37, 52, v50
	v_cmp_gt_u32_e32 vcc, s36, v37
	v_mov_b32_e32 v34, 0
	v_mov_b32_e32 v35, 0
	s_and_saveexec_b64 s[14:15], vcc
	s_cbranch_execz .LBB0_831
	v_add_u32_e32 v40, s27, v37
	v_ashrrev_i32_e32 v41, 31, v40
	v_lshlrev_b64 v[40:41], 10, v[40:41]
	v_lshl_add_u64 v[40:41], v[0:1], 0, v[40:41]
	global_load_dword v35, v[40:41], off
.LBB0_831:
	s_or_b64 exec, exec, s[14:15]
	v_add_u32_e32 v37, 53, v50
	v_cmp_gt_u32_e32 vcc, s36, v37
	s_and_saveexec_b64 s[14:15], vcc
	s_cbranch_execz .LBB0_833
	v_add_u32_e32 v40, s27, v37
	v_ashrrev_i32_e32 v41, 31, v40
	v_lshlrev_b64 v[40:41], 10, v[40:41]
	v_lshl_add_u64 v[40:41], v[0:1], 0, v[40:41]
	global_load_dword v34, v[40:41], off
.LBB0_833:
	s_or_b64 exec, exec, s[14:15]
	v_add_u32_e32 v40, 54, v50
	v_cmp_gt_u32_e32 vcc, s36, v40
	v_mov_b32_e32 v37, 0
	v_mov_b32_e32 v38, 0
	s_and_saveexec_b64 s[14:15], vcc
	s_cbranch_execz .LBB0_835
	v_add_u32_e32 v40, s27, v40
	v_ashrrev_i32_e32 v41, 31, v40
	v_lshlrev_b64 v[40:41], 10, v[40:41]
	v_lshl_add_u64 v[40:41], v[0:1], 0, v[40:41]
	global_load_dword v38, v[40:41], off
.LBB0_835:
	s_or_b64 exec, exec, s[14:15]
	v_add_u32_e32 v40, 55, v50
	v_cmp_gt_u32_e32 vcc, s36, v40
	s_and_saveexec_b64 s[14:15], vcc
	s_cbranch_execz .LBB0_837
	v_add_u32_e32 v40, s27, v40
	v_ashrrev_i32_e32 v41, 31, v40
	v_lshlrev_b64 v[40:41], 10, v[40:41]
	v_lshl_add_u64 v[40:41], v[0:1], 0, v[40:41]
	global_load_dword v37, v[40:41], off
.LBB0_837:
	s_or_b64 exec, exec, s[14:15]
	v_add_u32_e32 v43, 56, v50
	v_cmp_gt_u32_e32 vcc, s36, v43
	v_mov_b32_e32 v40, 0
	v_mov_b32_e32 v41, 0
	s_and_saveexec_b64 s[14:15], vcc
	s_cbranch_execz .LBB0_839
	v_add_u32_e32 v44, s27, v43
	v_ashrrev_i32_e32 v45, 31, v44
	v_lshlrev_b64 v[44:45], 10, v[44:45]
	v_lshl_add_u64 v[44:45], v[0:1], 0, v[44:45]
	global_load_dword v41, v[44:45], off
.LBB0_839:
	s_or_b64 exec, exec, s[14:15]
	v_add_u32_e32 v43, 57, v50
	v_cmp_gt_u32_e32 vcc, s36, v43
	s_and_saveexec_b64 s[14:15], vcc
	s_cbranch_execz .LBB0_841
	v_add_u32_e32 v44, s27, v43
	v_ashrrev_i32_e32 v45, 31, v44
	v_lshlrev_b64 v[44:45], 10, v[44:45]
	v_lshl_add_u64 v[44:45], v[0:1], 0, v[44:45]
	global_load_dword v40, v[44:45], off
.LBB0_841:
	s_or_b64 exec, exec, s[14:15]
	v_add_u32_e32 v45, 58, v50
	v_cmp_gt_u32_e32 vcc, s36, v45
	v_mov_b32_e32 v43, 0
	v_mov_b32_e32 v44, 0
	s_and_saveexec_b64 s[14:15], vcc
	s_cbranch_execz .LBB0_843
	v_add_u32_e32 v44, s27, v45
	v_ashrrev_i32_e32 v45, 31, v44
	v_lshlrev_b64 v[44:45], 10, v[44:45]
	v_lshl_add_u64 v[44:45], v[0:1], 0, v[44:45]
	global_load_dword v44, v[44:45], off
.LBB0_843:
	s_or_b64 exec, exec, s[14:15]
	v_add_u32_e32 v45, 59, v50
	v_cmp_gt_u32_e32 vcc, s36, v45
	s_and_saveexec_b64 s[14:15], vcc
	s_cbranch_execz .LBB0_845
	v_add_u32_e32 v54, s27, v45
	v_ashrrev_i32_e32 v55, 31, v54
	v_lshlrev_b64 v[54:55], 10, v[54:55]
	v_lshl_add_u64 v[54:55], v[0:1], 0, v[54:55]
	global_load_dword v43, v[54:55], off
.LBB0_845:
	s_or_b64 exec, exec, s[14:15]
	v_add_u32_e32 v51, 60, v50
	v_cmp_gt_u32_e32 vcc, s36, v51
	v_mov_b32_e32 v45, 0
	v_mov_b32_e32 v47, 0
	s_and_saveexec_b64 s[14:15], vcc
	s_cbranch_execz .LBB0_847
	v_add_u32_e32 v54, s27, v51
	v_ashrrev_i32_e32 v55, 31, v54
	v_lshlrev_b64 v[54:55], 10, v[54:55]
	v_lshl_add_u64 v[54:55], v[0:1], 0, v[54:55]
	global_load_dword v47, v[54:55], off
.LBB0_847:
	s_or_b64 exec, exec, s[14:15]
	v_add_u32_e32 v50, 61, v50
	v_cmp_gt_u32_e32 vcc, s36, v50
	s_and_saveexec_b64 s[14:15], vcc
	s_cbranch_execz .LBB0_849
	v_add_u32_e32 v50, s27, v50
	v_ashrrev_i32_e32 v51, 31, v50
	v_lshlrev_b64 v[50:51], 10, v[50:51]
	v_lshl_add_u64 v[0:1], v[0:1], 0, v[50:51]
	global_load_dword v45, v[0:1], off
; __device__ __forceinline__ void conv_unit(LAS unsigned char* lds, const float* uconv, const float* cw  , const float* cb, const float* lng, const float* lnb, bf16_t* mix, int row0) {
;     ...
;         float w[31];
; #pragma unroll
;         for (int j = 0; j < 31; ++j) w[j] = cw[j * 256 + ch];
;         const float bias = cb[ch];
; #pragma unroll
;         for (int i = 0; i < 32; ++i) {
;             float a = bias;
; #pragma unroll
;             for (int j = 0; j < 31; ++j) a += uwin[i + j] * w[j];
.LBB0_849:
	s_or_b64 exec, exec, s[14:15]
	global_load_dword v51, v176, s[12:13]
	global_load_dword v50, v176, s[12:13] offset:1024
	global_load_dword v1, v176, s[12:13] offset:2048
	global_load_dword v53, v176, s[12:13] offset:3072
	global_load_dword v0, v176, s[16:17]
	v_lshl_add_u64 v[62:63], s[12:13], 0, v[176:177]
	v_add_co_u32_e32 v54, vcc, 0x1000, v62
	s_movk_i32 s0, 0x3000
	s_nop 0
	v_addc_co_u32_e32 v55, vcc, 0, v63, vcc
	v_add_co_u32_e32 v56, vcc, s48, v62
	s_nop 1
	v_addc_co_u32_e32 v57, vcc, 0, v63, vcc
	v_add_co_u32_e32 v58, vcc, s0, v62
	s_movk_i32 s0, 0x4000
	s_nop 0
	v_addc_co_u32_e32 v59, vcc, 0, v63, vcc
	v_add_co_u32_e32 v60, vcc, s0, v62
	s_movk_i32 s0, 0x5000
	s_nop 0
	v_addc_co_u32_e32 v61, vcc, 0, v63, vcc
	v_add_co_u32_e32 v64, vcc, s0, v62
	s_movk_i32 s0, 0x7000
	s_nop 0
	v_addc_co_u32_e32 v65, vcc, 0, v63, vcc
	global_load_dword v81, v[54:55], off
	global_load_dword v80, v[54:55], off offset:1024
	global_load_dword v78, v[54:55], off offset:2048
	global_load_dword v77, v[54:55], off offset:3072
	global_load_dword v74, v[56:57], off offset:1024
	global_load_dword v72, v[56:57], off offset:2048
	global_load_dword v70, v[56:57], off offset:3072
	s_nop 0
	global_load_dword v56, v[60:61], off offset:1024
	global_load_dword v55, v[60:61], off offset:2048
	global_load_dword v54, v[60:61], off offset:3072
	global_load_dword v82, v[58:59], off offset:-4096
	global_load_dword v76, v[58:59], off
	global_load_dword v75, v[58:59], off offset:1024
	global_load_dword v73, v[58:59], off offset:2048
	global_load_dword v71, v[58:59], off offset:3072
	global_load_dword v68, v[64:65], off offset:-4096
	global_load_dword v60, v[64:65], off
	s_nop 0
	global_load_dword v58, v[64:65], off offset:1024
	v_add_co_u32_e32 v98, vcc, s50, v62
	v_add_u32_e32 v57, 0, v176
	s_nop 0
	v_addc_co_u32_e32 v99, vcc, 0, v63, vcc
	v_add_co_u32_e32 v100, vcc, s0, v62
	v_lshl_add_u32 v86, v86, 10, v57
	s_nop 0
	v_addc_co_u32_e32 v101, vcc, 0, v63, vcc
	global_load_dword v69, v[64:65], off offset:2048
	global_load_dword v67, v[64:65], off offset:3072
	global_load_dword v66, v[100:101], off offset:-4096
	s_nop 0
	global_load_dword v65, v[98:99], off offset:1024
	global_load_dword v64, v[98:99], off offset:2048
	global_load_dword v63, v[98:99], off offset:3072
	global_load_dword v62, v[100:101], off
	global_load_dword v61, v[100:101], off offset:1024
	global_load_dword v59, v[100:101], off offset:2048
	s_mov_b32 s0, 0x3b800000
	s_waitcnt vmcnt(0) lgkmcnt(0)
	v_fma_f32 v97, v97, v51, v0
	v_fma_f32 v98, v96, v51, v0
	v_fmac_f32_e32 v97, v96, v50
	v_fmac_f32_e32 v98, v95, v50
	v_fmac_f32_e32 v97, v95, v1
	v_fma_f32 v95, v95, v51, v0
	v_fmac_f32_e32 v98, v94, v1
	v_fmac_f32_e32 v97, v94, v53
	v_fmac_f32_e32 v95, v94, v50
	v_fma_f32 v94, v94, v51, v0
	v_fmac_f32_e32 v98, v93, v53
	v_fmac_f32_e32 v97, v93, v81
	v_fmac_f32_e32 v95, v93, v1
	v_fmac_f32_e32 v94, v93, v50
	v_fma_f32 v93, v93, v51, v0
	v_fmac_f32_e32 v98, v92, v81
	v_fmac_f32_e32 v97, v92, v80
	v_fmac_f32_e32 v95, v92, v53
	v_fmac_f32_e32 v94, v92, v1
	v_fmac_f32_e32 v93, v92, v50
	v_fma_f32 v92, v92, v51, v0
	v_fmac_f32_e32 v98, v91, v80
	v_fmac_f32_e32 v97, v91, v78
	v_fmac_f32_e32 v95, v91, v81
	v_fmac_f32_e32 v94, v91, v53
	v_fmac_f32_e32 v93, v91, v1
	v_fmac_f32_e32 v92, v91, v50
	v_fma_f32 v91, v91, v51, v0
	v_fmac_f32_e32 v98, v90, v78
	v_fmac_f32_e32 v97, v90, v77
	v_fmac_f32_e32 v95, v90, v80
	v_fmac_f32_e32 v94, v90, v81
	v_fmac_f32_e32 v93, v90, v53
	v_fmac_f32_e32 v92, v90, v1
	v_fmac_f32_e32 v91, v90, v50
	v_fma_f32 v90, v90, v51, v0
	v_fmac_f32_e32 v98, v89, v77
	v_fmac_f32_e32 v97, v89, v82
	v_fmac_f32_e32 v95, v89, v78
	v_fmac_f32_e32 v94, v89, v80
	v_fmac_f32_e32 v93, v89, v81
	v_fmac_f32_e32 v92, v89, v53
	v_fmac_f32_e32 v91, v89, v1
	v_fmac_f32_e32 v90, v89, v50
	v_fma_f32 v89, v89, v51, v0
	v_fmac_f32_e32 v98, v88, v82
	v_fmac_f32_e32 v97, v88, v74
	v_fmac_f32_e32 v95, v88, v77
	v_fmac_f32_e32 v94, v88, v78
	v_fmac_f32_e32 v93, v88, v80
	v_fmac_f32_e32 v92, v88, v81
	v_fmac_f32_e32 v91, v88, v53
	v_fmac_f32_e32 v90, v88, v1
	v_fmac_f32_e32 v89, v88, v50
	v_fma_f32 v88, v88, v51, v0
	v_fmac_f32_e32 v98, v87, v74
	v_fmac_f32_e32 v97, v87, v72
	v_fmac_f32_e32 v95, v87, v82
	v_fmac_f32_e32 v94, v87, v77
	v_fmac_f32_e32 v93, v87, v78
	v_fmac_f32_e32 v92, v87, v80
	v_fmac_f32_e32 v91, v87, v81
	v_fmac_f32_e32 v90, v87, v53
	v_fmac_f32_e32 v89, v87, v1
	v_fmac_f32_e32 v88, v87, v50
	v_fma_f32 v87, v87, v51, v0
	v_fmac_f32_e32 v97, v85, v70
	v_fmac_f32_e32 v98, v85, v72
	v_fmac_f32_e32 v95, v85, v74
	v_fmac_f32_e32 v94, v85, v82
	v_fmac_f32_e32 v93, v85, v77
	v_fmac_f32_e32 v92, v85, v78
	v_fmac_f32_e32 v91, v85, v80
	v_fmac_f32_e32 v90, v85, v81
	v_fmac_f32_e32 v89, v85, v53
	v_fmac_f32_e32 v88, v85, v1
	v_fmac_f32_e32 v87, v85, v50
	v_fma_f32 v85, v85, v51, v0
	v_fmac_f32_e32 v97, v84, v76
	v_fmac_f32_e32 v98, v84, v70
	v_fmac_f32_e32 v95, v84, v72
	v_fmac_f32_e32 v94, v84, v74
	v_fmac_f32_e32 v93, v84, v82
	v_fmac_f32_e32 v92, v84, v77
	v_fmac_f32_e32 v91, v84, v78
	v_fmac_f32_e32 v90, v84, v80
	v_fmac_f32_e32 v89, v84, v81
	v_fmac_f32_e32 v88, v84, v53
	v_fmac_f32_e32 v87, v84, v1
	v_fmac_f32_e32 v85, v84, v50
	v_fma_f32 v84, v84, v51, v0
	v_fmac_f32_e32 v97, v83, v75
	v_fmac_f32_e32 v98, v83, v76
	v_fmac_f32_e32 v95, v83, v70
	v_fmac_f32_e32 v94, v83, v72
	v_fmac_f32_e32 v93, v83, v74
	v_fmac_f32_e32 v92, v83, v82
	v_fmac_f32_e32 v91, v83, v77
	v_fmac_f32_e32 v90, v83, v78
	v_fmac_f32_e32 v89, v83, v80
	v_fmac_f32_e32 v88, v83, v81
	v_fmac_f32_e32 v87, v83, v53
	v_fmac_f32_e32 v85, v83, v1
	v_fmac_f32_e32 v84, v83, v50
	v_fma_f32 v83, v83, v51, v0
	v_fmac_f32_e32 v97, v79, v73
; __device__ __forceinline__ void conv_unit(LAS unsigned char* lds, const float* uconv, const float* cw  , const float* cb, const float* lng, const float* lnb, bf16_t* mix, int row0) {
;     ...
;         for (int i = 0; i < 32; ++i) {
;             float a = bias;
; #pragma unroll
;             for (int j = 0; j < 31; ++j) a += uwin[i + j] * w[j];
	v_fmac_f32_e32 v98, v79, v75
	v_fmac_f32_e32 v95, v79, v76
	v_fmac_f32_e32 v94, v79, v70
	v_fmac_f32_e32 v93, v79, v72
	v_fmac_f32_e32 v92, v79, v74
	v_fmac_f32_e32 v91, v79, v82
	v_fmac_f32_e32 v90, v79, v77
	v_fmac_f32_e32 v89, v79, v78
	v_fmac_f32_e32 v88, v79, v80
	v_fmac_f32_e32 v87, v79, v81
	v_fmac_f32_e32 v85, v79, v53
	v_fmac_f32_e32 v84, v79, v1
	v_fmac_f32_e32 v83, v79, v50
	v_fma_f32 v79, v79, v51, v0
	v_fmac_f32_e32 v97, v52, v71
	v_fmac_f32_e32 v98, v52, v73
	v_fmac_f32_e32 v95, v52, v75
	v_fmac_f32_e32 v94, v52, v76
	v_fmac_f32_e32 v93, v52, v70
	v_fmac_f32_e32 v92, v52, v72
	v_fmac_f32_e32 v91, v52, v74
	v_fmac_f32_e32 v90, v52, v82
	v_fmac_f32_e32 v89, v52, v77
	v_fmac_f32_e32 v88, v52, v78
	v_fmac_f32_e32 v87, v52, v80
	v_fmac_f32_e32 v85, v52, v81
	v_fmac_f32_e32 v84, v52, v53
	v_fmac_f32_e32 v83, v52, v1
	v_fmac_f32_e32 v79, v52, v50
	v_fma_f32 v52, v52, v51, v0
	v_fmac_f32_e32 v97, v49, v68
	v_fmac_f32_e32 v98, v49, v71
	v_fmac_f32_e32 v95, v49, v73
	v_fmac_f32_e32 v94, v49, v75
	v_fmac_f32_e32 v93, v49, v76
	v_fmac_f32_e32 v92, v49, v70
	v_fmac_f32_e32 v91, v49, v72
	v_fmac_f32_e32 v90, v49, v74
	v_fmac_f32_e32 v89, v49, v82
	v_fmac_f32_e32 v88, v49, v77
	v_fmac_f32_e32 v87, v49, v78
	v_fmac_f32_e32 v85, v49, v80
	v_fmac_f32_e32 v84, v49, v81
	v_fmac_f32_e32 v83, v49, v53
	v_fmac_f32_e32 v79, v49, v1
	v_fmac_f32_e32 v52, v49, v50
	v_fma_f32 v49, v49, v51, v0
	v_fmac_f32_e32 v97, v48, v56
	v_fmac_f32_e32 v98, v48, v68
	v_fmac_f32_e32 v95, v48, v71
	v_fmac_f32_e32 v94, v48, v73
	v_fmac_f32_e32 v93, v48, v75
	v_fmac_f32_e32 v92, v48, v76
	v_fmac_f32_e32 v91, v48, v70
	v_fmac_f32_e32 v90, v48, v72
	v_fmac_f32_e32 v89, v48, v74
	v_fmac_f32_e32 v88, v48, v82
	v_fmac_f32_e32 v87, v48, v77
	v_fmac_f32_e32 v85, v48, v78
	v_fmac_f32_e32 v84, v48, v80
	v_fmac_f32_e32 v83, v48, v81
	v_fmac_f32_e32 v79, v48, v53
	v_fmac_f32_e32 v52, v48, v1
	v_fmac_f32_e32 v49, v48, v50
	v_fma_f32 v48, v48, v51, v0
	v_fmac_f32_e32 v97, v46, v55
	v_fmac_f32_e32 v98, v46, v56
	v_fmac_f32_e32 v95, v46, v68
	v_fmac_f32_e32 v94, v46, v71
	v_fmac_f32_e32 v93, v46, v73
	v_fmac_f32_e32 v92, v46, v75
	v_fmac_f32_e32 v91, v46, v76
	v_fmac_f32_e32 v90, v46, v70
	v_fmac_f32_e32 v89, v46, v72
	v_fmac_f32_e32 v88, v46, v74
	v_fmac_f32_e32 v87, v46, v82
	v_fmac_f32_e32 v85, v46, v77
	v_fmac_f32_e32 v84, v46, v78
	v_fmac_f32_e32 v83, v46, v80
	v_fmac_f32_e32 v79, v46, v81
	v_fmac_f32_e32 v52, v46, v53
	v_fmac_f32_e32 v49, v46, v1
	v_fmac_f32_e32 v48, v46, v50
	v_fma_f32 v46, v46, v51, v0
	v_fmac_f32_e32 v97, v42, v54
	v_fmac_f32_e32 v98, v42, v55
	v_fmac_f32_e32 v95, v42, v56
	v_fmac_f32_e32 v94, v42, v68
	v_fmac_f32_e32 v93, v42, v71
	v_fmac_f32_e32 v92, v42, v73
	v_fmac_f32_e32 v91, v42, v75
	v_fmac_f32_e32 v90, v42, v76
	v_fmac_f32_e32 v89, v42, v70
	v_fmac_f32_e32 v88, v42, v72
	v_fmac_f32_e32 v87, v42, v74
	v_fmac_f32_e32 v85, v42, v82
	v_fmac_f32_e32 v84, v42, v77
	v_fmac_f32_e32 v83, v42, v78
	v_fmac_f32_e32 v79, v42, v80
	v_fmac_f32_e32 v52, v42, v81
	v_fmac_f32_e32 v49, v42, v53
	v_fmac_f32_e32 v48, v42, v1
	v_fmac_f32_e32 v46, v42, v50
	v_fma_f32 v42, v42, v51, v0
	v_fmac_f32_e32 v97, v39, v60
	v_fmac_f32_e32 v98, v39, v54
	v_fmac_f32_e32 v95, v39, v55
	v_fmac_f32_e32 v94, v39, v56
	v_fmac_f32_e32 v93, v39, v68
	v_fmac_f32_e32 v92, v39, v71
	v_fmac_f32_e32 v91, v39, v73
	v_fmac_f32_e32 v90, v39, v75
	v_fmac_f32_e32 v89, v39, v76
	v_fmac_f32_e32 v88, v39, v70
	v_fmac_f32_e32 v87, v39, v72
	v_fmac_f32_e32 v85, v39, v74
	v_fmac_f32_e32 v84, v39, v82
	v_fmac_f32_e32 v83, v39, v77
	v_fmac_f32_e32 v79, v39, v78
	v_fmac_f32_e32 v52, v39, v80
	v_fmac_f32_e32 v49, v39, v81
	v_fmac_f32_e32 v48, v39, v53
	v_fmac_f32_e32 v46, v39, v1
	v_fmac_f32_e32 v42, v39, v50
	v_fma_f32 v39, v39, v51, v0
	v_fmac_f32_e32 v97, v36, v58
	v_fmac_f32_e32 v98, v36, v60
	v_fmac_f32_e32 v95, v36, v54
	v_fmac_f32_e32 v94, v36, v55
	v_fmac_f32_e32 v93, v36, v56
	v_fmac_f32_e32 v92, v36, v68
	v_fmac_f32_e32 v91, v36, v71
	v_fmac_f32_e32 v90, v36, v73
	v_fmac_f32_e32 v89, v36, v75
	v_fmac_f32_e32 v88, v36, v76
	v_fmac_f32_e32 v87, v36, v70
	v_fmac_f32_e32 v85, v36, v72
	v_fmac_f32_e32 v84, v36, v74
	v_fmac_f32_e32 v83, v36, v82
	v_fmac_f32_e32 v79, v36, v77
	v_fmac_f32_e32 v52, v36, v78
	v_fmac_f32_e32 v49, v36, v80
	v_fmac_f32_e32 v48, v36, v81
	v_fmac_f32_e32 v46, v36, v53
	v_fmac_f32_e32 v42, v36, v1
	v_fmac_f32_e32 v39, v36, v50
	v_fma_f32 v36, v36, v51, v0
	v_fmac_f32_e32 v97, v33, v69
	v_fmac_f32_e32 v98, v33, v58
	v_fmac_f32_e32 v95, v33, v60
	v_fmac_f32_e32 v94, v33, v54
	v_fmac_f32_e32 v93, v33, v55
	v_fmac_f32_e32 v92, v33, v56
	v_fmac_f32_e32 v91, v33, v68
	v_fmac_f32_e32 v90, v33, v71
	v_fmac_f32_e32 v89, v33, v73
	v_fmac_f32_e32 v88, v33, v75
	v_fmac_f32_e32 v87, v33, v76
	v_fmac_f32_e32 v85, v33, v70
	v_fmac_f32_e32 v84, v33, v72
	v_fmac_f32_e32 v83, v33, v74
	v_fmac_f32_e32 v79, v33, v82
	v_fmac_f32_e32 v52, v33, v77
	v_fmac_f32_e32 v49, v33, v78
	v_fmac_f32_e32 v48, v33, v80
	v_fmac_f32_e32 v46, v33, v81
	v_fmac_f32_e32 v42, v33, v53
	v_fmac_f32_e32 v39, v33, v1
	v_fmac_f32_e32 v36, v33, v50
	v_fma_f32 v33, v33, v51, v0
	v_fmac_f32_e32 v97, v28, v67
	v_fmac_f32_e32 v98, v28, v69
	v_fmac_f32_e32 v95, v28, v58
	v_fmac_f32_e32 v94, v28, v60
	v_fmac_f32_e32 v93, v28, v54
	v_fmac_f32_e32 v92, v28, v55
	v_fmac_f32_e32 v91, v28, v56
	v_fmac_f32_e32 v90, v28, v68
	v_fmac_f32_e32 v89, v28, v71
	v_fmac_f32_e32 v88, v28, v73
	v_fmac_f32_e32 v87, v28, v75
	v_fmac_f32_e32 v85, v28, v76
	v_fmac_f32_e32 v84, v28, v70
	v_fmac_f32_e32 v83, v28, v72
	v_fmac_f32_e32 v79, v28, v74
	v_fmac_f32_e32 v52, v28, v82
	v_fmac_f32_e32 v49, v28, v77
	v_fmac_f32_e32 v48, v28, v78
	v_fmac_f32_e32 v46, v28, v80
; __device__ __forceinline__ void conv_unit(LAS unsigned char* lds, const float* uconv, const float* cw  , const float* cb, const float* lng, const float* lnb, bf16_t* mix, int row0) {
;     ...
;         for (int i = 0; i < 32; ++i) {
;             float a = bias;
; #pragma unroll
;             for (int j = 0; j < 31; ++j) a += uwin[i + j] * w[j];
	v_fmac_f32_e32 v42, v28, v81
	v_fmac_f32_e32 v39, v28, v53
	v_fmac_f32_e32 v36, v28, v1
	v_fmac_f32_e32 v33, v28, v50
	v_fma_f32 v28, v28, v51, v0
	v_fmac_f32_e32 v97, v27, v66
	v_fmac_f32_e32 v98, v27, v67
	v_fmac_f32_e32 v95, v27, v69
	v_fmac_f32_e32 v94, v27, v58
	v_fmac_f32_e32 v93, v27, v60
	v_fmac_f32_e32 v92, v27, v54
	v_fmac_f32_e32 v91, v27, v55
	v_fmac_f32_e32 v90, v27, v56
	v_fmac_f32_e32 v89, v27, v68
	v_fmac_f32_e32 v88, v27, v71
	v_fmac_f32_e32 v87, v27, v73
	v_fmac_f32_e32 v85, v27, v75
	v_fmac_f32_e32 v84, v27, v76
	v_fmac_f32_e32 v83, v27, v70
	v_fmac_f32_e32 v79, v27, v72
	v_fmac_f32_e32 v52, v27, v74
	v_fmac_f32_e32 v49, v27, v82
	v_fmac_f32_e32 v48, v27, v77
	v_fmac_f32_e32 v46, v27, v78
	v_fmac_f32_e32 v42, v27, v80
	v_fmac_f32_e32 v39, v27, v81
	v_fmac_f32_e32 v36, v27, v53
	v_fmac_f32_e32 v33, v27, v1
	v_fmac_f32_e32 v28, v27, v50
	v_fma_f32 v27, v27, v51, v0
	v_fmac_f32_e32 v97, v22, v65
	v_fmac_f32_e32 v98, v22, v66
	v_fmac_f32_e32 v95, v22, v67
	v_fmac_f32_e32 v94, v22, v69
	v_fmac_f32_e32 v93, v22, v58
	v_fmac_f32_e32 v92, v22, v60
	v_fmac_f32_e32 v91, v22, v54
	v_fmac_f32_e32 v90, v22, v55
	v_fmac_f32_e32 v89, v22, v56
	v_fmac_f32_e32 v88, v22, v68
	v_fmac_f32_e32 v87, v22, v71
	v_fmac_f32_e32 v85, v22, v73
	v_fmac_f32_e32 v84, v22, v75
	v_fmac_f32_e32 v83, v22, v76
	v_fmac_f32_e32 v79, v22, v70
	v_fmac_f32_e32 v52, v22, v72
	v_fmac_f32_e32 v49, v22, v74
	v_fmac_f32_e32 v48, v22, v82
	v_fmac_f32_e32 v46, v22, v77
	v_fmac_f32_e32 v42, v22, v78
	v_fmac_f32_e32 v39, v22, v80
	v_fmac_f32_e32 v36, v22, v81
	v_fmac_f32_e32 v33, v22, v53
	v_fmac_f32_e32 v28, v22, v1
	v_fmac_f32_e32 v27, v22, v50
	v_fma_f32 v22, v22, v51, v0
	v_fmac_f32_e32 v97, v21, v64
	v_fmac_f32_e32 v98, v21, v65
	v_fmac_f32_e32 v95, v21, v66
	v_fmac_f32_e32 v94, v21, v67
	v_fmac_f32_e32 v93, v21, v69
	v_fmac_f32_e32 v92, v21, v58
	v_fmac_f32_e32 v91, v21, v60
	v_fmac_f32_e32 v90, v21, v54
	v_fmac_f32_e32 v89, v21, v55
	v_fmac_f32_e32 v88, v21, v56
	v_fmac_f32_e32 v87, v21, v68
	v_fmac_f32_e32 v85, v21, v71
	v_fmac_f32_e32 v84, v21, v73
	v_fmac_f32_e32 v83, v21, v75
	v_fmac_f32_e32 v79, v21, v76
	v_fmac_f32_e32 v52, v21, v70
	v_fmac_f32_e32 v49, v21, v72
	v_fmac_f32_e32 v48, v21, v74
	v_fmac_f32_e32 v46, v21, v82
	v_fmac_f32_e32 v42, v21, v77
	v_fmac_f32_e32 v39, v21, v78
	v_fmac_f32_e32 v36, v21, v80
	v_fmac_f32_e32 v33, v21, v81
	v_fmac_f32_e32 v28, v21, v53
	v_fmac_f32_e32 v27, v21, v1
	v_fmac_f32_e32 v22, v21, v50
	v_fma_f32 v21, v21, v51, v0
	v_fmac_f32_e32 v97, v16, v63
	v_fmac_f32_e32 v98, v16, v64
	v_fmac_f32_e32 v95, v16, v65
	v_fmac_f32_e32 v94, v16, v66
	v_fmac_f32_e32 v93, v16, v67
	v_fmac_f32_e32 v92, v16, v69
	v_fmac_f32_e32 v91, v16, v58
	v_fmac_f32_e32 v90, v16, v60
	v_fmac_f32_e32 v89, v16, v54
	v_fmac_f32_e32 v88, v16, v55
	v_fmac_f32_e32 v87, v16, v56
	v_fmac_f32_e32 v85, v16, v68
	v_fmac_f32_e32 v84, v16, v71
	v_fmac_f32_e32 v83, v16, v73
	v_fmac_f32_e32 v79, v16, v75
	v_fmac_f32_e32 v52, v16, v76
	v_fmac_f32_e32 v49, v16, v70
	v_fmac_f32_e32 v48, v16, v72
	v_fmac_f32_e32 v46, v16, v74
	v_fmac_f32_e32 v42, v16, v82
	v_fmac_f32_e32 v39, v16, v77
	v_fmac_f32_e32 v36, v16, v78
	v_fmac_f32_e32 v33, v16, v80
	v_fmac_f32_e32 v28, v16, v81
	v_fmac_f32_e32 v27, v16, v53
	v_fmac_f32_e32 v22, v16, v1
	v_fmac_f32_e32 v21, v16, v50
	v_fma_f32 v16, v16, v51, v0
	v_fmac_f32_e32 v97, v13, v62
	v_fmac_f32_e32 v98, v13, v63
	v_fmac_f32_e32 v95, v13, v64
	v_fmac_f32_e32 v94, v13, v65
	v_fmac_f32_e32 v93, v13, v66
	v_fmac_f32_e32 v92, v13, v67
	v_fmac_f32_e32 v91, v13, v69
	v_fmac_f32_e32 v90, v13, v58
	v_fmac_f32_e32 v89, v13, v60
	v_fmac_f32_e32 v88, v13, v54
	v_fmac_f32_e32 v87, v13, v55
	v_fmac_f32_e32 v85, v13, v56
	v_fmac_f32_e32 v84, v13, v68
	v_fmac_f32_e32 v83, v13, v71
	v_fmac_f32_e32 v79, v13, v73
	v_fmac_f32_e32 v52, v13, v75
	v_fmac_f32_e32 v49, v13, v76
	v_fmac_f32_e32 v48, v13, v70
	v_fmac_f32_e32 v46, v13, v72
	v_fmac_f32_e32 v42, v13, v74
	v_fmac_f32_e32 v39, v13, v82
	v_fmac_f32_e32 v36, v13, v77
	v_fmac_f32_e32 v33, v13, v78
	v_fmac_f32_e32 v28, v13, v80
	v_fmac_f32_e32 v27, v13, v81
	v_fmac_f32_e32 v22, v13, v53
	v_fmac_f32_e32 v21, v13, v1
	v_fmac_f32_e32 v16, v13, v50
	v_fma_f32 v13, v13, v51, v0
	v_fmac_f32_e32 v97, v10, v61
	v_fmac_f32_e32 v98, v10, v62
	v_fmac_f32_e32 v95, v10, v63
	v_fmac_f32_e32 v94, v10, v64
	v_fmac_f32_e32 v93, v10, v65
	v_fmac_f32_e32 v92, v10, v66
	v_fmac_f32_e32 v91, v10, v67
	v_fmac_f32_e32 v90, v10, v69
	v_fmac_f32_e32 v89, v10, v58
	v_fmac_f32_e32 v88, v10, v60
	v_fmac_f32_e32 v87, v10, v54
	v_fmac_f32_e32 v85, v10, v55
	v_fmac_f32_e32 v84, v10, v56
	v_fmac_f32_e32 v83, v10, v68
	v_fmac_f32_e32 v79, v10, v71
	v_fmac_f32_e32 v52, v10, v73
	v_fmac_f32_e32 v49, v10, v75
	v_fmac_f32_e32 v48, v10, v76
	v_fmac_f32_e32 v46, v10, v70
	v_fmac_f32_e32 v42, v10, v72
	v_fmac_f32_e32 v39, v10, v74
	v_fmac_f32_e32 v36, v10, v82
	v_fmac_f32_e32 v33, v10, v77
	v_fmac_f32_e32 v28, v10, v78
	v_fmac_f32_e32 v27, v10, v80
	v_fmac_f32_e32 v22, v10, v81
	v_fmac_f32_e32 v21, v10, v53
	v_fmac_f32_e32 v16, v10, v1
	v_fmac_f32_e32 v13, v10, v50
	v_fma_f32 v10, v10, v51, v0
	v_fmac_f32_e32 v97, v7, v59
	v_fmac_f32_e32 v98, v7, v61
	v_fmac_f32_e32 v95, v7, v62
	v_fmac_f32_e32 v94, v7, v63
	v_fmac_f32_e32 v93, v7, v64
	v_fmac_f32_e32 v92, v7, v65
	v_fmac_f32_e32 v91, v7, v66
	v_fmac_f32_e32 v90, v7, v67
	v_fmac_f32_e32 v89, v7, v69
	v_fmac_f32_e32 v88, v7, v58
	v_fmac_f32_e32 v87, v7, v60
	v_fmac_f32_e32 v85, v7, v54
	v_fmac_f32_e32 v84, v7, v55
	v_fmac_f32_e32 v83, v7, v56
	v_fmac_f32_e32 v79, v7, v68
	v_fmac_f32_e32 v52, v7, v71
	v_fmac_f32_e32 v49, v7, v73
	v_fmac_f32_e32 v48, v7, v75
	v_fmac_f32_e32 v46, v7, v76
; __device__ __forceinline__ void conv_unit(LAS unsigned char* lds, const float* uconv, const float* cw  , const float* cb, const float* lng, const float* lnb, bf16_t* mix, int row0) {
;     ...
;         for (int i = 0; i < 32; ++i) {
;             float a = bias;
; #pragma unroll
;             for (int j = 0; j < 31; ++j) a += uwin[i + j] * w[j];
	v_fmac_f32_e32 v42, v7, v70
	v_fmac_f32_e32 v39, v7, v72
	v_fmac_f32_e32 v36, v7, v74
	v_fmac_f32_e32 v33, v7, v82
	v_fmac_f32_e32 v28, v7, v77
	v_fmac_f32_e32 v27, v7, v78
	v_fmac_f32_e32 v22, v7, v80
	v_fmac_f32_e32 v21, v7, v81
	v_fmac_f32_e32 v16, v7, v53
	v_fmac_f32_e32 v13, v7, v1
	v_fmac_f32_e32 v10, v7, v50
	v_fma_f32 v7, v7, v51, v0
	v_fmac_f32_e32 v0, v4, v51
	v_fmac_f32_e32 v7, v4, v50
	v_fmac_f32_e32 v0, v6, v50
	v_fmac_f32_e32 v10, v4, v1
	v_fmac_f32_e32 v7, v6, v1
	v_fmac_f32_e32 v0, v5, v1
	v_fmac_f32_e32 v13, v4, v53
	v_fmac_f32_e32 v10, v6, v53
	v_fmac_f32_e32 v7, v5, v53
	v_fmac_f32_e32 v0, v9, v53
	v_fmac_f32_e32 v16, v4, v81
	v_fmac_f32_e32 v13, v6, v81
	v_fmac_f32_e32 v10, v5, v81
	v_fmac_f32_e32 v7, v9, v81
	v_fmac_f32_e32 v0, v8, v81
	v_fmac_f32_e32 v21, v4, v80
	v_fmac_f32_e32 v16, v6, v80
	v_fmac_f32_e32 v13, v5, v80
	v_fmac_f32_e32 v10, v9, v80
	v_fmac_f32_e32 v7, v8, v80
	v_fmac_f32_e32 v0, v12, v80
	v_fmac_f32_e32 v22, v4, v78
	v_fmac_f32_e32 v21, v6, v78
	v_fmac_f32_e32 v16, v5, v78
	v_fmac_f32_e32 v13, v9, v78
	v_fmac_f32_e32 v10, v8, v78
	v_fmac_f32_e32 v7, v12, v78
	v_fmac_f32_e32 v0, v11, v78
	v_fmac_f32_e32 v27, v4, v77
	v_fmac_f32_e32 v22, v6, v77
	v_fmac_f32_e32 v21, v5, v77
	v_fmac_f32_e32 v16, v9, v77
	v_fmac_f32_e32 v13, v8, v77
	v_fmac_f32_e32 v10, v12, v77
	v_fmac_f32_e32 v7, v11, v77
	v_fmac_f32_e32 v0, v15, v77
	v_fmac_f32_e32 v28, v4, v82
	v_fmac_f32_e32 v27, v6, v82
	v_fmac_f32_e32 v22, v5, v82
	v_fmac_f32_e32 v21, v9, v82
	v_fmac_f32_e32 v16, v8, v82
	v_fmac_f32_e32 v13, v12, v82
	v_fmac_f32_e32 v10, v11, v82
	v_fmac_f32_e32 v7, v15, v82
	v_fmac_f32_e32 v0, v14, v82
	v_fmac_f32_e32 v33, v4, v74
	v_fmac_f32_e32 v28, v6, v74
	v_fmac_f32_e32 v27, v5, v74
	v_fmac_f32_e32 v22, v9, v74
	v_fmac_f32_e32 v21, v8, v74
	v_fmac_f32_e32 v16, v12, v74
	v_fmac_f32_e32 v13, v11, v74
	v_fmac_f32_e32 v10, v15, v74
	v_fmac_f32_e32 v7, v14, v74
	v_fmac_f32_e32 v0, v18, v74
	v_fmac_f32_e32 v36, v4, v72
	v_fmac_f32_e32 v33, v6, v72
	v_fmac_f32_e32 v28, v5, v72
	v_fmac_f32_e32 v27, v9, v72
	v_fmac_f32_e32 v22, v8, v72
	v_fmac_f32_e32 v21, v12, v72
	v_fmac_f32_e32 v16, v11, v72
	v_fmac_f32_e32 v13, v15, v72
	v_fmac_f32_e32 v10, v14, v72
	v_fmac_f32_e32 v7, v18, v72
	v_fmac_f32_e32 v0, v17, v72
	v_fmac_f32_e32 v39, v4, v70
	v_fmac_f32_e32 v36, v6, v70
	v_fmac_f32_e32 v33, v5, v70
	v_fmac_f32_e32 v28, v9, v70
	v_fmac_f32_e32 v27, v8, v70
	v_fmac_f32_e32 v22, v12, v70
	v_fmac_f32_e32 v21, v11, v70
	v_fmac_f32_e32 v16, v15, v70
	v_fmac_f32_e32 v13, v14, v70
	v_fmac_f32_e32 v10, v18, v70
	v_fmac_f32_e32 v7, v17, v70
	v_fmac_f32_e32 v0, v20, v70
	v_fmac_f32_e32 v42, v4, v76
	v_fmac_f32_e32 v39, v6, v76
	v_fmac_f32_e32 v36, v5, v76
	v_fmac_f32_e32 v33, v9, v76
	v_fmac_f32_e32 v28, v8, v76
	v_fmac_f32_e32 v27, v12, v76
	v_fmac_f32_e32 v22, v11, v76
	v_fmac_f32_e32 v21, v15, v76
	v_fmac_f32_e32 v16, v14, v76
	v_fmac_f32_e32 v13, v18, v76
	v_fmac_f32_e32 v10, v17, v76
	v_fmac_f32_e32 v7, v20, v76
	v_fmac_f32_e32 v0, v19, v76
	v_fmac_f32_e32 v46, v4, v75
	v_fmac_f32_e32 v42, v6, v75
	v_fmac_f32_e32 v39, v5, v75
	v_fmac_f32_e32 v36, v9, v75
	v_fmac_f32_e32 v33, v8, v75
	v_fmac_f32_e32 v28, v12, v75
	v_fmac_f32_e32 v27, v11, v75
	v_fmac_f32_e32 v22, v15, v75
	v_fmac_f32_e32 v21, v14, v75
	v_fmac_f32_e32 v16, v18, v75
	v_fmac_f32_e32 v13, v17, v75
	v_fmac_f32_e32 v10, v20, v75
	v_fmac_f32_e32 v7, v19, v75
	v_fmac_f32_e32 v0, v24, v75
	v_fmac_f32_e32 v48, v4, v73
	v_fmac_f32_e32 v46, v6, v73
	v_fmac_f32_e32 v42, v5, v73
	v_fmac_f32_e32 v39, v9, v73
	v_fmac_f32_e32 v36, v8, v73
	v_fmac_f32_e32 v33, v12, v73
	v_fmac_f32_e32 v28, v11, v73
	v_fmac_f32_e32 v27, v15, v73
	v_fmac_f32_e32 v22, v14, v73
	v_fmac_f32_e32 v21, v18, v73
	v_fmac_f32_e32 v16, v17, v73
	v_fmac_f32_e32 v13, v20, v73
	v_fmac_f32_e32 v10, v19, v73
	v_fmac_f32_e32 v7, v24, v73
	v_fmac_f32_e32 v0, v23, v73
	v_fmac_f32_e32 v49, v4, v71
	v_fmac_f32_e32 v48, v6, v71
	v_fmac_f32_e32 v46, v5, v71
	v_fmac_f32_e32 v42, v9, v71
	v_fmac_f32_e32 v39, v8, v71
	v_fmac_f32_e32 v36, v12, v71
	v_fmac_f32_e32 v33, v11, v71
	v_fmac_f32_e32 v28, v15, v71
	v_fmac_f32_e32 v27, v14, v71
	v_fmac_f32_e32 v22, v18, v71
	v_fmac_f32_e32 v21, v17, v71
	v_fmac_f32_e32 v16, v20, v71
	v_fmac_f32_e32 v13, v19, v71
	v_fmac_f32_e32 v10, v24, v71
	v_fmac_f32_e32 v7, v23, v71
	v_fmac_f32_e32 v0, v26, v71
	v_fmac_f32_e32 v52, v4, v68
	v_fmac_f32_e32 v49, v6, v68
	v_fmac_f32_e32 v48, v5, v68
	v_fmac_f32_e32 v46, v9, v68
	v_fmac_f32_e32 v42, v8, v68
	v_fmac_f32_e32 v39, v12, v68
	v_fmac_f32_e32 v36, v11, v68
	v_fmac_f32_e32 v33, v15, v68
	v_fmac_f32_e32 v28, v14, v68
	v_fmac_f32_e32 v27, v18, v68
	v_fmac_f32_e32 v22, v17, v68
	v_fmac_f32_e32 v21, v20, v68
	v_fmac_f32_e32 v16, v19, v68
	v_fmac_f32_e32 v13, v24, v68
	v_fmac_f32_e32 v10, v23, v68
	v_fmac_f32_e32 v7, v26, v68
	v_fmac_f32_e32 v0, v25, v68
	v_fmac_f32_e32 v79, v4, v56
	v_fmac_f32_e32 v52, v6, v56
	v_fmac_f32_e32 v49, v5, v56
	v_fmac_f32_e32 v48, v9, v56
	v_fmac_f32_e32 v46, v8, v56
	v_fmac_f32_e32 v42, v12, v56
	v_fmac_f32_e32 v39, v11, v56
	v_fmac_f32_e32 v36, v15, v56
	v_fmac_f32_e32 v33, v14, v56
	v_fmac_f32_e32 v28, v18, v56
	v_fmac_f32_e32 v27, v17, v56
	v_fmac_f32_e32 v22, v20, v56
	v_fmac_f32_e32 v21, v19, v56
	v_fmac_f32_e32 v16, v24, v56
	v_fmac_f32_e32 v13, v23, v56
	v_fmac_f32_e32 v10, v26, v56
	v_fmac_f32_e32 v7, v25, v56
	v_fmac_f32_e32 v0, v30, v56
	v_fmac_f32_e32 v83, v4, v55
	v_fmac_f32_e32 v79, v6, v55
	v_fmac_f32_e32 v52, v5, v55
	v_fmac_f32_e32 v49, v9, v55
	v_fmac_f32_e32 v48, v8, v55
	v_fmac_f32_e32 v46, v12, v55
	v_fmac_f32_e32 v42, v11, v55
	v_fmac_f32_e32 v39, v15, v55
	v_fmac_f32_e32 v36, v14, v55
	v_fmac_f32_e32 v33, v18, v55
; __device__ __forceinline__ void conv_unit(LAS unsigned char* lds, const float* uconv, const float* cw  , const float* cb, const float* lng, const float* lnb, bf16_t* mix, int row0) {
;     ...
;         for (int i = 0; i < 32; ++i) {
;             float a = bias;
; #pragma unroll
;             for (int j = 0; j < 31; ++j) a += uwin[i + j] * w[j];
	v_fmac_f32_e32 v28, v17, v55
	v_fmac_f32_e32 v27, v20, v55
	v_fmac_f32_e32 v22, v19, v55
	v_fmac_f32_e32 v21, v24, v55
	v_fmac_f32_e32 v16, v23, v55
	v_fmac_f32_e32 v13, v26, v55
	v_fmac_f32_e32 v10, v25, v55
	v_fmac_f32_e32 v7, v30, v55
	v_fmac_f32_e32 v0, v29, v55
	v_fmac_f32_e32 v84, v4, v54
	v_fmac_f32_e32 v83, v6, v54
	v_fmac_f32_e32 v79, v5, v54
	v_fmac_f32_e32 v52, v9, v54
	v_fmac_f32_e32 v49, v8, v54
	v_fmac_f32_e32 v48, v12, v54
	v_fmac_f32_e32 v46, v11, v54
	v_fmac_f32_e32 v42, v15, v54
	v_fmac_f32_e32 v39, v14, v54
	v_fmac_f32_e32 v36, v18, v54
	v_fmac_f32_e32 v33, v17, v54
	v_fmac_f32_e32 v28, v20, v54
	v_fmac_f32_e32 v27, v19, v54
	v_fmac_f32_e32 v22, v24, v54
	v_fmac_f32_e32 v21, v23, v54
	v_fmac_f32_e32 v16, v26, v54
	v_fmac_f32_e32 v13, v25, v54
	v_fmac_f32_e32 v10, v30, v54
	v_fmac_f32_e32 v7, v29, v54
	v_fmac_f32_e32 v0, v32, v54
	v_fmac_f32_e32 v85, v4, v60
	v_fmac_f32_e32 v84, v6, v60
	v_fmac_f32_e32 v83, v5, v60
	v_fmac_f32_e32 v79, v9, v60
	v_fmac_f32_e32 v52, v8, v60
	v_fmac_f32_e32 v49, v12, v60
	v_fmac_f32_e32 v48, v11, v60
	v_fmac_f32_e32 v46, v15, v60
	v_fmac_f32_e32 v42, v14, v60
	v_fmac_f32_e32 v39, v18, v60
	v_fmac_f32_e32 v36, v17, v60
	v_fmac_f32_e32 v33, v20, v60
	v_fmac_f32_e32 v28, v19, v60
	v_fmac_f32_e32 v27, v24, v60
	v_fmac_f32_e32 v22, v23, v60
	v_fmac_f32_e32 v21, v26, v60
	v_fmac_f32_e32 v16, v25, v60
	v_fmac_f32_e32 v13, v30, v60
	v_fmac_f32_e32 v10, v29, v60
	v_fmac_f32_e32 v7, v32, v60
	v_fmac_f32_e32 v0, v31, v60
	v_fmac_f32_e32 v87, v4, v58
	v_fmac_f32_e32 v85, v6, v58
	v_fmac_f32_e32 v84, v5, v58
	v_fmac_f32_e32 v83, v9, v58
	v_fmac_f32_e32 v79, v8, v58
	v_fmac_f32_e32 v52, v12, v58
	v_fmac_f32_e32 v49, v11, v58
	v_fmac_f32_e32 v48, v15, v58
	v_fmac_f32_e32 v46, v14, v58
	v_fmac_f32_e32 v42, v18, v58
	v_fmac_f32_e32 v39, v17, v58
	v_fmac_f32_e32 v36, v20, v58
	v_fmac_f32_e32 v33, v19, v58
	v_fmac_f32_e32 v28, v24, v58
	v_fmac_f32_e32 v27, v23, v58
	v_fmac_f32_e32 v22, v26, v58
	v_fmac_f32_e32 v21, v25, v58
	v_fmac_f32_e32 v16, v30, v58
	v_fmac_f32_e32 v13, v29, v58
	v_fmac_f32_e32 v10, v32, v58
	v_fmac_f32_e32 v7, v31, v58
	v_fmac_f32_e32 v0, v35, v58
	v_fmac_f32_e32 v88, v4, v69
	v_fmac_f32_e32 v87, v6, v69
	v_fmac_f32_e32 v85, v5, v69
	v_fmac_f32_e32 v84, v9, v69
	v_fmac_f32_e32 v83, v8, v69
	v_fmac_f32_e32 v79, v12, v69
	v_fmac_f32_e32 v52, v11, v69
	v_fmac_f32_e32 v49, v15, v69
	v_fmac_f32_e32 v48, v14, v69
	v_fmac_f32_e32 v46, v18, v69
	v_fmac_f32_e32 v42, v17, v69
	v_fmac_f32_e32 v39, v20, v69
	v_fmac_f32_e32 v36, v19, v69
	v_fmac_f32_e32 v33, v24, v69
	v_fmac_f32_e32 v28, v23, v69
	v_fmac_f32_e32 v27, v26, v69
	v_fmac_f32_e32 v22, v25, v69
	v_fmac_f32_e32 v21, v30, v69
	v_fmac_f32_e32 v16, v29, v69
	v_fmac_f32_e32 v13, v32, v69
	v_fmac_f32_e32 v10, v31, v69
	v_fmac_f32_e32 v7, v35, v69
	v_fmac_f32_e32 v0, v34, v69
	v_fmac_f32_e32 v89, v4, v67
	v_fmac_f32_e32 v88, v6, v67
	v_fmac_f32_e32 v87, v5, v67
	v_fmac_f32_e32 v85, v9, v67
	v_fmac_f32_e32 v84, v8, v67
	v_fmac_f32_e32 v83, v12, v67
	v_fmac_f32_e32 v79, v11, v67
	v_fmac_f32_e32 v52, v15, v67
	v_fmac_f32_e32 v49, v14, v67
	v_fmac_f32_e32 v48, v18, v67
	v_fmac_f32_e32 v46, v17, v67
	v_fmac_f32_e32 v42, v20, v67
	v_fmac_f32_e32 v39, v19, v67
	v_fmac_f32_e32 v36, v24, v67
	v_fmac_f32_e32 v33, v23, v67
	v_fmac_f32_e32 v28, v26, v67
	v_fmac_f32_e32 v27, v25, v67
	v_fmac_f32_e32 v22, v30, v67
	v_fmac_f32_e32 v21, v29, v67
	v_fmac_f32_e32 v16, v32, v67
	v_fmac_f32_e32 v13, v31, v67
	v_fmac_f32_e32 v10, v35, v67
	v_fmac_f32_e32 v7, v34, v67
	v_fmac_f32_e32 v0, v38, v67
	v_fmac_f32_e32 v90, v4, v66
	v_fmac_f32_e32 v89, v6, v66
	v_fmac_f32_e32 v88, v5, v66
	v_fmac_f32_e32 v87, v9, v66
	v_fmac_f32_e32 v85, v8, v66
	v_fmac_f32_e32 v84, v12, v66
	v_fmac_f32_e32 v83, v11, v66
	v_fmac_f32_e32 v79, v15, v66
	v_fmac_f32_e32 v52, v14, v66
	v_fmac_f32_e32 v49, v18, v66
	v_fmac_f32_e32 v48, v17, v66
	v_fmac_f32_e32 v46, v20, v66
	v_fmac_f32_e32 v42, v19, v66
	v_fmac_f32_e32 v39, v24, v66
	v_fmac_f32_e32 v36, v23, v66
	v_fmac_f32_e32 v33, v26, v66
	v_fmac_f32_e32 v28, v25, v66
	v_fmac_f32_e32 v27, v30, v66
	v_fmac_f32_e32 v22, v29, v66
	v_fmac_f32_e32 v21, v32, v66
	v_fmac_f32_e32 v16, v31, v66
	v_fmac_f32_e32 v13, v35, v66
	v_fmac_f32_e32 v10, v34, v66
	v_fmac_f32_e32 v7, v38, v66
	v_fmac_f32_e32 v0, v37, v66
	v_fmac_f32_e32 v91, v4, v65
	v_fmac_f32_e32 v90, v6, v65
	v_fmac_f32_e32 v89, v5, v65
	v_fmac_f32_e32 v88, v9, v65
	v_fmac_f32_e32 v87, v8, v65
	v_fmac_f32_e32 v85, v12, v65
	v_fmac_f32_e32 v84, v11, v65
	v_fmac_f32_e32 v83, v15, v65
	v_fmac_f32_e32 v79, v14, v65
	v_fmac_f32_e32 v52, v18, v65
	v_fmac_f32_e32 v49, v17, v65
	v_fmac_f32_e32 v48, v20, v65
	v_fmac_f32_e32 v46, v19, v65
	v_fmac_f32_e32 v42, v24, v65
	v_fmac_f32_e32 v39, v23, v65
	v_fmac_f32_e32 v36, v26, v65
	v_fmac_f32_e32 v33, v25, v65
	v_fmac_f32_e32 v28, v30, v65
	v_fmac_f32_e32 v27, v29, v65
	v_fmac_f32_e32 v22, v32, v65
	v_fmac_f32_e32 v21, v31, v65
	v_fmac_f32_e32 v16, v35, v65
	v_fmac_f32_e32 v13, v34, v65
	v_fmac_f32_e32 v10, v38, v65
	v_fmac_f32_e32 v7, v37, v65
	v_fmac_f32_e32 v0, v41, v65
	v_fmac_f32_e32 v92, v4, v64
	v_fmac_f32_e32 v91, v6, v64
	v_fmac_f32_e32 v90, v5, v64
	v_fmac_f32_e32 v89, v9, v64
	v_fmac_f32_e32 v88, v8, v64
	v_fmac_f32_e32 v87, v12, v64
	v_fmac_f32_e32 v85, v11, v64
	v_fmac_f32_e32 v84, v15, v64
	v_fmac_f32_e32 v83, v14, v64
	v_fmac_f32_e32 v79, v18, v64
	v_fmac_f32_e32 v52, v17, v64
	v_fmac_f32_e32 v49, v20, v64
	v_fmac_f32_e32 v48, v19, v64
	v_fmac_f32_e32 v46, v24, v64
	v_fmac_f32_e32 v42, v23, v64
	v_fmac_f32_e32 v39, v26, v64
	v_fmac_f32_e32 v36, v25, v64
	v_fmac_f32_e32 v33, v30, v64
	v_fmac_f32_e32 v28, v29, v64
	v_fmac_f32_e32 v27, v32, v64
; #define LAS __attribute__((address_space(3)))
; #define LAS __attribute__((address_space(3)))
; __device__ __forceinline__ void conv_unit(LAS unsigned char* lds, const float* uconv, const float* cw  , const float* cb, const float* lng, const float* lnb, bf16_t* mix, int row0) {
;     ...
;         for (int i = 0; i < 32; ++i) {
;             float a = bias;
; #pragma unroll
;             for (int j = 0; j < 31; ++j) a += uwin[i + j] * w[j];
;             Y[(half * 32 + i) * 256 + ch] = a;
;         }
;     }
;     __syncthreads();
;     {
;         const f32x4 g4 = *(const f32x4*)(lng + 4 * lane), b4 = *(const f32x4*)(lnb + 4 * lane);
;         f32x4 y[8]; float s1[8], s2[8];
; #pragma unroll
;         for (int i = 0; i < 8; ++i) {
;             y[i] = *(const LAS f32x4*)(Y + (wid * 8 + i) * 256 + 4 * lane);
	v_fmac_f32_e32 v22, v31, v64
	v_fmac_f32_e32 v21, v35, v64
	v_fmac_f32_e32 v16, v34, v64
	v_fmac_f32_e32 v13, v38, v64
	v_fmac_f32_e32 v10, v37, v64
	v_fmac_f32_e32 v7, v41, v64
	v_fmac_f32_e32 v0, v40, v64
	v_fmac_f32_e32 v93, v4, v63
	v_fmac_f32_e32 v92, v6, v63
	v_fmac_f32_e32 v91, v5, v63
	v_fmac_f32_e32 v90, v9, v63
	v_fmac_f32_e32 v89, v8, v63
	v_fmac_f32_e32 v88, v12, v63
	v_fmac_f32_e32 v87, v11, v63
	v_fmac_f32_e32 v85, v15, v63
	v_fmac_f32_e32 v84, v14, v63
	v_fmac_f32_e32 v83, v18, v63
	v_fmac_f32_e32 v79, v17, v63
	v_fmac_f32_e32 v52, v20, v63
	v_fmac_f32_e32 v49, v19, v63
	v_fmac_f32_e32 v48, v24, v63
	v_fmac_f32_e32 v46, v23, v63
	v_fmac_f32_e32 v42, v26, v63
	v_fmac_f32_e32 v39, v25, v63
	v_fmac_f32_e32 v36, v30, v63
	v_fmac_f32_e32 v33, v29, v63
	v_fmac_f32_e32 v28, v32, v63
	v_fmac_f32_e32 v27, v31, v63
	v_fmac_f32_e32 v22, v35, v63
	v_fmac_f32_e32 v21, v34, v63
	v_fmac_f32_e32 v16, v38, v63
	v_fmac_f32_e32 v13, v37, v63
	v_fmac_f32_e32 v10, v41, v63
	v_fmac_f32_e32 v7, v40, v63
	v_fmac_f32_e32 v0, v44, v63
	v_fmac_f32_e32 v94, v4, v62
	v_fmac_f32_e32 v93, v6, v62
	v_fmac_f32_e32 v92, v5, v62
	v_fmac_f32_e32 v91, v9, v62
	v_fmac_f32_e32 v90, v8, v62
	v_fmac_f32_e32 v89, v12, v62
	v_fmac_f32_e32 v88, v11, v62
	v_fmac_f32_e32 v87, v15, v62
	v_fmac_f32_e32 v85, v14, v62
	v_fmac_f32_e32 v84, v18, v62
	v_fmac_f32_e32 v83, v17, v62
	v_fmac_f32_e32 v79, v20, v62
	v_fmac_f32_e32 v52, v19, v62
	v_fmac_f32_e32 v49, v24, v62
	v_fmac_f32_e32 v48, v23, v62
	v_fmac_f32_e32 v46, v26, v62
	v_fmac_f32_e32 v42, v25, v62
	v_fmac_f32_e32 v39, v30, v62
	v_fmac_f32_e32 v36, v29, v62
	v_fmac_f32_e32 v33, v32, v62
	v_fmac_f32_e32 v28, v31, v62
	v_fmac_f32_e32 v27, v35, v62
	v_fmac_f32_e32 v22, v34, v62
	v_fmac_f32_e32 v21, v38, v62
	v_fmac_f32_e32 v16, v37, v62
	v_fmac_f32_e32 v13, v41, v62
	v_fmac_f32_e32 v10, v40, v62
	v_fmac_f32_e32 v7, v44, v62
	v_fmac_f32_e32 v0, v43, v62
	v_fmac_f32_e32 v95, v4, v61
	v_fmac_f32_e32 v94, v6, v61
	v_fmac_f32_e32 v93, v5, v61
	v_fmac_f32_e32 v92, v9, v61
	v_fmac_f32_e32 v91, v8, v61
	v_fmac_f32_e32 v90, v12, v61
	v_fmac_f32_e32 v89, v11, v61
	v_fmac_f32_e32 v88, v15, v61
	v_fmac_f32_e32 v87, v14, v61
	v_fmac_f32_e32 v85, v18, v61
	v_fmac_f32_e32 v84, v17, v61
	v_fmac_f32_e32 v83, v20, v61
	v_fmac_f32_e32 v79, v19, v61
	v_fmac_f32_e32 v52, v24, v61
	v_fmac_f32_e32 v49, v23, v61
	v_fmac_f32_e32 v48, v26, v61
	v_fmac_f32_e32 v46, v25, v61
	v_fmac_f32_e32 v42, v30, v61
	v_fmac_f32_e32 v39, v29, v61
	v_fmac_f32_e32 v36, v32, v61
	v_fmac_f32_e32 v33, v31, v61
	v_fmac_f32_e32 v28, v35, v61
	v_fmac_f32_e32 v27, v34, v61
	v_fmac_f32_e32 v22, v38, v61
	v_fmac_f32_e32 v21, v37, v61
	v_fmac_f32_e32 v16, v41, v61
	v_fmac_f32_e32 v13, v40, v61
	v_fmac_f32_e32 v10, v44, v61
	v_fmac_f32_e32 v7, v43, v61
	v_fmac_f32_e32 v0, v47, v61
	v_lshl_or_b32 v1, v3, 10, v233
	v_fmac_f32_e32 v98, v4, v59
	v_fmac_f32_e32 v95, v6, v59
	v_fmac_f32_e32 v94, v5, v59
	v_fmac_f32_e32 v93, v9, v59
	v_fmac_f32_e32 v92, v8, v59
	v_fmac_f32_e32 v91, v12, v59
	v_fmac_f32_e32 v90, v11, v59
	v_fmac_f32_e32 v89, v15, v59
	v_fmac_f32_e32 v88, v14, v59
	v_fmac_f32_e32 v87, v18, v59
	v_fmac_f32_e32 v85, v17, v59
	v_fmac_f32_e32 v84, v20, v59
	v_fmac_f32_e32 v83, v19, v59
	v_fmac_f32_e32 v79, v24, v59
	v_fmac_f32_e32 v52, v23, v59
	v_fmac_f32_e32 v49, v26, v59
	v_fmac_f32_e32 v48, v25, v59
	v_fmac_f32_e32 v46, v30, v59
	v_fmac_f32_e32 v42, v29, v59
	v_fmac_f32_e32 v39, v32, v59
	v_fmac_f32_e32 v36, v31, v59
	v_fmac_f32_e32 v33, v35, v59
	v_fmac_f32_e32 v28, v34, v59
	v_fmac_f32_e32 v27, v38, v59
	v_fmac_f32_e32 v22, v37, v59
	v_fmac_f32_e32 v21, v41, v59
	v_fmac_f32_e32 v16, v40, v59
	v_fmac_f32_e32 v13, v44, v59
	v_fmac_f32_e32 v10, v43, v59
	v_fmac_f32_e32 v7, v47, v59
	v_fmac_f32_e32 v0, v45, v59
	v_add_u32_e32 v1, v57, v1
	ds_write2st64_b32 v86, v97, v98 offset1:4
	ds_write2st64_b32 v86, v95, v94 offset0:8 offset1:12
	ds_write2st64_b32 v86, v93, v92 offset0:16 offset1:20
	ds_write2st64_b32 v86, v91, v90 offset0:24 offset1:28
	ds_write2st64_b32 v86, v89, v88 offset0:32 offset1:36
	ds_write2st64_b32 v86, v87, v85 offset0:40 offset1:44
	ds_write2st64_b32 v86, v84, v83 offset0:48 offset1:52
	ds_write2st64_b32 v86, v79, v52 offset0:56 offset1:60
	ds_write2st64_b32 v86, v49, v48 offset0:64 offset1:68
	ds_write2st64_b32 v86, v46, v42 offset0:72 offset1:76
	ds_write2st64_b32 v86, v39, v36 offset0:80 offset1:84
	ds_write2st64_b32 v86, v33, v28 offset0:88 offset1:92
	ds_write2st64_b32 v86, v27, v22 offset0:96 offset1:100
	ds_write2st64_b32 v86, v21, v16 offset0:104 offset1:108
	ds_write2st64_b32 v86, v13, v10 offset0:112 offset1:116
	ds_write_b32 v86, v7 offset:30720
	ds_write_b32 v1, v0
	v_lshlrev_b32_e32 v0, 2, v2
	v_ashrrev_i32_e32 v45, 6, v2
	v_and_b32_e32 v47, 0xfc, v0
	v_lshlrev_b32_e32 v4, 2, v47
	v_lshlrev_b32_e32 v0, 13, v45
	v_add3_u32 v8, 0, v0, v4
	s_waitcnt lgkmcnt(0)
	s_barrier
; #define LAS __attribute__((address_space(3)))
; #define LAS __attribute__((address_space(3)))
; __device__ __forceinline__ float sigm(float v) { return __builtin_amdgcn_rcpf(1.f + __builtin_amdgcn_exp2f(-1.4426950408889634f * v)); }
; __device__ __forceinline__ void conv_unit(LAS unsigned char* lds, const float* uconv, const float* cw  , const float* cb, const float* lng, const float* lnb, bf16_t* mix, int row0) {
;     ...
;     {
;         const f32x4 g4 = *(const f32x4*)(lng + 4 * lane), b4 = *(const f32x4*)(lnb + 4 * lane);
;         f32x4 y[8]; float s1[8], s2[8];
; #pragma unroll
;         for (int i = 0; i < 8; ++i) {
;             y[i] = *(const LAS f32x4*)(Y + (wid * 8 + i) * 256 + 4 * lane);
;             s1[i] = (y[i][0] + y[i][1]) + (y[i][2] + y[i][3]);
;             s2[i] = (y[i][0] * y[i][0] + y[i][1] * y[i][1]) + (y[i][2] * y[i][2] + y[i][3] * y[i][3]);
;         }
; #pragma unroll
;         for (int o = 1; o < 64; o <<= 1)
; #pragma unroll
;             for (int i = 0; i < 8; ++i) { s1[i] += __shfl_xor(s1[i], o); s2[i] += __shfl_xor(s2[i], o); }
; #pragma unroll
;         for (int i = 0; i < 8; ++i) {
;             const int tk = wid * 8 + i;
;             const float mu = s1[i] * (1.f / 256.f);
;             const float var = fmaxf(s2[i] * (1.f / 256.f) - mu * mu, 0.f);
;             const float rs = rsqrtf(var + EPSN);
;             f32x4 z = (y[i] - mu) * rs * g4 + b4;
; #pragma unroll
;             for (int j = 0; j < 4; ++j) z[j] = z[j] * sigm(z[j]);
	ds_read_b128 v[92:95], v8
	global_load_dwordx4 v[0:3], v4, s[18:19]
	s_nop 0
	global_load_dwordx4 v[4:7], v4, s[20:21]
	v_and_b32_e32 v37, 64, v229
	v_add_u32_e32 v44, 64, v37
	v_xor_b32_e32 v37, 1, v229
	v_cmp_lt_i32_e32 vcc, v37, v44
	s_waitcnt lgkmcnt(0)
	v_mul_f32_e32 v36, v92, v92
	v_mul_f32_e32 v38, v93, v93
	v_cndmask_b32_e32 v37, v229, v37, vcc
	v_mul_f32_e32 v40, v94, v94
	v_mul_f32_e32 v42, v95, v95
	v_lshlrev_b32_e32 v86, 2, v37
	v_mov_b32_e32 v37, v92
	v_mov_b32_e32 v39, v93
	v_mov_b32_e32 v41, v94
	v_mov_b32_e32 v43, v95
	v_pk_add_f32 v[36:37], v[36:37], v[38:39]
	v_pk_add_f32 v[38:39], v[40:41], v[42:43]
	v_xor_b32_e32 v40, 2, v229
	v_pk_add_f32 v[36:37], v[36:37], v[38:39]
	ds_bpermute_b32 v39, v86, v37
	ds_bpermute_b32 v38, v86, v36
	v_cmp_lt_i32_e32 vcc, v40, v44
	ds_read_b128 v[32:35], v8 offset:1024
	ds_read_b128 v[28:31], v8 offset:2048
	v_cndmask_b32_e32 v40, v229, v40, vcc
	v_lshlrev_b32_e32 v87, 2, v40
	s_waitcnt lgkmcnt(2)
	v_pk_add_f32 v[36:37], v[36:37], v[38:39]
	ds_bpermute_b32 v39, v87, v37
	ds_bpermute_b32 v38, v87, v36
	v_xor_b32_e32 v40, 4, v229
	v_cmp_lt_i32_e32 vcc, v40, v44
	s_waitcnt lgkmcnt(3)
	v_mul_f32_e32 v96, v32, v32
	v_mul_f32_e32 v98, v33, v33
	v_cndmask_b32_e32 v40, v229, v40, vcc
	v_lshlrev_b32_e32 v88, 2, v40
	s_waitcnt lgkmcnt(0)
	v_pk_add_f32 v[36:37], v[36:37], v[38:39]
	ds_bpermute_b32 v39, v88, v37
	ds_bpermute_b32 v38, v88, v36
	v_xor_b32_e32 v40, 8, v229
	v_cmp_lt_i32_e32 vcc, v40, v44
	v_mul_f32_e32 v100, v34, v34
	v_mul_f32_e32 v102, v35, v35
	v_cndmask_b32_e32 v40, v229, v40, vcc
	v_lshlrev_b32_e32 v89, 2, v40
	s_waitcnt lgkmcnt(0)
	v_pk_add_f32 v[36:37], v[36:37], v[38:39]
	ds_bpermute_b32 v39, v89, v37
	ds_bpermute_b32 v38, v89, v36
	v_xor_b32_e32 v40, 16, v229
	v_cmp_lt_i32_e32 vcc, v40, v44
	v_mov_b32_e32 v97, v32
	v_mov_b32_e32 v99, v33
	v_cndmask_b32_e32 v40, v229, v40, vcc
	v_lshlrev_b32_e32 v90, 2, v40
	s_waitcnt lgkmcnt(0)
	v_pk_add_f32 v[36:37], v[36:37], v[38:39]
	ds_bpermute_b32 v39, v90, v37
	ds_bpermute_b32 v38, v90, v36
	v_xor_b32_e32 v40, 32, v229
	v_cmp_lt_i32_e32 vcc, v40, v44
	v_mov_b32_e32 v101, v34
	v_mov_b32_e32 v103, v35
	v_cndmask_b32_e32 v40, v229, v40, vcc
	v_lshlrev_b32_e32 v91, 2, v40
	s_waitcnt lgkmcnt(0)
	v_pk_add_f32 v[36:37], v[36:37], v[38:39]
	v_pk_add_f32 v[96:97], v[96:97], v[98:99]
	v_pk_add_f32 v[98:99], v[100:101], v[102:103]
	ds_bpermute_b32 v43, v91, v37
	ds_bpermute_b32 v42, v91, v36
	v_pk_add_f32 v[96:97], v[96:97], v[98:99]
	ds_bpermute_b32 v99, v86, v97
	ds_bpermute_b32 v98, v86, v96
	ds_read_b128 v[24:27], v8 offset:3072
	ds_read_b128 v[20:23], v8 offset:4096
	s_waitcnt lgkmcnt(4)
	v_pk_add_f32 v[36:37], v[36:37], v[42:43]
	ds_read_b128 v[16:19], v8 offset:5120
	ds_read_b128 v[12:15], v8 offset:6144
	v_pk_mul_f32 v[36:37], v[36:37], s[0:1] op_sel_hi:[1,0]
	s_waitcnt lgkmcnt(4)
	v_pk_add_f32 v[96:97], v[96:97], v[98:99]
	v_fma_f32 v36, -v37, v37, v36
	ds_bpermute_b32 v99, v87, v97
	ds_bpermute_b32 v98, v87, v96
	v_max_f32_e32 v36, 0, v36
	v_add_f32_e32 v36, 0x358637bd, v36
	v_mul_f32_e32 v39, 0x4b800000, v36
	v_cmp_gt_f32_e32 vcc, s33, v36
	s_waitcnt lgkmcnt(0)
	v_pk_add_f32 v[96:97], v[96:97], v[98:99]
	ds_bpermute_b32 v99, v88, v97
	v_cndmask_b32_e32 v36, v36, v39, vcc
	v_rsq_f32_e32 v39, v36
	ds_bpermute_b32 v98, v88, v96
	v_sub_f32_e32 v95, v95, v37
	v_sub_f32_e32 v94, v94, v37
	v_mul_f32_e32 v41, 0x45800000, v39
	v_cndmask_b32_e32 v104, v39, v41, vcc
	v_pk_mul_f32 v[94:95], v[94:95], v[104:105] op_sel_hi:[1,0]
	s_waitcnt lgkmcnt(0)
	v_pk_add_f32 v[96:97], v[96:97], v[98:99]
	s_waitcnt vmcnt(0)
	v_pk_fma_f32 v[94:95], v[2:3], v[94:95], v[6:7]
	ds_bpermute_b32 v99, v89, v97
	ds_bpermute_b32 v98, v89, v96
	v_mul_f32_e32 v41, 0xbfb8aa3b, v94
	v_mul_f32_e32 v43, 0xbfb8aa3b, v95
	v_exp_f32_e32 v41, v41
	v_exp_f32_e32 v43, v43
	v_sub_f32_e32 v93, v93, v37
	v_sub_f32_e32 v92, v92, v37
	v_pk_mul_f32 v[92:93], v[92:93], v[104:105] op_sel_hi:[1,0]
	s_waitcnt lgkmcnt(0)
	v_pk_add_f32 v[96:97], v[96:97], v[98:99]
	v_pk_fma_f32 v[92:93], v[0:1], v[92:93], v[4:5]
	v_add_f32_e32 v41, 1.0, v41
	v_add_f32_e32 v43, 1.0, v43
	ds_bpermute_b32 v99, v90, v97
	ds_bpermute_b32 v98, v90, v96
	v_mul_f32_e32 v37, 0xbfb8aa3b, v92
	v_rcp_f32_e32 v41, v41
	v_rcp_f32_e32 v43, v43
	v_exp_f32_e32 v37, v37
	v_mul_f32_e32 v39, 0xbfb8aa3b, v93
	v_exp_f32_e32 v39, v39
	v_mul_f32_e32 v41, v94, v41
	v_mul_f32_e32 v43, v95, v43
	s_waitcnt lgkmcnt(0)
	v_pk_add_f32 v[94:95], v[96:97], v[98:99]
	v_add_f32_e32 v37, 1.0, v37
	ds_bpermute_b32 v97, v91, v95
	ds_bpermute_b32 v96, v91, v94
	v_rcp_f32_e32 v37, v37
	v_add_f32_e32 v39, 1.0, v39
	v_rcp_f32_e32 v39, v39
	v_lshl_add_u32 v36, v45, 3, s26
	v_mul_f32_e32 v37, v92, v37
	s_waitcnt lgkmcnt(0)
	v_pk_add_f32 v[94:95], v[94:95], v[96:97]
	ds_read_b128 v[8:11], v8 offset:7168
	v_mul_f32_e32 v39, v93, v39
	v_cvt_pk_bf16_f32 v92, v37, v39
	v_ashrrev_i32_e32 v37, 31, v36
	v_pk_mul_f32 v[94:95], v[94:95], s[0:1] op_sel_hi:[1,0]
	v_lshlrev_b64 v[98:99], 11, v[36:37]
	v_fma_f32 v37, -v95, v95, v94
	v_mul_f32_e32 v82, v28, v28
	v_mul_f32_e32 v84, v29, v29
	v_mul_f32_e32 v78, v30, v30
	v_mul_f32_e32 v80, v31, v31
	v_max_f32_e32 v37, 0, v37
	v_mov_b32_e32 v83, v28
	v_mov_b32_e32 v85, v29
	v_mov_b32_e32 v79, v30
	v_mov_b32_e32 v81, v31
	v_add_f32_e32 v37, 0x358637bd, v37
	v_pk_add_f32 v[82:83], v[82:83], v[84:85]
	v_pk_add_f32 v[78:79], v[78:79], v[80:81]
	v_mul_f32_e32 v39, 0x4b800000, v37
	v_cmp_gt_f32_e32 vcc, s33, v37
	v_pk_add_f32 v[78:79], v[82:83], v[78:79]
	ds_bpermute_b32 v81, v86, v79
	v_cndmask_b32_e32 v37, v37, v39, vcc
	ds_bpermute_b32 v80, v86, v78
	v_rsq_f32_e32 v37, v37
	v_lshl_add_u64 v[98:99], s[22:23], 0, v[98:99]
	v_lshlrev_b32_e32 v176, 1, v47
	v_lshl_add_u64 v[96:97], v[98:99], 0, v[176:177]
	v_mul_f32_e32 v39, 0x45800000, v37
	s_waitcnt lgkmcnt(0)
; __device__ __forceinline__ float sigm(float v) { return __builtin_amdgcn_rcpf(1.f + __builtin_amdgcn_exp2f(-1.4426950408889634f * v)); }
; __device__ __forceinline__ unsigned pkbf(float lo, float hi) { return pg8::cvt_pk_bf16(lo, hi); }
; __device__ __forceinline__ void conv_unit(LAS unsigned char* lds, const float* uconv, const float* cw  , const float* cb, const float* lng, const float* lnb, bf16_t* mix, int row0) {
;     ...
; #pragma unroll
;         for (int o = 1; o < 64; o <<= 1)
; #pragma unroll
;             for (int i = 0; i < 8; ++i) { s1[i] += __shfl_xor(s1[i], o); s2[i] += __shfl_xor(s2[i], o); }
; #pragma unroll
;         for (int i = 0; i < 8; ++i) {
;             const int tk = wid * 8 + i;
;             const float mu = s1[i] * (1.f / 256.f);
;             const float var = fmaxf(s2[i] * (1.f / 256.f) - mu * mu, 0.f);
;             const float rs = rsqrtf(var + EPSN);
;             f32x4 z = (y[i] - mu) * rs * g4 + b4;
; #pragma unroll
;             for (int j = 0; j < 4; ++j) z[j] = z[j] * sigm(z[j]);
;             u32x2 w; w.x = pkbf(z[0], z[1]); w.y = pkbf(z[2], z[3]);
;             *(u32x2*)(mix + (size_t)(row0 + tk) * DM + 768 + 4 * lane) = w;
;         }
;     }
;     __syncthreads();
	v_pk_add_f32 v[78:79], v[78:79], v[80:81]
	v_cvt_pk_bf16_f32 v93, v41, v43
	global_store_dwordx2 v[96:97], v[92:93], off offset:1536
	v_cndmask_b32_e32 v92, v37, v39, vcc
	v_sub_f32_e32 v33, v33, v95
	v_sub_f32_e32 v32, v32, v95
	ds_bpermute_b32 v81, v87, v79
	ds_bpermute_b32 v80, v87, v78
	v_pk_mul_f32 v[32:33], v[32:33], v[92:93] op_sel_hi:[1,0]
	v_sub_f32_e32 v35, v35, v95
	v_pk_fma_f32 v[32:33], v[0:1], v[32:33], v[4:5]
	v_sub_f32_e32 v34, v34, v95
	v_mul_f32_e32 v37, 0xbfb8aa3b, v32
	v_exp_f32_e32 v37, v37
	s_waitcnt lgkmcnt(0)
	v_pk_add_f32 v[78:79], v[78:79], v[80:81]
	ds_bpermute_b32 v81, v88, v79
	ds_bpermute_b32 v80, v88, v78
	v_add_f32_e32 v37, 1.0, v37
	v_mul_f32_e32 v39, 0xbfb8aa3b, v33
	v_rcp_f32_e32 v37, v37
	v_exp_f32_e32 v39, v39
	v_pk_mul_f32 v[34:35], v[34:35], v[92:93] op_sel_hi:[1,0]
	s_waitcnt lgkmcnt(0)
	v_pk_add_f32 v[78:79], v[78:79], v[80:81]
	v_pk_fma_f32 v[34:35], v[2:3], v[34:35], v[6:7]
	ds_bpermute_b32 v81, v89, v79
	ds_bpermute_b32 v80, v89, v78
	v_mul_f32_e32 v32, v32, v37
	v_add_f32_e32 v37, 1.0, v39
	v_mul_f32_e32 v39, 0xbfb8aa3b, v34
	v_mul_f32_e32 v41, 0xbfb8aa3b, v35
	v_exp_f32_e32 v39, v39
	v_exp_f32_e32 v41, v41
	s_waitcnt lgkmcnt(0)
	v_pk_add_f32 v[78:79], v[78:79], v[80:81]
	ds_bpermute_b32 v81, v90, v79
	v_add_f32_e32 v39, 1.0, v39
	v_add_f32_e32 v41, 1.0, v41
	ds_bpermute_b32 v80, v90, v78
	v_rcp_f32_e32 v37, v37
	v_rcp_f32_e32 v39, v39
	v_rcp_f32_e32 v41, v41
	v_mul_f32_e32 v70, v24, v24
	v_mul_f32_e32 v33, v33, v37
	v_mul_f32_e32 v37, v34, v39
	v_mul_f32_e32 v39, v35, v41
	s_waitcnt lgkmcnt(0)
	v_pk_add_f32 v[34:35], v[78:79], v[80:81]
	ds_bpermute_b32 v79, v91, v35
	ds_bpermute_b32 v78, v91, v34
	v_cvt_pk_bf16_f32 v32, v32, v33
	v_cvt_pk_bf16_f32 v33, v37, v39
	v_or_b32_e32 v80, 1, v36
	v_ashrrev_i32_e32 v81, 31, v80
	s_waitcnt lgkmcnt(0)
	v_pk_add_f32 v[34:35], v[34:35], v[78:79]
	v_lshlrev_b64 v[80:81], 11, v[80:81]
	v_pk_mul_f32 v[34:35], v[34:35], s[0:1] op_sel_hi:[1,0]
	v_lshl_add_u64 v[78:79], s[22:23], 0, v[80:81]
	v_fma_f32 v34, -v35, v35, v34
	v_max_f32_e32 v34, 0, v34
	v_add_f32_e32 v34, 0x358637bd, v34
	v_mul_f32_e32 v37, 0x4b800000, v34
	v_cmp_gt_f32_e32 vcc, s33, v34
	v_lshl_add_u64 v[78:79], v[78:79], 0, v[176:177]
	global_store_dwordx2 v[78:79], v[32:33], off offset:1536
	v_cndmask_b32_e32 v34, v34, v37, vcc
	v_rsq_f32_e32 v34, v34
	v_sub_f32_e32 v29, v29, v35
	v_sub_f32_e32 v28, v28, v35
	v_sub_f32_e32 v31, v31, v35
	v_mul_f32_e32 v32, 0x45800000, v34
	v_cndmask_b32_e32 v32, v34, v32, vcc
	v_pk_mul_f32 v[28:29], v[28:29], v[32:33] op_sel_hi:[1,0]
	v_sub_f32_e32 v30, v30, v35
	v_pk_fma_f32 v[28:29], v[0:1], v[28:29], v[4:5]
	v_mul_f32_e32 v76, v25, v25
	v_mul_f32_e32 v72, v26, v26
	v_mul_f32_e32 v74, v27, v27
	v_pk_mul_f32 v[30:31], v[30:31], v[32:33] op_sel_hi:[1,0]
	v_mul_f32_e32 v32, 0xbfb8aa3b, v28
	v_mov_b32_e32 v71, v24
	v_mov_b32_e32 v77, v25
	v_mov_b32_e32 v73, v26
	v_mov_b32_e32 v75, v27
	v_exp_f32_e32 v37, v32
	v_pk_add_f32 v[32:33], v[70:71], v[76:77]
	v_pk_add_f32 v[34:35], v[72:73], v[74:75]
	v_mul_f32_e32 v39, 0xbfb8aa3b, v29
	v_pk_add_f32 v[32:33], v[32:33], v[34:35]
	ds_bpermute_b32 v35, v86, v33
	ds_bpermute_b32 v34, v86, v32
	v_add_f32_e32 v37, 1.0, v37
	v_rcp_f32_e32 v37, v37
	v_exp_f32_e32 v39, v39
	v_pk_fma_f32 v[30:31], v[2:3], v[30:31], v[6:7]
	s_waitcnt lgkmcnt(0)
	v_pk_add_f32 v[32:33], v[32:33], v[34:35]
	ds_bpermute_b32 v35, v87, v33
	ds_bpermute_b32 v34, v87, v32
	v_mul_f32_e32 v28, v28, v37
	v_add_f32_e32 v37, 1.0, v39
	v_mul_f32_e32 v39, 0xbfb8aa3b, v30
	v_mul_f32_e32 v41, 0xbfb8aa3b, v31
	s_waitcnt lgkmcnt(0)
	v_pk_add_f32 v[32:33], v[32:33], v[34:35]
	ds_bpermute_b32 v35, v88, v33
	ds_bpermute_b32 v34, v88, v32
	v_exp_f32_e32 v39, v39
	v_exp_f32_e32 v41, v41
	v_rcp_f32_e32 v37, v37
	v_mul_f32_e32 v66, v20, v20
	s_waitcnt lgkmcnt(0)
	v_pk_add_f32 v[32:33], v[32:33], v[34:35]
	ds_bpermute_b32 v35, v89, v33
	ds_bpermute_b32 v34, v89, v32
	v_add_f32_e32 v39, 1.0, v39
	v_add_f32_e32 v41, 1.0, v41
	v_rcp_f32_e32 v39, v39
	v_rcp_f32_e32 v41, v41
	s_waitcnt lgkmcnt(0)
	v_pk_add_f32 v[32:33], v[32:33], v[34:35]
	ds_bpermute_b32 v35, v90, v33
	ds_bpermute_b32 v34, v90, v32
	v_mul_f32_e32 v29, v29, v37
	v_mul_f32_e32 v37, v30, v39
	v_mul_f32_e32 v39, v31, v41
	v_cvt_pk_bf16_f32 v28, v28, v29
	s_waitcnt lgkmcnt(0)
	v_pk_add_f32 v[30:31], v[32:33], v[34:35]
	ds_bpermute_b32 v33, v91, v31
	ds_bpermute_b32 v32, v91, v30
	v_or_b32_e32 v34, 2, v36
	v_ashrrev_i32_e32 v35, 31, v34
	v_lshlrev_b64 v[34:35], 11, v[34:35]
	v_cvt_pk_bf16_f32 v29, v37, v39
	s_waitcnt lgkmcnt(0)
	v_pk_add_f32 v[30:31], v[30:31], v[32:33]
	v_mul_f32_e32 v68, v21, v21
	v_pk_mul_f32 v[30:31], v[30:31], s[0:1] op_sel_hi:[1,0]
	v_mul_f32_e32 v62, v22, v22
	v_fma_f32 v30, -v31, v31, v30
	v_max_f32_e32 v30, 0, v30
	v_add_f32_e32 v30, 0x358637bd, v30
	v_mul_f32_e32 v32, 0x4b800000, v30
	v_cmp_gt_f32_e32 vcc, s33, v30
	v_sub_f32_e32 v25, v25, v31
	v_sub_f32_e32 v24, v24, v31
	v_cndmask_b32_e32 v30, v30, v32, vcc
	v_rsq_f32_e32 v30, v30
	v_lshl_add_u64 v[32:33], s[22:23], 0, v[34:35]
	v_lshl_add_u64 v[32:33], v[32:33], 0, v[176:177]
	global_store_dwordx2 v[32:33], v[28:29], off offset:1536
	v_mul_f32_e32 v28, 0x45800000, v30
	v_cndmask_b32_e32 v28, v30, v28, vcc
	v_pk_mul_f32 v[24:25], v[24:25], v[28:29] op_sel_hi:[1,0]
	v_sub_f32_e32 v27, v27, v31
	v_sub_f32_e32 v26, v26, v31
	v_pk_fma_f32 v[24:25], v[0:1], v[24:25], v[4:5]
	v_mul_f32_e32 v64, v23, v23
	v_pk_mul_f32 v[26:27], v[26:27], v[28:29] op_sel_hi:[1,0]
	v_mul_f32_e32 v28, 0xbfb8aa3b, v24
	v_mov_b32_e32 v67, v20
	v_mov_b32_e32 v69, v21
	v_mov_b32_e32 v63, v22
	v_mov_b32_e32 v65, v23
	v_exp_f32_e32 v32, v28
	v_pk_add_f32 v[28:29], v[66:67], v[68:69]
	v_pk_add_f32 v[30:31], v[62:63], v[64:65]
	v_mul_f32_e32 v33, 0xbfb8aa3b, v25
	v_pk_add_f32 v[28:29], v[28:29], v[30:31]
	ds_bpermute_b32 v31, v86, v29
	ds_bpermute_b32 v30, v86, v28
	v_add_f32_e32 v32, 1.0, v32
	v_rcp_f32_e32 v32, v32
	v_exp_f32_e32 v33, v33
	v_pk_fma_f32 v[26:27], v[2:3], v[26:27], v[6:7]
	s_waitcnt lgkmcnt(0)
; __device__ __forceinline__ float sigm(float v) { return __builtin_amdgcn_rcpf(1.f + __builtin_amdgcn_exp2f(-1.4426950408889634f * v)); }
; __device__ __forceinline__ unsigned pkbf(float lo, float hi) { return pg8::cvt_pk_bf16(lo, hi); }
; __device__ __forceinline__ void conv_unit(LAS unsigned char* lds, const float* uconv, const float* cw  , const float* cb, const float* lng, const float* lnb, bf16_t* mix, int row0) {
;     ...
; #pragma unroll
;         for (int o = 1; o < 64; o <<= 1)
; #pragma unroll
;             for (int i = 0; i < 8; ++i) { s1[i] += __shfl_xor(s1[i], o); s2[i] += __shfl_xor(s2[i], o); }
; #pragma unroll
;         for (int i = 0; i < 8; ++i) {
;             const int tk = wid * 8 + i;
;             const float mu = s1[i] * (1.f / 256.f);
;             const float var = fmaxf(s2[i] * (1.f / 256.f) - mu * mu, 0.f);
;             const float rs = rsqrtf(var + EPSN);
;             f32x4 z = (y[i] - mu) * rs * g4 + b4;
; #pragma unroll
;             for (int j = 0; j < 4; ++j) z[j] = z[j] * sigm(z[j]);
;             u32x2 w; w.x = pkbf(z[0], z[1]); w.y = pkbf(z[2], z[3]);
;             *(u32x2*)(mix + (size_t)(row0 + tk) * DM + 768 + 4 * lane) = w;
;         }
;     }
;     __syncthreads();
	v_pk_add_f32 v[28:29], v[28:29], v[30:31]
	ds_bpermute_b32 v31, v87, v29
	ds_bpermute_b32 v30, v87, v28
	v_mul_f32_e32 v24, v24, v32
	v_add_f32_e32 v32, 1.0, v33
	v_mul_f32_e32 v33, 0xbfb8aa3b, v26
	v_mul_f32_e32 v34, 0xbfb8aa3b, v27
	s_waitcnt lgkmcnt(0)
	v_pk_add_f32 v[28:29], v[28:29], v[30:31]
	ds_bpermute_b32 v31, v88, v29
	ds_bpermute_b32 v30, v88, v28
	v_exp_f32_e32 v33, v33
	v_exp_f32_e32 v34, v34
	v_rcp_f32_e32 v32, v32
	v_mul_f32_e32 v54, v16, v16
	s_waitcnt lgkmcnt(0)
	v_pk_add_f32 v[28:29], v[28:29], v[30:31]
	ds_bpermute_b32 v31, v89, v29
	ds_bpermute_b32 v30, v89, v28
	v_add_f32_e32 v33, 1.0, v33
	v_add_f32_e32 v34, 1.0, v34
	v_rcp_f32_e32 v33, v33
	v_rcp_f32_e32 v34, v34
	s_waitcnt lgkmcnt(0)
	v_pk_add_f32 v[28:29], v[28:29], v[30:31]
	ds_bpermute_b32 v31, v90, v29
	ds_bpermute_b32 v30, v90, v28
	v_mul_f32_e32 v25, v25, v32
	v_mul_f32_e32 v32, v26, v33
	v_mul_f32_e32 v33, v27, v34
	v_cvt_pk_bf16_f32 v24, v24, v25
	s_waitcnt lgkmcnt(0)
	v_pk_add_f32 v[26:27], v[28:29], v[30:31]
	ds_bpermute_b32 v29, v91, v27
	ds_bpermute_b32 v28, v91, v26
	v_or_b32_e32 v30, 3, v36
	v_ashrrev_i32_e32 v31, 31, v30
	v_lshlrev_b64 v[30:31], 11, v[30:31]
	v_cvt_pk_bf16_f32 v25, v32, v33
	s_waitcnt lgkmcnt(0)
	v_pk_add_f32 v[26:27], v[26:27], v[28:29]
	v_mul_f32_e32 v60, v17, v17
	v_pk_mul_f32 v[26:27], v[26:27], s[0:1] op_sel_hi:[1,0]
	v_mul_f32_e32 v56, v18, v18
	v_fma_f32 v26, -v27, v27, v26
	v_max_f32_e32 v26, 0, v26
	v_add_f32_e32 v26, 0x358637bd, v26
	v_mul_f32_e32 v28, 0x4b800000, v26
	v_cmp_gt_f32_e32 vcc, s33, v26
	v_sub_f32_e32 v21, v21, v27
	v_sub_f32_e32 v20, v20, v27
	v_cndmask_b32_e32 v26, v26, v28, vcc
	v_rsq_f32_e32 v26, v26
	v_lshl_add_u64 v[28:29], s[22:23], 0, v[30:31]
	v_lshl_add_u64 v[28:29], v[28:29], 0, v[176:177]
	global_store_dwordx2 v[28:29], v[24:25], off offset:1536
	v_mul_f32_e32 v24, 0x45800000, v26
	v_cndmask_b32_e32 v24, v26, v24, vcc
	v_pk_mul_f32 v[20:21], v[20:21], v[24:25] op_sel_hi:[1,0]
	v_sub_f32_e32 v23, v23, v27
	v_sub_f32_e32 v22, v22, v27
	v_pk_fma_f32 v[20:21], v[0:1], v[20:21], v[4:5]
	v_mul_f32_e32 v58, v19, v19
	v_pk_mul_f32 v[22:23], v[22:23], v[24:25] op_sel_hi:[1,0]
	v_mul_f32_e32 v24, 0xbfb8aa3b, v20
	v_mov_b32_e32 v55, v16
	v_mov_b32_e32 v61, v17
	v_mov_b32_e32 v57, v18
	v_mov_b32_e32 v59, v19
	v_exp_f32_e32 v28, v24
	v_pk_add_f32 v[24:25], v[54:55], v[60:61]
	v_pk_add_f32 v[26:27], v[56:57], v[58:59]
	v_mul_f32_e32 v29, 0xbfb8aa3b, v21
	v_pk_add_f32 v[24:25], v[24:25], v[26:27]
	ds_bpermute_b32 v27, v86, v25
	ds_bpermute_b32 v26, v86, v24
	v_add_f32_e32 v28, 1.0, v28
	v_rcp_f32_e32 v28, v28
	v_exp_f32_e32 v29, v29
	v_pk_fma_f32 v[22:23], v[2:3], v[22:23], v[6:7]
	s_waitcnt lgkmcnt(0)
	v_pk_add_f32 v[24:25], v[24:25], v[26:27]
	ds_bpermute_b32 v27, v87, v25
	ds_bpermute_b32 v26, v87, v24
	v_mul_f32_e32 v20, v20, v28
	v_add_f32_e32 v28, 1.0, v29
	v_mul_f32_e32 v29, 0xbfb8aa3b, v22
	v_mul_f32_e32 v30, 0xbfb8aa3b, v23
	s_waitcnt lgkmcnt(0)
	v_pk_add_f32 v[24:25], v[24:25], v[26:27]
	ds_bpermute_b32 v27, v88, v25
	ds_bpermute_b32 v26, v88, v24
	v_exp_f32_e32 v29, v29
	v_exp_f32_e32 v30, v30
	v_rcp_f32_e32 v28, v28
	v_mul_f32_e32 v46, v12, v12
	s_waitcnt lgkmcnt(0)
	v_pk_add_f32 v[24:25], v[24:25], v[26:27]
	ds_bpermute_b32 v27, v89, v25
	ds_bpermute_b32 v26, v89, v24
	v_add_f32_e32 v29, 1.0, v29
	v_add_f32_e32 v30, 1.0, v30
	v_rcp_f32_e32 v29, v29
	v_rcp_f32_e32 v30, v30
	s_waitcnt lgkmcnt(0)
	v_pk_add_f32 v[24:25], v[24:25], v[26:27]
	ds_bpermute_b32 v27, v90, v25
	ds_bpermute_b32 v26, v90, v24
	v_mul_f32_e32 v21, v21, v28
	v_mul_f32_e32 v28, v22, v29
	v_mul_f32_e32 v29, v23, v30
	v_cvt_pk_bf16_f32 v20, v20, v21
	s_waitcnt lgkmcnt(0)
	v_pk_add_f32 v[22:23], v[24:25], v[26:27]
	ds_bpermute_b32 v25, v91, v23
	ds_bpermute_b32 v24, v91, v22
	v_or_b32_e32 v26, 4, v36
	v_ashrrev_i32_e32 v27, 31, v26
	v_lshlrev_b64 v[26:27], 11, v[26:27]
	v_cvt_pk_bf16_f32 v21, v28, v29
	s_waitcnt lgkmcnt(0)
	v_pk_add_f32 v[22:23], v[22:23], v[24:25]
	v_mul_f32_e32 v48, v13, v13
	v_pk_mul_f32 v[22:23], v[22:23], s[0:1] op_sel_hi:[1,0]
	v_mul_f32_e32 v50, v14, v14
	v_fma_f32 v22, -v23, v23, v22
	v_max_f32_e32 v22, 0, v22
	v_add_f32_e32 v22, 0x358637bd, v22
	v_mul_f32_e32 v24, 0x4b800000, v22
	v_cmp_gt_f32_e32 vcc, s33, v22
	v_sub_f32_e32 v17, v17, v23
	v_sub_f32_e32 v16, v16, v23
	v_cndmask_b32_e32 v22, v22, v24, vcc
	v_rsq_f32_e32 v22, v22
	v_lshl_add_u64 v[24:25], s[22:23], 0, v[26:27]
	v_lshl_add_u64 v[24:25], v[24:25], 0, v[176:177]
	global_store_dwordx2 v[24:25], v[20:21], off offset:1536
	v_mul_f32_e32 v20, 0x45800000, v22
	v_cndmask_b32_e32 v20, v22, v20, vcc
	v_pk_mul_f32 v[16:17], v[16:17], v[20:21] op_sel_hi:[1,0]
	v_sub_f32_e32 v19, v19, v23
	v_sub_f32_e32 v18, v18, v23
	v_pk_fma_f32 v[16:17], v[0:1], v[16:17], v[4:5]
	v_mul_f32_e32 v52, v15, v15
	v_pk_mul_f32 v[18:19], v[18:19], v[20:21] op_sel_hi:[1,0]
	v_mul_f32_e32 v20, 0xbfb8aa3b, v16
	v_mov_b32_e32 v47, v12
	v_mov_b32_e32 v49, v13
	v_mov_b32_e32 v51, v14
	v_mov_b32_e32 v53, v15
	v_exp_f32_e32 v24, v20
	v_pk_add_f32 v[20:21], v[46:47], v[48:49]
	v_pk_add_f32 v[22:23], v[50:51], v[52:53]
	v_mul_f32_e32 v25, 0xbfb8aa3b, v17
	v_pk_add_f32 v[20:21], v[20:21], v[22:23]
	ds_bpermute_b32 v23, v86, v21
	ds_bpermute_b32 v22, v86, v20
	v_add_f32_e32 v24, 1.0, v24
	v_rcp_f32_e32 v24, v24
	v_exp_f32_e32 v25, v25
	v_pk_fma_f32 v[18:19], v[2:3], v[18:19], v[6:7]
	s_waitcnt lgkmcnt(0)
	v_pk_add_f32 v[20:21], v[20:21], v[22:23]
	ds_bpermute_b32 v23, v87, v21
	ds_bpermute_b32 v22, v87, v20
	v_mul_f32_e32 v16, v16, v24
	v_add_f32_e32 v24, 1.0, v25
	v_mul_f32_e32 v25, 0xbfb8aa3b, v18
	v_mul_f32_e32 v26, 0xbfb8aa3b, v19
	s_waitcnt lgkmcnt(0)
; __device__ __forceinline__ float sigm(float v) { return __builtin_amdgcn_rcpf(1.f + __builtin_amdgcn_exp2f(-1.4426950408889634f * v)); }
; __device__ __forceinline__ unsigned pkbf(float lo, float hi) { return pg8::cvt_pk_bf16(lo, hi); }
; __device__ __forceinline__ void conv_unit(LAS unsigned char* lds, const float* uconv, const float* cw  , const float* cb, const float* lng, const float* lnb, bf16_t* mix, int row0) {
;     ...
; #pragma unroll
;         for (int o = 1; o < 64; o <<= 1)
; #pragma unroll
;             for (int i = 0; i < 8; ++i) { s1[i] += __shfl_xor(s1[i], o); s2[i] += __shfl_xor(s2[i], o); }
; #pragma unroll
;         for (int i = 0; i < 8; ++i) {
;             const int tk = wid * 8 + i;
;             const float mu = s1[i] * (1.f / 256.f);
;             const float var = fmaxf(s2[i] * (1.f / 256.f) - mu * mu, 0.f);
;             const float rs = rsqrtf(var + EPSN);
;             f32x4 z = (y[i] - mu) * rs * g4 + b4;
; #pragma unroll
;             for (int j = 0; j < 4; ++j) z[j] = z[j] * sigm(z[j]);
;             u32x2 w; w.x = pkbf(z[0], z[1]); w.y = pkbf(z[2], z[3]);
;             *(u32x2*)(mix + (size_t)(row0 + tk) * DM + 768 + 4 * lane) = w;
;         }
;     }
;     __syncthreads();
	v_pk_add_f32 v[20:21], v[20:21], v[22:23]
	ds_bpermute_b32 v23, v88, v21
	ds_bpermute_b32 v22, v88, v20
	v_exp_f32_e32 v25, v25
	v_exp_f32_e32 v26, v26
	v_rcp_f32_e32 v24, v24
	v_mul_f32_e32 v38, v8, v8
	s_waitcnt lgkmcnt(0)
	v_pk_add_f32 v[20:21], v[20:21], v[22:23]
	ds_bpermute_b32 v23, v89, v21
	ds_bpermute_b32 v22, v89, v20
	v_add_f32_e32 v25, 1.0, v25
	v_add_f32_e32 v26, 1.0, v26
	v_rcp_f32_e32 v25, v25
	v_rcp_f32_e32 v26, v26
	s_waitcnt lgkmcnt(0)
	v_pk_add_f32 v[20:21], v[20:21], v[22:23]
	ds_bpermute_b32 v23, v90, v21
	ds_bpermute_b32 v22, v90, v20
	v_mul_f32_e32 v17, v17, v24
	v_mul_f32_e32 v24, v18, v25
	v_mul_f32_e32 v25, v19, v26
	v_cvt_pk_bf16_f32 v16, v16, v17
	s_waitcnt lgkmcnt(0)
	v_pk_add_f32 v[18:19], v[20:21], v[22:23]
	ds_bpermute_b32 v21, v91, v19
	ds_bpermute_b32 v20, v91, v18
	v_or_b32_e32 v22, 5, v36
	v_ashrrev_i32_e32 v23, 31, v22
	v_lshlrev_b64 v[22:23], 11, v[22:23]
	v_cvt_pk_bf16_f32 v17, v24, v25
	s_waitcnt lgkmcnt(0)
	v_pk_add_f32 v[18:19], v[18:19], v[20:21]
	v_mul_f32_e32 v40, v9, v9
	v_pk_mul_f32 v[18:19], v[18:19], s[0:1] op_sel_hi:[1,0]
	v_mul_f32_e32 v42, v10, v10
	v_fma_f32 v18, -v19, v19, v18
	v_max_f32_e32 v18, 0, v18
	v_add_f32_e32 v18, 0x358637bd, v18
	v_mul_f32_e32 v20, 0x4b800000, v18
	v_cmp_gt_f32_e32 vcc, s33, v18
	v_sub_f32_e32 v13, v13, v19
	v_sub_f32_e32 v12, v12, v19
	v_cndmask_b32_e32 v18, v18, v20, vcc
	v_rsq_f32_e32 v18, v18
	v_lshl_add_u64 v[20:21], s[22:23], 0, v[22:23]
	v_lshl_add_u64 v[20:21], v[20:21], 0, v[176:177]
	global_store_dwordx2 v[20:21], v[16:17], off offset:1536
	v_mul_f32_e32 v16, 0x45800000, v18
	v_cndmask_b32_e32 v16, v18, v16, vcc
	v_pk_mul_f32 v[12:13], v[12:13], v[16:17] op_sel_hi:[1,0]
	v_sub_f32_e32 v15, v15, v19
	v_sub_f32_e32 v14, v14, v19
	v_pk_fma_f32 v[12:13], v[0:1], v[12:13], v[4:5]
	v_mul_f32_e32 v44, v11, v11
	v_pk_mul_f32 v[14:15], v[14:15], v[16:17] op_sel_hi:[1,0]
	v_mul_f32_e32 v16, 0xbfb8aa3b, v12
	v_mov_b32_e32 v39, v8
	v_mov_b32_e32 v41, v9
	v_mov_b32_e32 v43, v10
	v_mov_b32_e32 v45, v11
	v_exp_f32_e32 v20, v16
	v_pk_add_f32 v[16:17], v[38:39], v[40:41]
	v_pk_add_f32 v[18:19], v[42:43], v[44:45]
	v_mul_f32_e32 v21, 0xbfb8aa3b, v13
	v_pk_add_f32 v[16:17], v[16:17], v[18:19]
	ds_bpermute_b32 v19, v86, v17
	ds_bpermute_b32 v18, v86, v16
	v_add_f32_e32 v20, 1.0, v20
	v_rcp_f32_e32 v20, v20
	v_exp_f32_e32 v21, v21
	v_pk_fma_f32 v[14:15], v[2:3], v[14:15], v[6:7]
	s_waitcnt lgkmcnt(0)
	v_pk_add_f32 v[16:17], v[16:17], v[18:19]
	ds_bpermute_b32 v19, v87, v17
	ds_bpermute_b32 v18, v87, v16
	v_mul_f32_e32 v12, v12, v20
	v_add_f32_e32 v20, 1.0, v21
	v_mul_f32_e32 v21, 0xbfb8aa3b, v14
	v_mul_f32_e32 v22, 0xbfb8aa3b, v15
	s_waitcnt lgkmcnt(0)
	v_pk_add_f32 v[16:17], v[16:17], v[18:19]
	ds_bpermute_b32 v19, v88, v17
	ds_bpermute_b32 v18, v88, v16
	v_exp_f32_e32 v21, v21
	v_exp_f32_e32 v22, v22
	v_rcp_f32_e32 v20, v20
	s_waitcnt lgkmcnt(0)
	v_pk_add_f32 v[16:17], v[16:17], v[18:19]
	ds_bpermute_b32 v19, v89, v17
	ds_bpermute_b32 v18, v89, v16
	v_add_f32_e32 v21, 1.0, v21
	v_add_f32_e32 v22, 1.0, v22
	v_rcp_f32_e32 v21, v21
	v_rcp_f32_e32 v22, v22
	s_waitcnt lgkmcnt(0)
	v_pk_add_f32 v[16:17], v[16:17], v[18:19]
	ds_bpermute_b32 v19, v90, v17
	ds_bpermute_b32 v18, v90, v16
	v_mul_f32_e32 v13, v13, v20
	v_mul_f32_e32 v20, v14, v21
	v_mul_f32_e32 v21, v15, v22
	v_cvt_pk_bf16_f32 v12, v12, v13
	s_waitcnt lgkmcnt(0)
	v_pk_add_f32 v[14:15], v[16:17], v[18:19]
	ds_bpermute_b32 v17, v91, v15
	ds_bpermute_b32 v16, v91, v14
	v_or_b32_e32 v18, 6, v36
	v_ashrrev_i32_e32 v19, 31, v18
	v_lshlrev_b64 v[18:19], 11, v[18:19]
	v_cvt_pk_bf16_f32 v13, v20, v21
	s_waitcnt lgkmcnt(0)
	v_pk_add_f32 v[14:15], v[14:15], v[16:17]
	s_nop 0
	v_pk_mul_f32 v[14:15], v[14:15], s[0:1] op_sel_hi:[1,0]
	s_nop 0
	v_fma_f32 v14, -v15, v15, v14
	v_max_f32_e32 v14, 0, v14
	v_add_f32_e32 v14, 0x358637bd, v14
	v_mul_f32_e32 v16, 0x4b800000, v14
	v_cmp_gt_f32_e32 vcc, s33, v14
	v_sub_f32_e32 v11, v11, v15
	v_sub_f32_e32 v10, v10, v15
	v_cndmask_b32_e32 v14, v14, v16, vcc
	v_rsq_f32_e32 v14, v14
	v_lshl_add_u64 v[16:17], s[22:23], 0, v[18:19]
	v_lshl_add_u64 v[16:17], v[16:17], 0, v[176:177]
	global_store_dwordx2 v[16:17], v[12:13], off offset:1536
	v_mul_f32_e32 v12, 0x45800000, v14
	v_cndmask_b32_e32 v12, v14, v12, vcc
	v_sub_f32_e32 v9, v9, v15
	v_sub_f32_e32 v8, v8, v15
	v_pk_mul_f32 v[8:9], v[8:9], v[12:13] op_sel_hi:[1,0]
	v_pk_mul_f32 v[10:11], v[10:11], v[12:13] op_sel_hi:[1,0]
	v_pk_fma_f32 v[0:1], v[0:1], v[8:9], v[4:5]
	v_pk_fma_f32 v[2:3], v[2:3], v[10:11], v[6:7]
	v_mul_f32_e32 v4, 0xbfb8aa3b, v0
	v_mul_f32_e32 v5, 0xbfb8aa3b, v1
	v_mul_f32_e32 v6, 0xbfb8aa3b, v2
	v_exp_f32_e32 v4, v4
	v_exp_f32_e32 v5, v5
	v_exp_f32_e32 v6, v6
	v_mul_f32_e32 v7, 0xbfb8aa3b, v3
	v_exp_f32_e32 v7, v7
	v_add_f32_e32 v4, 1.0, v4
	v_add_f32_e32 v5, 1.0, v5
	v_add_f32_e32 v6, 1.0, v6
	v_rcp_f32_e32 v4, v4
	v_rcp_f32_e32 v5, v5
	v_rcp_f32_e32 v6, v6
	v_add_f32_e32 v7, 1.0, v7
	v_rcp_f32_e32 v7, v7
	v_mul_f32_e32 v0, v0, v4
	v_mul_f32_e32 v1, v1, v5
	v_mul_f32_e32 v2, v2, v6
	v_mul_f32_e32 v3, v3, v7
	v_cvt_pk_bf16_f32 v0, v0, v1
	v_cvt_pk_bf16_f32 v1, v2, v3
	v_or_b32_e32 v2, 7, v36
	v_ashrrev_i32_e32 v3, 31, v2
	v_lshlrev_b64 v[2:3], 11, v[2:3]
	v_lshl_add_u64 v[2:3], s[22:23], 0, v[2:3]
	v_lshl_add_u64 v[2:3], v[2:3], 0, v[176:177]
	global_store_dwordx2 v[2:3], v[0:1], off offset:1536
	s_waitcnt lgkmcnt(0)
	s_barrier
	s_cbranch_execnz .LBB0_398
	s_branch .LBB0_420

; template <int W> __device__ __forceinline__ void pool_win(const float* up, int seq0, int L, int tfirst, int ch, LAS float* Pout) {
;     ...
;     for (int j = 0; j < NV; ++j) { const int tt = tfirst - LO + j; u[j] = (tt >= 0 && tt < L) ? up[(size_t)(seq0 + tt) * 256 + ch] : 0.f; }
.LBB0_852:
	s_add_i32 s76, s14, s51
	s_lshl_b64 s[96:97], s[76:77], 10
	v_lshl_add_u64 v[16:17], v[0:1], 0, s[96:97]
	global_load_dword v5, v[16:17], off
	s_mov_b32 s97, 0x10820
	s_movk_i32 s96, 0x1000
	s_add_i32 s37, s45, 32
	s_cmp_ge_u32 s37, s44
	v_mov_b32_e32 v57, 0
	s_cbranch_scc0 .LBB0_721
	s_branch .LBB0_722

; __device__ __forceinline__ unsigned xb_ld(unsigned* p)              { return __hip_atomic_load(p, __ATOMIC_RELAXED, __HIP_MEMORY_SCOPE_AGENT); }
; __device__ __forceinline__ void xcd_barrier_complete(unsigned* bar, unsigned x, unsigned& nloc, unsigned& nx) {
;     const unsigned G = gridDim.x * gridDim.y * gridDim.z;
;     unsigned sum, cnt, mine, sp = 0u;
;     for (;;) {
;         sum = 0u; cnt = 0u; mine = 0u;
; #pragma unroll
;         for (unsigned j = 0; j < 16; ++j) { const unsigned c = xb_ld(&bar[XB_XCNT(j)]); sum += c; cnt += (c > 0u) ? 1u : 0u; mine = (j == x) ? c : mine; }
;         if (sum == G) break;
;         __builtin_amdgcn_s_sleep(1);
;         if ((++sp & 255u) == 0u) { if (xb_ld(&bar[XB_TMO])) break; if (sp > XB_SPIN_CAP) { atomicAdd(&bar[XB_TMO], 1u); break; } }
;     }
;     nloc = mine > 0u ? mine : 1u; nx = cnt > 0u ? cnt : 1u;
; }
.LBB0_858:
	v_mov_b64_e32 v[12:13], s[40:41]
	global_load_dword v1, v[12:13], off offset:1024 sc1
	s_waitcnt lgkmcnt(0)
	global_load_dword v0, v[12:13], off offset:1280 sc1
	global_load_dword v2, v[12:13], off offset:1536 sc1
	s_or_b64 s[18:19], s[18:19], exec
	s_or_b64 s[16:17], s[16:17], exec
	s_waitcnt vmcnt(0) lgkmcnt(0)
	v_add_u32_e32 v3, v0, v1
	v_add_u32_e32 v4, v3, v2
	global_load_dword v3, v[12:13], off offset:1792 sc1
	s_waitcnt vmcnt(0) lgkmcnt(0)
	v_add_u32_e32 v5, v4, v3
	global_load_dword v4, v[12:13], off offset:2048 sc1
	s_waitcnt vmcnt(0) lgkmcnt(0)
	v_add_u32_e32 v6, v5, v4
	global_load_dword v5, v[12:13], off offset:2304 sc1
	s_waitcnt vmcnt(0) lgkmcnt(0)
	v_add_u32_e32 v7, v6, v5
	global_load_dword v6, v[12:13], off offset:2560 sc1
	s_waitcnt vmcnt(0) lgkmcnt(0)
	v_add_u32_e32 v8, v7, v6
	global_load_dword v7, v[12:13], off offset:2816 sc1
	s_waitcnt vmcnt(0) lgkmcnt(0)
	v_add_u32_e32 v9, v8, v7
	global_load_dword v8, v[12:13], off offset:3072 sc1
	s_waitcnt vmcnt(0) lgkmcnt(0)
	v_add_u32_e32 v10, v9, v8
	global_load_dword v9, v[12:13], off offset:3328 sc1
	s_waitcnt vmcnt(0) lgkmcnt(0)
	v_add_u32_e32 v11, v10, v9
	global_load_dword v10, v[12:13], off offset:3584 sc1
	s_waitcnt vmcnt(0) lgkmcnt(0)
	v_add_u32_e32 v14, v11, v10
	global_load_dword v11, v[12:13], off offset:3840 sc1
	v_mov_b64_e32 v[12:13], s[0:1]
	global_load_dword v12, v[12:13], off sc1
	s_waitcnt vmcnt(0) lgkmcnt(0)
	v_add_u32_e32 v14, v14, v11
	v_add_u32_e32 v16, v14, v12
	v_mov_b64_e32 v[14:15], s[4:5]
	global_load_dword v13, v[14:15], off sc1
	v_mov_b64_e32 v[14:15], s[6:7]
	global_load_dword v14, v[14:15], off sc1
	s_waitcnt vmcnt(0) lgkmcnt(0)
	v_add_u32_e32 v16, v16, v13
	v_add_u32_e32 v18, v16, v14
	v_mov_b64_e32 v[16:17], s[8:9]
	global_load_dword v15, v[16:17], off sc1
	s_waitcnt vmcnt(0) lgkmcnt(0)
	v_add_u32_e32 v16, v18, v15
	v_cmp_ne_u32_e32 vcc, s78, v16
	s_and_saveexec_b64 s[20:21], vcc
	s_cbranch_execz .LBB0_857
	s_and_b32 s24, s30, 0xff
	s_mov_b64 s[22:23], -1
	s_cmp_eq_u32 s24, 0
	s_mov_b64 s[26:27], -1
	s_mov_b64 s[24:25], -1
	s_sleep 1
	s_cbranch_scc1 .LBB0_861
	s_and_saveexec_b64 s[28:29], s[26:27]
	s_cbranch_execz .LBB0_856
	s_branch .LBB0_864
.LBB0_861:
	v_mov_b64_e32 v[16:17], s[40:41]
	global_load_dword v16, v[16:17], off offset:512 sc1
	s_mov_b64 s[26:27], 0
	s_waitcnt vmcnt(0) lgkmcnt(0)
	v_cmp_eq_u32_e32 vcc, 0, v16
	s_and_saveexec_b64 s[28:29], vcc
	s_cmp_lt_u32 s30, 0x40001
	s_cselect_b64 s[26:27], -1, 0
	s_xor_b64 s[24:25], exec, -1
	s_and_b64 s[26:27], s[26:27], exec
	s_or_b64 exec, exec, s[28:29]
	s_and_saveexec_b64 s[28:29], s[26:27]
	s_cbranch_execz .LBB0_856

; __device__ __forceinline__ unsigned xb_ld(unsigned* p)              { return __hip_atomic_load(p, __ATOMIC_RELAXED, __HIP_MEMORY_SCOPE_AGENT); }
; __device__ __forceinline__ void xcd_barrier_complete(unsigned* bar, unsigned x, unsigned& nloc, unsigned& nx) {
;     ...
;         if ((++sp & 255u) == 0u) { if (xb_ld(&bar[XB_TMO])) break; if (sp > XB_SPIN_CAP) { atomicAdd(&bar[XB_TMO], 1u); break; } }
.LBB0_865:
	s_or_b64 exec, exec, s[10:11]
	s_xor_b64 s[0:1], s[12:13], -1
	s_and_saveexec_b64 s[4:5], s[0:1]
	s_xor_b64 s[0:1], exec, s[4:5]
	s_cbranch_execz .LBB0_867
	v_mov_b64_e32 v[16:17], s[40:41]
	global_atomic_add v[16:17], v225, off offset:512

; __device__ __forceinline__ unsigned xb_ld(unsigned* p)              { return __hip_atomic_load(p, __ATOMIC_RELAXED, __HIP_MEMORY_SCOPE_AGENT); }
; __device__ __forceinline__ unsigned xb_add(unsigned* p, unsigned v) { return __hip_atomic_fetch_add(p, v, __ATOMIC_RELAXED, __HIP_MEMORY_SCOPE_AGENT); }
; #define XB_SPIN(cond, bar) do { unsigned _sp = 0; while (cond) { __builtin_amdgcn_s_sleep(1); \
;     if ((++_sp & 255u) == 0u) { if (xb_ld(&(bar)[XB_TMO])) break; if (_sp > XB_SPIN_CAP) { atomicAdd(&(bar)[XB_TMO], 1u); break; } } } } while (0)
; __device__ __forceinline__ void xcd_barrier(const XcdBarrier& b) {
;     ...
;         unsigned nloc = b.st[0], nx = b.st[1];
;         if (nloc == 0u) { xcd_barrier_complete(bar, b.x, nloc, nx); b.st[0] = nloc; b.st[1] = nx; }
;         const unsigned old = xb_add(&bar[XB_XSUB(b.x)], 1u);
;         const unsigned gen = old / nloc;
;         if (old + 1u == (gen + 1u) * nloc) {
;             __builtin_amdgcn_fence(__ATOMIC_RELEASE, "agent");
;             asm volatile("s_waitcnt vmcnt(0)" ::: "memory");
;             const unsigned og = xb_add(&bar[XB_TOP], 1u);
;             const unsigned tg = og / nx;
;             if (og + 1u == (tg + 1u) * nx) xb_add(&bar[XB_TOPGEN], 1u);
;             else XB_SPIN(xb_ld(&bar[XB_TOPGEN]) == tg, bar);
;             __builtin_amdgcn_fence(__ATOMIC_ACQUIRE, "agent");
;             xb_add(&bar[XB_XGEN(b.x)], 1u);
;             asm volatile("s_waitcnt vmcnt(0)" ::: "memory");
;         } else {
;             XB_SPIN(xb_ld(&bar[XB_XGEN(b.x)]) == gen, bar);
.LBB0_868:
	s_lshl_b32 s0, s36, 8
	s_add_u32 s25, s40, s0
	s_addc_u32 s24, s41, 0
	v_mov_b32_e32 v1, s25
	v_add_co_u32_e32 v4, vcc, 0x1000, v1
	v_mov_b32_e32 v1, s24
	s_nop 0
	v_addc_co_u32_e32 v5, vcc, 0, v1, vcc
	global_atomic_add v3, v[4:5], v225, off offset:1024 sc0
	v_cvt_f32_u32_e32 v1, v2
	v_sub_u32_e32 v4, 0, v2
	v_rcp_iflag_f32_e32 v1, v1
	s_nop 0
	v_mul_f32_e32 v1, 0x4f7ffffe, v1
	v_cvt_u32_f32_e32 v1, v1
	v_mul_lo_u32 v4, v4, v1
	v_mul_hi_u32 v4, v1, v4
	v_add_u32_e32 v1, v1, v4
	s_waitcnt vmcnt(0) lgkmcnt(0)
	v_mul_hi_u32 v1, v3, v1
	v_mul_lo_u32 v4, v1, v2
	v_sub_u32_e32 v4, v3, v4
	v_cmp_ge_u32_e32 vcc, v4, v2
	v_add_u32_e32 v5, 1, v1
	s_nop 0
	v_cndmask_b32_e32 v1, v1, v5, vcc
	v_sub_u32_e32 v5, v4, v2
	v_cndmask_b32_e32 v4, v4, v5, vcc
	v_cmp_ge_u32_e32 vcc, v4, v2
	v_add_u32_e32 v4, 1, v1
	s_nop 0
	v_cndmask_b32_e32 v1, v1, v4, vcc
	v_add_u32_e32 v4, 1, v3
	v_mad_u64_u32 v[2:3], s[0:1], v2, v1, v[2:3]
	v_cmp_ne_u32_e32 vcc, v4, v2
	s_and_saveexec_b64 s[0:1], vcc
	s_xor_b64 s[0:1], exec, s[0:1]
	s_cbranch_execz .LBB0_881
	v_mov_b32_e32 v0, s25
	v_add_co_u32_e32 v2, vcc, 0x2000, v0
	v_mov_b32_e32 v0, s24
	s_nop 0
	v_addc_co_u32_e32 v3, vcc, 0, v0, vcc
	global_load_dword v0, v[2:3], off offset:1024 sc1
	s_add_u32 s6, s25, 0x2400
	s_addc_u32 s7, s24, 0
	s_waitcnt vmcnt(0) lgkmcnt(0)
	v_cmp_eq_u32_e32 vcc, v0, v1
	s_and_saveexec_b64 s[4:5], vcc
	s_cbranch_execz .LBB0_880
	s_mov_b32 s26, 1
	s_mov_b64 s[8:9], 0
	s_branch .LBB0_872

; __device__ __forceinline__ unsigned xb_ld(unsigned* p)              { return __hip_atomic_load(p, __ATOMIC_RELAXED, __HIP_MEMORY_SCOPE_AGENT); }
; #define XB_SPIN(cond, bar) do { unsigned _sp = 0; while (cond) { __builtin_amdgcn_s_sleep(1); \
;     if ((++_sp & 255u) == 0u) { if (xb_ld(&(bar)[XB_TMO])) break; if (_sp > XB_SPIN_CAP) { atomicAdd(&(bar)[XB_TMO], 1u); break; } } } } while (0)
; __device__ __forceinline__ void xcd_barrier(const XcdBarrier& b) {
;     ...
;             XB_SPIN(xb_ld(&bar[XB_XGEN(b.x)]) == gen, bar);
.LBB0_872:
	s_and_b32 s18, s26, 0xff
	s_mov_b64 s[16:17], -1
	s_cmp_lg_u32 s18, 0
	s_mov_b64 s[18:19], -1
	s_sleep 1
	s_cbranch_scc1 .LBB0_876
	v_mov_b64_e32 v[2:3], s[40:41]
	global_load_dword v0, v[2:3], off offset:512 sc1
	s_mov_b64 s[18:19], 0
	s_mov_b64 s[20:21], -1
	s_waitcnt vmcnt(0) lgkmcnt(0)
	v_cmp_eq_u32_e32 vcc, 0, v0
	s_and_saveexec_b64 s[22:23], vcc
	s_cmp_lt_u32 s26, 0x40001
	s_cselect_b64 s[18:19], -1, 0
	s_xor_b64 s[20:21], exec, -1
	s_and_b64 s[18:19], s[18:19], exec
	s_or_b64 exec, exec, s[22:23]

; __device__ __forceinline__ unsigned xb_ld(unsigned* p)              { return __hip_atomic_load(p, __ATOMIC_RELAXED, __HIP_MEMORY_SCOPE_AGENT); }
; #define XB_SPIN(cond, bar) do { unsigned _sp = 0; while (cond) { __builtin_amdgcn_s_sleep(1); \
;     if ((++_sp & 255u) == 0u) { if (xb_ld(&(bar)[XB_TMO])) break; if (_sp > XB_SPIN_CAP) { atomicAdd(&(bar)[XB_TMO], 1u); break; } } } } while (0)
; __device__ __forceinline__ void xcd_barrier(const XcdBarrier& b) {
;     ...
;             XB_SPIN(xb_ld(&bar[XB_XGEN(b.x)]) == gen, bar);
.LBB0_878:
	s_or_b64 exec, exec, s[8:9]
	s_xor_b64 s[6:7], s[10:11], -1
	s_and_saveexec_b64 s[8:9], s[6:7]
	s_xor_b64 s[8:9], exec, s[8:9]
	s_cbranch_execz .LBB0_880
	v_mov_b64_e32 v[0:1], s[40:41]
	global_atomic_add v[0:1], v225, off offset:512

; __device__ __forceinline__ unsigned xb_ld(unsigned* p)              { return __hip_atomic_load(p, __ATOMIC_RELAXED, __HIP_MEMORY_SCOPE_AGENT); }
; __device__ __forceinline__ unsigned xb_add(unsigned* p, unsigned v) { return __hip_atomic_fetch_add(p, v, __ATOMIC_RELAXED, __HIP_MEMORY_SCOPE_AGENT); }
; #define XB_SPIN(cond, bar) do { unsigned _sp = 0; while (cond) { __builtin_amdgcn_s_sleep(1); \
;     if ((++_sp & 255u) == 0u) { if (xb_ld(&(bar)[XB_TMO])) break; if (_sp > XB_SPIN_CAP) { atomicAdd(&(bar)[XB_TMO], 1u); break; } } } } while (0)
; __device__ __forceinline__ void xcd_barrier(const XcdBarrier& b) {
;     ...
;         if (old + 1u == (gen + 1u) * nloc) {
;             __builtin_amdgcn_fence(__ATOMIC_RELEASE, "agent");
;             asm volatile("s_waitcnt vmcnt(0)" ::: "memory");
;             const unsigned og = xb_add(&bar[XB_TOP], 1u);
;             const unsigned tg = og / nx;
;             if (og + 1u == (tg + 1u) * nx) xb_add(&bar[XB_TOPGEN], 1u);
;             else XB_SPIN(xb_ld(&bar[XB_TOPGEN]) == tg, bar);
.LBB0_881:
	s_andn2_saveexec_b64 s[0:1], s[0:1]
	s_cbranch_execz .LBB0_897
	v_mov_b32_e32 v1, s40
	v_add_co_u32_e32 v2, vcc, 0x3000, v1
	v_mov_b32_e32 v1, s41
	buffer_wbl2 sc1
	s_waitcnt vmcnt(0)
	v_addc_co_u32_e32 v3, vcc, 0, v1, vcc
	global_atomic_add v1, v[2:3], v225, off offset:1024 sc0
	v_cvt_f32_u32_e32 v2, v0
	v_sub_u32_e32 v3, 0, v0
	s_mov_b64 s[6:7], -1
	v_rcp_iflag_f32_e32 v2, v2
	s_nop 0
	v_mul_f32_e32 v2, 0x4f7ffffe, v2
	v_cvt_u32_f32_e32 v2, v2
	v_mul_lo_u32 v3, v3, v2
	v_mul_hi_u32 v3, v2, v3
	v_add_u32_e32 v2, v2, v3
	s_waitcnt vmcnt(0) lgkmcnt(0)
	v_mul_hi_u32 v2, v1, v2
	v_mul_lo_u32 v3, v2, v0
	v_sub_u32_e32 v3, v1, v3
	v_cmp_ge_u32_e32 vcc, v3, v0
	v_add_u32_e32 v4, 1, v2
	s_nop 0
	v_cndmask_b32_e32 v2, v2, v4, vcc
	v_sub_u32_e32 v4, v3, v0
	v_cndmask_b32_e32 v3, v3, v4, vcc
	v_cmp_ge_u32_e32 vcc, v3, v0
	v_add_u32_e32 v3, 1, v2
	s_nop 0
	v_cndmask_b32_e32 v2, v2, v3, vcc
	v_add_u32_e32 v3, 1, v1
	v_mad_u64_u32 v[0:1], s[0:1], v0, v2, v[0:1]
	s_add_u32 s0, s40, 0x3500
	s_addc_u32 s1, s41, 0
	v_cmp_ne_u32_e32 vcc, v3, v0
	v_mov_b64_e32 v[0:1], s[0:1]
	s_and_saveexec_b64 s[4:5], vcc
	s_cbranch_execz .LBB0_894
	v_mov_b64_e32 v[0:1], s[0:1]
	global_load_dword v0, v[0:1], off sc1
	s_mov_b64 s[10:11], 0
	s_waitcnt vmcnt(0) lgkmcnt(0)
	v_cmp_eq_u32_e32 vcc, v0, v2
	s_and_saveexec_b64 s[8:9], vcc
	s_cbranch_execz .LBB0_893
	s_add_u32 s6, s40, 0x200
	s_addc_u32 s7, s41, 0
	s_mov_b32 s26, 1
	s_branch .LBB0_886

; __device__ __forceinline__ unsigned xb_ld(unsigned* p)              { return __hip_atomic_load(p, __ATOMIC_RELAXED, __HIP_MEMORY_SCOPE_AGENT); }
; #define XB_SPIN(cond, bar) do { unsigned _sp = 0; while (cond) { __builtin_amdgcn_s_sleep(1); \
;     if ((++_sp & 255u) == 0u) { if (xb_ld(&(bar)[XB_TMO])) break; if (_sp > XB_SPIN_CAP) { atomicAdd(&(bar)[XB_TMO], 1u); break; } } } } while (0)
; __device__ __forceinline__ void xcd_barrier(const XcdBarrier& b) {
;     ...
;             else XB_SPIN(xb_ld(&bar[XB_TOPGEN]) == tg, bar);
.LBB0_888:
	v_mov_b64_e32 v[0:1], s[6:7]
	global_load_dword v0, v[0:1], off sc1
	s_mov_b64 s[20:21], 0
	s_mov_b64 s[18:19], -1
	s_waitcnt vmcnt(0) lgkmcnt(0)
	v_cmp_eq_u32_e32 vcc, 0, v0
	s_and_saveexec_b64 s[22:23], vcc
	s_cmp_lt_u32 s26, 0x40001
	s_cselect_b64 s[20:21], -1, 0
	s_xor_b64 s[18:19], exec, -1
	s_and_b64 s[20:21], s[20:21], exec
	s_or_b64 exec, exec, s[22:23]
	s_and_saveexec_b64 s[22:23], s[20:21]
	s_cbranch_execz .LBB0_885
.LBB0_891:
	v_mov_b64_e32 v[0:1], s[0:1]
	global_load_dword v0, v[0:1], off sc1
	s_add_i32 s26, s26, 1
	s_or_b64 s[18:19], s[18:19], exec
	s_waitcnt vmcnt(0) lgkmcnt(0)
	v_cmp_ne_u32_e32 vcc, v0, v2
	s_orn2_b64 s[16:17], vcc, exec
	s_branch .LBB0_885

;     __device__ __forceinline__ void operator()(const f32x4 (&acc)[2][2][4][2], const Unit& u, int wr, int wc, int fr, int fq) const {
;     ...
;         f32x4 gt[2][2], gs[2][2];
; #pragma unroll
;         for (int bj = 0; bj < 2; ++bj)
; #pragma unroll
;             for (int n = 0; n < 2; ++n) {
;                 const int col = cb + 128 * bj + 4 * n;
;                 gt[bj][n] = *(const f32x4*)(gate + v * 6144 + col);
;                 if (nxt) { const f32x4 a = *(const f32x4*)(ng + col), s = *(const f32x4*)(nsc + v * 6144 + col); gs[bj][n] = a * (s + 1.f); } else gs[bj][n] = (f32x4){0.f, 0.f, 0.f, 0.f};
;             }
; #pragma unroll
;         for (int q2 = 0; q2 < 4; ++q2) {
;             const int ai = q2 >> 1, m0 = (q2 & 1) * 2;
;             f32x4 pre[2][2][2];
; #pragma unroll
;             for (int mm = 0; mm < 2; ++mm) {
;                 const int row = pm * 256 + ai * 128 + wr * 64 + (m0 + mm) * 16 + fr;
;                 const float* src = isctx ? res_ctx + (size_t)(row - MLAT) * DM : res_lat + (size_t)row * DM;
; #pragma unroll
;                 for (int bj = 0; bj < 2; ++bj) { pre[mm][bj][0] = *(const f32x4*)(src + cb + 128 * bj); pre[mm][bj][1] = *(const f32x4*)(src + cb + 128 * bj + 4); }
;             }
.LBB0_913:
	s_min_i32 s8, s52, 64
	s_lshr_b32 s8, s8, 5
	s_mulk_i32 s8, 0x1800
	s_ashr_i32 s9, s8, 31
	s_lshl_b64 s[8:9], s[8:9], 2
	v_lshl_or_b32 v192, s53, 8, v236
	s_add_u32 s10, s62, s8
	s_addc_u32 s11, s63, s9
	v_ashrrev_i32_e32 v193, 31, v192
	v_lshl_add_u64 v[56:57], v[192:193], 2, s[10:11]
	global_load_dwordx4 v[64:67], v[56:57], off
	s_add_u32 s10, s87, s8
	s_addc_u32 s11, s81, s9
	v_cndmask_b32_e64 v48, 0, 1, s[82:83]
	v_lshlrev_b64 v[210:211], 2, v[192:193]
	v_mov_b32_e32 v198, 0
	v_cmp_ne_u32_e64 s[8:9], 1, v48
	s_andn2_b64 vcc, exec, s[82:83]
	v_lshl_add_u64 v[144:145], s[24:25], 0, v[210:211]
	v_lshl_add_u64 v[146:147], s[10:11], 0, v[210:211]
	v_mov_b32_e32 v202, 0
	v_mov_b32_e32 v203, 0
	v_mov_b32_e32 v206, 0
	v_mov_b32_e32 v207, 0
	s_cbranch_vccnz .LBB0_915
	global_load_dwordx4 v[48:51], v[146:147], off
	global_load_dwordx4 v[68:71], v[144:145], off
	s_waitcnt vmcnt(0) lgkmcnt(0)
	v_pk_add_f32 v[50:51], v[50:51], 1.0 op_sel_hi:[1,0]
	v_pk_add_f32 v[48:49], v[48:49], 1.0 op_sel_hi:[1,0]
	v_pk_mul_f32 v[206:207], v[70:71], v[50:51]
	v_pk_mul_f32 v[202:203], v[68:69], v[48:49]
.LBB0_915:
	global_load_dwordx4 v[68:71], v[56:57], off offset:16
	s_and_b64 vcc, exec, s[8:9]
	v_mov_b32_e32 v199, 0
	v_mov_b32_e32 v208, 0
	v_mov_b32_e32 v209, 0
	s_cbranch_vccnz .LBB0_917
	global_load_dwordx4 v[48:51], v[146:147], off offset:16
	global_load_dwordx4 v[148:151], v[144:145], off offset:16
	s_waitcnt vmcnt(0) lgkmcnt(0)
	v_pk_add_f32 v[50:51], v[50:51], 1.0 op_sel_hi:[1,0]
	v_pk_add_f32 v[48:49], v[48:49], 1.0 op_sel_hi:[1,0]
	v_pk_mul_f32 v[208:209], v[150:151], v[50:51]
	v_pk_mul_f32 v[198:199], v[148:149], v[48:49]
.LBB0_917:
	global_load_dwordx4 v[48:51], v[56:57], off offset:512
	v_mov_b32_e32 v194, 0
	s_and_b64 vcc, exec, s[8:9]
	v_mov_b32_e32 v196, 0
	v_mov_b32_e32 v197, 0
	v_mov_b32_e32 v200, 0
	v_mov_b32_e32 v201, 0
	s_cbranch_vccnz .LBB0_919
	global_load_dwordx4 v[148:151], v[146:147], off offset:512
	global_load_dwordx4 v[152:155], v[144:145], off offset:512
	s_waitcnt vmcnt(0) lgkmcnt(0)
	v_pk_add_f32 v[58:59], v[150:151], 1.0 op_sel_hi:[1,0]
	v_pk_add_f32 v[148:149], v[148:149], 1.0 op_sel_hi:[1,0]
	v_pk_mul_f32 v[200:201], v[154:155], v[58:59]
	v_pk_mul_f32 v[196:197], v[152:153], v[148:149]
.LBB0_919:
	global_load_dwordx4 v[56:59], v[56:57], off offset:528
	s_and_b64 vcc, exec, s[8:9]
	v_mov_b32_e32 v195, 0
	v_mov_b32_e32 v204, 0
	v_mov_b32_e32 v205, 0
	s_cbranch_vccnz .LBB0_921
	global_load_dwordx4 v[146:149], v[146:147], off offset:528
	s_nop 0
	global_load_dwordx4 v[150:153], v[144:145], off offset:528
	s_waitcnt vmcnt(0) lgkmcnt(0)
	v_pk_add_f32 v[144:145], v[148:149], 1.0 op_sel_hi:[1,0]
	v_pk_add_f32 v[146:147], v[146:147], 1.0 op_sel_hi:[1,0]
	v_pk_mul_f32 v[204:205], v[152:153], v[144:145]
	v_pk_mul_f32 v[194:195], v[150:151], v[146:147]
.LBB0_921:
	s_cmp_lt_i32 s52, 64
	s_cselect_b64 s[72:73], -1, 0
	s_cmp_gt_i32 s52, 63
	v_lshl_add_u32 v212, s52, 8, v234
	v_add_u32_e32 v218, 0xffffc000, v212
	s_cselect_b64 s[10:11], -1, 0
	v_cndmask_b32_e64 v144, v212, v218, s[10:11]
	s_and_b64 s[12:13], s[10:11], exec
	v_ashrrev_i32_e32 v145, 31, v144
	s_cselect_b32 s53, s23, s16
	s_cselect_b32 s52, s22, s17
	v_lshlrev_b64 v[144:145], 12, v[144:145]
	v_lshl_add_u64 v[144:145], s[52:53], 0, v[144:145]
	v_lshl_add_u64 v[144:145], v[144:145], 0, v[210:211]
	v_or_b32_e32 v214, 16, v212
	v_add_u32_e32 v216, 0xffffc010, v212
	global_load_dwordx4 v[172:175], v[144:145], off
	global_load_dwordx4 v[168:171], v[144:145], off offset:16
	global_load_dwordx4 v[164:167], v[144:145], off offset:512
	global_load_dwordx4 v[160:163], v[144:145], off offset:528
	v_cndmask_b32_e64 v144, v214, v216, s[10:11]
	v_ashrrev_i32_e32 v145, 31, v144
	v_lshlrev_b64 v[144:145], 12, v[144:145]
	v_lshl_add_u64 v[144:145], s[52:53], 0, v[144:145]
	v_lshl_add_u64 v[144:145], v[144:145], 0, v[210:211]
	global_load_dwordx4 v[156:159], v[144:145], off
	global_load_dwordx4 v[152:155], v[144:145], off offset:16
	global_load_dwordx4 v[148:151], v[144:145], off offset:512
	s_nop 0
	global_load_dwordx4 v[144:147], v[144:145], off offset:528
	s_mov_b64 s[12:13], -1
	s_and_b64 vcc, exec, s[72:73]
	v_ashrrev_i32_e32 v213, 31, v212
	s_cbranch_vccz .LBB0_923
	v_lshlrev_b64 v[220:221], 12, v[212:213]
	v_lshl_add_u64 v[220:221], s[90:91], 0, v[220:221]
	s_mov_b64 s[12:13], 0

; __device__ __forceinline__ unsigned pkbf(float lo, float hi) { return pg8::cvt_pk_bf16(lo, hi); }
;     __device__ __forceinline__ void operator()(const f32x4 (&acc)[2][2][4][2], const Unit& u, int wr, int wc, int fr, int fq) const {
;     ...
;             for (int mm = 0; mm < 2; ++mm) {
;                 const int m = m0 + mm;
;                 const int row = pm * 256 + ai * 128 + wr * 64 + m * 16 + fr;
;                 float* dst = isctx ? dst_ctx + (size_t)(row - MLAT) * DM : dst_lat + (size_t)row * DM;
;                 float ss = 0.f;
; #pragma unroll
;                 for (int bj = 0; bj < 2; ++bj) {
;                     const int col = cb + 128 * bj;
;                     const f32x4 x0 = pre[mm][bj][0] + gt[bj][0] * acc[ai][bj][m][0];
;                     const f32x4 x1 = pre[mm][bj][1] + gt[bj][1] * acc[ai][bj][m][1];
;                     *(f32x4*)(dst + col) = x0; *(f32x4*)(dst + col + 4) = x1;
;                     if (nxt) {
;                         ss += (x0[0] * x0[0] + x0[1] * x0[1]) + (x0[2] * x0[2] + x0[3] * x0[3]) + (x1[0] * x1[0] + x1[1] * x1[1]) + (x1[2] * x1[2] + x1[3] * x1[3]);
;                         const f32x4 y0 = x0 * gs[bj][0], y1 = x1 * gs[bj][1];
;                         u32x4 w; w.x = pkbf(y0[0], y0[1]); w.y = pkbf(y0[2], y0[3]); w.z = pkbf(y1[0], y1[1]); w.w = pkbf(y1[2], y1[3]);
;                         *(u32x4*)(xg + (size_t)row * DM + col) = w;
;                     }
.LBB0_925:
	v_lshlrev_b64 v[218:219], 11, v[212:213]
	s_waitcnt vmcnt(0) lgkmcnt(0)
	v_pk_fma_f32 v[136:137], v[136:137], v[68:69], v[168:169]
	v_lshl_add_u64 v[168:169], s[26:27], 0, v[218:219]
	v_pk_fma_f32 v[142:143], v[142:143], v[66:67], v[174:175]
	v_pk_fma_f32 v[140:141], v[140:141], v[64:65], v[172:173]
	v_pk_fma_f32 v[138:139], v[138:139], v[70:71], v[170:171]
	v_lshl_add_u64 v[170:171], v[192:193], 2, v[220:221]
	s_and_b64 vcc, exec, s[8:9]
	v_lshl_add_u64 v[168:169], v[192:193], 1, v[168:169]
	global_store_dwordx4 v[170:171], v[140:143], off
	global_store_dwordx4 v[170:171], v[136:139], off offset:16
	s_cbranch_vccnz .LBB0_927
	v_pk_mul_f32 v[172:173], v[142:143], v[142:143]
	v_pk_mul_f32 v[174:175], v[140:141], v[140:141]
	v_pk_mul_f32 v[142:143], v[206:207], v[142:143]
	v_pk_mov_b32 v[218:219], v[174:175], v[172:173] op_sel:[1,0]
	v_mov_b32_e32 v175, v173
	v_pk_add_f32 v[172:173], v[218:219], v[174:175]
	v_pk_mul_f32 v[174:175], v[138:139], v[138:139]
	v_pk_mul_f32 v[218:219], v[136:137], v[136:137]
	v_mov_b32_e32 v220, v174
	v_mov_b32_e32 v221, v218
	v_mov_b32_e32 v218, v175
	v_pk_add_f32 v[174:175], v[220:221], v[218:219]
	v_add_f32_e32 v172, v172, v173
	v_add_f32_e32 v172, v172, v175
	v_add_f32_e32 v172, v174, v172
	v_pk_mul_f32 v[174:175], v[208:209], v[138:139]
	v_pk_mul_f32 v[138:139], v[198:199], v[136:137]
	v_pk_mul_f32 v[140:141], v[202:203], v[140:141]
	s_nop 0
	v_cvt_pk_bf16_f32 v136, v140, v141
	v_cvt_pk_bf16_f32 v137, v142, v143
	v_cvt_pk_bf16_f32 v138, v138, v139
	v_cvt_pk_bf16_f32 v139, v174, v175
	global_store_dwordx4 v[168:169], v[136:139], off
	s_branch .LBB0_928

; __device__ __forceinline__ unsigned pkbf(float lo, float hi) { return pg8::cvt_pk_bf16(lo, hi); }
;     __device__ __forceinline__ void operator()(const f32x4 (&acc)[2][2][4][2], const Unit& u, int wr, int wc, int fr, int fq) const {
;     ...
;                 for (int bj = 0; bj < 2; ++bj) {
;                     const int col = cb + 128 * bj;
;                     const f32x4 x0 = pre[mm][bj][0] + gt[bj][0] * acc[ai][bj][m][0];
;                     const f32x4 x1 = pre[mm][bj][1] + gt[bj][1] * acc[ai][bj][m][1];
;                     *(f32x4*)(dst + col) = x0; *(f32x4*)(dst + col + 4) = x1;
;                     if (nxt) {
;                         ss += (x0[0] * x0[0] + x0[1] * x0[1]) + (x0[2] * x0[2] + x0[3] * x0[3]) + (x1[0] * x1[0] + x1[1] * x1[1]) + (x1[2] * x1[2] + x1[3] * x1[3]);
;                         const f32x4 y0 = x0 * gs[bj][0], y1 = x1 * gs[bj][1];
;                         u32x4 w; w.x = pkbf(y0[0], y0[1]); w.y = pkbf(y0[2], y0[3]); w.z = pkbf(y1[0], y1[1]); w.w = pkbf(y1[2], y1[3]);
;                         *(u32x4*)(xg + (size_t)row * DM + col) = w;
;                     }
;                 }
;                 if (nxt) { ss += __shfl_xor(ss, 16); ss += __shfl_xor(ss, 32); if (fq == 0) unsafeAtomicAdd(rowsq_next + row, ss); }
.LBB0_928:
	v_pk_fma_f32 v[134:135], v[134:135], v[50:51], v[166:167]
	v_pk_fma_f32 v[132:133], v[132:133], v[48:49], v[164:165]
	v_pk_fma_f32 v[130:131], v[130:131], v[58:59], v[162:163]
	v_pk_fma_f32 v[128:129], v[128:129], v[56:57], v[160:161]
	s_and_b64 vcc, exec, s[8:9]
	global_store_dwordx4 v[170:171], v[132:135], off offset:512
	global_store_dwordx4 v[170:171], v[128:131], off offset:528
	s_cbranch_vccnz .LBB0_932
	v_mul_f32_e32 v136, v133, v133
	v_mul_f32_e32 v137, v135, v135
	v_fmac_f32_e32 v136, v132, v132
	v_fmac_f32_e32 v137, v134, v134
	v_add_f32_e32 v136, v136, v137
	v_mul_f32_e32 v137, v129, v129
	v_fmac_f32_e32 v137, v128, v128
	v_add_f32_e32 v136, v136, v137
	v_mul_f32_e32 v137, v131, v131
	v_fmac_f32_e32 v137, v130, v130
	v_add_f32_e32 v136, v137, v136
	v_add_f32_e32 v138, v136, v172
	v_pk_mul_f32 v[134:135], v[200:201], v[134:135]
	v_pk_mul_f32 v[132:133], v[196:197], v[132:133]
	v_pk_mul_f32 v[136:137], v[204:205], v[130:131]
	v_pk_mul_f32 v[130:131], v[194:195], v[128:129]
	v_cvt_pk_bf16_f32 v128, v132, v133
	v_cvt_pk_bf16_f32 v129, v134, v135
	s_nop 0
	v_cvt_pk_bf16_f32 v130, v130, v131
	v_cvt_pk_bf16_f32 v131, v136, v137
	global_store_dwordx4 v[168:169], v[128:131], off offset:256
	s_nop 1
	v_and_b32_e32 v129, 64, v229
	v_xor_b32_e32 v128, 16, v229
	v_add_u32_e32 v129, 64, v129
	v_cmp_lt_i32_e32 vcc, v128, v129
	v_xor_b32_e32 v130, 32, v229
	s_nop 0
	v_cndmask_b32_e32 v128, v229, v128, vcc
	v_lshlrev_b32_e32 v128, 2, v128
	ds_bpermute_b32 v128, v128, v138
	v_cmp_lt_i32_e32 vcc, v130, v129
	s_waitcnt lgkmcnt(0)
	v_add_f32_e32 v128, v138, v128
	v_cndmask_b32_e32 v129, v229, v130, vcc
	v_lshlrev_b32_e32 v129, 2, v129
	ds_bpermute_b32 v129, v129, v128
	s_and_saveexec_b64 s[12:13], s[4:5]
	s_cbranch_execz .LBB0_931
	v_lshl_add_u64 v[130:131], v[212:213], 2, s[28:29]
	s_waitcnt lgkmcnt(0)
	v_add_f32_e32 v128, v128, v129
	global_atomic_add_f32 v[130:131], v128, off

; __device__ __forceinline__ unsigned pkbf(float lo, float hi) { return pg8::cvt_pk_bf16(lo, hi); }
;     __device__ __forceinline__ void operator()(const f32x4 (&acc)[2][2][4][2], const Unit& u, int wr, int wc, int fr, int fq) const {
;     ...
;             for (int mm = 0; mm < 2; ++mm) {
;                 const int m = m0 + mm;
;                 const int row = pm * 256 + ai * 128 + wr * 64 + m * 16 + fr;
;                 float* dst = isctx ? dst_ctx + (size_t)(row - MLAT) * DM : dst_lat + (size_t)row * DM;
;                 float ss = 0.f;
; #pragma unroll
;                 for (int bj = 0; bj < 2; ++bj) {
;                     const int col = cb + 128 * bj;
;                     const f32x4 x0 = pre[mm][bj][0] + gt[bj][0] * acc[ai][bj][m][0];
;                     const f32x4 x1 = pre[mm][bj][1] + gt[bj][1] * acc[ai][bj][m][1];
;                     *(f32x4*)(dst + col) = x0; *(f32x4*)(dst + col + 4) = x1;
;                     if (nxt) {
;                         ss += (x0[0] * x0[0] + x0[1] * x0[1]) + (x0[2] * x0[2] + x0[3] * x0[3]) + (x1[0] * x1[0] + x1[1] * x1[1]) + (x1[2] * x1[2] + x1[3] * x1[3]);
;                         const f32x4 y0 = x0 * gs[bj][0], y1 = x1 * gs[bj][1];
;                         u32x4 w; w.x = pkbf(y0[0], y0[1]); w.y = pkbf(y0[2], y0[3]); w.z = pkbf(y1[0], y1[1]); w.w = pkbf(y1[2], y1[3]);
;                         *(u32x4*)(xg + (size_t)row * DM + col) = w;
;                     }
;                 }
;                 if (nxt) { ss += __shfl_xor(ss, 16); ss += __shfl_xor(ss, 32); if (fq == 0) unsafeAtomicAdd(rowsq_next + row, ss); }
.LBB0_936:
	s_waitcnt lgkmcnt(0)
	v_pk_fma_f32 v[128:129], v[126:127], v[66:67], v[158:159]
	v_pk_fma_f32 v[126:127], v[124:125], v[64:65], v[156:157]
	v_pk_fma_f32 v[132:133], v[122:123], v[70:71], v[154:155]
	v_pk_fma_f32 v[130:131], v[120:121], v[68:69], v[152:153]
	v_lshl_add_u64 v[134:135], v[192:193], 2, v[134:135]
	s_and_b64 vcc, exec, s[8:9]
	v_pk_fma_f32 v[124:125], v[116:117], v[48:49], v[148:149]
	v_pk_fma_f32 v[120:121], v[112:113], v[56:57], v[144:145]
	global_store_dwordx4 v[134:135], v[126:129], off
	global_store_dwordx4 v[134:135], v[130:133], off offset:16
	s_cbranch_vccnz .LBB0_998
	v_mul_f32_e32 v116, v127, v127
	v_mul_f32_e32 v117, v129, v129
	v_fmac_f32_e32 v116, v126, v126
	v_fmac_f32_e32 v117, v128, v128
	v_add_f32_e32 v116, v116, v117
	v_mul_f32_e32 v117, v131, v131
	v_fmac_f32_e32 v117, v130, v130
	v_lshlrev_b64 v[112:113], 11, v[214:215]
	v_add_f32_e32 v116, v116, v117
	v_mul_f32_e32 v117, v133, v133
	v_fmac_f32_e32 v117, v132, v132
	v_lshl_add_u64 v[112:113], s[26:27], 0, v[112:113]
	v_add_f32_e32 v136, v117, v116
	v_pk_mul_f32 v[116:117], v[206:207], v[128:129]
	v_pk_mul_f32 v[122:123], v[202:203], v[126:127]
	v_pk_mul_f32 v[128:129], v[198:199], v[130:131]
	v_cvt_pk_bf16_f32 v126, v122, v123
	v_cvt_pk_bf16_f32 v127, v116, v117
	v_lshl_add_u64 v[112:113], v[192:193], 1, v[112:113]
	v_pk_mul_f32 v[132:133], v[208:209], v[132:133]
	v_cvt_pk_bf16_f32 v128, v128, v129
	v_mul_f32_e32 v116, v125, v125
	v_cvt_pk_bf16_f32 v129, v132, v133
	global_store_dwordx4 v[112:113], v[126:129], off
	v_fmac_f32_e32 v116, v124, v124
	v_pk_fma_f32 v[122:123], v[114:115], v[58:59], v[146:147]
	v_pk_fma_f32 v[126:127], v[118:119], v[50:51], v[150:151]
	global_store_dwordx4 v[134:135], v[124:127], off offset:512
	global_store_dwordx4 v[134:135], v[120:123], off offset:528
	v_mul_f32_e32 v117, v127, v127
	v_fmac_f32_e32 v117, v126, v126
	v_add_f32_e32 v116, v116, v117
	v_mul_f32_e32 v117, v121, v121
	v_fmac_f32_e32 v117, v120, v120
	v_add_f32_e32 v116, v116, v117
	v_mul_f32_e32 v117, v123, v123
	v_fmac_f32_e32 v117, v122, v122
	v_add_f32_e32 v116, v117, v116
	v_add_f32_e32 v130, v136, v116
	v_pk_mul_f32 v[116:117], v[200:201], v[126:127]
	v_pk_mul_f32 v[126:127], v[196:197], v[124:125]
	v_pk_mul_f32 v[128:129], v[194:195], v[120:121]
	v_pk_mul_f32 v[122:123], v[204:205], v[122:123]
	v_cvt_pk_bf16_f32 v126, v126, v127
	v_cvt_pk_bf16_f32 v127, v116, v117
	v_cvt_pk_bf16_f32 v128, v128, v129
	v_xor_b32_e32 v116, 32, v229
	v_cvt_pk_bf16_f32 v129, v122, v123
	global_store_dwordx4 v[112:113], v[126:129], off offset:256
	v_and_b32_e32 v113, 64, v229
	v_xor_b32_e32 v112, 16, v229
	v_add_u32_e32 v113, 64, v113
	v_cmp_lt_i32_e32 vcc, v112, v113
	s_nop 1
	v_cndmask_b32_e32 v112, v229, v112, vcc
	v_lshlrev_b32_e32 v112, 2, v112
	ds_bpermute_b32 v112, v112, v130
	v_cmp_lt_i32_e32 vcc, v116, v113
	s_waitcnt lgkmcnt(0)
	v_add_f32_e32 v112, v130, v112
	v_cndmask_b32_e32 v113, v229, v116, vcc
	v_lshlrev_b32_e32 v113, 2, v113
	ds_bpermute_b32 v113, v113, v112
	s_and_saveexec_b64 s[72:73], s[4:5]
	s_cbranch_execz .LBB0_939
	v_lshl_add_u64 v[116:117], v[214:215], 2, s[28:29]
	s_waitcnt lgkmcnt(0)
	v_add_f32_e32 v112, v112, v113
	global_atomic_add_f32 v[116:117], v112, off

;     __device__ __forceinline__ void operator()(const f32x4 (&acc)[2][2][4][2], const Unit& u, int wr, int wc, int fr, int fq) const {
;     ...
;         for (int q2 = 0; q2 < 4; ++q2) {
;             const int ai = q2 >> 1, m0 = (q2 & 1) * 2;
;             f32x4 pre[2][2][2];
; #pragma unroll
;             for (int mm = 0; mm < 2; ++mm) {
;                 const int row = pm * 256 + ai * 128 + wr * 64 + (m0 + mm) * 16 + fr;
;                 const float* src = isctx ? res_ctx + (size_t)(row - MLAT) * DM : res_lat + (size_t)row * DM;
; #pragma unroll
;                 for (int bj = 0; bj < 2; ++bj) { pre[mm][bj][0] = *(const f32x4*)(src + cb + 128 * bj); pre[mm][bj][1] = *(const f32x4*)(src + cb + 128 * bj + 4); }
;             }
; #pragma unroll
;             for (int mm = 0; mm < 2; ++mm) {
;                 const int m = m0 + mm;
;                 const int row = pm * 256 + ai * 128 + wr * 64 + m * 16 + fr;
;                 float* dst = isctx ? dst_ctx + (size_t)(row - MLAT) * DM : dst_lat + (size_t)row * DM;
;                 float ss = 0.f;
; #pragma unroll
;                 for (int bj = 0; bj < 2; ++bj) {
;                     const int col = cb + 128 * bj;
;                     const f32x4 x0 = pre[mm][bj][0] + gt[bj][0] * acc[ai][bj][m][0];
;                     const f32x4 x1 = pre[mm][bj][1] + gt[bj][1] * acc[ai][bj][m][1];
;                     *(f32x4*)(dst + col) = x0; *(f32x4*)(dst + col + 4) = x1;
.LBB0_940:
	v_pk_fma_f32 v[126:127], v[118:119], v[50:51], v[150:151]
	v_pk_fma_f32 v[122:123], v[114:115], v[58:59], v[146:147]
	global_store_dwordx4 v[134:135], v[124:127], off offset:512
	global_store_dwordx4 v[134:135], v[120:123], off offset:528
.LBB0_941:
	v_or_b32_e32 v148, 32, v212
	v_add_u32_e32 v150, 0xffffc020, v212
	v_cndmask_b32_e64 v112, v148, v150, s[10:11]
	s_waitcnt lgkmcnt(0)
	v_ashrrev_i32_e32 v113, 31, v112
	v_lshlrev_b64 v[112:113], 12, v[112:113]
	v_lshl_add_u64 v[112:113], s[52:53], 0, v[112:113]
	v_lshl_add_u64 v[112:113], v[112:113], 0, v[210:211]
	v_or_b32_e32 v144, 48, v212
	v_add_u32_e32 v146, 0xffffc030, v212
	global_load_dwordx4 v[140:143], v[112:113], off
	global_load_dwordx4 v[136:139], v[112:113], off offset:16
	global_load_dwordx4 v[132:135], v[112:113], off offset:512
	global_load_dwordx4 v[128:131], v[112:113], off offset:528
	v_cndmask_b32_e64 v112, v144, v146, s[10:11]
	v_ashrrev_i32_e32 v113, 31, v112
	v_lshlrev_b64 v[112:113], 12, v[112:113]
	v_lshl_add_u64 v[112:113], s[52:53], 0, v[112:113]
	v_lshl_add_u64 v[112:113], v[112:113], 0, v[210:211]
	global_load_dwordx4 v[124:127], v[112:113], off
	global_load_dwordx4 v[120:123], v[112:113], off offset:16
	global_load_dwordx4 v[116:119], v[112:113], off offset:512
	s_nop 0
	global_load_dwordx4 v[112:115], v[112:113], off offset:528
	s_mov_b64 s[72:73], -1
	s_and_b64 vcc, exec, s[12:13]
	v_ashrrev_i32_e32 v149, 31, v148
	s_cbranch_vccnz .LBB0_943
	v_lshlrev_b64 v[152:153], 12, v[148:149]
	v_lshl_add_u64 v[152:153], s[90:91], 0, v[152:153]
	s_mov_b64 s[72:73], 0

; __device__ __forceinline__ unsigned pkbf(float lo, float hi) { return pg8::cvt_pk_bf16(lo, hi); }
;     __device__ __forceinline__ void operator()(const f32x4 (&acc)[2][2][4][2], const Unit& u, int wr, int wc, int fr, int fq) const {
;     ...
;             for (int mm = 0; mm < 2; ++mm) {
;                 const int m = m0 + mm;
;                 const int row = pm * 256 + ai * 128 + wr * 64 + m * 16 + fr;
;                 float* dst = isctx ? dst_ctx + (size_t)(row - MLAT) * DM : dst_lat + (size_t)row * DM;
;                 float ss = 0.f;
; #pragma unroll
;                 for (int bj = 0; bj < 2; ++bj) {
;                     const int col = cb + 128 * bj;
;                     const f32x4 x0 = pre[mm][bj][0] + gt[bj][0] * acc[ai][bj][m][0];
;                     const f32x4 x1 = pre[mm][bj][1] + gt[bj][1] * acc[ai][bj][m][1];
;                     *(f32x4*)(dst + col) = x0; *(f32x4*)(dst + col + 4) = x1;
;                     if (nxt) {
;                         ss += (x0[0] * x0[0] + x0[1] * x0[1]) + (x0[2] * x0[2] + x0[3] * x0[3]) + (x1[0] * x1[0] + x1[1] * x1[1]) + (x1[2] * x1[2] + x1[3] * x1[3]);
;                         const f32x4 y0 = x0 * gs[bj][0], y1 = x1 * gs[bj][1];
;                         u32x4 w; w.x = pkbf(y0[0], y0[1]); w.y = pkbf(y0[2], y0[3]); w.z = pkbf(y1[0], y1[1]); w.w = pkbf(y1[2], y1[3]);
;                         *(u32x4*)(xg + (size_t)row * DM + col) = w;
;                     }
;                 }
;                 if (nxt) { ss += __shfl_xor(ss, 16); ss += __shfl_xor(ss, 32); if (fq == 0) unsafeAtomicAdd(rowsq_next + row, ss); }
.LBB0_945:
	s_waitcnt vmcnt(0) lgkmcnt(0)
	v_pk_fma_f32 v[142:143], v[110:111], v[66:67], v[142:143]
	v_pk_fma_f32 v[140:141], v[108:109], v[64:65], v[140:141]
	v_pk_fma_f32 v[138:139], v[106:107], v[70:71], v[138:139]
	v_pk_fma_f32 v[136:137], v[104:105], v[68:69], v[136:137]
	v_lshl_add_u64 v[150:151], v[192:193], 2, v[152:153]
	s_and_b64 vcc, exec, s[8:9]
	v_pk_fma_f32 v[108:109], v[100:101], v[48:49], v[132:133]
	v_pk_fma_f32 v[104:105], v[96:97], v[56:57], v[128:129]
	global_store_dwordx4 v[150:151], v[140:143], off
	global_store_dwordx4 v[150:151], v[136:139], off offset:16
	s_cbranch_vccnz .LBB0_999
	v_mul_f32_e32 v100, v141, v141
	v_mul_f32_e32 v101, v143, v143
	v_fmac_f32_e32 v100, v140, v140
	v_fmac_f32_e32 v101, v142, v142
	v_add_f32_e32 v100, v100, v101
	v_mul_f32_e32 v101, v137, v137
	v_fmac_f32_e32 v101, v136, v136
	v_add_f32_e32 v100, v100, v101
	v_mul_f32_e32 v101, v139, v139
	v_fmac_f32_e32 v101, v138, v138
	v_pk_mul_f32 v[110:111], v[208:209], v[138:139]
	v_add_f32_e32 v132, v101, v100
	v_pk_mul_f32 v[100:101], v[206:207], v[142:143]
	v_pk_mul_f32 v[106:107], v[202:203], v[140:141]
	v_pk_mul_f32 v[128:129], v[198:199], v[136:137]
	v_cvt_pk_bf16_f32 v136, v106, v107
	v_cvt_pk_bf16_f32 v137, v100, v101
	v_mul_f32_e32 v100, v109, v109
	v_cvt_pk_bf16_f32 v138, v128, v129
	v_cvt_pk_bf16_f32 v139, v110, v111
	v_pk_fma_f32 v[110:111], v[102:103], v[50:51], v[134:135]
	v_fmac_f32_e32 v100, v108, v108
	v_mul_f32_e32 v101, v111, v111
	v_fmac_f32_e32 v101, v110, v110
	v_add_f32_e32 v100, v100, v101
	v_mul_f32_e32 v101, v105, v105
	v_pk_fma_f32 v[106:107], v[98:99], v[58:59], v[130:131]
	v_fmac_f32_e32 v101, v104, v104
	v_lshlrev_b64 v[96:97], 11, v[148:149]
	v_add_f32_e32 v100, v100, v101
	v_mul_f32_e32 v101, v107, v107
	v_lshl_add_u64 v[96:97], s[26:27], 0, v[96:97]
	v_fmac_f32_e32 v101, v106, v106
	v_lshl_add_u64 v[96:97], v[192:193], 1, v[96:97]
	v_add_f32_e32 v100, v101, v100
	global_store_dwordx4 v[96:97], v[136:139], off
	global_store_dwordx4 v[150:151], v[108:111], off offset:512
	global_store_dwordx4 v[150:151], v[104:107], off offset:528
	v_add_f32_e32 v132, v132, v100
	v_pk_mul_f32 v[100:101], v[200:201], v[110:111]
	v_pk_mul_f32 v[110:111], v[196:197], v[108:109]
	v_pk_mul_f32 v[106:107], v[204:205], v[106:107]
	v_pk_mul_f32 v[128:129], v[194:195], v[104:105]
	v_cvt_pk_bf16_f32 v136, v110, v111
	v_cvt_pk_bf16_f32 v137, v100, v101
	v_xor_b32_e32 v100, 32, v229
	v_cvt_pk_bf16_f32 v138, v128, v129
	v_cvt_pk_bf16_f32 v139, v106, v107
	global_store_dwordx4 v[96:97], v[136:139], off offset:256
	v_and_b32_e32 v97, 64, v229
	v_xor_b32_e32 v96, 16, v229
	v_add_u32_e32 v97, 64, v97
	v_cmp_lt_i32_e32 vcc, v96, v97
	s_nop 1
	v_cndmask_b32_e32 v96, v229, v96, vcc
	v_lshlrev_b32_e32 v96, 2, v96
	ds_bpermute_b32 v96, v96, v132
	v_cmp_lt_i32_e32 vcc, v100, v97
	s_waitcnt lgkmcnt(0)
	v_add_f32_e32 v96, v132, v96
	v_cndmask_b32_e32 v97, v229, v100, vcc
	v_lshlrev_b32_e32 v97, 2, v97
	ds_bpermute_b32 v97, v97, v96
	s_and_saveexec_b64 s[72:73], s[4:5]
	s_cbranch_execz .LBB0_948
	v_lshl_add_u64 v[100:101], v[148:149], 2, s[28:29]
	s_waitcnt lgkmcnt(0)
	v_add_f32_e32 v96, v96, v97
	global_atomic_add_f32 v[100:101], v96, off

;     __device__ __forceinline__ void operator()(const f32x4 (&acc)[2][2][4][2], const Unit& u, int wr, int wc, int fr, int fq) const {
;     ...
;                     const f32x4 x0 = pre[mm][bj][0] + gt[bj][0] * acc[ai][bj][m][0];
;                     const f32x4 x1 = pre[mm][bj][1] + gt[bj][1] * acc[ai][bj][m][1];
;                     *(f32x4*)(dst + col) = x0; *(f32x4*)(dst + col + 4) = x1;
.LBB0_949:
	v_pk_fma_f32 v[110:111], v[102:103], v[50:51], v[134:135]
	v_pk_fma_f32 v[106:107], v[98:99], v[58:59], v[130:131]
	global_store_dwordx4 v[150:151], v[108:111], off offset:512
	global_store_dwordx4 v[150:151], v[104:107], off offset:528

; __device__ __forceinline__ unsigned pkbf(float lo, float hi) { return pg8::cvt_pk_bf16(lo, hi); }
;     __device__ __forceinline__ void operator()(const f32x4 (&acc)[2][2][4][2], const Unit& u, int wr, int wc, int fr, int fq) const {
;     ...
;             for (int mm = 0; mm < 2; ++mm) {
;                 const int m = m0 + mm;
;                 const int row = pm * 256 + ai * 128 + wr * 64 + m * 16 + fr;
;                 float* dst = isctx ? dst_ctx + (size_t)(row - MLAT) * DM : dst_lat + (size_t)row * DM;
;                 float ss = 0.f;
; #pragma unroll
;                 for (int bj = 0; bj < 2; ++bj) {
;                     const int col = cb + 128 * bj;
;                     const f32x4 x0 = pre[mm][bj][0] + gt[bj][0] * acc[ai][bj][m][0];
;                     const f32x4 x1 = pre[mm][bj][1] + gt[bj][1] * acc[ai][bj][m][1];
;                     *(f32x4*)(dst + col) = x0; *(f32x4*)(dst + col + 4) = x1;
;                     if (nxt) {
;                         ss += (x0[0] * x0[0] + x0[1] * x0[1]) + (x0[2] * x0[2] + x0[3] * x0[3]) + (x1[0] * x1[0] + x1[1] * x1[1]) + (x1[2] * x1[2] + x1[3] * x1[3]);
;                         const f32x4 y0 = x0 * gs[bj][0], y1 = x1 * gs[bj][1];
;                         u32x4 w; w.x = pkbf(y0[0], y0[1]); w.y = pkbf(y0[2], y0[3]); w.z = pkbf(y1[0], y1[1]); w.w = pkbf(y1[2], y1[3]);
;                         *(u32x4*)(xg + (size_t)row * DM + col) = w;
;                     }
;                 }
;                 if (nxt) { ss += __shfl_xor(ss, 16); ss += __shfl_xor(ss, 32); if (fq == 0) unsafeAtomicAdd(rowsq_next + row, ss); }
.LBB0_954:
	s_waitcnt lgkmcnt(0)
	v_pk_fma_f32 v[96:97], v[94:95], v[66:67], v[126:127]
	v_pk_fma_f32 v[94:95], v[92:93], v[64:65], v[124:125]
	v_pk_fma_f32 v[100:101], v[90:91], v[70:71], v[122:123]
	v_pk_fma_f32 v[98:99], v[88:89], v[68:69], v[120:121]
	v_lshl_add_u64 v[102:103], v[192:193], 2, v[102:103]
	s_and_b64 vcc, exec, s[8:9]
	v_pk_fma_f32 v[92:93], v[84:85], v[48:49], v[116:117]
	v_pk_fma_f32 v[88:89], v[80:81], v[56:57], v[112:113]
	global_store_dwordx4 v[102:103], v[94:97], off
	global_store_dwordx4 v[102:103], v[98:101], off offset:16
	s_cbranch_vccnz .LBB0_1000
	v_mul_f32_e32 v84, v95, v95
	v_mul_f32_e32 v85, v97, v97
	v_fmac_f32_e32 v84, v94, v94
	v_fmac_f32_e32 v85, v96, v96
	v_add_f32_e32 v84, v84, v85
	v_mul_f32_e32 v85, v99, v99
	v_fmac_f32_e32 v85, v98, v98
	v_lshlrev_b64 v[80:81], 11, v[144:145]
	v_add_f32_e32 v84, v84, v85
	v_mul_f32_e32 v85, v101, v101
	v_fmac_f32_e32 v85, v100, v100
	v_lshl_add_u64 v[80:81], s[26:27], 0, v[80:81]
	v_add_f32_e32 v104, v85, v84
	v_pk_mul_f32 v[84:85], v[206:207], v[96:97]
	v_pk_mul_f32 v[90:91], v[202:203], v[94:95]
	v_pk_mul_f32 v[96:97], v[198:199], v[98:99]
	v_cvt_pk_bf16_f32 v94, v90, v91
	v_cvt_pk_bf16_f32 v95, v84, v85
	v_lshl_add_u64 v[80:81], v[192:193], 1, v[80:81]
	v_pk_mul_f32 v[100:101], v[208:209], v[100:101]
	v_cvt_pk_bf16_f32 v96, v96, v97
	v_mul_f32_e32 v84, v93, v93
	v_cvt_pk_bf16_f32 v97, v100, v101
	global_store_dwordx4 v[80:81], v[94:97], off
	v_fmac_f32_e32 v84, v92, v92
	v_pk_fma_f32 v[90:91], v[82:83], v[58:59], v[114:115]
	v_pk_fma_f32 v[94:95], v[86:87], v[50:51], v[118:119]
	global_store_dwordx4 v[102:103], v[92:95], off offset:512
	global_store_dwordx4 v[102:103], v[88:91], off offset:528
	v_mul_f32_e32 v85, v95, v95
	v_fmac_f32_e32 v85, v94, v94
	v_add_f32_e32 v84, v84, v85
	v_mul_f32_e32 v85, v89, v89
	v_fmac_f32_e32 v85, v88, v88
	v_add_f32_e32 v84, v84, v85
	v_mul_f32_e32 v85, v91, v91
	v_fmac_f32_e32 v85, v90, v90
	v_add_f32_e32 v84, v85, v84
	v_add_f32_e32 v98, v104, v84
	v_pk_mul_f32 v[84:85], v[200:201], v[94:95]
	v_pk_mul_f32 v[94:95], v[196:197], v[92:93]
	v_pk_mul_f32 v[96:97], v[194:195], v[88:89]
	v_pk_mul_f32 v[90:91], v[204:205], v[90:91]
	v_cvt_pk_bf16_f32 v94, v94, v95
	v_cvt_pk_bf16_f32 v95, v84, v85
	v_cvt_pk_bf16_f32 v96, v96, v97
	v_xor_b32_e32 v84, 32, v229
	v_cvt_pk_bf16_f32 v97, v90, v91
	global_store_dwordx4 v[80:81], v[94:97], off offset:256
	v_and_b32_e32 v81, 64, v229
	v_xor_b32_e32 v80, 16, v229
	v_add_u32_e32 v81, 64, v81
	v_cmp_lt_i32_e32 vcc, v80, v81
	s_nop 1
	v_cndmask_b32_e32 v80, v229, v80, vcc
	v_lshlrev_b32_e32 v80, 2, v80
	ds_bpermute_b32 v80, v80, v98
	v_cmp_lt_i32_e32 vcc, v84, v81
	s_waitcnt lgkmcnt(0)
	v_add_f32_e32 v80, v98, v80
	v_cndmask_b32_e32 v81, v229, v84, vcc
	v_lshlrev_b32_e32 v81, 2, v81
	ds_bpermute_b32 v81, v81, v80
	s_and_saveexec_b64 s[72:73], s[4:5]
	s_cbranch_execz .LBB0_957
	v_lshl_add_u64 v[84:85], v[144:145], 2, s[28:29]
	s_waitcnt lgkmcnt(0)
	v_add_f32_e32 v80, v80, v81
	global_atomic_add_f32 v[84:85], v80, off

;     __device__ __forceinline__ void operator()(const f32x4 (&acc)[2][2][4][2], const Unit& u, int wr, int wc, int fr, int fq) const {
;     ...
;         for (int q2 = 0; q2 < 4; ++q2) {
;             const int ai = q2 >> 1, m0 = (q2 & 1) * 2;
;             f32x4 pre[2][2][2];
; #pragma unroll
;             for (int mm = 0; mm < 2; ++mm) {
;                 const int row = pm * 256 + ai * 128 + wr * 64 + (m0 + mm) * 16 + fr;
;                 const float* src = isctx ? res_ctx + (size_t)(row - MLAT) * DM : res_lat + (size_t)row * DM;
; #pragma unroll
;                 for (int bj = 0; bj < 2; ++bj) { pre[mm][bj][0] = *(const f32x4*)(src + cb + 128 * bj); pre[mm][bj][1] = *(const f32x4*)(src + cb + 128 * bj + 4); }
;             }
; #pragma unroll
;             for (int mm = 0; mm < 2; ++mm) {
;                 const int m = m0 + mm;
;                 const int row = pm * 256 + ai * 128 + wr * 64 + m * 16 + fr;
;                 float* dst = isctx ? dst_ctx + (size_t)(row - MLAT) * DM : dst_lat + (size_t)row * DM;
;                 float ss = 0.f;
; #pragma unroll
;                 for (int bj = 0; bj < 2; ++bj) {
;                     const int col = cb + 128 * bj;
;                     const f32x4 x0 = pre[mm][bj][0] + gt[bj][0] * acc[ai][bj][m][0];
;                     const f32x4 x1 = pre[mm][bj][1] + gt[bj][1] * acc[ai][bj][m][1];
;                     *(f32x4*)(dst + col) = x0; *(f32x4*)(dst + col + 4) = x1;
.LBB0_958:
	v_pk_fma_f32 v[94:95], v[86:87], v[50:51], v[118:119]
	v_pk_fma_f32 v[90:91], v[82:83], v[58:59], v[114:115]
	global_store_dwordx4 v[102:103], v[92:95], off offset:512
	global_store_dwordx4 v[102:103], v[88:91], off offset:528
.LBB0_959:
	v_add_u32_e32 v116, 0x80, v212
	v_add_u32_e32 v118, 0xffffc080, v212
	v_cndmask_b32_e64 v80, v116, v118, s[10:11]
	s_waitcnt lgkmcnt(0)
	v_ashrrev_i32_e32 v81, 31, v80
	v_lshlrev_b64 v[80:81], 12, v[80:81]
	v_lshl_add_u64 v[80:81], s[52:53], 0, v[80:81]
	v_lshl_add_u64 v[80:81], v[80:81], 0, v[210:211]
	v_add_u32_e32 v112, 0x90, v212
	v_add_u32_e32 v114, 0xffffc090, v212
	global_load_dwordx4 v[108:111], v[80:81], off
	global_load_dwordx4 v[104:107], v[80:81], off offset:16
	global_load_dwordx4 v[100:103], v[80:81], off offset:512
	global_load_dwordx4 v[96:99], v[80:81], off offset:528
	v_cndmask_b32_e64 v80, v112, v114, s[10:11]
	v_ashrrev_i32_e32 v81, 31, v80
	v_lshlrev_b64 v[80:81], 12, v[80:81]
	v_lshl_add_u64 v[80:81], s[52:53], 0, v[80:81]
	v_lshl_add_u64 v[80:81], v[80:81], 0, v[210:211]
	global_load_dwordx4 v[92:95], v[80:81], off
	global_load_dwordx4 v[88:91], v[80:81], off offset:16
	global_load_dwordx4 v[84:87], v[80:81], off offset:512
	s_nop 0
	global_load_dwordx4 v[80:83], v[80:81], off offset:528
	s_mov_b64 s[72:73], -1
	s_and_b64 vcc, exec, s[12:13]
	v_ashrrev_i32_e32 v117, 31, v116
	s_cbranch_vccnz .LBB0_961
	v_lshlrev_b64 v[120:121], 12, v[116:117]
	v_lshl_add_u64 v[120:121], s[90:91], 0, v[120:121]
	s_mov_b64 s[72:73], 0

; __device__ __forceinline__ unsigned pkbf(float lo, float hi) { return pg8::cvt_pk_bf16(lo, hi); }
;     __device__ __forceinline__ void operator()(const f32x4 (&acc)[2][2][4][2], const Unit& u, int wr, int wc, int fr, int fq) const {
;     ...
;             for (int mm = 0; mm < 2; ++mm) {
;                 const int m = m0 + mm;
;                 const int row = pm * 256 + ai * 128 + wr * 64 + m * 16 + fr;
;                 float* dst = isctx ? dst_ctx + (size_t)(row - MLAT) * DM : dst_lat + (size_t)row * DM;
;                 float ss = 0.f;
; #pragma unroll
;                 for (int bj = 0; bj < 2; ++bj) {
;                     const int col = cb + 128 * bj;
;                     const f32x4 x0 = pre[mm][bj][0] + gt[bj][0] * acc[ai][bj][m][0];
;                     const f32x4 x1 = pre[mm][bj][1] + gt[bj][1] * acc[ai][bj][m][1];
;                     *(f32x4*)(dst + col) = x0; *(f32x4*)(dst + col + 4) = x1;
;                     if (nxt) {
;                         ss += (x0[0] * x0[0] + x0[1] * x0[1]) + (x0[2] * x0[2] + x0[3] * x0[3]) + (x1[0] * x1[0] + x1[1] * x1[1]) + (x1[2] * x1[2] + x1[3] * x1[3]);
;                         const f32x4 y0 = x0 * gs[bj][0], y1 = x1 * gs[bj][1];
;                         u32x4 w; w.x = pkbf(y0[0], y0[1]); w.y = pkbf(y0[2], y0[3]); w.z = pkbf(y1[0], y1[1]); w.w = pkbf(y1[2], y1[3]);
;                         *(u32x4*)(xg + (size_t)row * DM + col) = w;
;                     }
;                 }
;                 if (nxt) { ss += __shfl_xor(ss, 16); ss += __shfl_xor(ss, 32); if (fq == 0) unsafeAtomicAdd(rowsq_next + row, ss); }
.LBB0_963:
	s_waitcnt vmcnt(0) lgkmcnt(0)
	v_pk_fma_f32 v[110:111], v[78:79], v[66:67], v[110:111]
	v_pk_fma_f32 v[108:109], v[76:77], v[64:65], v[108:109]
	v_pk_fma_f32 v[106:107], v[74:75], v[70:71], v[106:107]
	v_pk_fma_f32 v[104:105], v[72:73], v[68:69], v[104:105]
	v_lshl_add_u64 v[118:119], v[192:193], 2, v[120:121]
	s_and_b64 vcc, exec, s[8:9]
	v_pk_fma_f32 v[76:77], v[60:61], v[48:49], v[100:101]
	v_pk_fma_f32 v[72:73], v[52:53], v[56:57], v[96:97]
	global_store_dwordx4 v[118:119], v[108:111], off
	global_store_dwordx4 v[118:119], v[104:107], off offset:16
	s_cbranch_vccnz .LBB0_1001
	v_mul_f32_e32 v60, v109, v109
	v_mul_f32_e32 v61, v111, v111
	v_fmac_f32_e32 v60, v108, v108
	v_fmac_f32_e32 v61, v110, v110
	v_add_f32_e32 v60, v60, v61
	v_mul_f32_e32 v61, v105, v105
	v_fmac_f32_e32 v61, v104, v104
	v_add_f32_e32 v60, v60, v61
	v_mul_f32_e32 v61, v107, v107
	v_fmac_f32_e32 v61, v106, v106
	v_pk_mul_f32 v[78:79], v[208:209], v[106:107]
	v_add_f32_e32 v100, v61, v60
	v_pk_mul_f32 v[60:61], v[206:207], v[110:111]
	v_pk_mul_f32 v[74:75], v[202:203], v[108:109]
	v_pk_mul_f32 v[96:97], v[198:199], v[104:105]
	v_cvt_pk_bf16_f32 v104, v74, v75
	v_cvt_pk_bf16_f32 v105, v60, v61
	v_mul_f32_e32 v60, v77, v77
	v_cvt_pk_bf16_f32 v106, v96, v97
	v_cvt_pk_bf16_f32 v107, v78, v79
	v_pk_fma_f32 v[78:79], v[62:63], v[50:51], v[102:103]
	v_fmac_f32_e32 v60, v76, v76
	v_mul_f32_e32 v61, v79, v79
	v_fmac_f32_e32 v61, v78, v78
	v_add_f32_e32 v60, v60, v61
	v_mul_f32_e32 v61, v73, v73
	v_pk_fma_f32 v[74:75], v[54:55], v[58:59], v[98:99]
	v_fmac_f32_e32 v61, v72, v72
	v_lshlrev_b64 v[52:53], 11, v[116:117]
	v_add_f32_e32 v60, v60, v61
	v_mul_f32_e32 v61, v75, v75
	v_lshl_add_u64 v[52:53], s[26:27], 0, v[52:53]
	v_fmac_f32_e32 v61, v74, v74
	v_lshl_add_u64 v[52:53], v[192:193], 1, v[52:53]
	v_add_f32_e32 v60, v61, v60
	global_store_dwordx4 v[52:53], v[104:107], off
	global_store_dwordx4 v[118:119], v[76:79], off offset:512
	global_store_dwordx4 v[118:119], v[72:75], off offset:528
	v_add_f32_e32 v100, v100, v60
	v_pk_mul_f32 v[60:61], v[200:201], v[78:79]
	v_pk_mul_f32 v[78:79], v[196:197], v[76:77]
	v_pk_mul_f32 v[74:75], v[204:205], v[74:75]
	v_pk_mul_f32 v[96:97], v[194:195], v[72:73]
	v_cvt_pk_bf16_f32 v104, v78, v79
	v_cvt_pk_bf16_f32 v105, v60, v61
	v_xor_b32_e32 v60, 32, v229
	v_cvt_pk_bf16_f32 v106, v96, v97
	v_cvt_pk_bf16_f32 v107, v74, v75
	global_store_dwordx4 v[52:53], v[104:107], off offset:256
	v_and_b32_e32 v53, 64, v229
	v_xor_b32_e32 v52, 16, v229
	v_add_u32_e32 v53, 64, v53
	v_cmp_lt_i32_e32 vcc, v52, v53
	s_nop 1
	v_cndmask_b32_e32 v52, v229, v52, vcc
	v_lshlrev_b32_e32 v52, 2, v52
	ds_bpermute_b32 v52, v52, v100
	v_cmp_lt_i32_e32 vcc, v60, v53
	s_waitcnt lgkmcnt(0)
	v_add_f32_e32 v52, v100, v52
	v_cndmask_b32_e32 v53, v229, v60, vcc
	v_lshlrev_b32_e32 v53, 2, v53
	ds_bpermute_b32 v53, v53, v52
	s_and_saveexec_b64 s[72:73], s[4:5]
	s_cbranch_execz .LBB0_966
	v_lshl_add_u64 v[60:61], v[116:117], 2, s[28:29]
	s_waitcnt lgkmcnt(0)
	v_add_f32_e32 v52, v52, v53
	global_atomic_add_f32 v[60:61], v52, off

;     __device__ __forceinline__ void operator()(const f32x4 (&acc)[2][2][4][2], const Unit& u, int wr, int wc, int fr, int fq) const {
;     ...
;                     const f32x4 x0 = pre[mm][bj][0] + gt[bj][0] * acc[ai][bj][m][0];
;                     const f32x4 x1 = pre[mm][bj][1] + gt[bj][1] * acc[ai][bj][m][1];
;                     *(f32x4*)(dst + col) = x0; *(f32x4*)(dst + col + 4) = x1;
.LBB0_967:
	v_pk_fma_f32 v[78:79], v[62:63], v[50:51], v[102:103]
	v_pk_fma_f32 v[74:75], v[54:55], v[58:59], v[98:99]
	global_store_dwordx4 v[118:119], v[76:79], off offset:512
	global_store_dwordx4 v[118:119], v[72:75], off offset:528

; __device__ __forceinline__ unsigned pkbf(float lo, float hi) { return pg8::cvt_pk_bf16(lo, hi); }
;     __device__ __forceinline__ void operator()(const f32x4 (&acc)[2][2][4][2], const Unit& u, int wr, int wc, int fr, int fq) const {
;     ...
;             for (int mm = 0; mm < 2; ++mm) {
;                 const int m = m0 + mm;
;                 const int row = pm * 256 + ai * 128 + wr * 64 + m * 16 + fr;
;                 float* dst = isctx ? dst_ctx + (size_t)(row - MLAT) * DM : dst_lat + (size_t)row * DM;
;                 float ss = 0.f;
; #pragma unroll
;                 for (int bj = 0; bj < 2; ++bj) {
;                     const int col = cb + 128 * bj;
;                     const f32x4 x0 = pre[mm][bj][0] + gt[bj][0] * acc[ai][bj][m][0];
;                     const f32x4 x1 = pre[mm][bj][1] + gt[bj][1] * acc[ai][bj][m][1];
;                     *(f32x4*)(dst + col) = x0; *(f32x4*)(dst + col + 4) = x1;
;                     if (nxt) {
;                         ss += (x0[0] * x0[0] + x0[1] * x0[1]) + (x0[2] * x0[2] + x0[3] * x0[3]) + (x1[0] * x1[0] + x1[1] * x1[1]) + (x1[2] * x1[2] + x1[3] * x1[3]);
;                         const f32x4 y0 = x0 * gs[bj][0], y1 = x1 * gs[bj][1];
;                         u32x4 w; w.x = pkbf(y0[0], y0[1]); w.y = pkbf(y0[2], y0[3]); w.z = pkbf(y1[0], y1[1]); w.w = pkbf(y1[2], y1[3]);
;                         *(u32x4*)(xg + (size_t)row * DM + col) = w;
;                     }
;                 }
;                 if (nxt) { ss += __shfl_xor(ss, 16); ss += __shfl_xor(ss, 32); if (fq == 0) unsafeAtomicAdd(rowsq_next + row, ss); }
.LBB0_972:
	v_pk_fma_f32 v[54:55], v[46:47], v[66:67], v[94:95]
	s_waitcnt lgkmcnt(0)
	v_pk_fma_f32 v[52:53], v[44:45], v[64:65], v[92:93]
	v_pk_fma_f32 v[62:63], v[42:43], v[70:71], v[90:91]
	v_pk_fma_f32 v[60:61], v[40:41], v[68:69], v[88:89]
	v_lshl_add_u64 v[72:73], v[192:193], 2, v[72:73]
	s_and_b64 vcc, exec, s[8:9]
	v_pk_fma_f32 v[44:45], v[36:37], v[48:49], v[84:85]
	v_pk_fma_f32 v[40:41], v[32:33], v[56:57], v[80:81]
	global_store_dwordx4 v[72:73], v[52:55], off
	global_store_dwordx4 v[72:73], v[60:63], off offset:16
	s_cbranch_vccnz .LBB0_1002
	v_mul_f32_e32 v36, v53, v53
	v_mul_f32_e32 v37, v55, v55
	v_fmac_f32_e32 v36, v52, v52
	v_fmac_f32_e32 v37, v54, v54
	v_add_f32_e32 v36, v36, v37
	v_mul_f32_e32 v37, v61, v61
	v_fmac_f32_e32 v37, v60, v60
	v_add_f32_e32 v36, v36, v37
	v_mul_f32_e32 v37, v63, v63
	v_fmac_f32_e32 v37, v62, v62
	v_add_f32_e32 v74, v37, v36
	v_pk_mul_f32 v[36:37], v[206:207], v[54:55]
	v_pk_mul_f32 v[46:47], v[208:209], v[62:63]
	v_pk_mul_f32 v[54:55], v[198:199], v[60:61]
	v_pk_mul_f32 v[42:43], v[202:203], v[52:53]
	v_lshlrev_b64 v[32:33], 11, v[112:113]
	v_cvt_pk_bf16_f32 v52, v42, v43
	v_cvt_pk_bf16_f32 v53, v36, v37
	v_cvt_pk_bf16_f32 v54, v54, v55
	v_cvt_pk_bf16_f32 v55, v46, v47
	v_pk_fma_f32 v[46:47], v[38:39], v[50:51], v[86:87]
	v_mul_f32_e32 v36, v45, v45
	v_mul_f32_e32 v37, v47, v47
	v_fmac_f32_e32 v36, v44, v44
	v_fmac_f32_e32 v37, v46, v46
	v_add_f32_e32 v36, v36, v37
	v_mul_f32_e32 v37, v41, v41
	v_pk_fma_f32 v[42:43], v[34:35], v[58:59], v[82:83]
	v_fmac_f32_e32 v37, v40, v40
	v_lshl_add_u64 v[32:33], s[26:27], 0, v[32:33]
	v_add_f32_e32 v36, v36, v37
	v_mul_f32_e32 v37, v43, v43
	v_lshl_add_u64 v[32:33], v[192:193], 1, v[32:33]
	v_fmac_f32_e32 v37, v42, v42
	global_store_dwordx4 v[32:33], v[52:55], off
	v_add_f32_e32 v36, v37, v36
	global_store_dwordx4 v[72:73], v[44:47], off offset:512
	global_store_dwordx4 v[72:73], v[40:43], off offset:528
	v_pk_mul_f32 v[54:55], v[194:195], v[40:41]
	v_add_f32_e32 v60, v74, v36
	v_pk_mul_f32 v[36:37], v[200:201], v[46:47]
	v_pk_mul_f32 v[46:47], v[196:197], v[44:45]
	v_pk_mul_f32 v[42:43], v[204:205], v[42:43]
	v_cvt_pk_bf16_f32 v52, v46, v47
	v_cvt_pk_bf16_f32 v53, v36, v37
	v_cvt_pk_bf16_f32 v54, v54, v55
	v_xor_b32_e32 v36, 32, v229
	v_cvt_pk_bf16_f32 v55, v42, v43
	global_store_dwordx4 v[32:33], v[52:55], off offset:256
	v_and_b32_e32 v33, 64, v229
	v_xor_b32_e32 v32, 16, v229
	v_add_u32_e32 v33, 64, v33
	v_cmp_lt_i32_e32 vcc, v32, v33
	s_nop 1
	v_cndmask_b32_e32 v32, v229, v32, vcc
	v_lshlrev_b32_e32 v32, 2, v32
	ds_bpermute_b32 v32, v32, v60
	v_cmp_lt_i32_e32 vcc, v36, v33
	s_waitcnt lgkmcnt(0)
	v_add_f32_e32 v32, v60, v32
	v_cndmask_b32_e32 v33, v229, v36, vcc
	v_lshlrev_b32_e32 v33, 2, v33
	ds_bpermute_b32 v33, v33, v32
	s_and_saveexec_b64 s[72:73], s[4:5]
	s_cbranch_execz .LBB0_975
	v_lshl_add_u64 v[36:37], v[112:113], 2, s[28:29]
	s_waitcnt lgkmcnt(0)
	v_add_f32_e32 v32, v32, v33
	global_atomic_add_f32 v[36:37], v32, off

;     __device__ __forceinline__ void operator()(const f32x4 (&acc)[2][2][4][2], const Unit& u, int wr, int wc, int fr, int fq) const {
;     ...
;         for (int q2 = 0; q2 < 4; ++q2) {
;             const int ai = q2 >> 1, m0 = (q2 & 1) * 2;
;             f32x4 pre[2][2][2];
; #pragma unroll
;             for (int mm = 0; mm < 2; ++mm) {
;                 const int row = pm * 256 + ai * 128 + wr * 64 + (m0 + mm) * 16 + fr;
;                 const float* src = isctx ? res_ctx + (size_t)(row - MLAT) * DM : res_lat + (size_t)row * DM;
; #pragma unroll
;                 for (int bj = 0; bj < 2; ++bj) { pre[mm][bj][0] = *(const f32x4*)(src + cb + 128 * bj); pre[mm][bj][1] = *(const f32x4*)(src + cb + 128 * bj + 4); }
;             }
; #pragma unroll
;             for (int mm = 0; mm < 2; ++mm) {
;                 const int m = m0 + mm;
;                 const int row = pm * 256 + ai * 128 + wr * 64 + m * 16 + fr;
;                 float* dst = isctx ? dst_ctx + (size_t)(row - MLAT) * DM : dst_lat + (size_t)row * DM;
;                 float ss = 0.f;
; #pragma unroll
;                 for (int bj = 0; bj < 2; ++bj) {
;                     const int col = cb + 128 * bj;
;                     const f32x4 x0 = pre[mm][bj][0] + gt[bj][0] * acc[ai][bj][m][0];
;                     const f32x4 x1 = pre[mm][bj][1] + gt[bj][1] * acc[ai][bj][m][1];
;                     *(f32x4*)(dst + col) = x0; *(f32x4*)(dst + col + 4) = x1;
.LBB0_976:
	v_pk_fma_f32 v[46:47], v[38:39], v[50:51], v[86:87]
	v_pk_fma_f32 v[42:43], v[34:35], v[58:59], v[82:83]
	global_store_dwordx4 v[72:73], v[44:47], off offset:512
	global_store_dwordx4 v[72:73], v[40:43], off offset:528
.LBB0_977:
	v_add_u32_e32 v84, 0xa0, v212
	v_add_u32_e32 v86, 0xffffc0a0, v212
	v_cndmask_b32_e64 v32, v84, v86, s[10:11]
	s_waitcnt lgkmcnt(0)
	v_ashrrev_i32_e32 v33, 31, v32
	v_lshlrev_b64 v[32:33], 12, v[32:33]
	v_lshl_add_u64 v[32:33], s[52:53], 0, v[32:33]
	v_lshl_add_u64 v[32:33], v[32:33], 0, v[210:211]
	v_add_u32_e32 v80, 0xb0, v212
	v_add_u32_e32 v82, 0xffffc0b0, v212
	global_load_dwordx4 v[76:79], v[32:33], off
	global_load_dwordx4 v[72:75], v[32:33], off offset:16
	global_load_dwordx4 v[60:63], v[32:33], off offset:512
	global_load_dwordx4 v[52:55], v[32:33], off offset:528
	v_cndmask_b32_e64 v32, v80, v82, s[10:11]
	v_ashrrev_i32_e32 v33, 31, v32
	v_lshlrev_b64 v[32:33], 12, v[32:33]
	v_lshl_add_u64 v[32:33], s[52:53], 0, v[32:33]
	v_lshl_add_u64 v[32:33], v[32:33], 0, v[210:211]
	global_load_dwordx4 v[44:47], v[32:33], off
	global_load_dwordx4 v[40:43], v[32:33], off offset:16
	global_load_dwordx4 v[36:39], v[32:33], off offset:512
	s_nop 0
	global_load_dwordx4 v[32:35], v[32:33], off offset:528
	s_mov_b64 s[10:11], -1
	s_and_b64 vcc, exec, s[12:13]
	v_ashrrev_i32_e32 v85, 31, v84
	s_cbranch_vccnz .LBB0_979
	v_lshlrev_b64 v[88:89], 12, v[84:85]
	v_lshl_add_u64 v[88:89], s[90:91], 0, v[88:89]
	s_mov_b64 s[10:11], 0

; __device__ __forceinline__ unsigned pkbf(float lo, float hi) { return pg8::cvt_pk_bf16(lo, hi); }
;     __device__ __forceinline__ void operator()(const f32x4 (&acc)[2][2][4][2], const Unit& u, int wr, int wc, int fr, int fq) const {
;     ...
;             for (int mm = 0; mm < 2; ++mm) {
;                 const int m = m0 + mm;
;                 const int row = pm * 256 + ai * 128 + wr * 64 + m * 16 + fr;
;                 float* dst = isctx ? dst_ctx + (size_t)(row - MLAT) * DM : dst_lat + (size_t)row * DM;
;                 float ss = 0.f;
; #pragma unroll
;                 for (int bj = 0; bj < 2; ++bj) {
;                     const int col = cb + 128 * bj;
;                     const f32x4 x0 = pre[mm][bj][0] + gt[bj][0] * acc[ai][bj][m][0];
;                     const f32x4 x1 = pre[mm][bj][1] + gt[bj][1] * acc[ai][bj][m][1];
;                     *(f32x4*)(dst + col) = x0; *(f32x4*)(dst + col + 4) = x1;
;                     if (nxt) {
;                         ss += (x0[0] * x0[0] + x0[1] * x0[1]) + (x0[2] * x0[2] + x0[3] * x0[3]) + (x1[0] * x1[0] + x1[1] * x1[1]) + (x1[2] * x1[2] + x1[3] * x1[3]);
;                         const f32x4 y0 = x0 * gs[bj][0], y1 = x1 * gs[bj][1];
;                         u32x4 w; w.x = pkbf(y0[0], y0[1]); w.y = pkbf(y0[2], y0[3]); w.z = pkbf(y1[0], y1[1]); w.w = pkbf(y1[2], y1[3]);
;                         *(u32x4*)(xg + (size_t)row * DM + col) = w;
;                     }
;                 }
;                 if (nxt) { ss += __shfl_xor(ss, 16); ss += __shfl_xor(ss, 32); if (fq == 0) unsafeAtomicAdd(rowsq_next + row, ss); }
.LBB0_981:
	s_waitcnt vmcnt(0) lgkmcnt(0)
	v_pk_fma_f32 v[78:79], v[30:31], v[66:67], v[78:79]
	v_pk_fma_f32 v[76:77], v[28:29], v[64:65], v[76:77]
	v_pk_fma_f32 v[74:75], v[26:27], v[70:71], v[74:75]
	v_pk_fma_f32 v[72:73], v[24:25], v[68:69], v[72:73]
	v_lshl_add_u64 v[86:87], v[192:193], 2, v[88:89]
	s_and_b64 vcc, exec, s[8:9]
	v_pk_fma_f32 v[28:29], v[20:21], v[48:49], v[60:61]
	v_pk_fma_f32 v[24:25], v[16:17], v[56:57], v[52:53]
	global_store_dwordx4 v[86:87], v[76:79], off
	global_store_dwordx4 v[86:87], v[72:75], off offset:16
	s_cbranch_vccnz .LBB0_1003
	v_mul_f32_e32 v20, v77, v77
	v_mul_f32_e32 v21, v79, v79
	v_fmac_f32_e32 v20, v76, v76
	v_fmac_f32_e32 v21, v78, v78
	v_add_f32_e32 v20, v20, v21
	v_mul_f32_e32 v21, v73, v73
	v_fmac_f32_e32 v21, v72, v72
	v_add_f32_e32 v20, v20, v21
	v_mul_f32_e32 v21, v75, v75
	v_fmac_f32_e32 v21, v74, v74
	v_pk_mul_f32 v[30:31], v[208:209], v[74:75]
	v_add_f32_e32 v60, v21, v20
	v_pk_mul_f32 v[20:21], v[206:207], v[78:79]
	v_pk_mul_f32 v[26:27], v[202:203], v[76:77]
	v_pk_mul_f32 v[52:53], v[198:199], v[72:73]
	v_cvt_pk_bf16_f32 v72, v26, v27
	v_cvt_pk_bf16_f32 v73, v20, v21
	v_mul_f32_e32 v20, v29, v29
	v_cvt_pk_bf16_f32 v74, v52, v53
	v_cvt_pk_bf16_f32 v75, v30, v31
	v_pk_fma_f32 v[30:31], v[22:23], v[50:51], v[62:63]
	v_fmac_f32_e32 v20, v28, v28
	v_mul_f32_e32 v21, v31, v31
	v_fmac_f32_e32 v21, v30, v30
	v_add_f32_e32 v20, v20, v21
	v_mul_f32_e32 v21, v25, v25
	v_pk_fma_f32 v[26:27], v[18:19], v[58:59], v[54:55]
	v_fmac_f32_e32 v21, v24, v24
	v_lshlrev_b64 v[16:17], 11, v[84:85]
	v_add_f32_e32 v20, v20, v21
	v_mul_f32_e32 v21, v27, v27
	v_lshl_add_u64 v[16:17], s[26:27], 0, v[16:17]
	v_fmac_f32_e32 v21, v26, v26
	v_lshl_add_u64 v[16:17], v[192:193], 1, v[16:17]
	v_add_f32_e32 v20, v21, v20
	global_store_dwordx4 v[16:17], v[72:75], off
	global_store_dwordx4 v[86:87], v[28:31], off offset:512
	global_store_dwordx4 v[86:87], v[24:27], off offset:528
	v_add_f32_e32 v60, v60, v20
	v_pk_mul_f32 v[20:21], v[200:201], v[30:31]
	v_pk_mul_f32 v[30:31], v[196:197], v[28:29]
	v_pk_mul_f32 v[26:27], v[204:205], v[26:27]
	v_pk_mul_f32 v[52:53], v[194:195], v[24:25]
	v_cvt_pk_bf16_f32 v72, v30, v31
	v_cvt_pk_bf16_f32 v73, v20, v21
	v_xor_b32_e32 v20, 32, v229
	v_cvt_pk_bf16_f32 v74, v52, v53
	v_cvt_pk_bf16_f32 v75, v26, v27
	global_store_dwordx4 v[16:17], v[72:75], off offset:256
	v_and_b32_e32 v17, 64, v229
	v_xor_b32_e32 v16, 16, v229
	v_add_u32_e32 v17, 64, v17
	v_cmp_lt_i32_e32 vcc, v16, v17
	s_nop 1
	v_cndmask_b32_e32 v16, v229, v16, vcc
	v_lshlrev_b32_e32 v16, 2, v16
	ds_bpermute_b32 v16, v16, v60
	v_cmp_lt_i32_e32 vcc, v20, v17
	s_waitcnt lgkmcnt(0)
	v_add_f32_e32 v16, v60, v16
	v_cndmask_b32_e32 v17, v229, v20, vcc
	v_lshlrev_b32_e32 v17, 2, v17
	ds_bpermute_b32 v17, v17, v16
	s_and_saveexec_b64 s[10:11], s[4:5]
	s_cbranch_execz .LBB0_984
	v_lshl_add_u64 v[20:21], v[84:85], 2, s[28:29]
	s_waitcnt lgkmcnt(0)
	v_add_f32_e32 v16, v16, v17
	global_atomic_add_f32 v[20:21], v16, off

;     __device__ __forceinline__ void operator()(const f32x4 (&acc)[2][2][4][2], const Unit& u, int wr, int wc, int fr, int fq) const {
;     ...
;                     const f32x4 x0 = pre[mm][bj][0] + gt[bj][0] * acc[ai][bj][m][0];
;                     const f32x4 x1 = pre[mm][bj][1] + gt[bj][1] * acc[ai][bj][m][1];
;                     *(f32x4*)(dst + col) = x0; *(f32x4*)(dst + col + 4) = x1;
.LBB0_985:
	v_pk_fma_f32 v[30:31], v[22:23], v[50:51], v[62:63]
	v_pk_fma_f32 v[26:27], v[18:19], v[58:59], v[54:55]
	global_store_dwordx4 v[86:87], v[28:31], off offset:512
	global_store_dwordx4 v[86:87], v[24:27], off offset:528

; __device__ __forceinline__ unsigned pkbf(float lo, float hi) { return pg8::cvt_pk_bf16(lo, hi); }
;     __device__ __forceinline__ void operator()(const f32x4 (&acc)[2][2][4][2], const Unit& u, int wr, int wc, int fr, int fq) const {
;     ...
;             for (int mm = 0; mm < 2; ++mm) {
;                 const int m = m0 + mm;
;                 const int row = pm * 256 + ai * 128 + wr * 64 + m * 16 + fr;
;                 float* dst = isctx ? dst_ctx + (size_t)(row - MLAT) * DM : dst_lat + (size_t)row * DM;
;                 float ss = 0.f;
; #pragma unroll
;                 for (int bj = 0; bj < 2; ++bj) {
;                     const int col = cb + 128 * bj;
;                     const f32x4 x0 = pre[mm][bj][0] + gt[bj][0] * acc[ai][bj][m][0];
;                     const f32x4 x1 = pre[mm][bj][1] + gt[bj][1] * acc[ai][bj][m][1];
;                     *(f32x4*)(dst + col) = x0; *(f32x4*)(dst + col + 4) = x1;
;                     if (nxt) {
;                         ss += (x0[0] * x0[0] + x0[1] * x0[1]) + (x0[2] * x0[2] + x0[3] * x0[3]) + (x1[0] * x1[0] + x1[1] * x1[1]) + (x1[2] * x1[2] + x1[3] * x1[3]);
;                         const f32x4 y0 = x0 * gs[bj][0], y1 = x1 * gs[bj][1];
;                         u32x4 w; w.x = pkbf(y0[0], y0[1]); w.y = pkbf(y0[2], y0[3]); w.z = pkbf(y1[0], y1[1]); w.w = pkbf(y1[2], y1[3]);
;                         *(u32x4*)(xg + (size_t)row * DM + col) = w;
;                     }
;                 }
;                 if (nxt) { ss += __shfl_xor(ss, 16); ss += __shfl_xor(ss, 32); if (fq == 0) unsafeAtomicAdd(rowsq_next + row, ss); }
.LBB0_990:
	s_waitcnt lgkmcnt(0)
	v_pk_fma_f32 v[16:17], v[14:15], v[66:67], v[46:47]
	v_pk_fma_f32 v[14:15], v[12:13], v[64:65], v[44:45]
	v_pk_fma_f32 v[20:21], v[10:11], v[70:71], v[42:43]
	v_pk_fma_f32 v[18:19], v[8:9], v[68:69], v[40:41]
	v_lshl_add_u64 v[22:23], v[192:193], 2, v[22:23]
	s_and_b64 vcc, exec, s[8:9]
	v_pk_fma_f32 v[12:13], v[4:5], v[48:49], v[36:37]
	v_pk_fma_f32 v[8:9], v[0:1], v[56:57], v[32:33]
	global_store_dwordx4 v[22:23], v[14:17], off
	global_store_dwordx4 v[22:23], v[18:21], off offset:16
	s_cbranch_vccnz .LBB0_1004
	v_mul_f32_e32 v4, v15, v15
	v_mul_f32_e32 v5, v17, v17
	v_fmac_f32_e32 v4, v14, v14
	v_fmac_f32_e32 v5, v16, v16
	v_add_f32_e32 v4, v4, v5
	v_mul_f32_e32 v5, v19, v19
	v_fmac_f32_e32 v5, v18, v18
	v_add_f32_e32 v4, v4, v5
	v_mul_f32_e32 v5, v21, v21
	v_lshlrev_b64 v[0:1], 11, v[80:81]
	v_fmac_f32_e32 v5, v20, v20
	v_add_f32_e32 v24, v5, v4
	v_pk_mul_f32 v[4:5], v[206:207], v[16:17]
	v_lshl_add_u64 v[0:1], s[26:27], 0, v[0:1]
	v_pk_mul_f32 v[10:11], v[202:203], v[14:15]
	v_pk_mul_f32 v[16:17], v[198:199], v[18:19]
	v_cvt_pk_bf16_f32 v14, v10, v11
	v_cvt_pk_bf16_f32 v15, v4, v5
	v_lshl_add_u64 v[4:5], v[192:193], 1, v[0:1]
	v_pk_mul_f32 v[20:21], v[208:209], v[20:21]
	v_cvt_pk_bf16_f32 v16, v16, v17
	v_mul_f32_e32 v0, v13, v13
	v_cvt_pk_bf16_f32 v17, v20, v21
	global_store_dwordx4 v[4:5], v[14:17], off
	v_fmac_f32_e32 v0, v12, v12
	v_pk_fma_f32 v[10:11], v[2:3], v[58:59], v[34:35]
	v_pk_fma_f32 v[14:15], v[6:7], v[50:51], v[38:39]
	global_store_dwordx4 v[22:23], v[12:15], off offset:512
	global_store_dwordx4 v[22:23], v[8:11], off offset:528
	v_mul_f32_e32 v1, v15, v15
	v_fmac_f32_e32 v1, v14, v14
	v_add_f32_e32 v0, v0, v1
	v_mul_f32_e32 v1, v9, v9
	v_fmac_f32_e32 v1, v8, v8
	v_add_f32_e32 v0, v0, v1
	v_mul_f32_e32 v1, v11, v11
	v_fmac_f32_e32 v1, v10, v10
	v_add_f32_e32 v0, v1, v0
	v_and_b32_e32 v1, 64, v229
	v_add_f32_e32 v20, v24, v0
	v_pk_mul_f32 v[16:17], v[200:201], v[14:15]
	v_xor_b32_e32 v0, 16, v229
	v_add_u32_e32 v15, 64, v1
	v_cmp_lt_i32_e32 vcc, v0, v15
	v_pk_mul_f32 v[10:11], v[204:205], v[10:11]
	v_pk_mul_f32 v[18:19], v[194:195], v[8:9]
	v_cndmask_b32_e32 v0, v229, v0, vcc
	v_lshlrev_b32_e32 v0, 2, v0
	ds_bpermute_b32 v21, v0, v20
	v_pk_mul_f32 v[0:1], v[196:197], v[12:13]
	s_nop 0
	v_cvt_pk_bf16_f32 v14, v0, v1
	v_xor_b32_e32 v1, 32, v229
	v_cmp_lt_i32_e32 vcc, v1, v15
	s_waitcnt lgkmcnt(0)
	v_add_f32_e32 v0, v20, v21
	v_cvt_pk_bf16_f32 v15, v16, v17
	v_cvt_pk_bf16_f32 v16, v18, v19
	v_cvt_pk_bf16_f32 v17, v10, v11
	global_store_dwordx4 v[4:5], v[14:17], off offset:256
	v_cndmask_b32_e32 v1, v229, v1, vcc
	v_lshlrev_b32_e32 v1, 2, v1
	ds_bpermute_b32 v1, v1, v0
	s_and_saveexec_b64 s[8:9], s[4:5]
	s_cbranch_execz .LBB0_993
	v_lshl_add_u64 v[4:5], v[80:81], 2, s[28:29]
	s_waitcnt lgkmcnt(0)
	v_add_f32_e32 v0, v0, v1
	global_atomic_add_f32 v[4:5], v0, off

;     __device__ __forceinline__ void operator()(const f32x4 (&acc)[2][2][4][2], const Unit& u, int wr, int wc, int fr, int fq) const {
;     ...
;                     const f32x4 x0 = pre[mm][bj][0] + gt[bj][0] * acc[ai][bj][m][0];
;                     const f32x4 x1 = pre[mm][bj][1] + gt[bj][1] * acc[ai][bj][m][1];
;                     *(f32x4*)(dst + col) = x0; *(f32x4*)(dst + col + 4) = x1;
.LBB0_994:
	v_pk_fma_f32 v[14:15], v[6:7], v[50:51], v[38:39]
	v_pk_fma_f32 v[10:11], v[2:3], v[58:59], v[34:35]
	global_store_dwordx4 v[22:23], v[12:15], off offset:512
	global_store_dwordx4 v[22:23], v[8:11], off offset:528

; #define LAS __attribute__((address_space(3)))
; #define LAS __attribute__((address_space(3)))
; __device__ __forceinline__ void ctx_slice_gemm(LAS unsigned char* lds, const bf16_t* A  , const bf16_t* Bt  , int K, ...
;     int tid_l = threadIdx.x; asm volatile("" : "+v"(tid_l)); const int tid = tid_l, lane = tid & 63, wid = __builtin_amdgcn_readfirstlane(tid >> 6), r16 = lane & 15, g4 = lane >> 4;
;     const int row0 = (blk >> 5) * 64, col0 = (blk & 31) * 32;
;     const int kw = K >> 3, kbeg = wid * kw;
;     const bf16_t* ap = A + (size_t)(MLAT + row0 + r16) * K + kbeg + 8 * g4;
;     const bf16_t* bp = Bt + (size_t)(col0 + r16) * K + kbeg + 8 * g4;
;     const size_t a16 = (size_t)16 * K;
;     f32x4 acc[4][2];
; #pragma unroll
;     for (int i = 0; i < 4; ++i)
; #pragma unroll
;         for (int j = 0; j < 2; ++j) acc[i][j] = (f32x4){0.f, 0.f, 0.f, 0.f};
; #pragma unroll 4
;     for (int k = 0; k < kw; k += 32) {
;         bf16x8 fa[4], fb[2];
; #pragma unroll
;         for (int i = 0; i < 4; ++i) fa[i] = *(const bf16x8*)(ap + i * a16 + k);
; #pragma unroll
;         for (int j = 0; j < 2; ++j) fb[j] = *(const bf16x8*)(bp + j * a16 + k);
; #pragma unroll
;         for (int i = 0; i < 4; ++i)
; #pragma unroll
;             for (int j = 0; j < 2; ++j) acc[i][j] = __builtin_amdgcn_mfma_f32_16x16x32_bf16(fa[i], fb[j], acc[i][j], 0, 0, 0);
;     }
;     LAS float* part = (LAS float*)lds;
; #pragma unroll
;     for (int i = 0; i < 4; ++i)
; #pragma unroll
;         for (int j = 0; j < 2; ++j)
; #pragma unroll
;             for (int q = 0; q < 4; ++q) part[((wid * 8 + i * 2 + j) * 4 + q) * 64 + lane] = acc[i][j][q];
;     __syncthreads();
;     {
;         const int t = wid, rgi = t >> 1, cg = t & 1, col = col0 + 16 * cg + r16;
;         const float gt = gate2[col];
;         const bool nxt = ng != nullptr;
;         const float gs = nxt ? ng[col] * (1.f + nsc2[col]) : 0.f;
.LBB0_1010:
	v_mov_b32_e32 v5, v222
	s_and_b32 s5, s17, 0xffffffc0
	s_add_i32 s7, s5, 0x4000
	v_readfirstlane_b32 s4, v5
	v_and_b32_e32 v4, 15, v5
	s_ashr_i32 s14, s4, 6
	v_or_b32_e32 v0, s7, v4
	s_and_b32 s6, s16, 0x3e0
	s_lshl_b32 s30, s14, 7
	s_waitcnt lgkmcnt(0)
	v_ashrrev_i32_e32 v1, 31, v0
	s_ashr_i32 s31, s30, 31
	v_or_b32_e32 v2, s6, v4
	v_lshlrev_b64 v[0:1], 11, v[0:1]
	v_lshlrev_b32_e32 v176, 11, v2
	s_lshl_b64 s[30:31], s[30:31], 1
	v_lshl_add_u64 v[0:1], s[0:1], 0, v[0:1]
	v_lshl_add_u64 v[2:3], s[18:19], 0, v[176:177]
	v_and_b32_e32 v176, 48, v5
	v_lshl_add_u64 v[0:1], v[0:1], 0, s[30:31]
	v_lshl_add_u64 v[54:55], v[0:1], 0, v[176:177]
	v_lshl_add_u64 v[0:1], v[2:3], 0, s[30:31]
	v_lshl_add_u64 v[2:3], v[0:1], 0, v[176:177]
	v_add_co_u32_e32 v58, vcc, s87, v2
	s_mov_b32 s7, 0x10000
	s_nop 0
	v_addc_co_u32_e32 v59, vcc, 0, v3, vcc
	v_add_co_u32_e32 v60, vcc, s87, v54
	s_nop 1
	v_addc_co_u32_e32 v61, vcc, 0, v55, vcc
	v_add_co_u32_e32 v62, vcc, s7, v54
	s_mov_b32 s7, 0x18000
	s_nop 1
	v_addc_co_u32_e32 v63, vcc, 0, v55, vcc
	v_add_co_u32_e32 v0, vcc, s7, v54
	s_nop 1
	v_addc_co_u32_e32 v1, vcc, 0, v55, vcc
	s_lshl_b32 s7, s14, 4
	s_and_b32 s7, s7, 16
	s_or_b32 s6, s6, s7
	s_andn2_b64 vcc, exec, s[82:83]
	global_load_dwordx4 v[80:83], v[54:55], off
	global_load_dwordx4 v[84:87], v[60:61], off
	global_load_dwordx4 v[88:91], v[62:63], off
	global_load_dwordx4 v[92:95], v[0:1], off
	global_load_dwordx4 v[96:99], v[2:3], off
	global_load_dwordx4 v[100:103], v[58:59], off
	global_load_dwordx4 v[104:107], v[54:55], off offset:64
	global_load_dwordx4 v[108:111], v[60:61], off offset:64
	global_load_dwordx4 v[112:115], v[62:63], off offset:64
	global_load_dwordx4 v[116:119], v[0:1], off offset:64
	global_load_dwordx4 v[120:123], v[2:3], off offset:64
	global_load_dwordx4 v[124:127], v[58:59], off offset:64
	global_load_dwordx4 v[128:131], v[54:55], off offset:128
	global_load_dwordx4 v[132:135], v[60:61], off offset:128
	global_load_dwordx4 v[136:139], v[62:63], off offset:128
	global_load_dwordx4 v[140:143], v[0:1], off offset:128
	global_load_dwordx4 v[144:147], v[2:3], off offset:128
	global_load_dwordx4 v[148:151], v[58:59], off offset:128
	s_waitcnt vmcnt(12)
	v_mfma_f32_16x16x32_bf16 v[6:9], v[80:83], v[96:99], 0
	v_mfma_f32_16x16x32_bf16 v[10:13], v[80:83], v[100:103], 0
	v_mfma_f32_16x16x32_bf16 v[14:17], v[84:87], v[96:99], 0
	v_mfma_f32_16x16x32_bf16 v[18:21], v[84:87], v[100:103], 0
	v_mfma_f32_16x16x32_bf16 v[22:25], v[88:91], v[96:99], 0
	v_mfma_f32_16x16x32_bf16 v[26:29], v[88:91], v[100:103], 0
	v_mfma_f32_16x16x32_bf16 v[30:33], v[92:95], v[96:99], 0
	v_mfma_f32_16x16x32_bf16 v[34:37], v[92:95], v[100:103], 0
	global_load_dwordx4 v[80:83], v[54:55], off offset:192
	global_load_dwordx4 v[84:87], v[60:61], off offset:192
	global_load_dwordx4 v[88:91], v[62:63], off offset:192
	global_load_dwordx4 v[92:95], v[0:1], off offset:192
	global_load_dwordx4 v[96:99], v[2:3], off offset:192
	global_load_dwordx4 v[100:103], v[58:59], off offset:192
	s_waitcnt vmcnt(12)
	v_mfma_f32_16x16x32_bf16 v[6:9], v[104:107], v[120:123], v[6:9]
	v_mfma_f32_16x16x32_bf16 v[10:13], v[104:107], v[124:127], v[10:13]
	v_mfma_f32_16x16x32_bf16 v[14:17], v[108:111], v[120:123], v[14:17]
	v_mfma_f32_16x16x32_bf16 v[18:21], v[108:111], v[124:127], v[18:21]
	v_mfma_f32_16x16x32_bf16 v[22:25], v[112:115], v[120:123], v[22:25]
	v_mfma_f32_16x16x32_bf16 v[26:29], v[112:115], v[124:127], v[26:29]
	v_mfma_f32_16x16x32_bf16 v[30:33], v[116:119], v[120:123], v[30:33]
	v_mfma_f32_16x16x32_bf16 v[34:37], v[116:119], v[124:127], v[34:37]
	s_waitcnt vmcnt(6)
	v_mfma_f32_16x16x32_bf16 v[6:9], v[128:131], v[144:147], v[6:9]
	v_mfma_f32_16x16x32_bf16 v[10:13], v[128:131], v[148:151], v[10:13]
	v_mfma_f32_16x16x32_bf16 v[14:17], v[132:135], v[144:147], v[14:17]
	v_mfma_f32_16x16x32_bf16 v[18:21], v[132:135], v[148:151], v[18:21]
	v_mfma_f32_16x16x32_bf16 v[22:25], v[136:139], v[144:147], v[22:25]
	v_mfma_f32_16x16x32_bf16 v[26:29], v[136:139], v[148:151], v[26:29]
	v_mfma_f32_16x16x32_bf16 v[30:33], v[140:143], v[144:147], v[30:33]
	v_mfma_f32_16x16x32_bf16 v[34:37], v[140:143], v[148:151], v[34:37]
	s_waitcnt vmcnt(0)
	v_mfma_f32_16x16x32_bf16 v[6:9], v[80:83], v[96:99], v[6:9]
	v_mfma_f32_16x16x32_bf16 v[10:13], v[80:83], v[100:103], v[10:13]
	v_mfma_f32_16x16x32_bf16 v[14:17], v[84:87], v[96:99], v[14:17]
	v_mfma_f32_16x16x32_bf16 v[18:21], v[84:87], v[100:103], v[18:21]
	v_mfma_f32_16x16x32_bf16 v[22:25], v[88:91], v[96:99], v[22:25]
	v_mfma_f32_16x16x32_bf16 v[26:29], v[88:91], v[100:103], v[26:29]
	v_mfma_f32_16x16x32_bf16 v[30:33], v[92:95], v[96:99], v[30:33]
	v_mfma_f32_16x16x32_bf16 v[34:37], v[92:95], v[100:103], v[34:37]
	v_and_b32_e32 v0, 63, v5
	v_lshl_add_u32 v1, v0, 2, 0
	v_lshl_add_u32 v0, s14, 13, v1
	s_nop 7
	ds_write2st64_b32 v0, v6, v7 offset1:1
	ds_write2st64_b32 v0, v8, v9 offset0:2 offset1:3
	ds_write2st64_b32 v0, v10, v11 offset0:4 offset1:5
	ds_write2st64_b32 v0, v12, v13 offset0:6 offset1:7
	ds_write2st64_b32 v0, v14, v15 offset0:8 offset1:9
	ds_write2st64_b32 v0, v16, v17 offset0:10 offset1:11
	ds_write2st64_b32 v0, v18, v19 offset0:12 offset1:13
	ds_write2st64_b32 v0, v20, v21 offset0:14 offset1:15
	ds_write2st64_b32 v0, v22, v23 offset0:16 offset1:17
	ds_write2st64_b32 v0, v24, v25 offset0:18 offset1:19
	ds_write2st64_b32 v0, v26, v27 offset0:20 offset1:21
	ds_write2st64_b32 v0, v28, v29 offset0:22 offset1:23
	ds_write2st64_b32 v0, v30, v31 offset0:24 offset1:25
	ds_write2st64_b32 v0, v32, v33 offset0:26 offset1:27
	ds_write2st64_b32 v0, v34, v35 offset0:28 offset1:29
	ds_write2st64_b32 v0, v36, v37 offset0:30 offset1:31
	v_or_b32_e32 v8, s6, v4
	v_lshlrev_b32_e32 v176, 2, v8
	v_lshl_add_u64 v[2:3], s[8:9], 0, v[176:177]
	s_waitcnt lgkmcnt(0)
	s_barrier
	global_load_dword v7, v[2:3], off
	v_cndmask_b32_e64 v0, 0, 1, s[82:83]
	v_cmp_ne_u32_e64 s[6:7], 1, v0
	s_cbranch_vccnz .LBB0_1012
	v_lshl_add_u64 v[2:3], s[10:11], 0, v[176:177]
	global_load_dword v0, v[2:3], off
	s_nop 0
	global_load_dword v2, v176, s[24:25]
	s_waitcnt vmcnt(0) lgkmcnt(0)
	v_add_f32_e32 v0, 1.0, v0
	v_mul_f32_e32 v6, v2, v0
	s_branch .LBB0_1013

; __device__ __forceinline__ unsigned pkbf(float lo, float hi) { return pg8::cvt_pk_bf16(lo, hi); }
; __device__ __forceinline__ void ctx_slice_gemm(LAS unsigned char* lds, const bf16_t* A  , const bf16_t* Bt  , int K, ...
;     ...
;         for (int q = 0; q < 4; ++q) {
;             float s = 0.f;
; #pragma unroll
;             for (int w = 0; w < 8; ++w) s += part[((w * 8 + t) * 4 + q) * 64 + lane];
;             const int rr = row0 + 16 * rgi + 4 * g4 + q;
;             const float x = res_ctx[(size_t)rr * DM + col] + gt * s;
;             dst_ctx[(size_t)rr * DM + col] = x;
;             if (nxt) {
;                 xg[(size_t)(MLAT + rr) * DM + col] = (bf16_t)(pkbf(x * gs, 0.f) & 0xffffu);
;                 float ss = x * x;
;                 ss += __shfl_xor(ss, 1); ss += __shfl_xor(ss, 2); ss += __shfl_xor(ss, 4); ss += __shfl_xor(ss, 8);
;                 if (r16 == 0) unsafeAtomicAdd(rowsq_next + MLAT + rr, ss);
;             }
.LBB0_1013:
	s_ashr_i32 s4, s4, 3
	s_and_b32 s4, s4, -16
	s_lshl_b32 s14, s14, 10
	v_bfe_u32 v0, v5, 4, 2
	s_add_i32 s4, s4, s5
	v_add_u32_e32 v9, s14, v1
	v_lshl_or_b32 v0, v0, 2, s4
	v_cmp_eq_u32_e64 s[4:5], 0, v4
	ds_read2st64_b32 v[4:5], v9 offset1:32
	v_lshlrev_b32_e32 v176, 1, v8
	v_lshl_add_u64 v[2:3], s[26:27], 0, v[176:177]
	s_and_b64 vcc, exec, s[6:7]
	s_waitcnt lgkmcnt(0)
	v_add_f32_e32 v1, 0, v4
	v_add_f32_e32 v1, v1, v5
	ds_read2st64_b32 v[4:5], v9 offset0:64 offset1:96
	s_waitcnt lgkmcnt(0)
	v_add_f32_e32 v1, v1, v4
	v_add_f32_e32 v1, v1, v5
	ds_read2st64_b32 v[4:5], v9 offset0:128 offset1:160
	s_waitcnt lgkmcnt(0)
	v_add_f32_e32 v1, v1, v4
	v_add_f32_e32 v1, v1, v5
	ds_read2st64_b32 v[4:5], v9 offset0:192 offset1:224
	s_waitcnt lgkmcnt(0)
	v_add_f32_e32 v1, v1, v4
	v_add_f32_e32 v12, v1, v5
	v_ashrrev_i32_e32 v1, 31, v0
	v_lshlrev_b64 v[10:11], 12, v[0:1]
	v_lshl_or_b32 v10, v8, 2, v10
	v_lshl_add_u64 v[4:5], s[22:23], 0, v[10:11]
	global_load_dword v4, v[4:5], off
	v_lshl_add_u64 v[10:11], s[20:21], 0, v[10:11]
	s_waitcnt vmcnt(0) lgkmcnt(0)
	v_fmac_f32_e32 v4, v7, v12
	global_store_dword v[10:11], v4, off
	v_lshlrev_b64 v[10:11], 11, v[0:1]
	v_lshl_add_u64 v[2:3], v[2:3], 0, v[10:11]
	s_cbranch_vccnz .LBB0_1017
	v_add_co_u32_e32 v10, vcc, 0x2000000, v2
	v_mul_f32_e32 v5, v6, v4
	s_nop 0
	v_addc_co_u32_e32 v11, vcc, 0, v3, vcc
	v_cvt_pk_bf16_f32 v5, v5, v177
	global_store_short v[10:11], v5, off
	v_and_b32_e32 v11, 64, v229
	v_xor_b32_e32 v10, 1, v229
	v_add_u32_e32 v11, 64, v11
	v_cmp_lt_i32_e32 vcc, v10, v11
	v_mul_f32_e32 v5, v4, v4
	s_nop 0
	v_cndmask_b32_e32 v10, v229, v10, vcc
	v_lshlrev_b32_e32 v10, 2, v10
	ds_bpermute_b32 v5, v10, v5
	s_waitcnt lgkmcnt(0)
	v_fmac_f32_e32 v5, v4, v4
	v_xor_b32_e32 v4, 2, v229
	v_cmp_lt_i32_e32 vcc, v4, v11
	s_nop 1
	v_cndmask_b32_e32 v4, v229, v4, vcc
	v_lshlrev_b32_e32 v4, 2, v4
	ds_bpermute_b32 v4, v4, v5
	s_waitcnt lgkmcnt(0)
	v_add_f32_e32 v4, v5, v4
	v_xor_b32_e32 v5, 4, v229
	v_cmp_lt_i32_e32 vcc, v5, v11
	s_nop 1
	v_cndmask_b32_e32 v5, v229, v5, vcc
	v_lshlrev_b32_e32 v5, 2, v5
	ds_bpermute_b32 v5, v5, v4
	s_waitcnt lgkmcnt(0)
	v_add_f32_e32 v4, v4, v5
	v_xor_b32_e32 v5, 8, v229
	v_cmp_lt_i32_e32 vcc, v5, v11
	s_nop 1
	v_cndmask_b32_e32 v5, v229, v5, vcc
	v_lshlrev_b32_e32 v5, 2, v5
	ds_bpermute_b32 v5, v5, v4
	s_and_saveexec_b64 s[14:15], s[4:5]
	s_cbranch_execz .LBB0_1016
	s_waitcnt lgkmcnt(0)
	v_add_f32_e32 v10, v4, v5
	v_lshl_add_u64 v[4:5], v[0:1], 2, s[12:13]
	global_atomic_add_f32 v[4:5], v10, off

; __device__ __forceinline__ unsigned pkbf(float lo, float hi) { return pg8::cvt_pk_bf16(lo, hi); }
; __device__ __forceinline__ void ctx_slice_gemm(LAS unsigned char* lds, const bf16_t* A  , const bf16_t* Bt  , int K, ...
;     ...
;         for (int q = 0; q < 4; ++q) {
;             float s = 0.f;
; #pragma unroll
;             for (int w = 0; w < 8; ++w) s += part[((w * 8 + t) * 4 + q) * 64 + lane];
;             const int rr = row0 + 16 * rgi + 4 * g4 + q;
;             const float x = res_ctx[(size_t)rr * DM + col] + gt * s;
;             dst_ctx[(size_t)rr * DM + col] = x;
;             if (nxt) {
;                 xg[(size_t)(MLAT + rr) * DM + col] = (bf16_t)(pkbf(x * gs, 0.f) & 0xffffu);
;                 float ss = x * x;
;                 ss += __shfl_xor(ss, 1); ss += __shfl_xor(ss, 2); ss += __shfl_xor(ss, 4); ss += __shfl_xor(ss, 8);
;                 if (r16 == 0) unsafeAtomicAdd(rowsq_next + MLAT + rr, ss);
;             }
.LBB0_1017:
	s_waitcnt lgkmcnt(0)
	ds_read2st64_b32 v[4:5], v9 offset0:1 offset1:33
	s_and_b64 vcc, exec, s[6:7]
	s_waitcnt lgkmcnt(0)
	v_add_f32_e32 v1, 0, v4
	v_add_f32_e32 v1, v1, v5
	ds_read2st64_b32 v[4:5], v9 offset0:65 offset1:97
	s_waitcnt lgkmcnt(0)
	v_add_f32_e32 v1, v1, v4
	v_add_f32_e32 v1, v1, v5
	ds_read2st64_b32 v[4:5], v9 offset0:129 offset1:161
	s_waitcnt lgkmcnt(0)
	v_add_f32_e32 v1, v1, v4
	v_add_f32_e32 v1, v1, v5
	ds_read2st64_b32 v[4:5], v9 offset0:193 offset1:225
	s_waitcnt lgkmcnt(0)
	v_add_f32_e32 v1, v1, v4
	v_or_b32_e32 v4, 1, v0
	v_add_f32_e32 v14, v1, v5
	v_ashrrev_i32_e32 v5, 31, v4
	v_lshlrev_b64 v[10:11], 12, v[4:5]
	v_lshl_or_b32 v10, v8, 2, v10
	v_lshl_add_u64 v[12:13], s[22:23], 0, v[10:11]
	global_load_dword v1, v[12:13], off
	v_lshl_add_u64 v[10:11], s[20:21], 0, v[10:11]
	s_waitcnt vmcnt(0) lgkmcnt(0)
	v_fmac_f32_e32 v1, v7, v14
	global_store_dword v[10:11], v1, off
	s_cbranch_vccnz .LBB0_1021
	v_mul_f32_e32 v10, v6, v1
	v_cvt_pk_bf16_f32 v12, v10, v177
	v_add_co_u32_e32 v10, vcc, 0x2000000, v2
	s_nop 1
	v_addc_co_u32_e32 v11, vcc, 0, v3, vcc
	global_store_short v[10:11], v12, off offset:2048
	v_and_b32_e32 v12, 64, v229
	v_xor_b32_e32 v11, 1, v229
	v_add_u32_e32 v12, 64, v12
	v_cmp_lt_i32_e32 vcc, v11, v12
	v_mul_f32_e32 v10, v1, v1
	s_nop 0
	v_cndmask_b32_e32 v11, v229, v11, vcc
	v_lshlrev_b32_e32 v11, 2, v11
	ds_bpermute_b32 v10, v11, v10
	s_waitcnt lgkmcnt(0)
	v_fmac_f32_e32 v10, v1, v1
	v_xor_b32_e32 v1, 2, v229
	v_cmp_lt_i32_e32 vcc, v1, v12
	s_nop 1
	v_cndmask_b32_e32 v1, v229, v1, vcc
	v_lshlrev_b32_e32 v1, 2, v1
	ds_bpermute_b32 v1, v1, v10
	s_waitcnt lgkmcnt(0)
	v_add_f32_e32 v1, v10, v1
	v_xor_b32_e32 v10, 4, v229
	v_cmp_lt_i32_e32 vcc, v10, v12
	s_nop 1
	v_cndmask_b32_e32 v10, v229, v10, vcc
	v_lshlrev_b32_e32 v10, 2, v10
	ds_bpermute_b32 v10, v10, v1
	s_waitcnt lgkmcnt(0)
	v_add_f32_e32 v1, v1, v10
	v_xor_b32_e32 v10, 8, v229
	v_cmp_lt_i32_e32 vcc, v10, v12
	s_nop 1
	v_cndmask_b32_e32 v10, v229, v10, vcc
	v_lshlrev_b32_e32 v10, 2, v10
	ds_bpermute_b32 v10, v10, v1
	s_and_saveexec_b64 s[14:15], s[4:5]
	s_cbranch_execz .LBB0_1020
	s_waitcnt lgkmcnt(0)
	v_add_f32_e32 v1, v1, v10
	v_lshl_add_u64 v[4:5], v[4:5], 2, s[12:13]
	global_atomic_add_f32 v[4:5], v1, off

; __device__ __forceinline__ unsigned pkbf(float lo, float hi) { return pg8::cvt_pk_bf16(lo, hi); }
; __device__ __forceinline__ void ctx_slice_gemm(LAS unsigned char* lds, const bf16_t* A  , const bf16_t* Bt  , int K, ...
;     ...
;         for (int q = 0; q < 4; ++q) {
;             float s = 0.f;
; #pragma unroll
;             for (int w = 0; w < 8; ++w) s += part[((w * 8 + t) * 4 + q) * 64 + lane];
;             const int rr = row0 + 16 * rgi + 4 * g4 + q;
;             const float x = res_ctx[(size_t)rr * DM + col] + gt * s;
;             dst_ctx[(size_t)rr * DM + col] = x;
;             if (nxt) {
;                 xg[(size_t)(MLAT + rr) * DM + col] = (bf16_t)(pkbf(x * gs, 0.f) & 0xffffu);
;                 float ss = x * x;
;                 ss += __shfl_xor(ss, 1); ss += __shfl_xor(ss, 2); ss += __shfl_xor(ss, 4); ss += __shfl_xor(ss, 8);
;                 if (r16 == 0) unsafeAtomicAdd(rowsq_next + MLAT + rr, ss);
;             }
.LBB0_1021:
	ds_read2st64_b32 v[4:5], v9 offset0:2 offset1:34
	s_and_b64 vcc, exec, s[6:7]
	s_waitcnt lgkmcnt(0)
	v_add_f32_e32 v1, 0, v4
	v_add_f32_e32 v1, v1, v5
	ds_read2st64_b32 v[4:5], v9 offset0:66 offset1:98
	s_waitcnt lgkmcnt(0)
	v_add_f32_e32 v1, v1, v4
	v_add_f32_e32 v1, v1, v5
	ds_read2st64_b32 v[4:5], v9 offset0:130 offset1:162
	s_waitcnt lgkmcnt(0)
	v_add_f32_e32 v1, v1, v4
	v_add_f32_e32 v1, v1, v5
	ds_read2st64_b32 v[4:5], v9 offset0:194 offset1:226
	s_waitcnt lgkmcnt(0)
	v_add_f32_e32 v1, v1, v4
	v_or_b32_e32 v4, 2, v0
	v_add_f32_e32 v14, v1, v5
	v_ashrrev_i32_e32 v5, 31, v4
	v_lshlrev_b64 v[10:11], 12, v[4:5]
	v_lshl_or_b32 v10, v8, 2, v10
	v_lshl_add_u64 v[12:13], s[22:23], 0, v[10:11]
	global_load_dword v1, v[12:13], off
	v_lshl_add_u64 v[10:11], s[20:21], 0, v[10:11]
	s_waitcnt vmcnt(0) lgkmcnt(0)
	v_fmac_f32_e32 v1, v7, v14
	global_store_dword v[10:11], v1, off
	s_cbranch_vccnz .LBB0_1025
	v_mul_f32_e32 v10, v6, v1
	v_cvt_pk_bf16_f32 v12, v10, v177
	v_add_co_u32_e32 v10, vcc, 0x2001000, v2
	s_nop 1
	v_addc_co_u32_e32 v11, vcc, 0, v3, vcc
	global_store_short v[10:11], v12, off
	v_and_b32_e32 v12, 64, v229
	v_xor_b32_e32 v11, 1, v229
	v_add_u32_e32 v12, 64, v12
	v_cmp_lt_i32_e32 vcc, v11, v12
	v_mul_f32_e32 v10, v1, v1
	s_nop 0
	v_cndmask_b32_e32 v11, v229, v11, vcc
	v_lshlrev_b32_e32 v11, 2, v11
	ds_bpermute_b32 v10, v11, v10
	s_waitcnt lgkmcnt(0)
	v_fmac_f32_e32 v10, v1, v1
	v_xor_b32_e32 v1, 2, v229
	v_cmp_lt_i32_e32 vcc, v1, v12
	s_nop 1
	v_cndmask_b32_e32 v1, v229, v1, vcc
	v_lshlrev_b32_e32 v1, 2, v1
	ds_bpermute_b32 v1, v1, v10
	s_waitcnt lgkmcnt(0)
	v_add_f32_e32 v1, v10, v1
	v_xor_b32_e32 v10, 4, v229
	v_cmp_lt_i32_e32 vcc, v10, v12
	s_nop 1
	v_cndmask_b32_e32 v10, v229, v10, vcc
	v_lshlrev_b32_e32 v10, 2, v10
	ds_bpermute_b32 v10, v10, v1
	s_waitcnt lgkmcnt(0)
	v_add_f32_e32 v1, v1, v10
	v_xor_b32_e32 v10, 8, v229
	v_cmp_lt_i32_e32 vcc, v10, v12
	s_nop 1
	v_cndmask_b32_e32 v10, v229, v10, vcc
	v_lshlrev_b32_e32 v10, 2, v10
	ds_bpermute_b32 v10, v10, v1
	s_and_saveexec_b64 s[14:15], s[4:5]
	s_cbranch_execz .LBB0_1024
	s_waitcnt lgkmcnt(0)
	v_add_f32_e32 v1, v1, v10
	v_lshl_add_u64 v[4:5], v[4:5], 2, s[12:13]
	global_atomic_add_f32 v[4:5], v1, off

; __device__ __forceinline__ unsigned pkbf(float lo, float hi) { return pg8::cvt_pk_bf16(lo, hi); }
; __device__ __forceinline__ void ctx_slice_gemm(LAS unsigned char* lds, const bf16_t* A  , const bf16_t* Bt  , int K, ...
;     ...
;         for (int q = 0; q < 4; ++q) {
;             float s = 0.f;
; #pragma unroll
;             for (int w = 0; w < 8; ++w) s += part[((w * 8 + t) * 4 + q) * 64 + lane];
;             const int rr = row0 + 16 * rgi + 4 * g4 + q;
;             const float x = res_ctx[(size_t)rr * DM + col] + gt * s;
;             dst_ctx[(size_t)rr * DM + col] = x;
;             if (nxt) {
;                 xg[(size_t)(MLAT + rr) * DM + col] = (bf16_t)(pkbf(x * gs, 0.f) & 0xffffu);
;                 float ss = x * x;
;                 ss += __shfl_xor(ss, 1); ss += __shfl_xor(ss, 2); ss += __shfl_xor(ss, 4); ss += __shfl_xor(ss, 8);
;                 if (r16 == 0) unsafeAtomicAdd(rowsq_next + MLAT + rr, ss);
;             }
.LBB0_1025:
	ds_read2st64_b32 v[4:5], v9 offset0:3 offset1:35
	v_or_b32_e32 v0, 3, v0
	s_and_b64 vcc, exec, s[6:7]
	s_waitcnt lgkmcnt(0)
	v_add_f32_e32 v1, 0, v4
	v_add_f32_e32 v1, v1, v5
	ds_read2st64_b32 v[4:5], v9 offset0:67 offset1:99
	s_waitcnt lgkmcnt(0)
	v_add_f32_e32 v1, v1, v4
	v_add_f32_e32 v1, v1, v5
	ds_read2st64_b32 v[4:5], v9 offset0:131 offset1:163
	s_waitcnt lgkmcnt(0)
	v_add_f32_e32 v1, v1, v4
	v_add_f32_e32 v1, v1, v5
	ds_read2st64_b32 v[4:5], v9 offset0:195 offset1:227
	s_waitcnt lgkmcnt(0)
	v_add_f32_e32 v1, v1, v4
	v_add_f32_e32 v9, v1, v5
	v_ashrrev_i32_e32 v1, 31, v0
	v_lshlrev_b64 v[10:11], 12, v[0:1]
	v_lshl_or_b32 v10, v8, 2, v10
	v_lshl_add_u64 v[4:5], s[22:23], 0, v[10:11]
	global_load_dword v4, v[4:5], off
	s_waitcnt vmcnt(0) lgkmcnt(0)
	v_fmac_f32_e32 v4, v7, v9
	v_lshl_add_u64 v[8:9], s[20:21], 0, v[10:11]
	global_store_dword v[8:9], v4, off
	s_cbranch_vccnz .LBB0_1009
	v_mul_f32_e32 v5, v6, v4
	v_add_co_u32_e32 v2, vcc, 0x2001000, v2
	v_cvt_pk_bf16_f32 v5, v5, v177
	s_nop 1
	v_addc_co_u32_e32 v3, vcc, 0, v3, vcc
	global_store_short v[2:3], v5, off offset:2048
	v_and_b32_e32 v5, 64, v229
	v_xor_b32_e32 v3, 1, v229
	v_add_u32_e32 v5, 64, v5
	v_cmp_lt_i32_e32 vcc, v3, v5
	v_mul_f32_e32 v2, v4, v4
	s_nop 0
	v_cndmask_b32_e32 v3, v229, v3, vcc
	v_lshlrev_b32_e32 v3, 2, v3
	ds_bpermute_b32 v2, v3, v2
	v_xor_b32_e32 v3, 2, v229
	v_cmp_lt_i32_e32 vcc, v3, v5
	s_waitcnt lgkmcnt(0)
	v_fmac_f32_e32 v2, v4, v4
	v_cndmask_b32_e32 v3, v229, v3, vcc
	v_lshlrev_b32_e32 v3, 2, v3
	ds_bpermute_b32 v3, v3, v2
	s_waitcnt lgkmcnt(0)
	v_add_f32_e32 v2, v2, v3
	v_xor_b32_e32 v3, 4, v229
	v_cmp_lt_i32_e32 vcc, v3, v5
	s_nop 1
	v_cndmask_b32_e32 v3, v229, v3, vcc
	v_lshlrev_b32_e32 v3, 2, v3
	ds_bpermute_b32 v3, v3, v2
	s_waitcnt lgkmcnt(0)
	v_add_f32_e32 v2, v2, v3
	v_xor_b32_e32 v3, 8, v229
	v_cmp_lt_i32_e32 vcc, v3, v5
	s_nop 1
	v_cndmask_b32_e32 v3, v229, v3, vcc
	v_lshlrev_b32_e32 v3, 2, v3
	ds_bpermute_b32 v3, v3, v2
	s_and_saveexec_b64 s[6:7], s[4:5]
	s_cbranch_execz .LBB0_1008
	s_waitcnt lgkmcnt(0)
	v_add_f32_e32 v2, v2, v3
	v_lshl_add_u64 v[0:1], v[0:1], 2, s[12:13]
	global_atomic_add_f32 v[0:1], v2, off
	s_branch .LBB0_1008

; __device__ __forceinline__ unsigned xb_ld(unsigned* p)              { return __hip_atomic_load(p, __ATOMIC_RELAXED, __HIP_MEMORY_SCOPE_AGENT); }
; __device__ __forceinline__ void xcd_barrier_complete(unsigned* bar, unsigned x, unsigned& nloc, unsigned& nx) {
;     ...
;     for (;;) {
;         sum = 0u; cnt = 0u; mine = 0u;
; #pragma unroll
;         for (unsigned j = 0; j < 16; ++j) { const unsigned c = xb_ld(&bar[XB_XCNT(j)]); sum += c; cnt += (c > 0u) ? 1u : 0u; mine = (j == x) ? c : mine; }
;         if (sum == G) break;
;         __builtin_amdgcn_s_sleep(1);
;         if ((++sp & 255u) == 0u) { if (xb_ld(&bar[XB_TMO])) break; if (sp > XB_SPIN_CAP) { atomicAdd(&bar[XB_TMO], 1u); break; } }
;     }
.LBB0_1033:
	v_mov_b64_e32 v[12:13], s[40:41]
	global_load_dword v1, v[12:13], off offset:1024 sc1
	s_waitcnt lgkmcnt(0)
	global_load_dword v0, v[12:13], off offset:1280 sc1
	global_load_dword v2, v[12:13], off offset:1536 sc1
	s_or_b64 s[20:21], s[20:21], exec
	s_or_b64 s[18:19], s[18:19], exec
	s_waitcnt vmcnt(0) lgkmcnt(0)
	v_add_u32_e32 v3, v0, v1
	v_add_u32_e32 v4, v3, v2
	global_load_dword v3, v[12:13], off offset:1792 sc1
	s_waitcnt vmcnt(0) lgkmcnt(0)
	v_add_u32_e32 v5, v4, v3
	global_load_dword v4, v[12:13], off offset:2048 sc1
	s_waitcnt vmcnt(0) lgkmcnt(0)
	v_add_u32_e32 v6, v5, v4
	global_load_dword v5, v[12:13], off offset:2304 sc1
	s_waitcnt vmcnt(0) lgkmcnt(0)
	v_add_u32_e32 v7, v6, v5
	global_load_dword v6, v[12:13], off offset:2560 sc1
	s_waitcnt vmcnt(0) lgkmcnt(0)
	v_add_u32_e32 v8, v7, v6
	global_load_dword v7, v[12:13], off offset:2816 sc1
	s_waitcnt vmcnt(0) lgkmcnt(0)
	v_add_u32_e32 v9, v8, v7
	global_load_dword v8, v[12:13], off offset:3072 sc1
	s_waitcnt vmcnt(0) lgkmcnt(0)
	v_add_u32_e32 v10, v9, v8
	global_load_dword v9, v[12:13], off offset:3328 sc1
	s_waitcnt vmcnt(0) lgkmcnt(0)
	v_add_u32_e32 v11, v10, v9
	global_load_dword v10, v[12:13], off offset:3584 sc1
	s_waitcnt vmcnt(0) lgkmcnt(0)
	v_add_u32_e32 v14, v11, v10
	global_load_dword v11, v[12:13], off offset:3840 sc1
	v_mov_b64_e32 v[12:13], s[0:1]
	global_load_dword v12, v[12:13], off sc1
	s_waitcnt vmcnt(0) lgkmcnt(0)
	v_add_u32_e32 v14, v14, v11
	v_add_u32_e32 v16, v14, v12
	v_mov_b64_e32 v[14:15], s[4:5]
	global_load_dword v13, v[14:15], off sc1
	v_mov_b64_e32 v[14:15], s[6:7]
	global_load_dword v14, v[14:15], off sc1
	s_waitcnt vmcnt(0) lgkmcnt(0)
	v_add_u32_e32 v16, v16, v13
	v_add_u32_e32 v18, v16, v14
	v_mov_b64_e32 v[16:17], s[8:9]
	global_load_dword v15, v[16:17], off sc1
	s_waitcnt vmcnt(0) lgkmcnt(0)
	v_add_u32_e32 v16, v18, v15
	v_cmp_ne_u32_e32 vcc, s78, v16
	s_and_saveexec_b64 s[22:23], vcc
	s_cbranch_execz .LBB0_1032
	s_and_b32 s26, s17, 0xff
	s_mov_b64 s[24:25], -1
	s_cmp_eq_u32 s26, 0
	s_mov_b64 s[28:29], -1
	s_mov_b64 s[26:27], -1
	s_sleep 1
	s_cbranch_scc1 .LBB0_1036
	s_and_saveexec_b64 s[30:31], s[28:29]
	s_cbranch_execz .LBB0_1031
	s_branch .LBB0_1039
.LBB0_1036:
	v_mov_b64_e32 v[16:17], s[40:41]
	global_load_dword v16, v[16:17], off offset:512 sc1
	s_mov_b64 s[28:29], 0
	s_waitcnt vmcnt(0) lgkmcnt(0)
	v_cmp_eq_u32_e32 vcc, 0, v16
	s_and_saveexec_b64 s[30:31], vcc
	s_cmp_lt_u32 s17, 0x40001
	s_cselect_b64 s[28:29], -1, 0
	s_xor_b64 s[26:27], exec, -1
	s_and_b64 s[28:29], s[28:29], exec
	s_or_b64 exec, exec, s[30:31]
	s_and_saveexec_b64 s[30:31], s[28:29]
	s_cbranch_execz .LBB0_1031

; __device__ __forceinline__ unsigned xb_ld(unsigned* p)              { return __hip_atomic_load(p, __ATOMIC_RELAXED, __HIP_MEMORY_SCOPE_AGENT); }
; __device__ __forceinline__ unsigned xb_add(unsigned* p, unsigned v) { return __hip_atomic_fetch_add(p, v, __ATOMIC_RELAXED, __HIP_MEMORY_SCOPE_AGENT); }
; #define XB_SPIN(cond, bar) do { unsigned _sp = 0; while (cond) { __builtin_amdgcn_s_sleep(1); \
;     if ((++_sp & 255u) == 0u) { if (xb_ld(&(bar)[XB_TMO])) break; if (_sp > XB_SPIN_CAP) { atomicAdd(&(bar)[XB_TMO], 1u); break; } } } } while (0)
; __device__ __forceinline__ void xcd_barrier(const XcdBarrier& b) {
;     ...
;         const unsigned old = xb_add(&bar[XB_XSUB(b.x)], 1u);
;         const unsigned gen = old / nloc;
;         if (old + 1u == (gen + 1u) * nloc) {
;             __builtin_amdgcn_fence(__ATOMIC_RELEASE, "agent");
;             asm volatile("s_waitcnt vmcnt(0)" ::: "memory");
;             const unsigned og = xb_add(&bar[XB_TOP], 1u);
;             const unsigned tg = og / nx;
;             if (og + 1u == (tg + 1u) * nx) xb_add(&bar[XB_TOPGEN], 1u);
;             else XB_SPIN(xb_ld(&bar[XB_TOPGEN]) == tg, bar);
;             __builtin_amdgcn_fence(__ATOMIC_ACQUIRE, "agent");
;             xb_add(&bar[XB_XGEN(b.x)], 1u);
;             asm volatile("s_waitcnt vmcnt(0)" ::: "memory");
;         } else {
;             XB_SPIN(xb_ld(&bar[XB_XGEN(b.x)]) == gen, bar);
.LBB0_1043:
	s_lshl_b32 s0, s16, 8
	s_add_u32 s17, s40, s0
	s_addc_u32 s16, s41, 0
	v_mov_b32_e32 v1, s17
	v_add_co_u32_e32 v4, vcc, 0x1000, v1
	v_mov_b32_e32 v1, s16
	s_nop 0
	v_addc_co_u32_e32 v5, vcc, 0, v1, vcc
	global_atomic_add v3, v[4:5], v225, off offset:1024 sc0
	v_cvt_f32_u32_e32 v1, v2
	v_sub_u32_e32 v4, 0, v2
	v_rcp_iflag_f32_e32 v1, v1
	s_nop 0
	v_mul_f32_e32 v1, 0x4f7ffffe, v1
	v_cvt_u32_f32_e32 v1, v1
	v_mul_lo_u32 v4, v4, v1
	v_mul_hi_u32 v4, v1, v4
	v_add_u32_e32 v1, v1, v4
	s_waitcnt vmcnt(0) lgkmcnt(0)
	v_mul_hi_u32 v1, v3, v1
	v_mul_lo_u32 v4, v1, v2
	v_sub_u32_e32 v4, v3, v4
	v_cmp_ge_u32_e32 vcc, v4, v2
	v_add_u32_e32 v5, 1, v1
	s_nop 0
	v_cndmask_b32_e32 v1, v1, v5, vcc
	v_sub_u32_e32 v5, v4, v2
	v_cndmask_b32_e32 v4, v4, v5, vcc
	v_cmp_ge_u32_e32 vcc, v4, v2
	v_add_u32_e32 v4, 1, v1
	s_nop 0
	v_cndmask_b32_e32 v1, v1, v4, vcc
	v_add_u32_e32 v4, 1, v3
	v_mad_u64_u32 v[2:3], s[0:1], v2, v1, v[2:3]
	v_cmp_ne_u32_e32 vcc, v4, v2
	s_and_saveexec_b64 s[0:1], vcc
	s_xor_b64 s[0:1], exec, s[0:1]
	s_cbranch_execz .LBB0_1056
	v_mov_b32_e32 v0, s17
	v_add_co_u32_e32 v2, vcc, 0x2000, v0
	v_mov_b32_e32 v0, s16
	s_nop 0
	v_addc_co_u32_e32 v3, vcc, 0, v0, vcc
	global_load_dword v0, v[2:3], off offset:1024 sc1
	s_add_u32 s6, s17, 0x2400
	s_addc_u32 s7, s16, 0
	s_waitcnt vmcnt(0) lgkmcnt(0)
	v_cmp_eq_u32_e32 vcc, v0, v1
	s_and_saveexec_b64 s[4:5], vcc
	s_cbranch_execz .LBB0_1055
	s_mov_b32 s26, 1
	s_mov_b64 s[8:9], 0
	s_branch .LBB0_1047

; __device__ __forceinline__ unsigned xb_ld(unsigned* p)              { return __hip_atomic_load(p, __ATOMIC_RELAXED, __HIP_MEMORY_SCOPE_AGENT); }
; #define XB_SPIN(cond, bar) do { unsigned _sp = 0; while (cond) { __builtin_amdgcn_s_sleep(1); \
;     if ((++_sp & 255u) == 0u) { if (xb_ld(&(bar)[XB_TMO])) break; if (_sp > XB_SPIN_CAP) { atomicAdd(&(bar)[XB_TMO], 1u); break; } } } } while (0)
; __device__ __forceinline__ void xcd_barrier(const XcdBarrier& b) {
;     ...
;             XB_SPIN(xb_ld(&bar[XB_XGEN(b.x)]) == gen, bar);
.LBB0_1047:
	s_and_b32 s20, s26, 0xff
	s_mov_b64 s[18:19], -1
	s_cmp_lg_u32 s20, 0
	s_mov_b64 s[20:21], -1
	s_sleep 1
	s_cbranch_scc1 .LBB0_1051
	v_mov_b64_e32 v[2:3], s[40:41]
	global_load_dword v0, v[2:3], off offset:512 sc1
	s_mov_b64 s[20:21], 0
	s_mov_b64 s[22:23], -1
	s_waitcnt vmcnt(0) lgkmcnt(0)
	v_cmp_eq_u32_e32 vcc, 0, v0
	s_and_saveexec_b64 s[24:25], vcc
	s_cmp_lt_u32 s26, 0x40001
	s_cselect_b64 s[20:21], -1, 0
	s_xor_b64 s[22:23], exec, -1
	s_and_b64 s[20:21], s[20:21], exec
	s_or_b64 exec, exec, s[24:25]
.LBB0_1051:
	s_andn2_b64 s[12:13], s[12:13], exec
	s_and_b64 s[22:23], s[22:23], exec
	s_or_b64 s[12:13], s[12:13], s[22:23]
	s_and_saveexec_b64 s[22:23], s[20:21]
	s_cbranch_execz .LBB0_1046
	v_mov_b64_e32 v[2:3], s[6:7]
	global_load_dword v0, v[2:3], off sc1
	s_add_i32 s26, s26, 1
	s_or_b64 s[12:13], s[12:13], exec
	s_waitcnt vmcnt(0) lgkmcnt(0)
	v_cmp_ne_u32_e32 vcc, v0, v1
	s_orn2_b64 s[18:19], vcc, exec
	s_branch .LBB0_1046

; __device__ __forceinline__ unsigned xb_ld(unsigned* p)              { return __hip_atomic_load(p, __ATOMIC_RELAXED, __HIP_MEMORY_SCOPE_AGENT); }
; #define XB_SPIN(cond, bar) do { unsigned _sp = 0; while (cond) { __builtin_amdgcn_s_sleep(1); \
;     if ((++_sp & 255u) == 0u) { if (xb_ld(&(bar)[XB_TMO])) break; if (_sp > XB_SPIN_CAP) { atomicAdd(&(bar)[XB_TMO], 1u); break; } } } } while (0)
; __device__ __forceinline__ void xcd_barrier(const XcdBarrier& b) {
;     ...
;             else XB_SPIN(xb_ld(&bar[XB_TOPGEN]) == tg, bar);
.LBB0_1063:
	v_mov_b64_e32 v[0:1], s[6:7]
	global_load_dword v0, v[0:1], off sc1
	s_mov_b64 s[22:23], 0
	s_mov_b64 s[20:21], -1
	s_waitcnt vmcnt(0) lgkmcnt(0)
	v_cmp_eq_u32_e32 vcc, 0, v0
	s_and_saveexec_b64 s[24:25], vcc
	s_cmp_lt_u32 s26, 0x40001
	s_cselect_b64 s[22:23], -1, 0
	s_xor_b64 s[20:21], exec, -1
	s_and_b64 s[22:23], s[22:23], exec
	s_or_b64 exec, exec, s[24:25]
	s_and_saveexec_b64 s[24:25], s[22:23]
	s_cbranch_execz .LBB0_1060
.LBB0_1066:
	v_mov_b64_e32 v[0:1], s[0:1]
	global_load_dword v0, v[0:1], off sc1
	s_add_i32 s26, s26, 1
	s_or_b64 s[20:21], s[20:21], exec
	s_waitcnt vmcnt(0) lgkmcnt(0)
	v_cmp_ne_u32_e32 vcc, v0, v2
	s_orn2_b64 s[18:19], vcc, exec
	s_branch .LBB0_1060

; __device__ __forceinline__ unsigned xb_add(unsigned* p, unsigned v) { return __hip_atomic_fetch_add(p, v, __ATOMIC_RELAXED, __HIP_MEMORY_SCOPE_AGENT); }
; __device__ __forceinline__ void xcd_barrier(const XcdBarrier& b) {
;     ...
;             __builtin_amdgcn_fence(__ATOMIC_ACQUIRE, "agent");
;             xb_add(&bar[XB_XGEN(b.x)], 1u);
;             asm volatile("s_waitcnt vmcnt(0)" ::: "memory");
.LBB0_1071:
	s_or_b64 exec, exec, s[0:1]
	v_mov_b32_e32 v0, s17
	v_add_co_u32_e32 v0, vcc, 0x2000, v0
	v_mov_b32_e32 v1, s16
	s_nop 0
	v_addc_co_u32_e32 v1, vcc, 0, v1, vcc
	s_waitcnt vmcnt(0) lgkmcnt(0)
	buffer_inv sc1
	global_atomic_add v[0:1], v225, off offset:1024
	s_waitcnt vmcnt(0)

; __device__ __forceinline__ float sigm(float v) { return __builtin_amdgcn_rcpf(1.f + __builtin_amdgcn_exp2f(-1.4426950408889634f * v)); }
; __device__ __forceinline__ unsigned pkbf(float lo, float hi) { return pg8::cvt_pk_bf16(lo, hi); }
;     __device__ __forceinline__ void operator()(const f32x4 (&acc)[2][2][4][2], const Unit& u, int wr, int wc, int fr, int fq) const {
;         const int pn = u.pn, pm = u.pm;
;         const int v = pm >= 64 ? 2 : (pm >> 5);
;         const int cb = pn * 256 + wc * 32 + 8 * fq;
;         f32x4 bv[2][2];
; #pragma unroll
;         for (int bj = 0; bj < 2; ++bj)
; #pragma unroll
;             for (int n = 0; n < 2; ++n) bv[bj][n] = *(const f32x4*)(bias + v * FFI + cb + 128 * bj + 4 * n);
; #pragma unroll
;         for (int ai = 0; ai < 2; ++ai)
; #pragma unroll
;             for (int m = 0; m < 4; ++m) {
;                 const int row = pm * 256 + ai * 128 + wr * 64 + m * 16 + fr;
;                 const float rinv = rsqrtf(rowsq[row] * (1.f / DM) + EPSN);
;                 f32x4 o[2];
; #pragma unroll
;                 for (int n = 0; n < 2; ++n) {
;                     const f32x4 g = acc[ai][0][m][n] * rinv + bv[0][n], up = acc[ai][1][m][n] * rinv + bv[1][n];
; #pragma unroll
;                     for (int j = 0; j < 4; ++j) o[n][j] = g[j] * sigm(g[j]) * up[j];
;                 }
;                 u32x4 w; w.x = pkbf(o[0][0], o[0][1]); w.y = pkbf(o[0][2], o[0][3]); w.z = pkbf(o[1][0], o[1][1]); w.w = pkbf(o[1][2], o[1][3]);
;                 *(u32x4*)(act + (size_t)row * FFH + pn * 128 + wc * 32 + 8 * fq) = w;
;             }
.LBB0_1092:
	v_lshl_add_u32 v148, s26, 8, v152
	v_ashrrev_i32_e32 v149, 31, v148
	v_lshl_add_u64 v[150:151], v[148:149], 2, s[10:11]
	s_min_i32 s1, s26, 64
	global_load_dword v149, v[150:151], off
	global_load_dword v182, v[150:151], off offset:64
	global_load_dword v183, v[150:151], off offset:128
	global_load_dword v184, v[150:151], off offset:192
	global_load_dword v185, v[150:151], off offset:512
	global_load_dword v186, v[150:151], off offset:576
	global_load_dword v187, v[150:151], off offset:640
	global_load_dword v188, v[150:151], off offset:704
	s_lshr_b32 s1, s1, 5
	s_mul_i32 s28, s1, 0x1600
	s_ashr_i32 s29, s28, 31
	s_lshl_b64 s[28:29], s[28:29], 2
	v_lshl_or_b32 v80, s0, 8, v154
	s_add_u32 s26, s38, s28
	s_addc_u32 s27, s39, s29
	v_ashrrev_i32_e32 v81, 31, v80
	v_lshl_add_u64 v[80:81], v[80:81], 2, s[26:27]
	global_load_dwordx4 v[156:159], v[80:81], off offset:512
	global_load_dwordx4 v[84:87], v[80:81], off
	global_load_dwordx4 v[160:163], v[80:81], off offset:528
	s_nop 0
	global_load_dwordx4 v[80:83], v[80:81], off offset:16
	v_mov_b32_e32 v168, v120
	v_mov_b32_e32 v169, v124
	v_mov_b32_e32 v124, v121
	v_mov_b32_e32 v164, v132
	v_mov_b32_e32 v165, v128
	v_mov_b32_e32 v128, v133
	v_mov_b32_e32 v166, v134
	v_mov_b32_e32 v167, v130
	v_mov_b32_e32 v130, v135
	v_mov_b32_e32 v170, v122
	v_mov_b32_e32 v171, v126
	v_mov_b32_e32 v126, v123
	s_lshl_b32 s0, s0, 7
	s_ashr_i32 s1, s0, 31
	s_waitcnt vmcnt(0) lgkmcnt(0)
	v_fmamk_f32 v120, v149, 0x3a800000, v224
	v_mul_f32_e32 v121, 0x4b800000, v120
	v_cmp_gt_f32_e32 vcc, s33, v120
	v_mov_b32_e32 v122, v158
	s_nop 0
	v_cndmask_b32_e32 v120, v120, v121, vcc
	v_rsq_f32_e32 v149, v120
	v_mov_b32_e32 v120, v156
	v_mov_b32_e32 v121, v84
	v_mov_b32_e32 v84, v157
	v_mul_f32_e32 v156, 0x45800000, v149
	v_mov_b32_e32 v123, v86
	v_mov_b32_e32 v133, v80
	v_mov_b32_e32 v80, v161
	v_mov_b32_e32 v134, v162
	v_mov_b32_e32 v135, v82
	v_cndmask_b32_e32 v156, v149, v156, vcc
	v_mov_b32_e32 v86, v159
	v_mov_b32_e32 v132, v160
	v_mov_b32_e32 v82, v163
	v_pk_fma_f32 v[158:159], v[164:165], v[156:157], v[120:121] op_sel_hi:[1,0,1]
	v_pk_fma_f32 v[128:129], v[128:129], v[156:157], v[84:85] op_sel_hi:[1,0,1]
	v_pk_fma_f32 v[160:161], v[166:167], v[156:157], v[122:123] op_sel_hi:[1,0,1]
	v_pk_fma_f32 v[124:125], v[124:125], v[156:157], v[80:81] op_sel_hi:[1,0,1]
	v_pk_fma_f32 v[164:165], v[170:171], v[156:157], v[134:135] op_sel_hi:[1,0,1]
	v_pk_fma_f32 v[130:131], v[130:131], v[156:157], v[86:87] op_sel_hi:[1,0,1]
	v_pk_fma_f32 v[162:163], v[168:169], v[156:157], v[132:133] op_sel_hi:[1,0,1]
	v_pk_fma_f32 v[126:127], v[126:127], v[156:157], v[82:83] op_sel_hi:[1,0,1]
	v_mul_f32_e32 v149, 0xbfb8aa3b, v159
	v_mul_f32_e32 v156, 0xbfb8aa3b, v129
	v_mul_f32_e32 v157, 0xbfb8aa3b, v161
	v_mul_f32_e32 v168, 0xbfb8aa3b, v125
	v_mul_f32_e32 v169, 0xbfb8aa3b, v165
	v_mul_f32_e32 v166, 0xbfb8aa3b, v131
	v_mul_f32_e32 v167, 0xbfb8aa3b, v163
	v_mul_f32_e32 v170, 0xbfb8aa3b, v127
	v_exp_f32_e32 v149, v149
	v_exp_f32_e32 v156, v156
	v_exp_f32_e32 v157, v157
	v_exp_f32_e32 v168, v168
	v_exp_f32_e32 v169, v169
	v_exp_f32_e32 v166, v166
	v_exp_f32_e32 v167, v167
	v_exp_f32_e32 v170, v170
	v_add_f32_e32 v149, 1.0, v149
	v_add_f32_e32 v156, 1.0, v156
	v_add_f32_e32 v157, 1.0, v157
	v_add_f32_e32 v168, 1.0, v168
	v_add_f32_e32 v169, 1.0, v169
	v_add_f32_e32 v166, 1.0, v166
	v_add_f32_e32 v167, 1.0, v167
	v_add_f32_e32 v170, 1.0, v170
	v_rcp_f32_e32 v149, v149
	v_rcp_f32_e32 v156, v156
	v_rcp_f32_e32 v157, v157
	v_rcp_f32_e32 v168, v168
	v_rcp_f32_e32 v169, v169
	v_rcp_f32_e32 v166, v166
	v_rcp_f32_e32 v167, v167
	v_rcp_f32_e32 v170, v170
	v_mul_f32_e32 v149, v159, v149
	v_mul_f32_e32 v129, v129, v156
	v_mul_f32_e32 v156, v161, v157
	v_mul_f32_e32 v125, v125, v168
	v_mul_f32_e32 v159, v165, v169
	v_mul_f32_e32 v131, v131, v166
	v_mul_f32_e32 v157, v163, v167
	v_mul_f32_e32 v128, v128, v129
	v_mul_f32_e32 v129, v160, v156
	v_mul_f32_e32 v124, v124, v125
	v_mul_f32_e32 v125, v164, v159
	v_mul_f32_e32 v127, v127, v170
	v_mul_f32_e32 v149, v158, v149
	v_mul_f32_e32 v130, v130, v131
	v_mul_f32_e32 v131, v162, v157
	v_mul_f32_e32 v156, v126, v127
	v_cvt_pk_bf16_f32 v126, v149, v128
	v_cvt_pk_bf16_f32 v127, v129, v130
	v_cvt_pk_bf16_f32 v128, v131, v124
	v_cvt_pk_bf16_f32 v129, v125, v156
	v_mov_b64_e32 v[124:125], s[12:13]
	v_mad_i64_i32 v[130:131], s[26:27], v148, s3, v[124:125]
	s_lshl_b64 s[26:27], s[0:1], 1
	s_nop 0
	v_lshl_add_u64 v[130:131], v[130:131], 0, s[26:27]
	v_lshl_add_u64 v[130:131], v[130:131], 0, s[76:77]
	v_lshl_add_u64 v[130:131], v[130:131], 0, v[176:177]
	global_store_dwordx4 v[130:131], v[126:129], off
	s_nop 0
	s_nop 0
	v_mov_b32_e32 v127, v112
	v_mov_b32_e32 v112, v117
	v_mov_b32_e32 v117, v114
	v_mov_b32_e32 v114, v119
	v_mov_b32_e32 v119, v104
	v_mov_b32_e32 v104, v109
	v_mov_b32_e32 v109, v106
	v_mov_b32_e32 v106, v111
	v_mov_b32_e32 v126, v116
	v_mov_b32_e32 v116, v118
	v_mov_b32_e32 v118, v108
	v_mov_b32_e32 v108, v110
	v_or_b32_e32 v110, 16, v148
	v_mad_i64_i32 v[110:111], s[0:1], v110, s3, v[124:125]
	v_lshl_add_u64 v[110:111], v[110:111], 0, s[26:27]
	v_lshl_add_u64 v[110:111], v[110:111], 0, s[76:77]
	v_lshl_add_u64 v[110:111], v[110:111], 0, v[176:177]
	v_fmamk_f32 v128, v182, 0x3a800000, v224
	v_mul_f32_e32 v129, 0x4b800000, v128
	v_cmp_gt_f32_e32 vcc, s33, v128
	s_nop 1
	v_cndmask_b32_e32 v128, v128, v129, vcc
	v_rsq_f32_e32 v128, v128
	s_nop 0
	v_mul_f32_e32 v129, 0x45800000, v128
	v_cndmask_b32_e32 v128, v128, v129, vcc
	v_pk_fma_f32 v[106:107], v[106:107], v[128:129], v[82:83] op_sel_hi:[1,0,1]
	v_pk_fma_f32 v[126:127], v[126:127], v[128:129], v[120:121] op_sel_hi:[1,0,1]
; __device__ __forceinline__ float sigm(float v) { return __builtin_amdgcn_rcpf(1.f + __builtin_amdgcn_exp2f(-1.4426950408889634f * v)); }
; __device__ __forceinline__ unsigned pkbf(float lo, float hi) { return pg8::cvt_pk_bf16(lo, hi); }
;     __device__ __forceinline__ void operator()(const f32x4 (&acc)[2][2][4][2], const Unit& u, int wr, int wc, int fr, int fq) const {
;     ...
;                 const int row = pm * 256 + ai * 128 + wr * 64 + m * 16 + fr;
;                 const float rinv = rsqrtf(rowsq[row] * (1.f / DM) + EPSN);
;                 f32x4 o[2];
; #pragma unroll
;                 for (int n = 0; n < 2; ++n) {
;                     const f32x4 g = acc[ai][0][m][n] * rinv + bv[0][n], up = acc[ai][1][m][n] * rinv + bv[1][n];
; #pragma unroll
;                     for (int j = 0; j < 4; ++j) o[n][j] = g[j] * sigm(g[j]) * up[j];
;                 }
;                 u32x4 w; w.x = pkbf(o[0][0], o[0][1]); w.y = pkbf(o[0][2], o[0][3]); w.z = pkbf(o[1][0], o[1][1]); w.w = pkbf(o[1][2], o[1][3]);
;                 *(u32x4*)(act + (size_t)row * FFH + pn * 128 + wc * 32 + 8 * fq) = w;
	v_pk_fma_f32 v[112:113], v[112:113], v[128:129], v[84:85] op_sel_hi:[1,0,1]
	v_pk_fma_f32 v[116:117], v[116:117], v[128:129], v[122:123] op_sel_hi:[1,0,1]
	v_pk_fma_f32 v[114:115], v[114:115], v[128:129], v[86:87] op_sel_hi:[1,0,1]
	v_pk_fma_f32 v[118:119], v[118:119], v[128:129], v[132:133] op_sel_hi:[1,0,1]
	v_pk_fma_f32 v[104:105], v[104:105], v[128:129], v[80:81] op_sel_hi:[1,0,1]
	v_pk_fma_f32 v[108:109], v[108:109], v[128:129], v[134:135] op_sel_hi:[1,0,1]
	v_mul_f32_e32 v158, 0xbfb8aa3b, v107
	v_mul_f32_e32 v128, 0xbfb8aa3b, v127
	v_mul_f32_e32 v129, 0xbfb8aa3b, v113
	v_mul_f32_e32 v130, 0xbfb8aa3b, v117
	v_mul_f32_e32 v131, 0xbfb8aa3b, v115
	v_mul_f32_e32 v149, 0xbfb8aa3b, v119
	v_mul_f32_e32 v156, 0xbfb8aa3b, v105
	v_mul_f32_e32 v157, 0xbfb8aa3b, v109
	v_exp_f32_e32 v158, v158
	v_exp_f32_e32 v128, v128
	v_exp_f32_e32 v129, v129
	v_exp_f32_e32 v130, v130
	v_exp_f32_e32 v131, v131
	v_exp_f32_e32 v149, v149
	v_exp_f32_e32 v156, v156
	v_exp_f32_e32 v157, v157
	v_add_f32_e32 v158, 1.0, v158
	v_add_f32_e32 v128, 1.0, v128
	v_add_f32_e32 v129, 1.0, v129
	v_add_f32_e32 v130, 1.0, v130
	v_add_f32_e32 v131, 1.0, v131
	v_add_f32_e32 v149, 1.0, v149
	v_add_f32_e32 v156, 1.0, v156
	v_add_f32_e32 v157, 1.0, v157
	v_rcp_f32_e32 v158, v158
	v_rcp_f32_e32 v128, v128
	v_rcp_f32_e32 v129, v129
	v_rcp_f32_e32 v130, v130
	v_rcp_f32_e32 v131, v131
	v_rcp_f32_e32 v149, v149
	v_rcp_f32_e32 v156, v156
	v_rcp_f32_e32 v157, v157
	v_mul_f32_e32 v107, v107, v158
	v_mul_f32_e32 v127, v127, v128
	v_mul_f32_e32 v113, v113, v129
	v_mul_f32_e32 v117, v117, v130
	v_mul_f32_e32 v115, v115, v131
	v_mul_f32_e32 v119, v119, v149
	v_mul_f32_e32 v105, v105, v156
	v_mul_f32_e32 v109, v109, v157
	v_mul_f32_e32 v107, v106, v107
	v_mul_f32_e32 v126, v126, v127
	v_mul_f32_e32 v112, v112, v113
	v_mul_f32_e32 v113, v116, v117
	v_mul_f32_e32 v114, v114, v115
	v_mul_f32_e32 v115, v118, v119
	v_mul_f32_e32 v116, v104, v105
	v_mul_f32_e32 v108, v108, v109
	v_cvt_pk_bf16_f32 v104, v126, v112
	v_cvt_pk_bf16_f32 v105, v113, v114
	v_cvt_pk_bf16_f32 v106, v115, v116
	v_cvt_pk_bf16_f32 v107, v108, v107
	global_store_dwordx4 v[110:111], v[104:107], off
	s_nop 0
	s_nop 0
	v_mov_b32_e32 v105, v96
	v_mov_b32_e32 v96, v101
	v_mov_b32_e32 v101, v98
	v_mov_b32_e32 v98, v103
	v_mov_b32_e32 v103, v88
	v_mov_b32_e32 v88, v93
	v_mov_b32_e32 v93, v90
	v_mov_b32_e32 v90, v95
	v_mov_b32_e32 v104, v100
	v_mov_b32_e32 v100, v102
	v_mov_b32_e32 v102, v92
	v_mov_b32_e32 v92, v94
	v_or_b32_e32 v94, 32, v148
	v_mad_i64_i32 v[94:95], s[0:1], v94, s3, v[124:125]
	v_lshl_add_u64 v[94:95], v[94:95], 0, s[26:27]
	v_lshl_add_u64 v[94:95], v[94:95], 0, s[76:77]
	v_lshl_add_u64 v[94:95], v[94:95], 0, v[176:177]
	v_fmamk_f32 v106, v183, 0x3a800000, v224
	v_mul_f32_e32 v107, 0x4b800000, v106
	v_cmp_gt_f32_e32 vcc, s33, v106
	s_nop 1
	v_cndmask_b32_e32 v106, v106, v107, vcc
	v_rsq_f32_e32 v106, v106
	s_nop 0
	v_mul_f32_e32 v107, 0x45800000, v106
	v_cndmask_b32_e32 v106, v106, v107, vcc
	v_pk_fma_f32 v[90:91], v[90:91], v[106:107], v[82:83] op_sel_hi:[1,0,1]
	v_pk_fma_f32 v[104:105], v[104:105], v[106:107], v[120:121] op_sel_hi:[1,0,1]
	v_pk_fma_f32 v[96:97], v[96:97], v[106:107], v[84:85] op_sel_hi:[1,0,1]
	v_pk_fma_f32 v[100:101], v[100:101], v[106:107], v[122:123] op_sel_hi:[1,0,1]
	v_pk_fma_f32 v[98:99], v[98:99], v[106:107], v[86:87] op_sel_hi:[1,0,1]
	v_pk_fma_f32 v[102:103], v[102:103], v[106:107], v[132:133] op_sel_hi:[1,0,1]
	v_pk_fma_f32 v[88:89], v[88:89], v[106:107], v[80:81] op_sel_hi:[1,0,1]
	v_pk_fma_f32 v[92:93], v[92:93], v[106:107], v[134:135] op_sel_hi:[1,0,1]
	v_mul_f32_e32 v113, 0xbfb8aa3b, v91
	v_mul_f32_e32 v106, 0xbfb8aa3b, v105
	v_mul_f32_e32 v107, 0xbfb8aa3b, v97
	v_mul_f32_e32 v108, 0xbfb8aa3b, v101
	v_mul_f32_e32 v109, 0xbfb8aa3b, v99
	v_mul_f32_e32 v110, 0xbfb8aa3b, v103
	v_mul_f32_e32 v111, 0xbfb8aa3b, v89
	v_mul_f32_e32 v112, 0xbfb8aa3b, v93
	v_exp_f32_e32 v113, v113
	v_exp_f32_e32 v106, v106
	v_exp_f32_e32 v107, v107
	v_exp_f32_e32 v108, v108
	v_exp_f32_e32 v109, v109
	v_exp_f32_e32 v110, v110
	v_exp_f32_e32 v111, v111
	v_exp_f32_e32 v112, v112
	v_add_f32_e32 v113, 1.0, v113
	v_add_f32_e32 v106, 1.0, v106
	v_add_f32_e32 v107, 1.0, v107
	v_add_f32_e32 v108, 1.0, v108
	v_add_f32_e32 v109, 1.0, v109
	v_add_f32_e32 v110, 1.0, v110
	v_add_f32_e32 v111, 1.0, v111
	v_add_f32_e32 v112, 1.0, v112
	v_rcp_f32_e32 v113, v113
	v_rcp_f32_e32 v106, v106
	v_rcp_f32_e32 v107, v107
	v_rcp_f32_e32 v108, v108
	v_rcp_f32_e32 v109, v109
	v_rcp_f32_e32 v110, v110
	v_rcp_f32_e32 v111, v111
	v_rcp_f32_e32 v112, v112
	v_mul_f32_e32 v91, v91, v113
	v_mul_f32_e32 v105, v105, v106
	v_mul_f32_e32 v97, v97, v107
	v_mul_f32_e32 v101, v101, v108
	v_mul_f32_e32 v99, v99, v109
	v_mul_f32_e32 v103, v103, v110
	v_mul_f32_e32 v89, v89, v111
	v_mul_f32_e32 v93, v93, v112
	v_mul_f32_e32 v91, v90, v91
	v_mul_f32_e32 v104, v104, v105
	v_mul_f32_e32 v96, v96, v97
	v_mul_f32_e32 v97, v100, v101
	v_mul_f32_e32 v98, v98, v99
	v_mul_f32_e32 v99, v102, v103
	v_mul_f32_e32 v100, v88, v89
	v_mul_f32_e32 v92, v92, v93
	v_cvt_pk_bf16_f32 v88, v104, v96
	v_cvt_pk_bf16_f32 v89, v97, v98
	v_cvt_pk_bf16_f32 v90, v99, v100
	v_cvt_pk_bf16_f32 v91, v92, v91
	global_store_dwordx4 v[94:95], v[88:91], off
	s_nop 0
	s_nop 0
	v_mov_b32_e32 v89, v72
	v_mov_b32_e32 v72, v77
	v_mov_b32_e32 v77, v74
	v_mov_b32_e32 v74, v79
	v_mov_b32_e32 v79, v64
	v_mov_b32_e32 v64, v69
	v_mov_b32_e32 v69, v66
	v_mov_b32_e32 v66, v71
	v_mov_b32_e32 v88, v76
	v_mov_b32_e32 v76, v78
	v_mov_b32_e32 v78, v68
	v_mov_b32_e32 v68, v70
	v_or_b32_e32 v70, 48, v148
	v_mad_i64_i32 v[70:71], s[0:1], v70, s3, v[124:125]
	v_lshl_add_u64 v[70:71], v[70:71], 0, s[26:27]
; __device__ __forceinline__ float sigm(float v) { return __builtin_amdgcn_rcpf(1.f + __builtin_amdgcn_exp2f(-1.4426950408889634f * v)); }
; __device__ __forceinline__ unsigned pkbf(float lo, float hi) { return pg8::cvt_pk_bf16(lo, hi); }
;     __device__ __forceinline__ void operator()(const f32x4 (&acc)[2][2][4][2], const Unit& u, int wr, int wc, int fr, int fq) const {
;     ...
;                 const int row = pm * 256 + ai * 128 + wr * 64 + m * 16 + fr;
;                 const float rinv = rsqrtf(rowsq[row] * (1.f / DM) + EPSN);
;                 f32x4 o[2];
; #pragma unroll
;                 for (int n = 0; n < 2; ++n) {
;                     const f32x4 g = acc[ai][0][m][n] * rinv + bv[0][n], up = acc[ai][1][m][n] * rinv + bv[1][n];
; #pragma unroll
;                     for (int j = 0; j < 4; ++j) o[n][j] = g[j] * sigm(g[j]) * up[j];
;                 }
;                 u32x4 w; w.x = pkbf(o[0][0], o[0][1]); w.y = pkbf(o[0][2], o[0][3]); w.z = pkbf(o[1][0], o[1][1]); w.w = pkbf(o[1][2], o[1][3]);
;                 *(u32x4*)(act + (size_t)row * FFH + pn * 128 + wc * 32 + 8 * fq) = w;
	v_lshl_add_u64 v[70:71], v[70:71], 0, s[76:77]
	v_lshl_add_u64 v[70:71], v[70:71], 0, v[176:177]
	v_fmamk_f32 v90, v184, 0x3a800000, v224
	v_mul_f32_e32 v91, 0x4b800000, v90
	v_cmp_gt_f32_e32 vcc, s33, v90
	s_nop 1
	v_cndmask_b32_e32 v90, v90, v91, vcc
	v_rsq_f32_e32 v90, v90
	s_nop 0
	v_mul_f32_e32 v91, 0x45800000, v90
	v_cndmask_b32_e32 v90, v90, v91, vcc
	v_pk_fma_f32 v[66:67], v[66:67], v[90:91], v[82:83] op_sel_hi:[1,0,1]
	v_pk_fma_f32 v[88:89], v[88:89], v[90:91], v[120:121] op_sel_hi:[1,0,1]
	v_pk_fma_f32 v[72:73], v[72:73], v[90:91], v[84:85] op_sel_hi:[1,0,1]
	v_pk_fma_f32 v[76:77], v[76:77], v[90:91], v[122:123] op_sel_hi:[1,0,1]
	v_pk_fma_f32 v[74:75], v[74:75], v[90:91], v[86:87] op_sel_hi:[1,0,1]
	v_pk_fma_f32 v[78:79], v[78:79], v[90:91], v[132:133] op_sel_hi:[1,0,1]
	v_pk_fma_f32 v[64:65], v[64:65], v[90:91], v[80:81] op_sel_hi:[1,0,1]
	v_pk_fma_f32 v[68:69], v[68:69], v[90:91], v[134:135] op_sel_hi:[1,0,1]
	v_mul_f32_e32 v97, 0xbfb8aa3b, v67
	v_mul_f32_e32 v90, 0xbfb8aa3b, v89
	v_mul_f32_e32 v91, 0xbfb8aa3b, v73
	v_mul_f32_e32 v92, 0xbfb8aa3b, v77
	v_mul_f32_e32 v93, 0xbfb8aa3b, v75
	v_mul_f32_e32 v94, 0xbfb8aa3b, v79
	v_mul_f32_e32 v95, 0xbfb8aa3b, v65
	v_mul_f32_e32 v96, 0xbfb8aa3b, v69
	v_exp_f32_e32 v97, v97
	v_exp_f32_e32 v90, v90
	v_exp_f32_e32 v91, v91
	v_exp_f32_e32 v92, v92
	v_exp_f32_e32 v93, v93
	v_exp_f32_e32 v94, v94
	v_exp_f32_e32 v95, v95
	v_exp_f32_e32 v96, v96
	v_add_f32_e32 v97, 1.0, v97
	v_add_f32_e32 v90, 1.0, v90
	v_add_f32_e32 v91, 1.0, v91
	v_add_f32_e32 v92, 1.0, v92
	v_add_f32_e32 v93, 1.0, v93
	v_add_f32_e32 v94, 1.0, v94
	v_add_f32_e32 v95, 1.0, v95
	v_add_f32_e32 v96, 1.0, v96
	v_rcp_f32_e32 v97, v97
	v_rcp_f32_e32 v90, v90
	v_rcp_f32_e32 v91, v91
	v_rcp_f32_e32 v92, v92
	v_rcp_f32_e32 v93, v93
	v_rcp_f32_e32 v94, v94
	v_rcp_f32_e32 v95, v95
	v_rcp_f32_e32 v96, v96
	v_mul_f32_e32 v67, v67, v97
	v_mul_f32_e32 v89, v89, v90
	v_mul_f32_e32 v73, v73, v91
	v_mul_f32_e32 v77, v77, v92
	v_mul_f32_e32 v75, v75, v93
	v_mul_f32_e32 v79, v79, v94
	v_mul_f32_e32 v65, v65, v95
	v_mul_f32_e32 v69, v69, v96
	v_mul_f32_e32 v67, v66, v67
	v_mul_f32_e32 v88, v88, v89
	v_mul_f32_e32 v72, v72, v73
	v_mul_f32_e32 v73, v76, v77
	v_mul_f32_e32 v74, v74, v75
	v_mul_f32_e32 v75, v78, v79
	v_mul_f32_e32 v76, v64, v65
	v_mul_f32_e32 v68, v68, v69
	v_cvt_pk_bf16_f32 v64, v88, v72
	v_cvt_pk_bf16_f32 v65, v73, v74
	v_cvt_pk_bf16_f32 v66, v75, v76
	v_cvt_pk_bf16_f32 v67, v68, v67
	global_store_dwordx4 v[70:71], v[64:67], off
	s_nop 0
	s_nop 0
	v_mov_b32_e32 v65, v56
	v_mov_b32_e32 v56, v61
	v_mov_b32_e32 v61, v58
	v_mov_b32_e32 v58, v63
	v_mov_b32_e32 v63, v48
	v_mov_b32_e32 v48, v53
	v_mov_b32_e32 v53, v50
	v_mov_b32_e32 v50, v55
	v_mov_b32_e32 v64, v60
	v_mov_b32_e32 v60, v62
	v_mov_b32_e32 v62, v52
	v_mov_b32_e32 v52, v54
	v_add_u32_e32 v54, 0x80, v148
	v_mad_i64_i32 v[54:55], s[0:1], v54, s3, v[124:125]
	v_lshl_add_u64 v[54:55], v[54:55], 0, s[26:27]
	v_lshl_add_u64 v[54:55], v[54:55], 0, s[76:77]
	v_lshl_add_u64 v[54:55], v[54:55], 0, v[176:177]
	v_fmamk_f32 v66, v185, 0x3a800000, v224
	v_mul_f32_e32 v67, 0x4b800000, v66
	v_cmp_gt_f32_e32 vcc, s33, v66
	s_nop 1
	v_cndmask_b32_e32 v66, v66, v67, vcc
	v_rsq_f32_e32 v66, v66
	s_nop 0
	v_mul_f32_e32 v67, 0x45800000, v66
	v_cndmask_b32_e32 v66, v66, v67, vcc
	v_pk_fma_f32 v[50:51], v[50:51], v[66:67], v[82:83] op_sel_hi:[1,0,1]
	v_pk_fma_f32 v[64:65], v[64:65], v[66:67], v[120:121] op_sel_hi:[1,0,1]
	v_pk_fma_f32 v[56:57], v[56:57], v[66:67], v[84:85] op_sel_hi:[1,0,1]
	v_pk_fma_f32 v[60:61], v[60:61], v[66:67], v[122:123] op_sel_hi:[1,0,1]
	v_pk_fma_f32 v[58:59], v[58:59], v[66:67], v[86:87] op_sel_hi:[1,0,1]
	v_pk_fma_f32 v[62:63], v[62:63], v[66:67], v[132:133] op_sel_hi:[1,0,1]
	v_pk_fma_f32 v[48:49], v[48:49], v[66:67], v[80:81] op_sel_hi:[1,0,1]
	v_pk_fma_f32 v[52:53], v[52:53], v[66:67], v[134:135] op_sel_hi:[1,0,1]
	v_mul_f32_e32 v73, 0xbfb8aa3b, v51
	v_mul_f32_e32 v66, 0xbfb8aa3b, v65
	v_mul_f32_e32 v67, 0xbfb8aa3b, v57
	v_mul_f32_e32 v68, 0xbfb8aa3b, v61
	v_mul_f32_e32 v69, 0xbfb8aa3b, v59
	v_mul_f32_e32 v70, 0xbfb8aa3b, v63
	v_mul_f32_e32 v71, 0xbfb8aa3b, v49
	v_mul_f32_e32 v72, 0xbfb8aa3b, v53
	v_exp_f32_e32 v73, v73
	v_exp_f32_e32 v66, v66
	v_exp_f32_e32 v67, v67
	v_exp_f32_e32 v68, v68
	v_exp_f32_e32 v69, v69
	v_exp_f32_e32 v70, v70
	v_exp_f32_e32 v71, v71
	v_exp_f32_e32 v72, v72
	v_add_f32_e32 v73, 1.0, v73
	v_add_f32_e32 v66, 1.0, v66
	v_add_f32_e32 v67, 1.0, v67
	v_add_f32_e32 v68, 1.0, v68
	v_add_f32_e32 v69, 1.0, v69
	v_add_f32_e32 v70, 1.0, v70
	v_add_f32_e32 v71, 1.0, v71
	v_add_f32_e32 v72, 1.0, v72
	v_rcp_f32_e32 v73, v73
	v_rcp_f32_e32 v66, v66
	v_rcp_f32_e32 v67, v67
	v_rcp_f32_e32 v68, v68
	v_rcp_f32_e32 v69, v69
	v_rcp_f32_e32 v70, v70
	v_rcp_f32_e32 v71, v71
	v_rcp_f32_e32 v72, v72
	v_mul_f32_e32 v51, v51, v73
	v_mul_f32_e32 v65, v65, v66
	v_mul_f32_e32 v57, v57, v67
	v_mul_f32_e32 v61, v61, v68
	v_mul_f32_e32 v59, v59, v69
	v_mul_f32_e32 v63, v63, v70
	v_mul_f32_e32 v49, v49, v71
	v_mul_f32_e32 v53, v53, v72
	v_mul_f32_e32 v51, v50, v51
	v_mul_f32_e32 v64, v64, v65
	v_mul_f32_e32 v56, v56, v57
	v_mul_f32_e32 v57, v60, v61
	v_mul_f32_e32 v58, v58, v59
	v_mul_f32_e32 v59, v62, v63
	v_mul_f32_e32 v60, v48, v49
	v_mul_f32_e32 v52, v52, v53
	v_cvt_pk_bf16_f32 v48, v64, v56
	v_cvt_pk_bf16_f32 v49, v57, v58
	v_cvt_pk_bf16_f32 v50, v59, v60
	v_cvt_pk_bf16_f32 v51, v52, v51
	global_store_dwordx4 v[54:55], v[48:51], off
	s_nop 0
	s_nop 0
	v_mov_b32_e32 v49, v40
	v_mov_b32_e32 v40, v45
	v_mov_b32_e32 v45, v42
	v_mov_b32_e32 v42, v47
	v_mov_b32_e32 v47, v32
	v_mov_b32_e32 v32, v37
	v_mov_b32_e32 v37, v34
	v_mov_b32_e32 v34, v39
	v_mov_b32_e32 v48, v44
; __device__ __forceinline__ float sigm(float v) { return __builtin_amdgcn_rcpf(1.f + __builtin_amdgcn_exp2f(-1.4426950408889634f * v)); }
; __device__ __forceinline__ unsigned pkbf(float lo, float hi) { return pg8::cvt_pk_bf16(lo, hi); }
;     __device__ __forceinline__ void operator()(const f32x4 (&acc)[2][2][4][2], const Unit& u, int wr, int wc, int fr, int fq) const {
;     ...
;                 const int row = pm * 256 + ai * 128 + wr * 64 + m * 16 + fr;
;                 const float rinv = rsqrtf(rowsq[row] * (1.f / DM) + EPSN);
;                 f32x4 o[2];
; #pragma unroll
;                 for (int n = 0; n < 2; ++n) {
;                     const f32x4 g = acc[ai][0][m][n] * rinv + bv[0][n], up = acc[ai][1][m][n] * rinv + bv[1][n];
; #pragma unroll
;                     for (int j = 0; j < 4; ++j) o[n][j] = g[j] * sigm(g[j]) * up[j];
;                 }
;                 u32x4 w; w.x = pkbf(o[0][0], o[0][1]); w.y = pkbf(o[0][2], o[0][3]); w.z = pkbf(o[1][0], o[1][1]); w.w = pkbf(o[1][2], o[1][3]);
;                 *(u32x4*)(act + (size_t)row * FFH + pn * 128 + wc * 32 + 8 * fq) = w;
	v_mov_b32_e32 v44, v46
	v_mov_b32_e32 v46, v36
	v_mov_b32_e32 v36, v38
	v_add_u32_e32 v38, 0x90, v148
	v_mad_i64_i32 v[38:39], s[0:1], v38, s3, v[124:125]
	v_lshl_add_u64 v[38:39], v[38:39], 0, s[26:27]
	v_lshl_add_u64 v[38:39], v[38:39], 0, s[76:77]
	v_lshl_add_u64 v[38:39], v[38:39], 0, v[176:177]
	v_fmamk_f32 v50, v186, 0x3a800000, v224
	v_mul_f32_e32 v51, 0x4b800000, v50
	v_cmp_gt_f32_e32 vcc, s33, v50
	s_nop 1
	v_cndmask_b32_e32 v50, v50, v51, vcc
	v_rsq_f32_e32 v50, v50
	s_nop 0
	v_mul_f32_e32 v51, 0x45800000, v50
	v_cndmask_b32_e32 v50, v50, v51, vcc
	v_pk_fma_f32 v[34:35], v[34:35], v[50:51], v[82:83] op_sel_hi:[1,0,1]
	v_pk_fma_f32 v[48:49], v[48:49], v[50:51], v[120:121] op_sel_hi:[1,0,1]
	v_pk_fma_f32 v[40:41], v[40:41], v[50:51], v[84:85] op_sel_hi:[1,0,1]
	v_pk_fma_f32 v[44:45], v[44:45], v[50:51], v[122:123] op_sel_hi:[1,0,1]
	v_pk_fma_f32 v[42:43], v[42:43], v[50:51], v[86:87] op_sel_hi:[1,0,1]
	v_pk_fma_f32 v[46:47], v[46:47], v[50:51], v[132:133] op_sel_hi:[1,0,1]
	v_pk_fma_f32 v[32:33], v[32:33], v[50:51], v[80:81] op_sel_hi:[1,0,1]
	v_pk_fma_f32 v[36:37], v[36:37], v[50:51], v[134:135] op_sel_hi:[1,0,1]
	v_mul_f32_e32 v57, 0xbfb8aa3b, v35
	v_mul_f32_e32 v50, 0xbfb8aa3b, v49
	v_mul_f32_e32 v51, 0xbfb8aa3b, v41
	v_mul_f32_e32 v52, 0xbfb8aa3b, v45
	v_mul_f32_e32 v53, 0xbfb8aa3b, v43
	v_mul_f32_e32 v54, 0xbfb8aa3b, v47
	v_mul_f32_e32 v55, 0xbfb8aa3b, v33
	v_mul_f32_e32 v56, 0xbfb8aa3b, v37
	v_exp_f32_e32 v57, v57
	v_exp_f32_e32 v50, v50
	v_exp_f32_e32 v51, v51
	v_exp_f32_e32 v52, v52
	v_exp_f32_e32 v53, v53
	v_exp_f32_e32 v54, v54
	v_exp_f32_e32 v55, v55
	v_exp_f32_e32 v56, v56
	v_add_f32_e32 v57, 1.0, v57
	v_add_f32_e32 v50, 1.0, v50
	v_add_f32_e32 v51, 1.0, v51
	v_add_f32_e32 v52, 1.0, v52
	v_add_f32_e32 v53, 1.0, v53
	v_add_f32_e32 v54, 1.0, v54
	v_add_f32_e32 v55, 1.0, v55
	v_add_f32_e32 v56, 1.0, v56
	v_rcp_f32_e32 v57, v57
	v_rcp_f32_e32 v50, v50
	v_rcp_f32_e32 v51, v51
	v_rcp_f32_e32 v52, v52
	v_rcp_f32_e32 v53, v53
	v_rcp_f32_e32 v54, v54
	v_rcp_f32_e32 v55, v55
	v_rcp_f32_e32 v56, v56
	v_mul_f32_e32 v35, v35, v57
	v_mul_f32_e32 v49, v49, v50
	v_mul_f32_e32 v41, v41, v51
	v_mul_f32_e32 v45, v45, v52
	v_mul_f32_e32 v43, v43, v53
	v_mul_f32_e32 v47, v47, v54
	v_mul_f32_e32 v33, v33, v55
	v_mul_f32_e32 v37, v37, v56
	v_mul_f32_e32 v35, v34, v35
	v_mul_f32_e32 v48, v48, v49
	v_mul_f32_e32 v40, v40, v41
	v_mul_f32_e32 v41, v44, v45
	v_mul_f32_e32 v42, v42, v43
	v_mul_f32_e32 v43, v46, v47
	v_mul_f32_e32 v44, v32, v33
	v_mul_f32_e32 v36, v36, v37
	v_cvt_pk_bf16_f32 v32, v48, v40
	v_cvt_pk_bf16_f32 v33, v41, v42
	v_cvt_pk_bf16_f32 v34, v43, v44
	v_cvt_pk_bf16_f32 v35, v36, v35
	global_store_dwordx4 v[38:39], v[32:35], off
	s_nop 0
	s_nop 0
	v_mov_b32_e32 v33, v24
	v_mov_b32_e32 v24, v29
	v_mov_b32_e32 v29, v26
	v_mov_b32_e32 v26, v31
	v_mov_b32_e32 v31, v16
	v_mov_b32_e32 v16, v21
	v_mov_b32_e32 v21, v18
	v_mov_b32_e32 v18, v23
	v_mov_b32_e32 v32, v28
	v_mov_b32_e32 v28, v30
	v_mov_b32_e32 v30, v20
	v_mov_b32_e32 v20, v22
	v_add_u32_e32 v22, 0xa0, v148
	v_mad_i64_i32 v[22:23], s[0:1], v22, s3, v[124:125]
	v_lshl_add_u64 v[22:23], v[22:23], 0, s[26:27]
	v_lshl_add_u64 v[22:23], v[22:23], 0, s[76:77]
	v_lshl_add_u64 v[22:23], v[22:23], 0, v[176:177]
	v_fmamk_f32 v34, v187, 0x3a800000, v224
	v_mul_f32_e32 v35, 0x4b800000, v34
	v_cmp_gt_f32_e32 vcc, s33, v34
	s_nop 1
	v_cndmask_b32_e32 v34, v34, v35, vcc
	v_rsq_f32_e32 v34, v34
	s_nop 0
	v_mul_f32_e32 v35, 0x45800000, v34
	v_cndmask_b32_e32 v34, v34, v35, vcc
	v_pk_fma_f32 v[18:19], v[18:19], v[34:35], v[82:83] op_sel_hi:[1,0,1]
	v_pk_fma_f32 v[32:33], v[32:33], v[34:35], v[120:121] op_sel_hi:[1,0,1]
	v_pk_fma_f32 v[24:25], v[24:25], v[34:35], v[84:85] op_sel_hi:[1,0,1]
	v_pk_fma_f32 v[28:29], v[28:29], v[34:35], v[122:123] op_sel_hi:[1,0,1]
	v_pk_fma_f32 v[26:27], v[26:27], v[34:35], v[86:87] op_sel_hi:[1,0,1]
	v_pk_fma_f32 v[30:31], v[30:31], v[34:35], v[132:133] op_sel_hi:[1,0,1]
	v_pk_fma_f32 v[16:17], v[16:17], v[34:35], v[80:81] op_sel_hi:[1,0,1]
	v_pk_fma_f32 v[20:21], v[20:21], v[34:35], v[134:135] op_sel_hi:[1,0,1]
	v_mul_f32_e32 v41, 0xbfb8aa3b, v19
	v_mul_f32_e32 v34, 0xbfb8aa3b, v33
	v_mul_f32_e32 v35, 0xbfb8aa3b, v25
	v_mul_f32_e32 v36, 0xbfb8aa3b, v29
	v_mul_f32_e32 v37, 0xbfb8aa3b, v27
	v_mul_f32_e32 v38, 0xbfb8aa3b, v31
	v_mul_f32_e32 v39, 0xbfb8aa3b, v17
; __device__ __forceinline__ float sigm(float v) { return __builtin_amdgcn_rcpf(1.f + __builtin_amdgcn_exp2f(-1.4426950408889634f * v)); }
; __device__ __forceinline__ unsigned pkbf(float lo, float hi) { return pg8::cvt_pk_bf16(lo, hi); }
;     __device__ __forceinline__ void operator()(const f32x4 (&acc)[2][2][4][2], const Unit& u, int wr, int wc, int fr, int fq) const {
;     ...
;                 const int row = pm * 256 + ai * 128 + wr * 64 + m * 16 + fr;
;                 const float rinv = rsqrtf(rowsq[row] * (1.f / DM) + EPSN);
;                 f32x4 o[2];
; #pragma unroll
;                 for (int n = 0; n < 2; ++n) {
;                     const f32x4 g = acc[ai][0][m][n] * rinv + bv[0][n], up = acc[ai][1][m][n] * rinv + bv[1][n];
; #pragma unroll
;                     for (int j = 0; j < 4; ++j) o[n][j] = g[j] * sigm(g[j]) * up[j];
;                 }
;                 u32x4 w; w.x = pkbf(o[0][0], o[0][1]); w.y = pkbf(o[0][2], o[0][3]); w.z = pkbf(o[1][0], o[1][1]); w.w = pkbf(o[1][2], o[1][3]);
;                 *(u32x4*)(act + (size_t)row * FFH + pn * 128 + wc * 32 + 8 * fq) = w;
	v_mul_f32_e32 v40, 0xbfb8aa3b, v21
	v_exp_f32_e32 v41, v41
	v_exp_f32_e32 v34, v34
	v_exp_f32_e32 v35, v35
	v_exp_f32_e32 v36, v36
	v_exp_f32_e32 v37, v37
	v_exp_f32_e32 v38, v38
	v_exp_f32_e32 v39, v39
	v_exp_f32_e32 v40, v40
	v_add_f32_e32 v41, 1.0, v41
	v_add_f32_e32 v34, 1.0, v34
	v_add_f32_e32 v35, 1.0, v35
	v_add_f32_e32 v36, 1.0, v36
	v_add_f32_e32 v37, 1.0, v37
	v_add_f32_e32 v38, 1.0, v38
	v_add_f32_e32 v39, 1.0, v39
	v_add_f32_e32 v40, 1.0, v40
	v_rcp_f32_e32 v41, v41
	v_rcp_f32_e32 v34, v34
	v_rcp_f32_e32 v35, v35
	v_rcp_f32_e32 v36, v36
	v_rcp_f32_e32 v37, v37
	v_rcp_f32_e32 v38, v38
	v_rcp_f32_e32 v39, v39
	v_rcp_f32_e32 v40, v40
	v_mul_f32_e32 v19, v19, v41
	v_mul_f32_e32 v33, v33, v34
	v_mul_f32_e32 v25, v25, v35
	v_mul_f32_e32 v29, v29, v36
	v_mul_f32_e32 v27, v27, v37
	v_mul_f32_e32 v31, v31, v38
	v_mul_f32_e32 v17, v17, v39
	v_mul_f32_e32 v21, v21, v40
	v_mul_f32_e32 v19, v18, v19
	v_mul_f32_e32 v32, v32, v33
	v_mul_f32_e32 v24, v24, v25
	v_mul_f32_e32 v25, v28, v29
	v_mul_f32_e32 v26, v26, v27
	v_mul_f32_e32 v27, v30, v31
	v_mul_f32_e32 v28, v16, v17
	v_mul_f32_e32 v20, v20, v21
	v_cvt_pk_bf16_f32 v16, v32, v24
	v_cvt_pk_bf16_f32 v17, v25, v26
	v_cvt_pk_bf16_f32 v18, v27, v28
	v_cvt_pk_bf16_f32 v19, v20, v19
	global_store_dwordx4 v[22:23], v[16:19], off
	s_nop 0
	s_andn2_b64 vcc, exec, s[4:5]
	v_mov_b32_e32 v16, v12
	v_mov_b32_e32 v12, v14
	v_mov_b32_e32 v14, v4
	v_mov_b32_e32 v4, v6
	v_add_u32_e32 v6, 0xb0, v148
	v_mov_b32_e32 v17, v8
	v_mov_b32_e32 v8, v13
	v_mov_b32_e32 v13, v10
	v_mov_b32_e32 v10, v15
	v_mov_b32_e32 v15, v0
	v_mov_b32_e32 v0, v5
	v_mov_b32_e32 v5, v2
	v_mov_b32_e32 v2, v7
	v_mad_i64_i32 v[6:7], s[0:1], v6, s3, v[124:125]
	v_lshl_add_u64 v[6:7], v[6:7], 0, s[26:27]
	v_lshl_add_u64 v[6:7], v[6:7], 0, s[76:77]
	v_lshl_add_u64 v[6:7], v[6:7], 0, v[176:177]
	v_fmamk_f32 v18, v188, 0x3a800000, v224
	v_mul_f32_e32 v19, 0x4b800000, v18
	v_cmp_gt_f32_e64 s[0:1], s33, v18
	s_nop 1
	v_cndmask_b32_e64 v18, v18, v19, s[0:1]
	v_rsq_f32_e32 v18, v18
	s_nop 0
	v_mul_f32_e32 v19, 0x45800000, v18
	v_cndmask_b32_e64 v18, v18, v19, s[0:1]
	v_pk_fma_f32 v[2:3], v[2:3], v[18:19], v[82:83] op_sel_hi:[1,0,1]
	v_pk_fma_f32 v[16:17], v[16:17], v[18:19], v[120:121] op_sel_hi:[1,0,1]
	v_pk_fma_f32 v[8:9], v[8:9], v[18:19], v[84:85] op_sel_hi:[1,0,1]
	v_pk_fma_f32 v[12:13], v[12:13], v[18:19], v[122:123] op_sel_hi:[1,0,1]
	v_pk_fma_f32 v[10:11], v[10:11], v[18:19], v[86:87] op_sel_hi:[1,0,1]
	v_pk_fma_f32 v[14:15], v[14:15], v[18:19], v[132:133] op_sel_hi:[1,0,1]
	v_pk_fma_f32 v[0:1], v[0:1], v[18:19], v[80:81] op_sel_hi:[1,0,1]
	v_pk_fma_f32 v[4:5], v[4:5], v[18:19], v[134:135] op_sel_hi:[1,0,1]
	v_mul_f32_e32 v25, 0xbfb8aa3b, v3
	v_mul_f32_e32 v18, 0xbfb8aa3b, v17
	v_mul_f32_e32 v19, 0xbfb8aa3b, v9
	v_mul_f32_e32 v20, 0xbfb8aa3b, v13
	v_mul_f32_e32 v21, 0xbfb8aa3b, v11
	v_mul_f32_e32 v22, 0xbfb8aa3b, v15
	v_mul_f32_e32 v23, 0xbfb8aa3b, v1
	v_mul_f32_e32 v24, 0xbfb8aa3b, v5
	v_exp_f32_e32 v25, v25
	v_exp_f32_e32 v18, v18
	v_exp_f32_e32 v19, v19
	v_exp_f32_e32 v20, v20
	v_exp_f32_e32 v21, v21
	v_exp_f32_e32 v22, v22
	v_exp_f32_e32 v23, v23
	v_exp_f32_e32 v24, v24
	v_add_f32_e32 v25, 1.0, v25
	v_add_f32_e32 v18, 1.0, v18
	v_add_f32_e32 v19, 1.0, v19
	v_add_f32_e32 v20, 1.0, v20
	v_add_f32_e32 v21, 1.0, v21
	v_add_f32_e32 v22, 1.0, v22
	v_add_f32_e32 v23, 1.0, v23
	v_add_f32_e32 v24, 1.0, v24
	v_rcp_f32_e32 v25, v25
	v_rcp_f32_e32 v18, v18
	v_rcp_f32_e32 v19, v19
	v_rcp_f32_e32 v20, v20
	v_rcp_f32_e32 v21, v21
	v_rcp_f32_e32 v22, v22
	v_rcp_f32_e32 v23, v23
	v_rcp_f32_e32 v24, v24
	v_mul_f32_e32 v3, v3, v25
	v_mul_f32_e32 v17, v17, v18
	v_mul_f32_e32 v9, v9, v19
	v_mul_f32_e32 v13, v13, v20
	v_mul_f32_e32 v11, v11, v21
	v_mul_f32_e32 v15, v15, v22
	v_mul_f32_e32 v1, v1, v23
	v_mul_f32_e32 v5, v5, v24
	v_mul_f32_e32 v3, v2, v3
	s_mov_b64 s[0:1], -1
	v_mul_f32_e32 v16, v16, v17
	v_mul_f32_e32 v8, v8, v9
	v_mul_f32_e32 v9, v12, v13
	v_mul_f32_e32 v10, v10, v11
	v_mul_f32_e32 v11, v14, v15
	v_mul_f32_e32 v12, v0, v1
	v_mul_f32_e32 v4, v4, v5
	v_cvt_pk_bf16_f32 v0, v16, v8
	v_cvt_pk_bf16_f32 v1, v9, v10
	v_cvt_pk_bf16_f32 v2, v11, v12
	v_cvt_pk_bf16_f32 v3, v4, v3
	global_store_dwordx4 v[6:7], v[0:3], off
	s_cbranch_vccnz .LBB0_1081
	s_andn2_b64 vcc, exec, s[8:9]
	s_cbranch_vccnz .LBB0_1080
	s_barrier
	s_branch .LBB0_1080

; __device__ __forceinline__ unsigned xb_ld(unsigned* p)              { return __hip_atomic_load(p, __ATOMIC_RELAXED, __HIP_MEMORY_SCOPE_AGENT); }
; __device__ __forceinline__ void xcd_barrier_complete(unsigned* bar, unsigned x, unsigned& nloc, unsigned& nx) {
;     ...
;     for (;;) {
;         sum = 0u; cnt = 0u; mine = 0u;
; #pragma unroll
;         for (unsigned j = 0; j < 16; ++j) { const unsigned c = xb_ld(&bar[XB_XCNT(j)]); sum += c; cnt += (c > 0u) ? 1u : 0u; mine = (j == x) ? c : mine; }
;         if (sum == G) break;
;         __builtin_amdgcn_s_sleep(1);
;         if ((++sp & 255u) == 0u) { if (xb_ld(&bar[XB_TMO])) break; if (sp > XB_SPIN_CAP) { atomicAdd(&bar[XB_TMO], 1u); break; } }
;     }
.LBB0_1122:
	v_mov_b64_e32 v[12:13], s[40:41]
	global_load_dword v1, v[12:13], off offset:1024 sc1
	s_waitcnt lgkmcnt(0)
	global_load_dword v0, v[12:13], off offset:1280 sc1
	global_load_dword v2, v[12:13], off offset:1536 sc1
	s_or_b64 s[22:23], s[22:23], exec
	s_or_b64 s[20:21], s[20:21], exec
	s_waitcnt vmcnt(0) lgkmcnt(0)
	v_add_u32_e32 v3, v0, v1
	v_add_u32_e32 v4, v3, v2
	global_load_dword v3, v[12:13], off offset:1792 sc1
	s_waitcnt vmcnt(0) lgkmcnt(0)
	v_add_u32_e32 v5, v4, v3
	global_load_dword v4, v[12:13], off offset:2048 sc1
	s_waitcnt vmcnt(0) lgkmcnt(0)
	v_add_u32_e32 v6, v5, v4
	global_load_dword v5, v[12:13], off offset:2304 sc1
	s_waitcnt vmcnt(0) lgkmcnt(0)
	v_add_u32_e32 v7, v6, v5
	global_load_dword v6, v[12:13], off offset:2560 sc1
	s_waitcnt vmcnt(0) lgkmcnt(0)
	v_add_u32_e32 v8, v7, v6
	global_load_dword v7, v[12:13], off offset:2816 sc1
	s_waitcnt vmcnt(0) lgkmcnt(0)
	v_add_u32_e32 v9, v8, v7
	global_load_dword v8, v[12:13], off offset:3072 sc1
	s_waitcnt vmcnt(0) lgkmcnt(0)
	v_add_u32_e32 v10, v9, v8
	global_load_dword v9, v[12:13], off offset:3328 sc1
	s_waitcnt vmcnt(0) lgkmcnt(0)
	v_add_u32_e32 v11, v10, v9
	global_load_dword v10, v[12:13], off offset:3584 sc1
	s_waitcnt vmcnt(0) lgkmcnt(0)
	v_add_u32_e32 v14, v11, v10
	global_load_dword v11, v[12:13], off offset:3840 sc1
	v_mov_b64_e32 v[12:13], s[0:1]
	global_load_dword v12, v[12:13], off sc1
	s_waitcnt vmcnt(0) lgkmcnt(0)
	v_add_u32_e32 v14, v14, v11
	v_add_u32_e32 v16, v14, v12
	v_mov_b64_e32 v[14:15], s[6:7]
	global_load_dword v13, v[14:15], off sc1
	v_mov_b64_e32 v[14:15], s[8:9]
	global_load_dword v14, v[14:15], off sc1
	s_waitcnt vmcnt(0) lgkmcnt(0)
	v_add_u32_e32 v16, v16, v13
	v_add_u32_e32 v18, v16, v14
	v_mov_b64_e32 v[16:17], s[10:11]
	global_load_dword v15, v[16:17], off sc1
	s_waitcnt vmcnt(0) lgkmcnt(0)
	v_add_u32_e32 v16, v18, v15
	v_cmp_ne_u32_e32 vcc, s78, v16
	s_and_saveexec_b64 s[24:25], vcc
	s_cbranch_execz .LBB0_1121
	s_and_b32 s28, s17, 0xff
	s_mov_b64 s[26:27], -1
	s_cmp_eq_u32 s28, 0
	s_mov_b64 s[30:31], -1
	s_mov_b64 s[28:29], -1
	s_sleep 1
	s_cbranch_scc1 .LBB0_1125
	s_and_saveexec_b64 s[34:35], s[30:31]
	s_cbranch_execz .LBB0_1120
	s_branch .LBB0_1128
.LBB0_1125:
	v_mov_b64_e32 v[16:17], s[40:41]
	global_load_dword v16, v[16:17], off offset:512 sc1
	s_mov_b64 s[30:31], 0
	s_waitcnt vmcnt(0) lgkmcnt(0)
	v_cmp_eq_u32_e32 vcc, 0, v16
	s_and_saveexec_b64 s[34:35], vcc
	s_cmp_lt_u32 s17, 0x40001
	s_cselect_b64 s[30:31], -1, 0
	s_xor_b64 s[28:29], exec, -1
	s_and_b64 s[30:31], s[30:31], exec
	s_or_b64 exec, exec, s[34:35]
	s_and_saveexec_b64 s[34:35], s[30:31]
	s_cbranch_execz .LBB0_1120

; __device__ __forceinline__ unsigned xb_ld(unsigned* p)              { return __hip_atomic_load(p, __ATOMIC_RELAXED, __HIP_MEMORY_SCOPE_AGENT); }
; __device__ __forceinline__ void xcd_barrier_complete(unsigned* bar, unsigned x, unsigned& nloc, unsigned& nx) {
;     ...
;         if ((++sp & 255u) == 0u) { if (xb_ld(&bar[XB_TMO])) break; if (sp > XB_SPIN_CAP) { atomicAdd(&bar[XB_TMO], 1u); break; } }
.LBB0_1129:
	s_or_b64 exec, exec, s[12:13]
	s_xor_b64 s[0:1], s[18:19], -1
	s_and_saveexec_b64 s[6:7], s[0:1]
	s_xor_b64 s[0:1], exec, s[6:7]
	s_cbranch_execz .LBB0_1131
	v_mov_b64_e32 v[16:17], s[40:41]
	global_atomic_add v[16:17], v225, off offset:512

; __device__ __forceinline__ unsigned xb_ld(unsigned* p)              { return __hip_atomic_load(p, __ATOMIC_RELAXED, __HIP_MEMORY_SCOPE_AGENT); }
; __device__ __forceinline__ unsigned xb_add(unsigned* p, unsigned v) { return __hip_atomic_fetch_add(p, v, __ATOMIC_RELAXED, __HIP_MEMORY_SCOPE_AGENT); }
; #define XB_SPIN(cond, bar) do { unsigned _sp = 0; while (cond) { __builtin_amdgcn_s_sleep(1); \
;     if ((++_sp & 255u) == 0u) { if (xb_ld(&(bar)[XB_TMO])) break; if (_sp > XB_SPIN_CAP) { atomicAdd(&(bar)[XB_TMO], 1u); break; } } } } while (0)
; __device__ __forceinline__ void xcd_barrier(const XcdBarrier& b) {
;     ...
;         const unsigned old = xb_add(&bar[XB_XSUB(b.x)], 1u);
;         const unsigned gen = old / nloc;
;         if (old + 1u == (gen + 1u) * nloc) {
;             __builtin_amdgcn_fence(__ATOMIC_RELEASE, "agent");
;             asm volatile("s_waitcnt vmcnt(0)" ::: "memory");
;             const unsigned og = xb_add(&bar[XB_TOP], 1u);
;             const unsigned tg = og / nx;
;             if (og + 1u == (tg + 1u) * nx) xb_add(&bar[XB_TOPGEN], 1u);
;             else XB_SPIN(xb_ld(&bar[XB_TOPGEN]) == tg, bar);
;             __builtin_amdgcn_fence(__ATOMIC_ACQUIRE, "agent");
;             xb_add(&bar[XB_XGEN(b.x)], 1u);
;             asm volatile("s_waitcnt vmcnt(0)" ::: "memory");
;         } else {
;             XB_SPIN(xb_ld(&bar[XB_XGEN(b.x)]) == gen, bar);
.LBB0_1132:
	s_lshl_b32 s0, s16, 8
	s_add_u32 s17, s40, s0
	s_addc_u32 s16, s41, 0
	v_mov_b32_e32 v1, s17
	v_add_co_u32_e32 v4, vcc, 0x1000, v1
	v_mov_b32_e32 v1, s16
	s_nop 0
	v_addc_co_u32_e32 v5, vcc, 0, v1, vcc
	global_atomic_add v3, v[4:5], v225, off offset:1024 sc0
	v_cvt_f32_u32_e32 v1, v2
	v_sub_u32_e32 v4, 0, v2
	v_rcp_iflag_f32_e32 v1, v1
	s_nop 0
	v_mul_f32_e32 v1, 0x4f7ffffe, v1
	v_cvt_u32_f32_e32 v1, v1
	v_mul_lo_u32 v4, v4, v1
	v_mul_hi_u32 v4, v1, v4
	v_add_u32_e32 v1, v1, v4
	s_waitcnt vmcnt(0) lgkmcnt(0)
	v_mul_hi_u32 v1, v3, v1
	v_mul_lo_u32 v4, v1, v2
	v_sub_u32_e32 v4, v3, v4
	v_cmp_ge_u32_e32 vcc, v4, v2
	v_add_u32_e32 v5, 1, v1
	s_nop 0
	v_cndmask_b32_e32 v1, v1, v5, vcc
	v_sub_u32_e32 v5, v4, v2
	v_cndmask_b32_e32 v4, v4, v5, vcc
	v_cmp_ge_u32_e32 vcc, v4, v2
	v_add_u32_e32 v4, 1, v1
	s_nop 0
	v_cndmask_b32_e32 v1, v1, v4, vcc
	v_add_u32_e32 v4, 1, v3
	v_mad_u64_u32 v[2:3], s[0:1], v2, v1, v[2:3]
	v_cmp_ne_u32_e32 vcc, v4, v2
	s_and_saveexec_b64 s[0:1], vcc
	s_xor_b64 s[0:1], exec, s[0:1]
	s_cbranch_execz .LBB0_1145
	v_mov_b32_e32 v0, s17
	v_add_co_u32_e32 v2, vcc, 0x2000, v0
	v_mov_b32_e32 v0, s16
	s_nop 0
	v_addc_co_u32_e32 v3, vcc, 0, v0, vcc
	global_load_dword v0, v[2:3], off offset:1024 sc1
	s_add_u32 s8, s17, 0x2400
	s_addc_u32 s9, s16, 0
	s_waitcnt vmcnt(0) lgkmcnt(0)
	v_cmp_eq_u32_e32 vcc, v0, v1
	s_and_saveexec_b64 s[6:7], vcc
	s_cbranch_execz .LBB0_1144
	s_mov_b32 s28, 1
	s_mov_b64 s[10:11], 0
	s_branch .LBB0_1136

; __device__ __forceinline__ unsigned xb_ld(unsigned* p)              { return __hip_atomic_load(p, __ATOMIC_RELAXED, __HIP_MEMORY_SCOPE_AGENT); }
; #define XB_SPIN(cond, bar) do { unsigned _sp = 0; while (cond) { __builtin_amdgcn_s_sleep(1); \
;     if ((++_sp & 255u) == 0u) { if (xb_ld(&(bar)[XB_TMO])) break; if (_sp > XB_SPIN_CAP) { atomicAdd(&(bar)[XB_TMO], 1u); break; } } } } while (0)
; __device__ __forceinline__ void xcd_barrier(const XcdBarrier& b) {
;     ...
;             XB_SPIN(xb_ld(&bar[XB_XGEN(b.x)]) == gen, bar);
.LBB0_1136:
	s_and_b32 s22, s28, 0xff
	s_mov_b64 s[20:21], -1
	s_cmp_lg_u32 s22, 0
	s_mov_b64 s[22:23], -1
	s_sleep 1
	s_cbranch_scc1 .LBB0_1140
	v_mov_b64_e32 v[2:3], s[40:41]
	global_load_dword v0, v[2:3], off offset:512 sc1
	s_mov_b64 s[22:23], 0
	s_mov_b64 s[24:25], -1
	s_waitcnt vmcnt(0) lgkmcnt(0)
	v_cmp_eq_u32_e32 vcc, 0, v0
	s_and_saveexec_b64 s[26:27], vcc
	s_cmp_lt_u32 s28, 0x40001
	s_cselect_b64 s[22:23], -1, 0
	s_xor_b64 s[24:25], exec, -1
	s_and_b64 s[22:23], s[22:23], exec
	s_or_b64 exec, exec, s[26:27]
.LBB0_1140:
	s_andn2_b64 s[18:19], s[18:19], exec
	s_and_b64 s[24:25], s[24:25], exec
	s_or_b64 s[18:19], s[18:19], s[24:25]
	s_and_saveexec_b64 s[24:25], s[22:23]
	s_cbranch_execz .LBB0_1135
	v_mov_b64_e32 v[2:3], s[8:9]
	global_load_dword v0, v[2:3], off sc1
	s_add_i32 s28, s28, 1
	s_or_b64 s[18:19], s[18:19], exec
	s_waitcnt vmcnt(0) lgkmcnt(0)
	v_cmp_ne_u32_e32 vcc, v0, v1
	s_orn2_b64 s[20:21], vcc, exec
	s_branch .LBB0_1135
.LBB0_1142:
	s_or_b64 exec, exec, s[10:11]
	s_xor_b64 s[8:9], s[12:13], -1
	s_and_saveexec_b64 s[10:11], s[8:9]
	s_xor_b64 s[10:11], exec, s[10:11]
	s_cbranch_execz .LBB0_1144
	v_mov_b64_e32 v[0:1], s[40:41]
	global_atomic_add v[0:1], v225, off offset:512

; __device__ __forceinline__ unsigned xb_ld(unsigned* p)              { return __hip_atomic_load(p, __ATOMIC_RELAXED, __HIP_MEMORY_SCOPE_AGENT); }
; __device__ __forceinline__ unsigned xb_add(unsigned* p, unsigned v) { return __hip_atomic_fetch_add(p, v, __ATOMIC_RELAXED, __HIP_MEMORY_SCOPE_AGENT); }
; #define XB_SPIN(cond, bar) do { unsigned _sp = 0; while (cond) { __builtin_amdgcn_s_sleep(1); \
;     if ((++_sp & 255u) == 0u) { if (xb_ld(&(bar)[XB_TMO])) break; if (_sp > XB_SPIN_CAP) { atomicAdd(&(bar)[XB_TMO], 1u); break; } } } } while (0)
; __device__ __forceinline__ void xcd_barrier(const XcdBarrier& b) {
;     ...
;         if (old + 1u == (gen + 1u) * nloc) {
;             __builtin_amdgcn_fence(__ATOMIC_RELEASE, "agent");
;             asm volatile("s_waitcnt vmcnt(0)" ::: "memory");
;             const unsigned og = xb_add(&bar[XB_TOP], 1u);
;             const unsigned tg = og / nx;
;             if (og + 1u == (tg + 1u) * nx) xb_add(&bar[XB_TOPGEN], 1u);
;             else XB_SPIN(xb_ld(&bar[XB_TOPGEN]) == tg, bar);
.LBB0_1145:
	s_andn2_saveexec_b64 s[0:1], s[0:1]
	s_cbranch_execz .LBB0_1161
	v_mov_b32_e32 v1, s40
	v_add_co_u32_e32 v2, vcc, 0x3000, v1
	v_mov_b32_e32 v1, s41
	buffer_wbl2 sc1
	s_waitcnt vmcnt(0)
	v_addc_co_u32_e32 v3, vcc, 0, v1, vcc
	global_atomic_add v1, v[2:3], v225, off offset:1024 sc0
	v_cvt_f32_u32_e32 v2, v0
	v_sub_u32_e32 v3, 0, v0
	s_mov_b64 s[8:9], -1
	v_rcp_iflag_f32_e32 v2, v2
	s_nop 0
	v_mul_f32_e32 v2, 0x4f7ffffe, v2
	v_cvt_u32_f32_e32 v2, v2
	v_mul_lo_u32 v3, v3, v2
	v_mul_hi_u32 v3, v2, v3
	v_add_u32_e32 v2, v2, v3
	s_waitcnt vmcnt(0) lgkmcnt(0)
	v_mul_hi_u32 v2, v1, v2
	v_mul_lo_u32 v3, v2, v0
	v_sub_u32_e32 v3, v1, v3
	v_cmp_ge_u32_e32 vcc, v3, v0
	v_add_u32_e32 v4, 1, v2
	s_nop 0
	v_cndmask_b32_e32 v2, v2, v4, vcc
	v_sub_u32_e32 v4, v3, v0
	v_cndmask_b32_e32 v3, v3, v4, vcc
	v_cmp_ge_u32_e32 vcc, v3, v0
	v_add_u32_e32 v3, 1, v2
	s_nop 0
	v_cndmask_b32_e32 v2, v2, v3, vcc
	v_add_u32_e32 v3, 1, v1
	v_mad_u64_u32 v[0:1], s[0:1], v0, v2, v[0:1]
	s_add_u32 s0, s40, 0x3500
	s_addc_u32 s1, s41, 0
	v_cmp_ne_u32_e32 vcc, v3, v0
	v_mov_b64_e32 v[0:1], s[0:1]
	s_and_saveexec_b64 s[6:7], vcc
	s_cbranch_execz .LBB0_1158
	v_mov_b64_e32 v[0:1], s[0:1]
	global_load_dword v0, v[0:1], off sc1
	s_mov_b64 s[12:13], 0
	s_waitcnt vmcnt(0) lgkmcnt(0)
	v_cmp_eq_u32_e32 vcc, v0, v2
	s_and_saveexec_b64 s[10:11], vcc
	s_cbranch_execz .LBB0_1157
	s_add_u32 s8, s40, 0x200
	s_addc_u32 s9, s41, 0
	s_mov_b32 s28, 1
	s_branch .LBB0_1150

; __device__ __forceinline__ unsigned xb_ld(unsigned* p)              { return __hip_atomic_load(p, __ATOMIC_RELAXED, __HIP_MEMORY_SCOPE_AGENT); }
; #define XB_SPIN(cond, bar) do { unsigned _sp = 0; while (cond) { __builtin_amdgcn_s_sleep(1); \
;     if ((++_sp & 255u) == 0u) { if (xb_ld(&(bar)[XB_TMO])) break; if (_sp > XB_SPIN_CAP) { atomicAdd(&(bar)[XB_TMO], 1u); break; } } } } while (0)
; __device__ __forceinline__ void xcd_barrier(const XcdBarrier& b) {
;     ...
;             else XB_SPIN(xb_ld(&bar[XB_TOPGEN]) == tg, bar);
.LBB0_1152:
	v_mov_b64_e32 v[0:1], s[8:9]
	global_load_dword v0, v[0:1], off sc1
	s_mov_b64 s[24:25], 0
	s_mov_b64 s[22:23], -1
	s_waitcnt vmcnt(0) lgkmcnt(0)
	v_cmp_eq_u32_e32 vcc, 0, v0
	s_and_saveexec_b64 s[26:27], vcc
	s_cmp_lt_u32 s28, 0x40001
	s_cselect_b64 s[24:25], -1, 0
	s_xor_b64 s[22:23], exec, -1
	s_and_b64 s[24:25], s[24:25], exec
	s_or_b64 exec, exec, s[26:27]
	s_and_saveexec_b64 s[26:27], s[24:25]
	s_cbranch_execz .LBB0_1149
.LBB0_1155:
	v_mov_b64_e32 v[0:1], s[0:1]
	global_load_dword v0, v[0:1], off sc1
	s_add_i32 s28, s28, 1
	s_or_b64 s[22:23], s[22:23], exec
	s_waitcnt vmcnt(0) lgkmcnt(0)
	v_cmp_ne_u32_e32 vcc, v0, v2
	s_orn2_b64 s[20:21], vcc, exec
	s_branch .LBB0_1149

; __device__ __forceinline__ unsigned xb_add(unsigned* p, unsigned v) { return __hip_atomic_fetch_add(p, v, __ATOMIC_RELAXED, __HIP_MEMORY_SCOPE_AGENT); }
; __device__ __forceinline__ void xcd_barrier(const XcdBarrier& b) {
;     ...
;             if (og + 1u == (tg + 1u) * nx) xb_add(&bar[XB_TOPGEN], 1u);
.LBB0_1158:
	s_or_b64 exec, exec, s[6:7]
	s_and_saveexec_b64 s[0:1], s[8:9]
	s_cbranch_execz .LBB0_1160
	global_atomic_add v[0:1], v225, off

;     __device__ __forceinline__ void operator()(const f32x4 (&acc)[2][2][4][2], const Unit& u, int wr, int wc, int fr, int fq) const {
;     ...
;         f32x4 gt[2][2], gs[2][2];
; #pragma unroll
;         for (int bj = 0; bj < 2; ++bj)
; #pragma unroll
;             for (int n = 0; n < 2; ++n) {
;                 const int col = cb + 128 * bj + 4 * n;
;                 gt[bj][n] = *(const f32x4*)(gate + v * 6144 + col);
;                 if (nxt) { const f32x4 a = *(const f32x4*)(ng + col), s = *(const f32x4*)(nsc + v * 6144 + col); gs[bj][n] = a * (s + 1.f); } else gs[bj][n] = (f32x4){0.f, 0.f, 0.f, 0.f};
;             }
; #pragma unroll
;         for (int q2 = 0; q2 < 4; ++q2) {
;             const int ai = q2 >> 1, m0 = (q2 & 1) * 2;
;             f32x4 pre[2][2][2];
; #pragma unroll
;             for (int mm = 0; mm < 2; ++mm) {
;                 const int row = pm * 256 + ai * 128 + wr * 64 + (m0 + mm) * 16 + fr;
;                 const float* src = isctx ? res_ctx + (size_t)(row - MLAT) * DM : res_lat + (size_t)row * DM;
; #pragma unroll
;                 for (int bj = 0; bj < 2; ++bj) { pre[mm][bj][0] = *(const f32x4*)(src + cb + 128 * bj); pre[mm][bj][1] = *(const f32x4*)(src + cb + 128 * bj + 4); }
;             }
.LBB0_1181:
	s_min_i32 s10, s40, 64
	s_lshr_b32 s10, s10, 5
	s_mulk_i32 s10, 0x1800
	s_ashr_i32 s11, s10, 31
	s_lshl_b64 s[10:11], s[10:11], 2
	v_lshl_or_b32 v192, s41, 8, v236
	s_add_u32 s12, s52, s10
	s_addc_u32 s13, s53, s11
	v_ashrrev_i32_e32 v193, 31, v192
	v_lshl_add_u64 v[60:61], v[192:193], 2, s[12:13]
	global_load_dwordx4 v[64:67], v[60:61], off
	s_add_u32 s10, s64, s10
	s_addc_u32 s11, s65, s11
	v_mov_b32_e32 v198, 0
	s_and_b64 vcc, exec, s[4:5]
	v_lshlrev_b64 v[210:211], 2, v[192:193]
	v_mov_b32_e32 v200, 0
	v_mov_b32_e32 v201, 0
	v_mov_b32_e32 v202, 0
	v_mov_b32_e32 v203, 0
	s_cbranch_vccnz .LBB0_1183
	v_lshl_add_u64 v[48:49], s[10:11], 0, v[210:211]
	global_load_dwordx4 v[48:51], v[48:49], off
	v_lshl_add_u64 v[62:63], s[30:31], 0, v[210:211]
	global_load_dwordx4 v[68:71], v[62:63], off
	s_waitcnt vmcnt(0) lgkmcnt(0)
	v_pk_add_f32 v[50:51], v[50:51], 1.0 op_sel_hi:[1,0]
	v_pk_add_f32 v[48:49], v[48:49], 1.0 op_sel_hi:[1,0]
	v_pk_mul_f32 v[202:203], v[70:71], v[50:51]
	v_pk_mul_f32 v[200:201], v[68:69], v[48:49]
.LBB0_1183:
	global_load_dwordx4 v[68:71], v[60:61], off offset:16
	s_and_b64 vcc, exec, s[4:5]
	v_lshl_add_u64 v[144:145], v[192:193], 2, s[10:11]
	v_mov_b32_e32 v199, 0
	v_mov_b32_e32 v208, 0
	v_mov_b32_e32 v209, 0
	s_cbranch_vccnz .LBB0_1185
	v_or_b32_e32 v62, 4, v192
	v_ashrrev_i32_e32 v63, 31, v62
	global_load_dwordx4 v[48:51], v[144:145], off offset:16
	v_lshl_add_u64 v[62:63], v[62:63], 2, s[30:31]
	global_load_dwordx4 v[146:149], v[62:63], off
	s_waitcnt vmcnt(0) lgkmcnt(0)
	v_pk_add_f32 v[50:51], v[50:51], 1.0 op_sel_hi:[1,0]
	v_pk_add_f32 v[48:49], v[48:49], 1.0 op_sel_hi:[1,0]
	v_pk_mul_f32 v[208:209], v[148:149], v[50:51]
	v_pk_mul_f32 v[198:199], v[146:147], v[48:49]
.LBB0_1185:
	global_load_dwordx4 v[48:51], v[60:61], off offset:512
	v_mov_b32_e32 v194, 0
	s_and_b64 vcc, exec, s[4:5]
	v_mov_b32_e32 v196, 0
	v_mov_b32_e32 v197, 0
	v_mov_b32_e32 v204, 0
	v_mov_b32_e32 v205, 0
	s_cbranch_vccnz .LBB0_1187
	v_or_b32_e32 v62, 0x80, v192
	v_ashrrev_i32_e32 v63, 31, v62
	global_load_dwordx4 v[146:149], v[144:145], off offset:512
	v_lshl_add_u64 v[62:63], v[62:63], 2, s[30:31]
	global_load_dwordx4 v[150:153], v[62:63], off
	s_waitcnt vmcnt(0) lgkmcnt(0)
	v_pk_add_f32 v[62:63], v[148:149], 1.0 op_sel_hi:[1,0]
	v_pk_add_f32 v[146:147], v[146:147], 1.0 op_sel_hi:[1,0]
	v_pk_mul_f32 v[204:205], v[152:153], v[62:63]
	v_pk_mul_f32 v[196:197], v[150:151], v[146:147]
.LBB0_1187:
	global_load_dwordx4 v[60:63], v[60:61], off offset:528
	s_and_b64 vcc, exec, s[4:5]
	v_mov_b32_e32 v195, 0
	v_mov_b32_e32 v206, 0
	v_mov_b32_e32 v207, 0
	s_cbranch_vccnz .LBB0_1189
	v_or_b32_e32 v148, 0x84, v192
	v_ashrrev_i32_e32 v149, 31, v148
	global_load_dwordx4 v[144:147], v[144:145], off offset:528
	v_lshl_add_u64 v[148:149], v[148:149], 2, s[30:31]
	global_load_dwordx4 v[148:151], v[148:149], off
	s_waitcnt vmcnt(0) lgkmcnt(0)
	v_pk_add_f32 v[146:147], v[146:147], 1.0 op_sel_hi:[1,0]
	v_pk_add_f32 v[144:145], v[144:145], 1.0 op_sel_hi:[1,0]
	v_pk_mul_f32 v[206:207], v[150:151], v[146:147]
	v_pk_mul_f32 v[194:195], v[148:149], v[144:145]
.LBB0_1189:
	s_cmp_lt_i32 s40, 64
	s_cselect_b64 s[38:39], -1, 0
	s_cmp_gt_i32 s40, 63
	v_lshl_add_u32 v212, s40, 8, v234
	v_add_u32_e32 v218, 0xffffc000, v212
	s_cselect_b64 s[10:11], -1, 0
	v_cndmask_b32_e64 v144, v212, v218, s[10:11]
	s_and_b64 s[12:13], s[10:11], exec
	v_ashrrev_i32_e32 v145, 31, v144
	s_cselect_b32 s37, s23, s91
	s_cselect_b32 s36, s22, s90
	v_lshlrev_b64 v[144:145], 12, v[144:145]
	v_lshl_add_u64 v[144:145], s[36:37], 0, v[144:145]
	v_lshl_add_u64 v[144:145], v[144:145], 0, v[210:211]
	v_or_b32_e32 v214, 16, v212
	v_add_u32_e32 v216, 0xffffc010, v212
	global_load_dwordx4 v[172:175], v[144:145], off
	global_load_dwordx4 v[168:171], v[144:145], off offset:16
	global_load_dwordx4 v[164:167], v[144:145], off offset:512
	global_load_dwordx4 v[160:163], v[144:145], off offset:528
	v_cndmask_b32_e64 v144, v214, v216, s[10:11]
	v_ashrrev_i32_e32 v145, 31, v144
	v_lshlrev_b64 v[144:145], 12, v[144:145]
	v_lshl_add_u64 v[144:145], s[36:37], 0, v[144:145]
	v_lshl_add_u64 v[144:145], v[144:145], 0, v[210:211]
	global_load_dwordx4 v[156:159], v[144:145], off
	global_load_dwordx4 v[152:155], v[144:145], off offset:16
	global_load_dwordx4 v[148:151], v[144:145], off offset:512
	s_nop 0
	global_load_dwordx4 v[144:147], v[144:145], off offset:528
	s_mov_b64 s[12:13], -1
	s_and_b64 vcc, exec, s[38:39]
	v_ashrrev_i32_e32 v213, 31, v212
	s_cbranch_vccz .LBB0_1191
	v_lshlrev_b64 v[220:221], 12, v[212:213]
	v_lshl_add_u64 v[220:221], s[90:91], 0, v[220:221]
	s_mov_b64 s[12:13], 0

; __device__ __forceinline__ unsigned pkbf(float lo, float hi) { return pg8::cvt_pk_bf16(lo, hi); }
;     __device__ __forceinline__ void operator()(const f32x4 (&acc)[2][2][4][2], const Unit& u, int wr, int wc, int fr, int fq) const {
;     ...
;             for (int mm = 0; mm < 2; ++mm) {
;                 const int m = m0 + mm;
;                 const int row = pm * 256 + ai * 128 + wr * 64 + m * 16 + fr;
;                 float* dst = isctx ? dst_ctx + (size_t)(row - MLAT) * DM : dst_lat + (size_t)row * DM;
;                 float ss = 0.f;
; #pragma unroll
;                 for (int bj = 0; bj < 2; ++bj) {
;                     const int col = cb + 128 * bj;
;                     const f32x4 x0 = pre[mm][bj][0] + gt[bj][0] * acc[ai][bj][m][0];
;                     const f32x4 x1 = pre[mm][bj][1] + gt[bj][1] * acc[ai][bj][m][1];
;                     *(f32x4*)(dst + col) = x0; *(f32x4*)(dst + col + 4) = x1;
;                     if (nxt) {
;                         ss += (x0[0] * x0[0] + x0[1] * x0[1]) + (x0[2] * x0[2] + x0[3] * x0[3]) + (x1[0] * x1[0] + x1[1] * x1[1]) + (x1[2] * x1[2] + x1[3] * x1[3]);
;                         const f32x4 y0 = x0 * gs[bj][0], y1 = x1 * gs[bj][1];
;                         u32x4 w; w.x = pkbf(y0[0], y0[1]); w.y = pkbf(y0[2], y0[3]); w.z = pkbf(y1[0], y1[1]); w.w = pkbf(y1[2], y1[3]);
;                         *(u32x4*)(xg + (size_t)row * DM + col) = w;
;                     }
;                 }
;                 if (nxt) { ss += __shfl_xor(ss, 16); ss += __shfl_xor(ss, 32); if (fq == 0) unsafeAtomicAdd(rowsq_next + row, ss); }
.LBB0_1193:
	v_lshlrev_b64 v[218:219], 11, v[212:213]
	s_waitcnt vmcnt(0) lgkmcnt(0)
	v_pk_fma_f32 v[136:137], v[136:137], v[68:69], v[168:169]
	v_lshl_add_u64 v[168:169], s[24:25], 0, v[218:219]
	v_pk_fma_f32 v[142:143], v[142:143], v[66:67], v[174:175]
	v_pk_fma_f32 v[140:141], v[140:141], v[64:65], v[172:173]
	v_pk_fma_f32 v[138:139], v[138:139], v[70:71], v[170:171]
	v_lshl_add_u64 v[170:171], v[192:193], 2, v[220:221]
	v_mov_b32_e32 v172, 0
	s_and_b64 vcc, exec, s[4:5]
	v_lshl_add_u64 v[168:169], v[192:193], 1, v[168:169]
	global_store_dwordx4 v[170:171], v[140:143], off
	global_store_dwordx4 v[170:171], v[136:139], off offset:16
	s_cbranch_vccnz .LBB0_1195
	v_pk_mul_f32 v[172:173], v[142:143], v[142:143]
	v_pk_mul_f32 v[174:175], v[140:141], v[140:141]
	v_pk_mul_f32 v[142:143], v[202:203], v[142:143]
	v_pk_mov_b32 v[218:219], v[174:175], v[172:173] op_sel:[1,0]
	v_mov_b32_e32 v175, v173
	v_pk_add_f32 v[172:173], v[218:219], v[174:175]
	v_pk_mul_f32 v[174:175], v[138:139], v[138:139]
	v_pk_mul_f32 v[218:219], v[136:137], v[136:137]
	v_mov_b32_e32 v220, v174
	v_mov_b32_e32 v221, v218
	v_mov_b32_e32 v218, v175
	v_pk_add_f32 v[174:175], v[220:221], v[218:219]
	v_add_f32_e32 v172, v172, v173
	v_add_f32_e32 v172, v172, v175
	v_add_f32_e32 v172, v174, v172
	v_pk_mul_f32 v[174:175], v[208:209], v[138:139]
	v_pk_mul_f32 v[138:139], v[198:199], v[136:137]
	v_pk_mul_f32 v[140:141], v[200:201], v[140:141]
	s_nop 0
	v_cvt_pk_bf16_f32 v136, v140, v141
	v_cvt_pk_bf16_f32 v137, v142, v143
	v_cvt_pk_bf16_f32 v138, v138, v139
	v_cvt_pk_bf16_f32 v139, v174, v175
	global_store_dwordx4 v[168:169], v[136:139], off
.LBB0_1195:
	v_pk_fma_f32 v[134:135], v[134:135], v[50:51], v[166:167]
	v_pk_fma_f32 v[132:133], v[132:133], v[48:49], v[164:165]
	v_pk_fma_f32 v[130:131], v[130:131], v[62:63], v[162:163]
	v_pk_fma_f32 v[128:129], v[128:129], v[60:61], v[160:161]
	s_and_b64 vcc, exec, s[4:5]
	global_store_dwordx4 v[170:171], v[132:135], off offset:512
	global_store_dwordx4 v[170:171], v[128:131], off offset:528
	s_cbranch_vccnz .LBB0_1199
	v_mul_f32_e32 v136, v133, v133
	v_mul_f32_e32 v137, v135, v135
	v_fmac_f32_e32 v136, v132, v132
	v_fmac_f32_e32 v137, v134, v134
	v_add_f32_e32 v136, v136, v137
	v_mul_f32_e32 v137, v129, v129
	v_fmac_f32_e32 v137, v128, v128
	v_add_f32_e32 v136, v136, v137
	v_mul_f32_e32 v137, v131, v131
	v_fmac_f32_e32 v137, v130, v130
	v_add_f32_e32 v136, v137, v136
	v_add_f32_e32 v138, v136, v172
	v_pk_mul_f32 v[134:135], v[204:205], v[134:135]
	v_pk_mul_f32 v[132:133], v[196:197], v[132:133]
	v_pk_mul_f32 v[136:137], v[206:207], v[130:131]
	v_pk_mul_f32 v[130:131], v[194:195], v[128:129]
	v_cvt_pk_bf16_f32 v128, v132, v133
	v_cvt_pk_bf16_f32 v129, v134, v135
	s_nop 0
	v_cvt_pk_bf16_f32 v130, v130, v131
	v_cvt_pk_bf16_f32 v131, v136, v137
	global_store_dwordx4 v[168:169], v[128:131], off offset:256
	s_nop 1
	v_and_b32_e32 v129, 64, v229
	v_xor_b32_e32 v128, 16, v229
	v_add_u32_e32 v129, 64, v129
	v_cmp_lt_i32_e32 vcc, v128, v129
	v_xor_b32_e32 v130, 32, v229
	s_nop 0
	v_cndmask_b32_e32 v128, v229, v128, vcc
	v_lshlrev_b32_e32 v128, 2, v128
	ds_bpermute_b32 v128, v128, v138
	v_cmp_lt_i32_e32 vcc, v130, v129
	s_waitcnt lgkmcnt(0)
	v_add_f32_e32 v128, v138, v128
	v_cndmask_b32_e32 v129, v229, v130, vcc
	v_lshlrev_b32_e32 v129, 2, v129
	ds_bpermute_b32 v129, v129, v128
	s_and_saveexec_b64 s[12:13], s[6:7]
	s_cbranch_execz .LBB0_1198
	v_lshl_add_u64 v[130:131], v[212:213], 2, s[26:27]
	s_waitcnt lgkmcnt(0)
	v_add_f32_e32 v128, v128, v129
	global_atomic_add_f32 v[130:131], v128, off

; __device__ __forceinline__ unsigned pkbf(float lo, float hi) { return pg8::cvt_pk_bf16(lo, hi); }
;     __device__ __forceinline__ void operator()(const f32x4 (&acc)[2][2][4][2], const Unit& u, int wr, int wc, int fr, int fq) const {
;     ...
;             for (int mm = 0; mm < 2; ++mm) {
;                 const int m = m0 + mm;
;                 const int row = pm * 256 + ai * 128 + wr * 64 + m * 16 + fr;
;                 float* dst = isctx ? dst_ctx + (size_t)(row - MLAT) * DM : dst_lat + (size_t)row * DM;
;                 float ss = 0.f;
; #pragma unroll
;                 for (int bj = 0; bj < 2; ++bj) {
;                     const int col = cb + 128 * bj;
;                     const f32x4 x0 = pre[mm][bj][0] + gt[bj][0] * acc[ai][bj][m][0];
;                     const f32x4 x1 = pre[mm][bj][1] + gt[bj][1] * acc[ai][bj][m][1];
;                     *(f32x4*)(dst + col) = x0; *(f32x4*)(dst + col + 4) = x1;
;                     if (nxt) {
;                         ss += (x0[0] * x0[0] + x0[1] * x0[1]) + (x0[2] * x0[2] + x0[3] * x0[3]) + (x1[0] * x1[0] + x1[1] * x1[1]) + (x1[2] * x1[2] + x1[3] * x1[3]);
;                         const f32x4 y0 = x0 * gs[bj][0], y1 = x1 * gs[bj][1];
;                         u32x4 w; w.x = pkbf(y0[0], y0[1]); w.y = pkbf(y0[2], y0[3]); w.z = pkbf(y1[0], y1[1]); w.w = pkbf(y1[2], y1[3]);
;                         *(u32x4*)(xg + (size_t)row * DM + col) = w;
;                     }
;                 }
;                 if (nxt) { ss += __shfl_xor(ss, 16); ss += __shfl_xor(ss, 32); if (fq == 0) unsafeAtomicAdd(rowsq_next + row, ss); }
.LBB0_1203:
	s_waitcnt lgkmcnt(0)
	v_pk_fma_f32 v[128:129], v[126:127], v[66:67], v[158:159]
	v_pk_fma_f32 v[126:127], v[124:125], v[64:65], v[156:157]
	v_pk_fma_f32 v[132:133], v[122:123], v[70:71], v[154:155]
	v_pk_fma_f32 v[130:131], v[120:121], v[68:69], v[152:153]
	v_lshl_add_u64 v[134:135], v[192:193], 2, v[134:135]
	s_mov_b64 s[38:39], -1
	s_and_b64 vcc, exec, s[4:5]
	v_pk_fma_f32 v[124:125], v[116:117], v[48:49], v[148:149]
	v_pk_fma_f32 v[120:121], v[112:113], v[60:61], v[144:145]
	global_store_dwordx4 v[134:135], v[126:129], off
	global_store_dwordx4 v[134:135], v[130:133], off offset:16
	s_cbranch_vccnz .LBB0_1207
	v_mul_f32_e32 v116, v127, v127
	v_mul_f32_e32 v117, v129, v129
	v_fmac_f32_e32 v116, v126, v126
	v_fmac_f32_e32 v117, v128, v128
	v_add_f32_e32 v116, v116, v117
	v_mul_f32_e32 v117, v131, v131
	v_fmac_f32_e32 v117, v130, v130
	v_lshlrev_b64 v[112:113], 11, v[214:215]
	v_add_f32_e32 v116, v116, v117
	v_mul_f32_e32 v117, v133, v133
	v_fmac_f32_e32 v117, v132, v132
	v_lshl_add_u64 v[112:113], s[24:25], 0, v[112:113]
	v_add_f32_e32 v136, v117, v116
	v_pk_mul_f32 v[116:117], v[202:203], v[128:129]
	v_pk_mul_f32 v[122:123], v[200:201], v[126:127]
	v_pk_mul_f32 v[128:129], v[198:199], v[130:131]
	v_cvt_pk_bf16_f32 v126, v122, v123
	v_cvt_pk_bf16_f32 v127, v116, v117
	v_lshl_add_u64 v[112:113], v[192:193], 1, v[112:113]
	v_pk_mul_f32 v[132:133], v[208:209], v[132:133]
	v_cvt_pk_bf16_f32 v128, v128, v129
	v_mul_f32_e32 v116, v125, v125
	v_cvt_pk_bf16_f32 v129, v132, v133
	global_store_dwordx4 v[112:113], v[126:129], off
	v_fmac_f32_e32 v116, v124, v124
	v_pk_fma_f32 v[122:123], v[114:115], v[62:63], v[146:147]
	v_pk_fma_f32 v[126:127], v[118:119], v[50:51], v[150:151]
	global_store_dwordx4 v[134:135], v[124:127], off offset:512
	global_store_dwordx4 v[134:135], v[120:123], off offset:528
	v_mul_f32_e32 v117, v127, v127
	v_fmac_f32_e32 v117, v126, v126
	v_add_f32_e32 v116, v116, v117
	v_mul_f32_e32 v117, v121, v121
	v_fmac_f32_e32 v117, v120, v120
	v_add_f32_e32 v116, v116, v117
	v_mul_f32_e32 v117, v123, v123
	v_fmac_f32_e32 v117, v122, v122
	v_add_f32_e32 v116, v117, v116
	v_add_f32_e32 v130, v136, v116
	v_pk_mul_f32 v[116:117], v[204:205], v[126:127]
	v_pk_mul_f32 v[126:127], v[196:197], v[124:125]
	v_pk_mul_f32 v[128:129], v[194:195], v[120:121]
	v_pk_mul_f32 v[122:123], v[206:207], v[122:123]
	v_cvt_pk_bf16_f32 v126, v126, v127
	v_cvt_pk_bf16_f32 v127, v116, v117
	v_cvt_pk_bf16_f32 v128, v128, v129
	v_xor_b32_e32 v116, 32, v229
	v_cvt_pk_bf16_f32 v129, v122, v123
	global_store_dwordx4 v[112:113], v[126:129], off offset:256
	v_and_b32_e32 v113, 64, v229
	v_xor_b32_e32 v112, 16, v229
	v_add_u32_e32 v113, 64, v113
	v_cmp_lt_i32_e32 vcc, v112, v113
	s_nop 1
	v_cndmask_b32_e32 v112, v229, v112, vcc
	v_lshlrev_b32_e32 v112, 2, v112
	ds_bpermute_b32 v112, v112, v130
	v_cmp_lt_i32_e32 vcc, v116, v113
	s_waitcnt lgkmcnt(0)
	v_add_f32_e32 v112, v130, v112
	v_cndmask_b32_e32 v113, v229, v116, vcc
	v_lshlrev_b32_e32 v113, 2, v113
	ds_bpermute_b32 v113, v113, v112
	s_and_saveexec_b64 s[38:39], s[6:7]
	s_cbranch_execz .LBB0_1206
	v_lshl_add_u64 v[116:117], v[214:215], 2, s[26:27]
	s_waitcnt lgkmcnt(0)
	v_add_f32_e32 v112, v112, v113
	global_atomic_add_f32 v[116:117], v112, off

;     __device__ __forceinline__ void operator()(const f32x4 (&acc)[2][2][4][2], const Unit& u, int wr, int wc, int fr, int fq) const {
;     ...
;         for (int q2 = 0; q2 < 4; ++q2) {
;             const int ai = q2 >> 1, m0 = (q2 & 1) * 2;
;             f32x4 pre[2][2][2];
; #pragma unroll
;             for (int mm = 0; mm < 2; ++mm) {
;                 const int row = pm * 256 + ai * 128 + wr * 64 + (m0 + mm) * 16 + fr;
;                 const float* src = isctx ? res_ctx + (size_t)(row - MLAT) * DM : res_lat + (size_t)row * DM;
; #pragma unroll
;                 for (int bj = 0; bj < 2; ++bj) { pre[mm][bj][0] = *(const f32x4*)(src + cb + 128 * bj); pre[mm][bj][1] = *(const f32x4*)(src + cb + 128 * bj + 4); }
;             }
; #pragma unroll
;             for (int mm = 0; mm < 2; ++mm) {
;                 const int m = m0 + mm;
;                 const int row = pm * 256 + ai * 128 + wr * 64 + m * 16 + fr;
;                 float* dst = isctx ? dst_ctx + (size_t)(row - MLAT) * DM : dst_lat + (size_t)row * DM;
;                 float ss = 0.f;
; #pragma unroll
;                 for (int bj = 0; bj < 2; ++bj) {
;                     const int col = cb + 128 * bj;
;                     const f32x4 x0 = pre[mm][bj][0] + gt[bj][0] * acc[ai][bj][m][0];
;                     const f32x4 x1 = pre[mm][bj][1] + gt[bj][1] * acc[ai][bj][m][1];
;                     *(f32x4*)(dst + col) = x0; *(f32x4*)(dst + col + 4) = x1;
.LBB0_1207:
	s_andn2_b64 vcc, exec, s[38:39]
	s_cbranch_vccnz .LBB0_1209
	v_pk_fma_f32 v[126:127], v[118:119], v[50:51], v[150:151]
	v_pk_fma_f32 v[122:123], v[114:115], v[62:63], v[146:147]
	global_store_dwordx4 v[134:135], v[124:127], off offset:512
	global_store_dwordx4 v[134:135], v[120:123], off offset:528
.LBB0_1209:
	v_or_b32_e32 v148, 32, v212
	v_add_u32_e32 v150, 0xffffc020, v212
	v_cndmask_b32_e64 v112, v148, v150, s[10:11]
	s_waitcnt lgkmcnt(0)
	v_ashrrev_i32_e32 v113, 31, v112
	v_lshlrev_b64 v[112:113], 12, v[112:113]
	v_lshl_add_u64 v[112:113], s[36:37], 0, v[112:113]
	v_lshl_add_u64 v[112:113], v[112:113], 0, v[210:211]
	v_or_b32_e32 v144, 48, v212
	v_add_u32_e32 v146, 0xffffc030, v212
	global_load_dwordx4 v[140:143], v[112:113], off
	global_load_dwordx4 v[136:139], v[112:113], off offset:16
	global_load_dwordx4 v[132:135], v[112:113], off offset:512
	global_load_dwordx4 v[128:131], v[112:113], off offset:528
	v_cndmask_b32_e64 v112, v144, v146, s[10:11]
	v_ashrrev_i32_e32 v113, 31, v112
	v_lshlrev_b64 v[112:113], 12, v[112:113]
	v_lshl_add_u64 v[112:113], s[36:37], 0, v[112:113]
	v_lshl_add_u64 v[112:113], v[112:113], 0, v[210:211]
	global_load_dwordx4 v[124:127], v[112:113], off
	global_load_dwordx4 v[120:123], v[112:113], off offset:16
	global_load_dwordx4 v[116:119], v[112:113], off offset:512
	s_nop 0
	global_load_dwordx4 v[112:115], v[112:113], off offset:528
	s_mov_b64 s[38:39], -1
	s_and_b64 vcc, exec, s[12:13]
	v_ashrrev_i32_e32 v149, 31, v148
	s_cbranch_vccnz .LBB0_1211
	v_lshlrev_b64 v[152:153], 12, v[148:149]
	v_lshl_add_u64 v[152:153], s[90:91], 0, v[152:153]
	s_mov_b64 s[38:39], 0

; __device__ __forceinline__ unsigned pkbf(float lo, float hi) { return pg8::cvt_pk_bf16(lo, hi); }
;     __device__ __forceinline__ void operator()(const f32x4 (&acc)[2][2][4][2], const Unit& u, int wr, int wc, int fr, int fq) const {
;     ...
;             for (int mm = 0; mm < 2; ++mm) {
;                 const int m = m0 + mm;
;                 const int row = pm * 256 + ai * 128 + wr * 64 + m * 16 + fr;
;                 float* dst = isctx ? dst_ctx + (size_t)(row - MLAT) * DM : dst_lat + (size_t)row * DM;
;                 float ss = 0.f;
; #pragma unroll
;                 for (int bj = 0; bj < 2; ++bj) {
;                     const int col = cb + 128 * bj;
;                     const f32x4 x0 = pre[mm][bj][0] + gt[bj][0] * acc[ai][bj][m][0];
;                     const f32x4 x1 = pre[mm][bj][1] + gt[bj][1] * acc[ai][bj][m][1];
;                     *(f32x4*)(dst + col) = x0; *(f32x4*)(dst + col + 4) = x1;
;                     if (nxt) {
;                         ss += (x0[0] * x0[0] + x0[1] * x0[1]) + (x0[2] * x0[2] + x0[3] * x0[3]) + (x1[0] * x1[0] + x1[1] * x1[1]) + (x1[2] * x1[2] + x1[3] * x1[3]);
;                         const f32x4 y0 = x0 * gs[bj][0], y1 = x1 * gs[bj][1];
;                         u32x4 w; w.x = pkbf(y0[0], y0[1]); w.y = pkbf(y0[2], y0[3]); w.z = pkbf(y1[0], y1[1]); w.w = pkbf(y1[2], y1[3]);
;                         *(u32x4*)(xg + (size_t)row * DM + col) = w;
;                     }
;                 }
;                 if (nxt) { ss += __shfl_xor(ss, 16); ss += __shfl_xor(ss, 32); if (fq == 0) unsafeAtomicAdd(rowsq_next + row, ss); }
.LBB0_1213:
	s_waitcnt vmcnt(0) lgkmcnt(0)
	v_pk_fma_f32 v[142:143], v[110:111], v[66:67], v[142:143]
	v_pk_fma_f32 v[140:141], v[108:109], v[64:65], v[140:141]
	v_pk_fma_f32 v[138:139], v[106:107], v[70:71], v[138:139]
	v_pk_fma_f32 v[136:137], v[104:105], v[68:69], v[136:137]
	v_lshl_add_u64 v[150:151], v[192:193], 2, v[152:153]
	s_mov_b64 s[38:39], -1
	s_and_b64 vcc, exec, s[4:5]
	v_pk_fma_f32 v[108:109], v[100:101], v[48:49], v[132:133]
	v_pk_fma_f32 v[104:105], v[96:97], v[60:61], v[128:129]
	global_store_dwordx4 v[150:151], v[140:143], off
	global_store_dwordx4 v[150:151], v[136:139], off offset:16
	s_cbranch_vccnz .LBB0_1217
	v_mul_f32_e32 v100, v141, v141
	v_mul_f32_e32 v101, v143, v143
	v_fmac_f32_e32 v100, v140, v140
	v_fmac_f32_e32 v101, v142, v142
	v_add_f32_e32 v100, v100, v101
	v_mul_f32_e32 v101, v137, v137
	v_fmac_f32_e32 v101, v136, v136
	v_add_f32_e32 v100, v100, v101
	v_mul_f32_e32 v101, v139, v139
	v_fmac_f32_e32 v101, v138, v138
	v_pk_mul_f32 v[110:111], v[208:209], v[138:139]
	v_add_f32_e32 v132, v101, v100
	v_pk_mul_f32 v[100:101], v[202:203], v[142:143]
	v_pk_mul_f32 v[106:107], v[200:201], v[140:141]
	v_pk_mul_f32 v[128:129], v[198:199], v[136:137]
	v_cvt_pk_bf16_f32 v136, v106, v107
	v_cvt_pk_bf16_f32 v137, v100, v101
	v_mul_f32_e32 v100, v109, v109
	v_cvt_pk_bf16_f32 v138, v128, v129
	v_cvt_pk_bf16_f32 v139, v110, v111
	v_pk_fma_f32 v[110:111], v[102:103], v[50:51], v[134:135]
	v_fmac_f32_e32 v100, v108, v108
	v_mul_f32_e32 v101, v111, v111
	v_fmac_f32_e32 v101, v110, v110
	v_add_f32_e32 v100, v100, v101
	v_mul_f32_e32 v101, v105, v105
	v_pk_fma_f32 v[106:107], v[98:99], v[62:63], v[130:131]
	v_fmac_f32_e32 v101, v104, v104
	v_lshlrev_b64 v[96:97], 11, v[148:149]
	v_add_f32_e32 v100, v100, v101
	v_mul_f32_e32 v101, v107, v107
	v_lshl_add_u64 v[96:97], s[24:25], 0, v[96:97]
	v_fmac_f32_e32 v101, v106, v106
	v_lshl_add_u64 v[96:97], v[192:193], 1, v[96:97]
	v_add_f32_e32 v100, v101, v100
	global_store_dwordx4 v[96:97], v[136:139], off
	global_store_dwordx4 v[150:151], v[108:111], off offset:512
	global_store_dwordx4 v[150:151], v[104:107], off offset:528
	v_add_f32_e32 v132, v132, v100
	v_pk_mul_f32 v[100:101], v[204:205], v[110:111]
	v_pk_mul_f32 v[110:111], v[196:197], v[108:109]
	v_pk_mul_f32 v[106:107], v[206:207], v[106:107]
	v_pk_mul_f32 v[128:129], v[194:195], v[104:105]
	v_cvt_pk_bf16_f32 v136, v110, v111
	v_cvt_pk_bf16_f32 v137, v100, v101
	v_xor_b32_e32 v100, 32, v229
	v_cvt_pk_bf16_f32 v138, v128, v129
	v_cvt_pk_bf16_f32 v139, v106, v107
	global_store_dwordx4 v[96:97], v[136:139], off offset:256
	v_and_b32_e32 v97, 64, v229
	v_xor_b32_e32 v96, 16, v229
	v_add_u32_e32 v97, 64, v97
	v_cmp_lt_i32_e32 vcc, v96, v97
	s_nop 1
	v_cndmask_b32_e32 v96, v229, v96, vcc
	v_lshlrev_b32_e32 v96, 2, v96
	ds_bpermute_b32 v96, v96, v132
	v_cmp_lt_i32_e32 vcc, v100, v97
	s_waitcnt lgkmcnt(0)
	v_add_f32_e32 v96, v132, v96
	v_cndmask_b32_e32 v97, v229, v100, vcc
	v_lshlrev_b32_e32 v97, 2, v97
	ds_bpermute_b32 v97, v97, v96
	s_and_saveexec_b64 s[38:39], s[6:7]
	s_cbranch_execz .LBB0_1216
	v_lshl_add_u64 v[100:101], v[148:149], 2, s[26:27]
	s_waitcnt lgkmcnt(0)
	v_add_f32_e32 v96, v96, v97
	global_atomic_add_f32 v[100:101], v96, off

;     __device__ __forceinline__ void operator()(const f32x4 (&acc)[2][2][4][2], const Unit& u, int wr, int wc, int fr, int fq) const {
;     ...
;                     const f32x4 x0 = pre[mm][bj][0] + gt[bj][0] * acc[ai][bj][m][0];
;                     const f32x4 x1 = pre[mm][bj][1] + gt[bj][1] * acc[ai][bj][m][1];
;                     *(f32x4*)(dst + col) = x0; *(f32x4*)(dst + col + 4) = x1;
.LBB0_1218:
	v_pk_fma_f32 v[110:111], v[102:103], v[50:51], v[134:135]
	v_pk_fma_f32 v[106:107], v[98:99], v[62:63], v[130:131]
	global_store_dwordx4 v[150:151], v[108:111], off offset:512
	global_store_dwordx4 v[150:151], v[104:107], off offset:528

; __device__ __forceinline__ unsigned pkbf(float lo, float hi) { return pg8::cvt_pk_bf16(lo, hi); }
;     __device__ __forceinline__ void operator()(const f32x4 (&acc)[2][2][4][2], const Unit& u, int wr, int wc, int fr, int fq) const {
;     ...
;             for (int mm = 0; mm < 2; ++mm) {
;                 const int m = m0 + mm;
;                 const int row = pm * 256 + ai * 128 + wr * 64 + m * 16 + fr;
;                 float* dst = isctx ? dst_ctx + (size_t)(row - MLAT) * DM : dst_lat + (size_t)row * DM;
;                 float ss = 0.f;
; #pragma unroll
;                 for (int bj = 0; bj < 2; ++bj) {
;                     const int col = cb + 128 * bj;
;                     const f32x4 x0 = pre[mm][bj][0] + gt[bj][0] * acc[ai][bj][m][0];
;                     const f32x4 x1 = pre[mm][bj][1] + gt[bj][1] * acc[ai][bj][m][1];
;                     *(f32x4*)(dst + col) = x0; *(f32x4*)(dst + col + 4) = x1;
;                     if (nxt) {
;                         ss += (x0[0] * x0[0] + x0[1] * x0[1]) + (x0[2] * x0[2] + x0[3] * x0[3]) + (x1[0] * x1[0] + x1[1] * x1[1]) + (x1[2] * x1[2] + x1[3] * x1[3]);
;                         const f32x4 y0 = x0 * gs[bj][0], y1 = x1 * gs[bj][1];
;                         u32x4 w; w.x = pkbf(y0[0], y0[1]); w.y = pkbf(y0[2], y0[3]); w.z = pkbf(y1[0], y1[1]); w.w = pkbf(y1[2], y1[3]);
;                         *(u32x4*)(xg + (size_t)row * DM + col) = w;
;                     }
;                 }
;                 if (nxt) { ss += __shfl_xor(ss, 16); ss += __shfl_xor(ss, 32); if (fq == 0) unsafeAtomicAdd(rowsq_next + row, ss); }
.LBB0_1223:
	s_waitcnt lgkmcnt(0)
	v_pk_fma_f32 v[96:97], v[94:95], v[66:67], v[126:127]
	v_pk_fma_f32 v[94:95], v[92:93], v[64:65], v[124:125]
	v_pk_fma_f32 v[100:101], v[90:91], v[70:71], v[122:123]
	v_pk_fma_f32 v[98:99], v[88:89], v[68:69], v[120:121]
	v_lshl_add_u64 v[102:103], v[192:193], 2, v[102:103]
	s_mov_b64 s[38:39], -1
	s_and_b64 vcc, exec, s[4:5]
	v_pk_fma_f32 v[92:93], v[84:85], v[48:49], v[116:117]
	v_pk_fma_f32 v[88:89], v[80:81], v[60:61], v[112:113]
	global_store_dwordx4 v[102:103], v[94:97], off
	global_store_dwordx4 v[102:103], v[98:101], off offset:16
	s_cbranch_vccnz .LBB0_1227
	v_mul_f32_e32 v84, v95, v95
	v_mul_f32_e32 v85, v97, v97
	v_fmac_f32_e32 v84, v94, v94
	v_fmac_f32_e32 v85, v96, v96
	v_add_f32_e32 v84, v84, v85
	v_mul_f32_e32 v85, v99, v99
	v_fmac_f32_e32 v85, v98, v98
	v_lshlrev_b64 v[80:81], 11, v[144:145]
	v_add_f32_e32 v84, v84, v85
	v_mul_f32_e32 v85, v101, v101
	v_fmac_f32_e32 v85, v100, v100
	v_lshl_add_u64 v[80:81], s[24:25], 0, v[80:81]
	v_add_f32_e32 v104, v85, v84
	v_pk_mul_f32 v[84:85], v[202:203], v[96:97]
	v_pk_mul_f32 v[90:91], v[200:201], v[94:95]
	v_pk_mul_f32 v[96:97], v[198:199], v[98:99]
	v_cvt_pk_bf16_f32 v94, v90, v91
	v_cvt_pk_bf16_f32 v95, v84, v85
	v_lshl_add_u64 v[80:81], v[192:193], 1, v[80:81]
	v_pk_mul_f32 v[100:101], v[208:209], v[100:101]
	v_cvt_pk_bf16_f32 v96, v96, v97
	v_mul_f32_e32 v84, v93, v93
	v_cvt_pk_bf16_f32 v97, v100, v101
	global_store_dwordx4 v[80:81], v[94:97], off
	v_fmac_f32_e32 v84, v92, v92
	v_pk_fma_f32 v[90:91], v[82:83], v[62:63], v[114:115]
	v_pk_fma_f32 v[94:95], v[86:87], v[50:51], v[118:119]
	global_store_dwordx4 v[102:103], v[92:95], off offset:512
	global_store_dwordx4 v[102:103], v[88:91], off offset:528
	v_mul_f32_e32 v85, v95, v95
	v_fmac_f32_e32 v85, v94, v94
	v_add_f32_e32 v84, v84, v85
	v_mul_f32_e32 v85, v89, v89
	v_fmac_f32_e32 v85, v88, v88
	v_add_f32_e32 v84, v84, v85
	v_mul_f32_e32 v85, v91, v91
	v_fmac_f32_e32 v85, v90, v90
	v_add_f32_e32 v84, v85, v84
	v_add_f32_e32 v98, v104, v84
	v_pk_mul_f32 v[84:85], v[204:205], v[94:95]
	v_pk_mul_f32 v[94:95], v[196:197], v[92:93]
	v_pk_mul_f32 v[96:97], v[194:195], v[88:89]
	v_pk_mul_f32 v[90:91], v[206:207], v[90:91]
	v_cvt_pk_bf16_f32 v94, v94, v95
	v_cvt_pk_bf16_f32 v95, v84, v85
	v_cvt_pk_bf16_f32 v96, v96, v97
	v_xor_b32_e32 v84, 32, v229
	v_cvt_pk_bf16_f32 v97, v90, v91
	global_store_dwordx4 v[80:81], v[94:97], off offset:256
	v_and_b32_e32 v81, 64, v229
	v_xor_b32_e32 v80, 16, v229
	v_add_u32_e32 v81, 64, v81
	v_cmp_lt_i32_e32 vcc, v80, v81
	s_nop 1
	v_cndmask_b32_e32 v80, v229, v80, vcc
	v_lshlrev_b32_e32 v80, 2, v80
	ds_bpermute_b32 v80, v80, v98
	v_cmp_lt_i32_e32 vcc, v84, v81
	s_waitcnt lgkmcnt(0)
	v_add_f32_e32 v80, v98, v80
	v_cndmask_b32_e32 v81, v229, v84, vcc
	v_lshlrev_b32_e32 v81, 2, v81
	ds_bpermute_b32 v81, v81, v80
	s_and_saveexec_b64 s[38:39], s[6:7]
	s_cbranch_execz .LBB0_1226
	v_lshl_add_u64 v[84:85], v[144:145], 2, s[26:27]
	s_waitcnt lgkmcnt(0)
	v_add_f32_e32 v80, v80, v81
	global_atomic_add_f32 v[84:85], v80, off

;     __device__ __forceinline__ void operator()(const f32x4 (&acc)[2][2][4][2], const Unit& u, int wr, int wc, int fr, int fq) const {
;     ...
;         for (int q2 = 0; q2 < 4; ++q2) {
;             const int ai = q2 >> 1, m0 = (q2 & 1) * 2;
;             f32x4 pre[2][2][2];
; #pragma unroll
;             for (int mm = 0; mm < 2; ++mm) {
;                 const int row = pm * 256 + ai * 128 + wr * 64 + (m0 + mm) * 16 + fr;
;                 const float* src = isctx ? res_ctx + (size_t)(row - MLAT) * DM : res_lat + (size_t)row * DM;
; #pragma unroll
;                 for (int bj = 0; bj < 2; ++bj) { pre[mm][bj][0] = *(const f32x4*)(src + cb + 128 * bj); pre[mm][bj][1] = *(const f32x4*)(src + cb + 128 * bj + 4); }
;             }
; #pragma unroll
;             for (int mm = 0; mm < 2; ++mm) {
;                 const int m = m0 + mm;
;                 const int row = pm * 256 + ai * 128 + wr * 64 + m * 16 + fr;
;                 float* dst = isctx ? dst_ctx + (size_t)(row - MLAT) * DM : dst_lat + (size_t)row * DM;
;                 float ss = 0.f;
; #pragma unroll
;                 for (int bj = 0; bj < 2; ++bj) {
;                     const int col = cb + 128 * bj;
;                     const f32x4 x0 = pre[mm][bj][0] + gt[bj][0] * acc[ai][bj][m][0];
;                     const f32x4 x1 = pre[mm][bj][1] + gt[bj][1] * acc[ai][bj][m][1];
;                     *(f32x4*)(dst + col) = x0; *(f32x4*)(dst + col + 4) = x1;
.LBB0_1227:
	s_andn2_b64 vcc, exec, s[38:39]
	s_cbranch_vccnz .LBB0_1229
	v_pk_fma_f32 v[94:95], v[86:87], v[50:51], v[118:119]
	v_pk_fma_f32 v[90:91], v[82:83], v[62:63], v[114:115]
	global_store_dwordx4 v[102:103], v[92:95], off offset:512
	global_store_dwordx4 v[102:103], v[88:91], off offset:528
.LBB0_1229:
	v_add_u32_e32 v116, 0x80, v212
	v_add_u32_e32 v118, 0xffffc080, v212
	v_cndmask_b32_e64 v80, v116, v118, s[10:11]
	s_waitcnt lgkmcnt(0)
	v_ashrrev_i32_e32 v81, 31, v80
	v_lshlrev_b64 v[80:81], 12, v[80:81]
	v_lshl_add_u64 v[80:81], s[36:37], 0, v[80:81]
	v_lshl_add_u64 v[80:81], v[80:81], 0, v[210:211]
	v_add_u32_e32 v112, 0x90, v212
	v_add_u32_e32 v114, 0xffffc090, v212
	global_load_dwordx4 v[108:111], v[80:81], off
	global_load_dwordx4 v[104:107], v[80:81], off offset:16
	global_load_dwordx4 v[100:103], v[80:81], off offset:512
	global_load_dwordx4 v[96:99], v[80:81], off offset:528
	v_cndmask_b32_e64 v80, v112, v114, s[10:11]
	v_ashrrev_i32_e32 v81, 31, v80
	v_lshlrev_b64 v[80:81], 12, v[80:81]
	v_lshl_add_u64 v[80:81], s[36:37], 0, v[80:81]
	v_lshl_add_u64 v[80:81], v[80:81], 0, v[210:211]
	global_load_dwordx4 v[92:95], v[80:81], off
	global_load_dwordx4 v[88:91], v[80:81], off offset:16
	global_load_dwordx4 v[84:87], v[80:81], off offset:512
	s_nop 0
	global_load_dwordx4 v[80:83], v[80:81], off offset:528
	s_mov_b64 s[38:39], -1
	s_and_b64 vcc, exec, s[12:13]
	v_ashrrev_i32_e32 v117, 31, v116
	s_cbranch_vccnz .LBB0_1231
	v_lshlrev_b64 v[120:121], 12, v[116:117]
	v_lshl_add_u64 v[120:121], s[90:91], 0, v[120:121]
	s_mov_b64 s[38:39], 0

; __device__ __forceinline__ unsigned pkbf(float lo, float hi) { return pg8::cvt_pk_bf16(lo, hi); }
;     __device__ __forceinline__ void operator()(const f32x4 (&acc)[2][2][4][2], const Unit& u, int wr, int wc, int fr, int fq) const {
;     ...
;             for (int mm = 0; mm < 2; ++mm) {
;                 const int m = m0 + mm;
;                 const int row = pm * 256 + ai * 128 + wr * 64 + m * 16 + fr;
;                 float* dst = isctx ? dst_ctx + (size_t)(row - MLAT) * DM : dst_lat + (size_t)row * DM;
;                 float ss = 0.f;
; #pragma unroll
;                 for (int bj = 0; bj < 2; ++bj) {
;                     const int col = cb + 128 * bj;
;                     const f32x4 x0 = pre[mm][bj][0] + gt[bj][0] * acc[ai][bj][m][0];
;                     const f32x4 x1 = pre[mm][bj][1] + gt[bj][1] * acc[ai][bj][m][1];
;                     *(f32x4*)(dst + col) = x0; *(f32x4*)(dst + col + 4) = x1;
;                     if (nxt) {
;                         ss += (x0[0] * x0[0] + x0[1] * x0[1]) + (x0[2] * x0[2] + x0[3] * x0[3]) + (x1[0] * x1[0] + x1[1] * x1[1]) + (x1[2] * x1[2] + x1[3] * x1[3]);
;                         const f32x4 y0 = x0 * gs[bj][0], y1 = x1 * gs[bj][1];
;                         u32x4 w; w.x = pkbf(y0[0], y0[1]); w.y = pkbf(y0[2], y0[3]); w.z = pkbf(y1[0], y1[1]); w.w = pkbf(y1[2], y1[3]);
;                         *(u32x4*)(xg + (size_t)row * DM + col) = w;
;                     }
;                 }
;                 if (nxt) { ss += __shfl_xor(ss, 16); ss += __shfl_xor(ss, 32); if (fq == 0) unsafeAtomicAdd(rowsq_next + row, ss); }
.LBB0_1233:
	s_waitcnt vmcnt(0) lgkmcnt(0)
	v_pk_fma_f32 v[110:111], v[78:79], v[66:67], v[110:111]
	v_pk_fma_f32 v[108:109], v[76:77], v[64:65], v[108:109]
	v_pk_fma_f32 v[106:107], v[74:75], v[70:71], v[106:107]
	v_pk_fma_f32 v[104:105], v[72:73], v[68:69], v[104:105]
	v_lshl_add_u64 v[118:119], v[192:193], 2, v[120:121]
	s_mov_b64 s[38:39], -1
	s_and_b64 vcc, exec, s[4:5]
	v_pk_fma_f32 v[76:77], v[56:57], v[48:49], v[100:101]
	v_pk_fma_f32 v[72:73], v[52:53], v[60:61], v[96:97]
	global_store_dwordx4 v[118:119], v[108:111], off
	global_store_dwordx4 v[118:119], v[104:107], off offset:16
	s_cbranch_vccnz .LBB0_1237
	v_mul_f32_e32 v56, v109, v109
	v_mul_f32_e32 v57, v111, v111
	v_fmac_f32_e32 v56, v108, v108
	v_fmac_f32_e32 v57, v110, v110
	v_add_f32_e32 v56, v56, v57
	v_mul_f32_e32 v57, v105, v105
	v_fmac_f32_e32 v57, v104, v104
	v_add_f32_e32 v56, v56, v57
	v_mul_f32_e32 v57, v107, v107
	v_fmac_f32_e32 v57, v106, v106
	v_pk_mul_f32 v[78:79], v[208:209], v[106:107]
	v_add_f32_e32 v100, v57, v56
	v_pk_mul_f32 v[56:57], v[202:203], v[110:111]
	v_pk_mul_f32 v[74:75], v[200:201], v[108:109]
	v_pk_mul_f32 v[96:97], v[198:199], v[104:105]
	v_cvt_pk_bf16_f32 v104, v74, v75
	v_cvt_pk_bf16_f32 v105, v56, v57
	v_mul_f32_e32 v56, v77, v77
	v_cvt_pk_bf16_f32 v106, v96, v97
	v_cvt_pk_bf16_f32 v107, v78, v79
	v_pk_fma_f32 v[78:79], v[58:59], v[50:51], v[102:103]
	v_fmac_f32_e32 v56, v76, v76
	v_mul_f32_e32 v57, v79, v79
	v_fmac_f32_e32 v57, v78, v78
	v_add_f32_e32 v56, v56, v57
	v_mul_f32_e32 v57, v73, v73
	v_pk_fma_f32 v[74:75], v[54:55], v[62:63], v[98:99]
	v_fmac_f32_e32 v57, v72, v72
	v_lshlrev_b64 v[52:53], 11, v[116:117]
	v_add_f32_e32 v56, v56, v57
	v_mul_f32_e32 v57, v75, v75
	v_lshl_add_u64 v[52:53], s[24:25], 0, v[52:53]
	v_fmac_f32_e32 v57, v74, v74
	v_lshl_add_u64 v[52:53], v[192:193], 1, v[52:53]
	v_add_f32_e32 v56, v57, v56
	global_store_dwordx4 v[52:53], v[104:107], off
	global_store_dwordx4 v[118:119], v[76:79], off offset:512
	global_store_dwordx4 v[118:119], v[72:75], off offset:528
	v_add_f32_e32 v100, v100, v56
	v_pk_mul_f32 v[56:57], v[204:205], v[78:79]
	v_pk_mul_f32 v[78:79], v[196:197], v[76:77]
	v_pk_mul_f32 v[74:75], v[206:207], v[74:75]
	v_pk_mul_f32 v[96:97], v[194:195], v[72:73]
	v_cvt_pk_bf16_f32 v104, v78, v79
	v_cvt_pk_bf16_f32 v105, v56, v57
	v_xor_b32_e32 v56, 32, v229
	v_cvt_pk_bf16_f32 v106, v96, v97
	v_cvt_pk_bf16_f32 v107, v74, v75
	global_store_dwordx4 v[52:53], v[104:107], off offset:256
	v_and_b32_e32 v53, 64, v229
	v_xor_b32_e32 v52, 16, v229
	v_add_u32_e32 v53, 64, v53
	v_cmp_lt_i32_e32 vcc, v52, v53
	s_nop 1
	v_cndmask_b32_e32 v52, v229, v52, vcc
	v_lshlrev_b32_e32 v52, 2, v52
	ds_bpermute_b32 v52, v52, v100
	v_cmp_lt_i32_e32 vcc, v56, v53
	s_waitcnt lgkmcnt(0)
	v_add_f32_e32 v52, v100, v52
	v_cndmask_b32_e32 v53, v229, v56, vcc
	v_lshlrev_b32_e32 v53, 2, v53
	ds_bpermute_b32 v53, v53, v52
	s_and_saveexec_b64 s[38:39], s[6:7]
	s_cbranch_execz .LBB0_1236
	v_lshl_add_u64 v[56:57], v[116:117], 2, s[26:27]
	s_waitcnt lgkmcnt(0)
	v_add_f32_e32 v52, v52, v53
	global_atomic_add_f32 v[56:57], v52, off

;     __device__ __forceinline__ void operator()(const f32x4 (&acc)[2][2][4][2], const Unit& u, int wr, int wc, int fr, int fq) const {
;     ...
;                     const f32x4 x0 = pre[mm][bj][0] + gt[bj][0] * acc[ai][bj][m][0];
;                     const f32x4 x1 = pre[mm][bj][1] + gt[bj][1] * acc[ai][bj][m][1];
;                     *(f32x4*)(dst + col) = x0; *(f32x4*)(dst + col + 4) = x1;
.LBB0_1238:
	v_pk_fma_f32 v[78:79], v[58:59], v[50:51], v[102:103]
	v_pk_fma_f32 v[74:75], v[54:55], v[62:63], v[98:99]
	global_store_dwordx4 v[118:119], v[76:79], off offset:512
	global_store_dwordx4 v[118:119], v[72:75], off offset:528

; __device__ __forceinline__ unsigned pkbf(float lo, float hi) { return pg8::cvt_pk_bf16(lo, hi); }
;     __device__ __forceinline__ void operator()(const f32x4 (&acc)[2][2][4][2], const Unit& u, int wr, int wc, int fr, int fq) const {
;     ...
;             for (int mm = 0; mm < 2; ++mm) {
;                 const int m = m0 + mm;
;                 const int row = pm * 256 + ai * 128 + wr * 64 + m * 16 + fr;
;                 float* dst = isctx ? dst_ctx + (size_t)(row - MLAT) * DM : dst_lat + (size_t)row * DM;
;                 float ss = 0.f;
; #pragma unroll
;                 for (int bj = 0; bj < 2; ++bj) {
;                     const int col = cb + 128 * bj;
;                     const f32x4 x0 = pre[mm][bj][0] + gt[bj][0] * acc[ai][bj][m][0];
;                     const f32x4 x1 = pre[mm][bj][1] + gt[bj][1] * acc[ai][bj][m][1];
;                     *(f32x4*)(dst + col) = x0; *(f32x4*)(dst + col + 4) = x1;
;                     if (nxt) {
;                         ss += (x0[0] * x0[0] + x0[1] * x0[1]) + (x0[2] * x0[2] + x0[3] * x0[3]) + (x1[0] * x1[0] + x1[1] * x1[1]) + (x1[2] * x1[2] + x1[3] * x1[3]);
;                         const f32x4 y0 = x0 * gs[bj][0], y1 = x1 * gs[bj][1];
;                         u32x4 w; w.x = pkbf(y0[0], y0[1]); w.y = pkbf(y0[2], y0[3]); w.z = pkbf(y1[0], y1[1]); w.w = pkbf(y1[2], y1[3]);
;                         *(u32x4*)(xg + (size_t)row * DM + col) = w;
;                     }
;                 }
;                 if (nxt) { ss += __shfl_xor(ss, 16); ss += __shfl_xor(ss, 32); if (fq == 0) unsafeAtomicAdd(rowsq_next + row, ss); }
.LBB0_1243:
	v_pk_fma_f32 v[54:55], v[46:47], v[66:67], v[94:95]
	s_waitcnt lgkmcnt(0)
	v_pk_fma_f32 v[52:53], v[44:45], v[64:65], v[92:93]
	v_pk_fma_f32 v[58:59], v[42:43], v[70:71], v[90:91]
	v_pk_fma_f32 v[56:57], v[40:41], v[68:69], v[88:89]
	v_lshl_add_u64 v[72:73], v[192:193], 2, v[72:73]
	s_mov_b64 s[38:39], -1
	s_and_b64 vcc, exec, s[4:5]
	v_pk_fma_f32 v[44:45], v[36:37], v[48:49], v[84:85]
	v_pk_fma_f32 v[40:41], v[32:33], v[60:61], v[80:81]
	global_store_dwordx4 v[72:73], v[52:55], off
	global_store_dwordx4 v[72:73], v[56:59], off offset:16
	s_cbranch_vccnz .LBB0_1247
	v_mul_f32_e32 v36, v53, v53
	v_mul_f32_e32 v37, v55, v55
	v_fmac_f32_e32 v36, v52, v52
	v_fmac_f32_e32 v37, v54, v54
	v_add_f32_e32 v36, v36, v37
	v_mul_f32_e32 v37, v57, v57
	v_fmac_f32_e32 v37, v56, v56
	v_add_f32_e32 v36, v36, v37
	v_mul_f32_e32 v37, v59, v59
	v_fmac_f32_e32 v37, v58, v58
	v_add_f32_e32 v74, v37, v36
	v_pk_mul_f32 v[36:37], v[202:203], v[54:55]
	v_pk_mul_f32 v[46:47], v[208:209], v[58:59]
	v_pk_mul_f32 v[54:55], v[198:199], v[56:57]
	v_pk_mul_f32 v[42:43], v[200:201], v[52:53]
	v_lshlrev_b64 v[32:33], 11, v[112:113]
	v_cvt_pk_bf16_f32 v52, v42, v43
	v_cvt_pk_bf16_f32 v53, v36, v37
	v_cvt_pk_bf16_f32 v54, v54, v55
	v_cvt_pk_bf16_f32 v55, v46, v47
	v_pk_fma_f32 v[46:47], v[38:39], v[50:51], v[86:87]
	v_mul_f32_e32 v36, v45, v45
	v_mul_f32_e32 v37, v47, v47
	v_fmac_f32_e32 v36, v44, v44
	v_fmac_f32_e32 v37, v46, v46
	v_add_f32_e32 v36, v36, v37
	v_mul_f32_e32 v37, v41, v41
	v_pk_fma_f32 v[42:43], v[34:35], v[62:63], v[82:83]
	v_fmac_f32_e32 v37, v40, v40
	v_lshl_add_u64 v[32:33], s[24:25], 0, v[32:33]
	v_add_f32_e32 v36, v36, v37
	v_mul_f32_e32 v37, v43, v43
	v_lshl_add_u64 v[32:33], v[192:193], 1, v[32:33]
	v_fmac_f32_e32 v37, v42, v42
	global_store_dwordx4 v[32:33], v[52:55], off
	v_add_f32_e32 v36, v37, v36
	global_store_dwordx4 v[72:73], v[44:47], off offset:512
	global_store_dwordx4 v[72:73], v[40:43], off offset:528
	v_pk_mul_f32 v[54:55], v[194:195], v[40:41]
	v_add_f32_e32 v56, v74, v36
	v_pk_mul_f32 v[36:37], v[204:205], v[46:47]
	v_pk_mul_f32 v[46:47], v[196:197], v[44:45]
	v_pk_mul_f32 v[42:43], v[206:207], v[42:43]
	v_cvt_pk_bf16_f32 v52, v46, v47
	v_cvt_pk_bf16_f32 v53, v36, v37
	v_cvt_pk_bf16_f32 v54, v54, v55
	v_xor_b32_e32 v36, 32, v229
	v_cvt_pk_bf16_f32 v55, v42, v43
	global_store_dwordx4 v[32:33], v[52:55], off offset:256
	v_and_b32_e32 v33, 64, v229
	v_xor_b32_e32 v32, 16, v229
	v_add_u32_e32 v33, 64, v33
	v_cmp_lt_i32_e32 vcc, v32, v33
	s_nop 1
	v_cndmask_b32_e32 v32, v229, v32, vcc
	v_lshlrev_b32_e32 v32, 2, v32
	ds_bpermute_b32 v32, v32, v56
	v_cmp_lt_i32_e32 vcc, v36, v33
	s_waitcnt lgkmcnt(0)
	v_add_f32_e32 v32, v56, v32
	v_cndmask_b32_e32 v33, v229, v36, vcc
	v_lshlrev_b32_e32 v33, 2, v33
	ds_bpermute_b32 v33, v33, v32
	s_and_saveexec_b64 s[38:39], s[6:7]
	s_cbranch_execz .LBB0_1246
	v_lshl_add_u64 v[36:37], v[112:113], 2, s[26:27]
	s_waitcnt lgkmcnt(0)
	v_add_f32_e32 v32, v32, v33
	global_atomic_add_f32 v[36:37], v32, off

;     __device__ __forceinline__ void operator()(const f32x4 (&acc)[2][2][4][2], const Unit& u, int wr, int wc, int fr, int fq) const {
;     ...
;             for (int mm = 0; mm < 2; ++mm) {
;                 const int row = pm * 256 + ai * 128 + wr * 64 + (m0 + mm) * 16 + fr;
;                 const float* src = isctx ? res_ctx + (size_t)(row - MLAT) * DM : res_lat + (size_t)row * DM;
; #pragma unroll
;                 for (int bj = 0; bj < 2; ++bj) { pre[mm][bj][0] = *(const f32x4*)(src + cb + 128 * bj); pre[mm][bj][1] = *(const f32x4*)(src + cb + 128 * bj + 4); }
;             }
;     ...
;                     const f32x4 x0 = pre[mm][bj][0] + gt[bj][0] * acc[ai][bj][m][0];
;                     const f32x4 x1 = pre[mm][bj][1] + gt[bj][1] * acc[ai][bj][m][1];
;                     *(f32x4*)(dst + col) = x0; *(f32x4*)(dst + col + 4) = x1;
.LBB0_1247:
	s_andn2_b64 vcc, exec, s[38:39]
	s_cbranch_vccnz .LBB0_1249
	v_pk_fma_f32 v[46:47], v[38:39], v[50:51], v[86:87]
	v_pk_fma_f32 v[42:43], v[34:35], v[62:63], v[82:83]
	global_store_dwordx4 v[72:73], v[44:47], off offset:512
	global_store_dwordx4 v[72:73], v[40:43], off offset:528
.LBB0_1249:
	v_add_u32_e32 v84, 0xa0, v212
	v_add_u32_e32 v86, 0xffffc0a0, v212
	v_cndmask_b32_e64 v32, v84, v86, s[10:11]
	s_waitcnt lgkmcnt(0)
	v_ashrrev_i32_e32 v33, 31, v32
	v_lshlrev_b64 v[32:33], 12, v[32:33]
	v_lshl_add_u64 v[32:33], s[36:37], 0, v[32:33]
	v_lshl_add_u64 v[32:33], v[32:33], 0, v[210:211]
	v_add_u32_e32 v80, 0xb0, v212
	v_add_u32_e32 v82, 0xffffc0b0, v212
	global_load_dwordx4 v[76:79], v[32:33], off
	global_load_dwordx4 v[72:75], v[32:33], off offset:16
	global_load_dwordx4 v[56:59], v[32:33], off offset:512
	global_load_dwordx4 v[52:55], v[32:33], off offset:528
	v_cndmask_b32_e64 v32, v80, v82, s[10:11]
	v_ashrrev_i32_e32 v33, 31, v32
	v_lshlrev_b64 v[32:33], 12, v[32:33]
	v_lshl_add_u64 v[32:33], s[36:37], 0, v[32:33]
	v_lshl_add_u64 v[32:33], v[32:33], 0, v[210:211]
	global_load_dwordx4 v[44:47], v[32:33], off
	global_load_dwordx4 v[40:43], v[32:33], off offset:16
	global_load_dwordx4 v[36:39], v[32:33], off offset:512
	s_nop 0
	global_load_dwordx4 v[32:35], v[32:33], off offset:528
	s_mov_b64 s[10:11], -1
	s_and_b64 vcc, exec, s[12:13]
	v_ashrrev_i32_e32 v85, 31, v84
	s_cbranch_vccnz .LBB0_1251
	v_lshlrev_b64 v[88:89], 12, v[84:85]
	v_lshl_add_u64 v[88:89], s[90:91], 0, v[88:89]
	s_mov_b64 s[10:11], 0

; __device__ __forceinline__ unsigned pkbf(float lo, float hi) { return pg8::cvt_pk_bf16(lo, hi); }
;     __device__ __forceinline__ void operator()(const f32x4 (&acc)[2][2][4][2], const Unit& u, int wr, int wc, int fr, int fq) const {
;     ...
;             for (int mm = 0; mm < 2; ++mm) {
;                 const int m = m0 + mm;
;                 const int row = pm * 256 + ai * 128 + wr * 64 + m * 16 + fr;
;                 float* dst = isctx ? dst_ctx + (size_t)(row - MLAT) * DM : dst_lat + (size_t)row * DM;
;                 float ss = 0.f;
; #pragma unroll
;                 for (int bj = 0; bj < 2; ++bj) {
;                     const int col = cb + 128 * bj;
;                     const f32x4 x0 = pre[mm][bj][0] + gt[bj][0] * acc[ai][bj][m][0];
;                     const f32x4 x1 = pre[mm][bj][1] + gt[bj][1] * acc[ai][bj][m][1];
;                     *(f32x4*)(dst + col) = x0; *(f32x4*)(dst + col + 4) = x1;
;                     if (nxt) {
;                         ss += (x0[0] * x0[0] + x0[1] * x0[1]) + (x0[2] * x0[2] + x0[3] * x0[3]) + (x1[0] * x1[0] + x1[1] * x1[1]) + (x1[2] * x1[2] + x1[3] * x1[3]);
;                         const f32x4 y0 = x0 * gs[bj][0], y1 = x1 * gs[bj][1];
;                         u32x4 w; w.x = pkbf(y0[0], y0[1]); w.y = pkbf(y0[2], y0[3]); w.z = pkbf(y1[0], y1[1]); w.w = pkbf(y1[2], y1[3]);
;                         *(u32x4*)(xg + (size_t)row * DM + col) = w;
;                     }
;                 }
;                 if (nxt) { ss += __shfl_xor(ss, 16); ss += __shfl_xor(ss, 32); if (fq == 0) unsafeAtomicAdd(rowsq_next + row, ss); }
.LBB0_1253:
	s_waitcnt vmcnt(0) lgkmcnt(0)
	v_pk_fma_f32 v[78:79], v[30:31], v[66:67], v[78:79]
	v_pk_fma_f32 v[76:77], v[28:29], v[64:65], v[76:77]
	v_pk_fma_f32 v[74:75], v[26:27], v[70:71], v[74:75]
	v_pk_fma_f32 v[72:73], v[24:25], v[68:69], v[72:73]
	v_lshl_add_u64 v[86:87], v[192:193], 2, v[88:89]
	s_mov_b64 s[10:11], -1
	s_and_b64 vcc, exec, s[4:5]
	v_pk_fma_f32 v[28:29], v[20:21], v[48:49], v[56:57]
	v_pk_fma_f32 v[24:25], v[16:17], v[60:61], v[52:53]
	global_store_dwordx4 v[86:87], v[76:79], off
	global_store_dwordx4 v[86:87], v[72:75], off offset:16
	s_cbranch_vccnz .LBB0_1257
	v_mul_f32_e32 v20, v77, v77
	v_mul_f32_e32 v21, v79, v79
	v_fmac_f32_e32 v20, v76, v76
	v_fmac_f32_e32 v21, v78, v78
	v_add_f32_e32 v20, v20, v21
	v_mul_f32_e32 v21, v73, v73
	v_fmac_f32_e32 v21, v72, v72
	v_add_f32_e32 v20, v20, v21
	v_mul_f32_e32 v21, v75, v75
	v_fmac_f32_e32 v21, v74, v74
	v_pk_mul_f32 v[30:31], v[208:209], v[74:75]
	v_add_f32_e32 v56, v21, v20
	v_pk_mul_f32 v[20:21], v[202:203], v[78:79]
	v_pk_mul_f32 v[26:27], v[200:201], v[76:77]
	v_pk_mul_f32 v[52:53], v[198:199], v[72:73]
	v_cvt_pk_bf16_f32 v72, v26, v27
	v_cvt_pk_bf16_f32 v73, v20, v21
	v_mul_f32_e32 v20, v29, v29
	v_cvt_pk_bf16_f32 v74, v52, v53
	v_cvt_pk_bf16_f32 v75, v30, v31
	v_pk_fma_f32 v[30:31], v[22:23], v[50:51], v[58:59]
	v_fmac_f32_e32 v20, v28, v28
	v_mul_f32_e32 v21, v31, v31
	v_fmac_f32_e32 v21, v30, v30
	v_add_f32_e32 v20, v20, v21
	v_mul_f32_e32 v21, v25, v25
	v_pk_fma_f32 v[26:27], v[18:19], v[62:63], v[54:55]
	v_fmac_f32_e32 v21, v24, v24
	v_lshlrev_b64 v[16:17], 11, v[84:85]
	v_add_f32_e32 v20, v20, v21
	v_mul_f32_e32 v21, v27, v27
	v_lshl_add_u64 v[16:17], s[24:25], 0, v[16:17]
	v_fmac_f32_e32 v21, v26, v26
	v_lshl_add_u64 v[16:17], v[192:193], 1, v[16:17]
	v_add_f32_e32 v20, v21, v20
	global_store_dwordx4 v[16:17], v[72:75], off
	global_store_dwordx4 v[86:87], v[28:31], off offset:512
	global_store_dwordx4 v[86:87], v[24:27], off offset:528
	v_add_f32_e32 v56, v56, v20
	v_pk_mul_f32 v[20:21], v[204:205], v[30:31]
	v_pk_mul_f32 v[30:31], v[196:197], v[28:29]
	v_pk_mul_f32 v[26:27], v[206:207], v[26:27]
	v_pk_mul_f32 v[52:53], v[194:195], v[24:25]
	v_cvt_pk_bf16_f32 v72, v30, v31
	v_cvt_pk_bf16_f32 v73, v20, v21
	v_xor_b32_e32 v20, 32, v229
	v_cvt_pk_bf16_f32 v74, v52, v53
	v_cvt_pk_bf16_f32 v75, v26, v27
	global_store_dwordx4 v[16:17], v[72:75], off offset:256
	v_and_b32_e32 v17, 64, v229
	v_xor_b32_e32 v16, 16, v229
	v_add_u32_e32 v17, 64, v17
	v_cmp_lt_i32_e32 vcc, v16, v17
	s_nop 1
	v_cndmask_b32_e32 v16, v229, v16, vcc
	v_lshlrev_b32_e32 v16, 2, v16
	ds_bpermute_b32 v16, v16, v56
	v_cmp_lt_i32_e32 vcc, v20, v17
	s_waitcnt lgkmcnt(0)
	v_add_f32_e32 v16, v56, v16
	v_cndmask_b32_e32 v17, v229, v20, vcc
	v_lshlrev_b32_e32 v17, 2, v17
	ds_bpermute_b32 v17, v17, v16
	s_and_saveexec_b64 s[10:11], s[6:7]
	s_cbranch_execz .LBB0_1256
	v_lshl_add_u64 v[20:21], v[84:85], 2, s[26:27]
	s_waitcnt lgkmcnt(0)
	v_add_f32_e32 v16, v16, v17
	global_atomic_add_f32 v[20:21], v16, off

;     __device__ __forceinline__ void operator()(const f32x4 (&acc)[2][2][4][2], const Unit& u, int wr, int wc, int fr, int fq) const {
;     ...
;                     const f32x4 x0 = pre[mm][bj][0] + gt[bj][0] * acc[ai][bj][m][0];
;                     const f32x4 x1 = pre[mm][bj][1] + gt[bj][1] * acc[ai][bj][m][1];
;                     *(f32x4*)(dst + col) = x0; *(f32x4*)(dst + col + 4) = x1;
.LBB0_1258:
	v_pk_fma_f32 v[30:31], v[22:23], v[50:51], v[58:59]
	v_pk_fma_f32 v[26:27], v[18:19], v[62:63], v[54:55]
	global_store_dwordx4 v[86:87], v[28:31], off offset:512
	global_store_dwordx4 v[86:87], v[24:27], off offset:528

; __device__ __forceinline__ unsigned pkbf(float lo, float hi) { return pg8::cvt_pk_bf16(lo, hi); }
;     __device__ __forceinline__ void operator()(const f32x4 (&acc)[2][2][4][2], const Unit& u, int wr, int wc, int fr, int fq) const {
;     ...
;             for (int mm = 0; mm < 2; ++mm) {
;                 const int m = m0 + mm;
;                 const int row = pm * 256 + ai * 128 + wr * 64 + m * 16 + fr;
;                 float* dst = isctx ? dst_ctx + (size_t)(row - MLAT) * DM : dst_lat + (size_t)row * DM;
;                 float ss = 0.f;
; #pragma unroll
;                 for (int bj = 0; bj < 2; ++bj) {
;                     const int col = cb + 128 * bj;
;                     const f32x4 x0 = pre[mm][bj][0] + gt[bj][0] * acc[ai][bj][m][0];
;                     const f32x4 x1 = pre[mm][bj][1] + gt[bj][1] * acc[ai][bj][m][1];
;                     *(f32x4*)(dst + col) = x0; *(f32x4*)(dst + col + 4) = x1;
;                     if (nxt) {
;                         ss += (x0[0] * x0[0] + x0[1] * x0[1]) + (x0[2] * x0[2] + x0[3] * x0[3]) + (x1[0] * x1[0] + x1[1] * x1[1]) + (x1[2] * x1[2] + x1[3] * x1[3]);
;                         const f32x4 y0 = x0 * gs[bj][0], y1 = x1 * gs[bj][1];
;                         u32x4 w; w.x = pkbf(y0[0], y0[1]); w.y = pkbf(y0[2], y0[3]); w.z = pkbf(y1[0], y1[1]); w.w = pkbf(y1[2], y1[3]);
;                         *(u32x4*)(xg + (size_t)row * DM + col) = w;
;                     }
;                 }
;                 if (nxt) { ss += __shfl_xor(ss, 16); ss += __shfl_xor(ss, 32); if (fq == 0) unsafeAtomicAdd(rowsq_next + row, ss); }
.LBB0_1263:
	s_waitcnt lgkmcnt(0)
	v_pk_fma_f32 v[16:17], v[14:15], v[66:67], v[46:47]
	v_pk_fma_f32 v[14:15], v[12:13], v[64:65], v[44:45]
	v_pk_fma_f32 v[20:21], v[10:11], v[70:71], v[42:43]
	v_pk_fma_f32 v[18:19], v[8:9], v[68:69], v[40:41]
	v_lshl_add_u64 v[22:23], v[192:193], 2, v[22:23]
	s_mov_b64 s[10:11], -1
	s_and_b64 vcc, exec, s[4:5]
	v_pk_fma_f32 v[12:13], v[4:5], v[48:49], v[36:37]
	v_pk_fma_f32 v[8:9], v[0:1], v[60:61], v[32:33]
	global_store_dwordx4 v[22:23], v[14:17], off
	global_store_dwordx4 v[22:23], v[18:21], off offset:16
	s_cbranch_vccnz .LBB0_1268
	v_mul_f32_e32 v4, v15, v15
	v_mul_f32_e32 v5, v17, v17
	v_fmac_f32_e32 v4, v14, v14
	v_fmac_f32_e32 v5, v16, v16
	v_add_f32_e32 v4, v4, v5
	v_mul_f32_e32 v5, v19, v19
	v_fmac_f32_e32 v5, v18, v18
	v_add_f32_e32 v4, v4, v5
	v_mul_f32_e32 v5, v21, v21
	v_lshlrev_b64 v[0:1], 11, v[80:81]
	v_fmac_f32_e32 v5, v20, v20
	v_add_f32_e32 v24, v5, v4
	v_pk_mul_f32 v[4:5], v[202:203], v[16:17]
	v_lshl_add_u64 v[0:1], s[24:25], 0, v[0:1]
	v_pk_mul_f32 v[10:11], v[200:201], v[14:15]
	v_pk_mul_f32 v[16:17], v[198:199], v[18:19]
	v_cvt_pk_bf16_f32 v14, v10, v11
	v_cvt_pk_bf16_f32 v15, v4, v5
	v_lshl_add_u64 v[4:5], v[192:193], 1, v[0:1]
	v_pk_mul_f32 v[20:21], v[208:209], v[20:21]
	v_cvt_pk_bf16_f32 v16, v16, v17
	v_mul_f32_e32 v0, v13, v13
	v_cvt_pk_bf16_f32 v17, v20, v21
	global_store_dwordx4 v[4:5], v[14:17], off
	v_fmac_f32_e32 v0, v12, v12
	v_pk_fma_f32 v[10:11], v[2:3], v[62:63], v[34:35]
	v_pk_fma_f32 v[14:15], v[6:7], v[50:51], v[38:39]
	global_store_dwordx4 v[22:23], v[12:15], off offset:512
	global_store_dwordx4 v[22:23], v[8:11], off offset:528
	v_mul_f32_e32 v1, v15, v15
	v_fmac_f32_e32 v1, v14, v14
	v_add_f32_e32 v0, v0, v1
	v_mul_f32_e32 v1, v9, v9
	v_fmac_f32_e32 v1, v8, v8
	v_add_f32_e32 v0, v0, v1
	v_mul_f32_e32 v1, v11, v11
	v_fmac_f32_e32 v1, v10, v10
	v_add_f32_e32 v0, v1, v0
	v_and_b32_e32 v1, 64, v229
	v_add_f32_e32 v20, v24, v0
	v_pk_mul_f32 v[16:17], v[204:205], v[14:15]
	v_xor_b32_e32 v0, 16, v229
	v_add_u32_e32 v15, 64, v1
	v_cmp_lt_i32_e32 vcc, v0, v15
	v_pk_mul_f32 v[10:11], v[206:207], v[10:11]
	v_pk_mul_f32 v[18:19], v[194:195], v[8:9]
	v_cndmask_b32_e32 v0, v229, v0, vcc
	v_lshlrev_b32_e32 v0, 2, v0
	ds_bpermute_b32 v21, v0, v20
	v_pk_mul_f32 v[0:1], v[196:197], v[12:13]
	s_nop 0
	v_cvt_pk_bf16_f32 v14, v0, v1
	v_xor_b32_e32 v1, 32, v229
	v_cmp_lt_i32_e32 vcc, v1, v15
	s_waitcnt lgkmcnt(0)
	v_add_f32_e32 v0, v20, v21
	v_cvt_pk_bf16_f32 v15, v16, v17
	v_cvt_pk_bf16_f32 v16, v18, v19
	v_cvt_pk_bf16_f32 v17, v10, v11
	global_store_dwordx4 v[4:5], v[14:17], off offset:256
	v_cndmask_b32_e32 v1, v229, v1, vcc
	v_lshlrev_b32_e32 v1, 2, v1
	ds_bpermute_b32 v1, v1, v0
	s_and_saveexec_b64 s[10:11], s[6:7]
	s_cbranch_execz .LBB0_1266
	v_lshl_add_u64 v[4:5], v[80:81], 2, s[26:27]
	s_waitcnt lgkmcnt(0)
	v_add_f32_e32 v0, v0, v1
	global_atomic_add_f32 v[4:5], v0, off

;     __device__ __forceinline__ void operator()(const f32x4 (&acc)[2][2][4][2], const Unit& u, int wr, int wc, int fr, int fq) const {
;     ...
;         for (int q2 = 0; q2 < 4; ++q2) {
;     ...
;                     const f32x4 x0 = pre[mm][bj][0] + gt[bj][0] * acc[ai][bj][m][0];
;                     const f32x4 x1 = pre[mm][bj][1] + gt[bj][1] * acc[ai][bj][m][1];
;                     *(f32x4*)(dst + col) = x0; *(f32x4*)(dst + col + 4) = x1;
.LBB0_1269:
	v_pk_fma_f32 v[14:15], v[6:7], v[50:51], v[38:39]
	v_pk_fma_f32 v[10:11], v[2:3], v[62:63], v[34:35]
	global_store_dwordx4 v[22:23], v[12:15], off offset:512
	global_store_dwordx4 v[22:23], v[8:11], off offset:528
	s_and_b64 vcc, exec, s[8:9]
	s_mov_b64 s[8:9], -1
	s_cbranch_vccnz .LBB0_1166

; __device__ __forceinline__ void ctx_slice_gemm(LAS unsigned char* lds, const bf16_t* A  , const bf16_t* Bt  , int K, ...
;     int tid_l = threadIdx.x; asm volatile("" : "+v"(tid_l)); const int tid = tid_l, lane = tid & 63, wid = __builtin_amdgcn_readfirstlane(tid >> 6), r16 = lane & 15, g4 = lane >> 4;
;     const int row0 = (blk >> 5) * 64, col0 = (blk & 31) * 32;
;     const int kw = K >> 3, kbeg = wid * kw;
;     const bf16_t* ap = A + (size_t)(MLAT + row0 + r16) * K + kbeg + 8 * g4;
;     const bf16_t* bp = Bt + (size_t)(col0 + r16) * K + kbeg + 8 * g4;
;     const size_t a16 = (size_t)16 * K;
;     f32x4 acc[4][2];
; #pragma unroll
;     for (int i = 0; i < 4; ++i)
; #pragma unroll
;         for (int j = 0; j < 2; ++j) acc[i][j] = (f32x4){0.f, 0.f, 0.f, 0.f};
; #pragma unroll 4
;     for (int k = 0; k < kw; k += 32) {
;         bf16x8 fa[4], fb[2];
; #pragma unroll
;         for (int i = 0; i < 4; ++i) fa[i] = *(const bf16x8*)(ap + i * a16 + k);
; #pragma unroll
;         for (int j = 0; j < 2; ++j) fb[j] = *(const bf16x8*)(bp + j * a16 + k);
; #pragma unroll
;         for (int i = 0; i < 4; ++i)
; #pragma unroll
;             for (int j = 0; j < 2; ++j) acc[i][j] = __builtin_amdgcn_mfma_f32_16x16x32_bf16(fa[i], fb[j], acc[i][j], 0, 0, 0);
;     }
.LBB0_1277:
	v_mov_b32_e32 v61, v222
	s_and_b32 s13, s14, 0x3e0
	v_readfirstlane_b32 s1, v61
	v_and_b32_e32 v60, 15, v61
	s_ashr_i32 s0, s1, 6
	v_or_b32_e32 v0, s13, v60
	s_mul_i32 s26, s0, 0x160
	v_mul_u32_u24_e32 v0, 0xb00, v0
	s_and_b32 s12, s15, 0xffffffc0
	s_ashr_i32 s27, s26, 31
	v_lshlrev_b32_e32 v176, 1, v0
	s_add_i32 s17, s12, 0x4000
	v_lshl_add_u64 v[4:5], s[20:21], 0, v[176:177]
	s_lshl_b64 s[26:27], s[26:27], 1
	v_or_b32_e32 v2, s17, v60
	v_and_b32_e32 v176, 48, v61
	s_waitcnt lgkmcnt(0)
	v_mov_b64_e32 v[0:1], s[18:19]
	v_lshl_add_u64 v[4:5], v[4:5], 0, s[26:27]
	v_mad_i64_i32 v[0:1], s[28:29], v2, s3, v[0:1]
	v_lshl_add_u64 v[24:25], v[4:5], 0, v[176:177]
	v_lshl_add_u64 v[0:1], v[0:1], 0, s[26:27]
	v_add_co_u32_e32 v54, vcc, s30, v24
	v_lshl_add_u64 v[50:51], v[0:1], 0, v[176:177]
	s_nop 0
	v_addc_co_u32_e32 v55, vcc, 0, v25, vcc
	v_add_co_u32_e32 v56, vcc, s30, v50
	s_mov_b32 s17, 0x2c000
	s_nop 0
	v_addc_co_u32_e32 v57, vcc, 0, v51, vcc
	v_add_co_u32_e32 v58, vcc, s17, v50
	s_mov_b32 s17, 0x42000
	s_nop 0
	v_addc_co_u32_e32 v59, vcc, 0, v51, vcc
	v_add_co_u32_e32 v52, vcc, s17, v50
	s_nop 1
	v_addc_co_u32_e32 v53, vcc, 0, v51, vcc
	s_lshl_b32 s17, s0, 4
	s_and_b32 s17, s17, 16
	s_or_b32 s13, s13, s17
	s_ashr_i32 s1, s1, 3
	s_and_b32 s1, s1, -16
	s_add_i32 s1, s1, s12
	s_brev_b32 s12, 64
	global_load_dwordx4 v[80:83], v[50:51], off
	global_load_dwordx4 v[84:87], v[56:57], off
	global_load_dwordx4 v[88:91], v[58:59], off
	global_load_dwordx4 v[92:95], v[52:53], off
	global_load_dwordx4 v[96:99], v[24:25], off
	global_load_dwordx4 v[100:103], v[54:55], off
	global_load_dwordx4 v[104:107], v[50:51], off offset:64
	global_load_dwordx4 v[108:111], v[56:57], off offset:64
	global_load_dwordx4 v[112:115], v[58:59], off offset:64
	global_load_dwordx4 v[116:119], v[52:53], off offset:64
	global_load_dwordx4 v[120:123], v[24:25], off offset:64
	global_load_dwordx4 v[124:127], v[54:55], off offset:64
	global_load_dwordx4 v[128:131], v[50:51], off offset:128
	global_load_dwordx4 v[132:135], v[56:57], off offset:128
	global_load_dwordx4 v[136:139], v[58:59], off offset:128
	global_load_dwordx4 v[140:143], v[52:53], off offset:128
	global_load_dwordx4 v[144:147], v[24:25], off offset:128
	global_load_dwordx4 v[148:151], v[54:55], off offset:128
	s_waitcnt vmcnt(12)
	v_mfma_f32_16x16x32_bf16 v[62:65], v[80:83], v[96:99], 0
	v_mfma_f32_16x16x32_bf16 v[66:69], v[80:83], v[100:103], 0
	v_mfma_f32_16x16x32_bf16 v[70:73], v[84:87], v[96:99], 0
	v_mfma_f32_16x16x32_bf16 v[74:77], v[84:87], v[100:103], 0
	v_mfma_f32_16x16x32_bf16 v[26:29], v[88:91], v[96:99], 0
	v_mfma_f32_16x16x32_bf16 v[30:33], v[88:91], v[100:103], 0
	v_mfma_f32_16x16x32_bf16 v[34:37], v[92:95], v[96:99], 0
	v_mfma_f32_16x16x32_bf16 v[38:41], v[92:95], v[100:103], 0
	global_load_dwordx4 v[80:83], v[50:51], off offset:192
	global_load_dwordx4 v[84:87], v[56:57], off offset:192
	global_load_dwordx4 v[88:91], v[58:59], off offset:192
	global_load_dwordx4 v[92:95], v[52:53], off offset:192
	global_load_dwordx4 v[96:99], v[24:25], off offset:192
	global_load_dwordx4 v[100:103], v[54:55], off offset:192
	s_waitcnt vmcnt(12)
	v_mfma_f32_16x16x32_bf16 v[62:65], v[104:107], v[120:123], v[62:65]
	v_mfma_f32_16x16x32_bf16 v[66:69], v[104:107], v[124:127], v[66:69]
	v_mfma_f32_16x16x32_bf16 v[70:73], v[108:111], v[120:123], v[70:73]
	v_mfma_f32_16x16x32_bf16 v[74:77], v[108:111], v[124:127], v[74:77]
	v_mfma_f32_16x16x32_bf16 v[26:29], v[112:115], v[120:123], v[26:29]
	v_mfma_f32_16x16x32_bf16 v[30:33], v[112:115], v[124:127], v[30:33]
	v_mfma_f32_16x16x32_bf16 v[34:37], v[116:119], v[120:123], v[34:37]
	v_mfma_f32_16x16x32_bf16 v[38:41], v[116:119], v[124:127], v[38:41]
	global_load_dwordx4 v[104:107], v[50:51], off offset:256
	global_load_dwordx4 v[108:111], v[56:57], off offset:256
	global_load_dwordx4 v[112:115], v[58:59], off offset:256
	global_load_dwordx4 v[116:119], v[52:53], off offset:256
	global_load_dwordx4 v[120:123], v[24:25], off offset:256
	global_load_dwordx4 v[124:127], v[54:55], off offset:256
	s_waitcnt vmcnt(12)
	v_mfma_f32_16x16x32_bf16 v[62:65], v[128:131], v[144:147], v[62:65]
	v_mfma_f32_16x16x32_bf16 v[66:69], v[128:131], v[148:151], v[66:69]
	v_mfma_f32_16x16x32_bf16 v[70:73], v[132:135], v[144:147], v[70:73]
	v_mfma_f32_16x16x32_bf16 v[74:77], v[132:135], v[148:151], v[74:77]
	v_mfma_f32_16x16x32_bf16 v[26:29], v[136:139], v[144:147], v[26:29]
	v_mfma_f32_16x16x32_bf16 v[30:33], v[136:139], v[148:151], v[30:33]
	v_mfma_f32_16x16x32_bf16 v[34:37], v[140:143], v[144:147], v[34:37]
	v_mfma_f32_16x16x32_bf16 v[38:41], v[140:143], v[148:151], v[38:41]
	global_load_dwordx4 v[128:131], v[50:51], off offset:320
	global_load_dwordx4 v[132:135], v[56:57], off offset:320
	global_load_dwordx4 v[136:139], v[58:59], off offset:320
	global_load_dwordx4 v[140:143], v[52:53], off offset:320
	global_load_dwordx4 v[144:147], v[24:25], off offset:320
	global_load_dwordx4 v[148:151], v[54:55], off offset:320
	s_waitcnt vmcnt(12)
	v_mfma_f32_16x16x32_bf16 v[62:65], v[80:83], v[96:99], v[62:65]
	v_mfma_f32_16x16x32_bf16 v[66:69], v[80:83], v[100:103], v[66:69]
	v_mfma_f32_16x16x32_bf16 v[70:73], v[84:87], v[96:99], v[70:73]
	v_mfma_f32_16x16x32_bf16 v[74:77], v[84:87], v[100:103], v[74:77]
	v_mfma_f32_16x16x32_bf16 v[26:29], v[88:91], v[96:99], v[26:29]
	v_mfma_f32_16x16x32_bf16 v[30:33], v[88:91], v[100:103], v[30:33]
	v_mfma_f32_16x16x32_bf16 v[34:37], v[92:95], v[96:99], v[34:37]
	v_mfma_f32_16x16x32_bf16 v[38:41], v[92:95], v[100:103], v[38:41]
	global_load_dwordx4 v[80:83], v[50:51], off offset:384
	global_load_dwordx4 v[84:87], v[56:57], off offset:384
	global_load_dwordx4 v[88:91], v[58:59], off offset:384
	global_load_dwordx4 v[92:95], v[52:53], off offset:384
	global_load_dwordx4 v[96:99], v[24:25], off offset:384
	global_load_dwordx4 v[100:103], v[54:55], off offset:384
	s_waitcnt vmcnt(12)
; #define LAS __attribute__((address_space(3)))
; #define LAS __attribute__((address_space(3)))
; __device__ __forceinline__ void ctx_slice_gemm(LAS unsigned char* lds, const bf16_t* A  , const bf16_t* Bt  , int K, ...
;     ...
;     for (int k = 0; k < kw; k += 32) {
;         bf16x8 fa[4], fb[2];
; #pragma unroll
;         for (int i = 0; i < 4; ++i) fa[i] = *(const bf16x8*)(ap + i * a16 + k);
; #pragma unroll
;         for (int j = 0; j < 2; ++j) fb[j] = *(const bf16x8*)(bp + j * a16 + k);
; #pragma unroll
;         for (int i = 0; i < 4; ++i)
; #pragma unroll
;             for (int j = 0; j < 2; ++j) acc[i][j] = __builtin_amdgcn_mfma_f32_16x16x32_bf16(fa[i], fb[j], acc[i][j], 0, 0, 0);
;     }
;     LAS float* part = (LAS float*)lds;
; #pragma unroll
;     for (int i = 0; i < 4; ++i)
; #pragma unroll
;         for (int j = 0; j < 2; ++j)
; #pragma unroll
;             for (int q = 0; q < 4; ++q) part[((wid * 8 + i * 2 + j) * 4 + q) * 64 + lane] = acc[i][j][q];
;     __syncthreads();
	v_mfma_f32_16x16x32_bf16 v[62:65], v[104:107], v[120:123], v[62:65]
	v_mfma_f32_16x16x32_bf16 v[66:69], v[104:107], v[124:127], v[66:69]
	v_mfma_f32_16x16x32_bf16 v[70:73], v[108:111], v[120:123], v[70:73]
	v_mfma_f32_16x16x32_bf16 v[74:77], v[108:111], v[124:127], v[74:77]
	v_mfma_f32_16x16x32_bf16 v[26:29], v[112:115], v[120:123], v[26:29]
	v_mfma_f32_16x16x32_bf16 v[30:33], v[112:115], v[124:127], v[30:33]
	v_mfma_f32_16x16x32_bf16 v[34:37], v[116:119], v[120:123], v[34:37]
	v_mfma_f32_16x16x32_bf16 v[38:41], v[116:119], v[124:127], v[38:41]
	global_load_dwordx4 v[104:107], v[50:51], off offset:448
	global_load_dwordx4 v[108:111], v[56:57], off offset:448
	global_load_dwordx4 v[112:115], v[58:59], off offset:448
	global_load_dwordx4 v[116:119], v[52:53], off offset:448
	global_load_dwordx4 v[120:123], v[24:25], off offset:448
	global_load_dwordx4 v[124:127], v[54:55], off offset:448
	s_waitcnt vmcnt(12)
	v_mfma_f32_16x16x32_bf16 v[62:65], v[128:131], v[144:147], v[62:65]
	v_mfma_f32_16x16x32_bf16 v[66:69], v[128:131], v[148:151], v[66:69]
	v_mfma_f32_16x16x32_bf16 v[70:73], v[132:135], v[144:147], v[70:73]
	v_mfma_f32_16x16x32_bf16 v[74:77], v[132:135], v[148:151], v[74:77]
	v_mfma_f32_16x16x32_bf16 v[26:29], v[136:139], v[144:147], v[26:29]
	v_mfma_f32_16x16x32_bf16 v[30:33], v[136:139], v[148:151], v[30:33]
	v_mfma_f32_16x16x32_bf16 v[34:37], v[140:143], v[144:147], v[34:37]
	v_mfma_f32_16x16x32_bf16 v[38:41], v[140:143], v[148:151], v[38:41]
	global_load_dwordx4 v[128:131], v[50:51], off offset:512
	global_load_dwordx4 v[132:135], v[56:57], off offset:512
	global_load_dwordx4 v[136:139], v[58:59], off offset:512
	global_load_dwordx4 v[140:143], v[52:53], off offset:512
	global_load_dwordx4 v[144:147], v[24:25], off offset:512
	global_load_dwordx4 v[148:151], v[54:55], off offset:512
	s_waitcnt vmcnt(12)
	v_mfma_f32_16x16x32_bf16 v[62:65], v[80:83], v[96:99], v[62:65]
	v_mfma_f32_16x16x32_bf16 v[66:69], v[80:83], v[100:103], v[66:69]
	v_mfma_f32_16x16x32_bf16 v[70:73], v[84:87], v[96:99], v[70:73]
	v_mfma_f32_16x16x32_bf16 v[74:77], v[84:87], v[100:103], v[74:77]
	v_mfma_f32_16x16x32_bf16 v[26:29], v[88:91], v[96:99], v[26:29]
	v_mfma_f32_16x16x32_bf16 v[30:33], v[88:91], v[100:103], v[30:33]
	v_mfma_f32_16x16x32_bf16 v[34:37], v[92:95], v[96:99], v[34:37]
	v_mfma_f32_16x16x32_bf16 v[38:41], v[92:95], v[100:103], v[38:41]
	global_load_dwordx4 v[80:83], v[50:51], off offset:576
	global_load_dwordx4 v[84:87], v[56:57], off offset:576
	global_load_dwordx4 v[88:91], v[58:59], off offset:576
	global_load_dwordx4 v[92:95], v[52:53], off offset:576
	global_load_dwordx4 v[96:99], v[24:25], off offset:576
	global_load_dwordx4 v[100:103], v[54:55], off offset:576
	s_waitcnt vmcnt(12)
	v_mfma_f32_16x16x32_bf16 v[62:65], v[104:107], v[120:123], v[62:65]
	v_mfma_f32_16x16x32_bf16 v[66:69], v[104:107], v[124:127], v[66:69]
	v_mfma_f32_16x16x32_bf16 v[70:73], v[108:111], v[120:123], v[70:73]
	v_mfma_f32_16x16x32_bf16 v[74:77], v[108:111], v[124:127], v[74:77]
	v_mfma_f32_16x16x32_bf16 v[26:29], v[112:115], v[120:123], v[26:29]
	v_mfma_f32_16x16x32_bf16 v[30:33], v[112:115], v[124:127], v[30:33]
	v_mfma_f32_16x16x32_bf16 v[34:37], v[116:119], v[120:123], v[34:37]
	v_mfma_f32_16x16x32_bf16 v[38:41], v[116:119], v[124:127], v[38:41]
	global_load_dwordx4 v[104:107], v[50:51], off offset:640
	global_load_dwordx4 v[108:111], v[56:57], off offset:640
	global_load_dwordx4 v[112:115], v[58:59], off offset:640
	global_load_dwordx4 v[116:119], v[52:53], off offset:640
	global_load_dwordx4 v[120:123], v[24:25], off offset:640
	global_load_dwordx4 v[124:127], v[54:55], off offset:640
	s_waitcnt vmcnt(12)
	v_mfma_f32_16x16x32_bf16 v[62:65], v[128:131], v[144:147], v[62:65]
	v_mfma_f32_16x16x32_bf16 v[66:69], v[128:131], v[148:151], v[66:69]
	v_mfma_f32_16x16x32_bf16 v[70:73], v[132:135], v[144:147], v[70:73]
	v_mfma_f32_16x16x32_bf16 v[74:77], v[132:135], v[148:151], v[74:77]
	v_mfma_f32_16x16x32_bf16 v[26:29], v[136:139], v[144:147], v[26:29]
	v_mfma_f32_16x16x32_bf16 v[30:33], v[136:139], v[148:151], v[30:33]
	v_mfma_f32_16x16x32_bf16 v[34:37], v[140:143], v[144:147], v[34:37]
	v_mfma_f32_16x16x32_bf16 v[38:41], v[140:143], v[148:151], v[38:41]
	s_waitcnt vmcnt(6)
	v_mfma_f32_16x16x32_bf16 v[62:65], v[80:83], v[96:99], v[62:65]
	v_mfma_f32_16x16x32_bf16 v[66:69], v[80:83], v[100:103], v[66:69]
	v_mfma_f32_16x16x32_bf16 v[70:73], v[84:87], v[96:99], v[70:73]
	v_mfma_f32_16x16x32_bf16 v[74:77], v[84:87], v[100:103], v[74:77]
	v_mfma_f32_16x16x32_bf16 v[26:29], v[88:91], v[96:99], v[26:29]
	v_mfma_f32_16x16x32_bf16 v[30:33], v[88:91], v[100:103], v[30:33]
	v_mfma_f32_16x16x32_bf16 v[34:37], v[92:95], v[96:99], v[34:37]
	v_mfma_f32_16x16x32_bf16 v[38:41], v[92:95], v[100:103], v[38:41]
	s_waitcnt vmcnt(0)
	v_mfma_f32_16x16x32_bf16 v[62:65], v[104:107], v[120:123], v[62:65]
	v_mfma_f32_16x16x32_bf16 v[66:69], v[104:107], v[124:127], v[66:69]
	v_mfma_f32_16x16x32_bf16 v[70:73], v[108:111], v[120:123], v[70:73]
	v_mfma_f32_16x16x32_bf16 v[74:77], v[108:111], v[124:127], v[74:77]
	v_mfma_f32_16x16x32_bf16 v[26:29], v[112:115], v[120:123], v[26:29]
	v_mfma_f32_16x16x32_bf16 v[30:33], v[112:115], v[124:127], v[30:33]
	v_mfma_f32_16x16x32_bf16 v[34:37], v[116:119], v[120:123], v[34:37]
	v_mfma_f32_16x16x32_bf16 v[38:41], v[116:119], v[124:127], v[38:41]
	v_and_b32_e32 v52, 63, v61
	v_lshl_add_u32 v52, v52, 2, 0
	v_lshl_add_u32 v53, s0, 13, v52
	v_or_b32_e32 v13, s13, v60
	v_lshlrev_b32_e32 v176, 2, v13
	s_lshl_b32 s0, s0, 10
	v_add_u32_e32 v14, s0, v52
	s_nop 7
	ds_write2st64_b32 v53, v62, v63 offset1:1
	ds_write2st64_b32 v53, v64, v65 offset0:2 offset1:3
	ds_write2st64_b32 v53, v66, v67 offset0:4 offset1:5
	ds_write2st64_b32 v53, v68, v69 offset0:6 offset1:7
	ds_write2st64_b32 v53, v70, v71 offset0:8 offset1:9
	ds_write2st64_b32 v53, v72, v73 offset0:10 offset1:11
	ds_write2st64_b32 v53, v74, v75 offset0:12 offset1:13
	ds_write2st64_b32 v53, v76, v77 offset0:14 offset1:15
	ds_write2st64_b32 v53, v26, v27 offset0:16 offset1:17
	ds_write2st64_b32 v53, v28, v29 offset0:18 offset1:19
	ds_write2st64_b32 v53, v30, v31 offset0:20 offset1:21
	ds_write2st64_b32 v53, v32, v33 offset0:22 offset1:23
	ds_write2st64_b32 v53, v34, v35 offset0:24 offset1:25
	ds_write2st64_b32 v53, v36, v37 offset0:26 offset1:27
	ds_write2st64_b32 v53, v38, v39 offset0:28 offset1:29
	ds_write2st64_b32 v53, v40, v41 offset0:30 offset1:31
	v_lshl_add_u64 v[0:1], s[4:5], 0, v[176:177]
	s_waitcnt lgkmcnt(0)
	s_barrier
; __device__ __forceinline__ unsigned pkbf(float lo, float hi) { return pg8::cvt_pk_bf16(lo, hi); }
; __device__ __forceinline__ void ctx_slice_gemm(LAS unsigned char* lds, const bf16_t* A  , const bf16_t* Bt  , int K, ...
;     ...
;     {
;         const int t = wid, rgi = t >> 1, cg = t & 1, col = col0 + 16 * cg + r16;
;         const float gt = gate2[col];
;         const bool nxt = ng != nullptr;
;         const float gs = nxt ? ng[col] * (1.f + nsc2[col]) : 0.f;
; #pragma unroll
;         for (int q = 0; q < 4; ++q) {
;             float s = 0.f;
; #pragma unroll
;             for (int w = 0; w < 8; ++w) s += part[((w * 8 + t) * 4 + q) * 64 + lane];
;             const int rr = row0 + 16 * rgi + 4 * g4 + q;
;             const float x = res_ctx[(size_t)rr * DM + col] + gt * s;
;             dst_ctx[(size_t)rr * DM + col] = x;
;             if (nxt) {
;                 xg[(size_t)(MLAT + rr) * DM + col] = (bf16_t)(pkbf(x * gs, 0.f) & 0xffffu);
;                 float ss = x * x;
;                 ss += __shfl_xor(ss, 1); ss += __shfl_xor(ss, 2); ss += __shfl_xor(ss, 4); ss += __shfl_xor(ss, 8);
;                 if (r16 == 0) unsafeAtomicAdd(rowsq_next + MLAT + rr, ss);
;             }
;         }
;     }
	global_load_dword v8, v[0:1], off
	v_lshrrev_b32_e32 v0, 2, v61
	v_and_or_b32 v0, v0, 12, s1
	v_ashrrev_i32_e32 v1, 31, v0
	v_lshlrev_b64 v[2:3], 12, v[0:1]
	v_lshl_add_u64 v[2:3], s[22:23], 0, v[2:3]
	v_lshl_add_u64 v[2:3], v[2:3], 0, v[176:177]
	global_load_dword v15, v[2:3], off
	v_lshl_add_u64 v[4:5], s[8:9], 0, v[176:177]
	global_load_dword v12, v[4:5], off
	global_load_dword v16, v176, s[6:7]
	ds_read2st64_b32 v[4:5], v14 offset1:32
	ds_read2st64_b32 v[6:7], v14 offset0:64 offset1:96
	ds_read2st64_b32 v[10:11], v14 offset0:128 offset1:160
	v_cmp_eq_u32_e64 s[0:1], 0, v60
	s_waitcnt lgkmcnt(0)
	v_add_f32_e32 v4, 0, v4
	v_add_f32_e32 v9, v4, v5
	ds_read2st64_b32 v[4:5], v14 offset0:192 offset1:224
	v_add_f32_e32 v6, v9, v6
	v_add_f32_e32 v6, v6, v7
	v_add_f32_e32 v6, v6, v10
	v_add_f32_e32 v6, v6, v11
	s_waitcnt lgkmcnt(0)
	v_add_f32_e32 v4, v6, v4
	v_and_b32_e32 v6, 64, v229
	v_add_f32_e32 v4, v4, v5
	v_xor_b32_e32 v5, 1, v229
	v_add_u32_e32 v7, 64, v6
	v_cmp_lt_i32_e32 vcc, v5, v7
	s_waitcnt vmcnt(0)
	v_fmac_f32_e32 v15, v8, v4
	v_cndmask_b32_e32 v5, v229, v5, vcc
	v_mul_f32_e32 v4, v15, v15
	v_lshlrev_b32_e32 v9, 2, v5
	ds_bpermute_b32 v6, v9, v4
	v_xor_b32_e32 v5, 2, v229
	v_cmp_lt_i32_e32 vcc, v5, v7
	global_store_dword v[2:3], v15, off
	v_xor_b32_e32 v2, 4, v229
	v_cndmask_b32_e32 v5, v229, v5, vcc
	s_waitcnt lgkmcnt(0)
	v_fmac_f32_e32 v6, v15, v15
	v_lshlrev_b32_e32 v10, 2, v5
	ds_bpermute_b32 v11, v10, v6
	v_cmp_lt_i32_e32 vcc, v2, v7
	v_add_f32_e32 v4, 1.0, v12
	v_mul_f32_e32 v12, v16, v4
	v_cndmask_b32_e32 v2, v229, v2, vcc
	s_waitcnt lgkmcnt(0)
	v_add_f32_e32 v6, v6, v11
	v_lshlrev_b32_e32 v11, 2, v2
	v_lshlrev_b32_e32 v4, 1, v13
	v_mov_b32_e32 v5, v177
	ds_bpermute_b32 v13, v11, v6
	v_mul_f32_e32 v2, v12, v15
	v_lshl_add_u64 v[4:5], s[24:25], 0, v[4:5]
	v_cvt_pk_bf16_f32 v15, v2, v177
	v_lshlrev_b64 v[2:3], 11, v[0:1]
	v_lshl_add_u64 v[2:3], v[4:5], 0, v[2:3]
	v_xor_b32_e32 v4, 8, v229
	v_cmp_lt_i32_e32 vcc, v4, v7
	s_waitcnt lgkmcnt(0)
	v_add_f32_e32 v6, v6, v13
	v_cndmask_b32_e32 v4, v229, v4, vcc
	v_lshlrev_b32_e32 v13, 2, v4
	ds_bpermute_b32 v7, v13, v6
	v_add_co_u32_e32 v4, vcc, s12, v2
	s_nop 1
	v_addc_co_u32_e32 v5, vcc, 0, v3, vcc
	global_store_short v[4:5], v15, off
	s_and_saveexec_b64 s[12:13], s[0:1]
	s_cbranch_execz .LBB0_1279
	s_waitcnt lgkmcnt(0)
	v_add_f32_e32 v15, v6, v7
	v_lshl_add_u64 v[6:7], v[0:1], 2, s[10:11]
	global_atomic_add_f32 v[6:7], v15, off
.LBB0_1279:
	s_or_b64 exec, exec, s[12:13]
	s_waitcnt lgkmcnt(0)
	ds_read2st64_b32 v[6:7], v14 offset0:1 offset1:33
	s_waitcnt lgkmcnt(0)
	v_add_f32_e32 v1, 0, v6
	v_add_f32_e32 v1, v1, v7
	ds_read2st64_b32 v[6:7], v14 offset0:65 offset1:97
	s_waitcnt lgkmcnt(0)
	v_add_f32_e32 v1, v1, v6
	v_add_f32_e32 v1, v1, v7
	ds_read2st64_b32 v[6:7], v14 offset0:129 offset1:161
	s_waitcnt lgkmcnt(0)
	v_add_f32_e32 v1, v1, v6
	v_add_f32_e32 v1, v1, v7
	ds_read2st64_b32 v[6:7], v14 offset0:193 offset1:225
	s_waitcnt lgkmcnt(0)
	v_add_f32_e32 v1, v1, v6
	v_or_b32_e32 v6, 1, v0
	v_add_f32_e32 v1, v1, v7
	v_ashrrev_i32_e32 v7, 31, v6
	v_lshlrev_b64 v[16:17], 12, v[6:7]
	v_lshl_add_u64 v[16:17], s[22:23], 0, v[16:17]
	v_lshl_add_u64 v[16:17], v[16:17], 0, v[176:177]
	global_load_dword v15, v[16:17], off
	s_waitcnt vmcnt(0) lgkmcnt(0)
	v_fmac_f32_e32 v15, v8, v1
	v_mul_f32_e32 v1, v12, v15
	global_store_dword v[16:17], v15, off
	v_cvt_pk_bf16_f32 v1, v1, v177
	global_store_short v[4:5], v1, off offset:2048
	v_mul_f32_e32 v1, v15, v15
	ds_bpermute_b32 v1, v9, v1
	s_waitcnt lgkmcnt(0)
	v_fmac_f32_e32 v1, v15, v15
	ds_bpermute_b32 v4, v10, v1
	s_waitcnt lgkmcnt(0)
	v_add_f32_e32 v1, v1, v4
	ds_bpermute_b32 v4, v11, v1
	s_waitcnt lgkmcnt(0)
	v_add_f32_e32 v1, v1, v4
	ds_bpermute_b32 v4, v13, v1
	s_and_saveexec_b64 s[12:13], s[0:1]
	s_cbranch_execz .LBB0_1281
	s_waitcnt lgkmcnt(0)
	v_add_f32_e32 v1, v1, v4
	v_lshl_add_u64 v[4:5], v[6:7], 2, s[10:11]
	global_atomic_add_f32 v[4:5], v1, off
.LBB0_1281:
	s_or_b64 exec, exec, s[12:13]
	s_waitcnt lgkmcnt(0)
	ds_read2st64_b32 v[4:5], v14 offset0:2 offset1:34
	s_mov_b32 s12, 0x2001000
	v_add_co_u32_e32 v2, vcc, s12, v2
	s_waitcnt lgkmcnt(0)
	v_add_f32_e32 v1, 0, v4
	v_add_f32_e32 v1, v1, v5
	ds_read2st64_b32 v[4:5], v14 offset0:66 offset1:98
	v_addc_co_u32_e32 v3, vcc, 0, v3, vcc
	s_waitcnt lgkmcnt(0)
	v_add_f32_e32 v1, v1, v4
	v_add_f32_e32 v1, v1, v5
	ds_read2st64_b32 v[4:5], v14 offset0:130 offset1:162
	s_waitcnt lgkmcnt(0)
	v_add_f32_e32 v1, v1, v4
	v_add_f32_e32 v1, v1, v5
	ds_read2st64_b32 v[4:5], v14 offset0:194 offset1:226
	s_waitcnt lgkmcnt(0)
	v_add_f32_e32 v1, v1, v4
	v_or_b32_e32 v4, 2, v0
	v_add_f32_e32 v1, v1, v5
	v_ashrrev_i32_e32 v5, 31, v4
	v_lshlrev_b64 v[6:7], 12, v[4:5]
	v_lshl_add_u64 v[6:7], s[22:23], 0, v[6:7]
	v_lshl_add_u64 v[6:7], v[6:7], 0, v[176:177]
	global_load_dword v15, v[6:7], off
	s_waitcnt vmcnt(0) lgkmcnt(0)
	v_fmac_f32_e32 v15, v8, v1
	v_mul_f32_e32 v1, v12, v15
	global_store_dword v[6:7], v15, off
	v_cvt_pk_bf16_f32 v1, v1, v177
	global_store_short v[2:3], v1, off
	v_mul_f32_e32 v1, v15, v15
	ds_bpermute_b32 v1, v9, v1
	s_waitcnt lgkmcnt(0)
	v_fmac_f32_e32 v1, v15, v15
	ds_bpermute_b32 v6, v10, v1
	s_waitcnt lgkmcnt(0)
	v_add_f32_e32 v1, v1, v6
	ds_bpermute_b32 v6, v11, v1
	s_waitcnt lgkmcnt(0)
	v_add_f32_e32 v1, v1, v6
	ds_bpermute_b32 v6, v13, v1
	s_and_saveexec_b64 s[12:13], s[0:1]
	s_cbranch_execz .LBB0_1283
	s_waitcnt lgkmcnt(0)
	v_add_f32_e32 v1, v1, v6
	v_lshl_add_u64 v[4:5], v[4:5], 2, s[10:11]
	global_atomic_add_f32 v[4:5], v1, off
.LBB0_1283:
	s_or_b64 exec, exec, s[12:13]
	ds_read2st64_b32 v[4:5], v14 offset0:3 offset1:35
	v_or_b32_e32 v0, 3, v0
	s_waitcnt lgkmcnt(0)
	v_add_f32_e32 v1, 0, v4
	v_add_f32_e32 v1, v1, v5
	ds_read2st64_b32 v[4:5], v14 offset0:67 offset1:99
	s_waitcnt lgkmcnt(0)
	v_add_f32_e32 v1, v1, v4
	v_add_f32_e32 v1, v1, v5
	ds_read2st64_b32 v[4:5], v14 offset0:131 offset1:163
	s_waitcnt lgkmcnt(0)
	v_add_f32_e32 v1, v1, v4
	v_add_f32_e32 v1, v1, v5
	ds_read2st64_b32 v[4:5], v14 offset0:195 offset1:227
	s_waitcnt lgkmcnt(0)
	v_add_f32_e32 v1, v1, v4
	v_add_f32_e32 v6, v1, v5
	v_ashrrev_i32_e32 v1, 31, v0
	v_lshlrev_b64 v[4:5], 12, v[0:1]
	v_lshl_add_u64 v[4:5], s[22:23], 0, v[4:5]
	v_lshl_add_u64 v[4:5], v[4:5], 0, v[176:177]
	global_load_dword v7, v[4:5], off
	s_waitcnt vmcnt(0) lgkmcnt(0)
	v_fmac_f32_e32 v7, v8, v6
	global_store_dword v[4:5], v7, off
	v_mul_f32_e32 v4, v12, v7
	v_cvt_pk_bf16_f32 v4, v4, v177
	global_store_short v[2:3], v4, off offset:2048
	v_mul_f32_e32 v2, v7, v7
	ds_bpermute_b32 v2, v9, v2
	s_waitcnt lgkmcnt(0)
	v_fmac_f32_e32 v2, v7, v7
	ds_bpermute_b32 v3, v10, v2
	s_waitcnt lgkmcnt(0)
	v_add_f32_e32 v2, v2, v3
	ds_bpermute_b32 v3, v11, v2
	s_waitcnt lgkmcnt(0)
	v_add_f32_e32 v2, v2, v3
	ds_bpermute_b32 v3, v13, v2
	s_and_saveexec_b64 s[12:13], s[0:1]
	s_cbranch_execz .LBB0_1276
	s_waitcnt lgkmcnt(0)
	v_add_f32_e32 v2, v2, v3
	v_lshl_add_u64 v[0:1], v[0:1], 2, s[10:11]
	global_atomic_add_f32 v[0:1], v2, off
	s_branch .LBB0_1276

; __device__ __forceinline__ unsigned xb_ld(unsigned* p)              { return __hip_atomic_load(p, __ATOMIC_RELAXED, __HIP_MEMORY_SCOPE_AGENT); }
; __device__ __forceinline__ void xcd_barrier_complete(unsigned* bar, unsigned x, unsigned& nloc, unsigned& nx) {
;     ...
;     for (;;) {
;         sum = 0u; cnt = 0u; mine = 0u;
; #pragma unroll
;         for (unsigned j = 0; j < 16; ++j) { const unsigned c = xb_ld(&bar[XB_XCNT(j)]); sum += c; cnt += (c > 0u) ? 1u : 0u; mine = (j == x) ? c : mine; }
;         if (sum == G) break;
;         __builtin_amdgcn_s_sleep(1);
;         if ((++sp & 255u) == 0u) { if (xb_ld(&bar[XB_TMO])) break; if (sp > XB_SPIN_CAP) { atomicAdd(&bar[XB_TMO], 1u); break; } }
;     }
.LBB0_1290:
	v_mov_b64_e32 v[12:13], s[36:37]
	global_load_dword v1, v[12:13], off offset:1024 sc1
	s_waitcnt lgkmcnt(0)
	global_load_dword v0, v[12:13], off offset:1280 sc1
	global_load_dword v2, v[12:13], off offset:1536 sc1
	s_or_b64 s[18:19], s[18:19], exec
	s_or_b64 s[16:17], s[16:17], exec
	s_waitcnt vmcnt(0) lgkmcnt(0)
	v_add_u32_e32 v3, v0, v1
	v_add_u32_e32 v4, v3, v2
	global_load_dword v3, v[12:13], off offset:1792 sc1
	s_waitcnt vmcnt(0) lgkmcnt(0)
	v_add_u32_e32 v5, v4, v3
	global_load_dword v4, v[12:13], off offset:2048 sc1
	s_waitcnt vmcnt(0) lgkmcnt(0)
	v_add_u32_e32 v6, v5, v4
	global_load_dword v5, v[12:13], off offset:2304 sc1
	s_waitcnt vmcnt(0) lgkmcnt(0)
	v_add_u32_e32 v7, v6, v5
	global_load_dword v6, v[12:13], off offset:2560 sc1
	s_waitcnt vmcnt(0) lgkmcnt(0)
	v_add_u32_e32 v8, v7, v6
	global_load_dword v7, v[12:13], off offset:2816 sc1
	s_waitcnt vmcnt(0) lgkmcnt(0)
	v_add_u32_e32 v9, v8, v7
	global_load_dword v8, v[12:13], off offset:3072 sc1
	s_waitcnt vmcnt(0) lgkmcnt(0)
	v_add_u32_e32 v10, v9, v8
	global_load_dword v9, v[12:13], off offset:3328 sc1
	s_waitcnt vmcnt(0) lgkmcnt(0)
	v_add_u32_e32 v11, v10, v9
	global_load_dword v10, v[12:13], off offset:3584 sc1
	s_waitcnt vmcnt(0) lgkmcnt(0)
	v_add_u32_e32 v14, v11, v10
	global_load_dword v11, v[12:13], off offset:3840 sc1
	v_mov_b64_e32 v[12:13], s[0:1]
	global_load_dword v12, v[12:13], off sc1
	s_waitcnt vmcnt(0) lgkmcnt(0)
	v_add_u32_e32 v14, v14, v11
	v_add_u32_e32 v16, v14, v12
	v_mov_b64_e32 v[14:15], s[4:5]
	global_load_dword v13, v[14:15], off sc1
	v_mov_b64_e32 v[14:15], s[6:7]
	global_load_dword v14, v[14:15], off sc1
	s_waitcnt vmcnt(0) lgkmcnt(0)
	v_add_u32_e32 v16, v16, v13
	v_add_u32_e32 v18, v16, v14
	v_mov_b64_e32 v[16:17], s[8:9]
	global_load_dword v15, v[16:17], off sc1
	s_waitcnt vmcnt(0) lgkmcnt(0)
	v_add_u32_e32 v16, v18, v15
	v_cmp_ne_u32_e32 vcc, s78, v16
	s_and_saveexec_b64 s[20:21], vcc
	s_cbranch_execz .LBB0_1289
	s_and_b32 s24, s30, 0xff
	s_mov_b64 s[22:23], -1
	s_cmp_eq_u32 s24, 0
	s_mov_b64 s[26:27], -1
	s_mov_b64 s[24:25], -1
	s_sleep 1
	s_cbranch_scc1 .LBB0_1293
	s_and_saveexec_b64 s[28:29], s[26:27]
	s_cbranch_execz .LBB0_1288
	s_branch .LBB0_1296
.LBB0_1293:
	v_mov_b64_e32 v[16:17], s[36:37]
	global_load_dword v16, v[16:17], off offset:512 sc1
	s_mov_b64 s[26:27], 0
	s_waitcnt vmcnt(0) lgkmcnt(0)
	v_cmp_eq_u32_e32 vcc, 0, v16
	s_and_saveexec_b64 s[28:29], vcc
	s_cmp_lt_u32 s30, 0x40001
	s_cselect_b64 s[26:27], -1, 0
	s_xor_b64 s[24:25], exec, -1
	s_and_b64 s[26:27], s[26:27], exec
	s_or_b64 exec, exec, s[28:29]
	s_and_saveexec_b64 s[28:29], s[26:27]
	s_cbranch_execz .LBB0_1288

; __device__ __forceinline__ unsigned xb_ld(unsigned* p)              { return __hip_atomic_load(p, __ATOMIC_RELAXED, __HIP_MEMORY_SCOPE_AGENT); }
; __device__ __forceinline__ void xcd_barrier_complete(unsigned* bar, unsigned x, unsigned& nloc, unsigned& nx) {
;     ...
;         if ((++sp & 255u) == 0u) { if (xb_ld(&bar[XB_TMO])) break; if (sp > XB_SPIN_CAP) { atomicAdd(&bar[XB_TMO], 1u); break; } }
.LBB0_1297:
	s_or_b64 exec, exec, s[10:11]
	s_xor_b64 s[0:1], s[12:13], -1
	s_and_saveexec_b64 s[4:5], s[0:1]
	s_xor_b64 s[0:1], exec, s[4:5]
	s_cbranch_execz .LBB0_1299
	v_mov_b64_e32 v[16:17], s[36:37]
	global_atomic_add v[16:17], v225, off offset:512

; __device__ __forceinline__ unsigned xb_ld(unsigned* p)              { return __hip_atomic_load(p, __ATOMIC_RELAXED, __HIP_MEMORY_SCOPE_AGENT); }
; __device__ __forceinline__ unsigned xb_add(unsigned* p, unsigned v) { return __hip_atomic_fetch_add(p, v, __ATOMIC_RELAXED, __HIP_MEMORY_SCOPE_AGENT); }
; #define XB_SPIN(cond, bar) do { unsigned _sp = 0; while (cond) { __builtin_amdgcn_s_sleep(1); \
;     if ((++_sp & 255u) == 0u) { if (xb_ld(&(bar)[XB_TMO])) break; if (_sp > XB_SPIN_CAP) { atomicAdd(&(bar)[XB_TMO], 1u); break; } } } } while (0)
; __device__ __forceinline__ void xcd_barrier(const XcdBarrier& b) {
;     ...
;         const unsigned old = xb_add(&bar[XB_XSUB(b.x)], 1u);
;         const unsigned gen = old / nloc;
;         if (old + 1u == (gen + 1u) * nloc) {
;             __builtin_amdgcn_fence(__ATOMIC_RELEASE, "agent");
;             asm volatile("s_waitcnt vmcnt(0)" ::: "memory");
;             const unsigned og = xb_add(&bar[XB_TOP], 1u);
;             const unsigned tg = og / nx;
;             if (og + 1u == (tg + 1u) * nx) xb_add(&bar[XB_TOPGEN], 1u);
;             else XB_SPIN(xb_ld(&bar[XB_TOPGEN]) == tg, bar);
;             __builtin_amdgcn_fence(__ATOMIC_ACQUIRE, "agent");
;             xb_add(&bar[XB_XGEN(b.x)], 1u);
;             asm volatile("s_waitcnt vmcnt(0)" ::: "memory");
;         } else {
;             XB_SPIN(xb_ld(&bar[XB_XGEN(b.x)]) == gen, bar);
.LBB0_1300:
	s_lshl_b32 s0, s38, 8
	s_add_u32 s25, s36, s0
	s_addc_u32 s24, s37, 0
	v_mov_b32_e32 v1, s25
	v_add_co_u32_e32 v4, vcc, 0x1000, v1
	v_mov_b32_e32 v1, s24
	s_nop 0
	v_addc_co_u32_e32 v5, vcc, 0, v1, vcc
	global_atomic_add v3, v[4:5], v225, off offset:1024 sc0
	v_cvt_f32_u32_e32 v1, v2
	v_sub_u32_e32 v4, 0, v2
	v_rcp_iflag_f32_e32 v1, v1
	s_nop 0
	v_mul_f32_e32 v1, 0x4f7ffffe, v1
	v_cvt_u32_f32_e32 v1, v1
	v_mul_lo_u32 v4, v4, v1
	v_mul_hi_u32 v4, v1, v4
	v_add_u32_e32 v1, v1, v4
	s_waitcnt vmcnt(0) lgkmcnt(0)
	v_mul_hi_u32 v1, v3, v1
	v_mul_lo_u32 v4, v1, v2
	v_sub_u32_e32 v4, v3, v4
	v_cmp_ge_u32_e32 vcc, v4, v2
	v_add_u32_e32 v5, 1, v1
	s_nop 0
	v_cndmask_b32_e32 v1, v1, v5, vcc
	v_sub_u32_e32 v5, v4, v2
	v_cndmask_b32_e32 v4, v4, v5, vcc
	v_cmp_ge_u32_e32 vcc, v4, v2
	v_add_u32_e32 v4, 1, v1
	s_nop 0
	v_cndmask_b32_e32 v1, v1, v4, vcc
	v_add_u32_e32 v4, 1, v3
	v_mad_u64_u32 v[2:3], s[0:1], v2, v1, v[2:3]
	v_cmp_ne_u32_e32 vcc, v4, v2
	s_and_saveexec_b64 s[0:1], vcc
	s_xor_b64 s[0:1], exec, s[0:1]
	s_cbranch_execz .LBB0_1313
	v_mov_b32_e32 v0, s25
	v_add_co_u32_e32 v2, vcc, 0x2000, v0
	v_mov_b32_e32 v0, s24
	s_nop 0
	v_addc_co_u32_e32 v3, vcc, 0, v0, vcc
	global_load_dword v0, v[2:3], off offset:1024 sc1
	s_add_u32 s6, s25, 0x2400
	s_addc_u32 s7, s24, 0
	s_waitcnt vmcnt(0) lgkmcnt(0)
	v_cmp_eq_u32_e32 vcc, v0, v1
	s_and_saveexec_b64 s[4:5], vcc
	s_cbranch_execz .LBB0_1312
	s_mov_b32 s26, 1
	s_mov_b64 s[8:9], 0
	s_branch .LBB0_1304

.LBB0_1304:
	s_and_b32 s18, s26, 0xff
	s_mov_b64 s[16:17], -1
	s_cmp_lg_u32 s18, 0
	s_mov_b64 s[18:19], -1
	s_sleep 1
	s_cbranch_scc1 .LBB0_1308
	v_mov_b64_e32 v[2:3], s[36:37]
	global_load_dword v0, v[2:3], off offset:512 sc1
	s_mov_b64 s[18:19], 0
	s_mov_b64 s[20:21], -1
	s_waitcnt vmcnt(0) lgkmcnt(0)
	v_cmp_eq_u32_e32 vcc, 0, v0
	s_and_saveexec_b64 s[22:23], vcc
	s_cmp_lt_u32 s26, 0x40001
	s_cselect_b64 s[18:19], -1, 0
	s_xor_b64 s[20:21], exec, -1
	s_and_b64 s[18:19], s[18:19], exec
	s_or_b64 exec, exec, s[22:23]

.LBB0_1310:
	s_or_b64 exec, exec, s[8:9]
	s_xor_b64 s[6:7], s[10:11], -1
	s_and_saveexec_b64 s[8:9], s[6:7]
	s_xor_b64 s[8:9], exec, s[8:9]
	s_cbranch_execz .LBB0_1312
	v_mov_b64_e32 v[0:1], s[36:37]
	global_atomic_add v[0:1], v225, off offset:512

; __device__ __forceinline__ unsigned xb_ld(unsigned* p)              { return __hip_atomic_load(p, __ATOMIC_RELAXED, __HIP_MEMORY_SCOPE_AGENT); }
; __device__ __forceinline__ unsigned xb_add(unsigned* p, unsigned v) { return __hip_atomic_fetch_add(p, v, __ATOMIC_RELAXED, __HIP_MEMORY_SCOPE_AGENT); }
; #define XB_SPIN(cond, bar) do { unsigned _sp = 0; while (cond) { __builtin_amdgcn_s_sleep(1); \
;     if ((++_sp & 255u) == 0u) { if (xb_ld(&(bar)[XB_TMO])) break; if (_sp > XB_SPIN_CAP) { atomicAdd(&(bar)[XB_TMO], 1u); break; } } } } while (0)
; __device__ __forceinline__ void xcd_barrier(const XcdBarrier& b) {
;     ...
;         if (old + 1u == (gen + 1u) * nloc) {
;             __builtin_amdgcn_fence(__ATOMIC_RELEASE, "agent");
;             asm volatile("s_waitcnt vmcnt(0)" ::: "memory");
;             const unsigned og = xb_add(&bar[XB_TOP], 1u);
;             const unsigned tg = og / nx;
;             if (og + 1u == (tg + 1u) * nx) xb_add(&bar[XB_TOPGEN], 1u);
;             else XB_SPIN(xb_ld(&bar[XB_TOPGEN]) == tg, bar);
.LBB0_1314:
	v_mov_b32_e32 v1, s36
	v_add_co_u32_e32 v2, vcc, 0x3000, v1
	v_mov_b32_e32 v1, s37
	buffer_wbl2 sc1
	s_waitcnt vmcnt(0)
	v_addc_co_u32_e32 v3, vcc, 0, v1, vcc
	global_atomic_add v1, v[2:3], v225, off offset:1024 sc0
	v_cvt_f32_u32_e32 v2, v0
	v_sub_u32_e32 v3, 0, v0
	s_mov_b64 s[6:7], -1
	v_rcp_iflag_f32_e32 v2, v2
	s_nop 0
	v_mul_f32_e32 v2, 0x4f7ffffe, v2
	v_cvt_u32_f32_e32 v2, v2
	v_mul_lo_u32 v3, v3, v2
	v_mul_hi_u32 v3, v2, v3
	v_add_u32_e32 v2, v2, v3
	s_waitcnt vmcnt(0) lgkmcnt(0)
	v_mul_hi_u32 v2, v1, v2
	v_mul_lo_u32 v3, v2, v0
	v_sub_u32_e32 v3, v1, v3
	v_cmp_ge_u32_e32 vcc, v3, v0
	v_add_u32_e32 v4, 1, v2
	s_nop 0
	v_cndmask_b32_e32 v2, v2, v4, vcc
	v_sub_u32_e32 v4, v3, v0
	v_cndmask_b32_e32 v3, v3, v4, vcc
	v_cmp_ge_u32_e32 vcc, v3, v0
	v_add_u32_e32 v3, 1, v2
	s_nop 0
	v_cndmask_b32_e32 v2, v2, v3, vcc
	v_add_u32_e32 v3, 1, v1
	v_mad_u64_u32 v[0:1], s[0:1], v0, v2, v[0:1]
	s_add_u32 s0, s36, 0x3500
	s_addc_u32 s1, s37, 0
	v_cmp_ne_u32_e32 vcc, v3, v0
	v_mov_b64_e32 v[0:1], s[0:1]
	s_and_saveexec_b64 s[4:5], vcc
	s_cbranch_execz .LBB0_1326
	v_mov_b64_e32 v[0:1], s[0:1]
	global_load_dword v0, v[0:1], off sc1
	s_mov_b64 s[10:11], 0
	s_waitcnt vmcnt(0) lgkmcnt(0)
	v_cmp_eq_u32_e32 vcc, v0, v2
	s_and_saveexec_b64 s[8:9], vcc
	s_cbranch_execz .LBB0_1325
	s_add_u32 s6, s36, 0x200
	s_addc_u32 s7, s37, 0
	s_mov_b32 s26, 1
	s_branch .LBB0_1318

; __device__ __forceinline__ unsigned xb_add(unsigned* p, unsigned v) { return __hip_atomic_fetch_add(p, v, __ATOMIC_RELAXED, __HIP_MEMORY_SCOPE_AGENT); }
; __device__ __forceinline__ void xcd_barrier(const XcdBarrier& b) {
;     ...
;             if (og + 1u == (tg + 1u) * nx) xb_add(&bar[XB_TOPGEN], 1u);
.LBB0_1327:
	global_atomic_add v[0:1], v225, off
	s_getpc_b64 s[98:99]
